# v43 + s_setprio 1 from first staging ds_write to s_barrier (prio 0 after) in all GEMM k-loops: barrier-approach priority
# speedup vs baseline: 1.0215x; 1.0215x over previous
.LBB0_257:
	v_ashrrev_i32_e32 v3, 31, v2
	v_lshlrev_b64 v[2:3], 11, v[2:3]
	v_lshl_add_u64 v[70:71], v[86:87], 0, v[2:3]
	v_or_b32_e32 v2, s56, v154
	v_ashrrev_i32_e32 v3, 31, v2
	v_lshlrev_b64 v[2:3], 11, v[2:3]
	v_lshl_add_u64 v[72:73], v[84:85], 0, v[2:3]
	v_add_u32_e32 v2, s56, v155
	v_ashrrev_i32_e32 v3, 31, v2
	v_lshlrev_b64 v[2:3], 11, v[2:3]
	v_lshl_add_u64 v[74:75], v[84:85], 0, v[2:3]
	v_add_u32_e32 v2, s56, v156
	v_ashrrev_i32_e32 v3, 31, v2
	v_lshlrev_b64 v[2:3], 11, v[2:3]
	v_lshl_add_u64 v[76:77], v[84:85], 0, v[2:3]
	v_add_u32_e32 v2, s56, v157
	v_ashrrev_i32_e32 v3, 31, v2
	v_ashrrev_i32_e32 v9, 31, v8
	v_ashrrev_i32_e32 v5, 31, v4
	v_lshlrev_b64 v[2:3], 11, v[2:3]
	v_ashrrev_i32_e32 v7, 31, v6
	v_lshlrev_b64 v[8:9], 11, v[8:9]
	v_lshlrev_b64 v[4:5], 11, v[4:5]
	v_lshl_add_u64 v[78:79], v[84:85], 0, v[2:3]
	v_lshlrev_b64 v[2:3], 11, v[6:7]
	v_lshl_add_u64 v[66:67], v[86:87], 0, v[8:9]
	v_lshl_add_u64 v[68:69], v[86:87], 0, v[4:5]
	v_lshl_add_u64 v[80:81], v[86:87], 0, v[2:3]
	global_load_dwordx4 v[2:5], v[70:71], off
	global_load_dwordx4 v[6:9], v[68:69], off
	global_load_dwordx4 v[10:13], v[66:67], off
	global_load_dwordx4 v[14:17], v[80:81], off
	global_load_dwordx4 v[18:21], v[72:73], off
	global_load_dwordx4 v[22:25], v[74:75], off
	global_load_dwordx4 v[26:29], v[76:77], off
	global_load_dwordx4 v[30:33], v[78:79], off
	global_load_dwordx4 v[122:125], v[70:71], off offset:128
	global_load_dwordx4 v[126:129], v[68:69], off offset:128
	global_load_dwordx4 v[136:139], v[66:67], off offset:128
	global_load_dwordx4 v[140:143], v[80:81], off offset:128
	global_load_dwordx4 v[144:147], v[72:73], off offset:128
	global_load_dwordx4 v[148:151], v[74:75], off offset:128
	global_load_dwordx4 v[172:175], v[76:77], off offset:128
	global_load_dwordx4 v[176:179], v[78:79], off offset:128
	s_waitcnt vmcnt(15)
	ds_write_b128 v165, v[2:5] offset:36864
	s_waitcnt vmcnt(14)
	ds_write_b128 v165, v[6:9] offset:41472
	s_waitcnt vmcnt(13)
	ds_write_b128 v165, v[10:13] offset:46080
	s_waitcnt vmcnt(12)
	ds_write_b128 v165, v[14:17] offset:50688
	s_waitcnt vmcnt(11)
	ds_write_b128 v165, v[18:21]
	s_waitcnt vmcnt(10)
	ds_write_b128 v165, v[22:25] offset:4608
	s_waitcnt vmcnt(9)
	ds_write_b128 v165, v[26:29] offset:9216
	s_waitcnt vmcnt(8)
	ds_write_b128 v165, v[30:33] offset:13824
	s_waitcnt lgkmcnt(0)
	s_barrier
	global_load_dwordx4 v[180:183], v[74:75], off offset:256
	global_load_dwordx4 v[184:187], v[76:77], off offset:256
	global_load_dwordx4 v[188:191], v[72:73], off offset:256
	global_load_dwordx4 v[192:195], v[70:71], off offset:256
	global_load_dwordx4 v[196:199], v[68:69], off offset:256
	global_load_dwordx4 v[200:203], v[66:67], off offset:256
	global_load_dwordx4 v[204:207], v[78:79], off offset:256
	global_load_dwordx4 v[208:211], v[80:81], off offset:256
	v_and_b32_e32 v246, 15, v1
	v_add_u32_e32 v246, 4, v246
	v_bfe_u32 v246, v246, 3, 1
	v_bfe_u32 v249, v1, 4, 2
	v_xor_b32_e32 v246, v246, v249
	v_bfe_u32 v249, v1, 5, 1
	v_sub_u32_e32 v246, v246, v249
	v_lshlrev_b32_e32 v246, 4, v246
	v_bfe_u32 v249, v1, 4, 1
	v_mul_u32_u24_e32 v249, 0x900, v249
	v_sub_u32_e32 v246, v246, v249
	v_add_u32_e32 v244, v246, v162
	v_add_u32_e32 v245, v246, v164
	ds_read_b128 v[228:231], v245 offset:36864
	ds_read_b128 v[212:215], v244
	ds_read_b128 v[236:239], v245 offset:39168
	ds_read_b128 v[240:243], v245 offset:41472
	ds_read_b128 v[252:255], v245 offset:43776
	ds_read_b128 v[216:219], v244 offset:2304
	ds_read_b128 v[220:223], v244 offset:4608
	ds_read_b128 v[224:227], v244 offset:6912
	s_waitcnt lgkmcnt(6)
	v_mfma_f32_16x16x32_bf16 v[50:53], v[212:215], v[228:231], 0
	s_waitcnt lgkmcnt(5)
	v_mfma_f32_16x16x32_bf16 v[54:57], v[212:215], v[236:239], 0
	s_waitcnt lgkmcnt(4)
	v_mfma_f32_16x16x32_bf16 v[34:37], v[212:215], v[240:243], 0
	s_waitcnt lgkmcnt(3)
	v_mfma_f32_16x16x32_bf16 v[38:41], v[212:215], v[252:255], 0
	ds_read_b128 v[212:215], v244 offset:64
	s_waitcnt lgkmcnt(3)
	v_mfma_f32_16x16x32_bf16 v[58:61], v[216:219], v[228:231], 0
	v_mfma_f32_16x16x32_bf16 v[62:65], v[216:219], v[236:239], 0
	v_mfma_f32_16x16x32_bf16 v[42:45], v[216:219], v[240:243], 0
	v_mfma_f32_16x16x32_bf16 v[46:49], v[216:219], v[252:255], 0
	ds_read_b128 v[216:219], v244 offset:2368
	s_setprio 1
	s_waitcnt vmcnt(11)
	ds_write_b128 v165, v[144:147] offset:18432
	s_waitcnt vmcnt(10)
	ds_write_b128 v165, v[148:151] offset:23040
	s_waitcnt lgkmcnt(5)
	v_mfma_f32_16x16x32_bf16 v[18:21], v[220:223], v[228:231], 0
	v_mfma_f32_16x16x32_bf16 v[22:25], v[220:223], v[236:239], 0
	v_mfma_f32_16x16x32_bf16 v[2:5], v[220:223], v[240:243], 0
	v_mfma_f32_16x16x32_bf16 v[6:9], v[220:223], v[252:255], 0
	ds_read_b128 v[220:223], v244 offset:4672
	s_waitcnt vmcnt(9)
	ds_write_b128 v165, v[172:175] offset:27648
	s_waitcnt vmcnt(8)
	ds_write_b128 v165, v[176:179] offset:32256
	s_waitcnt lgkmcnt(7)
	v_mfma_f32_16x16x32_bf16 v[26:29], v[224:227], v[228:231], 0
	ds_read_b128 v[228:231], v245 offset:36928
	v_mfma_f32_16x16x32_bf16 v[30:33], v[224:227], v[236:239], 0
	ds_read_b128 v[236:239], v245 offset:39232
	v_mfma_f32_16x16x32_bf16 v[10:13], v[224:227], v[240:243], 0
	ds_read_b128 v[240:243], v245 offset:41536
	v_mfma_f32_16x16x32_bf16 v[14:17], v[224:227], v[252:255], 0
	ds_read_b128 v[252:255], v245 offset:43840
	ds_read_b128 v[224:227], v244 offset:6976
	s_waitcnt lgkmcnt(4)
	v_mfma_f32_16x16x32_bf16 v[50:53], v[212:215], v[228:231], v[50:53]
	s_waitcnt lgkmcnt(3)
	v_mfma_f32_16x16x32_bf16 v[54:57], v[212:215], v[236:239], v[54:57]
	s_waitcnt lgkmcnt(2)
	v_mfma_f32_16x16x32_bf16 v[34:37], v[212:215], v[240:243], v[34:37]
	s_waitcnt lgkmcnt(1)
	v_mfma_f32_16x16x32_bf16 v[38:41], v[212:215], v[252:255], v[38:41]
	ds_write_b128 v165, v[122:125] offset:55296
	ds_write_b128 v165, v[126:129] offset:59904
	v_mfma_f32_16x16x32_bf16 v[58:61], v[216:219], v[228:231], v[58:61]
	v_mfma_f32_16x16x32_bf16 v[62:65], v[216:219], v[236:239], v[62:65]
	v_mfma_f32_16x16x32_bf16 v[42:45], v[216:219], v[240:243], v[42:45]
	v_mfma_f32_16x16x32_bf16 v[46:49], v[216:219], v[252:255], v[46:49]
	ds_write_b128 v165, v[136:139] offset:64512
	ds_write_b128 v166, v[140:143] offset:32256
	v_mfma_f32_16x16x32_bf16 v[18:21], v[220:223], v[228:231], v[18:21]
	v_mfma_f32_16x16x32_bf16 v[22:25], v[220:223], v[236:239], v[22:25]
	v_mfma_f32_16x16x32_bf16 v[2:5], v[220:223], v[240:243], v[2:5]
	v_mfma_f32_16x16x32_bf16 v[6:9], v[220:223], v[252:255], v[6:9]
	s_waitcnt lgkmcnt(4)
	v_mfma_f32_16x16x32_bf16 v[26:29], v[224:227], v[228:231], v[26:29]
	v_mfma_f32_16x16x32_bf16 v[30:33], v[224:227], v[236:239], v[30:33]
	v_mfma_f32_16x16x32_bf16 v[10:13], v[224:227], v[240:243], v[10:13]
	v_mfma_f32_16x16x32_bf16 v[14:17], v[224:227], v[252:255], v[14:17]
	s_waitcnt lgkmcnt(0)
	s_barrier
	s_setprio 0
	global_load_dwordx4 v[122:125], v[72:73], off offset:384
	global_load_dwordx4 v[126:129], v[74:75], off offset:384
	global_load_dwordx4 v[136:139], v[76:77], off offset:384
	global_load_dwordx4 v[140:143], v[78:79], off offset:384
	global_load_dwordx4 v[144:147], v[70:71], off offset:384
	global_load_dwordx4 v[148:151], v[68:69], off offset:384
	global_load_dwordx4 v[172:175], v[66:67], off offset:384
	global_load_dwordx4 v[176:179], v[80:81], off offset:384
	ds_read_b128 v[228:231], v245 offset:55296
	ds_read_b128 v[212:215], v244 offset:18432
	ds_read_b128 v[236:239], v245 offset:57600
	ds_read_b128 v[240:243], v245 offset:59904
	ds_read_b128 v[252:255], v245 offset:62208
	ds_read_b128 v[216:219], v244 offset:20736
	ds_read_b128 v[220:223], v244 offset:23040
	ds_read_b128 v[224:227], v244 offset:25344
	s_waitcnt lgkmcnt(6)
	v_mfma_f32_16x16x32_bf16 v[50:53], v[212:215], v[228:231], v[50:53]
	s_waitcnt lgkmcnt(5)
	v_mfma_f32_16x16x32_bf16 v[54:57], v[212:215], v[236:239], v[54:57]
	s_waitcnt lgkmcnt(4)
	v_mfma_f32_16x16x32_bf16 v[34:37], v[212:215], v[240:243], v[34:37]
	s_waitcnt lgkmcnt(3)
	v_mfma_f32_16x16x32_bf16 v[38:41], v[212:215], v[252:255], v[38:41]
	ds_read_b128 v[212:215], v244 offset:18496
	s_waitcnt lgkmcnt(3)
	v_mfma_f32_16x16x32_bf16 v[58:61], v[216:219], v[228:231], v[58:61]
	v_mfma_f32_16x16x32_bf16 v[62:65], v[216:219], v[236:239], v[62:65]
	v_mfma_f32_16x16x32_bf16 v[42:45], v[216:219], v[240:243], v[42:45]
	v_mfma_f32_16x16x32_bf16 v[46:49], v[216:219], v[252:255], v[46:49]
	ds_read_b128 v[216:219], v244 offset:20800
	s_setprio 1
	s_waitcnt vmcnt(13)
	ds_write_b128 v165, v[188:191]
	ds_write_b128 v165, v[180:183] offset:4608
	s_waitcnt lgkmcnt(5)
	v_mfma_f32_16x16x32_bf16 v[18:21], v[220:223], v[228:231], v[18:21]
	v_mfma_f32_16x16x32_bf16 v[22:25], v[220:223], v[236:239], v[22:25]
	v_mfma_f32_16x16x32_bf16 v[2:5], v[220:223], v[240:243], v[2:5]
	v_mfma_f32_16x16x32_bf16 v[6:9], v[220:223], v[252:255], v[6:9]
	ds_read_b128 v[220:223], v244 offset:23104
	ds_write_b128 v165, v[184:187] offset:9216
	s_waitcnt vmcnt(9)
	ds_write_b128 v165, v[204:207] offset:13824
	s_waitcnt lgkmcnt(7)
	v_mfma_f32_16x16x32_bf16 v[26:29], v[224:227], v[228:231], v[26:29]
	ds_read_b128 v[228:231], v245 offset:55360
	v_mfma_f32_16x16x32_bf16 v[30:33], v[224:227], v[236:239], v[30:33]
	ds_read_b128 v[236:239], v245 offset:57664
	v_mfma_f32_16x16x32_bf16 v[10:13], v[224:227], v[240:243], v[10:13]
	ds_read_b128 v[240:243], v245 offset:59968
	v_mfma_f32_16x16x32_bf16 v[14:17], v[224:227], v[252:255], v[14:17]
	ds_read_b128 v[252:255], v245 offset:62272
	ds_read_b128 v[224:227], v244 offset:25408
	s_waitcnt lgkmcnt(4)
	v_mfma_f32_16x16x32_bf16 v[50:53], v[212:215], v[228:231], v[50:53]
	s_waitcnt lgkmcnt(3)
	v_mfma_f32_16x16x32_bf16 v[54:57], v[212:215], v[236:239], v[54:57]
	s_waitcnt lgkmcnt(2)
	v_mfma_f32_16x16x32_bf16 v[34:37], v[212:215], v[240:243], v[34:37]
	s_waitcnt lgkmcnt(1)
	v_mfma_f32_16x16x32_bf16 v[38:41], v[212:215], v[252:255], v[38:41]
	ds_write_b128 v165, v[192:195] offset:36864
	ds_write_b128 v165, v[196:199] offset:41472
	v_mfma_f32_16x16x32_bf16 v[58:61], v[216:219], v[228:231], v[58:61]
	v_mfma_f32_16x16x32_bf16 v[62:65], v[216:219], v[236:239], v[62:65]
	v_mfma_f32_16x16x32_bf16 v[42:45], v[216:219], v[240:243], v[42:45]
	v_mfma_f32_16x16x32_bf16 v[46:49], v[216:219], v[252:255], v[46:49]
	ds_write_b128 v165, v[200:203] offset:46080
	s_waitcnt vmcnt(8)
	ds_write_b128 v165, v[208:211] offset:50688
	v_mfma_f32_16x16x32_bf16 v[18:21], v[220:223], v[228:231], v[18:21]
	v_mfma_f32_16x16x32_bf16 v[22:25], v[220:223], v[236:239], v[22:25]
	v_mfma_f32_16x16x32_bf16 v[2:5], v[220:223], v[240:243], v[2:5]
	v_mfma_f32_16x16x32_bf16 v[6:9], v[220:223], v[252:255], v[6:9]
	s_waitcnt lgkmcnt(4)
	v_mfma_f32_16x16x32_bf16 v[26:29], v[224:227], v[228:231], v[26:29]
	v_mfma_f32_16x16x32_bf16 v[30:33], v[224:227], v[236:239], v[30:33]
	v_mfma_f32_16x16x32_bf16 v[10:13], v[224:227], v[240:243], v[10:13]
	v_mfma_f32_16x16x32_bf16 v[14:17], v[224:227], v[252:255], v[14:17]
	s_waitcnt lgkmcnt(0)
	s_barrier
	s_setprio 0
	global_load_dwordx4 v[180:183], v[72:73], off offset:512
	global_load_dwordx4 v[184:187], v[74:75], off offset:512
	global_load_dwordx4 v[188:191], v[76:77], off offset:512
	global_load_dwordx4 v[192:195], v[78:79], off offset:512
	global_load_dwordx4 v[196:199], v[70:71], off offset:512
	global_load_dwordx4 v[200:203], v[68:69], off offset:512
	global_load_dwordx4 v[204:207], v[66:67], off offset:512
	global_load_dwordx4 v[208:211], v[80:81], off offset:512
	ds_read_b128 v[228:231], v245 offset:36864
	ds_read_b128 v[212:215], v244
	ds_read_b128 v[236:239], v245 offset:39168
	ds_read_b128 v[240:243], v245 offset:41472
	ds_read_b128 v[252:255], v245 offset:43776
	ds_read_b128 v[216:219], v244 offset:2304
	ds_read_b128 v[220:223], v244 offset:4608
	ds_read_b128 v[224:227], v244 offset:6912
	s_waitcnt lgkmcnt(6)
	v_mfma_f32_16x16x32_bf16 v[50:53], v[212:215], v[228:231], v[50:53]
	s_waitcnt lgkmcnt(5)
	v_mfma_f32_16x16x32_bf16 v[54:57], v[212:215], v[236:239], v[54:57]
	s_waitcnt lgkmcnt(4)
	v_mfma_f32_16x16x32_bf16 v[34:37], v[212:215], v[240:243], v[34:37]
	s_waitcnt lgkmcnt(3)
	v_mfma_f32_16x16x32_bf16 v[38:41], v[212:215], v[252:255], v[38:41]
	ds_read_b128 v[212:215], v244 offset:64
	s_waitcnt lgkmcnt(3)
	v_mfma_f32_16x16x32_bf16 v[58:61], v[216:219], v[228:231], v[58:61]
	v_mfma_f32_16x16x32_bf16 v[62:65], v[216:219], v[236:239], v[62:65]
	v_mfma_f32_16x16x32_bf16 v[42:45], v[216:219], v[240:243], v[42:45]
	v_mfma_f32_16x16x32_bf16 v[46:49], v[216:219], v[252:255], v[46:49]
	ds_read_b128 v[216:219], v244 offset:2368
	s_setprio 1
	s_waitcnt vmcnt(15)
	ds_write_b128 v165, v[122:125] offset:18432
	s_waitcnt vmcnt(14)
	ds_write_b128 v165, v[126:129] offset:23040
	s_waitcnt lgkmcnt(5)
	v_mfma_f32_16x16x32_bf16 v[18:21], v[220:223], v[228:231], v[18:21]
	v_mfma_f32_16x16x32_bf16 v[22:25], v[220:223], v[236:239], v[22:25]
	v_mfma_f32_16x16x32_bf16 v[2:5], v[220:223], v[240:243], v[2:5]
	v_mfma_f32_16x16x32_bf16 v[6:9], v[220:223], v[252:255], v[6:9]
	ds_read_b128 v[220:223], v244 offset:4672
	s_waitcnt vmcnt(13)
	ds_write_b128 v165, v[136:139] offset:27648
	s_waitcnt vmcnt(12)
	ds_write_b128 v165, v[140:143] offset:32256
	s_waitcnt lgkmcnt(7)
	v_mfma_f32_16x16x32_bf16 v[26:29], v[224:227], v[228:231], v[26:29]
	ds_read_b128 v[228:231], v245 offset:36928
	v_mfma_f32_16x16x32_bf16 v[30:33], v[224:227], v[236:239], v[30:33]
	ds_read_b128 v[236:239], v245 offset:39232
	v_mfma_f32_16x16x32_bf16 v[10:13], v[224:227], v[240:243], v[10:13]
	ds_read_b128 v[240:243], v245 offset:41536
	v_mfma_f32_16x16x32_bf16 v[14:17], v[224:227], v[252:255], v[14:17]
	ds_read_b128 v[252:255], v245 offset:43840
	ds_read_b128 v[224:227], v244 offset:6976
	s_waitcnt lgkmcnt(4)
	v_mfma_f32_16x16x32_bf16 v[50:53], v[212:215], v[228:231], v[50:53]
	s_waitcnt lgkmcnt(3)
	v_mfma_f32_16x16x32_bf16 v[54:57], v[212:215], v[236:239], v[54:57]
	s_waitcnt lgkmcnt(2)
	v_mfma_f32_16x16x32_bf16 v[34:37], v[212:215], v[240:243], v[34:37]
	s_waitcnt lgkmcnt(1)
	v_mfma_f32_16x16x32_bf16 v[38:41], v[212:215], v[252:255], v[38:41]
	s_waitcnt vmcnt(11)
	ds_write_b128 v165, v[144:147] offset:55296
	s_waitcnt vmcnt(10)
	ds_write_b128 v165, v[148:151] offset:59904
	v_mfma_f32_16x16x32_bf16 v[58:61], v[216:219], v[228:231], v[58:61]
	v_mfma_f32_16x16x32_bf16 v[62:65], v[216:219], v[236:239], v[62:65]
	v_mfma_f32_16x16x32_bf16 v[42:45], v[216:219], v[240:243], v[42:45]
	v_mfma_f32_16x16x32_bf16 v[46:49], v[216:219], v[252:255], v[46:49]
	s_waitcnt vmcnt(9)
	ds_write_b128 v165, v[172:175] offset:64512
	s_waitcnt vmcnt(8)
	ds_write_b128 v166, v[176:179] offset:32256
	v_mfma_f32_16x16x32_bf16 v[18:21], v[220:223], v[228:231], v[18:21]
	v_mfma_f32_16x16x32_bf16 v[22:25], v[220:223], v[236:239], v[22:25]
	v_mfma_f32_16x16x32_bf16 v[2:5], v[220:223], v[240:243], v[2:5]
	v_mfma_f32_16x16x32_bf16 v[6:9], v[220:223], v[252:255], v[6:9]
	s_waitcnt lgkmcnt(4)
	v_mfma_f32_16x16x32_bf16 v[26:29], v[224:227], v[228:231], v[26:29]
	v_mfma_f32_16x16x32_bf16 v[30:33], v[224:227], v[236:239], v[30:33]
	v_mfma_f32_16x16x32_bf16 v[10:13], v[224:227], v[240:243], v[10:13]
	v_mfma_f32_16x16x32_bf16 v[14:17], v[224:227], v[252:255], v[14:17]
	s_waitcnt lgkmcnt(0)
	s_barrier
	s_setprio 0
	global_load_dwordx4 v[122:125], v[72:73], off offset:640
	global_load_dwordx4 v[126:129], v[74:75], off offset:640
	global_load_dwordx4 v[136:139], v[76:77], off offset:640
	global_load_dwordx4 v[140:143], v[78:79], off offset:640
	global_load_dwordx4 v[144:147], v[70:71], off offset:640
	global_load_dwordx4 v[148:151], v[68:69], off offset:640
	global_load_dwordx4 v[172:175], v[66:67], off offset:640
	global_load_dwordx4 v[176:179], v[80:81], off offset:640
	ds_read_b128 v[228:231], v245 offset:55296
	ds_read_b128 v[212:215], v244 offset:18432
	ds_read_b128 v[236:239], v245 offset:57600
	ds_read_b128 v[240:243], v245 offset:59904
	ds_read_b128 v[252:255], v245 offset:62208
	ds_read_b128 v[216:219], v244 offset:20736
	ds_read_b128 v[220:223], v244 offset:23040
	ds_read_b128 v[224:227], v244 offset:25344
	s_waitcnt lgkmcnt(6)
	v_mfma_f32_16x16x32_bf16 v[50:53], v[212:215], v[228:231], v[50:53]
	s_waitcnt lgkmcnt(5)
	v_mfma_f32_16x16x32_bf16 v[54:57], v[212:215], v[236:239], v[54:57]
	s_waitcnt lgkmcnt(4)
	v_mfma_f32_16x16x32_bf16 v[34:37], v[212:215], v[240:243], v[34:37]
	s_waitcnt lgkmcnt(3)
	v_mfma_f32_16x16x32_bf16 v[38:41], v[212:215], v[252:255], v[38:41]
	ds_read_b128 v[212:215], v244 offset:18496
	s_waitcnt lgkmcnt(3)
	v_mfma_f32_16x16x32_bf16 v[58:61], v[216:219], v[228:231], v[58:61]
	v_mfma_f32_16x16x32_bf16 v[62:65], v[216:219], v[236:239], v[62:65]
	v_mfma_f32_16x16x32_bf16 v[42:45], v[216:219], v[240:243], v[42:45]
	v_mfma_f32_16x16x32_bf16 v[46:49], v[216:219], v[252:255], v[46:49]
	ds_read_b128 v[216:219], v244 offset:20800
	s_setprio 1
	s_waitcnt vmcnt(15)
	ds_write_b128 v165, v[180:183]
	s_waitcnt vmcnt(14)
	ds_write_b128 v165, v[184:187] offset:4608
	s_waitcnt lgkmcnt(5)
	v_mfma_f32_16x16x32_bf16 v[18:21], v[220:223], v[228:231], v[18:21]
	v_mfma_f32_16x16x32_bf16 v[22:25], v[220:223], v[236:239], v[22:25]
	v_mfma_f32_16x16x32_bf16 v[2:5], v[220:223], v[240:243], v[2:5]
	v_mfma_f32_16x16x32_bf16 v[6:9], v[220:223], v[252:255], v[6:9]
	ds_read_b128 v[220:223], v244 offset:23104
	s_waitcnt vmcnt(13)
	ds_write_b128 v165, v[188:191] offset:9216
	s_waitcnt vmcnt(12)
	ds_write_b128 v165, v[192:195] offset:13824
	s_waitcnt lgkmcnt(7)
	v_mfma_f32_16x16x32_bf16 v[26:29], v[224:227], v[228:231], v[26:29]
	ds_read_b128 v[228:231], v245 offset:55360
	v_mfma_f32_16x16x32_bf16 v[30:33], v[224:227], v[236:239], v[30:33]
	ds_read_b128 v[236:239], v245 offset:57664
	v_mfma_f32_16x16x32_bf16 v[10:13], v[224:227], v[240:243], v[10:13]
	ds_read_b128 v[240:243], v245 offset:59968
	v_mfma_f32_16x16x32_bf16 v[14:17], v[224:227], v[252:255], v[14:17]
	ds_read_b128 v[252:255], v245 offset:62272
	ds_read_b128 v[224:227], v244 offset:25408
	s_waitcnt lgkmcnt(4)
	v_mfma_f32_16x16x32_bf16 v[50:53], v[212:215], v[228:231], v[50:53]
	s_waitcnt lgkmcnt(3)
	v_mfma_f32_16x16x32_bf16 v[54:57], v[212:215], v[236:239], v[54:57]
	s_waitcnt lgkmcnt(2)
	v_mfma_f32_16x16x32_bf16 v[34:37], v[212:215], v[240:243], v[34:37]
	s_waitcnt lgkmcnt(1)
	v_mfma_f32_16x16x32_bf16 v[38:41], v[212:215], v[252:255], v[38:41]
	s_waitcnt vmcnt(11)
	ds_write_b128 v165, v[196:199] offset:36864
	s_waitcnt vmcnt(10)
	ds_write_b128 v165, v[200:203] offset:41472
	v_mfma_f32_16x16x32_bf16 v[58:61], v[216:219], v[228:231], v[58:61]
	v_mfma_f32_16x16x32_bf16 v[62:65], v[216:219], v[236:239], v[62:65]
	v_mfma_f32_16x16x32_bf16 v[42:45], v[216:219], v[240:243], v[42:45]
	v_mfma_f32_16x16x32_bf16 v[46:49], v[216:219], v[252:255], v[46:49]
	s_waitcnt vmcnt(9)
	ds_write_b128 v165, v[204:207] offset:46080
	s_waitcnt vmcnt(8)
	ds_write_b128 v165, v[208:211] offset:50688
	v_mfma_f32_16x16x32_bf16 v[18:21], v[220:223], v[228:231], v[18:21]
	v_mfma_f32_16x16x32_bf16 v[22:25], v[220:223], v[236:239], v[22:25]
	v_mfma_f32_16x16x32_bf16 v[2:5], v[220:223], v[240:243], v[2:5]
	v_mfma_f32_16x16x32_bf16 v[6:9], v[220:223], v[252:255], v[6:9]
	s_waitcnt lgkmcnt(4)
	v_mfma_f32_16x16x32_bf16 v[26:29], v[224:227], v[228:231], v[26:29]
	v_mfma_f32_16x16x32_bf16 v[30:33], v[224:227], v[236:239], v[30:33]
	v_mfma_f32_16x16x32_bf16 v[10:13], v[224:227], v[240:243], v[10:13]
	v_mfma_f32_16x16x32_bf16 v[14:17], v[224:227], v[252:255], v[14:17]
	s_waitcnt lgkmcnt(0)
	s_barrier
	s_setprio 0
	global_load_dwordx4 v[180:183], v[72:73], off offset:768
	global_load_dwordx4 v[184:187], v[74:75], off offset:768
	global_load_dwordx4 v[188:191], v[76:77], off offset:768
	global_load_dwordx4 v[192:195], v[78:79], off offset:768
	global_load_dwordx4 v[196:199], v[70:71], off offset:768
	global_load_dwordx4 v[200:203], v[68:69], off offset:768
	global_load_dwordx4 v[204:207], v[66:67], off offset:768
	global_load_dwordx4 v[208:211], v[80:81], off offset:768
	ds_read_b128 v[228:231], v245 offset:36864
	ds_read_b128 v[212:215], v244
	ds_read_b128 v[236:239], v245 offset:39168
	ds_read_b128 v[240:243], v245 offset:41472
	ds_read_b128 v[252:255], v245 offset:43776
	ds_read_b128 v[216:219], v244 offset:2304
	ds_read_b128 v[220:223], v244 offset:4608
	ds_read_b128 v[224:227], v244 offset:6912
	s_waitcnt lgkmcnt(6)
	v_mfma_f32_16x16x32_bf16 v[50:53], v[212:215], v[228:231], v[50:53]
	s_waitcnt lgkmcnt(5)
	v_mfma_f32_16x16x32_bf16 v[54:57], v[212:215], v[236:239], v[54:57]
	s_waitcnt lgkmcnt(4)
	v_mfma_f32_16x16x32_bf16 v[34:37], v[212:215], v[240:243], v[34:37]
	s_waitcnt lgkmcnt(3)
	v_mfma_f32_16x16x32_bf16 v[38:41], v[212:215], v[252:255], v[38:41]
	ds_read_b128 v[212:215], v244 offset:64
	s_waitcnt lgkmcnt(3)
	v_mfma_f32_16x16x32_bf16 v[58:61], v[216:219], v[228:231], v[58:61]
	v_mfma_f32_16x16x32_bf16 v[62:65], v[216:219], v[236:239], v[62:65]
	v_mfma_f32_16x16x32_bf16 v[42:45], v[216:219], v[240:243], v[42:45]
	v_mfma_f32_16x16x32_bf16 v[46:49], v[216:219], v[252:255], v[46:49]
	ds_read_b128 v[216:219], v244 offset:2368
	s_setprio 1
	s_waitcnt vmcnt(15)
	ds_write_b128 v165, v[122:125] offset:18432
	s_waitcnt vmcnt(14)
	ds_write_b128 v165, v[126:129] offset:23040
	s_waitcnt lgkmcnt(5)
	v_mfma_f32_16x16x32_bf16 v[18:21], v[220:223], v[228:231], v[18:21]
	v_mfma_f32_16x16x32_bf16 v[22:25], v[220:223], v[236:239], v[22:25]
	v_mfma_f32_16x16x32_bf16 v[2:5], v[220:223], v[240:243], v[2:5]
	v_mfma_f32_16x16x32_bf16 v[6:9], v[220:223], v[252:255], v[6:9]
	ds_read_b128 v[220:223], v244 offset:4672
	s_waitcnt vmcnt(13)
	ds_write_b128 v165, v[136:139] offset:27648
	s_waitcnt vmcnt(12)
	ds_write_b128 v165, v[140:143] offset:32256
	s_waitcnt lgkmcnt(7)
	v_mfma_f32_16x16x32_bf16 v[26:29], v[224:227], v[228:231], v[26:29]
	ds_read_b128 v[228:231], v245 offset:36928
	v_mfma_f32_16x16x32_bf16 v[30:33], v[224:227], v[236:239], v[30:33]
	ds_read_b128 v[236:239], v245 offset:39232
	v_mfma_f32_16x16x32_bf16 v[10:13], v[224:227], v[240:243], v[10:13]
	ds_read_b128 v[240:243], v245 offset:41536
	v_mfma_f32_16x16x32_bf16 v[14:17], v[224:227], v[252:255], v[14:17]
	ds_read_b128 v[252:255], v245 offset:43840
	ds_read_b128 v[224:227], v244 offset:6976
	s_waitcnt lgkmcnt(4)
	v_mfma_f32_16x16x32_bf16 v[50:53], v[212:215], v[228:231], v[50:53]
	s_waitcnt lgkmcnt(3)
	v_mfma_f32_16x16x32_bf16 v[54:57], v[212:215], v[236:239], v[54:57]
	s_waitcnt lgkmcnt(2)
	v_mfma_f32_16x16x32_bf16 v[34:37], v[212:215], v[240:243], v[34:37]
	s_waitcnt lgkmcnt(1)
	v_mfma_f32_16x16x32_bf16 v[38:41], v[212:215], v[252:255], v[38:41]
	s_waitcnt vmcnt(11)
	ds_write_b128 v165, v[144:147] offset:55296
	s_waitcnt vmcnt(10)
	ds_write_b128 v165, v[148:151] offset:59904
	v_mfma_f32_16x16x32_bf16 v[58:61], v[216:219], v[228:231], v[58:61]
	v_mfma_f32_16x16x32_bf16 v[62:65], v[216:219], v[236:239], v[62:65]
	v_mfma_f32_16x16x32_bf16 v[42:45], v[216:219], v[240:243], v[42:45]
	v_mfma_f32_16x16x32_bf16 v[46:49], v[216:219], v[252:255], v[46:49]
	s_waitcnt vmcnt(9)
	ds_write_b128 v165, v[172:175] offset:64512
	s_waitcnt vmcnt(8)
	ds_write_b128 v166, v[176:179] offset:32256
	v_mfma_f32_16x16x32_bf16 v[18:21], v[220:223], v[228:231], v[18:21]
	v_mfma_f32_16x16x32_bf16 v[22:25], v[220:223], v[236:239], v[22:25]
	v_mfma_f32_16x16x32_bf16 v[2:5], v[220:223], v[240:243], v[2:5]
	v_mfma_f32_16x16x32_bf16 v[6:9], v[220:223], v[252:255], v[6:9]
	s_waitcnt lgkmcnt(4)
	v_mfma_f32_16x16x32_bf16 v[26:29], v[224:227], v[228:231], v[26:29]
	v_mfma_f32_16x16x32_bf16 v[30:33], v[224:227], v[236:239], v[30:33]
	v_mfma_f32_16x16x32_bf16 v[10:13], v[224:227], v[240:243], v[10:13]
	v_mfma_f32_16x16x32_bf16 v[14:17], v[224:227], v[252:255], v[14:17]
	s_waitcnt lgkmcnt(0)
	s_barrier
	s_setprio 0
	global_load_dwordx4 v[122:125], v[72:73], off offset:896
	global_load_dwordx4 v[126:129], v[74:75], off offset:896
	global_load_dwordx4 v[136:139], v[76:77], off offset:896
	global_load_dwordx4 v[140:143], v[78:79], off offset:896
	global_load_dwordx4 v[144:147], v[70:71], off offset:896
	global_load_dwordx4 v[148:151], v[68:69], off offset:896
	global_load_dwordx4 v[172:175], v[66:67], off offset:896
	global_load_dwordx4 v[176:179], v[80:81], off offset:896
	ds_read_b128 v[228:231], v245 offset:55296
	ds_read_b128 v[212:215], v244 offset:18432
	ds_read_b128 v[236:239], v245 offset:57600
	ds_read_b128 v[240:243], v245 offset:59904
	ds_read_b128 v[252:255], v245 offset:62208
	ds_read_b128 v[216:219], v244 offset:20736
	ds_read_b128 v[220:223], v244 offset:23040
	ds_read_b128 v[224:227], v244 offset:25344
	s_waitcnt lgkmcnt(6)
	v_mfma_f32_16x16x32_bf16 v[50:53], v[212:215], v[228:231], v[50:53]
	s_waitcnt lgkmcnt(5)
	v_mfma_f32_16x16x32_bf16 v[54:57], v[212:215], v[236:239], v[54:57]
	s_waitcnt lgkmcnt(4)
	v_mfma_f32_16x16x32_bf16 v[34:37], v[212:215], v[240:243], v[34:37]
	s_waitcnt lgkmcnt(3)
	v_mfma_f32_16x16x32_bf16 v[38:41], v[212:215], v[252:255], v[38:41]
	ds_read_b128 v[212:215], v244 offset:18496
	s_waitcnt lgkmcnt(3)
	v_mfma_f32_16x16x32_bf16 v[58:61], v[216:219], v[228:231], v[58:61]
	v_mfma_f32_16x16x32_bf16 v[62:65], v[216:219], v[236:239], v[62:65]
	v_mfma_f32_16x16x32_bf16 v[42:45], v[216:219], v[240:243], v[42:45]
	v_mfma_f32_16x16x32_bf16 v[46:49], v[216:219], v[252:255], v[46:49]
	ds_read_b128 v[216:219], v244 offset:20800
	s_setprio 1
	s_waitcnt vmcnt(15)
	ds_write_b128 v165, v[180:183]
	s_waitcnt vmcnt(14)
	ds_write_b128 v165, v[184:187] offset:4608
	s_waitcnt lgkmcnt(5)
	v_mfma_f32_16x16x32_bf16 v[18:21], v[220:223], v[228:231], v[18:21]
	v_mfma_f32_16x16x32_bf16 v[22:25], v[220:223], v[236:239], v[22:25]
	v_mfma_f32_16x16x32_bf16 v[2:5], v[220:223], v[240:243], v[2:5]
	v_mfma_f32_16x16x32_bf16 v[6:9], v[220:223], v[252:255], v[6:9]
	ds_read_b128 v[220:223], v244 offset:23104
	s_waitcnt vmcnt(13)
	ds_write_b128 v165, v[188:191] offset:9216
	s_waitcnt vmcnt(12)
	ds_write_b128 v165, v[192:195] offset:13824
	s_waitcnt lgkmcnt(7)
	v_mfma_f32_16x16x32_bf16 v[26:29], v[224:227], v[228:231], v[26:29]
	ds_read_b128 v[228:231], v245 offset:55360
	v_mfma_f32_16x16x32_bf16 v[30:33], v[224:227], v[236:239], v[30:33]
	ds_read_b128 v[236:239], v245 offset:57664
	v_mfma_f32_16x16x32_bf16 v[10:13], v[224:227], v[240:243], v[10:13]
	ds_read_b128 v[240:243], v245 offset:59968
	v_mfma_f32_16x16x32_bf16 v[14:17], v[224:227], v[252:255], v[14:17]
	ds_read_b128 v[252:255], v245 offset:62272
	ds_read_b128 v[224:227], v244 offset:25408
	s_waitcnt lgkmcnt(4)
	v_mfma_f32_16x16x32_bf16 v[50:53], v[212:215], v[228:231], v[50:53]
	s_waitcnt lgkmcnt(3)
	v_mfma_f32_16x16x32_bf16 v[54:57], v[212:215], v[236:239], v[54:57]
	s_waitcnt lgkmcnt(2)
	v_mfma_f32_16x16x32_bf16 v[34:37], v[212:215], v[240:243], v[34:37]
	s_waitcnt lgkmcnt(1)
	v_mfma_f32_16x16x32_bf16 v[38:41], v[212:215], v[252:255], v[38:41]
	s_waitcnt vmcnt(11)
	ds_write_b128 v165, v[196:199] offset:36864
	s_waitcnt vmcnt(10)
	ds_write_b128 v165, v[200:203] offset:41472
	v_mfma_f32_16x16x32_bf16 v[58:61], v[216:219], v[228:231], v[58:61]
	v_mfma_f32_16x16x32_bf16 v[62:65], v[216:219], v[236:239], v[62:65]
	v_mfma_f32_16x16x32_bf16 v[42:45], v[216:219], v[240:243], v[42:45]
	v_mfma_f32_16x16x32_bf16 v[46:49], v[216:219], v[252:255], v[46:49]
	s_waitcnt vmcnt(9)
	ds_write_b128 v165, v[204:207] offset:46080
	s_waitcnt vmcnt(8)
	ds_write_b128 v165, v[208:211] offset:50688
	v_mfma_f32_16x16x32_bf16 v[18:21], v[220:223], v[228:231], v[18:21]
	v_mfma_f32_16x16x32_bf16 v[22:25], v[220:223], v[236:239], v[22:25]
	v_mfma_f32_16x16x32_bf16 v[2:5], v[220:223], v[240:243], v[2:5]
	v_mfma_f32_16x16x32_bf16 v[6:9], v[220:223], v[252:255], v[6:9]
	s_waitcnt lgkmcnt(4)
	v_mfma_f32_16x16x32_bf16 v[26:29], v[224:227], v[228:231], v[26:29]
	v_mfma_f32_16x16x32_bf16 v[30:33], v[224:227], v[236:239], v[30:33]
	v_mfma_f32_16x16x32_bf16 v[10:13], v[224:227], v[240:243], v[10:13]
	v_mfma_f32_16x16x32_bf16 v[14:17], v[224:227], v[252:255], v[14:17]
	s_waitcnt lgkmcnt(0)
	s_barrier
	s_setprio 0
	global_load_dwordx4 v[180:183], v[72:73], off offset:1024
	global_load_dwordx4 v[184:187], v[74:75], off offset:1024
	global_load_dwordx4 v[188:191], v[76:77], off offset:1024
	global_load_dwordx4 v[192:195], v[78:79], off offset:1024
	global_load_dwordx4 v[196:199], v[70:71], off offset:1024
	global_load_dwordx4 v[200:203], v[68:69], off offset:1024
	global_load_dwordx4 v[204:207], v[66:67], off offset:1024
	global_load_dwordx4 v[208:211], v[80:81], off offset:1024
	ds_read_b128 v[228:231], v245 offset:36864
	ds_read_b128 v[212:215], v244
	ds_read_b128 v[236:239], v245 offset:39168
	ds_read_b128 v[240:243], v245 offset:41472
	ds_read_b128 v[252:255], v245 offset:43776
	ds_read_b128 v[216:219], v244 offset:2304
	ds_read_b128 v[220:223], v244 offset:4608
	ds_read_b128 v[224:227], v244 offset:6912
	s_waitcnt lgkmcnt(6)
	v_mfma_f32_16x16x32_bf16 v[50:53], v[212:215], v[228:231], v[50:53]
	s_waitcnt lgkmcnt(5)
	v_mfma_f32_16x16x32_bf16 v[54:57], v[212:215], v[236:239], v[54:57]
	s_waitcnt lgkmcnt(4)
	v_mfma_f32_16x16x32_bf16 v[34:37], v[212:215], v[240:243], v[34:37]
	s_waitcnt lgkmcnt(3)
	v_mfma_f32_16x16x32_bf16 v[38:41], v[212:215], v[252:255], v[38:41]
	ds_read_b128 v[212:215], v244 offset:64
	s_waitcnt lgkmcnt(3)
	v_mfma_f32_16x16x32_bf16 v[58:61], v[216:219], v[228:231], v[58:61]
	v_mfma_f32_16x16x32_bf16 v[62:65], v[216:219], v[236:239], v[62:65]
	v_mfma_f32_16x16x32_bf16 v[42:45], v[216:219], v[240:243], v[42:45]
	v_mfma_f32_16x16x32_bf16 v[46:49], v[216:219], v[252:255], v[46:49]
	ds_read_b128 v[216:219], v244 offset:2368
	s_setprio 1
	s_waitcnt vmcnt(15)
	ds_write_b128 v165, v[122:125] offset:18432
	s_waitcnt vmcnt(14)
	ds_write_b128 v165, v[126:129] offset:23040
	s_waitcnt lgkmcnt(5)
	v_mfma_f32_16x16x32_bf16 v[18:21], v[220:223], v[228:231], v[18:21]
	v_mfma_f32_16x16x32_bf16 v[22:25], v[220:223], v[236:239], v[22:25]
	v_mfma_f32_16x16x32_bf16 v[2:5], v[220:223], v[240:243], v[2:5]
	v_mfma_f32_16x16x32_bf16 v[6:9], v[220:223], v[252:255], v[6:9]
	ds_read_b128 v[220:223], v244 offset:4672
	s_waitcnt vmcnt(13)
	ds_write_b128 v165, v[136:139] offset:27648
	s_waitcnt vmcnt(12)
	ds_write_b128 v165, v[140:143] offset:32256
	s_waitcnt lgkmcnt(7)
	v_mfma_f32_16x16x32_bf16 v[26:29], v[224:227], v[228:231], v[26:29]
	ds_read_b128 v[228:231], v245 offset:36928
	v_mfma_f32_16x16x32_bf16 v[30:33], v[224:227], v[236:239], v[30:33]
	ds_read_b128 v[236:239], v245 offset:39232
	v_mfma_f32_16x16x32_bf16 v[10:13], v[224:227], v[240:243], v[10:13]
	ds_read_b128 v[240:243], v245 offset:41536
	v_mfma_f32_16x16x32_bf16 v[14:17], v[224:227], v[252:255], v[14:17]
	ds_read_b128 v[252:255], v245 offset:43840
	ds_read_b128 v[224:227], v244 offset:6976
	s_waitcnt lgkmcnt(4)
	v_mfma_f32_16x16x32_bf16 v[50:53], v[212:215], v[228:231], v[50:53]
	s_waitcnt lgkmcnt(3)
	v_mfma_f32_16x16x32_bf16 v[54:57], v[212:215], v[236:239], v[54:57]
	s_waitcnt lgkmcnt(2)
	v_mfma_f32_16x16x32_bf16 v[34:37], v[212:215], v[240:243], v[34:37]
	s_waitcnt lgkmcnt(1)
	v_mfma_f32_16x16x32_bf16 v[38:41], v[212:215], v[252:255], v[38:41]
	s_waitcnt vmcnt(11)
	ds_write_b128 v165, v[144:147] offset:55296
	s_waitcnt vmcnt(10)
	ds_write_b128 v165, v[148:151] offset:59904
	v_mfma_f32_16x16x32_bf16 v[58:61], v[216:219], v[228:231], v[58:61]
	v_mfma_f32_16x16x32_bf16 v[62:65], v[216:219], v[236:239], v[62:65]
	v_mfma_f32_16x16x32_bf16 v[42:45], v[216:219], v[240:243], v[42:45]
	v_mfma_f32_16x16x32_bf16 v[46:49], v[216:219], v[252:255], v[46:49]
	s_waitcnt vmcnt(9)
	ds_write_b128 v165, v[172:175] offset:64512
	s_waitcnt vmcnt(8)
	ds_write_b128 v166, v[176:179] offset:32256
	v_mfma_f32_16x16x32_bf16 v[18:21], v[220:223], v[228:231], v[18:21]
	v_mfma_f32_16x16x32_bf16 v[22:25], v[220:223], v[236:239], v[22:25]
	v_mfma_f32_16x16x32_bf16 v[2:5], v[220:223], v[240:243], v[2:5]
	v_mfma_f32_16x16x32_bf16 v[6:9], v[220:223], v[252:255], v[6:9]
	s_waitcnt lgkmcnt(4)
	v_mfma_f32_16x16x32_bf16 v[26:29], v[224:227], v[228:231], v[26:29]
	v_mfma_f32_16x16x32_bf16 v[30:33], v[224:227], v[236:239], v[30:33]
	v_mfma_f32_16x16x32_bf16 v[10:13], v[224:227], v[240:243], v[10:13]
	v_mfma_f32_16x16x32_bf16 v[14:17], v[224:227], v[252:255], v[14:17]
	s_waitcnt lgkmcnt(0)
	s_barrier
	s_setprio 0
	global_load_dwordx4 v[122:125], v[72:73], off offset:1152
	global_load_dwordx4 v[126:129], v[74:75], off offset:1152
	global_load_dwordx4 v[136:139], v[76:77], off offset:1152
	global_load_dwordx4 v[140:143], v[78:79], off offset:1152
	global_load_dwordx4 v[144:147], v[70:71], off offset:1152
	global_load_dwordx4 v[148:151], v[68:69], off offset:1152
	global_load_dwordx4 v[172:175], v[66:67], off offset:1152
	global_load_dwordx4 v[176:179], v[80:81], off offset:1152
	ds_read_b128 v[228:231], v245 offset:55296
	ds_read_b128 v[212:215], v244 offset:18432
	ds_read_b128 v[236:239], v245 offset:57600
	ds_read_b128 v[240:243], v245 offset:59904
	ds_read_b128 v[252:255], v245 offset:62208
	ds_read_b128 v[216:219], v244 offset:20736
	ds_read_b128 v[220:223], v244 offset:23040
	ds_read_b128 v[224:227], v244 offset:25344
	s_waitcnt lgkmcnt(6)
	v_mfma_f32_16x16x32_bf16 v[50:53], v[212:215], v[228:231], v[50:53]
	s_waitcnt lgkmcnt(5)
	v_mfma_f32_16x16x32_bf16 v[54:57], v[212:215], v[236:239], v[54:57]
	s_waitcnt lgkmcnt(4)
	v_mfma_f32_16x16x32_bf16 v[34:37], v[212:215], v[240:243], v[34:37]
	s_waitcnt lgkmcnt(3)
	v_mfma_f32_16x16x32_bf16 v[38:41], v[212:215], v[252:255], v[38:41]
	ds_read_b128 v[212:215], v244 offset:18496
	s_waitcnt lgkmcnt(3)
	v_mfma_f32_16x16x32_bf16 v[58:61], v[216:219], v[228:231], v[58:61]
	v_mfma_f32_16x16x32_bf16 v[62:65], v[216:219], v[236:239], v[62:65]
	v_mfma_f32_16x16x32_bf16 v[42:45], v[216:219], v[240:243], v[42:45]
	v_mfma_f32_16x16x32_bf16 v[46:49], v[216:219], v[252:255], v[46:49]
	ds_read_b128 v[216:219], v244 offset:20800
	s_setprio 1
	s_waitcnt vmcnt(15)
	ds_write_b128 v165, v[180:183]
	s_waitcnt vmcnt(14)
	ds_write_b128 v165, v[184:187] offset:4608
	s_waitcnt lgkmcnt(5)
	v_mfma_f32_16x16x32_bf16 v[18:21], v[220:223], v[228:231], v[18:21]
	v_mfma_f32_16x16x32_bf16 v[22:25], v[220:223], v[236:239], v[22:25]
	v_mfma_f32_16x16x32_bf16 v[2:5], v[220:223], v[240:243], v[2:5]
	v_mfma_f32_16x16x32_bf16 v[6:9], v[220:223], v[252:255], v[6:9]
	ds_read_b128 v[220:223], v244 offset:23104
	s_waitcnt vmcnt(13)
	ds_write_b128 v165, v[188:191] offset:9216
	s_waitcnt vmcnt(12)
	ds_write_b128 v165, v[192:195] offset:13824
	s_waitcnt lgkmcnt(7)
	v_mfma_f32_16x16x32_bf16 v[26:29], v[224:227], v[228:231], v[26:29]
	ds_read_b128 v[228:231], v245 offset:55360
	v_mfma_f32_16x16x32_bf16 v[30:33], v[224:227], v[236:239], v[30:33]
	ds_read_b128 v[236:239], v245 offset:57664
	v_mfma_f32_16x16x32_bf16 v[10:13], v[224:227], v[240:243], v[10:13]
	ds_read_b128 v[240:243], v245 offset:59968
	v_mfma_f32_16x16x32_bf16 v[14:17], v[224:227], v[252:255], v[14:17]
	ds_read_b128 v[252:255], v245 offset:62272
	ds_read_b128 v[224:227], v244 offset:25408
	s_waitcnt lgkmcnt(4)
	v_mfma_f32_16x16x32_bf16 v[50:53], v[212:215], v[228:231], v[50:53]
	s_waitcnt lgkmcnt(3)
	v_mfma_f32_16x16x32_bf16 v[54:57], v[212:215], v[236:239], v[54:57]
	s_waitcnt lgkmcnt(2)
	v_mfma_f32_16x16x32_bf16 v[34:37], v[212:215], v[240:243], v[34:37]
	s_waitcnt lgkmcnt(1)
	v_mfma_f32_16x16x32_bf16 v[38:41], v[212:215], v[252:255], v[38:41]
	s_waitcnt vmcnt(11)
	ds_write_b128 v165, v[196:199] offset:36864
	s_waitcnt vmcnt(10)
	ds_write_b128 v165, v[200:203] offset:41472
	v_mfma_f32_16x16x32_bf16 v[58:61], v[216:219], v[228:231], v[58:61]
	v_mfma_f32_16x16x32_bf16 v[62:65], v[216:219], v[236:239], v[62:65]
	v_mfma_f32_16x16x32_bf16 v[42:45], v[216:219], v[240:243], v[42:45]
	v_mfma_f32_16x16x32_bf16 v[46:49], v[216:219], v[252:255], v[46:49]
	s_waitcnt vmcnt(9)
	ds_write_b128 v165, v[204:207] offset:46080
	s_waitcnt vmcnt(8)
	ds_write_b128 v165, v[208:211] offset:50688
	v_mfma_f32_16x16x32_bf16 v[18:21], v[220:223], v[228:231], v[18:21]
	v_mfma_f32_16x16x32_bf16 v[22:25], v[220:223], v[236:239], v[22:25]
	v_mfma_f32_16x16x32_bf16 v[2:5], v[220:223], v[240:243], v[2:5]
	v_mfma_f32_16x16x32_bf16 v[6:9], v[220:223], v[252:255], v[6:9]
	s_waitcnt lgkmcnt(4)
	v_mfma_f32_16x16x32_bf16 v[26:29], v[224:227], v[228:231], v[26:29]
	v_mfma_f32_16x16x32_bf16 v[30:33], v[224:227], v[236:239], v[30:33]
	v_mfma_f32_16x16x32_bf16 v[10:13], v[224:227], v[240:243], v[10:13]
	v_mfma_f32_16x16x32_bf16 v[14:17], v[224:227], v[252:255], v[14:17]
	s_waitcnt lgkmcnt(0)
	s_barrier
	s_setprio 0
	global_load_dwordx4 v[180:183], v[72:73], off offset:1280
	global_load_dwordx4 v[184:187], v[74:75], off offset:1280
	global_load_dwordx4 v[188:191], v[76:77], off offset:1280
	global_load_dwordx4 v[192:195], v[78:79], off offset:1280
	global_load_dwordx4 v[196:199], v[70:71], off offset:1280
	global_load_dwordx4 v[200:203], v[68:69], off offset:1280
	global_load_dwordx4 v[204:207], v[66:67], off offset:1280
	global_load_dwordx4 v[208:211], v[80:81], off offset:1280
	ds_read_b128 v[228:231], v245 offset:36864
	ds_read_b128 v[212:215], v244
	ds_read_b128 v[236:239], v245 offset:39168
	ds_read_b128 v[240:243], v245 offset:41472
	ds_read_b128 v[252:255], v245 offset:43776
	ds_read_b128 v[216:219], v244 offset:2304
	ds_read_b128 v[220:223], v244 offset:4608
	ds_read_b128 v[224:227], v244 offset:6912
	s_waitcnt lgkmcnt(6)
	v_mfma_f32_16x16x32_bf16 v[50:53], v[212:215], v[228:231], v[50:53]
	s_waitcnt lgkmcnt(5)
	v_mfma_f32_16x16x32_bf16 v[54:57], v[212:215], v[236:239], v[54:57]
	s_waitcnt lgkmcnt(4)
	v_mfma_f32_16x16x32_bf16 v[34:37], v[212:215], v[240:243], v[34:37]
	s_waitcnt lgkmcnt(3)
	v_mfma_f32_16x16x32_bf16 v[38:41], v[212:215], v[252:255], v[38:41]
	ds_read_b128 v[212:215], v244 offset:64
	s_waitcnt lgkmcnt(3)
	v_mfma_f32_16x16x32_bf16 v[58:61], v[216:219], v[228:231], v[58:61]
	v_mfma_f32_16x16x32_bf16 v[62:65], v[216:219], v[236:239], v[62:65]
	v_mfma_f32_16x16x32_bf16 v[42:45], v[216:219], v[240:243], v[42:45]
	v_mfma_f32_16x16x32_bf16 v[46:49], v[216:219], v[252:255], v[46:49]
	ds_read_b128 v[216:219], v244 offset:2368
	s_setprio 1
	s_waitcnt vmcnt(15)
	ds_write_b128 v165, v[122:125] offset:18432
	s_waitcnt vmcnt(14)
	ds_write_b128 v165, v[126:129] offset:23040
	s_waitcnt lgkmcnt(5)
	v_mfma_f32_16x16x32_bf16 v[18:21], v[220:223], v[228:231], v[18:21]
	v_mfma_f32_16x16x32_bf16 v[22:25], v[220:223], v[236:239], v[22:25]
	v_mfma_f32_16x16x32_bf16 v[2:5], v[220:223], v[240:243], v[2:5]
	v_mfma_f32_16x16x32_bf16 v[6:9], v[220:223], v[252:255], v[6:9]
	ds_read_b128 v[220:223], v244 offset:4672
	s_waitcnt vmcnt(13)
	ds_write_b128 v165, v[136:139] offset:27648
	s_waitcnt vmcnt(12)
	ds_write_b128 v165, v[140:143] offset:32256
	s_waitcnt lgkmcnt(7)
	v_mfma_f32_16x16x32_bf16 v[26:29], v[224:227], v[228:231], v[26:29]
	ds_read_b128 v[228:231], v245 offset:36928
	v_mfma_f32_16x16x32_bf16 v[30:33], v[224:227], v[236:239], v[30:33]
	ds_read_b128 v[236:239], v245 offset:39232
	v_mfma_f32_16x16x32_bf16 v[10:13], v[224:227], v[240:243], v[10:13]
	ds_read_b128 v[240:243], v245 offset:41536
	v_mfma_f32_16x16x32_bf16 v[14:17], v[224:227], v[252:255], v[14:17]
	ds_read_b128 v[252:255], v245 offset:43840
	ds_read_b128 v[224:227], v244 offset:6976
	s_waitcnt lgkmcnt(4)
	v_mfma_f32_16x16x32_bf16 v[50:53], v[212:215], v[228:231], v[50:53]
	s_waitcnt lgkmcnt(3)
	v_mfma_f32_16x16x32_bf16 v[54:57], v[212:215], v[236:239], v[54:57]
	s_waitcnt lgkmcnt(2)
	v_mfma_f32_16x16x32_bf16 v[34:37], v[212:215], v[240:243], v[34:37]
	s_waitcnt lgkmcnt(1)
	v_mfma_f32_16x16x32_bf16 v[38:41], v[212:215], v[252:255], v[38:41]
	s_waitcnt vmcnt(11)
	ds_write_b128 v165, v[144:147] offset:55296
	s_waitcnt vmcnt(10)
	ds_write_b128 v165, v[148:151] offset:59904
	v_mfma_f32_16x16x32_bf16 v[58:61], v[216:219], v[228:231], v[58:61]
	v_mfma_f32_16x16x32_bf16 v[62:65], v[216:219], v[236:239], v[62:65]
	v_mfma_f32_16x16x32_bf16 v[42:45], v[216:219], v[240:243], v[42:45]
	v_mfma_f32_16x16x32_bf16 v[46:49], v[216:219], v[252:255], v[46:49]
	s_waitcnt vmcnt(9)
	ds_write_b128 v165, v[172:175] offset:64512
	s_waitcnt vmcnt(8)
	ds_write_b128 v166, v[176:179] offset:32256
	v_mfma_f32_16x16x32_bf16 v[18:21], v[220:223], v[228:231], v[18:21]
	v_mfma_f32_16x16x32_bf16 v[22:25], v[220:223], v[236:239], v[22:25]
	v_mfma_f32_16x16x32_bf16 v[2:5], v[220:223], v[240:243], v[2:5]
	v_mfma_f32_16x16x32_bf16 v[6:9], v[220:223], v[252:255], v[6:9]
	s_waitcnt lgkmcnt(4)
	v_mfma_f32_16x16x32_bf16 v[26:29], v[224:227], v[228:231], v[26:29]
	v_mfma_f32_16x16x32_bf16 v[30:33], v[224:227], v[236:239], v[30:33]
	v_mfma_f32_16x16x32_bf16 v[10:13], v[224:227], v[240:243], v[10:13]
	v_mfma_f32_16x16x32_bf16 v[14:17], v[224:227], v[252:255], v[14:17]
	s_waitcnt lgkmcnt(0)
	s_barrier
	s_setprio 0
	global_load_dwordx4 v[122:125], v[72:73], off offset:1408
	global_load_dwordx4 v[126:129], v[74:75], off offset:1408
	global_load_dwordx4 v[136:139], v[76:77], off offset:1408
	global_load_dwordx4 v[140:143], v[78:79], off offset:1408
	global_load_dwordx4 v[144:147], v[70:71], off offset:1408
	global_load_dwordx4 v[148:151], v[68:69], off offset:1408
	global_load_dwordx4 v[172:175], v[66:67], off offset:1408
	global_load_dwordx4 v[176:179], v[80:81], off offset:1408
	ds_read_b128 v[228:231], v245 offset:55296
	ds_read_b128 v[212:215], v244 offset:18432
	ds_read_b128 v[236:239], v245 offset:57600
	ds_read_b128 v[240:243], v245 offset:59904
	ds_read_b128 v[252:255], v245 offset:62208
	ds_read_b128 v[216:219], v244 offset:20736
	ds_read_b128 v[220:223], v244 offset:23040
	ds_read_b128 v[224:227], v244 offset:25344
	s_waitcnt lgkmcnt(6)
	v_mfma_f32_16x16x32_bf16 v[50:53], v[212:215], v[228:231], v[50:53]
	s_waitcnt lgkmcnt(5)
	v_mfma_f32_16x16x32_bf16 v[54:57], v[212:215], v[236:239], v[54:57]
	s_waitcnt lgkmcnt(4)
	v_mfma_f32_16x16x32_bf16 v[34:37], v[212:215], v[240:243], v[34:37]
	s_waitcnt lgkmcnt(3)
	v_mfma_f32_16x16x32_bf16 v[38:41], v[212:215], v[252:255], v[38:41]
	ds_read_b128 v[212:215], v244 offset:18496
	s_waitcnt lgkmcnt(3)
	v_mfma_f32_16x16x32_bf16 v[58:61], v[216:219], v[228:231], v[58:61]
	v_mfma_f32_16x16x32_bf16 v[62:65], v[216:219], v[236:239], v[62:65]
	v_mfma_f32_16x16x32_bf16 v[42:45], v[216:219], v[240:243], v[42:45]
	v_mfma_f32_16x16x32_bf16 v[46:49], v[216:219], v[252:255], v[46:49]
	ds_read_b128 v[216:219], v244 offset:20800
	s_setprio 1
	s_waitcnt vmcnt(15)
	ds_write_b128 v165, v[180:183]
	s_waitcnt vmcnt(14)
	ds_write_b128 v165, v[184:187] offset:4608
	s_waitcnt lgkmcnt(5)
	v_mfma_f32_16x16x32_bf16 v[18:21], v[220:223], v[228:231], v[18:21]
	v_mfma_f32_16x16x32_bf16 v[22:25], v[220:223], v[236:239], v[22:25]
	v_mfma_f32_16x16x32_bf16 v[2:5], v[220:223], v[240:243], v[2:5]
	v_mfma_f32_16x16x32_bf16 v[6:9], v[220:223], v[252:255], v[6:9]
	ds_read_b128 v[220:223], v244 offset:23104
	s_waitcnt vmcnt(13)
	ds_write_b128 v165, v[188:191] offset:9216
	s_waitcnt vmcnt(12)
	ds_write_b128 v165, v[192:195] offset:13824
	s_waitcnt lgkmcnt(7)
	v_mfma_f32_16x16x32_bf16 v[26:29], v[224:227], v[228:231], v[26:29]
	ds_read_b128 v[228:231], v245 offset:55360
	v_mfma_f32_16x16x32_bf16 v[30:33], v[224:227], v[236:239], v[30:33]
	ds_read_b128 v[236:239], v245 offset:57664
	v_mfma_f32_16x16x32_bf16 v[10:13], v[224:227], v[240:243], v[10:13]
	ds_read_b128 v[240:243], v245 offset:59968
	v_mfma_f32_16x16x32_bf16 v[14:17], v[224:227], v[252:255], v[14:17]
	ds_read_b128 v[252:255], v245 offset:62272
	ds_read_b128 v[224:227], v244 offset:25408
	s_waitcnt lgkmcnt(4)
	v_mfma_f32_16x16x32_bf16 v[50:53], v[212:215], v[228:231], v[50:53]
	s_waitcnt lgkmcnt(3)
	v_mfma_f32_16x16x32_bf16 v[54:57], v[212:215], v[236:239], v[54:57]
	s_waitcnt lgkmcnt(2)
	v_mfma_f32_16x16x32_bf16 v[34:37], v[212:215], v[240:243], v[34:37]
	s_waitcnt lgkmcnt(1)
	v_mfma_f32_16x16x32_bf16 v[38:41], v[212:215], v[252:255], v[38:41]
	s_waitcnt vmcnt(11)
	ds_write_b128 v165, v[196:199] offset:36864
	s_waitcnt vmcnt(10)
	ds_write_b128 v165, v[200:203] offset:41472
	v_mfma_f32_16x16x32_bf16 v[58:61], v[216:219], v[228:231], v[58:61]
	v_mfma_f32_16x16x32_bf16 v[62:65], v[216:219], v[236:239], v[62:65]
	v_mfma_f32_16x16x32_bf16 v[42:45], v[216:219], v[240:243], v[42:45]
	v_mfma_f32_16x16x32_bf16 v[46:49], v[216:219], v[252:255], v[46:49]
	s_waitcnt vmcnt(9)
	ds_write_b128 v165, v[204:207] offset:46080
	s_waitcnt vmcnt(8)
	ds_write_b128 v165, v[208:211] offset:50688
	v_mfma_f32_16x16x32_bf16 v[18:21], v[220:223], v[228:231], v[18:21]
	v_mfma_f32_16x16x32_bf16 v[22:25], v[220:223], v[236:239], v[22:25]
	v_mfma_f32_16x16x32_bf16 v[2:5], v[220:223], v[240:243], v[2:5]
	v_mfma_f32_16x16x32_bf16 v[6:9], v[220:223], v[252:255], v[6:9]
	s_waitcnt lgkmcnt(4)
	v_mfma_f32_16x16x32_bf16 v[26:29], v[224:227], v[228:231], v[26:29]
	v_mfma_f32_16x16x32_bf16 v[30:33], v[224:227], v[236:239], v[30:33]
	v_mfma_f32_16x16x32_bf16 v[10:13], v[224:227], v[240:243], v[10:13]
	v_mfma_f32_16x16x32_bf16 v[14:17], v[224:227], v[252:255], v[14:17]
	s_waitcnt lgkmcnt(0)
	s_barrier
	s_setprio 0
	global_load_dwordx4 v[180:183], v[72:73], off offset:1536
	global_load_dwordx4 v[184:187], v[74:75], off offset:1536
	global_load_dwordx4 v[188:191], v[76:77], off offset:1536
	global_load_dwordx4 v[192:195], v[78:79], off offset:1536
	global_load_dwordx4 v[196:199], v[70:71], off offset:1536
	global_load_dwordx4 v[200:203], v[68:69], off offset:1536
	global_load_dwordx4 v[204:207], v[66:67], off offset:1536
	global_load_dwordx4 v[208:211], v[80:81], off offset:1536
	ds_read_b128 v[228:231], v245 offset:36864
	ds_read_b128 v[212:215], v244
	ds_read_b128 v[236:239], v245 offset:39168
	ds_read_b128 v[240:243], v245 offset:41472
	ds_read_b128 v[252:255], v245 offset:43776
	ds_read_b128 v[216:219], v244 offset:2304
	ds_read_b128 v[220:223], v244 offset:4608
	ds_read_b128 v[224:227], v244 offset:6912
	s_waitcnt lgkmcnt(6)
	v_mfma_f32_16x16x32_bf16 v[50:53], v[212:215], v[228:231], v[50:53]
	s_waitcnt lgkmcnt(5)
	v_mfma_f32_16x16x32_bf16 v[54:57], v[212:215], v[236:239], v[54:57]
	s_waitcnt lgkmcnt(4)
	v_mfma_f32_16x16x32_bf16 v[34:37], v[212:215], v[240:243], v[34:37]
	s_waitcnt lgkmcnt(3)
	v_mfma_f32_16x16x32_bf16 v[38:41], v[212:215], v[252:255], v[38:41]
	ds_read_b128 v[212:215], v244 offset:64
	s_waitcnt lgkmcnt(3)
	v_mfma_f32_16x16x32_bf16 v[58:61], v[216:219], v[228:231], v[58:61]
	v_mfma_f32_16x16x32_bf16 v[62:65], v[216:219], v[236:239], v[62:65]
	v_mfma_f32_16x16x32_bf16 v[42:45], v[216:219], v[240:243], v[42:45]
	v_mfma_f32_16x16x32_bf16 v[46:49], v[216:219], v[252:255], v[46:49]
	ds_read_b128 v[216:219], v244 offset:2368
	s_setprio 1
	s_waitcnt vmcnt(15)
	ds_write_b128 v165, v[122:125] offset:18432
	s_waitcnt vmcnt(14)
	ds_write_b128 v165, v[126:129] offset:23040
	s_waitcnt lgkmcnt(5)
	v_mfma_f32_16x16x32_bf16 v[18:21], v[220:223], v[228:231], v[18:21]
	v_mfma_f32_16x16x32_bf16 v[22:25], v[220:223], v[236:239], v[22:25]
	v_mfma_f32_16x16x32_bf16 v[2:5], v[220:223], v[240:243], v[2:5]
	v_mfma_f32_16x16x32_bf16 v[6:9], v[220:223], v[252:255], v[6:9]
	ds_read_b128 v[220:223], v244 offset:4672
	s_waitcnt vmcnt(13)
	ds_write_b128 v165, v[136:139] offset:27648
	s_waitcnt vmcnt(12)
	ds_write_b128 v165, v[140:143] offset:32256
	s_waitcnt lgkmcnt(7)
	v_mfma_f32_16x16x32_bf16 v[26:29], v[224:227], v[228:231], v[26:29]
	ds_read_b128 v[228:231], v245 offset:36928
	v_mfma_f32_16x16x32_bf16 v[30:33], v[224:227], v[236:239], v[30:33]
	ds_read_b128 v[236:239], v245 offset:39232
	v_mfma_f32_16x16x32_bf16 v[10:13], v[224:227], v[240:243], v[10:13]
	ds_read_b128 v[240:243], v245 offset:41536
	v_mfma_f32_16x16x32_bf16 v[14:17], v[224:227], v[252:255], v[14:17]
	ds_read_b128 v[252:255], v245 offset:43840
	ds_read_b128 v[224:227], v244 offset:6976
	s_waitcnt lgkmcnt(4)
	v_mfma_f32_16x16x32_bf16 v[50:53], v[212:215], v[228:231], v[50:53]
	s_waitcnt lgkmcnt(3)
	v_mfma_f32_16x16x32_bf16 v[54:57], v[212:215], v[236:239], v[54:57]
	s_waitcnt lgkmcnt(2)
	v_mfma_f32_16x16x32_bf16 v[34:37], v[212:215], v[240:243], v[34:37]
	s_waitcnt lgkmcnt(1)
	v_mfma_f32_16x16x32_bf16 v[38:41], v[212:215], v[252:255], v[38:41]
	s_waitcnt vmcnt(11)
	ds_write_b128 v165, v[144:147] offset:55296
	s_waitcnt vmcnt(10)
	ds_write_b128 v165, v[148:151] offset:59904
	v_mfma_f32_16x16x32_bf16 v[58:61], v[216:219], v[228:231], v[58:61]
	v_mfma_f32_16x16x32_bf16 v[62:65], v[216:219], v[236:239], v[62:65]
	v_mfma_f32_16x16x32_bf16 v[42:45], v[216:219], v[240:243], v[42:45]
	v_mfma_f32_16x16x32_bf16 v[46:49], v[216:219], v[252:255], v[46:49]
	s_waitcnt vmcnt(9)
	ds_write_b128 v165, v[172:175] offset:64512
	s_waitcnt vmcnt(8)
	ds_write_b128 v166, v[176:179] offset:32256
	v_mfma_f32_16x16x32_bf16 v[18:21], v[220:223], v[228:231], v[18:21]
	v_mfma_f32_16x16x32_bf16 v[22:25], v[220:223], v[236:239], v[22:25]
	v_mfma_f32_16x16x32_bf16 v[2:5], v[220:223], v[240:243], v[2:5]
	v_mfma_f32_16x16x32_bf16 v[6:9], v[220:223], v[252:255], v[6:9]
	s_waitcnt lgkmcnt(4)
	v_mfma_f32_16x16x32_bf16 v[26:29], v[224:227], v[228:231], v[26:29]
	v_mfma_f32_16x16x32_bf16 v[30:33], v[224:227], v[236:239], v[30:33]
	v_mfma_f32_16x16x32_bf16 v[10:13], v[224:227], v[240:243], v[10:13]
	v_mfma_f32_16x16x32_bf16 v[14:17], v[224:227], v[252:255], v[14:17]
	s_waitcnt lgkmcnt(0)
	s_barrier
	s_setprio 0
	global_load_dwordx4 v[122:125], v[72:73], off offset:1664
	global_load_dwordx4 v[126:129], v[74:75], off offset:1664
	global_load_dwordx4 v[136:139], v[76:77], off offset:1664
	global_load_dwordx4 v[140:143], v[78:79], off offset:1664
	global_load_dwordx4 v[144:147], v[70:71], off offset:1664
	global_load_dwordx4 v[148:151], v[68:69], off offset:1664
	global_load_dwordx4 v[172:175], v[66:67], off offset:1664
	global_load_dwordx4 v[176:179], v[80:81], off offset:1664
	ds_read_b128 v[228:231], v245 offset:55296
	ds_read_b128 v[212:215], v244 offset:18432
	ds_read_b128 v[236:239], v245 offset:57600
	ds_read_b128 v[240:243], v245 offset:59904
	ds_read_b128 v[252:255], v245 offset:62208
	ds_read_b128 v[216:219], v244 offset:20736
	ds_read_b128 v[220:223], v244 offset:23040
	ds_read_b128 v[224:227], v244 offset:25344
	s_waitcnt lgkmcnt(6)
	v_mfma_f32_16x16x32_bf16 v[50:53], v[212:215], v[228:231], v[50:53]
	s_waitcnt lgkmcnt(5)
	v_mfma_f32_16x16x32_bf16 v[54:57], v[212:215], v[236:239], v[54:57]
	s_waitcnt lgkmcnt(4)
	v_mfma_f32_16x16x32_bf16 v[34:37], v[212:215], v[240:243], v[34:37]
	s_waitcnt lgkmcnt(3)
	v_mfma_f32_16x16x32_bf16 v[38:41], v[212:215], v[252:255], v[38:41]
	ds_read_b128 v[212:215], v244 offset:18496
	s_waitcnt lgkmcnt(3)
	v_mfma_f32_16x16x32_bf16 v[58:61], v[216:219], v[228:231], v[58:61]
	v_mfma_f32_16x16x32_bf16 v[62:65], v[216:219], v[236:239], v[62:65]
	v_mfma_f32_16x16x32_bf16 v[42:45], v[216:219], v[240:243], v[42:45]
	v_mfma_f32_16x16x32_bf16 v[46:49], v[216:219], v[252:255], v[46:49]
	ds_read_b128 v[216:219], v244 offset:20800
	s_setprio 1
	s_waitcnt vmcnt(15)
	ds_write_b128 v165, v[180:183]
	s_waitcnt vmcnt(14)
	ds_write_b128 v165, v[184:187] offset:4608
	s_waitcnt lgkmcnt(5)
	v_mfma_f32_16x16x32_bf16 v[18:21], v[220:223], v[228:231], v[18:21]
	v_mfma_f32_16x16x32_bf16 v[22:25], v[220:223], v[236:239], v[22:25]
	v_mfma_f32_16x16x32_bf16 v[2:5], v[220:223], v[240:243], v[2:5]
	v_mfma_f32_16x16x32_bf16 v[6:9], v[220:223], v[252:255], v[6:9]
	ds_read_b128 v[220:223], v244 offset:23104
	s_waitcnt vmcnt(13)
	ds_write_b128 v165, v[188:191] offset:9216
	s_waitcnt vmcnt(12)
	ds_write_b128 v165, v[192:195] offset:13824
	s_waitcnt lgkmcnt(7)
	v_mfma_f32_16x16x32_bf16 v[26:29], v[224:227], v[228:231], v[26:29]
	ds_read_b128 v[228:231], v245 offset:55360
	v_mfma_f32_16x16x32_bf16 v[30:33], v[224:227], v[236:239], v[30:33]
	ds_read_b128 v[236:239], v245 offset:57664
	v_mfma_f32_16x16x32_bf16 v[10:13], v[224:227], v[240:243], v[10:13]
	ds_read_b128 v[240:243], v245 offset:59968
	v_mfma_f32_16x16x32_bf16 v[14:17], v[224:227], v[252:255], v[14:17]
	ds_read_b128 v[252:255], v245 offset:62272
	ds_read_b128 v[224:227], v244 offset:25408
	s_waitcnt lgkmcnt(4)
	v_mfma_f32_16x16x32_bf16 v[50:53], v[212:215], v[228:231], v[50:53]
	s_waitcnt lgkmcnt(3)
	v_mfma_f32_16x16x32_bf16 v[54:57], v[212:215], v[236:239], v[54:57]
	s_waitcnt lgkmcnt(2)
	v_mfma_f32_16x16x32_bf16 v[34:37], v[212:215], v[240:243], v[34:37]
	s_waitcnt lgkmcnt(1)
	v_mfma_f32_16x16x32_bf16 v[38:41], v[212:215], v[252:255], v[38:41]
	s_waitcnt vmcnt(11)
	ds_write_b128 v165, v[196:199] offset:36864
	s_waitcnt vmcnt(10)
	ds_write_b128 v165, v[200:203] offset:41472
	v_mfma_f32_16x16x32_bf16 v[58:61], v[216:219], v[228:231], v[58:61]
	v_mfma_f32_16x16x32_bf16 v[62:65], v[216:219], v[236:239], v[62:65]
	v_mfma_f32_16x16x32_bf16 v[42:45], v[216:219], v[240:243], v[42:45]
	v_mfma_f32_16x16x32_bf16 v[46:49], v[216:219], v[252:255], v[46:49]
	s_waitcnt vmcnt(9)
	ds_write_b128 v165, v[204:207] offset:46080
	s_waitcnt vmcnt(8)
	ds_write_b128 v165, v[208:211] offset:50688
	v_mfma_f32_16x16x32_bf16 v[18:21], v[220:223], v[228:231], v[18:21]
	v_mfma_f32_16x16x32_bf16 v[22:25], v[220:223], v[236:239], v[22:25]
	v_mfma_f32_16x16x32_bf16 v[2:5], v[220:223], v[240:243], v[2:5]
	v_mfma_f32_16x16x32_bf16 v[6:9], v[220:223], v[252:255], v[6:9]
	s_waitcnt lgkmcnt(4)
	v_mfma_f32_16x16x32_bf16 v[26:29], v[224:227], v[228:231], v[26:29]
	v_mfma_f32_16x16x32_bf16 v[30:33], v[224:227], v[236:239], v[30:33]
	v_mfma_f32_16x16x32_bf16 v[10:13], v[224:227], v[240:243], v[10:13]
	v_mfma_f32_16x16x32_bf16 v[14:17], v[224:227], v[252:255], v[14:17]
	s_waitcnt lgkmcnt(0)
	s_barrier
	s_setprio 0
	global_load_dwordx4 v[180:183], v[72:73], off offset:1792
	global_load_dwordx4 v[184:187], v[74:75], off offset:1792
	global_load_dwordx4 v[188:191], v[76:77], off offset:1792
	global_load_dwordx4 v[192:195], v[78:79], off offset:1792
	global_load_dwordx4 v[196:199], v[70:71], off offset:1792
	global_load_dwordx4 v[200:203], v[68:69], off offset:1792
	global_load_dwordx4 v[204:207], v[66:67], off offset:1792
	global_load_dwordx4 v[208:211], v[80:81], off offset:1792
	ds_read_b128 v[228:231], v245 offset:36864
	ds_read_b128 v[212:215], v244
	ds_read_b128 v[236:239], v245 offset:39168
	ds_read_b128 v[240:243], v245 offset:41472
	ds_read_b128 v[252:255], v245 offset:43776
	ds_read_b128 v[216:219], v244 offset:2304
	ds_read_b128 v[220:223], v244 offset:4608
	ds_read_b128 v[224:227], v244 offset:6912
	s_waitcnt lgkmcnt(6)
	v_mfma_f32_16x16x32_bf16 v[50:53], v[212:215], v[228:231], v[50:53]
	s_waitcnt lgkmcnt(5)
	v_mfma_f32_16x16x32_bf16 v[54:57], v[212:215], v[236:239], v[54:57]
	s_waitcnt lgkmcnt(4)
	v_mfma_f32_16x16x32_bf16 v[34:37], v[212:215], v[240:243], v[34:37]
	s_waitcnt lgkmcnt(3)
	v_mfma_f32_16x16x32_bf16 v[38:41], v[212:215], v[252:255], v[38:41]
	ds_read_b128 v[212:215], v244 offset:64
	s_waitcnt lgkmcnt(3)
	v_mfma_f32_16x16x32_bf16 v[58:61], v[216:219], v[228:231], v[58:61]
	v_mfma_f32_16x16x32_bf16 v[62:65], v[216:219], v[236:239], v[62:65]
	v_mfma_f32_16x16x32_bf16 v[42:45], v[216:219], v[240:243], v[42:45]
	v_mfma_f32_16x16x32_bf16 v[46:49], v[216:219], v[252:255], v[46:49]
	ds_read_b128 v[216:219], v244 offset:2368
	s_setprio 1
	s_waitcnt vmcnt(15)
	ds_write_b128 v165, v[122:125] offset:18432
	s_waitcnt vmcnt(14)
	ds_write_b128 v165, v[126:129] offset:23040
	s_waitcnt lgkmcnt(5)
	v_mfma_f32_16x16x32_bf16 v[18:21], v[220:223], v[228:231], v[18:21]
	v_mfma_f32_16x16x32_bf16 v[22:25], v[220:223], v[236:239], v[22:25]
	v_mfma_f32_16x16x32_bf16 v[2:5], v[220:223], v[240:243], v[2:5]
	v_mfma_f32_16x16x32_bf16 v[6:9], v[220:223], v[252:255], v[6:9]
	ds_read_b128 v[220:223], v244 offset:4672
	s_waitcnt vmcnt(13)
	ds_write_b128 v165, v[136:139] offset:27648
	s_waitcnt vmcnt(12)
	ds_write_b128 v165, v[140:143] offset:32256
	s_waitcnt lgkmcnt(7)
	v_mfma_f32_16x16x32_bf16 v[26:29], v[224:227], v[228:231], v[26:29]
	ds_read_b128 v[228:231], v245 offset:36928
	v_mfma_f32_16x16x32_bf16 v[30:33], v[224:227], v[236:239], v[30:33]
	ds_read_b128 v[236:239], v245 offset:39232
	v_mfma_f32_16x16x32_bf16 v[10:13], v[224:227], v[240:243], v[10:13]
	ds_read_b128 v[240:243], v245 offset:41536
	v_mfma_f32_16x16x32_bf16 v[14:17], v[224:227], v[252:255], v[14:17]
	ds_read_b128 v[252:255], v245 offset:43840
	ds_read_b128 v[224:227], v244 offset:6976
	s_waitcnt lgkmcnt(4)
	v_mfma_f32_16x16x32_bf16 v[50:53], v[212:215], v[228:231], v[50:53]
	s_waitcnt lgkmcnt(3)
	v_mfma_f32_16x16x32_bf16 v[54:57], v[212:215], v[236:239], v[54:57]
	s_waitcnt lgkmcnt(2)
	v_mfma_f32_16x16x32_bf16 v[34:37], v[212:215], v[240:243], v[34:37]
	s_waitcnt lgkmcnt(1)
	v_mfma_f32_16x16x32_bf16 v[38:41], v[212:215], v[252:255], v[38:41]
	s_waitcnt vmcnt(11)
	ds_write_b128 v165, v[144:147] offset:55296
	s_waitcnt vmcnt(10)
	ds_write_b128 v165, v[148:151] offset:59904
	v_mfma_f32_16x16x32_bf16 v[58:61], v[216:219], v[228:231], v[58:61]
	v_mfma_f32_16x16x32_bf16 v[62:65], v[216:219], v[236:239], v[62:65]
	v_mfma_f32_16x16x32_bf16 v[42:45], v[216:219], v[240:243], v[42:45]
	v_mfma_f32_16x16x32_bf16 v[46:49], v[216:219], v[252:255], v[46:49]
	s_waitcnt vmcnt(9)
	ds_write_b128 v165, v[172:175] offset:64512
	s_waitcnt vmcnt(8)
	ds_write_b128 v166, v[176:179] offset:32256
	v_mfma_f32_16x16x32_bf16 v[18:21], v[220:223], v[228:231], v[18:21]
	v_mfma_f32_16x16x32_bf16 v[22:25], v[220:223], v[236:239], v[22:25]
	v_mfma_f32_16x16x32_bf16 v[2:5], v[220:223], v[240:243], v[2:5]
	v_mfma_f32_16x16x32_bf16 v[6:9], v[220:223], v[252:255], v[6:9]
	s_waitcnt lgkmcnt(4)
	v_mfma_f32_16x16x32_bf16 v[26:29], v[224:227], v[228:231], v[26:29]
	v_mfma_f32_16x16x32_bf16 v[30:33], v[224:227], v[236:239], v[30:33]
	v_mfma_f32_16x16x32_bf16 v[10:13], v[224:227], v[240:243], v[10:13]
	v_mfma_f32_16x16x32_bf16 v[14:17], v[224:227], v[252:255], v[14:17]
	s_waitcnt lgkmcnt(0)
	s_barrier
	s_setprio 0
	global_load_dwordx4 v[122:125], v[72:73], off offset:1920
	s_nop 0
	global_load_dwordx4 v[72:75], v[74:75], off offset:1920
	s_nop 0
	global_load_dwordx4 v[126:129], v[76:77], off offset:1920
	s_nop 0
	global_load_dwordx4 v[76:79], v[78:79], off offset:1920
	s_nop 0
	global_load_dwordx4 v[136:139], v[70:71], off offset:1920
	s_nop 0
	global_load_dwordx4 v[68:71], v[68:69], off offset:1920
	s_nop 0
	global_load_dwordx4 v[140:143], v[66:67], off offset:1920
	global_load_dwordx4 v[144:147], v[80:81], off offset:1920
	ds_read_b128 v[228:231], v245 offset:55296
	ds_read_b128 v[212:215], v244 offset:18432
	ds_read_b128 v[236:239], v245 offset:57600
	ds_read_b128 v[240:243], v245 offset:59904
	ds_read_b128 v[252:255], v245 offset:62208
	ds_read_b128 v[216:219], v244 offset:20736
	ds_read_b128 v[220:223], v244 offset:23040
	ds_read_b128 v[224:227], v244 offset:25344
	s_waitcnt lgkmcnt(6)
	v_mfma_f32_16x16x32_bf16 v[50:53], v[212:215], v[228:231], v[50:53]
	s_waitcnt lgkmcnt(5)
	v_mfma_f32_16x16x32_bf16 v[54:57], v[212:215], v[236:239], v[54:57]
	s_waitcnt lgkmcnt(4)
	v_mfma_f32_16x16x32_bf16 v[34:37], v[212:215], v[240:243], v[34:37]
	s_waitcnt lgkmcnt(3)
	v_mfma_f32_16x16x32_bf16 v[38:41], v[212:215], v[252:255], v[38:41]
	ds_read_b128 v[212:215], v244 offset:18496
	s_waitcnt lgkmcnt(3)
	v_mfma_f32_16x16x32_bf16 v[58:61], v[216:219], v[228:231], v[58:61]
	v_mfma_f32_16x16x32_bf16 v[62:65], v[216:219], v[236:239], v[62:65]
	v_mfma_f32_16x16x32_bf16 v[42:45], v[216:219], v[240:243], v[42:45]
	v_mfma_f32_16x16x32_bf16 v[46:49], v[216:219], v[252:255], v[46:49]
	ds_read_b128 v[216:219], v244 offset:20800
	s_setprio 1
	s_waitcnt vmcnt(15)
	ds_write_b128 v165, v[180:183]
	s_waitcnt vmcnt(14)
	ds_write_b128 v165, v[184:187] offset:4608
	s_waitcnt lgkmcnt(5)
	v_mfma_f32_16x16x32_bf16 v[18:21], v[220:223], v[228:231], v[18:21]
	v_mfma_f32_16x16x32_bf16 v[22:25], v[220:223], v[236:239], v[22:25]
	v_mfma_f32_16x16x32_bf16 v[2:5], v[220:223], v[240:243], v[2:5]
	v_mfma_f32_16x16x32_bf16 v[6:9], v[220:223], v[252:255], v[6:9]
	ds_read_b128 v[220:223], v244 offset:23104
	s_waitcnt vmcnt(13)
	ds_write_b128 v165, v[188:191] offset:9216
	s_waitcnt vmcnt(12)
	ds_write_b128 v165, v[192:195] offset:13824
	s_waitcnt lgkmcnt(7)
	v_mfma_f32_16x16x32_bf16 v[26:29], v[224:227], v[228:231], v[26:29]
	ds_read_b128 v[228:231], v245 offset:55360
	v_mfma_f32_16x16x32_bf16 v[30:33], v[224:227], v[236:239], v[30:33]
	ds_read_b128 v[236:239], v245 offset:57664
	v_mfma_f32_16x16x32_bf16 v[10:13], v[224:227], v[240:243], v[10:13]
	ds_read_b128 v[240:243], v245 offset:59968
	v_mfma_f32_16x16x32_bf16 v[14:17], v[224:227], v[252:255], v[14:17]
	ds_read_b128 v[252:255], v245 offset:62272
	ds_read_b128 v[224:227], v244 offset:25408
	s_waitcnt lgkmcnt(4)
	v_mfma_f32_16x16x32_bf16 v[50:53], v[212:215], v[228:231], v[50:53]
	s_waitcnt lgkmcnt(3)
	v_mfma_f32_16x16x32_bf16 v[54:57], v[212:215], v[236:239], v[54:57]
	s_waitcnt lgkmcnt(2)
	v_mfma_f32_16x16x32_bf16 v[34:37], v[212:215], v[240:243], v[34:37]
	s_waitcnt lgkmcnt(1)
	v_mfma_f32_16x16x32_bf16 v[38:41], v[212:215], v[252:255], v[38:41]
	s_waitcnt vmcnt(11)
	ds_write_b128 v165, v[196:199] offset:36864
	s_waitcnt vmcnt(10)
	ds_write_b128 v165, v[200:203] offset:41472
	v_mfma_f32_16x16x32_bf16 v[58:61], v[216:219], v[228:231], v[58:61]
	v_mfma_f32_16x16x32_bf16 v[62:65], v[216:219], v[236:239], v[62:65]
	v_mfma_f32_16x16x32_bf16 v[42:45], v[216:219], v[240:243], v[42:45]
	v_mfma_f32_16x16x32_bf16 v[46:49], v[216:219], v[252:255], v[46:49]
	s_waitcnt vmcnt(9)
	ds_write_b128 v165, v[204:207] offset:46080
	s_waitcnt vmcnt(8)
	ds_write_b128 v165, v[208:211] offset:50688
	v_mfma_f32_16x16x32_bf16 v[18:21], v[220:223], v[228:231], v[18:21]
	v_mfma_f32_16x16x32_bf16 v[22:25], v[220:223], v[236:239], v[22:25]
	v_mfma_f32_16x16x32_bf16 v[2:5], v[220:223], v[240:243], v[2:5]
	v_mfma_f32_16x16x32_bf16 v[6:9], v[220:223], v[252:255], v[6:9]
	s_waitcnt lgkmcnt(4)
	v_mfma_f32_16x16x32_bf16 v[26:29], v[224:227], v[228:231], v[26:29]
	v_mfma_f32_16x16x32_bf16 v[30:33], v[224:227], v[236:239], v[30:33]
	v_mfma_f32_16x16x32_bf16 v[10:13], v[224:227], v[240:243], v[10:13]
	v_mfma_f32_16x16x32_bf16 v[14:17], v[224:227], v[252:255], v[14:17]
	s_waitcnt lgkmcnt(0)
	s_barrier
	s_setprio 0
	ds_read_b128 v[228:231], v245 offset:36864
	ds_read_b128 v[212:215], v244
	ds_read_b128 v[236:239], v245 offset:39168
	ds_read_b128 v[240:243], v245 offset:41472
	ds_read_b128 v[252:255], v245 offset:43776
	ds_read_b128 v[216:219], v244 offset:2304
	ds_read_b128 v[220:223], v244 offset:4608
	ds_read_b128 v[224:227], v244 offset:6912
	s_waitcnt lgkmcnt(6)
	v_mfma_f32_16x16x32_bf16 v[50:53], v[212:215], v[228:231], v[50:53]
	s_waitcnt lgkmcnt(5)
	v_mfma_f32_16x16x32_bf16 v[54:57], v[212:215], v[236:239], v[54:57]
	s_waitcnt lgkmcnt(4)
	v_mfma_f32_16x16x32_bf16 v[34:37], v[212:215], v[240:243], v[34:37]
	s_waitcnt lgkmcnt(3)
	v_mfma_f32_16x16x32_bf16 v[38:41], v[212:215], v[252:255], v[38:41]
	ds_read_b128 v[212:215], v244 offset:64
	s_waitcnt lgkmcnt(3)
	v_mfma_f32_16x16x32_bf16 v[58:61], v[216:219], v[228:231], v[58:61]
	v_mfma_f32_16x16x32_bf16 v[62:65], v[216:219], v[236:239], v[62:65]
	v_mfma_f32_16x16x32_bf16 v[42:45], v[216:219], v[240:243], v[42:45]
	v_mfma_f32_16x16x32_bf16 v[46:49], v[216:219], v[252:255], v[46:49]
	ds_read_b128 v[216:219], v244 offset:2368
	s_setprio 1
	s_waitcnt vmcnt(7)
	ds_write_b128 v165, v[122:125] offset:18432
	s_waitcnt vmcnt(6)
	ds_write_b128 v165, v[72:75] offset:23040
	s_waitcnt lgkmcnt(5)
	v_mfma_f32_16x16x32_bf16 v[18:21], v[220:223], v[228:231], v[18:21]
	v_mfma_f32_16x16x32_bf16 v[22:25], v[220:223], v[236:239], v[22:25]
	v_mfma_f32_16x16x32_bf16 v[2:5], v[220:223], v[240:243], v[2:5]
	v_mfma_f32_16x16x32_bf16 v[6:9], v[220:223], v[252:255], v[6:9]
	ds_read_b128 v[220:223], v244 offset:4672
	s_waitcnt vmcnt(5)
	ds_write_b128 v165, v[126:129] offset:27648
	s_waitcnt vmcnt(4)
	ds_write_b128 v165, v[76:79] offset:32256
	s_waitcnt lgkmcnt(7)
	v_mfma_f32_16x16x32_bf16 v[26:29], v[224:227], v[228:231], v[26:29]
	ds_read_b128 v[228:231], v245 offset:36928
	v_mfma_f32_16x16x32_bf16 v[30:33], v[224:227], v[236:239], v[30:33]
	ds_read_b128 v[236:239], v245 offset:39232
	v_mfma_f32_16x16x32_bf16 v[10:13], v[224:227], v[240:243], v[10:13]
	ds_read_b128 v[240:243], v245 offset:41536
	v_mfma_f32_16x16x32_bf16 v[14:17], v[224:227], v[252:255], v[14:17]
	ds_read_b128 v[252:255], v245 offset:43840
	ds_read_b128 v[224:227], v244 offset:6976
	s_waitcnt lgkmcnt(4)
	v_mfma_f32_16x16x32_bf16 v[50:53], v[212:215], v[228:231], v[50:53]
	s_waitcnt lgkmcnt(3)
	v_mfma_f32_16x16x32_bf16 v[54:57], v[212:215], v[236:239], v[54:57]
	s_waitcnt lgkmcnt(2)
	v_mfma_f32_16x16x32_bf16 v[34:37], v[212:215], v[240:243], v[34:37]
	s_waitcnt lgkmcnt(1)
	v_mfma_f32_16x16x32_bf16 v[38:41], v[212:215], v[252:255], v[38:41]
	s_waitcnt vmcnt(3)
	ds_write_b128 v165, v[136:139] offset:55296
	s_waitcnt vmcnt(2)
	ds_write_b128 v165, v[68:71] offset:59904
	v_mfma_f32_16x16x32_bf16 v[58:61], v[216:219], v[228:231], v[58:61]
	v_mfma_f32_16x16x32_bf16 v[62:65], v[216:219], v[236:239], v[62:65]
	v_mfma_f32_16x16x32_bf16 v[42:45], v[216:219], v[240:243], v[42:45]
	v_mfma_f32_16x16x32_bf16 v[46:49], v[216:219], v[252:255], v[46:49]
	s_waitcnt vmcnt(1)
	ds_write_b128 v165, v[140:143] offset:64512
	s_waitcnt vmcnt(0)
	ds_write_b128 v166, v[144:147] offset:32256
	v_mfma_f32_16x16x32_bf16 v[18:21], v[220:223], v[228:231], v[18:21]
	v_mfma_f32_16x16x32_bf16 v[22:25], v[220:223], v[236:239], v[22:25]
	v_mfma_f32_16x16x32_bf16 v[2:5], v[220:223], v[240:243], v[2:5]
	v_mfma_f32_16x16x32_bf16 v[6:9], v[220:223], v[252:255], v[6:9]
	s_waitcnt lgkmcnt(4)
	v_mfma_f32_16x16x32_bf16 v[26:29], v[224:227], v[228:231], v[26:29]
	v_mfma_f32_16x16x32_bf16 v[30:33], v[224:227], v[236:239], v[30:33]
	v_mfma_f32_16x16x32_bf16 v[10:13], v[224:227], v[240:243], v[10:13]
	v_mfma_f32_16x16x32_bf16 v[14:17], v[224:227], v[252:255], v[14:17]
	s_waitcnt lgkmcnt(0)
	s_barrier
	s_setprio 0
	ds_read_b128 v[228:231], v245 offset:55296
	ds_read_b128 v[212:215], v244 offset:18432
	ds_read_b128 v[236:239], v245 offset:57600
	ds_read_b128 v[240:243], v245 offset:59904
	ds_read_b128 v[252:255], v245 offset:62208
	ds_read_b128 v[216:219], v244 offset:20736
	ds_read_b128 v[220:223], v244 offset:23040
	ds_read_b128 v[224:227], v244 offset:25344
	s_waitcnt lgkmcnt(6)
	v_mfma_f32_16x16x32_bf16 v[50:53], v[212:215], v[228:231], v[50:53]
	s_waitcnt lgkmcnt(5)
	v_mfma_f32_16x16x32_bf16 v[54:57], v[212:215], v[236:239], v[54:57]
	s_waitcnt lgkmcnt(4)
	v_mfma_f32_16x16x32_bf16 v[34:37], v[212:215], v[240:243], v[34:37]
	s_waitcnt lgkmcnt(3)
	v_mfma_f32_16x16x32_bf16 v[38:41], v[212:215], v[252:255], v[38:41]
	ds_read_b128 v[212:215], v244 offset:18496
	s_waitcnt lgkmcnt(3)
	v_mfma_f32_16x16x32_bf16 v[58:61], v[216:219], v[228:231], v[58:61]
	v_mfma_f32_16x16x32_bf16 v[62:65], v[216:219], v[236:239], v[62:65]
	v_mfma_f32_16x16x32_bf16 v[42:45], v[216:219], v[240:243], v[42:45]
	v_mfma_f32_16x16x32_bf16 v[46:49], v[216:219], v[252:255], v[46:49]
	ds_read_b128 v[216:219], v244 offset:20800
	s_waitcnt lgkmcnt(3)
	v_mfma_f32_16x16x32_bf16 v[18:21], v[220:223], v[228:231], v[18:21]
	v_mfma_f32_16x16x32_bf16 v[22:25], v[220:223], v[236:239], v[22:25]
	v_mfma_f32_16x16x32_bf16 v[2:5], v[220:223], v[240:243], v[2:5]
	v_mfma_f32_16x16x32_bf16 v[6:9], v[220:223], v[252:255], v[6:9]
	ds_read_b128 v[220:223], v244 offset:23104
	s_waitcnt lgkmcnt(3)
	v_mfma_f32_16x16x32_bf16 v[26:29], v[224:227], v[228:231], v[26:29]
	ds_read_b128 v[228:231], v245 offset:55360
	v_mfma_f32_16x16x32_bf16 v[30:33], v[224:227], v[236:239], v[30:33]
	ds_read_b128 v[236:239], v245 offset:57664
	v_mfma_f32_16x16x32_bf16 v[10:13], v[224:227], v[240:243], v[10:13]
	ds_read_b128 v[240:243], v245 offset:59968
	v_mfma_f32_16x16x32_bf16 v[14:17], v[224:227], v[252:255], v[14:17]
	ds_read_b128 v[252:255], v245 offset:62272
	ds_read_b128 v[224:227], v244 offset:25408
	s_waitcnt lgkmcnt(4)
	v_mfma_f32_16x16x32_bf16 v[50:53], v[212:215], v[228:231], v[50:53]
	s_waitcnt lgkmcnt(3)
	v_mfma_f32_16x16x32_bf16 v[54:57], v[212:215], v[236:239], v[54:57]
	s_waitcnt lgkmcnt(2)
	v_mfma_f32_16x16x32_bf16 v[34:37], v[212:215], v[240:243], v[34:37]
	s_waitcnt lgkmcnt(1)
	v_mfma_f32_16x16x32_bf16 v[38:41], v[212:215], v[252:255], v[38:41]
	v_mfma_f32_16x16x32_bf16 v[58:61], v[216:219], v[228:231], v[58:61]
	v_mfma_f32_16x16x32_bf16 v[62:65], v[216:219], v[236:239], v[62:65]
	v_mfma_f32_16x16x32_bf16 v[42:45], v[216:219], v[240:243], v[42:45]
	v_mfma_f32_16x16x32_bf16 v[46:49], v[216:219], v[252:255], v[46:49]
	v_mfma_f32_16x16x32_bf16 v[18:21], v[220:223], v[228:231], v[18:21]
	v_mfma_f32_16x16x32_bf16 v[22:25], v[220:223], v[236:239], v[22:25]
	v_mfma_f32_16x16x32_bf16 v[2:5], v[220:223], v[240:243], v[2:5]
	v_mfma_f32_16x16x32_bf16 v[6:9], v[220:223], v[252:255], v[6:9]
	s_waitcnt lgkmcnt(0)
	v_mfma_f32_16x16x32_bf16 v[26:29], v[224:227], v[228:231], v[26:29]
	v_mfma_f32_16x16x32_bf16 v[30:33], v[224:227], v[236:239], v[30:33]
	v_mfma_f32_16x16x32_bf16 v[10:13], v[224:227], v[240:243], v[10:13]
	v_mfma_f32_16x16x32_bf16 v[14:17], v[224:227], v[252:255], v[14:17]
	s_mov_b64 s[2:3], 0
	s_waitcnt lgkmcnt(0)
	s_barrier
	s_nop 7
	v_permlane16_swap_b32_e32 v50, v54
	v_permlane16_swap_b32_e32 v51, v55
	v_permlane16_swap_b32_e32 v52, v56
	v_permlane16_swap_b32_e32 v53, v57
	v_permlane16_swap_b32_e32 v58, v62
	v_permlane16_swap_b32_e32 v59, v63
	v_permlane16_swap_b32_e32 v60, v64
	v_permlane16_swap_b32_e32 v61, v65
	v_permlane16_swap_b32_e32 v34, v38
	v_permlane16_swap_b32_e32 v35, v39
	v_permlane16_swap_b32_e32 v36, v40
	v_permlane16_swap_b32_e32 v37, v41
	v_permlane16_swap_b32_e32 v42, v46
	v_permlane16_swap_b32_e32 v43, v47
	v_permlane16_swap_b32_e32 v44, v48
	v_permlane16_swap_b32_e32 v45, v49
	v_permlane16_swap_b32_e32 v18, v22
	v_permlane16_swap_b32_e32 v19, v23
	v_permlane16_swap_b32_e32 v20, v24
	v_permlane16_swap_b32_e32 v21, v25
	v_permlane16_swap_b32_e32 v26, v30
	v_permlane16_swap_b32_e32 v27, v31
	v_permlane16_swap_b32_e32 v28, v32
	v_permlane16_swap_b32_e32 v29, v33
	v_permlane16_swap_b32_e32 v2, v6
	v_permlane16_swap_b32_e32 v3, v7
	v_permlane16_swap_b32_e32 v4, v8
	v_permlane16_swap_b32_e32 v5, v9
	v_permlane16_swap_b32_e32 v10, v14
	v_permlane16_swap_b32_e32 v11, v15
	v_permlane16_swap_b32_e32 v12, v16
	v_permlane16_swap_b32_e32 v13, v17
	v_permlane32_swap_b32_e32 v50, v54
	v_permlane32_swap_b32_e32 v51, v55
	v_permlane32_swap_b32_e32 v52, v56
	v_permlane32_swap_b32_e32 v53, v57
	v_permlane32_swap_b32_e32 v58, v62
	v_permlane32_swap_b32_e32 v59, v63
	v_permlane32_swap_b32_e32 v60, v64
	v_permlane32_swap_b32_e32 v61, v65
	v_permlane32_swap_b32_e32 v34, v38
	v_permlane32_swap_b32_e32 v35, v39
	v_permlane32_swap_b32_e32 v36, v40
	v_permlane32_swap_b32_e32 v37, v41
	v_permlane32_swap_b32_e32 v42, v46
	v_permlane32_swap_b32_e32 v43, v47
	v_permlane32_swap_b32_e32 v44, v48
	v_permlane32_swap_b32_e32 v45, v49
	v_permlane32_swap_b32_e32 v18, v22
	v_permlane32_swap_b32_e32 v19, v23
	v_permlane32_swap_b32_e32 v20, v24
	v_permlane32_swap_b32_e32 v21, v25
	v_permlane32_swap_b32_e32 v26, v30
	v_permlane32_swap_b32_e32 v27, v31
	v_permlane32_swap_b32_e32 v28, v32
	v_permlane32_swap_b32_e32 v29, v33
	v_permlane32_swap_b32_e32 v2, v6
	v_permlane32_swap_b32_e32 v3, v7
	v_permlane32_swap_b32_e32 v4, v8
	v_permlane32_swap_b32_e32 v5, v9
	v_permlane32_swap_b32_e32 v10, v14
	v_permlane32_swap_b32_e32 v11, v15
	v_permlane32_swap_b32_e32 v12, v16
	v_permlane32_swap_b32_e32 v13, v17

.LBB0_275:
	v_ashrrev_i32_e32 v3, 31, v2
	v_lshlrev_b64 v[2:3], 11, v[2:3]
	v_ashrrev_i32_e32 v9, 31, v8
	v_lshl_add_u64 v[70:71], v[86:87], 0, v[2:3]
	v_lshlrev_b64 v[2:3], 11, v[8:9]
	v_lshl_add_u64 v[72:73], v[86:87], 0, v[2:3]
	v_or_b32_e32 v2, s56, v154
	v_ashrrev_i32_e32 v3, 31, v2
	v_lshlrev_b64 v[2:3], 11, v[2:3]
	v_lshl_add_u64 v[74:75], v[84:85], 0, v[2:3]
	v_add_u32_e32 v2, s56, v155
	v_ashrrev_i32_e32 v3, 31, v2
	v_lshlrev_b64 v[2:3], 11, v[2:3]
	v_lshl_add_u64 v[76:77], v[84:85], 0, v[2:3]
	v_add_u32_e32 v2, s56, v156
	v_ashrrev_i32_e32 v3, 31, v2
	v_lshlrev_b64 v[2:3], 11, v[2:3]
	v_lshl_add_u64 v[78:79], v[84:85], 0, v[2:3]
	v_add_u32_e32 v2, s56, v157
	v_ashrrev_i32_e32 v7, 31, v6
	v_ashrrev_i32_e32 v5, 31, v4
	v_ashrrev_i32_e32 v3, 31, v2
	v_lshlrev_b64 v[6:7], 11, v[6:7]
	v_lshlrev_b64 v[4:5], 11, v[4:5]
	v_lshlrev_b64 v[2:3], 11, v[2:3]
	v_lshl_add_u64 v[66:67], v[86:87], 0, v[6:7]
	v_lshl_add_u64 v[68:69], v[86:87], 0, v[4:5]
	v_lshl_add_u64 v[80:81], v[84:85], 0, v[2:3]
	global_load_dwordx4 v[2:5], v[70:71], off
	global_load_dwordx4 v[6:9], v[68:69], off
	global_load_dwordx4 v[10:13], v[66:67], off
	global_load_dwordx4 v[14:17], v[72:73], off
	global_load_dwordx4 v[18:21], v[74:75], off
	global_load_dwordx4 v[22:25], v[76:77], off
	global_load_dwordx4 v[26:29], v[78:79], off
	global_load_dwordx4 v[30:33], v[80:81], off
	global_load_dwordx4 v[122:125], v[70:71], off offset:128
	global_load_dwordx4 v[126:129], v[68:69], off offset:128
	global_load_dwordx4 v[136:139], v[66:67], off offset:128
	global_load_dwordx4 v[140:143], v[72:73], off offset:128
	global_load_dwordx4 v[144:147], v[74:75], off offset:128
	global_load_dwordx4 v[148:151], v[76:77], off offset:128
	global_load_dwordx4 v[172:175], v[78:79], off offset:128
	global_load_dwordx4 v[176:179], v[80:81], off offset:128
	s_waitcnt vmcnt(15)
	ds_write_b128 v165, v[2:5]
	s_waitcnt vmcnt(14)
	ds_write_b128 v165, v[6:9] offset:4608
	s_waitcnt vmcnt(13)
	ds_write_b128 v165, v[10:13] offset:9216
	s_waitcnt vmcnt(12)
	ds_write_b128 v165, v[14:17] offset:13824
	s_waitcnt vmcnt(11)
	ds_write_b128 v165, v[18:21] offset:36864
	s_waitcnt vmcnt(10)
	ds_write_b128 v165, v[22:25] offset:41472
	s_waitcnt vmcnt(9)
	ds_write_b128 v165, v[26:29] offset:46080
	s_waitcnt vmcnt(8)
	ds_write_b128 v165, v[30:33] offset:50688
	s_waitcnt lgkmcnt(0)
	s_barrier
	global_load_dwordx4 v[180:183], v[68:69], off offset:256
	global_load_dwordx4 v[184:187], v[66:67], off offset:256
	global_load_dwordx4 v[188:191], v[70:71], off offset:256
	global_load_dwordx4 v[192:195], v[72:73], off offset:256
	global_load_dwordx4 v[196:199], v[74:75], off offset:256
	global_load_dwordx4 v[200:203], v[76:77], off offset:256
	global_load_dwordx4 v[204:207], v[78:79], off offset:256
	global_load_dwordx4 v[208:211], v[80:81], off offset:256
	v_and_b32_e32 v246, 15, v1
	v_add_u32_e32 v246, 4, v246
	v_bfe_u32 v246, v246, 3, 1
	v_bfe_u32 v249, v1, 4, 2
	v_xor_b32_e32 v246, v246, v249
	v_bfe_u32 v249, v1, 5, 1
	v_sub_u32_e32 v246, v246, v249
	v_lshlrev_b32_e32 v246, 4, v246
	v_bfe_u32 v249, v1, 4, 1
	v_mul_u32_u24_e32 v249, 0x900, v249
	v_sub_u32_e32 v246, v246, v249
	v_add_u32_e32 v244, v246, v162
	v_add_u32_e32 v245, v246, v164
	ds_read_b128 v[228:231], v245 offset:36864
	ds_read_b128 v[212:215], v244
	ds_read_b128 v[236:239], v245 offset:39168
	ds_read_b128 v[240:243], v245 offset:41472
	ds_read_b128 v[252:255], v245 offset:43776
	ds_read_b128 v[216:219], v244 offset:2304
	ds_read_b128 v[220:223], v244 offset:4608
	ds_read_b128 v[224:227], v244 offset:6912
	s_waitcnt lgkmcnt(6)
	v_mfma_f32_16x16x32_bf16 v[50:53], v[212:215], v[228:231], 0
	s_waitcnt lgkmcnt(5)
	v_mfma_f32_16x16x32_bf16 v[54:57], v[212:215], v[236:239], 0
	s_waitcnt lgkmcnt(4)
	v_mfma_f32_16x16x32_bf16 v[34:37], v[212:215], v[240:243], 0
	s_waitcnt lgkmcnt(3)
	v_mfma_f32_16x16x32_bf16 v[38:41], v[212:215], v[252:255], 0
	ds_read_b128 v[212:215], v244 offset:64
	s_waitcnt lgkmcnt(3)
	v_mfma_f32_16x16x32_bf16 v[58:61], v[216:219], v[228:231], 0
	v_mfma_f32_16x16x32_bf16 v[62:65], v[216:219], v[236:239], 0
	v_mfma_f32_16x16x32_bf16 v[42:45], v[216:219], v[240:243], 0
	v_mfma_f32_16x16x32_bf16 v[46:49], v[216:219], v[252:255], 0
	ds_read_b128 v[216:219], v244 offset:2368
	s_setprio 1
	s_waitcnt vmcnt(15)
	ds_write_b128 v165, v[122:125] offset:18432
	s_waitcnt vmcnt(14)
	ds_write_b128 v165, v[126:129] offset:23040
	s_waitcnt lgkmcnt(5)
	v_mfma_f32_16x16x32_bf16 v[18:21], v[220:223], v[228:231], 0
	v_mfma_f32_16x16x32_bf16 v[22:25], v[220:223], v[236:239], 0
	v_mfma_f32_16x16x32_bf16 v[2:5], v[220:223], v[240:243], 0
	v_mfma_f32_16x16x32_bf16 v[6:9], v[220:223], v[252:255], 0
	ds_read_b128 v[220:223], v244 offset:4672
	s_waitcnt vmcnt(13)
	ds_write_b128 v165, v[136:139] offset:27648
	s_waitcnt vmcnt(12)
	ds_write_b128 v165, v[140:143] offset:32256
	s_waitcnt lgkmcnt(7)
	v_mfma_f32_16x16x32_bf16 v[26:29], v[224:227], v[228:231], 0
	ds_read_b128 v[228:231], v245 offset:36928
	v_mfma_f32_16x16x32_bf16 v[30:33], v[224:227], v[236:239], 0
	ds_read_b128 v[236:239], v245 offset:39232
	v_mfma_f32_16x16x32_bf16 v[10:13], v[224:227], v[240:243], 0
	ds_read_b128 v[240:243], v245 offset:41536
	v_mfma_f32_16x16x32_bf16 v[14:17], v[224:227], v[252:255], 0
	ds_read_b128 v[252:255], v245 offset:43840
	ds_read_b128 v[224:227], v244 offset:6976
	s_waitcnt lgkmcnt(4)
	v_mfma_f32_16x16x32_bf16 v[50:53], v[212:215], v[228:231], v[50:53]
	s_waitcnt lgkmcnt(3)
	v_mfma_f32_16x16x32_bf16 v[54:57], v[212:215], v[236:239], v[54:57]
	s_waitcnt lgkmcnt(2)
	v_mfma_f32_16x16x32_bf16 v[34:37], v[212:215], v[240:243], v[34:37]
	s_waitcnt lgkmcnt(1)
	v_mfma_f32_16x16x32_bf16 v[38:41], v[212:215], v[252:255], v[38:41]
	s_waitcnt vmcnt(11)
	ds_write_b128 v165, v[144:147] offset:55296
	s_waitcnt vmcnt(10)
	ds_write_b128 v165, v[148:151] offset:59904
	v_mfma_f32_16x16x32_bf16 v[58:61], v[216:219], v[228:231], v[58:61]
	v_mfma_f32_16x16x32_bf16 v[62:65], v[216:219], v[236:239], v[62:65]
	v_mfma_f32_16x16x32_bf16 v[42:45], v[216:219], v[240:243], v[42:45]
	v_mfma_f32_16x16x32_bf16 v[46:49], v[216:219], v[252:255], v[46:49]
	s_waitcnt vmcnt(9)
	ds_write_b128 v165, v[172:175] offset:64512
	s_waitcnt vmcnt(8)
	ds_write_b128 v166, v[176:179] offset:32256
	v_mfma_f32_16x16x32_bf16 v[18:21], v[220:223], v[228:231], v[18:21]
	v_mfma_f32_16x16x32_bf16 v[22:25], v[220:223], v[236:239], v[22:25]
	v_mfma_f32_16x16x32_bf16 v[2:5], v[220:223], v[240:243], v[2:5]
	v_mfma_f32_16x16x32_bf16 v[6:9], v[220:223], v[252:255], v[6:9]
	s_waitcnt lgkmcnt(4)
	v_mfma_f32_16x16x32_bf16 v[26:29], v[224:227], v[228:231], v[26:29]
	v_mfma_f32_16x16x32_bf16 v[30:33], v[224:227], v[236:239], v[30:33]
	v_mfma_f32_16x16x32_bf16 v[10:13], v[224:227], v[240:243], v[10:13]
	v_mfma_f32_16x16x32_bf16 v[14:17], v[224:227], v[252:255], v[14:17]
	s_waitcnt lgkmcnt(0)
	s_barrier
	s_setprio 0
	global_load_dwordx4 v[122:125], v[70:71], off offset:384
	global_load_dwordx4 v[126:129], v[68:69], off offset:384
	global_load_dwordx4 v[136:139], v[66:67], off offset:384
	global_load_dwordx4 v[140:143], v[72:73], off offset:384
	global_load_dwordx4 v[144:147], v[74:75], off offset:384
	global_load_dwordx4 v[148:151], v[76:77], off offset:384
	global_load_dwordx4 v[172:175], v[78:79], off offset:384
	global_load_dwordx4 v[176:179], v[80:81], off offset:384
	ds_read_b128 v[228:231], v245 offset:55296
	ds_read_b128 v[212:215], v244 offset:18432
	ds_read_b128 v[236:239], v245 offset:57600
	ds_read_b128 v[240:243], v245 offset:59904
	ds_read_b128 v[252:255], v245 offset:62208
	ds_read_b128 v[216:219], v244 offset:20736
	ds_read_b128 v[220:223], v244 offset:23040
	ds_read_b128 v[224:227], v244 offset:25344
	s_waitcnt lgkmcnt(6)
	v_mfma_f32_16x16x32_bf16 v[50:53], v[212:215], v[228:231], v[50:53]
	s_waitcnt lgkmcnt(5)
	v_mfma_f32_16x16x32_bf16 v[54:57], v[212:215], v[236:239], v[54:57]
	s_waitcnt lgkmcnt(4)
	v_mfma_f32_16x16x32_bf16 v[34:37], v[212:215], v[240:243], v[34:37]
	s_waitcnt lgkmcnt(3)
	v_mfma_f32_16x16x32_bf16 v[38:41], v[212:215], v[252:255], v[38:41]
	ds_read_b128 v[212:215], v244 offset:18496
	s_waitcnt lgkmcnt(3)
	v_mfma_f32_16x16x32_bf16 v[58:61], v[216:219], v[228:231], v[58:61]
	v_mfma_f32_16x16x32_bf16 v[62:65], v[216:219], v[236:239], v[62:65]
	v_mfma_f32_16x16x32_bf16 v[42:45], v[216:219], v[240:243], v[42:45]
	v_mfma_f32_16x16x32_bf16 v[46:49], v[216:219], v[252:255], v[46:49]
	ds_read_b128 v[216:219], v244 offset:20800
	s_setprio 1
	s_waitcnt vmcnt(13)
	ds_write_b128 v165, v[188:191]
	ds_write_b128 v165, v[180:183] offset:4608
	s_waitcnt lgkmcnt(5)
	v_mfma_f32_16x16x32_bf16 v[18:21], v[220:223], v[228:231], v[18:21]
	v_mfma_f32_16x16x32_bf16 v[22:25], v[220:223], v[236:239], v[22:25]
	v_mfma_f32_16x16x32_bf16 v[2:5], v[220:223], v[240:243], v[2:5]
	v_mfma_f32_16x16x32_bf16 v[6:9], v[220:223], v[252:255], v[6:9]
	ds_read_b128 v[220:223], v244 offset:23104
	ds_write_b128 v165, v[184:187] offset:9216
	s_waitcnt vmcnt(12)
	ds_write_b128 v165, v[192:195] offset:13824
	s_waitcnt lgkmcnt(7)
	v_mfma_f32_16x16x32_bf16 v[26:29], v[224:227], v[228:231], v[26:29]
	ds_read_b128 v[228:231], v245 offset:55360
	v_mfma_f32_16x16x32_bf16 v[30:33], v[224:227], v[236:239], v[30:33]
	ds_read_b128 v[236:239], v245 offset:57664
	v_mfma_f32_16x16x32_bf16 v[10:13], v[224:227], v[240:243], v[10:13]
	ds_read_b128 v[240:243], v245 offset:59968
	v_mfma_f32_16x16x32_bf16 v[14:17], v[224:227], v[252:255], v[14:17]
	ds_read_b128 v[252:255], v245 offset:62272
	ds_read_b128 v[224:227], v244 offset:25408
	s_waitcnt lgkmcnt(4)
	v_mfma_f32_16x16x32_bf16 v[50:53], v[212:215], v[228:231], v[50:53]
	s_waitcnt lgkmcnt(3)
	v_mfma_f32_16x16x32_bf16 v[54:57], v[212:215], v[236:239], v[54:57]
	s_waitcnt lgkmcnt(2)
	v_mfma_f32_16x16x32_bf16 v[34:37], v[212:215], v[240:243], v[34:37]
	s_waitcnt lgkmcnt(1)
	v_mfma_f32_16x16x32_bf16 v[38:41], v[212:215], v[252:255], v[38:41]
	s_waitcnt vmcnt(11)
	ds_write_b128 v165, v[196:199] offset:36864
	s_waitcnt vmcnt(10)
	ds_write_b128 v165, v[200:203] offset:41472
	v_mfma_f32_16x16x32_bf16 v[58:61], v[216:219], v[228:231], v[58:61]
	v_mfma_f32_16x16x32_bf16 v[62:65], v[216:219], v[236:239], v[62:65]
	v_mfma_f32_16x16x32_bf16 v[42:45], v[216:219], v[240:243], v[42:45]
	v_mfma_f32_16x16x32_bf16 v[46:49], v[216:219], v[252:255], v[46:49]
	s_waitcnt vmcnt(9)
	ds_write_b128 v165, v[204:207] offset:46080
	s_waitcnt vmcnt(8)
	ds_write_b128 v165, v[208:211] offset:50688
	v_mfma_f32_16x16x32_bf16 v[18:21], v[220:223], v[228:231], v[18:21]
	v_mfma_f32_16x16x32_bf16 v[22:25], v[220:223], v[236:239], v[22:25]
	v_mfma_f32_16x16x32_bf16 v[2:5], v[220:223], v[240:243], v[2:5]
	v_mfma_f32_16x16x32_bf16 v[6:9], v[220:223], v[252:255], v[6:9]
	s_waitcnt lgkmcnt(4)
	v_mfma_f32_16x16x32_bf16 v[26:29], v[224:227], v[228:231], v[26:29]
	v_mfma_f32_16x16x32_bf16 v[30:33], v[224:227], v[236:239], v[30:33]
	v_mfma_f32_16x16x32_bf16 v[10:13], v[224:227], v[240:243], v[10:13]
	v_mfma_f32_16x16x32_bf16 v[14:17], v[224:227], v[252:255], v[14:17]
	s_waitcnt lgkmcnt(0)
	s_barrier
	s_setprio 0
	global_load_dwordx4 v[180:183], v[70:71], off offset:512
	global_load_dwordx4 v[184:187], v[68:69], off offset:512
	global_load_dwordx4 v[188:191], v[66:67], off offset:512
	global_load_dwordx4 v[192:195], v[72:73], off offset:512
	global_load_dwordx4 v[196:199], v[74:75], off offset:512
	global_load_dwordx4 v[200:203], v[76:77], off offset:512
	global_load_dwordx4 v[204:207], v[78:79], off offset:512
	global_load_dwordx4 v[208:211], v[80:81], off offset:512
	ds_read_b128 v[228:231], v245 offset:36864
	ds_read_b128 v[212:215], v244
	ds_read_b128 v[236:239], v245 offset:39168
	ds_read_b128 v[240:243], v245 offset:41472
	ds_read_b128 v[252:255], v245 offset:43776
	ds_read_b128 v[216:219], v244 offset:2304
	ds_read_b128 v[220:223], v244 offset:4608
	ds_read_b128 v[224:227], v244 offset:6912
	s_waitcnt lgkmcnt(6)
	v_mfma_f32_16x16x32_bf16 v[50:53], v[212:215], v[228:231], v[50:53]
	s_waitcnt lgkmcnt(5)
	v_mfma_f32_16x16x32_bf16 v[54:57], v[212:215], v[236:239], v[54:57]
	s_waitcnt lgkmcnt(4)
	v_mfma_f32_16x16x32_bf16 v[34:37], v[212:215], v[240:243], v[34:37]
	s_waitcnt lgkmcnt(3)
	v_mfma_f32_16x16x32_bf16 v[38:41], v[212:215], v[252:255], v[38:41]
	ds_read_b128 v[212:215], v244 offset:64
	s_waitcnt lgkmcnt(3)
	v_mfma_f32_16x16x32_bf16 v[58:61], v[216:219], v[228:231], v[58:61]
	v_mfma_f32_16x16x32_bf16 v[62:65], v[216:219], v[236:239], v[62:65]
	v_mfma_f32_16x16x32_bf16 v[42:45], v[216:219], v[240:243], v[42:45]
	v_mfma_f32_16x16x32_bf16 v[46:49], v[216:219], v[252:255], v[46:49]
	ds_read_b128 v[216:219], v244 offset:2368
	s_setprio 1
	s_waitcnt vmcnt(15)
	ds_write_b128 v165, v[122:125] offset:18432
	s_waitcnt vmcnt(14)
	ds_write_b128 v165, v[126:129] offset:23040
	s_waitcnt lgkmcnt(5)
	v_mfma_f32_16x16x32_bf16 v[18:21], v[220:223], v[228:231], v[18:21]
	v_mfma_f32_16x16x32_bf16 v[22:25], v[220:223], v[236:239], v[22:25]
	v_mfma_f32_16x16x32_bf16 v[2:5], v[220:223], v[240:243], v[2:5]
	v_mfma_f32_16x16x32_bf16 v[6:9], v[220:223], v[252:255], v[6:9]
	ds_read_b128 v[220:223], v244 offset:4672
	s_waitcnt vmcnt(13)
	ds_write_b128 v165, v[136:139] offset:27648
	s_waitcnt vmcnt(12)
	ds_write_b128 v165, v[140:143] offset:32256
	s_waitcnt lgkmcnt(7)
	v_mfma_f32_16x16x32_bf16 v[26:29], v[224:227], v[228:231], v[26:29]
	ds_read_b128 v[228:231], v245 offset:36928
	v_mfma_f32_16x16x32_bf16 v[30:33], v[224:227], v[236:239], v[30:33]
	ds_read_b128 v[236:239], v245 offset:39232
	v_mfma_f32_16x16x32_bf16 v[10:13], v[224:227], v[240:243], v[10:13]
	ds_read_b128 v[240:243], v245 offset:41536
	v_mfma_f32_16x16x32_bf16 v[14:17], v[224:227], v[252:255], v[14:17]
	ds_read_b128 v[252:255], v245 offset:43840
	ds_read_b128 v[224:227], v244 offset:6976
	s_waitcnt lgkmcnt(4)
	v_mfma_f32_16x16x32_bf16 v[50:53], v[212:215], v[228:231], v[50:53]
	s_waitcnt lgkmcnt(3)
	v_mfma_f32_16x16x32_bf16 v[54:57], v[212:215], v[236:239], v[54:57]
	s_waitcnt lgkmcnt(2)
	v_mfma_f32_16x16x32_bf16 v[34:37], v[212:215], v[240:243], v[34:37]
	s_waitcnt lgkmcnt(1)
	v_mfma_f32_16x16x32_bf16 v[38:41], v[212:215], v[252:255], v[38:41]
	s_waitcnt vmcnt(11)
	ds_write_b128 v165, v[144:147] offset:55296
	s_waitcnt vmcnt(10)
	ds_write_b128 v165, v[148:151] offset:59904
	v_mfma_f32_16x16x32_bf16 v[58:61], v[216:219], v[228:231], v[58:61]
	v_mfma_f32_16x16x32_bf16 v[62:65], v[216:219], v[236:239], v[62:65]
	v_mfma_f32_16x16x32_bf16 v[42:45], v[216:219], v[240:243], v[42:45]
	v_mfma_f32_16x16x32_bf16 v[46:49], v[216:219], v[252:255], v[46:49]
	s_waitcnt vmcnt(9)
	ds_write_b128 v165, v[172:175] offset:64512
	s_waitcnt vmcnt(8)
	ds_write_b128 v166, v[176:179] offset:32256
	v_mfma_f32_16x16x32_bf16 v[18:21], v[220:223], v[228:231], v[18:21]
	v_mfma_f32_16x16x32_bf16 v[22:25], v[220:223], v[236:239], v[22:25]
	v_mfma_f32_16x16x32_bf16 v[2:5], v[220:223], v[240:243], v[2:5]
	v_mfma_f32_16x16x32_bf16 v[6:9], v[220:223], v[252:255], v[6:9]
	s_waitcnt lgkmcnt(4)
	v_mfma_f32_16x16x32_bf16 v[26:29], v[224:227], v[228:231], v[26:29]
	v_mfma_f32_16x16x32_bf16 v[30:33], v[224:227], v[236:239], v[30:33]
	v_mfma_f32_16x16x32_bf16 v[10:13], v[224:227], v[240:243], v[10:13]
	v_mfma_f32_16x16x32_bf16 v[14:17], v[224:227], v[252:255], v[14:17]
	s_waitcnt lgkmcnt(0)
	s_barrier
	s_setprio 0
	global_load_dwordx4 v[122:125], v[70:71], off offset:640
	global_load_dwordx4 v[126:129], v[68:69], off offset:640
	global_load_dwordx4 v[136:139], v[66:67], off offset:640
	global_load_dwordx4 v[140:143], v[72:73], off offset:640
	global_load_dwordx4 v[144:147], v[74:75], off offset:640
	global_load_dwordx4 v[148:151], v[76:77], off offset:640
	global_load_dwordx4 v[172:175], v[78:79], off offset:640
	global_load_dwordx4 v[176:179], v[80:81], off offset:640
	ds_read_b128 v[228:231], v245 offset:55296
	ds_read_b128 v[212:215], v244 offset:18432
	ds_read_b128 v[236:239], v245 offset:57600
	ds_read_b128 v[240:243], v245 offset:59904
	ds_read_b128 v[252:255], v245 offset:62208
	ds_read_b128 v[216:219], v244 offset:20736
	ds_read_b128 v[220:223], v244 offset:23040
	ds_read_b128 v[224:227], v244 offset:25344
	s_waitcnt lgkmcnt(6)
	v_mfma_f32_16x16x32_bf16 v[50:53], v[212:215], v[228:231], v[50:53]
	s_waitcnt lgkmcnt(5)
	v_mfma_f32_16x16x32_bf16 v[54:57], v[212:215], v[236:239], v[54:57]
	s_waitcnt lgkmcnt(4)
	v_mfma_f32_16x16x32_bf16 v[34:37], v[212:215], v[240:243], v[34:37]
	s_waitcnt lgkmcnt(3)
	v_mfma_f32_16x16x32_bf16 v[38:41], v[212:215], v[252:255], v[38:41]
	ds_read_b128 v[212:215], v244 offset:18496
	s_waitcnt lgkmcnt(3)
	v_mfma_f32_16x16x32_bf16 v[58:61], v[216:219], v[228:231], v[58:61]
	v_mfma_f32_16x16x32_bf16 v[62:65], v[216:219], v[236:239], v[62:65]
	v_mfma_f32_16x16x32_bf16 v[42:45], v[216:219], v[240:243], v[42:45]
	v_mfma_f32_16x16x32_bf16 v[46:49], v[216:219], v[252:255], v[46:49]
	ds_read_b128 v[216:219], v244 offset:20800
	s_setprio 1
	s_waitcnt vmcnt(15)
	ds_write_b128 v165, v[180:183]
	s_waitcnt vmcnt(14)
	ds_write_b128 v165, v[184:187] offset:4608
	s_waitcnt lgkmcnt(5)
	v_mfma_f32_16x16x32_bf16 v[18:21], v[220:223], v[228:231], v[18:21]
	v_mfma_f32_16x16x32_bf16 v[22:25], v[220:223], v[236:239], v[22:25]
	v_mfma_f32_16x16x32_bf16 v[2:5], v[220:223], v[240:243], v[2:5]
	v_mfma_f32_16x16x32_bf16 v[6:9], v[220:223], v[252:255], v[6:9]
	ds_read_b128 v[220:223], v244 offset:23104
	s_waitcnt vmcnt(13)
	ds_write_b128 v165, v[188:191] offset:9216
	s_waitcnt vmcnt(12)
	ds_write_b128 v165, v[192:195] offset:13824
	s_waitcnt lgkmcnt(7)
	v_mfma_f32_16x16x32_bf16 v[26:29], v[224:227], v[228:231], v[26:29]
	ds_read_b128 v[228:231], v245 offset:55360
	v_mfma_f32_16x16x32_bf16 v[30:33], v[224:227], v[236:239], v[30:33]
	ds_read_b128 v[236:239], v245 offset:57664
	v_mfma_f32_16x16x32_bf16 v[10:13], v[224:227], v[240:243], v[10:13]
	ds_read_b128 v[240:243], v245 offset:59968
	v_mfma_f32_16x16x32_bf16 v[14:17], v[224:227], v[252:255], v[14:17]
	ds_read_b128 v[252:255], v245 offset:62272
	ds_read_b128 v[224:227], v244 offset:25408
	s_waitcnt lgkmcnt(4)
	v_mfma_f32_16x16x32_bf16 v[50:53], v[212:215], v[228:231], v[50:53]
	s_waitcnt lgkmcnt(3)
	v_mfma_f32_16x16x32_bf16 v[54:57], v[212:215], v[236:239], v[54:57]
	s_waitcnt lgkmcnt(2)
	v_mfma_f32_16x16x32_bf16 v[34:37], v[212:215], v[240:243], v[34:37]
	s_waitcnt lgkmcnt(1)
	v_mfma_f32_16x16x32_bf16 v[38:41], v[212:215], v[252:255], v[38:41]
	s_waitcnt vmcnt(11)
	ds_write_b128 v165, v[196:199] offset:36864
	s_waitcnt vmcnt(10)
	ds_write_b128 v165, v[200:203] offset:41472
	v_mfma_f32_16x16x32_bf16 v[58:61], v[216:219], v[228:231], v[58:61]
	v_mfma_f32_16x16x32_bf16 v[62:65], v[216:219], v[236:239], v[62:65]
	v_mfma_f32_16x16x32_bf16 v[42:45], v[216:219], v[240:243], v[42:45]
	v_mfma_f32_16x16x32_bf16 v[46:49], v[216:219], v[252:255], v[46:49]
	s_waitcnt vmcnt(9)
	ds_write_b128 v165, v[204:207] offset:46080
	s_waitcnt vmcnt(8)
	ds_write_b128 v165, v[208:211] offset:50688
	v_mfma_f32_16x16x32_bf16 v[18:21], v[220:223], v[228:231], v[18:21]
	v_mfma_f32_16x16x32_bf16 v[22:25], v[220:223], v[236:239], v[22:25]
	v_mfma_f32_16x16x32_bf16 v[2:5], v[220:223], v[240:243], v[2:5]
	v_mfma_f32_16x16x32_bf16 v[6:9], v[220:223], v[252:255], v[6:9]
	s_waitcnt lgkmcnt(4)
	v_mfma_f32_16x16x32_bf16 v[26:29], v[224:227], v[228:231], v[26:29]
	v_mfma_f32_16x16x32_bf16 v[30:33], v[224:227], v[236:239], v[30:33]
	v_mfma_f32_16x16x32_bf16 v[10:13], v[224:227], v[240:243], v[10:13]
	v_mfma_f32_16x16x32_bf16 v[14:17], v[224:227], v[252:255], v[14:17]
	s_waitcnt lgkmcnt(0)
	s_barrier
	s_setprio 0
	global_load_dwordx4 v[180:183], v[70:71], off offset:768
	global_load_dwordx4 v[184:187], v[68:69], off offset:768
	global_load_dwordx4 v[188:191], v[66:67], off offset:768
	global_load_dwordx4 v[192:195], v[72:73], off offset:768
	global_load_dwordx4 v[196:199], v[74:75], off offset:768
	global_load_dwordx4 v[200:203], v[76:77], off offset:768
	global_load_dwordx4 v[204:207], v[78:79], off offset:768
	global_load_dwordx4 v[208:211], v[80:81], off offset:768
	ds_read_b128 v[228:231], v245 offset:36864
	ds_read_b128 v[212:215], v244
	ds_read_b128 v[236:239], v245 offset:39168
	ds_read_b128 v[240:243], v245 offset:41472
	ds_read_b128 v[252:255], v245 offset:43776
	ds_read_b128 v[216:219], v244 offset:2304
	ds_read_b128 v[220:223], v244 offset:4608
	ds_read_b128 v[224:227], v244 offset:6912
	s_waitcnt lgkmcnt(6)
	v_mfma_f32_16x16x32_bf16 v[50:53], v[212:215], v[228:231], v[50:53]
	s_waitcnt lgkmcnt(5)
	v_mfma_f32_16x16x32_bf16 v[54:57], v[212:215], v[236:239], v[54:57]
	s_waitcnt lgkmcnt(4)
	v_mfma_f32_16x16x32_bf16 v[34:37], v[212:215], v[240:243], v[34:37]
	s_waitcnt lgkmcnt(3)
	v_mfma_f32_16x16x32_bf16 v[38:41], v[212:215], v[252:255], v[38:41]
	ds_read_b128 v[212:215], v244 offset:64
	s_waitcnt lgkmcnt(3)
	v_mfma_f32_16x16x32_bf16 v[58:61], v[216:219], v[228:231], v[58:61]
	v_mfma_f32_16x16x32_bf16 v[62:65], v[216:219], v[236:239], v[62:65]
	v_mfma_f32_16x16x32_bf16 v[42:45], v[216:219], v[240:243], v[42:45]
	v_mfma_f32_16x16x32_bf16 v[46:49], v[216:219], v[252:255], v[46:49]
	ds_read_b128 v[216:219], v244 offset:2368
	s_setprio 1
	s_waitcnt vmcnt(15)
	ds_write_b128 v165, v[122:125] offset:18432
	s_waitcnt vmcnt(14)
	ds_write_b128 v165, v[126:129] offset:23040
	s_waitcnt lgkmcnt(5)
	v_mfma_f32_16x16x32_bf16 v[18:21], v[220:223], v[228:231], v[18:21]
	v_mfma_f32_16x16x32_bf16 v[22:25], v[220:223], v[236:239], v[22:25]
	v_mfma_f32_16x16x32_bf16 v[2:5], v[220:223], v[240:243], v[2:5]
	v_mfma_f32_16x16x32_bf16 v[6:9], v[220:223], v[252:255], v[6:9]
	ds_read_b128 v[220:223], v244 offset:4672
	s_waitcnt vmcnt(13)
	ds_write_b128 v165, v[136:139] offset:27648
	s_waitcnt vmcnt(12)
	ds_write_b128 v165, v[140:143] offset:32256
	s_waitcnt lgkmcnt(7)
	v_mfma_f32_16x16x32_bf16 v[26:29], v[224:227], v[228:231], v[26:29]
	ds_read_b128 v[228:231], v245 offset:36928
	v_mfma_f32_16x16x32_bf16 v[30:33], v[224:227], v[236:239], v[30:33]
	ds_read_b128 v[236:239], v245 offset:39232
	v_mfma_f32_16x16x32_bf16 v[10:13], v[224:227], v[240:243], v[10:13]
	ds_read_b128 v[240:243], v245 offset:41536
	v_mfma_f32_16x16x32_bf16 v[14:17], v[224:227], v[252:255], v[14:17]
	ds_read_b128 v[252:255], v245 offset:43840
	ds_read_b128 v[224:227], v244 offset:6976
	s_waitcnt lgkmcnt(4)
	v_mfma_f32_16x16x32_bf16 v[50:53], v[212:215], v[228:231], v[50:53]
	s_waitcnt lgkmcnt(3)
	v_mfma_f32_16x16x32_bf16 v[54:57], v[212:215], v[236:239], v[54:57]
	s_waitcnt lgkmcnt(2)
	v_mfma_f32_16x16x32_bf16 v[34:37], v[212:215], v[240:243], v[34:37]
	s_waitcnt lgkmcnt(1)
	v_mfma_f32_16x16x32_bf16 v[38:41], v[212:215], v[252:255], v[38:41]
	s_waitcnt vmcnt(11)
	ds_write_b128 v165, v[144:147] offset:55296
	s_waitcnt vmcnt(10)
	ds_write_b128 v165, v[148:151] offset:59904
	v_mfma_f32_16x16x32_bf16 v[58:61], v[216:219], v[228:231], v[58:61]
	v_mfma_f32_16x16x32_bf16 v[62:65], v[216:219], v[236:239], v[62:65]
	v_mfma_f32_16x16x32_bf16 v[42:45], v[216:219], v[240:243], v[42:45]
	v_mfma_f32_16x16x32_bf16 v[46:49], v[216:219], v[252:255], v[46:49]
	s_waitcnt vmcnt(9)
	ds_write_b128 v165, v[172:175] offset:64512
	s_waitcnt vmcnt(8)
	ds_write_b128 v166, v[176:179] offset:32256
	v_mfma_f32_16x16x32_bf16 v[18:21], v[220:223], v[228:231], v[18:21]
	v_mfma_f32_16x16x32_bf16 v[22:25], v[220:223], v[236:239], v[22:25]
	v_mfma_f32_16x16x32_bf16 v[2:5], v[220:223], v[240:243], v[2:5]
	v_mfma_f32_16x16x32_bf16 v[6:9], v[220:223], v[252:255], v[6:9]
	s_waitcnt lgkmcnt(4)
	v_mfma_f32_16x16x32_bf16 v[26:29], v[224:227], v[228:231], v[26:29]
	v_mfma_f32_16x16x32_bf16 v[30:33], v[224:227], v[236:239], v[30:33]
	v_mfma_f32_16x16x32_bf16 v[10:13], v[224:227], v[240:243], v[10:13]
	v_mfma_f32_16x16x32_bf16 v[14:17], v[224:227], v[252:255], v[14:17]
	s_waitcnt lgkmcnt(0)
	s_barrier
	s_setprio 0
	global_load_dwordx4 v[122:125], v[70:71], off offset:896
	global_load_dwordx4 v[126:129], v[68:69], off offset:896
	global_load_dwordx4 v[136:139], v[66:67], off offset:896
	global_load_dwordx4 v[140:143], v[72:73], off offset:896
	global_load_dwordx4 v[144:147], v[74:75], off offset:896
	global_load_dwordx4 v[148:151], v[76:77], off offset:896
	global_load_dwordx4 v[172:175], v[78:79], off offset:896
	global_load_dwordx4 v[176:179], v[80:81], off offset:896
	ds_read_b128 v[228:231], v245 offset:55296
	ds_read_b128 v[212:215], v244 offset:18432
	ds_read_b128 v[236:239], v245 offset:57600
	ds_read_b128 v[240:243], v245 offset:59904
	ds_read_b128 v[252:255], v245 offset:62208
	ds_read_b128 v[216:219], v244 offset:20736
	ds_read_b128 v[220:223], v244 offset:23040
	ds_read_b128 v[224:227], v244 offset:25344
	s_waitcnt lgkmcnt(6)
	v_mfma_f32_16x16x32_bf16 v[50:53], v[212:215], v[228:231], v[50:53]
	s_waitcnt lgkmcnt(5)
	v_mfma_f32_16x16x32_bf16 v[54:57], v[212:215], v[236:239], v[54:57]
	s_waitcnt lgkmcnt(4)
	v_mfma_f32_16x16x32_bf16 v[34:37], v[212:215], v[240:243], v[34:37]
	s_waitcnt lgkmcnt(3)
	v_mfma_f32_16x16x32_bf16 v[38:41], v[212:215], v[252:255], v[38:41]
	ds_read_b128 v[212:215], v244 offset:18496
	s_waitcnt lgkmcnt(3)
	v_mfma_f32_16x16x32_bf16 v[58:61], v[216:219], v[228:231], v[58:61]
	v_mfma_f32_16x16x32_bf16 v[62:65], v[216:219], v[236:239], v[62:65]
	v_mfma_f32_16x16x32_bf16 v[42:45], v[216:219], v[240:243], v[42:45]
	v_mfma_f32_16x16x32_bf16 v[46:49], v[216:219], v[252:255], v[46:49]
	ds_read_b128 v[216:219], v244 offset:20800
	s_setprio 1
	s_waitcnt vmcnt(15)
	ds_write_b128 v165, v[180:183]
	s_waitcnt vmcnt(14)
	ds_write_b128 v165, v[184:187] offset:4608
	s_waitcnt lgkmcnt(5)
	v_mfma_f32_16x16x32_bf16 v[18:21], v[220:223], v[228:231], v[18:21]
	v_mfma_f32_16x16x32_bf16 v[22:25], v[220:223], v[236:239], v[22:25]
	v_mfma_f32_16x16x32_bf16 v[2:5], v[220:223], v[240:243], v[2:5]
	v_mfma_f32_16x16x32_bf16 v[6:9], v[220:223], v[252:255], v[6:9]
	ds_read_b128 v[220:223], v244 offset:23104
	s_waitcnt vmcnt(13)
	ds_write_b128 v165, v[188:191] offset:9216
	s_waitcnt vmcnt(12)
	ds_write_b128 v165, v[192:195] offset:13824
	s_waitcnt lgkmcnt(7)
	v_mfma_f32_16x16x32_bf16 v[26:29], v[224:227], v[228:231], v[26:29]
	ds_read_b128 v[228:231], v245 offset:55360
	v_mfma_f32_16x16x32_bf16 v[30:33], v[224:227], v[236:239], v[30:33]
	ds_read_b128 v[236:239], v245 offset:57664
	v_mfma_f32_16x16x32_bf16 v[10:13], v[224:227], v[240:243], v[10:13]
	ds_read_b128 v[240:243], v245 offset:59968
	v_mfma_f32_16x16x32_bf16 v[14:17], v[224:227], v[252:255], v[14:17]
	ds_read_b128 v[252:255], v245 offset:62272
	ds_read_b128 v[224:227], v244 offset:25408
	s_waitcnt lgkmcnt(4)
	v_mfma_f32_16x16x32_bf16 v[50:53], v[212:215], v[228:231], v[50:53]
	s_waitcnt lgkmcnt(3)
	v_mfma_f32_16x16x32_bf16 v[54:57], v[212:215], v[236:239], v[54:57]
	s_waitcnt lgkmcnt(2)
	v_mfma_f32_16x16x32_bf16 v[34:37], v[212:215], v[240:243], v[34:37]
	s_waitcnt lgkmcnt(1)
	v_mfma_f32_16x16x32_bf16 v[38:41], v[212:215], v[252:255], v[38:41]
	s_waitcnt vmcnt(11)
	ds_write_b128 v165, v[196:199] offset:36864
	s_waitcnt vmcnt(10)
	ds_write_b128 v165, v[200:203] offset:41472
	v_mfma_f32_16x16x32_bf16 v[58:61], v[216:219], v[228:231], v[58:61]
	v_mfma_f32_16x16x32_bf16 v[62:65], v[216:219], v[236:239], v[62:65]
	v_mfma_f32_16x16x32_bf16 v[42:45], v[216:219], v[240:243], v[42:45]
	v_mfma_f32_16x16x32_bf16 v[46:49], v[216:219], v[252:255], v[46:49]
	s_waitcnt vmcnt(9)
	ds_write_b128 v165, v[204:207] offset:46080
	s_waitcnt vmcnt(8)
	ds_write_b128 v165, v[208:211] offset:50688
	v_mfma_f32_16x16x32_bf16 v[18:21], v[220:223], v[228:231], v[18:21]
	v_mfma_f32_16x16x32_bf16 v[22:25], v[220:223], v[236:239], v[22:25]
	v_mfma_f32_16x16x32_bf16 v[2:5], v[220:223], v[240:243], v[2:5]
	v_mfma_f32_16x16x32_bf16 v[6:9], v[220:223], v[252:255], v[6:9]
	s_waitcnt lgkmcnt(4)
	v_mfma_f32_16x16x32_bf16 v[26:29], v[224:227], v[228:231], v[26:29]
	v_mfma_f32_16x16x32_bf16 v[30:33], v[224:227], v[236:239], v[30:33]
	v_mfma_f32_16x16x32_bf16 v[10:13], v[224:227], v[240:243], v[10:13]
	v_mfma_f32_16x16x32_bf16 v[14:17], v[224:227], v[252:255], v[14:17]
	s_waitcnt lgkmcnt(0)
	s_barrier
	s_setprio 0
	global_load_dwordx4 v[180:183], v[70:71], off offset:1024
	global_load_dwordx4 v[184:187], v[68:69], off offset:1024
	global_load_dwordx4 v[188:191], v[66:67], off offset:1024
	global_load_dwordx4 v[192:195], v[72:73], off offset:1024
	global_load_dwordx4 v[196:199], v[74:75], off offset:1024
	global_load_dwordx4 v[200:203], v[76:77], off offset:1024
	global_load_dwordx4 v[204:207], v[78:79], off offset:1024
	global_load_dwordx4 v[208:211], v[80:81], off offset:1024
	ds_read_b128 v[228:231], v245 offset:36864
	ds_read_b128 v[212:215], v244
	ds_read_b128 v[236:239], v245 offset:39168
	ds_read_b128 v[240:243], v245 offset:41472
	ds_read_b128 v[252:255], v245 offset:43776
	ds_read_b128 v[216:219], v244 offset:2304
	ds_read_b128 v[220:223], v244 offset:4608
	ds_read_b128 v[224:227], v244 offset:6912
	s_waitcnt lgkmcnt(6)
	v_mfma_f32_16x16x32_bf16 v[50:53], v[212:215], v[228:231], v[50:53]
	s_waitcnt lgkmcnt(5)
	v_mfma_f32_16x16x32_bf16 v[54:57], v[212:215], v[236:239], v[54:57]
	s_waitcnt lgkmcnt(4)
	v_mfma_f32_16x16x32_bf16 v[34:37], v[212:215], v[240:243], v[34:37]
	s_waitcnt lgkmcnt(3)
	v_mfma_f32_16x16x32_bf16 v[38:41], v[212:215], v[252:255], v[38:41]
	ds_read_b128 v[212:215], v244 offset:64
	s_waitcnt lgkmcnt(3)
	v_mfma_f32_16x16x32_bf16 v[58:61], v[216:219], v[228:231], v[58:61]
	v_mfma_f32_16x16x32_bf16 v[62:65], v[216:219], v[236:239], v[62:65]
	v_mfma_f32_16x16x32_bf16 v[42:45], v[216:219], v[240:243], v[42:45]
	v_mfma_f32_16x16x32_bf16 v[46:49], v[216:219], v[252:255], v[46:49]
	ds_read_b128 v[216:219], v244 offset:2368
	s_setprio 1
	s_waitcnt vmcnt(15)
	ds_write_b128 v165, v[122:125] offset:18432
	s_waitcnt vmcnt(14)
	ds_write_b128 v165, v[126:129] offset:23040
	s_waitcnt lgkmcnt(5)
	v_mfma_f32_16x16x32_bf16 v[18:21], v[220:223], v[228:231], v[18:21]
	v_mfma_f32_16x16x32_bf16 v[22:25], v[220:223], v[236:239], v[22:25]
	v_mfma_f32_16x16x32_bf16 v[2:5], v[220:223], v[240:243], v[2:5]
	v_mfma_f32_16x16x32_bf16 v[6:9], v[220:223], v[252:255], v[6:9]
	ds_read_b128 v[220:223], v244 offset:4672
	s_waitcnt vmcnt(13)
	ds_write_b128 v165, v[136:139] offset:27648
	s_waitcnt vmcnt(12)
	ds_write_b128 v165, v[140:143] offset:32256
	s_waitcnt lgkmcnt(7)
	v_mfma_f32_16x16x32_bf16 v[26:29], v[224:227], v[228:231], v[26:29]
	ds_read_b128 v[228:231], v245 offset:36928
	v_mfma_f32_16x16x32_bf16 v[30:33], v[224:227], v[236:239], v[30:33]
	ds_read_b128 v[236:239], v245 offset:39232
	v_mfma_f32_16x16x32_bf16 v[10:13], v[224:227], v[240:243], v[10:13]
	ds_read_b128 v[240:243], v245 offset:41536
	v_mfma_f32_16x16x32_bf16 v[14:17], v[224:227], v[252:255], v[14:17]
	ds_read_b128 v[252:255], v245 offset:43840
	ds_read_b128 v[224:227], v244 offset:6976
	s_waitcnt lgkmcnt(4)
	v_mfma_f32_16x16x32_bf16 v[50:53], v[212:215], v[228:231], v[50:53]
	s_waitcnt lgkmcnt(3)
	v_mfma_f32_16x16x32_bf16 v[54:57], v[212:215], v[236:239], v[54:57]
	s_waitcnt lgkmcnt(2)
	v_mfma_f32_16x16x32_bf16 v[34:37], v[212:215], v[240:243], v[34:37]
	s_waitcnt lgkmcnt(1)
	v_mfma_f32_16x16x32_bf16 v[38:41], v[212:215], v[252:255], v[38:41]
	s_waitcnt vmcnt(11)
	ds_write_b128 v165, v[144:147] offset:55296
	s_waitcnt vmcnt(10)
	ds_write_b128 v165, v[148:151] offset:59904
	v_mfma_f32_16x16x32_bf16 v[58:61], v[216:219], v[228:231], v[58:61]
	v_mfma_f32_16x16x32_bf16 v[62:65], v[216:219], v[236:239], v[62:65]
	v_mfma_f32_16x16x32_bf16 v[42:45], v[216:219], v[240:243], v[42:45]
	v_mfma_f32_16x16x32_bf16 v[46:49], v[216:219], v[252:255], v[46:49]
	s_waitcnt vmcnt(9)
	ds_write_b128 v165, v[172:175] offset:64512
	s_waitcnt vmcnt(8)
	ds_write_b128 v166, v[176:179] offset:32256
	v_mfma_f32_16x16x32_bf16 v[18:21], v[220:223], v[228:231], v[18:21]
	v_mfma_f32_16x16x32_bf16 v[22:25], v[220:223], v[236:239], v[22:25]
	v_mfma_f32_16x16x32_bf16 v[2:5], v[220:223], v[240:243], v[2:5]
	v_mfma_f32_16x16x32_bf16 v[6:9], v[220:223], v[252:255], v[6:9]
	s_waitcnt lgkmcnt(4)
	v_mfma_f32_16x16x32_bf16 v[26:29], v[224:227], v[228:231], v[26:29]
	v_mfma_f32_16x16x32_bf16 v[30:33], v[224:227], v[236:239], v[30:33]
	v_mfma_f32_16x16x32_bf16 v[10:13], v[224:227], v[240:243], v[10:13]
	v_mfma_f32_16x16x32_bf16 v[14:17], v[224:227], v[252:255], v[14:17]
	s_waitcnt lgkmcnt(0)
	s_barrier
	s_setprio 0
	global_load_dwordx4 v[122:125], v[70:71], off offset:1152
	global_load_dwordx4 v[126:129], v[68:69], off offset:1152
	global_load_dwordx4 v[136:139], v[66:67], off offset:1152
	global_load_dwordx4 v[140:143], v[72:73], off offset:1152
	global_load_dwordx4 v[144:147], v[74:75], off offset:1152
	global_load_dwordx4 v[148:151], v[76:77], off offset:1152
	global_load_dwordx4 v[172:175], v[78:79], off offset:1152
	global_load_dwordx4 v[176:179], v[80:81], off offset:1152
	ds_read_b128 v[228:231], v245 offset:55296
	ds_read_b128 v[212:215], v244 offset:18432
	ds_read_b128 v[236:239], v245 offset:57600
	ds_read_b128 v[240:243], v245 offset:59904
	ds_read_b128 v[252:255], v245 offset:62208
	ds_read_b128 v[216:219], v244 offset:20736
	ds_read_b128 v[220:223], v244 offset:23040
	ds_read_b128 v[224:227], v244 offset:25344
	s_waitcnt lgkmcnt(6)
	v_mfma_f32_16x16x32_bf16 v[50:53], v[212:215], v[228:231], v[50:53]
	s_waitcnt lgkmcnt(5)
	v_mfma_f32_16x16x32_bf16 v[54:57], v[212:215], v[236:239], v[54:57]
	s_waitcnt lgkmcnt(4)
	v_mfma_f32_16x16x32_bf16 v[34:37], v[212:215], v[240:243], v[34:37]
	s_waitcnt lgkmcnt(3)
	v_mfma_f32_16x16x32_bf16 v[38:41], v[212:215], v[252:255], v[38:41]
	ds_read_b128 v[212:215], v244 offset:18496
	s_waitcnt lgkmcnt(3)
	v_mfma_f32_16x16x32_bf16 v[58:61], v[216:219], v[228:231], v[58:61]
	v_mfma_f32_16x16x32_bf16 v[62:65], v[216:219], v[236:239], v[62:65]
	v_mfma_f32_16x16x32_bf16 v[42:45], v[216:219], v[240:243], v[42:45]
	v_mfma_f32_16x16x32_bf16 v[46:49], v[216:219], v[252:255], v[46:49]
	ds_read_b128 v[216:219], v244 offset:20800
	s_setprio 1
	s_waitcnt vmcnt(15)
	ds_write_b128 v165, v[180:183]
	s_waitcnt vmcnt(14)
	ds_write_b128 v165, v[184:187] offset:4608
	s_waitcnt lgkmcnt(5)
	v_mfma_f32_16x16x32_bf16 v[18:21], v[220:223], v[228:231], v[18:21]
	v_mfma_f32_16x16x32_bf16 v[22:25], v[220:223], v[236:239], v[22:25]
	v_mfma_f32_16x16x32_bf16 v[2:5], v[220:223], v[240:243], v[2:5]
	v_mfma_f32_16x16x32_bf16 v[6:9], v[220:223], v[252:255], v[6:9]
	ds_read_b128 v[220:223], v244 offset:23104
	s_waitcnt vmcnt(13)
	ds_write_b128 v165, v[188:191] offset:9216
	s_waitcnt vmcnt(12)
	ds_write_b128 v165, v[192:195] offset:13824
	s_waitcnt lgkmcnt(7)
	v_mfma_f32_16x16x32_bf16 v[26:29], v[224:227], v[228:231], v[26:29]
	ds_read_b128 v[228:231], v245 offset:55360
	v_mfma_f32_16x16x32_bf16 v[30:33], v[224:227], v[236:239], v[30:33]
	ds_read_b128 v[236:239], v245 offset:57664
	v_mfma_f32_16x16x32_bf16 v[10:13], v[224:227], v[240:243], v[10:13]
	ds_read_b128 v[240:243], v245 offset:59968
	v_mfma_f32_16x16x32_bf16 v[14:17], v[224:227], v[252:255], v[14:17]
	ds_read_b128 v[252:255], v245 offset:62272
	ds_read_b128 v[224:227], v244 offset:25408
	s_waitcnt lgkmcnt(4)
	v_mfma_f32_16x16x32_bf16 v[50:53], v[212:215], v[228:231], v[50:53]
	s_waitcnt lgkmcnt(3)
	v_mfma_f32_16x16x32_bf16 v[54:57], v[212:215], v[236:239], v[54:57]
	s_waitcnt lgkmcnt(2)
	v_mfma_f32_16x16x32_bf16 v[34:37], v[212:215], v[240:243], v[34:37]
	s_waitcnt lgkmcnt(1)
	v_mfma_f32_16x16x32_bf16 v[38:41], v[212:215], v[252:255], v[38:41]
	s_waitcnt vmcnt(11)
	ds_write_b128 v165, v[196:199] offset:36864
	s_waitcnt vmcnt(10)
	ds_write_b128 v165, v[200:203] offset:41472
	v_mfma_f32_16x16x32_bf16 v[58:61], v[216:219], v[228:231], v[58:61]
	v_mfma_f32_16x16x32_bf16 v[62:65], v[216:219], v[236:239], v[62:65]
	v_mfma_f32_16x16x32_bf16 v[42:45], v[216:219], v[240:243], v[42:45]
	v_mfma_f32_16x16x32_bf16 v[46:49], v[216:219], v[252:255], v[46:49]
	s_waitcnt vmcnt(9)
	ds_write_b128 v165, v[204:207] offset:46080
	s_waitcnt vmcnt(8)
	ds_write_b128 v165, v[208:211] offset:50688
	v_mfma_f32_16x16x32_bf16 v[18:21], v[220:223], v[228:231], v[18:21]
	v_mfma_f32_16x16x32_bf16 v[22:25], v[220:223], v[236:239], v[22:25]
	v_mfma_f32_16x16x32_bf16 v[2:5], v[220:223], v[240:243], v[2:5]
	v_mfma_f32_16x16x32_bf16 v[6:9], v[220:223], v[252:255], v[6:9]
	s_waitcnt lgkmcnt(4)
	v_mfma_f32_16x16x32_bf16 v[26:29], v[224:227], v[228:231], v[26:29]
	v_mfma_f32_16x16x32_bf16 v[30:33], v[224:227], v[236:239], v[30:33]
	v_mfma_f32_16x16x32_bf16 v[10:13], v[224:227], v[240:243], v[10:13]
	v_mfma_f32_16x16x32_bf16 v[14:17], v[224:227], v[252:255], v[14:17]
	s_waitcnt lgkmcnt(0)
	s_barrier
	s_setprio 0
	global_load_dwordx4 v[180:183], v[70:71], off offset:1280
	global_load_dwordx4 v[184:187], v[68:69], off offset:1280
	global_load_dwordx4 v[188:191], v[66:67], off offset:1280
	global_load_dwordx4 v[192:195], v[72:73], off offset:1280
	global_load_dwordx4 v[196:199], v[74:75], off offset:1280
	global_load_dwordx4 v[200:203], v[76:77], off offset:1280
	global_load_dwordx4 v[204:207], v[78:79], off offset:1280
	global_load_dwordx4 v[208:211], v[80:81], off offset:1280
	ds_read_b128 v[228:231], v245 offset:36864
	ds_read_b128 v[212:215], v244
	ds_read_b128 v[236:239], v245 offset:39168
	ds_read_b128 v[240:243], v245 offset:41472
	ds_read_b128 v[252:255], v245 offset:43776
	ds_read_b128 v[216:219], v244 offset:2304
	ds_read_b128 v[220:223], v244 offset:4608
	ds_read_b128 v[224:227], v244 offset:6912
	s_waitcnt lgkmcnt(6)
	v_mfma_f32_16x16x32_bf16 v[50:53], v[212:215], v[228:231], v[50:53]
	s_waitcnt lgkmcnt(5)
	v_mfma_f32_16x16x32_bf16 v[54:57], v[212:215], v[236:239], v[54:57]
	s_waitcnt lgkmcnt(4)
	v_mfma_f32_16x16x32_bf16 v[34:37], v[212:215], v[240:243], v[34:37]
	s_waitcnt lgkmcnt(3)
	v_mfma_f32_16x16x32_bf16 v[38:41], v[212:215], v[252:255], v[38:41]
	ds_read_b128 v[212:215], v244 offset:64
	s_waitcnt lgkmcnt(3)
	v_mfma_f32_16x16x32_bf16 v[58:61], v[216:219], v[228:231], v[58:61]
	v_mfma_f32_16x16x32_bf16 v[62:65], v[216:219], v[236:239], v[62:65]
	v_mfma_f32_16x16x32_bf16 v[42:45], v[216:219], v[240:243], v[42:45]
	v_mfma_f32_16x16x32_bf16 v[46:49], v[216:219], v[252:255], v[46:49]
	ds_read_b128 v[216:219], v244 offset:2368
	s_setprio 1
	s_waitcnt vmcnt(15)
	ds_write_b128 v165, v[122:125] offset:18432
	s_waitcnt vmcnt(14)
	ds_write_b128 v165, v[126:129] offset:23040
	s_waitcnt lgkmcnt(5)
	v_mfma_f32_16x16x32_bf16 v[18:21], v[220:223], v[228:231], v[18:21]
	v_mfma_f32_16x16x32_bf16 v[22:25], v[220:223], v[236:239], v[22:25]
	v_mfma_f32_16x16x32_bf16 v[2:5], v[220:223], v[240:243], v[2:5]
	v_mfma_f32_16x16x32_bf16 v[6:9], v[220:223], v[252:255], v[6:9]
	ds_read_b128 v[220:223], v244 offset:4672
	s_waitcnt vmcnt(13)
	ds_write_b128 v165, v[136:139] offset:27648
	s_waitcnt vmcnt(12)
	ds_write_b128 v165, v[140:143] offset:32256
	s_waitcnt lgkmcnt(7)
	v_mfma_f32_16x16x32_bf16 v[26:29], v[224:227], v[228:231], v[26:29]
	ds_read_b128 v[228:231], v245 offset:36928
	v_mfma_f32_16x16x32_bf16 v[30:33], v[224:227], v[236:239], v[30:33]
	ds_read_b128 v[236:239], v245 offset:39232
	v_mfma_f32_16x16x32_bf16 v[10:13], v[224:227], v[240:243], v[10:13]
	ds_read_b128 v[240:243], v245 offset:41536
	v_mfma_f32_16x16x32_bf16 v[14:17], v[224:227], v[252:255], v[14:17]
	ds_read_b128 v[252:255], v245 offset:43840
	ds_read_b128 v[224:227], v244 offset:6976
	s_waitcnt lgkmcnt(4)
	v_mfma_f32_16x16x32_bf16 v[50:53], v[212:215], v[228:231], v[50:53]
	s_waitcnt lgkmcnt(3)
	v_mfma_f32_16x16x32_bf16 v[54:57], v[212:215], v[236:239], v[54:57]
	s_waitcnt lgkmcnt(2)
	v_mfma_f32_16x16x32_bf16 v[34:37], v[212:215], v[240:243], v[34:37]
	s_waitcnt lgkmcnt(1)
	v_mfma_f32_16x16x32_bf16 v[38:41], v[212:215], v[252:255], v[38:41]
	s_waitcnt vmcnt(11)
	ds_write_b128 v165, v[144:147] offset:55296
	s_waitcnt vmcnt(10)
	ds_write_b128 v165, v[148:151] offset:59904
	v_mfma_f32_16x16x32_bf16 v[58:61], v[216:219], v[228:231], v[58:61]
	v_mfma_f32_16x16x32_bf16 v[62:65], v[216:219], v[236:239], v[62:65]
	v_mfma_f32_16x16x32_bf16 v[42:45], v[216:219], v[240:243], v[42:45]
	v_mfma_f32_16x16x32_bf16 v[46:49], v[216:219], v[252:255], v[46:49]
	s_waitcnt vmcnt(9)
	ds_write_b128 v165, v[172:175] offset:64512
	s_waitcnt vmcnt(8)
	ds_write_b128 v166, v[176:179] offset:32256
	v_mfma_f32_16x16x32_bf16 v[18:21], v[220:223], v[228:231], v[18:21]
	v_mfma_f32_16x16x32_bf16 v[22:25], v[220:223], v[236:239], v[22:25]
	v_mfma_f32_16x16x32_bf16 v[2:5], v[220:223], v[240:243], v[2:5]
	v_mfma_f32_16x16x32_bf16 v[6:9], v[220:223], v[252:255], v[6:9]
	s_waitcnt lgkmcnt(4)
	v_mfma_f32_16x16x32_bf16 v[26:29], v[224:227], v[228:231], v[26:29]
	v_mfma_f32_16x16x32_bf16 v[30:33], v[224:227], v[236:239], v[30:33]
	v_mfma_f32_16x16x32_bf16 v[10:13], v[224:227], v[240:243], v[10:13]
	v_mfma_f32_16x16x32_bf16 v[14:17], v[224:227], v[252:255], v[14:17]
	s_waitcnt lgkmcnt(0)
	s_barrier
	s_setprio 0
	global_load_dwordx4 v[122:125], v[70:71], off offset:1408
	global_load_dwordx4 v[126:129], v[68:69], off offset:1408
	global_load_dwordx4 v[136:139], v[66:67], off offset:1408
	global_load_dwordx4 v[140:143], v[72:73], off offset:1408
	global_load_dwordx4 v[144:147], v[74:75], off offset:1408
	global_load_dwordx4 v[148:151], v[76:77], off offset:1408
	global_load_dwordx4 v[172:175], v[78:79], off offset:1408
	global_load_dwordx4 v[176:179], v[80:81], off offset:1408
	ds_read_b128 v[228:231], v245 offset:55296
	ds_read_b128 v[212:215], v244 offset:18432
	ds_read_b128 v[236:239], v245 offset:57600
	ds_read_b128 v[240:243], v245 offset:59904
	ds_read_b128 v[252:255], v245 offset:62208
	ds_read_b128 v[216:219], v244 offset:20736
	ds_read_b128 v[220:223], v244 offset:23040
	ds_read_b128 v[224:227], v244 offset:25344
	s_waitcnt lgkmcnt(6)
	v_mfma_f32_16x16x32_bf16 v[50:53], v[212:215], v[228:231], v[50:53]
	s_waitcnt lgkmcnt(5)
	v_mfma_f32_16x16x32_bf16 v[54:57], v[212:215], v[236:239], v[54:57]
	s_waitcnt lgkmcnt(4)
	v_mfma_f32_16x16x32_bf16 v[34:37], v[212:215], v[240:243], v[34:37]
	s_waitcnt lgkmcnt(3)
	v_mfma_f32_16x16x32_bf16 v[38:41], v[212:215], v[252:255], v[38:41]
	ds_read_b128 v[212:215], v244 offset:18496
	s_waitcnt lgkmcnt(3)
	v_mfma_f32_16x16x32_bf16 v[58:61], v[216:219], v[228:231], v[58:61]
	v_mfma_f32_16x16x32_bf16 v[62:65], v[216:219], v[236:239], v[62:65]
	v_mfma_f32_16x16x32_bf16 v[42:45], v[216:219], v[240:243], v[42:45]
	v_mfma_f32_16x16x32_bf16 v[46:49], v[216:219], v[252:255], v[46:49]
	ds_read_b128 v[216:219], v244 offset:20800
	s_setprio 1
	s_waitcnt vmcnt(15)
	ds_write_b128 v165, v[180:183]
	s_waitcnt vmcnt(14)
	ds_write_b128 v165, v[184:187] offset:4608
	s_waitcnt lgkmcnt(5)
	v_mfma_f32_16x16x32_bf16 v[18:21], v[220:223], v[228:231], v[18:21]
	v_mfma_f32_16x16x32_bf16 v[22:25], v[220:223], v[236:239], v[22:25]
	v_mfma_f32_16x16x32_bf16 v[2:5], v[220:223], v[240:243], v[2:5]
	v_mfma_f32_16x16x32_bf16 v[6:9], v[220:223], v[252:255], v[6:9]
	ds_read_b128 v[220:223], v244 offset:23104
	s_waitcnt vmcnt(13)
	ds_write_b128 v165, v[188:191] offset:9216
	s_waitcnt vmcnt(12)
	ds_write_b128 v165, v[192:195] offset:13824
	s_waitcnt lgkmcnt(7)
	v_mfma_f32_16x16x32_bf16 v[26:29], v[224:227], v[228:231], v[26:29]
	ds_read_b128 v[228:231], v245 offset:55360
	v_mfma_f32_16x16x32_bf16 v[30:33], v[224:227], v[236:239], v[30:33]
	ds_read_b128 v[236:239], v245 offset:57664
	v_mfma_f32_16x16x32_bf16 v[10:13], v[224:227], v[240:243], v[10:13]
	ds_read_b128 v[240:243], v245 offset:59968
	v_mfma_f32_16x16x32_bf16 v[14:17], v[224:227], v[252:255], v[14:17]
	ds_read_b128 v[252:255], v245 offset:62272
	ds_read_b128 v[224:227], v244 offset:25408
	s_waitcnt lgkmcnt(4)
	v_mfma_f32_16x16x32_bf16 v[50:53], v[212:215], v[228:231], v[50:53]
	s_waitcnt lgkmcnt(3)
	v_mfma_f32_16x16x32_bf16 v[54:57], v[212:215], v[236:239], v[54:57]
	s_waitcnt lgkmcnt(2)
	v_mfma_f32_16x16x32_bf16 v[34:37], v[212:215], v[240:243], v[34:37]
	s_waitcnt lgkmcnt(1)
	v_mfma_f32_16x16x32_bf16 v[38:41], v[212:215], v[252:255], v[38:41]
	s_waitcnt vmcnt(11)
	ds_write_b128 v165, v[196:199] offset:36864
	s_waitcnt vmcnt(10)
	ds_write_b128 v165, v[200:203] offset:41472
	v_mfma_f32_16x16x32_bf16 v[58:61], v[216:219], v[228:231], v[58:61]
	v_mfma_f32_16x16x32_bf16 v[62:65], v[216:219], v[236:239], v[62:65]
	v_mfma_f32_16x16x32_bf16 v[42:45], v[216:219], v[240:243], v[42:45]
	v_mfma_f32_16x16x32_bf16 v[46:49], v[216:219], v[252:255], v[46:49]
	s_waitcnt vmcnt(9)
	ds_write_b128 v165, v[204:207] offset:46080
	s_waitcnt vmcnt(8)
	ds_write_b128 v165, v[208:211] offset:50688
	v_mfma_f32_16x16x32_bf16 v[18:21], v[220:223], v[228:231], v[18:21]
	v_mfma_f32_16x16x32_bf16 v[22:25], v[220:223], v[236:239], v[22:25]
	v_mfma_f32_16x16x32_bf16 v[2:5], v[220:223], v[240:243], v[2:5]
	v_mfma_f32_16x16x32_bf16 v[6:9], v[220:223], v[252:255], v[6:9]
	s_waitcnt lgkmcnt(4)
	v_mfma_f32_16x16x32_bf16 v[26:29], v[224:227], v[228:231], v[26:29]
	v_mfma_f32_16x16x32_bf16 v[30:33], v[224:227], v[236:239], v[30:33]
	v_mfma_f32_16x16x32_bf16 v[10:13], v[224:227], v[240:243], v[10:13]
	v_mfma_f32_16x16x32_bf16 v[14:17], v[224:227], v[252:255], v[14:17]
	s_waitcnt lgkmcnt(0)
	s_barrier
	s_setprio 0
	global_load_dwordx4 v[180:183], v[70:71], off offset:1536
	global_load_dwordx4 v[184:187], v[68:69], off offset:1536
	global_load_dwordx4 v[188:191], v[66:67], off offset:1536
	global_load_dwordx4 v[192:195], v[72:73], off offset:1536
	global_load_dwordx4 v[196:199], v[74:75], off offset:1536
	global_load_dwordx4 v[200:203], v[76:77], off offset:1536
	global_load_dwordx4 v[204:207], v[78:79], off offset:1536
	global_load_dwordx4 v[208:211], v[80:81], off offset:1536
	ds_read_b128 v[228:231], v245 offset:36864
	ds_read_b128 v[212:215], v244
	ds_read_b128 v[236:239], v245 offset:39168
	ds_read_b128 v[240:243], v245 offset:41472
	ds_read_b128 v[252:255], v245 offset:43776
	ds_read_b128 v[216:219], v244 offset:2304
	ds_read_b128 v[220:223], v244 offset:4608
	ds_read_b128 v[224:227], v244 offset:6912
	s_waitcnt lgkmcnt(6)
	v_mfma_f32_16x16x32_bf16 v[50:53], v[212:215], v[228:231], v[50:53]
	s_waitcnt lgkmcnt(5)
	v_mfma_f32_16x16x32_bf16 v[54:57], v[212:215], v[236:239], v[54:57]
	s_waitcnt lgkmcnt(4)
	v_mfma_f32_16x16x32_bf16 v[34:37], v[212:215], v[240:243], v[34:37]
	s_waitcnt lgkmcnt(3)
	v_mfma_f32_16x16x32_bf16 v[38:41], v[212:215], v[252:255], v[38:41]
	ds_read_b128 v[212:215], v244 offset:64
	s_waitcnt lgkmcnt(3)
	v_mfma_f32_16x16x32_bf16 v[58:61], v[216:219], v[228:231], v[58:61]
	v_mfma_f32_16x16x32_bf16 v[62:65], v[216:219], v[236:239], v[62:65]
	v_mfma_f32_16x16x32_bf16 v[42:45], v[216:219], v[240:243], v[42:45]
	v_mfma_f32_16x16x32_bf16 v[46:49], v[216:219], v[252:255], v[46:49]
	ds_read_b128 v[216:219], v244 offset:2368
	s_setprio 1
	s_waitcnt vmcnt(15)
	ds_write_b128 v165, v[122:125] offset:18432
	s_waitcnt vmcnt(14)
	ds_write_b128 v165, v[126:129] offset:23040
	s_waitcnt lgkmcnt(5)
	v_mfma_f32_16x16x32_bf16 v[18:21], v[220:223], v[228:231], v[18:21]
	v_mfma_f32_16x16x32_bf16 v[22:25], v[220:223], v[236:239], v[22:25]
	v_mfma_f32_16x16x32_bf16 v[2:5], v[220:223], v[240:243], v[2:5]
	v_mfma_f32_16x16x32_bf16 v[6:9], v[220:223], v[252:255], v[6:9]
	ds_read_b128 v[220:223], v244 offset:4672
	s_waitcnt vmcnt(13)
	ds_write_b128 v165, v[136:139] offset:27648
	s_waitcnt vmcnt(12)
	ds_write_b128 v165, v[140:143] offset:32256
	s_waitcnt lgkmcnt(7)
	v_mfma_f32_16x16x32_bf16 v[26:29], v[224:227], v[228:231], v[26:29]
	ds_read_b128 v[228:231], v245 offset:36928
	v_mfma_f32_16x16x32_bf16 v[30:33], v[224:227], v[236:239], v[30:33]
	ds_read_b128 v[236:239], v245 offset:39232
	v_mfma_f32_16x16x32_bf16 v[10:13], v[224:227], v[240:243], v[10:13]
	ds_read_b128 v[240:243], v245 offset:41536
	v_mfma_f32_16x16x32_bf16 v[14:17], v[224:227], v[252:255], v[14:17]
	ds_read_b128 v[252:255], v245 offset:43840
	ds_read_b128 v[224:227], v244 offset:6976
	s_waitcnt lgkmcnt(4)
	v_mfma_f32_16x16x32_bf16 v[50:53], v[212:215], v[228:231], v[50:53]
	s_waitcnt lgkmcnt(3)
	v_mfma_f32_16x16x32_bf16 v[54:57], v[212:215], v[236:239], v[54:57]
	s_waitcnt lgkmcnt(2)
	v_mfma_f32_16x16x32_bf16 v[34:37], v[212:215], v[240:243], v[34:37]
	s_waitcnt lgkmcnt(1)
	v_mfma_f32_16x16x32_bf16 v[38:41], v[212:215], v[252:255], v[38:41]
	s_waitcnt vmcnt(11)
	ds_write_b128 v165, v[144:147] offset:55296
	s_waitcnt vmcnt(10)
	ds_write_b128 v165, v[148:151] offset:59904
	v_mfma_f32_16x16x32_bf16 v[58:61], v[216:219], v[228:231], v[58:61]
	v_mfma_f32_16x16x32_bf16 v[62:65], v[216:219], v[236:239], v[62:65]
	v_mfma_f32_16x16x32_bf16 v[42:45], v[216:219], v[240:243], v[42:45]
	v_mfma_f32_16x16x32_bf16 v[46:49], v[216:219], v[252:255], v[46:49]
	s_waitcnt vmcnt(9)
	ds_write_b128 v165, v[172:175] offset:64512
	s_waitcnt vmcnt(8)
	ds_write_b128 v166, v[176:179] offset:32256
	v_mfma_f32_16x16x32_bf16 v[18:21], v[220:223], v[228:231], v[18:21]
	v_mfma_f32_16x16x32_bf16 v[22:25], v[220:223], v[236:239], v[22:25]
	v_mfma_f32_16x16x32_bf16 v[2:5], v[220:223], v[240:243], v[2:5]
	v_mfma_f32_16x16x32_bf16 v[6:9], v[220:223], v[252:255], v[6:9]
	s_waitcnt lgkmcnt(4)
	v_mfma_f32_16x16x32_bf16 v[26:29], v[224:227], v[228:231], v[26:29]
	v_mfma_f32_16x16x32_bf16 v[30:33], v[224:227], v[236:239], v[30:33]
	v_mfma_f32_16x16x32_bf16 v[10:13], v[224:227], v[240:243], v[10:13]
	v_mfma_f32_16x16x32_bf16 v[14:17], v[224:227], v[252:255], v[14:17]
	s_waitcnt lgkmcnt(0)
	s_barrier
	s_setprio 0
	global_load_dwordx4 v[122:125], v[70:71], off offset:1664
	global_load_dwordx4 v[126:129], v[68:69], off offset:1664
	global_load_dwordx4 v[136:139], v[66:67], off offset:1664
	global_load_dwordx4 v[140:143], v[72:73], off offset:1664
	global_load_dwordx4 v[144:147], v[74:75], off offset:1664
	global_load_dwordx4 v[148:151], v[76:77], off offset:1664
	global_load_dwordx4 v[172:175], v[78:79], off offset:1664
	global_load_dwordx4 v[176:179], v[80:81], off offset:1664
	ds_read_b128 v[228:231], v245 offset:55296
	ds_read_b128 v[212:215], v244 offset:18432
	ds_read_b128 v[236:239], v245 offset:57600
	ds_read_b128 v[240:243], v245 offset:59904
	ds_read_b128 v[252:255], v245 offset:62208
	ds_read_b128 v[216:219], v244 offset:20736
	ds_read_b128 v[220:223], v244 offset:23040
	ds_read_b128 v[224:227], v244 offset:25344
	s_waitcnt lgkmcnt(6)
	v_mfma_f32_16x16x32_bf16 v[50:53], v[212:215], v[228:231], v[50:53]
	s_waitcnt lgkmcnt(5)
	v_mfma_f32_16x16x32_bf16 v[54:57], v[212:215], v[236:239], v[54:57]
	s_waitcnt lgkmcnt(4)
	v_mfma_f32_16x16x32_bf16 v[34:37], v[212:215], v[240:243], v[34:37]
	s_waitcnt lgkmcnt(3)
	v_mfma_f32_16x16x32_bf16 v[38:41], v[212:215], v[252:255], v[38:41]
	ds_read_b128 v[212:215], v244 offset:18496
	s_waitcnt lgkmcnt(3)
	v_mfma_f32_16x16x32_bf16 v[58:61], v[216:219], v[228:231], v[58:61]
	v_mfma_f32_16x16x32_bf16 v[62:65], v[216:219], v[236:239], v[62:65]
	v_mfma_f32_16x16x32_bf16 v[42:45], v[216:219], v[240:243], v[42:45]
	v_mfma_f32_16x16x32_bf16 v[46:49], v[216:219], v[252:255], v[46:49]
	ds_read_b128 v[216:219], v244 offset:20800
	s_setprio 1
	s_waitcnt vmcnt(15)
	ds_write_b128 v165, v[180:183]
	s_waitcnt vmcnt(14)
	ds_write_b128 v165, v[184:187] offset:4608
	s_waitcnt lgkmcnt(5)
	v_mfma_f32_16x16x32_bf16 v[18:21], v[220:223], v[228:231], v[18:21]
	v_mfma_f32_16x16x32_bf16 v[22:25], v[220:223], v[236:239], v[22:25]
	v_mfma_f32_16x16x32_bf16 v[2:5], v[220:223], v[240:243], v[2:5]
	v_mfma_f32_16x16x32_bf16 v[6:9], v[220:223], v[252:255], v[6:9]
	ds_read_b128 v[220:223], v244 offset:23104
	s_waitcnt vmcnt(13)
	ds_write_b128 v165, v[188:191] offset:9216
	s_waitcnt vmcnt(12)
	ds_write_b128 v165, v[192:195] offset:13824
	s_waitcnt lgkmcnt(7)
	v_mfma_f32_16x16x32_bf16 v[26:29], v[224:227], v[228:231], v[26:29]
	ds_read_b128 v[228:231], v245 offset:55360
	v_mfma_f32_16x16x32_bf16 v[30:33], v[224:227], v[236:239], v[30:33]
	ds_read_b128 v[236:239], v245 offset:57664
	v_mfma_f32_16x16x32_bf16 v[10:13], v[224:227], v[240:243], v[10:13]
	ds_read_b128 v[240:243], v245 offset:59968
	v_mfma_f32_16x16x32_bf16 v[14:17], v[224:227], v[252:255], v[14:17]
	ds_read_b128 v[252:255], v245 offset:62272
	ds_read_b128 v[224:227], v244 offset:25408
	s_waitcnt lgkmcnt(4)
	v_mfma_f32_16x16x32_bf16 v[50:53], v[212:215], v[228:231], v[50:53]
	s_waitcnt lgkmcnt(3)
	v_mfma_f32_16x16x32_bf16 v[54:57], v[212:215], v[236:239], v[54:57]
	s_waitcnt lgkmcnt(2)
	v_mfma_f32_16x16x32_bf16 v[34:37], v[212:215], v[240:243], v[34:37]
	s_waitcnt lgkmcnt(1)
	v_mfma_f32_16x16x32_bf16 v[38:41], v[212:215], v[252:255], v[38:41]
	s_waitcnt vmcnt(11)
	ds_write_b128 v165, v[196:199] offset:36864
	s_waitcnt vmcnt(10)
	ds_write_b128 v165, v[200:203] offset:41472
	v_mfma_f32_16x16x32_bf16 v[58:61], v[216:219], v[228:231], v[58:61]
	v_mfma_f32_16x16x32_bf16 v[62:65], v[216:219], v[236:239], v[62:65]
	v_mfma_f32_16x16x32_bf16 v[42:45], v[216:219], v[240:243], v[42:45]
	v_mfma_f32_16x16x32_bf16 v[46:49], v[216:219], v[252:255], v[46:49]
	s_waitcnt vmcnt(9)
	ds_write_b128 v165, v[204:207] offset:46080
	s_waitcnt vmcnt(8)
	ds_write_b128 v165, v[208:211] offset:50688
	v_mfma_f32_16x16x32_bf16 v[18:21], v[220:223], v[228:231], v[18:21]
	v_mfma_f32_16x16x32_bf16 v[22:25], v[220:223], v[236:239], v[22:25]
	v_mfma_f32_16x16x32_bf16 v[2:5], v[220:223], v[240:243], v[2:5]
	v_mfma_f32_16x16x32_bf16 v[6:9], v[220:223], v[252:255], v[6:9]
	s_waitcnt lgkmcnt(4)
	v_mfma_f32_16x16x32_bf16 v[26:29], v[224:227], v[228:231], v[26:29]
	v_mfma_f32_16x16x32_bf16 v[30:33], v[224:227], v[236:239], v[30:33]
	v_mfma_f32_16x16x32_bf16 v[10:13], v[224:227], v[240:243], v[10:13]
	v_mfma_f32_16x16x32_bf16 v[14:17], v[224:227], v[252:255], v[14:17]
	s_waitcnt lgkmcnt(0)
	s_barrier
	s_setprio 0
	global_load_dwordx4 v[180:183], v[70:71], off offset:1792
	global_load_dwordx4 v[184:187], v[68:69], off offset:1792
	global_load_dwordx4 v[188:191], v[66:67], off offset:1792
	global_load_dwordx4 v[192:195], v[72:73], off offset:1792
	global_load_dwordx4 v[196:199], v[74:75], off offset:1792
	global_load_dwordx4 v[200:203], v[76:77], off offset:1792
	global_load_dwordx4 v[204:207], v[78:79], off offset:1792
	global_load_dwordx4 v[208:211], v[80:81], off offset:1792
	ds_read_b128 v[228:231], v245 offset:36864
	ds_read_b128 v[212:215], v244
	ds_read_b128 v[236:239], v245 offset:39168
	ds_read_b128 v[240:243], v245 offset:41472
	ds_read_b128 v[252:255], v245 offset:43776
	ds_read_b128 v[216:219], v244 offset:2304
	ds_read_b128 v[220:223], v244 offset:4608
	ds_read_b128 v[224:227], v244 offset:6912
	s_waitcnt lgkmcnt(6)
	v_mfma_f32_16x16x32_bf16 v[50:53], v[212:215], v[228:231], v[50:53]
	s_waitcnt lgkmcnt(5)
	v_mfma_f32_16x16x32_bf16 v[54:57], v[212:215], v[236:239], v[54:57]
	s_waitcnt lgkmcnt(4)
	v_mfma_f32_16x16x32_bf16 v[34:37], v[212:215], v[240:243], v[34:37]
	s_waitcnt lgkmcnt(3)
	v_mfma_f32_16x16x32_bf16 v[38:41], v[212:215], v[252:255], v[38:41]
	ds_read_b128 v[212:215], v244 offset:64
	s_waitcnt lgkmcnt(3)
	v_mfma_f32_16x16x32_bf16 v[58:61], v[216:219], v[228:231], v[58:61]
	v_mfma_f32_16x16x32_bf16 v[62:65], v[216:219], v[236:239], v[62:65]
	v_mfma_f32_16x16x32_bf16 v[42:45], v[216:219], v[240:243], v[42:45]
	v_mfma_f32_16x16x32_bf16 v[46:49], v[216:219], v[252:255], v[46:49]
	ds_read_b128 v[216:219], v244 offset:2368
	s_setprio 1
	s_waitcnt vmcnt(15)
	ds_write_b128 v165, v[122:125] offset:18432
	s_waitcnt vmcnt(14)
	ds_write_b128 v165, v[126:129] offset:23040
	s_waitcnt lgkmcnt(5)
	v_mfma_f32_16x16x32_bf16 v[18:21], v[220:223], v[228:231], v[18:21]
	v_mfma_f32_16x16x32_bf16 v[22:25], v[220:223], v[236:239], v[22:25]
	v_mfma_f32_16x16x32_bf16 v[2:5], v[220:223], v[240:243], v[2:5]
	v_mfma_f32_16x16x32_bf16 v[6:9], v[220:223], v[252:255], v[6:9]
	ds_read_b128 v[220:223], v244 offset:4672
	s_waitcnt vmcnt(13)
	ds_write_b128 v165, v[136:139] offset:27648
	s_waitcnt vmcnt(12)
	ds_write_b128 v165, v[140:143] offset:32256
	s_waitcnt lgkmcnt(7)
	v_mfma_f32_16x16x32_bf16 v[26:29], v[224:227], v[228:231], v[26:29]
	ds_read_b128 v[228:231], v245 offset:36928
	v_mfma_f32_16x16x32_bf16 v[30:33], v[224:227], v[236:239], v[30:33]
	ds_read_b128 v[236:239], v245 offset:39232
	v_mfma_f32_16x16x32_bf16 v[10:13], v[224:227], v[240:243], v[10:13]
	ds_read_b128 v[240:243], v245 offset:41536
	v_mfma_f32_16x16x32_bf16 v[14:17], v[224:227], v[252:255], v[14:17]
	ds_read_b128 v[252:255], v245 offset:43840
	ds_read_b128 v[224:227], v244 offset:6976
	s_waitcnt lgkmcnt(4)
	v_mfma_f32_16x16x32_bf16 v[50:53], v[212:215], v[228:231], v[50:53]
	s_waitcnt lgkmcnt(3)
	v_mfma_f32_16x16x32_bf16 v[54:57], v[212:215], v[236:239], v[54:57]
	s_waitcnt lgkmcnt(2)
	v_mfma_f32_16x16x32_bf16 v[34:37], v[212:215], v[240:243], v[34:37]
	s_waitcnt lgkmcnt(1)
	v_mfma_f32_16x16x32_bf16 v[38:41], v[212:215], v[252:255], v[38:41]
	s_waitcnt vmcnt(11)
	ds_write_b128 v165, v[144:147] offset:55296
	s_waitcnt vmcnt(10)
	ds_write_b128 v165, v[148:151] offset:59904
	v_mfma_f32_16x16x32_bf16 v[58:61], v[216:219], v[228:231], v[58:61]
	v_mfma_f32_16x16x32_bf16 v[62:65], v[216:219], v[236:239], v[62:65]
	v_mfma_f32_16x16x32_bf16 v[42:45], v[216:219], v[240:243], v[42:45]
	v_mfma_f32_16x16x32_bf16 v[46:49], v[216:219], v[252:255], v[46:49]
	s_waitcnt vmcnt(9)
	ds_write_b128 v165, v[172:175] offset:64512
	s_waitcnt vmcnt(8)
	ds_write_b128 v166, v[176:179] offset:32256
	v_mfma_f32_16x16x32_bf16 v[18:21], v[220:223], v[228:231], v[18:21]
	v_mfma_f32_16x16x32_bf16 v[22:25], v[220:223], v[236:239], v[22:25]
	v_mfma_f32_16x16x32_bf16 v[2:5], v[220:223], v[240:243], v[2:5]
	v_mfma_f32_16x16x32_bf16 v[6:9], v[220:223], v[252:255], v[6:9]
	s_waitcnt lgkmcnt(4)
	v_mfma_f32_16x16x32_bf16 v[26:29], v[224:227], v[228:231], v[26:29]
	v_mfma_f32_16x16x32_bf16 v[30:33], v[224:227], v[236:239], v[30:33]
	v_mfma_f32_16x16x32_bf16 v[10:13], v[224:227], v[240:243], v[10:13]
	v_mfma_f32_16x16x32_bf16 v[14:17], v[224:227], v[252:255], v[14:17]
	s_waitcnt lgkmcnt(0)
	s_barrier
	s_setprio 0
	global_load_dwordx4 v[122:125], v[70:71], off offset:1920
	s_nop 0
	global_load_dwordx4 v[68:71], v[68:69], off offset:1920
	s_nop 0
	global_load_dwordx4 v[126:129], v[66:67], off offset:1920
	global_load_dwordx4 v[136:139], v[72:73], off offset:1920
	s_nop 0
	global_load_dwordx4 v[72:75], v[74:75], off offset:1920
	s_nop 0
	global_load_dwordx4 v[140:143], v[76:77], off offset:1920
	s_nop 0
	global_load_dwordx4 v[76:79], v[78:79], off offset:1920
	s_nop 0
	global_load_dwordx4 v[144:147], v[80:81], off offset:1920
	ds_read_b128 v[228:231], v245 offset:55296
	ds_read_b128 v[212:215], v244 offset:18432
	ds_read_b128 v[236:239], v245 offset:57600
	ds_read_b128 v[240:243], v245 offset:59904
	ds_read_b128 v[252:255], v245 offset:62208
	ds_read_b128 v[216:219], v244 offset:20736
	ds_read_b128 v[220:223], v244 offset:23040
	ds_read_b128 v[224:227], v244 offset:25344
	s_waitcnt lgkmcnt(6)
	v_mfma_f32_16x16x32_bf16 v[50:53], v[212:215], v[228:231], v[50:53]
	s_waitcnt lgkmcnt(5)
	v_mfma_f32_16x16x32_bf16 v[54:57], v[212:215], v[236:239], v[54:57]
	s_waitcnt lgkmcnt(4)
	v_mfma_f32_16x16x32_bf16 v[34:37], v[212:215], v[240:243], v[34:37]
	s_waitcnt lgkmcnt(3)
	v_mfma_f32_16x16x32_bf16 v[38:41], v[212:215], v[252:255], v[38:41]
	ds_read_b128 v[212:215], v244 offset:18496
	s_waitcnt lgkmcnt(3)
	v_mfma_f32_16x16x32_bf16 v[58:61], v[216:219], v[228:231], v[58:61]
	v_mfma_f32_16x16x32_bf16 v[62:65], v[216:219], v[236:239], v[62:65]
	v_mfma_f32_16x16x32_bf16 v[42:45], v[216:219], v[240:243], v[42:45]
	v_mfma_f32_16x16x32_bf16 v[46:49], v[216:219], v[252:255], v[46:49]
	ds_read_b128 v[216:219], v244 offset:20800
	s_setprio 1
	s_waitcnt vmcnt(15)
	ds_write_b128 v165, v[180:183]
	s_waitcnt vmcnt(14)
	ds_write_b128 v165, v[184:187] offset:4608
	s_waitcnt lgkmcnt(5)
	v_mfma_f32_16x16x32_bf16 v[18:21], v[220:223], v[228:231], v[18:21]
	v_mfma_f32_16x16x32_bf16 v[22:25], v[220:223], v[236:239], v[22:25]
	v_mfma_f32_16x16x32_bf16 v[2:5], v[220:223], v[240:243], v[2:5]
	v_mfma_f32_16x16x32_bf16 v[6:9], v[220:223], v[252:255], v[6:9]
	ds_read_b128 v[220:223], v244 offset:23104
	s_waitcnt vmcnt(13)
	ds_write_b128 v165, v[188:191] offset:9216
	s_waitcnt vmcnt(12)
	ds_write_b128 v165, v[192:195] offset:13824
	s_waitcnt lgkmcnt(7)
	v_mfma_f32_16x16x32_bf16 v[26:29], v[224:227], v[228:231], v[26:29]
	ds_read_b128 v[228:231], v245 offset:55360
	v_mfma_f32_16x16x32_bf16 v[30:33], v[224:227], v[236:239], v[30:33]
	ds_read_b128 v[236:239], v245 offset:57664
	v_mfma_f32_16x16x32_bf16 v[10:13], v[224:227], v[240:243], v[10:13]
	ds_read_b128 v[240:243], v245 offset:59968
	v_mfma_f32_16x16x32_bf16 v[14:17], v[224:227], v[252:255], v[14:17]
	ds_read_b128 v[252:255], v245 offset:62272
	ds_read_b128 v[224:227], v244 offset:25408
	s_waitcnt lgkmcnt(4)
	v_mfma_f32_16x16x32_bf16 v[50:53], v[212:215], v[228:231], v[50:53]
	s_waitcnt lgkmcnt(3)
	v_mfma_f32_16x16x32_bf16 v[54:57], v[212:215], v[236:239], v[54:57]
	s_waitcnt lgkmcnt(2)
	v_mfma_f32_16x16x32_bf16 v[34:37], v[212:215], v[240:243], v[34:37]
	s_waitcnt lgkmcnt(1)
	v_mfma_f32_16x16x32_bf16 v[38:41], v[212:215], v[252:255], v[38:41]
	s_waitcnt vmcnt(11)
	ds_write_b128 v165, v[196:199] offset:36864
	s_waitcnt vmcnt(10)
	ds_write_b128 v165, v[200:203] offset:41472
	v_mfma_f32_16x16x32_bf16 v[58:61], v[216:219], v[228:231], v[58:61]
	v_mfma_f32_16x16x32_bf16 v[62:65], v[216:219], v[236:239], v[62:65]
	v_mfma_f32_16x16x32_bf16 v[42:45], v[216:219], v[240:243], v[42:45]
	v_mfma_f32_16x16x32_bf16 v[46:49], v[216:219], v[252:255], v[46:49]
	s_waitcnt vmcnt(9)
	ds_write_b128 v165, v[204:207] offset:46080
	s_waitcnt vmcnt(8)
	ds_write_b128 v165, v[208:211] offset:50688
	v_mfma_f32_16x16x32_bf16 v[18:21], v[220:223], v[228:231], v[18:21]
	v_mfma_f32_16x16x32_bf16 v[22:25], v[220:223], v[236:239], v[22:25]
	v_mfma_f32_16x16x32_bf16 v[2:5], v[220:223], v[240:243], v[2:5]
	v_mfma_f32_16x16x32_bf16 v[6:9], v[220:223], v[252:255], v[6:9]
	s_waitcnt lgkmcnt(4)
	v_mfma_f32_16x16x32_bf16 v[26:29], v[224:227], v[228:231], v[26:29]
	v_mfma_f32_16x16x32_bf16 v[30:33], v[224:227], v[236:239], v[30:33]
	v_mfma_f32_16x16x32_bf16 v[10:13], v[224:227], v[240:243], v[10:13]
	v_mfma_f32_16x16x32_bf16 v[14:17], v[224:227], v[252:255], v[14:17]
	s_waitcnt lgkmcnt(0)
	s_barrier
	s_setprio 0
	ds_read_b128 v[228:231], v245 offset:36864
	ds_read_b128 v[212:215], v244
	ds_read_b128 v[236:239], v245 offset:39168
	ds_read_b128 v[240:243], v245 offset:41472
	ds_read_b128 v[252:255], v245 offset:43776
	ds_read_b128 v[216:219], v244 offset:2304
	ds_read_b128 v[220:223], v244 offset:4608
	ds_read_b128 v[224:227], v244 offset:6912
	s_waitcnt lgkmcnt(6)
	v_mfma_f32_16x16x32_bf16 v[50:53], v[212:215], v[228:231], v[50:53]
	s_waitcnt lgkmcnt(5)
	v_mfma_f32_16x16x32_bf16 v[54:57], v[212:215], v[236:239], v[54:57]
	s_waitcnt lgkmcnt(4)
	v_mfma_f32_16x16x32_bf16 v[34:37], v[212:215], v[240:243], v[34:37]
	s_waitcnt lgkmcnt(3)
	v_mfma_f32_16x16x32_bf16 v[38:41], v[212:215], v[252:255], v[38:41]
	ds_read_b128 v[212:215], v244 offset:64
	s_waitcnt lgkmcnt(3)
	v_mfma_f32_16x16x32_bf16 v[58:61], v[216:219], v[228:231], v[58:61]
	v_mfma_f32_16x16x32_bf16 v[62:65], v[216:219], v[236:239], v[62:65]
	v_mfma_f32_16x16x32_bf16 v[42:45], v[216:219], v[240:243], v[42:45]
	v_mfma_f32_16x16x32_bf16 v[46:49], v[216:219], v[252:255], v[46:49]
	ds_read_b128 v[216:219], v244 offset:2368
	s_setprio 1
	s_waitcnt vmcnt(7)
	ds_write_b128 v165, v[122:125] offset:18432
	s_waitcnt vmcnt(6)
	ds_write_b128 v165, v[68:71] offset:23040
	s_waitcnt lgkmcnt(5)
	v_mfma_f32_16x16x32_bf16 v[18:21], v[220:223], v[228:231], v[18:21]
	v_mfma_f32_16x16x32_bf16 v[22:25], v[220:223], v[236:239], v[22:25]
	v_mfma_f32_16x16x32_bf16 v[2:5], v[220:223], v[240:243], v[2:5]
	v_mfma_f32_16x16x32_bf16 v[6:9], v[220:223], v[252:255], v[6:9]
	ds_read_b128 v[220:223], v244 offset:4672
	s_waitcnt vmcnt(5)
	ds_write_b128 v165, v[126:129] offset:27648
	s_waitcnt vmcnt(4)
	ds_write_b128 v165, v[136:139] offset:32256
	s_waitcnt lgkmcnt(7)
	v_mfma_f32_16x16x32_bf16 v[26:29], v[224:227], v[228:231], v[26:29]
	ds_read_b128 v[228:231], v245 offset:36928
	v_mfma_f32_16x16x32_bf16 v[30:33], v[224:227], v[236:239], v[30:33]
	ds_read_b128 v[236:239], v245 offset:39232
	v_mfma_f32_16x16x32_bf16 v[10:13], v[224:227], v[240:243], v[10:13]
	ds_read_b128 v[240:243], v245 offset:41536
	v_mfma_f32_16x16x32_bf16 v[14:17], v[224:227], v[252:255], v[14:17]
	ds_read_b128 v[252:255], v245 offset:43840
	ds_read_b128 v[224:227], v244 offset:6976
	s_waitcnt lgkmcnt(4)
	v_mfma_f32_16x16x32_bf16 v[50:53], v[212:215], v[228:231], v[50:53]
	s_waitcnt lgkmcnt(3)
	v_mfma_f32_16x16x32_bf16 v[54:57], v[212:215], v[236:239], v[54:57]
	s_waitcnt lgkmcnt(2)
	v_mfma_f32_16x16x32_bf16 v[34:37], v[212:215], v[240:243], v[34:37]
	s_waitcnt lgkmcnt(1)
	v_mfma_f32_16x16x32_bf16 v[38:41], v[212:215], v[252:255], v[38:41]
	s_waitcnt vmcnt(3)
	ds_write_b128 v165, v[72:75] offset:55296
	s_waitcnt vmcnt(2)
	ds_write_b128 v165, v[140:143] offset:59904
	v_mfma_f32_16x16x32_bf16 v[58:61], v[216:219], v[228:231], v[58:61]
	v_mfma_f32_16x16x32_bf16 v[62:65], v[216:219], v[236:239], v[62:65]
	v_mfma_f32_16x16x32_bf16 v[42:45], v[216:219], v[240:243], v[42:45]
	v_mfma_f32_16x16x32_bf16 v[46:49], v[216:219], v[252:255], v[46:49]
	s_waitcnt vmcnt(1)
	ds_write_b128 v165, v[76:79] offset:64512
	s_waitcnt vmcnt(0)
	ds_write_b128 v166, v[144:147] offset:32256
	v_mfma_f32_16x16x32_bf16 v[18:21], v[220:223], v[228:231], v[18:21]
	v_mfma_f32_16x16x32_bf16 v[22:25], v[220:223], v[236:239], v[22:25]
	v_mfma_f32_16x16x32_bf16 v[2:5], v[220:223], v[240:243], v[2:5]
	v_mfma_f32_16x16x32_bf16 v[6:9], v[220:223], v[252:255], v[6:9]
	s_waitcnt lgkmcnt(4)
	v_mfma_f32_16x16x32_bf16 v[26:29], v[224:227], v[228:231], v[26:29]
	v_mfma_f32_16x16x32_bf16 v[30:33], v[224:227], v[236:239], v[30:33]
	v_mfma_f32_16x16x32_bf16 v[10:13], v[224:227], v[240:243], v[10:13]
	v_mfma_f32_16x16x32_bf16 v[14:17], v[224:227], v[252:255], v[14:17]
	s_waitcnt lgkmcnt(0)
	s_barrier
	s_setprio 0
	ds_read_b128 v[228:231], v245 offset:55296
	ds_read_b128 v[212:215], v244 offset:18432
	ds_read_b128 v[236:239], v245 offset:57600
	ds_read_b128 v[240:243], v245 offset:59904
	ds_read_b128 v[252:255], v245 offset:62208
	ds_read_b128 v[216:219], v244 offset:20736
	ds_read_b128 v[220:223], v244 offset:23040
	ds_read_b128 v[224:227], v244 offset:25344
	s_waitcnt lgkmcnt(6)
	v_mfma_f32_16x16x32_bf16 v[50:53], v[212:215], v[228:231], v[50:53]
	s_waitcnt lgkmcnt(5)
	v_mfma_f32_16x16x32_bf16 v[54:57], v[212:215], v[236:239], v[54:57]
	s_waitcnt lgkmcnt(4)
	v_mfma_f32_16x16x32_bf16 v[34:37], v[212:215], v[240:243], v[34:37]
	s_waitcnt lgkmcnt(3)
	v_mfma_f32_16x16x32_bf16 v[38:41], v[212:215], v[252:255], v[38:41]
	ds_read_b128 v[212:215], v244 offset:18496
	s_waitcnt lgkmcnt(3)
	v_mfma_f32_16x16x32_bf16 v[58:61], v[216:219], v[228:231], v[58:61]
	v_mfma_f32_16x16x32_bf16 v[62:65], v[216:219], v[236:239], v[62:65]
	v_mfma_f32_16x16x32_bf16 v[42:45], v[216:219], v[240:243], v[42:45]
	v_mfma_f32_16x16x32_bf16 v[46:49], v[216:219], v[252:255], v[46:49]
	ds_read_b128 v[216:219], v244 offset:20800
	s_waitcnt lgkmcnt(3)
	v_mfma_f32_16x16x32_bf16 v[18:21], v[220:223], v[228:231], v[18:21]
	v_mfma_f32_16x16x32_bf16 v[22:25], v[220:223], v[236:239], v[22:25]
	v_mfma_f32_16x16x32_bf16 v[2:5], v[220:223], v[240:243], v[2:5]
	v_mfma_f32_16x16x32_bf16 v[6:9], v[220:223], v[252:255], v[6:9]
	ds_read_b128 v[220:223], v244 offset:23104
	s_waitcnt lgkmcnt(3)
	v_mfma_f32_16x16x32_bf16 v[26:29], v[224:227], v[228:231], v[26:29]
	ds_read_b128 v[228:231], v245 offset:55360
	v_mfma_f32_16x16x32_bf16 v[30:33], v[224:227], v[236:239], v[30:33]
	ds_read_b128 v[236:239], v245 offset:57664
	v_mfma_f32_16x16x32_bf16 v[10:13], v[224:227], v[240:243], v[10:13]
	ds_read_b128 v[240:243], v245 offset:59968
	v_mfma_f32_16x16x32_bf16 v[14:17], v[224:227], v[252:255], v[14:17]
	ds_read_b128 v[252:255], v245 offset:62272
	ds_read_b128 v[224:227], v244 offset:25408
	s_waitcnt lgkmcnt(4)
	v_mfma_f32_16x16x32_bf16 v[50:53], v[212:215], v[228:231], v[50:53]
	s_waitcnt lgkmcnt(3)
	v_mfma_f32_16x16x32_bf16 v[54:57], v[212:215], v[236:239], v[54:57]
	s_waitcnt lgkmcnt(2)
	v_mfma_f32_16x16x32_bf16 v[34:37], v[212:215], v[240:243], v[34:37]
	s_waitcnt lgkmcnt(1)
	v_mfma_f32_16x16x32_bf16 v[38:41], v[212:215], v[252:255], v[38:41]
	v_mfma_f32_16x16x32_bf16 v[58:61], v[216:219], v[228:231], v[58:61]
	v_mfma_f32_16x16x32_bf16 v[62:65], v[216:219], v[236:239], v[62:65]
	v_mfma_f32_16x16x32_bf16 v[42:45], v[216:219], v[240:243], v[42:45]
	v_mfma_f32_16x16x32_bf16 v[46:49], v[216:219], v[252:255], v[46:49]
	v_mfma_f32_16x16x32_bf16 v[18:21], v[220:223], v[228:231], v[18:21]
	v_mfma_f32_16x16x32_bf16 v[22:25], v[220:223], v[236:239], v[22:25]
	v_mfma_f32_16x16x32_bf16 v[2:5], v[220:223], v[240:243], v[2:5]
	v_mfma_f32_16x16x32_bf16 v[6:9], v[220:223], v[252:255], v[6:9]
	s_waitcnt lgkmcnt(0)
	v_mfma_f32_16x16x32_bf16 v[26:29], v[224:227], v[228:231], v[26:29]
	v_mfma_f32_16x16x32_bf16 v[30:33], v[224:227], v[236:239], v[30:33]
	v_mfma_f32_16x16x32_bf16 v[10:13], v[224:227], v[240:243], v[10:13]
	v_mfma_f32_16x16x32_bf16 v[14:17], v[224:227], v[252:255], v[14:17]
	s_waitcnt lgkmcnt(0)
	s_barrier
	s_nop 7
	v_permlane16_swap_b32_e32 v50, v54
	v_permlane16_swap_b32_e32 v51, v55
	v_permlane16_swap_b32_e32 v52, v56
	v_permlane16_swap_b32_e32 v53, v57
	v_permlane16_swap_b32_e32 v58, v62
	v_permlane16_swap_b32_e32 v59, v63
	v_permlane16_swap_b32_e32 v60, v64
	v_permlane16_swap_b32_e32 v61, v65
	v_permlane16_swap_b32_e32 v34, v38
	v_permlane16_swap_b32_e32 v35, v39
	v_permlane16_swap_b32_e32 v36, v40
	v_permlane16_swap_b32_e32 v37, v41
	v_permlane16_swap_b32_e32 v42, v46
	v_permlane16_swap_b32_e32 v43, v47
	v_permlane16_swap_b32_e32 v44, v48
	v_permlane16_swap_b32_e32 v45, v49
	v_permlane16_swap_b32_e32 v18, v22
	v_permlane16_swap_b32_e32 v19, v23
	v_permlane16_swap_b32_e32 v20, v24
	v_permlane16_swap_b32_e32 v21, v25
	v_permlane16_swap_b32_e32 v26, v30
	v_permlane16_swap_b32_e32 v27, v31
	v_permlane16_swap_b32_e32 v28, v32
	v_permlane16_swap_b32_e32 v29, v33
	v_permlane16_swap_b32_e32 v2, v6
	v_permlane16_swap_b32_e32 v3, v7
	v_permlane16_swap_b32_e32 v4, v8
	v_permlane16_swap_b32_e32 v5, v9
	v_permlane16_swap_b32_e32 v10, v14
	v_permlane16_swap_b32_e32 v11, v15
	v_permlane16_swap_b32_e32 v12, v16
	v_permlane16_swap_b32_e32 v13, v17
	v_permlane32_swap_b32_e32 v50, v54
	v_permlane32_swap_b32_e32 v51, v55
	v_permlane32_swap_b32_e32 v52, v56
	v_permlane32_swap_b32_e32 v53, v57
	v_permlane32_swap_b32_e32 v58, v62
	v_permlane32_swap_b32_e32 v59, v63
	v_permlane32_swap_b32_e32 v60, v64
	v_permlane32_swap_b32_e32 v61, v65
	v_permlane32_swap_b32_e32 v34, v38
	v_permlane32_swap_b32_e32 v35, v39
	v_permlane32_swap_b32_e32 v36, v40
	v_permlane32_swap_b32_e32 v37, v41
	v_permlane32_swap_b32_e32 v42, v46
	v_permlane32_swap_b32_e32 v43, v47
	v_permlane32_swap_b32_e32 v44, v48
	v_permlane32_swap_b32_e32 v45, v49
	v_permlane32_swap_b32_e32 v18, v22
	v_permlane32_swap_b32_e32 v19, v23
	v_permlane32_swap_b32_e32 v20, v24
	v_permlane32_swap_b32_e32 v21, v25
	v_permlane32_swap_b32_e32 v26, v30
	v_permlane32_swap_b32_e32 v27, v31
	v_permlane32_swap_b32_e32 v28, v32
	v_permlane32_swap_b32_e32 v29, v33
	v_permlane32_swap_b32_e32 v2, v6
	v_permlane32_swap_b32_e32 v3, v7
	v_permlane32_swap_b32_e32 v4, v8
	v_permlane32_swap_b32_e32 v5, v9
	v_permlane32_swap_b32_e32 v10, v14
	v_permlane32_swap_b32_e32 v11, v15
	v_permlane32_swap_b32_e32 v12, v16
	v_permlane32_swap_b32_e32 v13, v17

.LBB0_749:
	s_and_b32 s3, s2, 0xffff
	s_mul_i32 s3, s3, 0xaaab
	s_lshr_b32 s3, s3, 18
	s_mul_i32 s10, s3, 6
	s_sub_i32 s2, s2, s10
	s_and_b32 s2, s2, 0xffff
	s_add_i32 s2, s6, s2
	s_lshl_b32 s10, s2, 7
	v_or_b32_e32 v2, s10, v91
	v_lshlrev_b32_e32 v66, 11, v2
	v_lshl_add_u64 v[74:75], v[68:69], 0, v[66:67]
	v_add_lshl_u32 v66, s10, v92, 11
	s_add_i32 s3, s8, s3
	v_lshl_add_u64 v[76:77], v[68:69], 0, v[66:67]
	v_add_lshl_u32 v66, s10, v93, 11
	s_lshl_b32 s11, s3, 7
	v_lshl_add_u64 v[78:79], v[68:69], 0, v[66:67]
	v_add_lshl_u32 v66, s10, v94, 11
	v_lshl_add_u64 v[80:81], v[68:69], 0, v[66:67]
	v_or_b32_e32 v66, s11, v91
	v_lshlrev_b64 v[2:3], 11, v[66:67]
	v_add_u32_e32 v66, s11, v92
	v_lshl_add_u64 v[82:83], v[70:71], 0, v[2:3]
	v_lshlrev_b64 v[2:3], 11, v[66:67]
	v_add_u32_e32 v66, s11, v93
	v_lshl_add_u64 v[84:85], v[70:71], 0, v[2:3]
	v_lshlrev_b64 v[2:3], 11, v[66:67]
	v_add_u32_e32 v66, s11, v94
	v_lshl_add_u64 v[86:87], v[70:71], 0, v[2:3]
	v_lshlrev_b64 v[2:3], 11, v[66:67]
	v_lshl_add_u64 v[88:89], v[70:71], 0, v[2:3]
	global_load_dwordx4 v[2:5], v[74:75], off
	global_load_dwordx4 v[6:9], v[76:77], off
	global_load_dwordx4 v[10:13], v[78:79], off
	global_load_dwordx4 v[14:17], v[80:81], off
	global_load_dwordx4 v[18:21], v[82:83], off
	global_load_dwordx4 v[22:25], v[84:85], off
	global_load_dwordx4 v[26:29], v[86:87], off
	global_load_dwordx4 v[30:33], v[88:89], off
	global_load_dwordx4 v[102:105], v[74:75], off offset:128
	global_load_dwordx4 v[106:109], v[76:77], off offset:128
	global_load_dwordx4 v[110:113], v[78:79], off offset:128
	global_load_dwordx4 v[114:117], v[80:81], off offset:128
	global_load_dwordx4 v[118:121], v[82:83], off offset:128
	global_load_dwordx4 v[122:125], v[84:85], off offset:128
	global_load_dwordx4 v[126:129], v[86:87], off offset:128
	global_load_dwordx4 v[136:139], v[88:89], off offset:128
	s_waitcnt vmcnt(15)
	ds_write_b128 v98, v[2:5]
	s_waitcnt vmcnt(14)
	ds_write_b128 v98, v[6:9] offset:4608
	s_waitcnt vmcnt(13)
	ds_write_b128 v98, v[10:13] offset:9216
	s_waitcnt vmcnt(12)
	ds_write_b128 v98, v[14:17] offset:13824
	s_waitcnt vmcnt(11)
	ds_write_b128 v98, v[18:21] offset:36864
	s_waitcnt vmcnt(10)
	ds_write_b128 v98, v[22:25] offset:41472
	s_waitcnt vmcnt(9)
	ds_write_b128 v98, v[26:29] offset:46080
	s_waitcnt vmcnt(8)
	ds_write_b128 v98, v[30:33] offset:50688
	s_waitcnt lgkmcnt(0)
	s_barrier
	global_load_dwordx4 v[140:143], v[74:75], off offset:256
	global_load_dwordx4 v[144:147], v[76:77], off offset:256
	global_load_dwordx4 v[148:151], v[78:79], off offset:256
	global_load_dwordx4 v[152:155], v[80:81], off offset:256
	global_load_dwordx4 v[156:159], v[82:83], off offset:256
	global_load_dwordx4 v[160:163], v[84:85], off offset:256
	global_load_dwordx4 v[164:167], v[86:87], off offset:256
	global_load_dwordx4 v[168:171], v[88:89], off offset:256
	v_and_b32_e32 v246, 15, v1
	v_add_u32_e32 v246, 4, v246
	v_bfe_u32 v246, v246, 3, 1
	v_bfe_u32 v249, v1, 4, 2
	v_xor_b32_e32 v246, v246, v249
	v_bfe_u32 v249, v1, 5, 1
	v_sub_u32_e32 v246, v246, v249
	v_lshlrev_b32_e32 v246, 4, v246
	v_bfe_u32 v249, v1, 4, 1
	v_mul_u32_u24_e32 v249, 0x900, v249
	v_sub_u32_e32 v246, v246, v249
	v_add_u32_e32 v244, v246, v96
	v_add_u32_e32 v245, v246, v97
	ds_read_b128 v[212:215], v245 offset:36864
	ds_read_b128 v[196:199], v244
	ds_read_b128 v[216:219], v245 offset:39168
	ds_read_b128 v[220:223], v245 offset:41472
	ds_read_b128 v[224:227], v245 offset:43776
	ds_read_b128 v[200:203], v244 offset:2304
	ds_read_b128 v[204:207], v244 offset:4608
	ds_read_b128 v[208:211], v244 offset:6912
	s_waitcnt lgkmcnt(6)
	v_mfma_f32_16x16x32_bf16 v[50:53], v[196:199], v[212:215], 0
	ds_read_b128 v[228:231], v245 offset:36928
	s_waitcnt lgkmcnt(6)
	v_mfma_f32_16x16x32_bf16 v[54:57], v[196:199], v[216:219], 0
	ds_read_b128 v[232:235], v245 offset:39232
	s_waitcnt lgkmcnt(6)
	v_mfma_f32_16x16x32_bf16 v[18:21], v[196:199], v[220:223], 0
	ds_read_b128 v[236:239], v245 offset:41536
	s_waitcnt lgkmcnt(6)
	v_mfma_f32_16x16x32_bf16 v[22:25], v[196:199], v[224:227], 0
	ds_read_b128 v[240:243], v245 offset:43840
	ds_read_b128 v[196:199], v244 offset:64
	s_waitcnt lgkmcnt(7)
	v_mfma_f32_16x16x32_bf16 v[58:61], v[200:203], v[212:215], 0
	v_mfma_f32_16x16x32_bf16 v[62:65], v[200:203], v[216:219], 0
	v_mfma_f32_16x16x32_bf16 v[26:29], v[200:203], v[220:223], 0
	v_mfma_f32_16x16x32_bf16 v[30:33], v[200:203], v[224:227], 0
	ds_read_b128 v[200:203], v244 offset:2368
	s_waitcnt lgkmcnt(7)
	v_mfma_f32_16x16x32_bf16 v[34:37], v[204:207], v[212:215], 0
	v_mfma_f32_16x16x32_bf16 v[38:41], v[204:207], v[216:219], 0
	v_mfma_f32_16x16x32_bf16 v[2:5], v[204:207], v[220:223], 0
	v_mfma_f32_16x16x32_bf16 v[6:9], v[204:207], v[224:227], 0
	ds_read_b128 v[204:207], v244 offset:4672
	s_setprio 1
	s_waitcnt vmcnt(15)
	ds_write_b128 v98, v[102:105] offset:18432
	s_waitcnt vmcnt(14)
	ds_write_b128 v98, v[106:109] offset:23040
	s_waitcnt lgkmcnt(9)
	v_mfma_f32_16x16x32_bf16 v[42:45], v[208:211], v[212:215], 0
	v_mfma_f32_16x16x32_bf16 v[46:49], v[208:211], v[216:219], 0
	v_mfma_f32_16x16x32_bf16 v[10:13], v[208:211], v[220:223], 0
	v_mfma_f32_16x16x32_bf16 v[14:17], v[208:211], v[224:227], 0
	ds_read_b128 v[208:211], v244 offset:6976
	s_waitcnt vmcnt(13)
	ds_write_b128 v98, v[110:113] offset:27648
	s_waitcnt vmcnt(12)
	ds_write_b128 v98, v[114:117] offset:32256
	s_waitcnt lgkmcnt(7)
	v_mfma_f32_16x16x32_bf16 v[50:53], v[196:199], v[228:231], v[50:53]
	v_mfma_f32_16x16x32_bf16 v[54:57], v[196:199], v[232:235], v[54:57]
	v_mfma_f32_16x16x32_bf16 v[18:21], v[196:199], v[236:239], v[18:21]
	v_mfma_f32_16x16x32_bf16 v[22:25], v[196:199], v[240:243], v[22:25]
	s_waitcnt vmcnt(11)
	ds_write_b128 v98, v[118:121] offset:55296
	s_waitcnt vmcnt(10)
	ds_write_b128 v98, v[122:125] offset:59904
	s_waitcnt lgkmcnt(8)
	v_mfma_f32_16x16x32_bf16 v[58:61], v[200:203], v[228:231], v[58:61]
	v_mfma_f32_16x16x32_bf16 v[62:65], v[200:203], v[232:235], v[62:65]
	v_mfma_f32_16x16x32_bf16 v[26:29], v[200:203], v[236:239], v[26:29]
	v_mfma_f32_16x16x32_bf16 v[30:33], v[200:203], v[240:243], v[30:33]
	s_waitcnt vmcnt(9)
	ds_write_b128 v98, v[126:129] offset:64512
	s_waitcnt vmcnt(8)
	ds_write_b128 v99, v[136:139] offset:32256
	s_waitcnt lgkmcnt(0)
	s_barrier
	s_setprio 0
	ds_read_b128 v[212:215], v245 offset:55296
	ds_read_b128 v[196:199], v244 offset:18432
	ds_read_b128 v[216:219], v245 offset:57600
	ds_read_b128 v[220:223], v245 offset:59904
	ds_read_b128 v[224:227], v245 offset:62208
	ds_read_b128 v[200:203], v244 offset:20736
	v_mfma_f32_16x16x32_bf16 v[34:37], v[204:207], v[228:231], v[34:37]
	v_mfma_f32_16x16x32_bf16 v[38:41], v[204:207], v[232:235], v[38:41]
	v_mfma_f32_16x16x32_bf16 v[2:5], v[204:207], v[236:239], v[2:5]
	v_mfma_f32_16x16x32_bf16 v[6:9], v[204:207], v[240:243], v[6:9]
	ds_read_b128 v[204:207], v244 offset:23040
	v_mfma_f32_16x16x32_bf16 v[42:45], v[208:211], v[228:231], v[42:45]
	v_mfma_f32_16x16x32_bf16 v[46:49], v[208:211], v[232:235], v[46:49]
	v_mfma_f32_16x16x32_bf16 v[10:13], v[208:211], v[236:239], v[10:13]
	v_mfma_f32_16x16x32_bf16 v[14:17], v[208:211], v[240:243], v[14:17]
	ds_read_b128 v[208:211], v244 offset:25344
	global_load_dwordx4 v[102:105], v[74:75], off offset:384
	global_load_dwordx4 v[106:109], v[76:77], off offset:384
	global_load_dwordx4 v[110:113], v[78:79], off offset:384
	global_load_dwordx4 v[114:117], v[80:81], off offset:384
	global_load_dwordx4 v[118:121], v[82:83], off offset:384
	global_load_dwordx4 v[122:125], v[84:85], off offset:384
	global_load_dwordx4 v[126:129], v[86:87], off offset:384
	global_load_dwordx4 v[136:139], v[88:89], off offset:384
	s_waitcnt lgkmcnt(6)
	v_mfma_f32_16x16x32_bf16 v[50:53], v[196:199], v[212:215], v[50:53]
	ds_read_b128 v[228:231], v245 offset:55360
	s_waitcnt lgkmcnt(6)
	v_mfma_f32_16x16x32_bf16 v[54:57], v[196:199], v[216:219], v[54:57]
	ds_read_b128 v[232:235], v245 offset:57664
	s_waitcnt lgkmcnt(6)
	v_mfma_f32_16x16x32_bf16 v[18:21], v[196:199], v[220:223], v[18:21]
	ds_read_b128 v[236:239], v245 offset:59968
	s_waitcnt lgkmcnt(6)
	v_mfma_f32_16x16x32_bf16 v[22:25], v[196:199], v[224:227], v[22:25]
	ds_read_b128 v[240:243], v245 offset:62272
	ds_read_b128 v[196:199], v244 offset:18496
	s_waitcnt lgkmcnt(7)
	v_mfma_f32_16x16x32_bf16 v[58:61], v[200:203], v[212:215], v[58:61]
	v_mfma_f32_16x16x32_bf16 v[62:65], v[200:203], v[216:219], v[62:65]
	v_mfma_f32_16x16x32_bf16 v[26:29], v[200:203], v[220:223], v[26:29]
	v_mfma_f32_16x16x32_bf16 v[30:33], v[200:203], v[224:227], v[30:33]
	ds_read_b128 v[200:203], v244 offset:20800
	s_waitcnt lgkmcnt(7)
	v_mfma_f32_16x16x32_bf16 v[34:37], v[204:207], v[212:215], v[34:37]
	v_mfma_f32_16x16x32_bf16 v[38:41], v[204:207], v[216:219], v[38:41]
	v_mfma_f32_16x16x32_bf16 v[2:5], v[204:207], v[220:223], v[2:5]
	v_mfma_f32_16x16x32_bf16 v[6:9], v[204:207], v[224:227], v[6:9]
	ds_read_b128 v[204:207], v244 offset:23104
	s_setprio 1
	s_waitcnt vmcnt(15)
	ds_write_b128 v98, v[140:143]
	s_waitcnt vmcnt(14)
	ds_write_b128 v98, v[144:147] offset:4608
	s_waitcnt lgkmcnt(9)
	v_mfma_f32_16x16x32_bf16 v[42:45], v[208:211], v[212:215], v[42:45]
	v_mfma_f32_16x16x32_bf16 v[46:49], v[208:211], v[216:219], v[46:49]
	v_mfma_f32_16x16x32_bf16 v[10:13], v[208:211], v[220:223], v[10:13]
	v_mfma_f32_16x16x32_bf16 v[14:17], v[208:211], v[224:227], v[14:17]
	ds_read_b128 v[208:211], v244 offset:25408
	s_waitcnt vmcnt(13)
	ds_write_b128 v98, v[148:151] offset:9216
	s_waitcnt vmcnt(12)
	ds_write_b128 v98, v[152:155] offset:13824
	s_waitcnt lgkmcnt(7)
	v_mfma_f32_16x16x32_bf16 v[50:53], v[196:199], v[228:231], v[50:53]
	v_mfma_f32_16x16x32_bf16 v[54:57], v[196:199], v[232:235], v[54:57]
	v_mfma_f32_16x16x32_bf16 v[18:21], v[196:199], v[236:239], v[18:21]
	v_mfma_f32_16x16x32_bf16 v[22:25], v[196:199], v[240:243], v[22:25]
	s_waitcnt vmcnt(11)
	ds_write_b128 v98, v[156:159] offset:36864
	s_waitcnt vmcnt(10)
	ds_write_b128 v98, v[160:163] offset:41472
	s_waitcnt lgkmcnt(8)
	v_mfma_f32_16x16x32_bf16 v[58:61], v[200:203], v[228:231], v[58:61]
	v_mfma_f32_16x16x32_bf16 v[62:65], v[200:203], v[232:235], v[62:65]
	v_mfma_f32_16x16x32_bf16 v[26:29], v[200:203], v[236:239], v[26:29]
	v_mfma_f32_16x16x32_bf16 v[30:33], v[200:203], v[240:243], v[30:33]
	s_waitcnt vmcnt(9)
	ds_write_b128 v98, v[164:167] offset:46080
	s_waitcnt vmcnt(8)
	ds_write_b128 v98, v[168:171] offset:50688
	s_waitcnt lgkmcnt(0)
	s_barrier
	s_setprio 0
	ds_read_b128 v[212:215], v245 offset:36864
	ds_read_b128 v[196:199], v244
	ds_read_b128 v[216:219], v245 offset:39168
	ds_read_b128 v[220:223], v245 offset:41472
	ds_read_b128 v[224:227], v245 offset:43776
	ds_read_b128 v[200:203], v244 offset:2304
	v_mfma_f32_16x16x32_bf16 v[34:37], v[204:207], v[228:231], v[34:37]
	v_mfma_f32_16x16x32_bf16 v[38:41], v[204:207], v[232:235], v[38:41]
	v_mfma_f32_16x16x32_bf16 v[2:5], v[204:207], v[236:239], v[2:5]
	v_mfma_f32_16x16x32_bf16 v[6:9], v[204:207], v[240:243], v[6:9]
	ds_read_b128 v[204:207], v244 offset:4608
	v_mfma_f32_16x16x32_bf16 v[42:45], v[208:211], v[228:231], v[42:45]
	v_mfma_f32_16x16x32_bf16 v[46:49], v[208:211], v[232:235], v[46:49]
	v_mfma_f32_16x16x32_bf16 v[10:13], v[208:211], v[236:239], v[10:13]
	v_mfma_f32_16x16x32_bf16 v[14:17], v[208:211], v[240:243], v[14:17]
	ds_read_b128 v[208:211], v244 offset:6912
	global_load_dwordx4 v[140:143], v[74:75], off offset:512
	global_load_dwordx4 v[144:147], v[76:77], off offset:512
	global_load_dwordx4 v[148:151], v[78:79], off offset:512
	global_load_dwordx4 v[152:155], v[80:81], off offset:512
	global_load_dwordx4 v[156:159], v[82:83], off offset:512
	global_load_dwordx4 v[160:163], v[84:85], off offset:512
	global_load_dwordx4 v[164:167], v[86:87], off offset:512
	global_load_dwordx4 v[168:171], v[88:89], off offset:512
	s_waitcnt lgkmcnt(6)
	v_mfma_f32_16x16x32_bf16 v[50:53], v[196:199], v[212:215], v[50:53]
	ds_read_b128 v[228:231], v245 offset:36928
	s_waitcnt lgkmcnt(6)
	v_mfma_f32_16x16x32_bf16 v[54:57], v[196:199], v[216:219], v[54:57]
	ds_read_b128 v[232:235], v245 offset:39232
	s_waitcnt lgkmcnt(6)
	v_mfma_f32_16x16x32_bf16 v[18:21], v[196:199], v[220:223], v[18:21]
	ds_read_b128 v[236:239], v245 offset:41536
	s_waitcnt lgkmcnt(6)
	v_mfma_f32_16x16x32_bf16 v[22:25], v[196:199], v[224:227], v[22:25]
	ds_read_b128 v[240:243], v245 offset:43840
	ds_read_b128 v[196:199], v244 offset:64
	s_waitcnt lgkmcnt(7)
	v_mfma_f32_16x16x32_bf16 v[58:61], v[200:203], v[212:215], v[58:61]
	v_mfma_f32_16x16x32_bf16 v[62:65], v[200:203], v[216:219], v[62:65]
	v_mfma_f32_16x16x32_bf16 v[26:29], v[200:203], v[220:223], v[26:29]
	v_mfma_f32_16x16x32_bf16 v[30:33], v[200:203], v[224:227], v[30:33]
	ds_read_b128 v[200:203], v244 offset:2368
	s_waitcnt lgkmcnt(7)
	v_mfma_f32_16x16x32_bf16 v[34:37], v[204:207], v[212:215], v[34:37]
	v_mfma_f32_16x16x32_bf16 v[38:41], v[204:207], v[216:219], v[38:41]
	v_mfma_f32_16x16x32_bf16 v[2:5], v[204:207], v[220:223], v[2:5]
	v_mfma_f32_16x16x32_bf16 v[6:9], v[204:207], v[224:227], v[6:9]
	ds_read_b128 v[204:207], v244 offset:4672
	s_setprio 1
	s_waitcnt vmcnt(15)
	ds_write_b128 v98, v[102:105] offset:18432
	s_waitcnt vmcnt(14)
	ds_write_b128 v98, v[106:109] offset:23040
	s_waitcnt lgkmcnt(9)
	v_mfma_f32_16x16x32_bf16 v[42:45], v[208:211], v[212:215], v[42:45]
	v_mfma_f32_16x16x32_bf16 v[46:49], v[208:211], v[216:219], v[46:49]
	v_mfma_f32_16x16x32_bf16 v[10:13], v[208:211], v[220:223], v[10:13]
	v_mfma_f32_16x16x32_bf16 v[14:17], v[208:211], v[224:227], v[14:17]
	ds_read_b128 v[208:211], v244 offset:6976
	s_waitcnt vmcnt(13)
	ds_write_b128 v98, v[110:113] offset:27648
	s_waitcnt vmcnt(12)
	ds_write_b128 v98, v[114:117] offset:32256
	s_waitcnt lgkmcnt(7)
	v_mfma_f32_16x16x32_bf16 v[50:53], v[196:199], v[228:231], v[50:53]
	v_mfma_f32_16x16x32_bf16 v[54:57], v[196:199], v[232:235], v[54:57]
	v_mfma_f32_16x16x32_bf16 v[18:21], v[196:199], v[236:239], v[18:21]
	v_mfma_f32_16x16x32_bf16 v[22:25], v[196:199], v[240:243], v[22:25]
	s_waitcnt vmcnt(11)
	ds_write_b128 v98, v[118:121] offset:55296
	s_waitcnt vmcnt(10)
	ds_write_b128 v98, v[122:125] offset:59904
	s_waitcnt lgkmcnt(8)
	v_mfma_f32_16x16x32_bf16 v[58:61], v[200:203], v[228:231], v[58:61]
	v_mfma_f32_16x16x32_bf16 v[62:65], v[200:203], v[232:235], v[62:65]
	v_mfma_f32_16x16x32_bf16 v[26:29], v[200:203], v[236:239], v[26:29]
	v_mfma_f32_16x16x32_bf16 v[30:33], v[200:203], v[240:243], v[30:33]
	s_waitcnt vmcnt(9)
	ds_write_b128 v98, v[126:129] offset:64512
	s_waitcnt vmcnt(8)
	ds_write_b128 v99, v[136:139] offset:32256
	s_waitcnt lgkmcnt(0)
	s_barrier
	s_setprio 0
	ds_read_b128 v[212:215], v245 offset:55296
	ds_read_b128 v[196:199], v244 offset:18432
	ds_read_b128 v[216:219], v245 offset:57600
	ds_read_b128 v[220:223], v245 offset:59904
	ds_read_b128 v[224:227], v245 offset:62208
	ds_read_b128 v[200:203], v244 offset:20736
	v_mfma_f32_16x16x32_bf16 v[34:37], v[204:207], v[228:231], v[34:37]
	v_mfma_f32_16x16x32_bf16 v[38:41], v[204:207], v[232:235], v[38:41]
	v_mfma_f32_16x16x32_bf16 v[2:5], v[204:207], v[236:239], v[2:5]
	v_mfma_f32_16x16x32_bf16 v[6:9], v[204:207], v[240:243], v[6:9]
	ds_read_b128 v[204:207], v244 offset:23040
	v_mfma_f32_16x16x32_bf16 v[42:45], v[208:211], v[228:231], v[42:45]
	v_mfma_f32_16x16x32_bf16 v[46:49], v[208:211], v[232:235], v[46:49]
	v_mfma_f32_16x16x32_bf16 v[10:13], v[208:211], v[236:239], v[10:13]
	v_mfma_f32_16x16x32_bf16 v[14:17], v[208:211], v[240:243], v[14:17]
	ds_read_b128 v[208:211], v244 offset:25344
	global_load_dwordx4 v[102:105], v[74:75], off offset:640
	global_load_dwordx4 v[106:109], v[76:77], off offset:640
	global_load_dwordx4 v[110:113], v[78:79], off offset:640
	global_load_dwordx4 v[114:117], v[80:81], off offset:640
	global_load_dwordx4 v[118:121], v[82:83], off offset:640
	global_load_dwordx4 v[122:125], v[84:85], off offset:640
	global_load_dwordx4 v[126:129], v[86:87], off offset:640
	global_load_dwordx4 v[136:139], v[88:89], off offset:640
	s_waitcnt lgkmcnt(6)
	v_mfma_f32_16x16x32_bf16 v[50:53], v[196:199], v[212:215], v[50:53]
	ds_read_b128 v[228:231], v245 offset:55360
	s_waitcnt lgkmcnt(6)
	v_mfma_f32_16x16x32_bf16 v[54:57], v[196:199], v[216:219], v[54:57]
	ds_read_b128 v[232:235], v245 offset:57664
	s_waitcnt lgkmcnt(6)
	v_mfma_f32_16x16x32_bf16 v[18:21], v[196:199], v[220:223], v[18:21]
	ds_read_b128 v[236:239], v245 offset:59968
	s_waitcnt lgkmcnt(6)
	v_mfma_f32_16x16x32_bf16 v[22:25], v[196:199], v[224:227], v[22:25]
	ds_read_b128 v[240:243], v245 offset:62272
	ds_read_b128 v[196:199], v244 offset:18496
	s_waitcnt lgkmcnt(7)
	v_mfma_f32_16x16x32_bf16 v[58:61], v[200:203], v[212:215], v[58:61]
	v_mfma_f32_16x16x32_bf16 v[62:65], v[200:203], v[216:219], v[62:65]
	v_mfma_f32_16x16x32_bf16 v[26:29], v[200:203], v[220:223], v[26:29]
	v_mfma_f32_16x16x32_bf16 v[30:33], v[200:203], v[224:227], v[30:33]
	ds_read_b128 v[200:203], v244 offset:20800
	s_waitcnt lgkmcnt(7)
	v_mfma_f32_16x16x32_bf16 v[34:37], v[204:207], v[212:215], v[34:37]
	v_mfma_f32_16x16x32_bf16 v[38:41], v[204:207], v[216:219], v[38:41]
	v_mfma_f32_16x16x32_bf16 v[2:5], v[204:207], v[220:223], v[2:5]
	v_mfma_f32_16x16x32_bf16 v[6:9], v[204:207], v[224:227], v[6:9]
	ds_read_b128 v[204:207], v244 offset:23104
	s_setprio 1
	s_waitcnt vmcnt(15)
	ds_write_b128 v98, v[140:143]
	s_waitcnt vmcnt(14)
	ds_write_b128 v98, v[144:147] offset:4608
	s_waitcnt lgkmcnt(9)
	v_mfma_f32_16x16x32_bf16 v[42:45], v[208:211], v[212:215], v[42:45]
	v_mfma_f32_16x16x32_bf16 v[46:49], v[208:211], v[216:219], v[46:49]
	v_mfma_f32_16x16x32_bf16 v[10:13], v[208:211], v[220:223], v[10:13]
	v_mfma_f32_16x16x32_bf16 v[14:17], v[208:211], v[224:227], v[14:17]
	ds_read_b128 v[208:211], v244 offset:25408
	s_waitcnt vmcnt(13)
	ds_write_b128 v98, v[148:151] offset:9216
	s_waitcnt vmcnt(12)
	ds_write_b128 v98, v[152:155] offset:13824
	s_waitcnt lgkmcnt(7)
	v_mfma_f32_16x16x32_bf16 v[50:53], v[196:199], v[228:231], v[50:53]
	v_mfma_f32_16x16x32_bf16 v[54:57], v[196:199], v[232:235], v[54:57]
	v_mfma_f32_16x16x32_bf16 v[18:21], v[196:199], v[236:239], v[18:21]
	v_mfma_f32_16x16x32_bf16 v[22:25], v[196:199], v[240:243], v[22:25]
	s_waitcnt vmcnt(11)
	ds_write_b128 v98, v[156:159] offset:36864
	s_waitcnt vmcnt(10)
	ds_write_b128 v98, v[160:163] offset:41472
	s_waitcnt lgkmcnt(8)
	v_mfma_f32_16x16x32_bf16 v[58:61], v[200:203], v[228:231], v[58:61]
	v_mfma_f32_16x16x32_bf16 v[62:65], v[200:203], v[232:235], v[62:65]
	v_mfma_f32_16x16x32_bf16 v[26:29], v[200:203], v[236:239], v[26:29]
	v_mfma_f32_16x16x32_bf16 v[30:33], v[200:203], v[240:243], v[30:33]
	s_waitcnt vmcnt(9)
	ds_write_b128 v98, v[164:167] offset:46080
	s_waitcnt vmcnt(8)
	ds_write_b128 v98, v[168:171] offset:50688
	s_waitcnt lgkmcnt(0)
	s_barrier
	s_setprio 0
	ds_read_b128 v[212:215], v245 offset:36864
	ds_read_b128 v[196:199], v244
	ds_read_b128 v[216:219], v245 offset:39168
	ds_read_b128 v[220:223], v245 offset:41472
	ds_read_b128 v[224:227], v245 offset:43776
	ds_read_b128 v[200:203], v244 offset:2304
	v_mfma_f32_16x16x32_bf16 v[34:37], v[204:207], v[228:231], v[34:37]
	v_mfma_f32_16x16x32_bf16 v[38:41], v[204:207], v[232:235], v[38:41]
	v_mfma_f32_16x16x32_bf16 v[2:5], v[204:207], v[236:239], v[2:5]
	v_mfma_f32_16x16x32_bf16 v[6:9], v[204:207], v[240:243], v[6:9]
	ds_read_b128 v[204:207], v244 offset:4608
	v_mfma_f32_16x16x32_bf16 v[42:45], v[208:211], v[228:231], v[42:45]
	v_mfma_f32_16x16x32_bf16 v[46:49], v[208:211], v[232:235], v[46:49]
	v_mfma_f32_16x16x32_bf16 v[10:13], v[208:211], v[236:239], v[10:13]
	v_mfma_f32_16x16x32_bf16 v[14:17], v[208:211], v[240:243], v[14:17]
	ds_read_b128 v[208:211], v244 offset:6912
	global_load_dwordx4 v[140:143], v[74:75], off offset:768
	global_load_dwordx4 v[144:147], v[76:77], off offset:768
	global_load_dwordx4 v[148:151], v[78:79], off offset:768
	global_load_dwordx4 v[152:155], v[80:81], off offset:768
	global_load_dwordx4 v[156:159], v[82:83], off offset:768
	global_load_dwordx4 v[160:163], v[84:85], off offset:768
	global_load_dwordx4 v[164:167], v[86:87], off offset:768
	global_load_dwordx4 v[168:171], v[88:89], off offset:768
	s_waitcnt lgkmcnt(6)
	v_mfma_f32_16x16x32_bf16 v[50:53], v[196:199], v[212:215], v[50:53]
	ds_read_b128 v[228:231], v245 offset:36928
	s_waitcnt lgkmcnt(6)
	v_mfma_f32_16x16x32_bf16 v[54:57], v[196:199], v[216:219], v[54:57]
	ds_read_b128 v[232:235], v245 offset:39232
	s_waitcnt lgkmcnt(6)
	v_mfma_f32_16x16x32_bf16 v[18:21], v[196:199], v[220:223], v[18:21]
	ds_read_b128 v[236:239], v245 offset:41536
	s_waitcnt lgkmcnt(6)
	v_mfma_f32_16x16x32_bf16 v[22:25], v[196:199], v[224:227], v[22:25]
	ds_read_b128 v[240:243], v245 offset:43840
	ds_read_b128 v[196:199], v244 offset:64
	s_waitcnt lgkmcnt(7)
	v_mfma_f32_16x16x32_bf16 v[58:61], v[200:203], v[212:215], v[58:61]
	v_mfma_f32_16x16x32_bf16 v[62:65], v[200:203], v[216:219], v[62:65]
	v_mfma_f32_16x16x32_bf16 v[26:29], v[200:203], v[220:223], v[26:29]
	v_mfma_f32_16x16x32_bf16 v[30:33], v[200:203], v[224:227], v[30:33]
	ds_read_b128 v[200:203], v244 offset:2368
	s_waitcnt lgkmcnt(7)
	v_mfma_f32_16x16x32_bf16 v[34:37], v[204:207], v[212:215], v[34:37]
	v_mfma_f32_16x16x32_bf16 v[38:41], v[204:207], v[216:219], v[38:41]
	v_mfma_f32_16x16x32_bf16 v[2:5], v[204:207], v[220:223], v[2:5]
	v_mfma_f32_16x16x32_bf16 v[6:9], v[204:207], v[224:227], v[6:9]
	ds_read_b128 v[204:207], v244 offset:4672
	s_setprio 1
	s_waitcnt vmcnt(15)
	ds_write_b128 v98, v[102:105] offset:18432
	s_waitcnt vmcnt(14)
	ds_write_b128 v98, v[106:109] offset:23040
	s_waitcnt lgkmcnt(9)
	v_mfma_f32_16x16x32_bf16 v[42:45], v[208:211], v[212:215], v[42:45]
	v_mfma_f32_16x16x32_bf16 v[46:49], v[208:211], v[216:219], v[46:49]
	v_mfma_f32_16x16x32_bf16 v[10:13], v[208:211], v[220:223], v[10:13]
	v_mfma_f32_16x16x32_bf16 v[14:17], v[208:211], v[224:227], v[14:17]
	ds_read_b128 v[208:211], v244 offset:6976
	s_waitcnt vmcnt(13)
	ds_write_b128 v98, v[110:113] offset:27648
	s_waitcnt vmcnt(12)
	ds_write_b128 v98, v[114:117] offset:32256
	s_waitcnt lgkmcnt(7)
	v_mfma_f32_16x16x32_bf16 v[50:53], v[196:199], v[228:231], v[50:53]
	v_mfma_f32_16x16x32_bf16 v[54:57], v[196:199], v[232:235], v[54:57]
	v_mfma_f32_16x16x32_bf16 v[18:21], v[196:199], v[236:239], v[18:21]
	v_mfma_f32_16x16x32_bf16 v[22:25], v[196:199], v[240:243], v[22:25]
	s_waitcnt vmcnt(11)
	ds_write_b128 v98, v[118:121] offset:55296
	s_waitcnt vmcnt(10)
	ds_write_b128 v98, v[122:125] offset:59904
	s_waitcnt lgkmcnt(8)
	v_mfma_f32_16x16x32_bf16 v[58:61], v[200:203], v[228:231], v[58:61]
	v_mfma_f32_16x16x32_bf16 v[62:65], v[200:203], v[232:235], v[62:65]
	v_mfma_f32_16x16x32_bf16 v[26:29], v[200:203], v[236:239], v[26:29]
	v_mfma_f32_16x16x32_bf16 v[30:33], v[200:203], v[240:243], v[30:33]
	s_waitcnt vmcnt(9)
	ds_write_b128 v98, v[126:129] offset:64512
	s_waitcnt vmcnt(8)
	ds_write_b128 v99, v[136:139] offset:32256
	s_waitcnt lgkmcnt(0)
	s_barrier
	s_setprio 0
	ds_read_b128 v[212:215], v245 offset:55296
	ds_read_b128 v[196:199], v244 offset:18432
	ds_read_b128 v[216:219], v245 offset:57600
	ds_read_b128 v[220:223], v245 offset:59904
	ds_read_b128 v[224:227], v245 offset:62208
	ds_read_b128 v[200:203], v244 offset:20736
	v_mfma_f32_16x16x32_bf16 v[34:37], v[204:207], v[228:231], v[34:37]
	v_mfma_f32_16x16x32_bf16 v[38:41], v[204:207], v[232:235], v[38:41]
	v_mfma_f32_16x16x32_bf16 v[2:5], v[204:207], v[236:239], v[2:5]
	v_mfma_f32_16x16x32_bf16 v[6:9], v[204:207], v[240:243], v[6:9]
	ds_read_b128 v[204:207], v244 offset:23040
	v_mfma_f32_16x16x32_bf16 v[42:45], v[208:211], v[228:231], v[42:45]
	v_mfma_f32_16x16x32_bf16 v[46:49], v[208:211], v[232:235], v[46:49]
	v_mfma_f32_16x16x32_bf16 v[10:13], v[208:211], v[236:239], v[10:13]
	v_mfma_f32_16x16x32_bf16 v[14:17], v[208:211], v[240:243], v[14:17]
	ds_read_b128 v[208:211], v244 offset:25344
	global_load_dwordx4 v[102:105], v[74:75], off offset:896
	global_load_dwordx4 v[106:109], v[76:77], off offset:896
	global_load_dwordx4 v[110:113], v[78:79], off offset:896
	global_load_dwordx4 v[114:117], v[80:81], off offset:896
	global_load_dwordx4 v[118:121], v[82:83], off offset:896
	global_load_dwordx4 v[122:125], v[84:85], off offset:896
	global_load_dwordx4 v[126:129], v[86:87], off offset:896
	global_load_dwordx4 v[136:139], v[88:89], off offset:896
	s_waitcnt lgkmcnt(6)
	v_mfma_f32_16x16x32_bf16 v[50:53], v[196:199], v[212:215], v[50:53]
	ds_read_b128 v[228:231], v245 offset:55360
	s_waitcnt lgkmcnt(6)
	v_mfma_f32_16x16x32_bf16 v[54:57], v[196:199], v[216:219], v[54:57]
	ds_read_b128 v[232:235], v245 offset:57664
	s_waitcnt lgkmcnt(6)
	v_mfma_f32_16x16x32_bf16 v[18:21], v[196:199], v[220:223], v[18:21]
	ds_read_b128 v[236:239], v245 offset:59968
	s_waitcnt lgkmcnt(6)
	v_mfma_f32_16x16x32_bf16 v[22:25], v[196:199], v[224:227], v[22:25]
	ds_read_b128 v[240:243], v245 offset:62272
	ds_read_b128 v[196:199], v244 offset:18496
	s_waitcnt lgkmcnt(7)
	v_mfma_f32_16x16x32_bf16 v[58:61], v[200:203], v[212:215], v[58:61]
	v_mfma_f32_16x16x32_bf16 v[62:65], v[200:203], v[216:219], v[62:65]
	v_mfma_f32_16x16x32_bf16 v[26:29], v[200:203], v[220:223], v[26:29]
	v_mfma_f32_16x16x32_bf16 v[30:33], v[200:203], v[224:227], v[30:33]
	ds_read_b128 v[200:203], v244 offset:20800
	s_waitcnt lgkmcnt(7)
	v_mfma_f32_16x16x32_bf16 v[34:37], v[204:207], v[212:215], v[34:37]
	v_mfma_f32_16x16x32_bf16 v[38:41], v[204:207], v[216:219], v[38:41]
	v_mfma_f32_16x16x32_bf16 v[2:5], v[204:207], v[220:223], v[2:5]
	v_mfma_f32_16x16x32_bf16 v[6:9], v[204:207], v[224:227], v[6:9]
	ds_read_b128 v[204:207], v244 offset:23104
	s_setprio 1
	s_waitcnt vmcnt(15)
	ds_write_b128 v98, v[140:143]
	s_waitcnt vmcnt(14)
	ds_write_b128 v98, v[144:147] offset:4608
	s_waitcnt lgkmcnt(9)
	v_mfma_f32_16x16x32_bf16 v[42:45], v[208:211], v[212:215], v[42:45]
	v_mfma_f32_16x16x32_bf16 v[46:49], v[208:211], v[216:219], v[46:49]
	v_mfma_f32_16x16x32_bf16 v[10:13], v[208:211], v[220:223], v[10:13]
	v_mfma_f32_16x16x32_bf16 v[14:17], v[208:211], v[224:227], v[14:17]
	ds_read_b128 v[208:211], v244 offset:25408
	s_waitcnt vmcnt(13)
	ds_write_b128 v98, v[148:151] offset:9216
	s_waitcnt vmcnt(12)
	ds_write_b128 v98, v[152:155] offset:13824
	s_waitcnt lgkmcnt(7)
	v_mfma_f32_16x16x32_bf16 v[50:53], v[196:199], v[228:231], v[50:53]
	v_mfma_f32_16x16x32_bf16 v[54:57], v[196:199], v[232:235], v[54:57]
	v_mfma_f32_16x16x32_bf16 v[18:21], v[196:199], v[236:239], v[18:21]
	v_mfma_f32_16x16x32_bf16 v[22:25], v[196:199], v[240:243], v[22:25]
	s_waitcnt vmcnt(11)
	ds_write_b128 v98, v[156:159] offset:36864
	s_waitcnt vmcnt(10)
	ds_write_b128 v98, v[160:163] offset:41472
	s_waitcnt lgkmcnt(8)
	v_mfma_f32_16x16x32_bf16 v[58:61], v[200:203], v[228:231], v[58:61]
	v_mfma_f32_16x16x32_bf16 v[62:65], v[200:203], v[232:235], v[62:65]
	v_mfma_f32_16x16x32_bf16 v[26:29], v[200:203], v[236:239], v[26:29]
	v_mfma_f32_16x16x32_bf16 v[30:33], v[200:203], v[240:243], v[30:33]
	s_waitcnt vmcnt(9)
	ds_write_b128 v98, v[164:167] offset:46080
	s_waitcnt vmcnt(8)
	ds_write_b128 v98, v[168:171] offset:50688
	s_waitcnt lgkmcnt(0)
	s_barrier
	s_setprio 0
	ds_read_b128 v[212:215], v245 offset:36864
	ds_read_b128 v[196:199], v244
	ds_read_b128 v[216:219], v245 offset:39168
	ds_read_b128 v[220:223], v245 offset:41472
	ds_read_b128 v[224:227], v245 offset:43776
	ds_read_b128 v[200:203], v244 offset:2304
	v_mfma_f32_16x16x32_bf16 v[34:37], v[204:207], v[228:231], v[34:37]
	v_mfma_f32_16x16x32_bf16 v[38:41], v[204:207], v[232:235], v[38:41]
	v_mfma_f32_16x16x32_bf16 v[2:5], v[204:207], v[236:239], v[2:5]
	v_mfma_f32_16x16x32_bf16 v[6:9], v[204:207], v[240:243], v[6:9]
	ds_read_b128 v[204:207], v244 offset:4608
	v_mfma_f32_16x16x32_bf16 v[42:45], v[208:211], v[228:231], v[42:45]
	v_mfma_f32_16x16x32_bf16 v[46:49], v[208:211], v[232:235], v[46:49]
	v_mfma_f32_16x16x32_bf16 v[10:13], v[208:211], v[236:239], v[10:13]
	v_mfma_f32_16x16x32_bf16 v[14:17], v[208:211], v[240:243], v[14:17]
	ds_read_b128 v[208:211], v244 offset:6912
	global_load_dwordx4 v[140:143], v[74:75], off offset:1024
	global_load_dwordx4 v[144:147], v[76:77], off offset:1024
	global_load_dwordx4 v[148:151], v[78:79], off offset:1024
	global_load_dwordx4 v[152:155], v[80:81], off offset:1024
	global_load_dwordx4 v[156:159], v[82:83], off offset:1024
	global_load_dwordx4 v[160:163], v[84:85], off offset:1024
	global_load_dwordx4 v[164:167], v[86:87], off offset:1024
	global_load_dwordx4 v[168:171], v[88:89], off offset:1024
	s_waitcnt lgkmcnt(6)
	v_mfma_f32_16x16x32_bf16 v[50:53], v[196:199], v[212:215], v[50:53]
	ds_read_b128 v[228:231], v245 offset:36928
	s_waitcnt lgkmcnt(6)
	v_mfma_f32_16x16x32_bf16 v[54:57], v[196:199], v[216:219], v[54:57]
	ds_read_b128 v[232:235], v245 offset:39232
	s_waitcnt lgkmcnt(6)
	v_mfma_f32_16x16x32_bf16 v[18:21], v[196:199], v[220:223], v[18:21]
	ds_read_b128 v[236:239], v245 offset:41536
	s_waitcnt lgkmcnt(6)
	v_mfma_f32_16x16x32_bf16 v[22:25], v[196:199], v[224:227], v[22:25]
	ds_read_b128 v[240:243], v245 offset:43840
	ds_read_b128 v[196:199], v244 offset:64
	s_waitcnt lgkmcnt(7)
	v_mfma_f32_16x16x32_bf16 v[58:61], v[200:203], v[212:215], v[58:61]
	v_mfma_f32_16x16x32_bf16 v[62:65], v[200:203], v[216:219], v[62:65]
	v_mfma_f32_16x16x32_bf16 v[26:29], v[200:203], v[220:223], v[26:29]
	v_mfma_f32_16x16x32_bf16 v[30:33], v[200:203], v[224:227], v[30:33]
	ds_read_b128 v[200:203], v244 offset:2368
	s_waitcnt lgkmcnt(7)
	v_mfma_f32_16x16x32_bf16 v[34:37], v[204:207], v[212:215], v[34:37]
	v_mfma_f32_16x16x32_bf16 v[38:41], v[204:207], v[216:219], v[38:41]
	v_mfma_f32_16x16x32_bf16 v[2:5], v[204:207], v[220:223], v[2:5]
	v_mfma_f32_16x16x32_bf16 v[6:9], v[204:207], v[224:227], v[6:9]
	ds_read_b128 v[204:207], v244 offset:4672
	s_setprio 1
	s_waitcnt vmcnt(15)
	ds_write_b128 v98, v[102:105] offset:18432
	s_waitcnt vmcnt(14)
	ds_write_b128 v98, v[106:109] offset:23040
	s_waitcnt lgkmcnt(9)
	v_mfma_f32_16x16x32_bf16 v[42:45], v[208:211], v[212:215], v[42:45]
	v_mfma_f32_16x16x32_bf16 v[46:49], v[208:211], v[216:219], v[46:49]
	v_mfma_f32_16x16x32_bf16 v[10:13], v[208:211], v[220:223], v[10:13]
	v_mfma_f32_16x16x32_bf16 v[14:17], v[208:211], v[224:227], v[14:17]
	ds_read_b128 v[208:211], v244 offset:6976
	s_waitcnt vmcnt(13)
	ds_write_b128 v98, v[110:113] offset:27648
	s_waitcnt vmcnt(12)
	ds_write_b128 v98, v[114:117] offset:32256
	s_waitcnt lgkmcnt(7)
	v_mfma_f32_16x16x32_bf16 v[50:53], v[196:199], v[228:231], v[50:53]
	v_mfma_f32_16x16x32_bf16 v[54:57], v[196:199], v[232:235], v[54:57]
	v_mfma_f32_16x16x32_bf16 v[18:21], v[196:199], v[236:239], v[18:21]
	v_mfma_f32_16x16x32_bf16 v[22:25], v[196:199], v[240:243], v[22:25]
	s_waitcnt vmcnt(11)
	ds_write_b128 v98, v[118:121] offset:55296
	s_waitcnt vmcnt(10)
	ds_write_b128 v98, v[122:125] offset:59904
	s_waitcnt lgkmcnt(8)
	v_mfma_f32_16x16x32_bf16 v[58:61], v[200:203], v[228:231], v[58:61]
	v_mfma_f32_16x16x32_bf16 v[62:65], v[200:203], v[232:235], v[62:65]
	v_mfma_f32_16x16x32_bf16 v[26:29], v[200:203], v[236:239], v[26:29]
	v_mfma_f32_16x16x32_bf16 v[30:33], v[200:203], v[240:243], v[30:33]
	s_waitcnt vmcnt(9)
	ds_write_b128 v98, v[126:129] offset:64512
	s_waitcnt vmcnt(8)
	ds_write_b128 v99, v[136:139] offset:32256
	s_waitcnt lgkmcnt(0)
	s_barrier
	s_setprio 0
	ds_read_b128 v[212:215], v245 offset:55296
	ds_read_b128 v[196:199], v244 offset:18432
	ds_read_b128 v[216:219], v245 offset:57600
	ds_read_b128 v[220:223], v245 offset:59904
	ds_read_b128 v[224:227], v245 offset:62208
	ds_read_b128 v[200:203], v244 offset:20736
	v_mfma_f32_16x16x32_bf16 v[34:37], v[204:207], v[228:231], v[34:37]
	v_mfma_f32_16x16x32_bf16 v[38:41], v[204:207], v[232:235], v[38:41]
	v_mfma_f32_16x16x32_bf16 v[2:5], v[204:207], v[236:239], v[2:5]
	v_mfma_f32_16x16x32_bf16 v[6:9], v[204:207], v[240:243], v[6:9]
	ds_read_b128 v[204:207], v244 offset:23040
	v_mfma_f32_16x16x32_bf16 v[42:45], v[208:211], v[228:231], v[42:45]
	v_mfma_f32_16x16x32_bf16 v[46:49], v[208:211], v[232:235], v[46:49]
	v_mfma_f32_16x16x32_bf16 v[10:13], v[208:211], v[236:239], v[10:13]
	v_mfma_f32_16x16x32_bf16 v[14:17], v[208:211], v[240:243], v[14:17]
	ds_read_b128 v[208:211], v244 offset:25344
	global_load_dwordx4 v[102:105], v[74:75], off offset:1152
	global_load_dwordx4 v[106:109], v[76:77], off offset:1152
	global_load_dwordx4 v[110:113], v[78:79], off offset:1152
	global_load_dwordx4 v[114:117], v[80:81], off offset:1152
	global_load_dwordx4 v[118:121], v[82:83], off offset:1152
	global_load_dwordx4 v[122:125], v[84:85], off offset:1152
	global_load_dwordx4 v[126:129], v[86:87], off offset:1152
	global_load_dwordx4 v[136:139], v[88:89], off offset:1152
	s_waitcnt lgkmcnt(6)
	v_mfma_f32_16x16x32_bf16 v[50:53], v[196:199], v[212:215], v[50:53]
	ds_read_b128 v[228:231], v245 offset:55360
	s_waitcnt lgkmcnt(6)
	v_mfma_f32_16x16x32_bf16 v[54:57], v[196:199], v[216:219], v[54:57]
	ds_read_b128 v[232:235], v245 offset:57664
	s_waitcnt lgkmcnt(6)
	v_mfma_f32_16x16x32_bf16 v[18:21], v[196:199], v[220:223], v[18:21]
	ds_read_b128 v[236:239], v245 offset:59968
	s_waitcnt lgkmcnt(6)
	v_mfma_f32_16x16x32_bf16 v[22:25], v[196:199], v[224:227], v[22:25]
	ds_read_b128 v[240:243], v245 offset:62272
	ds_read_b128 v[196:199], v244 offset:18496
	s_waitcnt lgkmcnt(7)
	v_mfma_f32_16x16x32_bf16 v[58:61], v[200:203], v[212:215], v[58:61]
	v_mfma_f32_16x16x32_bf16 v[62:65], v[200:203], v[216:219], v[62:65]
	v_mfma_f32_16x16x32_bf16 v[26:29], v[200:203], v[220:223], v[26:29]
	v_mfma_f32_16x16x32_bf16 v[30:33], v[200:203], v[224:227], v[30:33]
	ds_read_b128 v[200:203], v244 offset:20800
	s_waitcnt lgkmcnt(7)
	v_mfma_f32_16x16x32_bf16 v[34:37], v[204:207], v[212:215], v[34:37]
	v_mfma_f32_16x16x32_bf16 v[38:41], v[204:207], v[216:219], v[38:41]
	v_mfma_f32_16x16x32_bf16 v[2:5], v[204:207], v[220:223], v[2:5]
	v_mfma_f32_16x16x32_bf16 v[6:9], v[204:207], v[224:227], v[6:9]
	ds_read_b128 v[204:207], v244 offset:23104
	s_setprio 1
	s_waitcnt vmcnt(15)
	ds_write_b128 v98, v[140:143]
	s_waitcnt vmcnt(14)
	ds_write_b128 v98, v[144:147] offset:4608
	s_waitcnt lgkmcnt(9)
	v_mfma_f32_16x16x32_bf16 v[42:45], v[208:211], v[212:215], v[42:45]
	v_mfma_f32_16x16x32_bf16 v[46:49], v[208:211], v[216:219], v[46:49]
	v_mfma_f32_16x16x32_bf16 v[10:13], v[208:211], v[220:223], v[10:13]
	v_mfma_f32_16x16x32_bf16 v[14:17], v[208:211], v[224:227], v[14:17]
	ds_read_b128 v[208:211], v244 offset:25408
	s_waitcnt vmcnt(13)
	ds_write_b128 v98, v[148:151] offset:9216
	s_waitcnt vmcnt(12)
	ds_write_b128 v98, v[152:155] offset:13824
	s_waitcnt lgkmcnt(7)
	v_mfma_f32_16x16x32_bf16 v[50:53], v[196:199], v[228:231], v[50:53]
	v_mfma_f32_16x16x32_bf16 v[54:57], v[196:199], v[232:235], v[54:57]
	v_mfma_f32_16x16x32_bf16 v[18:21], v[196:199], v[236:239], v[18:21]
	v_mfma_f32_16x16x32_bf16 v[22:25], v[196:199], v[240:243], v[22:25]
	s_waitcnt vmcnt(11)
	ds_write_b128 v98, v[156:159] offset:36864
	s_waitcnt vmcnt(10)
	ds_write_b128 v98, v[160:163] offset:41472
	s_waitcnt lgkmcnt(8)
	v_mfma_f32_16x16x32_bf16 v[58:61], v[200:203], v[228:231], v[58:61]
	v_mfma_f32_16x16x32_bf16 v[62:65], v[200:203], v[232:235], v[62:65]
	v_mfma_f32_16x16x32_bf16 v[26:29], v[200:203], v[236:239], v[26:29]
	v_mfma_f32_16x16x32_bf16 v[30:33], v[200:203], v[240:243], v[30:33]
	s_waitcnt vmcnt(9)
	ds_write_b128 v98, v[164:167] offset:46080
	s_waitcnt vmcnt(8)
	ds_write_b128 v98, v[168:171] offset:50688
	s_waitcnt lgkmcnt(0)
	s_barrier
	s_setprio 0
	ds_read_b128 v[212:215], v245 offset:36864
	ds_read_b128 v[196:199], v244
	ds_read_b128 v[216:219], v245 offset:39168
	ds_read_b128 v[220:223], v245 offset:41472
	ds_read_b128 v[224:227], v245 offset:43776
	ds_read_b128 v[200:203], v244 offset:2304
	v_mfma_f32_16x16x32_bf16 v[34:37], v[204:207], v[228:231], v[34:37]
	v_mfma_f32_16x16x32_bf16 v[38:41], v[204:207], v[232:235], v[38:41]
	v_mfma_f32_16x16x32_bf16 v[2:5], v[204:207], v[236:239], v[2:5]
	v_mfma_f32_16x16x32_bf16 v[6:9], v[204:207], v[240:243], v[6:9]
	ds_read_b128 v[204:207], v244 offset:4608
	v_mfma_f32_16x16x32_bf16 v[42:45], v[208:211], v[228:231], v[42:45]
	v_mfma_f32_16x16x32_bf16 v[46:49], v[208:211], v[232:235], v[46:49]
	v_mfma_f32_16x16x32_bf16 v[10:13], v[208:211], v[236:239], v[10:13]
	v_mfma_f32_16x16x32_bf16 v[14:17], v[208:211], v[240:243], v[14:17]
	ds_read_b128 v[208:211], v244 offset:6912
	global_load_dwordx4 v[140:143], v[74:75], off offset:1280
	global_load_dwordx4 v[144:147], v[76:77], off offset:1280
	global_load_dwordx4 v[148:151], v[78:79], off offset:1280
	global_load_dwordx4 v[152:155], v[80:81], off offset:1280
	global_load_dwordx4 v[156:159], v[82:83], off offset:1280
	global_load_dwordx4 v[160:163], v[84:85], off offset:1280
	global_load_dwordx4 v[164:167], v[86:87], off offset:1280
	global_load_dwordx4 v[168:171], v[88:89], off offset:1280
	s_waitcnt lgkmcnt(6)
	v_mfma_f32_16x16x32_bf16 v[50:53], v[196:199], v[212:215], v[50:53]
	ds_read_b128 v[228:231], v245 offset:36928
	s_waitcnt lgkmcnt(6)
	v_mfma_f32_16x16x32_bf16 v[54:57], v[196:199], v[216:219], v[54:57]
	ds_read_b128 v[232:235], v245 offset:39232
	s_waitcnt lgkmcnt(6)
	v_mfma_f32_16x16x32_bf16 v[18:21], v[196:199], v[220:223], v[18:21]
	ds_read_b128 v[236:239], v245 offset:41536
	s_waitcnt lgkmcnt(6)
	v_mfma_f32_16x16x32_bf16 v[22:25], v[196:199], v[224:227], v[22:25]
	ds_read_b128 v[240:243], v245 offset:43840
	ds_read_b128 v[196:199], v244 offset:64
	s_waitcnt lgkmcnt(7)
	v_mfma_f32_16x16x32_bf16 v[58:61], v[200:203], v[212:215], v[58:61]
	v_mfma_f32_16x16x32_bf16 v[62:65], v[200:203], v[216:219], v[62:65]
	v_mfma_f32_16x16x32_bf16 v[26:29], v[200:203], v[220:223], v[26:29]
	v_mfma_f32_16x16x32_bf16 v[30:33], v[200:203], v[224:227], v[30:33]
	ds_read_b128 v[200:203], v244 offset:2368
	s_waitcnt lgkmcnt(7)
	v_mfma_f32_16x16x32_bf16 v[34:37], v[204:207], v[212:215], v[34:37]
	v_mfma_f32_16x16x32_bf16 v[38:41], v[204:207], v[216:219], v[38:41]
	v_mfma_f32_16x16x32_bf16 v[2:5], v[204:207], v[220:223], v[2:5]
	v_mfma_f32_16x16x32_bf16 v[6:9], v[204:207], v[224:227], v[6:9]
	ds_read_b128 v[204:207], v244 offset:4672
	s_setprio 1
	s_waitcnt vmcnt(15)
	ds_write_b128 v98, v[102:105] offset:18432
	s_waitcnt vmcnt(14)
	ds_write_b128 v98, v[106:109] offset:23040
	s_waitcnt lgkmcnt(9)
	v_mfma_f32_16x16x32_bf16 v[42:45], v[208:211], v[212:215], v[42:45]
	v_mfma_f32_16x16x32_bf16 v[46:49], v[208:211], v[216:219], v[46:49]
	v_mfma_f32_16x16x32_bf16 v[10:13], v[208:211], v[220:223], v[10:13]
	v_mfma_f32_16x16x32_bf16 v[14:17], v[208:211], v[224:227], v[14:17]
	ds_read_b128 v[208:211], v244 offset:6976
	s_waitcnt vmcnt(13)
	ds_write_b128 v98, v[110:113] offset:27648
	s_waitcnt vmcnt(12)
	ds_write_b128 v98, v[114:117] offset:32256
	s_waitcnt lgkmcnt(7)
	v_mfma_f32_16x16x32_bf16 v[50:53], v[196:199], v[228:231], v[50:53]
	v_mfma_f32_16x16x32_bf16 v[54:57], v[196:199], v[232:235], v[54:57]
	v_mfma_f32_16x16x32_bf16 v[18:21], v[196:199], v[236:239], v[18:21]
	v_mfma_f32_16x16x32_bf16 v[22:25], v[196:199], v[240:243], v[22:25]
	s_waitcnt vmcnt(11)
	ds_write_b128 v98, v[118:121] offset:55296
	s_waitcnt vmcnt(10)
	ds_write_b128 v98, v[122:125] offset:59904
	s_waitcnt lgkmcnt(8)
	v_mfma_f32_16x16x32_bf16 v[58:61], v[200:203], v[228:231], v[58:61]
	v_mfma_f32_16x16x32_bf16 v[62:65], v[200:203], v[232:235], v[62:65]
	v_mfma_f32_16x16x32_bf16 v[26:29], v[200:203], v[236:239], v[26:29]
	v_mfma_f32_16x16x32_bf16 v[30:33], v[200:203], v[240:243], v[30:33]
	s_waitcnt vmcnt(9)
	ds_write_b128 v98, v[126:129] offset:64512
	s_waitcnt vmcnt(8)
	ds_write_b128 v99, v[136:139] offset:32256
	s_waitcnt lgkmcnt(0)
	s_barrier
	s_setprio 0
	ds_read_b128 v[212:215], v245 offset:55296
	ds_read_b128 v[196:199], v244 offset:18432
	ds_read_b128 v[216:219], v245 offset:57600
	ds_read_b128 v[220:223], v245 offset:59904
	ds_read_b128 v[224:227], v245 offset:62208
	ds_read_b128 v[200:203], v244 offset:20736
	v_mfma_f32_16x16x32_bf16 v[34:37], v[204:207], v[228:231], v[34:37]
	v_mfma_f32_16x16x32_bf16 v[38:41], v[204:207], v[232:235], v[38:41]
	v_mfma_f32_16x16x32_bf16 v[2:5], v[204:207], v[236:239], v[2:5]
	v_mfma_f32_16x16x32_bf16 v[6:9], v[204:207], v[240:243], v[6:9]
	ds_read_b128 v[204:207], v244 offset:23040
	v_mfma_f32_16x16x32_bf16 v[42:45], v[208:211], v[228:231], v[42:45]
	v_mfma_f32_16x16x32_bf16 v[46:49], v[208:211], v[232:235], v[46:49]
	v_mfma_f32_16x16x32_bf16 v[10:13], v[208:211], v[236:239], v[10:13]
	v_mfma_f32_16x16x32_bf16 v[14:17], v[208:211], v[240:243], v[14:17]
	ds_read_b128 v[208:211], v244 offset:25344
	global_load_dwordx4 v[102:105], v[74:75], off offset:1408
	global_load_dwordx4 v[106:109], v[76:77], off offset:1408
	global_load_dwordx4 v[110:113], v[78:79], off offset:1408
	global_load_dwordx4 v[114:117], v[80:81], off offset:1408
	global_load_dwordx4 v[118:121], v[82:83], off offset:1408
	global_load_dwordx4 v[122:125], v[84:85], off offset:1408
	global_load_dwordx4 v[126:129], v[86:87], off offset:1408
	global_load_dwordx4 v[136:139], v[88:89], off offset:1408
	s_waitcnt lgkmcnt(6)
	v_mfma_f32_16x16x32_bf16 v[50:53], v[196:199], v[212:215], v[50:53]
	ds_read_b128 v[228:231], v245 offset:55360
	s_waitcnt lgkmcnt(6)
	v_mfma_f32_16x16x32_bf16 v[54:57], v[196:199], v[216:219], v[54:57]
	ds_read_b128 v[232:235], v245 offset:57664
	s_waitcnt lgkmcnt(6)
	v_mfma_f32_16x16x32_bf16 v[18:21], v[196:199], v[220:223], v[18:21]
	ds_read_b128 v[236:239], v245 offset:59968
	s_waitcnt lgkmcnt(6)
	v_mfma_f32_16x16x32_bf16 v[22:25], v[196:199], v[224:227], v[22:25]
	ds_read_b128 v[240:243], v245 offset:62272
	ds_read_b128 v[196:199], v244 offset:18496
	s_waitcnt lgkmcnt(7)
	v_mfma_f32_16x16x32_bf16 v[58:61], v[200:203], v[212:215], v[58:61]
	v_mfma_f32_16x16x32_bf16 v[62:65], v[200:203], v[216:219], v[62:65]
	v_mfma_f32_16x16x32_bf16 v[26:29], v[200:203], v[220:223], v[26:29]
	v_mfma_f32_16x16x32_bf16 v[30:33], v[200:203], v[224:227], v[30:33]
	ds_read_b128 v[200:203], v244 offset:20800
	s_waitcnt lgkmcnt(7)
	v_mfma_f32_16x16x32_bf16 v[34:37], v[204:207], v[212:215], v[34:37]
	v_mfma_f32_16x16x32_bf16 v[38:41], v[204:207], v[216:219], v[38:41]
	v_mfma_f32_16x16x32_bf16 v[2:5], v[204:207], v[220:223], v[2:5]
	v_mfma_f32_16x16x32_bf16 v[6:9], v[204:207], v[224:227], v[6:9]
	ds_read_b128 v[204:207], v244 offset:23104
	s_setprio 1
	s_waitcnt vmcnt(15)
	ds_write_b128 v98, v[140:143]
	s_waitcnt vmcnt(14)
	ds_write_b128 v98, v[144:147] offset:4608
	s_waitcnt lgkmcnt(9)
	v_mfma_f32_16x16x32_bf16 v[42:45], v[208:211], v[212:215], v[42:45]
	v_mfma_f32_16x16x32_bf16 v[46:49], v[208:211], v[216:219], v[46:49]
	v_mfma_f32_16x16x32_bf16 v[10:13], v[208:211], v[220:223], v[10:13]
	v_mfma_f32_16x16x32_bf16 v[14:17], v[208:211], v[224:227], v[14:17]
	ds_read_b128 v[208:211], v244 offset:25408
	s_waitcnt vmcnt(13)
	ds_write_b128 v98, v[148:151] offset:9216
	s_waitcnt vmcnt(12)
	ds_write_b128 v98, v[152:155] offset:13824
	s_waitcnt lgkmcnt(7)
	v_mfma_f32_16x16x32_bf16 v[50:53], v[196:199], v[228:231], v[50:53]
	v_mfma_f32_16x16x32_bf16 v[54:57], v[196:199], v[232:235], v[54:57]
	v_mfma_f32_16x16x32_bf16 v[18:21], v[196:199], v[236:239], v[18:21]
	v_mfma_f32_16x16x32_bf16 v[22:25], v[196:199], v[240:243], v[22:25]
	s_waitcnt vmcnt(11)
	ds_write_b128 v98, v[156:159] offset:36864
	s_waitcnt vmcnt(10)
	ds_write_b128 v98, v[160:163] offset:41472
	s_waitcnt lgkmcnt(8)
	v_mfma_f32_16x16x32_bf16 v[58:61], v[200:203], v[228:231], v[58:61]
	v_mfma_f32_16x16x32_bf16 v[62:65], v[200:203], v[232:235], v[62:65]
	v_mfma_f32_16x16x32_bf16 v[26:29], v[200:203], v[236:239], v[26:29]
	v_mfma_f32_16x16x32_bf16 v[30:33], v[200:203], v[240:243], v[30:33]
	s_waitcnt vmcnt(9)
	ds_write_b128 v98, v[164:167] offset:46080
	s_waitcnt vmcnt(8)
	ds_write_b128 v98, v[168:171] offset:50688
	s_waitcnt lgkmcnt(0)
	s_barrier
	s_setprio 0
	ds_read_b128 v[212:215], v245 offset:36864
	ds_read_b128 v[196:199], v244
	ds_read_b128 v[216:219], v245 offset:39168
	ds_read_b128 v[220:223], v245 offset:41472
	ds_read_b128 v[224:227], v245 offset:43776
	ds_read_b128 v[200:203], v244 offset:2304
	v_mfma_f32_16x16x32_bf16 v[34:37], v[204:207], v[228:231], v[34:37]
	v_mfma_f32_16x16x32_bf16 v[38:41], v[204:207], v[232:235], v[38:41]
	v_mfma_f32_16x16x32_bf16 v[2:5], v[204:207], v[236:239], v[2:5]
	v_mfma_f32_16x16x32_bf16 v[6:9], v[204:207], v[240:243], v[6:9]
	ds_read_b128 v[204:207], v244 offset:4608
	v_mfma_f32_16x16x32_bf16 v[42:45], v[208:211], v[228:231], v[42:45]
	v_mfma_f32_16x16x32_bf16 v[46:49], v[208:211], v[232:235], v[46:49]
	v_mfma_f32_16x16x32_bf16 v[10:13], v[208:211], v[236:239], v[10:13]
	v_mfma_f32_16x16x32_bf16 v[14:17], v[208:211], v[240:243], v[14:17]
	ds_read_b128 v[208:211], v244 offset:6912
	global_load_dwordx4 v[140:143], v[74:75], off offset:1536
	global_load_dwordx4 v[144:147], v[76:77], off offset:1536
	global_load_dwordx4 v[148:151], v[78:79], off offset:1536
	global_load_dwordx4 v[152:155], v[80:81], off offset:1536
	global_load_dwordx4 v[156:159], v[82:83], off offset:1536
	global_load_dwordx4 v[160:163], v[84:85], off offset:1536
	global_load_dwordx4 v[164:167], v[86:87], off offset:1536
	global_load_dwordx4 v[168:171], v[88:89], off offset:1536
	s_waitcnt lgkmcnt(6)
	v_mfma_f32_16x16x32_bf16 v[50:53], v[196:199], v[212:215], v[50:53]
	ds_read_b128 v[228:231], v245 offset:36928
	s_waitcnt lgkmcnt(6)
	v_mfma_f32_16x16x32_bf16 v[54:57], v[196:199], v[216:219], v[54:57]
	ds_read_b128 v[232:235], v245 offset:39232
	s_waitcnt lgkmcnt(6)
	v_mfma_f32_16x16x32_bf16 v[18:21], v[196:199], v[220:223], v[18:21]
	ds_read_b128 v[236:239], v245 offset:41536
	s_waitcnt lgkmcnt(6)
	v_mfma_f32_16x16x32_bf16 v[22:25], v[196:199], v[224:227], v[22:25]
	ds_read_b128 v[240:243], v245 offset:43840
	ds_read_b128 v[196:199], v244 offset:64
	s_waitcnt lgkmcnt(7)
	v_mfma_f32_16x16x32_bf16 v[58:61], v[200:203], v[212:215], v[58:61]
	v_mfma_f32_16x16x32_bf16 v[62:65], v[200:203], v[216:219], v[62:65]
	v_mfma_f32_16x16x32_bf16 v[26:29], v[200:203], v[220:223], v[26:29]
	v_mfma_f32_16x16x32_bf16 v[30:33], v[200:203], v[224:227], v[30:33]
	ds_read_b128 v[200:203], v244 offset:2368
	s_waitcnt lgkmcnt(7)
	v_mfma_f32_16x16x32_bf16 v[34:37], v[204:207], v[212:215], v[34:37]
	v_mfma_f32_16x16x32_bf16 v[38:41], v[204:207], v[216:219], v[38:41]
	v_mfma_f32_16x16x32_bf16 v[2:5], v[204:207], v[220:223], v[2:5]
	v_mfma_f32_16x16x32_bf16 v[6:9], v[204:207], v[224:227], v[6:9]
	ds_read_b128 v[204:207], v244 offset:4672
	s_setprio 1
	s_waitcnt vmcnt(15)
	ds_write_b128 v98, v[102:105] offset:18432
	s_waitcnt vmcnt(14)
	ds_write_b128 v98, v[106:109] offset:23040
	s_waitcnt lgkmcnt(9)
	v_mfma_f32_16x16x32_bf16 v[42:45], v[208:211], v[212:215], v[42:45]
	v_mfma_f32_16x16x32_bf16 v[46:49], v[208:211], v[216:219], v[46:49]
	v_mfma_f32_16x16x32_bf16 v[10:13], v[208:211], v[220:223], v[10:13]
	v_mfma_f32_16x16x32_bf16 v[14:17], v[208:211], v[224:227], v[14:17]
	ds_read_b128 v[208:211], v244 offset:6976
	s_waitcnt vmcnt(13)
	ds_write_b128 v98, v[110:113] offset:27648
	s_waitcnt vmcnt(12)
	ds_write_b128 v98, v[114:117] offset:32256
	s_waitcnt lgkmcnt(7)
	v_mfma_f32_16x16x32_bf16 v[50:53], v[196:199], v[228:231], v[50:53]
	v_mfma_f32_16x16x32_bf16 v[54:57], v[196:199], v[232:235], v[54:57]
	v_mfma_f32_16x16x32_bf16 v[18:21], v[196:199], v[236:239], v[18:21]
	v_mfma_f32_16x16x32_bf16 v[22:25], v[196:199], v[240:243], v[22:25]
	s_waitcnt vmcnt(11)
	ds_write_b128 v98, v[118:121] offset:55296
	s_waitcnt vmcnt(10)
	ds_write_b128 v98, v[122:125] offset:59904
	s_waitcnt lgkmcnt(8)
	v_mfma_f32_16x16x32_bf16 v[58:61], v[200:203], v[228:231], v[58:61]
	v_mfma_f32_16x16x32_bf16 v[62:65], v[200:203], v[232:235], v[62:65]
	v_mfma_f32_16x16x32_bf16 v[26:29], v[200:203], v[236:239], v[26:29]
	v_mfma_f32_16x16x32_bf16 v[30:33], v[200:203], v[240:243], v[30:33]
	s_waitcnt vmcnt(9)
	ds_write_b128 v98, v[126:129] offset:64512
	s_waitcnt vmcnt(8)
	ds_write_b128 v99, v[136:139] offset:32256
	s_waitcnt lgkmcnt(0)
	s_barrier
	s_setprio 0
	ds_read_b128 v[212:215], v245 offset:55296
	ds_read_b128 v[196:199], v244 offset:18432
	ds_read_b128 v[216:219], v245 offset:57600
	ds_read_b128 v[220:223], v245 offset:59904
	ds_read_b128 v[224:227], v245 offset:62208
	ds_read_b128 v[200:203], v244 offset:20736
	v_mfma_f32_16x16x32_bf16 v[34:37], v[204:207], v[228:231], v[34:37]
	v_mfma_f32_16x16x32_bf16 v[38:41], v[204:207], v[232:235], v[38:41]
	v_mfma_f32_16x16x32_bf16 v[2:5], v[204:207], v[236:239], v[2:5]
	v_mfma_f32_16x16x32_bf16 v[6:9], v[204:207], v[240:243], v[6:9]
	ds_read_b128 v[204:207], v244 offset:23040
	v_mfma_f32_16x16x32_bf16 v[42:45], v[208:211], v[228:231], v[42:45]
	v_mfma_f32_16x16x32_bf16 v[46:49], v[208:211], v[232:235], v[46:49]
	v_mfma_f32_16x16x32_bf16 v[10:13], v[208:211], v[236:239], v[10:13]
	v_mfma_f32_16x16x32_bf16 v[14:17], v[208:211], v[240:243], v[14:17]
	ds_read_b128 v[208:211], v244 offset:25344
	global_load_dwordx4 v[102:105], v[74:75], off offset:1664
	global_load_dwordx4 v[106:109], v[76:77], off offset:1664
	global_load_dwordx4 v[110:113], v[78:79], off offset:1664
	global_load_dwordx4 v[114:117], v[80:81], off offset:1664
	global_load_dwordx4 v[118:121], v[82:83], off offset:1664
	global_load_dwordx4 v[122:125], v[84:85], off offset:1664
	global_load_dwordx4 v[126:129], v[86:87], off offset:1664
	global_load_dwordx4 v[136:139], v[88:89], off offset:1664
	s_waitcnt lgkmcnt(6)
	v_mfma_f32_16x16x32_bf16 v[50:53], v[196:199], v[212:215], v[50:53]
	ds_read_b128 v[228:231], v245 offset:55360
	s_waitcnt lgkmcnt(6)
	v_mfma_f32_16x16x32_bf16 v[54:57], v[196:199], v[216:219], v[54:57]
	ds_read_b128 v[232:235], v245 offset:57664
	s_waitcnt lgkmcnt(6)
	v_mfma_f32_16x16x32_bf16 v[18:21], v[196:199], v[220:223], v[18:21]
	ds_read_b128 v[236:239], v245 offset:59968
	s_waitcnt lgkmcnt(6)
	v_mfma_f32_16x16x32_bf16 v[22:25], v[196:199], v[224:227], v[22:25]
	ds_read_b128 v[240:243], v245 offset:62272
	ds_read_b128 v[196:199], v244 offset:18496
	s_waitcnt lgkmcnt(7)
	v_mfma_f32_16x16x32_bf16 v[58:61], v[200:203], v[212:215], v[58:61]
	v_mfma_f32_16x16x32_bf16 v[62:65], v[200:203], v[216:219], v[62:65]
	v_mfma_f32_16x16x32_bf16 v[26:29], v[200:203], v[220:223], v[26:29]
	v_mfma_f32_16x16x32_bf16 v[30:33], v[200:203], v[224:227], v[30:33]
	ds_read_b128 v[200:203], v244 offset:20800
	s_waitcnt lgkmcnt(7)
	v_mfma_f32_16x16x32_bf16 v[34:37], v[204:207], v[212:215], v[34:37]
	v_mfma_f32_16x16x32_bf16 v[38:41], v[204:207], v[216:219], v[38:41]
	v_mfma_f32_16x16x32_bf16 v[2:5], v[204:207], v[220:223], v[2:5]
	v_mfma_f32_16x16x32_bf16 v[6:9], v[204:207], v[224:227], v[6:9]
	ds_read_b128 v[204:207], v244 offset:23104
	s_setprio 1
	s_waitcnt vmcnt(15)
	ds_write_b128 v98, v[140:143]
	s_waitcnt vmcnt(14)
	ds_write_b128 v98, v[144:147] offset:4608
	s_waitcnt lgkmcnt(9)
	v_mfma_f32_16x16x32_bf16 v[42:45], v[208:211], v[212:215], v[42:45]
	v_mfma_f32_16x16x32_bf16 v[46:49], v[208:211], v[216:219], v[46:49]
	v_mfma_f32_16x16x32_bf16 v[10:13], v[208:211], v[220:223], v[10:13]
	v_mfma_f32_16x16x32_bf16 v[14:17], v[208:211], v[224:227], v[14:17]
	ds_read_b128 v[208:211], v244 offset:25408
	s_waitcnt vmcnt(13)
	ds_write_b128 v98, v[148:151] offset:9216
	s_waitcnt vmcnt(12)
	ds_write_b128 v98, v[152:155] offset:13824
	s_waitcnt lgkmcnt(7)
	v_mfma_f32_16x16x32_bf16 v[50:53], v[196:199], v[228:231], v[50:53]
	v_mfma_f32_16x16x32_bf16 v[54:57], v[196:199], v[232:235], v[54:57]
	v_mfma_f32_16x16x32_bf16 v[18:21], v[196:199], v[236:239], v[18:21]
	v_mfma_f32_16x16x32_bf16 v[22:25], v[196:199], v[240:243], v[22:25]
	s_waitcnt vmcnt(11)
	ds_write_b128 v98, v[156:159] offset:36864
	s_waitcnt vmcnt(10)
	ds_write_b128 v98, v[160:163] offset:41472
	s_waitcnt lgkmcnt(8)
	v_mfma_f32_16x16x32_bf16 v[58:61], v[200:203], v[228:231], v[58:61]
	v_mfma_f32_16x16x32_bf16 v[62:65], v[200:203], v[232:235], v[62:65]
	v_mfma_f32_16x16x32_bf16 v[26:29], v[200:203], v[236:239], v[26:29]
	v_mfma_f32_16x16x32_bf16 v[30:33], v[200:203], v[240:243], v[30:33]
	s_waitcnt vmcnt(9)
	ds_write_b128 v98, v[164:167] offset:46080
	s_waitcnt vmcnt(8)
	ds_write_b128 v98, v[168:171] offset:50688
	s_waitcnt lgkmcnt(0)
	s_barrier
	s_setprio 0
	ds_read_b128 v[212:215], v245 offset:36864
	ds_read_b128 v[196:199], v244
	ds_read_b128 v[216:219], v245 offset:39168
	ds_read_b128 v[220:223], v245 offset:41472
	ds_read_b128 v[224:227], v245 offset:43776
	ds_read_b128 v[200:203], v244 offset:2304
	v_mfma_f32_16x16x32_bf16 v[34:37], v[204:207], v[228:231], v[34:37]
	v_mfma_f32_16x16x32_bf16 v[38:41], v[204:207], v[232:235], v[38:41]
	v_mfma_f32_16x16x32_bf16 v[2:5], v[204:207], v[236:239], v[2:5]
	v_mfma_f32_16x16x32_bf16 v[6:9], v[204:207], v[240:243], v[6:9]
	ds_read_b128 v[204:207], v244 offset:4608
	v_mfma_f32_16x16x32_bf16 v[42:45], v[208:211], v[228:231], v[42:45]
	v_mfma_f32_16x16x32_bf16 v[46:49], v[208:211], v[232:235], v[46:49]
	v_mfma_f32_16x16x32_bf16 v[10:13], v[208:211], v[236:239], v[10:13]
	v_mfma_f32_16x16x32_bf16 v[14:17], v[208:211], v[240:243], v[14:17]
	ds_read_b128 v[208:211], v244 offset:6912
	global_load_dwordx4 v[140:143], v[74:75], off offset:1792
	global_load_dwordx4 v[144:147], v[76:77], off offset:1792
	global_load_dwordx4 v[148:151], v[78:79], off offset:1792
	global_load_dwordx4 v[152:155], v[80:81], off offset:1792
	global_load_dwordx4 v[156:159], v[82:83], off offset:1792
	global_load_dwordx4 v[160:163], v[84:85], off offset:1792
	global_load_dwordx4 v[164:167], v[86:87], off offset:1792
	global_load_dwordx4 v[168:171], v[88:89], off offset:1792
	s_waitcnt lgkmcnt(6)
	v_mfma_f32_16x16x32_bf16 v[50:53], v[196:199], v[212:215], v[50:53]
	ds_read_b128 v[228:231], v245 offset:36928
	s_waitcnt lgkmcnt(6)
	v_mfma_f32_16x16x32_bf16 v[54:57], v[196:199], v[216:219], v[54:57]
	ds_read_b128 v[232:235], v245 offset:39232
	s_waitcnt lgkmcnt(6)
	v_mfma_f32_16x16x32_bf16 v[18:21], v[196:199], v[220:223], v[18:21]
	ds_read_b128 v[236:239], v245 offset:41536
	s_waitcnt lgkmcnt(6)
	v_mfma_f32_16x16x32_bf16 v[22:25], v[196:199], v[224:227], v[22:25]
	ds_read_b128 v[240:243], v245 offset:43840
	ds_read_b128 v[196:199], v244 offset:64
	s_waitcnt lgkmcnt(7)
	v_mfma_f32_16x16x32_bf16 v[58:61], v[200:203], v[212:215], v[58:61]
	v_mfma_f32_16x16x32_bf16 v[62:65], v[200:203], v[216:219], v[62:65]
	v_mfma_f32_16x16x32_bf16 v[26:29], v[200:203], v[220:223], v[26:29]
	v_mfma_f32_16x16x32_bf16 v[30:33], v[200:203], v[224:227], v[30:33]
	ds_read_b128 v[200:203], v244 offset:2368
	s_waitcnt lgkmcnt(7)
	v_mfma_f32_16x16x32_bf16 v[34:37], v[204:207], v[212:215], v[34:37]
	v_mfma_f32_16x16x32_bf16 v[38:41], v[204:207], v[216:219], v[38:41]
	v_mfma_f32_16x16x32_bf16 v[2:5], v[204:207], v[220:223], v[2:5]
	v_mfma_f32_16x16x32_bf16 v[6:9], v[204:207], v[224:227], v[6:9]
	ds_read_b128 v[204:207], v244 offset:4672
	s_setprio 1
	s_waitcnt vmcnt(15)
	ds_write_b128 v98, v[102:105] offset:18432
	s_waitcnt vmcnt(14)
	ds_write_b128 v98, v[106:109] offset:23040
	s_waitcnt lgkmcnt(9)
	v_mfma_f32_16x16x32_bf16 v[42:45], v[208:211], v[212:215], v[42:45]
	v_mfma_f32_16x16x32_bf16 v[46:49], v[208:211], v[216:219], v[46:49]
	v_mfma_f32_16x16x32_bf16 v[10:13], v[208:211], v[220:223], v[10:13]
	v_mfma_f32_16x16x32_bf16 v[14:17], v[208:211], v[224:227], v[14:17]
	ds_read_b128 v[208:211], v244 offset:6976
	s_waitcnt vmcnt(13)
	ds_write_b128 v98, v[110:113] offset:27648
	s_waitcnt vmcnt(12)
	ds_write_b128 v98, v[114:117] offset:32256
	s_waitcnt lgkmcnt(7)
	v_mfma_f32_16x16x32_bf16 v[50:53], v[196:199], v[228:231], v[50:53]
	v_mfma_f32_16x16x32_bf16 v[54:57], v[196:199], v[232:235], v[54:57]
	v_mfma_f32_16x16x32_bf16 v[18:21], v[196:199], v[236:239], v[18:21]
	v_mfma_f32_16x16x32_bf16 v[22:25], v[196:199], v[240:243], v[22:25]
	s_waitcnt vmcnt(11)
	ds_write_b128 v98, v[118:121] offset:55296
	s_waitcnt vmcnt(10)
	ds_write_b128 v98, v[122:125] offset:59904
	s_waitcnt lgkmcnt(8)
	v_mfma_f32_16x16x32_bf16 v[58:61], v[200:203], v[228:231], v[58:61]
	v_mfma_f32_16x16x32_bf16 v[62:65], v[200:203], v[232:235], v[62:65]
	v_mfma_f32_16x16x32_bf16 v[26:29], v[200:203], v[236:239], v[26:29]
	v_mfma_f32_16x16x32_bf16 v[30:33], v[200:203], v[240:243], v[30:33]
	s_waitcnt vmcnt(9)
	ds_write_b128 v98, v[126:129] offset:64512
	s_waitcnt vmcnt(8)
	ds_write_b128 v99, v[136:139] offset:32256
	s_waitcnt lgkmcnt(0)
	s_barrier
	s_setprio 0
	ds_read_b128 v[212:215], v245 offset:55296
	ds_read_b128 v[196:199], v244 offset:18432
	ds_read_b128 v[216:219], v245 offset:57600
	ds_read_b128 v[220:223], v245 offset:59904
	ds_read_b128 v[224:227], v245 offset:62208
	ds_read_b128 v[200:203], v244 offset:20736
	v_mfma_f32_16x16x32_bf16 v[34:37], v[204:207], v[228:231], v[34:37]
	v_mfma_f32_16x16x32_bf16 v[38:41], v[204:207], v[232:235], v[38:41]
	v_mfma_f32_16x16x32_bf16 v[2:5], v[204:207], v[236:239], v[2:5]
	v_mfma_f32_16x16x32_bf16 v[6:9], v[204:207], v[240:243], v[6:9]
	ds_read_b128 v[204:207], v244 offset:23040
	v_mfma_f32_16x16x32_bf16 v[42:45], v[208:211], v[228:231], v[42:45]
	v_mfma_f32_16x16x32_bf16 v[46:49], v[208:211], v[232:235], v[46:49]
	v_mfma_f32_16x16x32_bf16 v[10:13], v[208:211], v[236:239], v[10:13]
	v_mfma_f32_16x16x32_bf16 v[14:17], v[208:211], v[240:243], v[14:17]
	ds_read_b128 v[208:211], v244 offset:25344
	global_load_dwordx4 v[102:105], v[74:75], off offset:1920
	s_nop 0
	global_load_dwordx4 v[74:77], v[76:77], off offset:1920
	s_nop 0
	global_load_dwordx4 v[106:109], v[78:79], off offset:1920
	s_nop 0
	global_load_dwordx4 v[78:81], v[80:81], off offset:1920
	s_nop 0
	global_load_dwordx4 v[110:113], v[82:83], off offset:1920
	s_nop 0
	global_load_dwordx4 v[82:85], v[84:85], off offset:1920
	s_nop 0
	global_load_dwordx4 v[114:117], v[86:87], off offset:1920
	s_nop 0
	global_load_dwordx4 v[86:89], v[88:89], off offset:1920
	s_waitcnt lgkmcnt(6)
	v_mfma_f32_16x16x32_bf16 v[50:53], v[196:199], v[212:215], v[50:53]
	ds_read_b128 v[228:231], v245 offset:55360
	s_waitcnt lgkmcnt(6)
	v_mfma_f32_16x16x32_bf16 v[54:57], v[196:199], v[216:219], v[54:57]
	ds_read_b128 v[232:235], v245 offset:57664
	s_waitcnt lgkmcnt(6)
	v_mfma_f32_16x16x32_bf16 v[18:21], v[196:199], v[220:223], v[18:21]
	ds_read_b128 v[236:239], v245 offset:59968
	s_waitcnt lgkmcnt(6)
	v_mfma_f32_16x16x32_bf16 v[22:25], v[196:199], v[224:227], v[22:25]
	ds_read_b128 v[240:243], v245 offset:62272
	ds_read_b128 v[196:199], v244 offset:18496
	s_waitcnt lgkmcnt(7)
	v_mfma_f32_16x16x32_bf16 v[58:61], v[200:203], v[212:215], v[58:61]
	v_mfma_f32_16x16x32_bf16 v[62:65], v[200:203], v[216:219], v[62:65]
	v_mfma_f32_16x16x32_bf16 v[26:29], v[200:203], v[220:223], v[26:29]
	v_mfma_f32_16x16x32_bf16 v[30:33], v[200:203], v[224:227], v[30:33]
	ds_read_b128 v[200:203], v244 offset:20800
	s_waitcnt lgkmcnt(7)
	v_mfma_f32_16x16x32_bf16 v[34:37], v[204:207], v[212:215], v[34:37]
	v_mfma_f32_16x16x32_bf16 v[38:41], v[204:207], v[216:219], v[38:41]
	v_mfma_f32_16x16x32_bf16 v[2:5], v[204:207], v[220:223], v[2:5]
	v_mfma_f32_16x16x32_bf16 v[6:9], v[204:207], v[224:227], v[6:9]
	ds_read_b128 v[204:207], v244 offset:23104
	s_setprio 1
	s_waitcnt vmcnt(15)
	ds_write_b128 v98, v[140:143]
	s_waitcnt vmcnt(14)
	ds_write_b128 v98, v[144:147] offset:4608
	s_waitcnt lgkmcnt(9)
	v_mfma_f32_16x16x32_bf16 v[42:45], v[208:211], v[212:215], v[42:45]
	v_mfma_f32_16x16x32_bf16 v[46:49], v[208:211], v[216:219], v[46:49]
	v_mfma_f32_16x16x32_bf16 v[10:13], v[208:211], v[220:223], v[10:13]
	v_mfma_f32_16x16x32_bf16 v[14:17], v[208:211], v[224:227], v[14:17]
	ds_read_b128 v[208:211], v244 offset:25408
	s_waitcnt vmcnt(13)
	ds_write_b128 v98, v[148:151] offset:9216
	s_waitcnt vmcnt(12)
	ds_write_b128 v98, v[152:155] offset:13824
	s_waitcnt lgkmcnt(7)
	v_mfma_f32_16x16x32_bf16 v[50:53], v[196:199], v[228:231], v[50:53]
	v_mfma_f32_16x16x32_bf16 v[54:57], v[196:199], v[232:235], v[54:57]
	v_mfma_f32_16x16x32_bf16 v[18:21], v[196:199], v[236:239], v[18:21]
	v_mfma_f32_16x16x32_bf16 v[22:25], v[196:199], v[240:243], v[22:25]
	s_waitcnt vmcnt(11)
	ds_write_b128 v98, v[156:159] offset:36864
	s_waitcnt vmcnt(10)
	ds_write_b128 v98, v[160:163] offset:41472
	s_waitcnt lgkmcnt(8)
	v_mfma_f32_16x16x32_bf16 v[58:61], v[200:203], v[228:231], v[58:61]
	v_mfma_f32_16x16x32_bf16 v[62:65], v[200:203], v[232:235], v[62:65]
	v_mfma_f32_16x16x32_bf16 v[26:29], v[200:203], v[236:239], v[26:29]
	v_mfma_f32_16x16x32_bf16 v[30:33], v[200:203], v[240:243], v[30:33]
	s_waitcnt vmcnt(9)
	ds_write_b128 v98, v[164:167] offset:46080
	s_waitcnt vmcnt(8)
	ds_write_b128 v98, v[168:171] offset:50688
	s_waitcnt lgkmcnt(0)
	s_barrier
	s_setprio 0
	ds_read_b128 v[212:215], v245 offset:36864
	ds_read_b128 v[196:199], v244
	ds_read_b128 v[216:219], v245 offset:39168
	ds_read_b128 v[220:223], v245 offset:41472
	ds_read_b128 v[224:227], v245 offset:43776
	ds_read_b128 v[200:203], v244 offset:2304
	v_mfma_f32_16x16x32_bf16 v[34:37], v[204:207], v[228:231], v[34:37]
	v_mfma_f32_16x16x32_bf16 v[38:41], v[204:207], v[232:235], v[38:41]
	v_mfma_f32_16x16x32_bf16 v[2:5], v[204:207], v[236:239], v[2:5]
	v_mfma_f32_16x16x32_bf16 v[6:9], v[204:207], v[240:243], v[6:9]
	ds_read_b128 v[204:207], v244 offset:4608
	v_mfma_f32_16x16x32_bf16 v[42:45], v[208:211], v[228:231], v[42:45]
	v_mfma_f32_16x16x32_bf16 v[46:49], v[208:211], v[232:235], v[46:49]
	v_mfma_f32_16x16x32_bf16 v[10:13], v[208:211], v[236:239], v[10:13]
	v_mfma_f32_16x16x32_bf16 v[14:17], v[208:211], v[240:243], v[14:17]
	ds_read_b128 v[208:211], v244 offset:6912
	s_waitcnt lgkmcnt(6)
	v_mfma_f32_16x16x32_bf16 v[50:53], v[196:199], v[212:215], v[50:53]
	ds_read_b128 v[228:231], v245 offset:36928
	s_waitcnt lgkmcnt(6)
	v_mfma_f32_16x16x32_bf16 v[54:57], v[196:199], v[216:219], v[54:57]
	ds_read_b128 v[232:235], v245 offset:39232
	s_waitcnt lgkmcnt(6)
	v_mfma_f32_16x16x32_bf16 v[18:21], v[196:199], v[220:223], v[18:21]
	ds_read_b128 v[236:239], v245 offset:41536
	s_waitcnt lgkmcnt(6)
	v_mfma_f32_16x16x32_bf16 v[22:25], v[196:199], v[224:227], v[22:25]
	ds_read_b128 v[240:243], v245 offset:43840
	ds_read_b128 v[196:199], v244 offset:64
	s_waitcnt lgkmcnt(7)
	v_mfma_f32_16x16x32_bf16 v[58:61], v[200:203], v[212:215], v[58:61]
	v_mfma_f32_16x16x32_bf16 v[62:65], v[200:203], v[216:219], v[62:65]
	v_mfma_f32_16x16x32_bf16 v[26:29], v[200:203], v[220:223], v[26:29]
	v_mfma_f32_16x16x32_bf16 v[30:33], v[200:203], v[224:227], v[30:33]
	ds_read_b128 v[200:203], v244 offset:2368
	s_waitcnt lgkmcnt(7)
	v_mfma_f32_16x16x32_bf16 v[34:37], v[204:207], v[212:215], v[34:37]
	v_mfma_f32_16x16x32_bf16 v[38:41], v[204:207], v[216:219], v[38:41]
	v_mfma_f32_16x16x32_bf16 v[2:5], v[204:207], v[220:223], v[2:5]
	v_mfma_f32_16x16x32_bf16 v[6:9], v[204:207], v[224:227], v[6:9]
	ds_read_b128 v[204:207], v244 offset:4672
	s_setprio 1
	s_waitcnt vmcnt(7)
	ds_write_b128 v98, v[102:105] offset:18432
	s_waitcnt vmcnt(6)
	ds_write_b128 v98, v[74:77] offset:23040
	s_waitcnt lgkmcnt(9)
	v_mfma_f32_16x16x32_bf16 v[42:45], v[208:211], v[212:215], v[42:45]
	v_mfma_f32_16x16x32_bf16 v[46:49], v[208:211], v[216:219], v[46:49]
	v_mfma_f32_16x16x32_bf16 v[10:13], v[208:211], v[220:223], v[10:13]
	v_mfma_f32_16x16x32_bf16 v[14:17], v[208:211], v[224:227], v[14:17]
	ds_read_b128 v[208:211], v244 offset:6976
	s_waitcnt vmcnt(5)
	ds_write_b128 v98, v[106:109] offset:27648
	s_waitcnt vmcnt(4)
	ds_write_b128 v98, v[78:81] offset:32256
	s_waitcnt lgkmcnt(7)
	v_mfma_f32_16x16x32_bf16 v[50:53], v[196:199], v[228:231], v[50:53]
	v_mfma_f32_16x16x32_bf16 v[54:57], v[196:199], v[232:235], v[54:57]
	v_mfma_f32_16x16x32_bf16 v[18:21], v[196:199], v[236:239], v[18:21]
	v_mfma_f32_16x16x32_bf16 v[22:25], v[196:199], v[240:243], v[22:25]
	s_waitcnt vmcnt(3)
	ds_write_b128 v98, v[110:113] offset:55296
	s_waitcnt vmcnt(2)
	ds_write_b128 v98, v[82:85] offset:59904
	s_waitcnt lgkmcnt(8)
	v_mfma_f32_16x16x32_bf16 v[58:61], v[200:203], v[228:231], v[58:61]
	v_mfma_f32_16x16x32_bf16 v[62:65], v[200:203], v[232:235], v[62:65]
	v_mfma_f32_16x16x32_bf16 v[26:29], v[200:203], v[236:239], v[26:29]
	v_mfma_f32_16x16x32_bf16 v[30:33], v[200:203], v[240:243], v[30:33]
	s_waitcnt vmcnt(1)
	ds_write_b128 v98, v[114:117] offset:64512
	s_waitcnt vmcnt(0)
	ds_write_b128 v99, v[86:89] offset:32256
	s_waitcnt lgkmcnt(0)
	s_barrier
	s_setprio 0
	ds_read_b128 v[212:215], v245 offset:55296
	ds_read_b128 v[196:199], v244 offset:18432
	ds_read_b128 v[216:219], v245 offset:57600
	ds_read_b128 v[220:223], v245 offset:59904
	ds_read_b128 v[224:227], v245 offset:62208
	ds_read_b128 v[200:203], v244 offset:20736
	v_mfma_f32_16x16x32_bf16 v[34:37], v[204:207], v[228:231], v[34:37]
	v_mfma_f32_16x16x32_bf16 v[38:41], v[204:207], v[232:235], v[38:41]
	v_mfma_f32_16x16x32_bf16 v[2:5], v[204:207], v[236:239], v[2:5]
	v_mfma_f32_16x16x32_bf16 v[6:9], v[204:207], v[240:243], v[6:9]
	ds_read_b128 v[204:207], v244 offset:23040
	v_mfma_f32_16x16x32_bf16 v[42:45], v[208:211], v[228:231], v[42:45]
	v_mfma_f32_16x16x32_bf16 v[46:49], v[208:211], v[232:235], v[46:49]
	v_mfma_f32_16x16x32_bf16 v[10:13], v[208:211], v[236:239], v[10:13]
	v_mfma_f32_16x16x32_bf16 v[14:17], v[208:211], v[240:243], v[14:17]
	ds_read_b128 v[208:211], v244 offset:25344
	s_waitcnt lgkmcnt(6)
	v_mfma_f32_16x16x32_bf16 v[50:53], v[196:199], v[212:215], v[50:53]
	ds_read_b128 v[228:231], v245 offset:55360
	s_waitcnt lgkmcnt(6)
	v_mfma_f32_16x16x32_bf16 v[54:57], v[196:199], v[216:219], v[54:57]
	ds_read_b128 v[232:235], v245 offset:57664
	s_waitcnt lgkmcnt(6)
	v_mfma_f32_16x16x32_bf16 v[18:21], v[196:199], v[220:223], v[18:21]
	ds_read_b128 v[236:239], v245 offset:59968
	s_waitcnt lgkmcnt(6)
	v_mfma_f32_16x16x32_bf16 v[22:25], v[196:199], v[224:227], v[22:25]
	ds_read_b128 v[240:243], v245 offset:62272
	ds_read_b128 v[196:199], v244 offset:18496
	s_waitcnt lgkmcnt(7)
	v_mfma_f32_16x16x32_bf16 v[58:61], v[200:203], v[212:215], v[58:61]
	v_mfma_f32_16x16x32_bf16 v[62:65], v[200:203], v[216:219], v[62:65]
	v_mfma_f32_16x16x32_bf16 v[26:29], v[200:203], v[220:223], v[26:29]
	v_mfma_f32_16x16x32_bf16 v[30:33], v[200:203], v[224:227], v[30:33]
	ds_read_b128 v[200:203], v244 offset:20800
	s_waitcnt lgkmcnt(7)
	v_mfma_f32_16x16x32_bf16 v[34:37], v[204:207], v[212:215], v[34:37]
	v_mfma_f32_16x16x32_bf16 v[38:41], v[204:207], v[216:219], v[38:41]
	v_mfma_f32_16x16x32_bf16 v[2:5], v[204:207], v[220:223], v[2:5]
	v_mfma_f32_16x16x32_bf16 v[6:9], v[204:207], v[224:227], v[6:9]
	ds_read_b128 v[204:207], v244 offset:23104
	s_waitcnt lgkmcnt(7)
	v_mfma_f32_16x16x32_bf16 v[42:45], v[208:211], v[212:215], v[42:45]
	v_mfma_f32_16x16x32_bf16 v[46:49], v[208:211], v[216:219], v[46:49]
	v_mfma_f32_16x16x32_bf16 v[10:13], v[208:211], v[220:223], v[10:13]
	v_mfma_f32_16x16x32_bf16 v[14:17], v[208:211], v[224:227], v[14:17]
	ds_read_b128 v[208:211], v244 offset:25408
	s_waitcnt lgkmcnt(3)
	v_mfma_f32_16x16x32_bf16 v[50:53], v[196:199], v[228:231], v[50:53]
	v_mfma_f32_16x16x32_bf16 v[54:57], v[196:199], v[232:235], v[54:57]
	v_mfma_f32_16x16x32_bf16 v[18:21], v[196:199], v[236:239], v[18:21]
	v_mfma_f32_16x16x32_bf16 v[22:25], v[196:199], v[240:243], v[22:25]
	s_waitcnt lgkmcnt(2)
	v_mfma_f32_16x16x32_bf16 v[58:61], v[200:203], v[228:231], v[58:61]
	v_mfma_f32_16x16x32_bf16 v[62:65], v[200:203], v[232:235], v[62:65]
	v_mfma_f32_16x16x32_bf16 v[26:29], v[200:203], v[236:239], v[26:29]
	v_mfma_f32_16x16x32_bf16 v[30:33], v[200:203], v[240:243], v[30:33]
	s_lshr_b32 s14, s2, 3
	s_bfe_u32 s13, s2, 0x10002
	s_cmp_lt_i32 s14, 1
	s_mov_b64 s[2:3], -1
	s_waitcnt lgkmcnt(0)
	s_barrier
	v_mfma_f32_16x16x32_bf16 v[34:37], v[204:207], v[228:231], v[34:37]
	v_mfma_f32_16x16x32_bf16 v[38:41], v[204:207], v[232:235], v[38:41]
	v_mfma_f32_16x16x32_bf16 v[2:5], v[204:207], v[236:239], v[2:5]
	v_mfma_f32_16x16x32_bf16 v[6:9], v[204:207], v[240:243], v[6:9]
	v_mfma_f32_16x16x32_bf16 v[42:45], v[208:211], v[228:231], v[42:45]
	v_mfma_f32_16x16x32_bf16 v[46:49], v[208:211], v[232:235], v[46:49]
	v_mfma_f32_16x16x32_bf16 v[10:13], v[208:211], v[236:239], v[10:13]
	v_mfma_f32_16x16x32_bf16 v[14:17], v[208:211], v[240:243], v[14:17]
	s_nop 7
	v_permlane16_swap_b32_e32 v50, v54
	v_permlane16_swap_b32_e32 v51, v55
	v_permlane16_swap_b32_e32 v52, v56
	v_permlane16_swap_b32_e32 v53, v57
	v_permlane16_swap_b32_e32 v58, v62
	v_permlane16_swap_b32_e32 v59, v63
	v_permlane16_swap_b32_e32 v60, v64
	v_permlane16_swap_b32_e32 v61, v65
	v_permlane16_swap_b32_e32 v18, v22
	v_permlane16_swap_b32_e32 v19, v23
	v_permlane16_swap_b32_e32 v20, v24
	v_permlane16_swap_b32_e32 v21, v25
	v_permlane16_swap_b32_e32 v26, v30
	v_permlane16_swap_b32_e32 v27, v31
	v_permlane16_swap_b32_e32 v28, v32
	v_permlane16_swap_b32_e32 v29, v33
	v_permlane16_swap_b32_e32 v34, v38
	v_permlane16_swap_b32_e32 v35, v39
	v_permlane16_swap_b32_e32 v36, v40
	v_permlane16_swap_b32_e32 v37, v41
	v_permlane16_swap_b32_e32 v42, v46
	v_permlane16_swap_b32_e32 v43, v47
	v_permlane16_swap_b32_e32 v44, v48
	v_permlane16_swap_b32_e32 v45, v49
	v_permlane16_swap_b32_e32 v2, v6
	v_permlane16_swap_b32_e32 v3, v7
	v_permlane16_swap_b32_e32 v4, v8
	v_permlane16_swap_b32_e32 v5, v9
	v_permlane16_swap_b32_e32 v10, v14
	v_permlane16_swap_b32_e32 v11, v15
	v_permlane16_swap_b32_e32 v12, v16
	v_permlane16_swap_b32_e32 v13, v17
	v_permlane32_swap_b32_e32 v50, v54
	v_permlane32_swap_b32_e32 v51, v55
	v_permlane32_swap_b32_e32 v52, v56
	v_permlane32_swap_b32_e32 v53, v57
	v_permlane32_swap_b32_e32 v58, v62
	v_permlane32_swap_b32_e32 v59, v63
	v_permlane32_swap_b32_e32 v60, v64
	v_permlane32_swap_b32_e32 v61, v65
	v_permlane32_swap_b32_e32 v18, v22
	v_permlane32_swap_b32_e32 v19, v23
	v_permlane32_swap_b32_e32 v20, v24
	v_permlane32_swap_b32_e32 v21, v25
	v_permlane32_swap_b32_e32 v26, v30
	v_permlane32_swap_b32_e32 v27, v31
	v_permlane32_swap_b32_e32 v28, v32
	v_permlane32_swap_b32_e32 v29, v33
	v_permlane32_swap_b32_e32 v34, v38
	v_permlane32_swap_b32_e32 v35, v39
	v_permlane32_swap_b32_e32 v36, v40
	v_permlane32_swap_b32_e32 v37, v41
	v_permlane32_swap_b32_e32 v42, v46
	v_permlane32_swap_b32_e32 v43, v47
	v_permlane32_swap_b32_e32 v44, v48
	v_permlane32_swap_b32_e32 v45, v49
	v_permlane32_swap_b32_e32 v2, v6
	v_permlane32_swap_b32_e32 v3, v7
	v_permlane32_swap_b32_e32 v4, v8
	v_permlane32_swap_b32_e32 v5, v9
	v_permlane32_swap_b32_e32 v10, v14
	v_permlane32_swap_b32_e32 v11, v15
	v_permlane32_swap_b32_e32 v12, v16
	v_permlane32_swap_b32_e32 v13, v17
	s_cbranch_scc1 .LBB0_755
	s_and_b32 s2, 0xffff, s14
	s_cmp_lg_u32 s2, 1
	s_mov_b64 s[2:3], -1
	s_cbranch_scc0 .LBB0_752
	s_cmp_eq_u32 s13, 0
	s_cselect_b32 s12, 3, 10
	s_mov_b64 s[2:3], 0

.LBB0_828:
	s_lshr_b32 s8, s0, 2
	s_lshl_b32 s0, s0, 7
	s_and_b32 s7, s0, 0x180
	v_or_b32_e32 v2, s7, v93
	v_lshlrev_b32_e32 v74, 10, v2
	s_add_i32 s8, s8, s4
	v_lshl_add_u64 v[66:67], v[76:77], 0, v[74:75]
	v_add_lshl_u32 v74, s7, v94, 10
	s_lshl_b32 s0, s8, 7
	v_lshl_add_u64 v[68:69], v[76:77], 0, v[74:75]
	v_add_lshl_u32 v74, s7, v95, 10
	v_lshl_add_u64 v[70:71], v[76:77], 0, v[74:75]
	v_add_lshl_u32 v74, s7, v96, 10
	v_or_b32_e32 v2, s0, v93
	v_lshl_add_u64 v[72:73], v[76:77], 0, v[74:75]
	v_lshlrev_b32_e32 v74, 10, v2
	v_lshl_add_u64 v[84:85], v[78:79], 0, v[74:75]
	v_add_lshl_u32 v74, s0, v94, 10
	v_lshl_add_u64 v[86:87], v[78:79], 0, v[74:75]
	v_add_lshl_u32 v74, s0, v95, 10
	v_lshl_add_u64 v[88:89], v[78:79], 0, v[74:75]
	v_add_lshl_u32 v74, s0, v96, 10
	v_lshl_add_u64 v[90:91], v[78:79], 0, v[74:75]
	global_load_dwordx4 v[2:5], v[66:67], off
	global_load_dwordx4 v[6:9], v[68:69], off
	global_load_dwordx4 v[10:13], v[70:71], off
	global_load_dwordx4 v[14:17], v[72:73], off
	global_load_dwordx4 v[18:21], v[84:85], off
	global_load_dwordx4 v[22:25], v[86:87], off
	global_load_dwordx4 v[26:29], v[88:89], off
	global_load_dwordx4 v[30:33], v[90:91], off
	global_load_dwordx4 v[102:105], v[66:67], off offset:128
	global_load_dwordx4 v[106:109], v[68:69], off offset:128
	global_load_dwordx4 v[110:113], v[70:71], off offset:128
	global_load_dwordx4 v[114:117], v[72:73], off offset:128
	global_load_dwordx4 v[118:121], v[84:85], off offset:128
	global_load_dwordx4 v[122:125], v[86:87], off offset:128
	global_load_dwordx4 v[126:129], v[88:89], off offset:128
	global_load_dwordx4 v[136:139], v[90:91], off offset:128
	s_waitcnt vmcnt(15)
	ds_write_b128 v100, v[2:5]
	s_waitcnt vmcnt(14)
	ds_write_b128 v100, v[6:9] offset:4608
	s_waitcnt vmcnt(13)
	ds_write_b128 v100, v[10:13] offset:9216
	s_waitcnt vmcnt(12)
	ds_write_b128 v100, v[14:17] offset:13824
	s_waitcnt vmcnt(11)
	ds_write_b128 v100, v[18:21] offset:36864
	s_waitcnt vmcnt(10)
	ds_write_b128 v100, v[22:25] offset:41472
	s_waitcnt vmcnt(9)
	ds_write_b128 v100, v[26:29] offset:46080
	s_waitcnt vmcnt(8)
	ds_write_b128 v100, v[30:33] offset:50688
	s_waitcnt lgkmcnt(0)
	s_barrier
	global_load_dwordx4 v[140:143], v[66:67], off offset:256
	global_load_dwordx4 v[144:147], v[68:69], off offset:256
	global_load_dwordx4 v[148:151], v[70:71], off offset:256
	global_load_dwordx4 v[152:155], v[72:73], off offset:256
	global_load_dwordx4 v[156:159], v[84:85], off offset:256
	global_load_dwordx4 v[160:163], v[86:87], off offset:256
	global_load_dwordx4 v[164:167], v[88:89], off offset:256
	global_load_dwordx4 v[168:171], v[90:91], off offset:256
	v_and_b32_e32 v246, 15, v1
	v_add_u32_e32 v246, 4, v246
	v_bfe_u32 v246, v246, 3, 1
	v_bfe_u32 v249, v1, 4, 2
	v_xor_b32_e32 v246, v246, v249
	v_bfe_u32 v249, v1, 5, 1
	v_sub_u32_e32 v246, v246, v249
	v_lshlrev_b32_e32 v246, 4, v246
	v_bfe_u32 v249, v1, 4, 1
	v_mul_u32_u24_e32 v249, 0x900, v249
	v_sub_u32_e32 v246, v246, v249
	v_add_u32_e32 v244, v246, v98
	v_add_u32_e32 v245, v246, v99
	ds_read_b128 v[212:215], v245 offset:36864
	ds_read_b128 v[196:199], v244
	ds_read_b128 v[216:219], v245 offset:39168
	ds_read_b128 v[220:223], v245 offset:41472
	ds_read_b128 v[224:227], v245 offset:43776
	ds_read_b128 v[200:203], v244 offset:2304
	ds_read_b128 v[204:207], v244 offset:4608
	ds_read_b128 v[208:211], v244 offset:6912
	s_waitcnt lgkmcnt(6)
	v_mfma_f32_16x16x32_bf16 v[50:53], v[196:199], v[212:215], 0
	ds_read_b128 v[228:231], v245 offset:36928
	s_waitcnt lgkmcnt(6)
	v_mfma_f32_16x16x32_bf16 v[54:57], v[196:199], v[216:219], 0
	ds_read_b128 v[232:235], v245 offset:39232
	s_waitcnt lgkmcnt(6)
	v_mfma_f32_16x16x32_bf16 v[18:21], v[196:199], v[220:223], 0
	ds_read_b128 v[236:239], v245 offset:41536
	s_waitcnt lgkmcnt(6)
	v_mfma_f32_16x16x32_bf16 v[22:25], v[196:199], v[224:227], 0
	ds_read_b128 v[240:243], v245 offset:43840
	ds_read_b128 v[196:199], v244 offset:64
	s_waitcnt lgkmcnt(7)
	v_mfma_f32_16x16x32_bf16 v[58:61], v[200:203], v[212:215], 0
	v_mfma_f32_16x16x32_bf16 v[62:65], v[200:203], v[216:219], 0
	v_mfma_f32_16x16x32_bf16 v[26:29], v[200:203], v[220:223], 0
	v_mfma_f32_16x16x32_bf16 v[30:33], v[200:203], v[224:227], 0
	ds_read_b128 v[200:203], v244 offset:2368
	s_waitcnt lgkmcnt(7)
	v_mfma_f32_16x16x32_bf16 v[34:37], v[204:207], v[212:215], 0
	v_mfma_f32_16x16x32_bf16 v[38:41], v[204:207], v[216:219], 0
	v_mfma_f32_16x16x32_bf16 v[2:5], v[204:207], v[220:223], 0
	v_mfma_f32_16x16x32_bf16 v[6:9], v[204:207], v[224:227], 0
	ds_read_b128 v[204:207], v244 offset:4672
	s_setprio 1
	s_waitcnt vmcnt(15)
	ds_write_b128 v100, v[102:105] offset:18432
	s_waitcnt vmcnt(14)
	ds_write_b128 v100, v[106:109] offset:23040
	s_waitcnt lgkmcnt(9)
	v_mfma_f32_16x16x32_bf16 v[42:45], v[208:211], v[212:215], 0
	v_mfma_f32_16x16x32_bf16 v[46:49], v[208:211], v[216:219], 0
	v_mfma_f32_16x16x32_bf16 v[10:13], v[208:211], v[220:223], 0
	v_mfma_f32_16x16x32_bf16 v[14:17], v[208:211], v[224:227], 0
	ds_read_b128 v[208:211], v244 offset:6976
	s_waitcnt vmcnt(13)
	ds_write_b128 v100, v[110:113] offset:27648
	s_waitcnt vmcnt(12)
	ds_write_b128 v100, v[114:117] offset:32256
	s_waitcnt lgkmcnt(7)
	v_mfma_f32_16x16x32_bf16 v[50:53], v[196:199], v[228:231], v[50:53]
	v_mfma_f32_16x16x32_bf16 v[54:57], v[196:199], v[232:235], v[54:57]
	v_mfma_f32_16x16x32_bf16 v[18:21], v[196:199], v[236:239], v[18:21]
	v_mfma_f32_16x16x32_bf16 v[22:25], v[196:199], v[240:243], v[22:25]
	s_waitcnt vmcnt(11)
	ds_write_b128 v100, v[118:121] offset:55296
	s_waitcnt vmcnt(10)
	ds_write_b128 v100, v[122:125] offset:59904
	s_waitcnt lgkmcnt(8)
	v_mfma_f32_16x16x32_bf16 v[58:61], v[200:203], v[228:231], v[58:61]
	v_mfma_f32_16x16x32_bf16 v[62:65], v[200:203], v[232:235], v[62:65]
	v_mfma_f32_16x16x32_bf16 v[26:29], v[200:203], v[236:239], v[26:29]
	v_mfma_f32_16x16x32_bf16 v[30:33], v[200:203], v[240:243], v[30:33]
	s_waitcnt vmcnt(9)
	ds_write_b128 v100, v[126:129] offset:64512
	s_waitcnt vmcnt(8)
	ds_write_b128 v101, v[136:139] offset:32256
	s_waitcnt lgkmcnt(0)
	s_barrier
	s_setprio 0
	ds_read_b128 v[212:215], v245 offset:55296
	ds_read_b128 v[196:199], v244 offset:18432
	ds_read_b128 v[216:219], v245 offset:57600
	ds_read_b128 v[220:223], v245 offset:59904
	ds_read_b128 v[224:227], v245 offset:62208
	ds_read_b128 v[200:203], v244 offset:20736
	v_mfma_f32_16x16x32_bf16 v[34:37], v[204:207], v[228:231], v[34:37]
	v_mfma_f32_16x16x32_bf16 v[38:41], v[204:207], v[232:235], v[38:41]
	v_mfma_f32_16x16x32_bf16 v[2:5], v[204:207], v[236:239], v[2:5]
	v_mfma_f32_16x16x32_bf16 v[6:9], v[204:207], v[240:243], v[6:9]
	ds_read_b128 v[204:207], v244 offset:23040
	v_mfma_f32_16x16x32_bf16 v[42:45], v[208:211], v[228:231], v[42:45]
	v_mfma_f32_16x16x32_bf16 v[46:49], v[208:211], v[232:235], v[46:49]
	v_mfma_f32_16x16x32_bf16 v[10:13], v[208:211], v[236:239], v[10:13]
	v_mfma_f32_16x16x32_bf16 v[14:17], v[208:211], v[240:243], v[14:17]
	ds_read_b128 v[208:211], v244 offset:25344
	global_load_dwordx4 v[102:105], v[66:67], off offset:384
	global_load_dwordx4 v[106:109], v[68:69], off offset:384
	global_load_dwordx4 v[110:113], v[70:71], off offset:384
	global_load_dwordx4 v[114:117], v[72:73], off offset:384
	global_load_dwordx4 v[118:121], v[84:85], off offset:384
	global_load_dwordx4 v[122:125], v[86:87], off offset:384
	global_load_dwordx4 v[126:129], v[88:89], off offset:384
	global_load_dwordx4 v[136:139], v[90:91], off offset:384
	s_waitcnt lgkmcnt(6)
	v_mfma_f32_16x16x32_bf16 v[50:53], v[196:199], v[212:215], v[50:53]
	ds_read_b128 v[228:231], v245 offset:55360
	s_waitcnt lgkmcnt(6)
	v_mfma_f32_16x16x32_bf16 v[54:57], v[196:199], v[216:219], v[54:57]
	ds_read_b128 v[232:235], v245 offset:57664
	s_waitcnt lgkmcnt(6)
	v_mfma_f32_16x16x32_bf16 v[18:21], v[196:199], v[220:223], v[18:21]
	ds_read_b128 v[236:239], v245 offset:59968
	s_waitcnt lgkmcnt(6)
	v_mfma_f32_16x16x32_bf16 v[22:25], v[196:199], v[224:227], v[22:25]
	ds_read_b128 v[240:243], v245 offset:62272
	ds_read_b128 v[196:199], v244 offset:18496
	s_waitcnt lgkmcnt(7)
	v_mfma_f32_16x16x32_bf16 v[58:61], v[200:203], v[212:215], v[58:61]
	v_mfma_f32_16x16x32_bf16 v[62:65], v[200:203], v[216:219], v[62:65]
	v_mfma_f32_16x16x32_bf16 v[26:29], v[200:203], v[220:223], v[26:29]
	v_mfma_f32_16x16x32_bf16 v[30:33], v[200:203], v[224:227], v[30:33]
	ds_read_b128 v[200:203], v244 offset:20800
	s_waitcnt lgkmcnt(7)
	v_mfma_f32_16x16x32_bf16 v[34:37], v[204:207], v[212:215], v[34:37]
	v_mfma_f32_16x16x32_bf16 v[38:41], v[204:207], v[216:219], v[38:41]
	v_mfma_f32_16x16x32_bf16 v[2:5], v[204:207], v[220:223], v[2:5]
	v_mfma_f32_16x16x32_bf16 v[6:9], v[204:207], v[224:227], v[6:9]
	ds_read_b128 v[204:207], v244 offset:23104
	s_setprio 1
	s_waitcnt vmcnt(15)
	ds_write_b128 v100, v[140:143]
	s_waitcnt vmcnt(14)
	ds_write_b128 v100, v[144:147] offset:4608
	s_waitcnt lgkmcnt(9)
	v_mfma_f32_16x16x32_bf16 v[42:45], v[208:211], v[212:215], v[42:45]
	v_mfma_f32_16x16x32_bf16 v[46:49], v[208:211], v[216:219], v[46:49]
	v_mfma_f32_16x16x32_bf16 v[10:13], v[208:211], v[220:223], v[10:13]
	v_mfma_f32_16x16x32_bf16 v[14:17], v[208:211], v[224:227], v[14:17]
	ds_read_b128 v[208:211], v244 offset:25408
	s_waitcnt vmcnt(13)
	ds_write_b128 v100, v[148:151] offset:9216
	s_waitcnt vmcnt(12)
	ds_write_b128 v100, v[152:155] offset:13824
	s_waitcnt lgkmcnt(7)
	v_mfma_f32_16x16x32_bf16 v[50:53], v[196:199], v[228:231], v[50:53]
	v_mfma_f32_16x16x32_bf16 v[54:57], v[196:199], v[232:235], v[54:57]
	v_mfma_f32_16x16x32_bf16 v[18:21], v[196:199], v[236:239], v[18:21]
	v_mfma_f32_16x16x32_bf16 v[22:25], v[196:199], v[240:243], v[22:25]
	s_waitcnt vmcnt(11)
	ds_write_b128 v100, v[156:159] offset:36864
	s_waitcnt vmcnt(10)
	ds_write_b128 v100, v[160:163] offset:41472
	s_waitcnt lgkmcnt(8)
	v_mfma_f32_16x16x32_bf16 v[58:61], v[200:203], v[228:231], v[58:61]
	v_mfma_f32_16x16x32_bf16 v[62:65], v[200:203], v[232:235], v[62:65]
	v_mfma_f32_16x16x32_bf16 v[26:29], v[200:203], v[236:239], v[26:29]
	v_mfma_f32_16x16x32_bf16 v[30:33], v[200:203], v[240:243], v[30:33]
	s_waitcnt vmcnt(9)
	ds_write_b128 v100, v[164:167] offset:46080
	s_waitcnt vmcnt(8)
	ds_write_b128 v100, v[168:171] offset:50688
	s_waitcnt lgkmcnt(0)
	s_barrier
	s_setprio 0
	ds_read_b128 v[212:215], v245 offset:36864
	ds_read_b128 v[196:199], v244
	ds_read_b128 v[216:219], v245 offset:39168
	ds_read_b128 v[220:223], v245 offset:41472
	ds_read_b128 v[224:227], v245 offset:43776
	ds_read_b128 v[200:203], v244 offset:2304
	v_mfma_f32_16x16x32_bf16 v[34:37], v[204:207], v[228:231], v[34:37]
	v_mfma_f32_16x16x32_bf16 v[38:41], v[204:207], v[232:235], v[38:41]
	v_mfma_f32_16x16x32_bf16 v[2:5], v[204:207], v[236:239], v[2:5]
	v_mfma_f32_16x16x32_bf16 v[6:9], v[204:207], v[240:243], v[6:9]
	ds_read_b128 v[204:207], v244 offset:4608
	v_mfma_f32_16x16x32_bf16 v[42:45], v[208:211], v[228:231], v[42:45]
	v_mfma_f32_16x16x32_bf16 v[46:49], v[208:211], v[232:235], v[46:49]
	v_mfma_f32_16x16x32_bf16 v[10:13], v[208:211], v[236:239], v[10:13]
	v_mfma_f32_16x16x32_bf16 v[14:17], v[208:211], v[240:243], v[14:17]
	ds_read_b128 v[208:211], v244 offset:6912
	global_load_dwordx4 v[140:143], v[66:67], off offset:512
	global_load_dwordx4 v[144:147], v[68:69], off offset:512
	global_load_dwordx4 v[148:151], v[70:71], off offset:512
	global_load_dwordx4 v[152:155], v[72:73], off offset:512
	global_load_dwordx4 v[156:159], v[84:85], off offset:512
	global_load_dwordx4 v[160:163], v[86:87], off offset:512
	global_load_dwordx4 v[164:167], v[88:89], off offset:512
	global_load_dwordx4 v[168:171], v[90:91], off offset:512
	s_waitcnt lgkmcnt(6)
	v_mfma_f32_16x16x32_bf16 v[50:53], v[196:199], v[212:215], v[50:53]
	ds_read_b128 v[228:231], v245 offset:36928
	s_waitcnt lgkmcnt(6)
	v_mfma_f32_16x16x32_bf16 v[54:57], v[196:199], v[216:219], v[54:57]
	ds_read_b128 v[232:235], v245 offset:39232
	s_waitcnt lgkmcnt(6)
	v_mfma_f32_16x16x32_bf16 v[18:21], v[196:199], v[220:223], v[18:21]
	ds_read_b128 v[236:239], v245 offset:41536
	s_waitcnt lgkmcnt(6)
	v_mfma_f32_16x16x32_bf16 v[22:25], v[196:199], v[224:227], v[22:25]
	ds_read_b128 v[240:243], v245 offset:43840
	ds_read_b128 v[196:199], v244 offset:64
	s_waitcnt lgkmcnt(7)
	v_mfma_f32_16x16x32_bf16 v[58:61], v[200:203], v[212:215], v[58:61]
	v_mfma_f32_16x16x32_bf16 v[62:65], v[200:203], v[216:219], v[62:65]
	v_mfma_f32_16x16x32_bf16 v[26:29], v[200:203], v[220:223], v[26:29]
	v_mfma_f32_16x16x32_bf16 v[30:33], v[200:203], v[224:227], v[30:33]
	ds_read_b128 v[200:203], v244 offset:2368
	s_waitcnt lgkmcnt(7)
	v_mfma_f32_16x16x32_bf16 v[34:37], v[204:207], v[212:215], v[34:37]
	v_mfma_f32_16x16x32_bf16 v[38:41], v[204:207], v[216:219], v[38:41]
	v_mfma_f32_16x16x32_bf16 v[2:5], v[204:207], v[220:223], v[2:5]
	v_mfma_f32_16x16x32_bf16 v[6:9], v[204:207], v[224:227], v[6:9]
	ds_read_b128 v[204:207], v244 offset:4672
	s_setprio 1
	s_waitcnt vmcnt(15)
	ds_write_b128 v100, v[102:105] offset:18432
	s_waitcnt vmcnt(14)
	ds_write_b128 v100, v[106:109] offset:23040
	s_waitcnt lgkmcnt(9)
	v_mfma_f32_16x16x32_bf16 v[42:45], v[208:211], v[212:215], v[42:45]
	v_mfma_f32_16x16x32_bf16 v[46:49], v[208:211], v[216:219], v[46:49]
	v_mfma_f32_16x16x32_bf16 v[10:13], v[208:211], v[220:223], v[10:13]
	v_mfma_f32_16x16x32_bf16 v[14:17], v[208:211], v[224:227], v[14:17]
	ds_read_b128 v[208:211], v244 offset:6976
	s_waitcnt vmcnt(13)
	ds_write_b128 v100, v[110:113] offset:27648
	s_waitcnt vmcnt(12)
	ds_write_b128 v100, v[114:117] offset:32256
	s_waitcnt lgkmcnt(7)
	v_mfma_f32_16x16x32_bf16 v[50:53], v[196:199], v[228:231], v[50:53]
	v_mfma_f32_16x16x32_bf16 v[54:57], v[196:199], v[232:235], v[54:57]
	v_mfma_f32_16x16x32_bf16 v[18:21], v[196:199], v[236:239], v[18:21]
	v_mfma_f32_16x16x32_bf16 v[22:25], v[196:199], v[240:243], v[22:25]
	s_waitcnt vmcnt(11)
	ds_write_b128 v100, v[118:121] offset:55296
	s_waitcnt vmcnt(10)
	ds_write_b128 v100, v[122:125] offset:59904
	s_waitcnt lgkmcnt(8)
	v_mfma_f32_16x16x32_bf16 v[58:61], v[200:203], v[228:231], v[58:61]
	v_mfma_f32_16x16x32_bf16 v[62:65], v[200:203], v[232:235], v[62:65]
	v_mfma_f32_16x16x32_bf16 v[26:29], v[200:203], v[236:239], v[26:29]
	v_mfma_f32_16x16x32_bf16 v[30:33], v[200:203], v[240:243], v[30:33]
	s_waitcnt vmcnt(9)
	ds_write_b128 v100, v[126:129] offset:64512
	s_waitcnt vmcnt(8)
	ds_write_b128 v101, v[136:139] offset:32256
	s_waitcnt lgkmcnt(0)
	s_barrier
	s_setprio 0
	ds_read_b128 v[212:215], v245 offset:55296
	ds_read_b128 v[196:199], v244 offset:18432
	ds_read_b128 v[216:219], v245 offset:57600
	ds_read_b128 v[220:223], v245 offset:59904
	ds_read_b128 v[224:227], v245 offset:62208
	ds_read_b128 v[200:203], v244 offset:20736
	v_mfma_f32_16x16x32_bf16 v[34:37], v[204:207], v[228:231], v[34:37]
	v_mfma_f32_16x16x32_bf16 v[38:41], v[204:207], v[232:235], v[38:41]
	v_mfma_f32_16x16x32_bf16 v[2:5], v[204:207], v[236:239], v[2:5]
	v_mfma_f32_16x16x32_bf16 v[6:9], v[204:207], v[240:243], v[6:9]
	ds_read_b128 v[204:207], v244 offset:23040
	v_mfma_f32_16x16x32_bf16 v[42:45], v[208:211], v[228:231], v[42:45]
	v_mfma_f32_16x16x32_bf16 v[46:49], v[208:211], v[232:235], v[46:49]
	v_mfma_f32_16x16x32_bf16 v[10:13], v[208:211], v[236:239], v[10:13]
	v_mfma_f32_16x16x32_bf16 v[14:17], v[208:211], v[240:243], v[14:17]
	ds_read_b128 v[208:211], v244 offset:25344
	global_load_dwordx4 v[102:105], v[66:67], off offset:640
	global_load_dwordx4 v[106:109], v[68:69], off offset:640
	global_load_dwordx4 v[110:113], v[70:71], off offset:640
	global_load_dwordx4 v[114:117], v[72:73], off offset:640
	global_load_dwordx4 v[118:121], v[84:85], off offset:640
	global_load_dwordx4 v[122:125], v[86:87], off offset:640
	global_load_dwordx4 v[126:129], v[88:89], off offset:640
	global_load_dwordx4 v[136:139], v[90:91], off offset:640
	s_waitcnt lgkmcnt(6)
	v_mfma_f32_16x16x32_bf16 v[50:53], v[196:199], v[212:215], v[50:53]
	ds_read_b128 v[228:231], v245 offset:55360
	s_waitcnt lgkmcnt(6)
	v_mfma_f32_16x16x32_bf16 v[54:57], v[196:199], v[216:219], v[54:57]
	ds_read_b128 v[232:235], v245 offset:57664
	s_waitcnt lgkmcnt(6)
	v_mfma_f32_16x16x32_bf16 v[18:21], v[196:199], v[220:223], v[18:21]
	ds_read_b128 v[236:239], v245 offset:59968
	s_waitcnt lgkmcnt(6)
	v_mfma_f32_16x16x32_bf16 v[22:25], v[196:199], v[224:227], v[22:25]
	ds_read_b128 v[240:243], v245 offset:62272
	ds_read_b128 v[196:199], v244 offset:18496
	s_waitcnt lgkmcnt(7)
	v_mfma_f32_16x16x32_bf16 v[58:61], v[200:203], v[212:215], v[58:61]
	v_mfma_f32_16x16x32_bf16 v[62:65], v[200:203], v[216:219], v[62:65]
	v_mfma_f32_16x16x32_bf16 v[26:29], v[200:203], v[220:223], v[26:29]
	v_mfma_f32_16x16x32_bf16 v[30:33], v[200:203], v[224:227], v[30:33]
	ds_read_b128 v[200:203], v244 offset:20800
	s_waitcnt lgkmcnt(7)
	v_mfma_f32_16x16x32_bf16 v[34:37], v[204:207], v[212:215], v[34:37]
	v_mfma_f32_16x16x32_bf16 v[38:41], v[204:207], v[216:219], v[38:41]
	v_mfma_f32_16x16x32_bf16 v[2:5], v[204:207], v[220:223], v[2:5]
	v_mfma_f32_16x16x32_bf16 v[6:9], v[204:207], v[224:227], v[6:9]
	ds_read_b128 v[204:207], v244 offset:23104
	s_setprio 1
	s_waitcnt vmcnt(15)
	ds_write_b128 v100, v[140:143]
	s_waitcnt vmcnt(14)
	ds_write_b128 v100, v[144:147] offset:4608
	s_waitcnt lgkmcnt(9)
	v_mfma_f32_16x16x32_bf16 v[42:45], v[208:211], v[212:215], v[42:45]
	v_mfma_f32_16x16x32_bf16 v[46:49], v[208:211], v[216:219], v[46:49]
	v_mfma_f32_16x16x32_bf16 v[10:13], v[208:211], v[220:223], v[10:13]
	v_mfma_f32_16x16x32_bf16 v[14:17], v[208:211], v[224:227], v[14:17]
	ds_read_b128 v[208:211], v244 offset:25408
	s_waitcnt vmcnt(13)
	ds_write_b128 v100, v[148:151] offset:9216
	s_waitcnt vmcnt(12)
	ds_write_b128 v100, v[152:155] offset:13824
	s_waitcnt lgkmcnt(7)
	v_mfma_f32_16x16x32_bf16 v[50:53], v[196:199], v[228:231], v[50:53]
	v_mfma_f32_16x16x32_bf16 v[54:57], v[196:199], v[232:235], v[54:57]
	v_mfma_f32_16x16x32_bf16 v[18:21], v[196:199], v[236:239], v[18:21]
	v_mfma_f32_16x16x32_bf16 v[22:25], v[196:199], v[240:243], v[22:25]
	s_waitcnt vmcnt(11)
	ds_write_b128 v100, v[156:159] offset:36864
	s_waitcnt vmcnt(10)
	ds_write_b128 v100, v[160:163] offset:41472
	s_waitcnt lgkmcnt(8)
	v_mfma_f32_16x16x32_bf16 v[58:61], v[200:203], v[228:231], v[58:61]
	v_mfma_f32_16x16x32_bf16 v[62:65], v[200:203], v[232:235], v[62:65]
	v_mfma_f32_16x16x32_bf16 v[26:29], v[200:203], v[236:239], v[26:29]
	v_mfma_f32_16x16x32_bf16 v[30:33], v[200:203], v[240:243], v[30:33]
	s_waitcnt vmcnt(9)
	ds_write_b128 v100, v[164:167] offset:46080
	s_waitcnt vmcnt(8)
	ds_write_b128 v100, v[168:171] offset:50688
	s_waitcnt lgkmcnt(0)
	s_barrier
	s_setprio 0
	ds_read_b128 v[212:215], v245 offset:36864
	ds_read_b128 v[196:199], v244
	ds_read_b128 v[216:219], v245 offset:39168
	ds_read_b128 v[220:223], v245 offset:41472
	ds_read_b128 v[224:227], v245 offset:43776
	ds_read_b128 v[200:203], v244 offset:2304
	v_mfma_f32_16x16x32_bf16 v[34:37], v[204:207], v[228:231], v[34:37]
	v_mfma_f32_16x16x32_bf16 v[38:41], v[204:207], v[232:235], v[38:41]
	v_mfma_f32_16x16x32_bf16 v[2:5], v[204:207], v[236:239], v[2:5]
	v_mfma_f32_16x16x32_bf16 v[6:9], v[204:207], v[240:243], v[6:9]
	ds_read_b128 v[204:207], v244 offset:4608
	v_mfma_f32_16x16x32_bf16 v[42:45], v[208:211], v[228:231], v[42:45]
	v_mfma_f32_16x16x32_bf16 v[46:49], v[208:211], v[232:235], v[46:49]
	v_mfma_f32_16x16x32_bf16 v[10:13], v[208:211], v[236:239], v[10:13]
	v_mfma_f32_16x16x32_bf16 v[14:17], v[208:211], v[240:243], v[14:17]
	ds_read_b128 v[208:211], v244 offset:6912
	global_load_dwordx4 v[140:143], v[66:67], off offset:768
	global_load_dwordx4 v[144:147], v[68:69], off offset:768
	global_load_dwordx4 v[148:151], v[70:71], off offset:768
	global_load_dwordx4 v[152:155], v[72:73], off offset:768
	global_load_dwordx4 v[156:159], v[84:85], off offset:768
	global_load_dwordx4 v[160:163], v[86:87], off offset:768
	global_load_dwordx4 v[164:167], v[88:89], off offset:768
	global_load_dwordx4 v[168:171], v[90:91], off offset:768
	s_waitcnt lgkmcnt(6)
	v_mfma_f32_16x16x32_bf16 v[50:53], v[196:199], v[212:215], v[50:53]
	ds_read_b128 v[228:231], v245 offset:36928
	s_waitcnt lgkmcnt(6)
	v_mfma_f32_16x16x32_bf16 v[54:57], v[196:199], v[216:219], v[54:57]
	ds_read_b128 v[232:235], v245 offset:39232
	s_waitcnt lgkmcnt(6)
	v_mfma_f32_16x16x32_bf16 v[18:21], v[196:199], v[220:223], v[18:21]
	ds_read_b128 v[236:239], v245 offset:41536
	s_waitcnt lgkmcnt(6)
	v_mfma_f32_16x16x32_bf16 v[22:25], v[196:199], v[224:227], v[22:25]
	ds_read_b128 v[240:243], v245 offset:43840
	ds_read_b128 v[196:199], v244 offset:64
	s_waitcnt lgkmcnt(7)
	v_mfma_f32_16x16x32_bf16 v[58:61], v[200:203], v[212:215], v[58:61]
	v_mfma_f32_16x16x32_bf16 v[62:65], v[200:203], v[216:219], v[62:65]
	v_mfma_f32_16x16x32_bf16 v[26:29], v[200:203], v[220:223], v[26:29]
	v_mfma_f32_16x16x32_bf16 v[30:33], v[200:203], v[224:227], v[30:33]
	ds_read_b128 v[200:203], v244 offset:2368
	s_waitcnt lgkmcnt(7)
	v_mfma_f32_16x16x32_bf16 v[34:37], v[204:207], v[212:215], v[34:37]
	v_mfma_f32_16x16x32_bf16 v[38:41], v[204:207], v[216:219], v[38:41]
	v_mfma_f32_16x16x32_bf16 v[2:5], v[204:207], v[220:223], v[2:5]
	v_mfma_f32_16x16x32_bf16 v[6:9], v[204:207], v[224:227], v[6:9]
	ds_read_b128 v[204:207], v244 offset:4672
	s_setprio 1
	s_waitcnt vmcnt(15)
	ds_write_b128 v100, v[102:105] offset:18432
	s_waitcnt vmcnt(14)
	ds_write_b128 v100, v[106:109] offset:23040
	s_waitcnt lgkmcnt(9)
	v_mfma_f32_16x16x32_bf16 v[42:45], v[208:211], v[212:215], v[42:45]
	v_mfma_f32_16x16x32_bf16 v[46:49], v[208:211], v[216:219], v[46:49]
	v_mfma_f32_16x16x32_bf16 v[10:13], v[208:211], v[220:223], v[10:13]
	v_mfma_f32_16x16x32_bf16 v[14:17], v[208:211], v[224:227], v[14:17]
	ds_read_b128 v[208:211], v244 offset:6976
	s_waitcnt vmcnt(13)
	ds_write_b128 v100, v[110:113] offset:27648
	s_waitcnt vmcnt(12)
	ds_write_b128 v100, v[114:117] offset:32256
	s_waitcnt lgkmcnt(7)
	v_mfma_f32_16x16x32_bf16 v[50:53], v[196:199], v[228:231], v[50:53]
	v_mfma_f32_16x16x32_bf16 v[54:57], v[196:199], v[232:235], v[54:57]
	v_mfma_f32_16x16x32_bf16 v[18:21], v[196:199], v[236:239], v[18:21]
	v_mfma_f32_16x16x32_bf16 v[22:25], v[196:199], v[240:243], v[22:25]
	s_waitcnt vmcnt(11)
	ds_write_b128 v100, v[118:121] offset:55296
	s_waitcnt vmcnt(10)
	ds_write_b128 v100, v[122:125] offset:59904
	s_waitcnt lgkmcnt(8)
	v_mfma_f32_16x16x32_bf16 v[58:61], v[200:203], v[228:231], v[58:61]
	v_mfma_f32_16x16x32_bf16 v[62:65], v[200:203], v[232:235], v[62:65]
	v_mfma_f32_16x16x32_bf16 v[26:29], v[200:203], v[236:239], v[26:29]
	v_mfma_f32_16x16x32_bf16 v[30:33], v[200:203], v[240:243], v[30:33]
	s_waitcnt vmcnt(9)
	ds_write_b128 v100, v[126:129] offset:64512
	s_waitcnt vmcnt(8)
	ds_write_b128 v101, v[136:139] offset:32256
	s_waitcnt lgkmcnt(0)
	s_barrier
	s_setprio 0
	ds_read_b128 v[212:215], v245 offset:55296
	ds_read_b128 v[196:199], v244 offset:18432
	ds_read_b128 v[216:219], v245 offset:57600
	ds_read_b128 v[220:223], v245 offset:59904
	ds_read_b128 v[224:227], v245 offset:62208
	ds_read_b128 v[200:203], v244 offset:20736
	v_mfma_f32_16x16x32_bf16 v[34:37], v[204:207], v[228:231], v[34:37]
	v_mfma_f32_16x16x32_bf16 v[38:41], v[204:207], v[232:235], v[38:41]
	v_mfma_f32_16x16x32_bf16 v[2:5], v[204:207], v[236:239], v[2:5]
	v_mfma_f32_16x16x32_bf16 v[6:9], v[204:207], v[240:243], v[6:9]
	ds_read_b128 v[204:207], v244 offset:23040
	v_mfma_f32_16x16x32_bf16 v[42:45], v[208:211], v[228:231], v[42:45]
	v_mfma_f32_16x16x32_bf16 v[46:49], v[208:211], v[232:235], v[46:49]
	v_mfma_f32_16x16x32_bf16 v[10:13], v[208:211], v[236:239], v[10:13]
	v_mfma_f32_16x16x32_bf16 v[14:17], v[208:211], v[240:243], v[14:17]
	ds_read_b128 v[208:211], v244 offset:25344
	global_load_dwordx4 v[102:105], v[66:67], off offset:896
	s_nop 0
	global_load_dwordx4 v[66:69], v[68:69], off offset:896
	s_nop 0
	global_load_dwordx4 v[106:109], v[70:71], off offset:896
	s_nop 0
	global_load_dwordx4 v[70:73], v[72:73], off offset:896
	s_nop 0
	global_load_dwordx4 v[110:113], v[84:85], off offset:896
	s_nop 0
	global_load_dwordx4 v[84:87], v[86:87], off offset:896
	s_nop 0
	global_load_dwordx4 v[114:117], v[88:89], off offset:896
	s_nop 0
	global_load_dwordx4 v[88:91], v[90:91], off offset:896
	s_waitcnt lgkmcnt(6)
	v_mfma_f32_16x16x32_bf16 v[50:53], v[196:199], v[212:215], v[50:53]
	ds_read_b128 v[228:231], v245 offset:55360
	s_waitcnt lgkmcnt(6)
	v_mfma_f32_16x16x32_bf16 v[54:57], v[196:199], v[216:219], v[54:57]
	ds_read_b128 v[232:235], v245 offset:57664
	s_waitcnt lgkmcnt(6)
	v_mfma_f32_16x16x32_bf16 v[18:21], v[196:199], v[220:223], v[18:21]
	ds_read_b128 v[236:239], v245 offset:59968
	s_waitcnt lgkmcnt(6)
	v_mfma_f32_16x16x32_bf16 v[22:25], v[196:199], v[224:227], v[22:25]
	ds_read_b128 v[240:243], v245 offset:62272
	ds_read_b128 v[196:199], v244 offset:18496
	s_waitcnt lgkmcnt(7)
	v_mfma_f32_16x16x32_bf16 v[58:61], v[200:203], v[212:215], v[58:61]
	v_mfma_f32_16x16x32_bf16 v[62:65], v[200:203], v[216:219], v[62:65]
	v_mfma_f32_16x16x32_bf16 v[26:29], v[200:203], v[220:223], v[26:29]
	v_mfma_f32_16x16x32_bf16 v[30:33], v[200:203], v[224:227], v[30:33]
	ds_read_b128 v[200:203], v244 offset:20800
	s_waitcnt lgkmcnt(7)
	v_mfma_f32_16x16x32_bf16 v[34:37], v[204:207], v[212:215], v[34:37]
	v_mfma_f32_16x16x32_bf16 v[38:41], v[204:207], v[216:219], v[38:41]
	v_mfma_f32_16x16x32_bf16 v[2:5], v[204:207], v[220:223], v[2:5]
	v_mfma_f32_16x16x32_bf16 v[6:9], v[204:207], v[224:227], v[6:9]
	ds_read_b128 v[204:207], v244 offset:23104
	s_setprio 1
	s_waitcnt vmcnt(15)
	ds_write_b128 v100, v[140:143]
	s_waitcnt vmcnt(14)
	ds_write_b128 v100, v[144:147] offset:4608
	s_waitcnt lgkmcnt(9)
	v_mfma_f32_16x16x32_bf16 v[42:45], v[208:211], v[212:215], v[42:45]
	v_mfma_f32_16x16x32_bf16 v[46:49], v[208:211], v[216:219], v[46:49]
	v_mfma_f32_16x16x32_bf16 v[10:13], v[208:211], v[220:223], v[10:13]
	v_mfma_f32_16x16x32_bf16 v[14:17], v[208:211], v[224:227], v[14:17]
	ds_read_b128 v[208:211], v244 offset:25408
	s_waitcnt vmcnt(13)
	ds_write_b128 v100, v[148:151] offset:9216
	s_waitcnt vmcnt(12)
	ds_write_b128 v100, v[152:155] offset:13824
	s_waitcnt lgkmcnt(7)
	v_mfma_f32_16x16x32_bf16 v[50:53], v[196:199], v[228:231], v[50:53]
	v_mfma_f32_16x16x32_bf16 v[54:57], v[196:199], v[232:235], v[54:57]
	v_mfma_f32_16x16x32_bf16 v[18:21], v[196:199], v[236:239], v[18:21]
	v_mfma_f32_16x16x32_bf16 v[22:25], v[196:199], v[240:243], v[22:25]
	s_waitcnt vmcnt(11)
	ds_write_b128 v100, v[156:159] offset:36864
	s_waitcnt vmcnt(10)
	ds_write_b128 v100, v[160:163] offset:41472
	s_waitcnt lgkmcnt(8)
	v_mfma_f32_16x16x32_bf16 v[58:61], v[200:203], v[228:231], v[58:61]
	v_mfma_f32_16x16x32_bf16 v[62:65], v[200:203], v[232:235], v[62:65]
	v_mfma_f32_16x16x32_bf16 v[26:29], v[200:203], v[236:239], v[26:29]
	v_mfma_f32_16x16x32_bf16 v[30:33], v[200:203], v[240:243], v[30:33]
	s_waitcnt vmcnt(9)
	ds_write_b128 v100, v[164:167] offset:46080
	s_waitcnt vmcnt(8)
	ds_write_b128 v100, v[168:171] offset:50688
	s_waitcnt lgkmcnt(0)
	s_barrier
	s_setprio 0
	ds_read_b128 v[212:215], v245 offset:36864
	ds_read_b128 v[196:199], v244
	ds_read_b128 v[216:219], v245 offset:39168
	ds_read_b128 v[220:223], v245 offset:41472
	ds_read_b128 v[224:227], v245 offset:43776
	ds_read_b128 v[200:203], v244 offset:2304
	v_mfma_f32_16x16x32_bf16 v[34:37], v[204:207], v[228:231], v[34:37]
	v_mfma_f32_16x16x32_bf16 v[38:41], v[204:207], v[232:235], v[38:41]
	v_mfma_f32_16x16x32_bf16 v[2:5], v[204:207], v[236:239], v[2:5]
	v_mfma_f32_16x16x32_bf16 v[6:9], v[204:207], v[240:243], v[6:9]
	ds_read_b128 v[204:207], v244 offset:4608
	v_mfma_f32_16x16x32_bf16 v[42:45], v[208:211], v[228:231], v[42:45]
	v_mfma_f32_16x16x32_bf16 v[46:49], v[208:211], v[232:235], v[46:49]
	v_mfma_f32_16x16x32_bf16 v[10:13], v[208:211], v[236:239], v[10:13]
	v_mfma_f32_16x16x32_bf16 v[14:17], v[208:211], v[240:243], v[14:17]
	ds_read_b128 v[208:211], v244 offset:6912
	s_waitcnt lgkmcnt(6)
	v_mfma_f32_16x16x32_bf16 v[50:53], v[196:199], v[212:215], v[50:53]
	ds_read_b128 v[228:231], v245 offset:36928
	s_waitcnt lgkmcnt(6)
	v_mfma_f32_16x16x32_bf16 v[54:57], v[196:199], v[216:219], v[54:57]
	ds_read_b128 v[232:235], v245 offset:39232
	s_waitcnt lgkmcnt(6)
	v_mfma_f32_16x16x32_bf16 v[18:21], v[196:199], v[220:223], v[18:21]
	ds_read_b128 v[236:239], v245 offset:41536
	s_waitcnt lgkmcnt(6)
	v_mfma_f32_16x16x32_bf16 v[22:25], v[196:199], v[224:227], v[22:25]
	ds_read_b128 v[240:243], v245 offset:43840
	ds_read_b128 v[196:199], v244 offset:64
	s_waitcnt lgkmcnt(7)
	v_mfma_f32_16x16x32_bf16 v[58:61], v[200:203], v[212:215], v[58:61]
	v_mfma_f32_16x16x32_bf16 v[62:65], v[200:203], v[216:219], v[62:65]
	v_mfma_f32_16x16x32_bf16 v[26:29], v[200:203], v[220:223], v[26:29]
	v_mfma_f32_16x16x32_bf16 v[30:33], v[200:203], v[224:227], v[30:33]
	ds_read_b128 v[200:203], v244 offset:2368
	s_waitcnt lgkmcnt(7)
	v_mfma_f32_16x16x32_bf16 v[34:37], v[204:207], v[212:215], v[34:37]
	v_mfma_f32_16x16x32_bf16 v[38:41], v[204:207], v[216:219], v[38:41]
	v_mfma_f32_16x16x32_bf16 v[2:5], v[204:207], v[220:223], v[2:5]
	v_mfma_f32_16x16x32_bf16 v[6:9], v[204:207], v[224:227], v[6:9]
	ds_read_b128 v[204:207], v244 offset:4672
	s_setprio 1
	s_waitcnt vmcnt(7)
	ds_write_b128 v100, v[102:105] offset:18432
	s_waitcnt vmcnt(6)
	ds_write_b128 v100, v[66:69] offset:23040
	s_waitcnt lgkmcnt(9)
	v_mfma_f32_16x16x32_bf16 v[42:45], v[208:211], v[212:215], v[42:45]
	v_mfma_f32_16x16x32_bf16 v[46:49], v[208:211], v[216:219], v[46:49]
	v_mfma_f32_16x16x32_bf16 v[10:13], v[208:211], v[220:223], v[10:13]
	v_mfma_f32_16x16x32_bf16 v[14:17], v[208:211], v[224:227], v[14:17]
	ds_read_b128 v[208:211], v244 offset:6976
	s_waitcnt vmcnt(5)
	ds_write_b128 v100, v[106:109] offset:27648
	s_waitcnt vmcnt(4)
	ds_write_b128 v100, v[70:73] offset:32256
	s_waitcnt lgkmcnt(7)
	v_mfma_f32_16x16x32_bf16 v[50:53], v[196:199], v[228:231], v[50:53]
	v_mfma_f32_16x16x32_bf16 v[54:57], v[196:199], v[232:235], v[54:57]
	v_mfma_f32_16x16x32_bf16 v[18:21], v[196:199], v[236:239], v[18:21]
	v_mfma_f32_16x16x32_bf16 v[22:25], v[196:199], v[240:243], v[22:25]
	s_waitcnt vmcnt(3)
	ds_write_b128 v100, v[110:113] offset:55296
	s_waitcnt vmcnt(2)
	ds_write_b128 v100, v[84:87] offset:59904
	s_waitcnt lgkmcnt(8)
	v_mfma_f32_16x16x32_bf16 v[58:61], v[200:203], v[228:231], v[58:61]
	v_mfma_f32_16x16x32_bf16 v[62:65], v[200:203], v[232:235], v[62:65]
	v_mfma_f32_16x16x32_bf16 v[26:29], v[200:203], v[236:239], v[26:29]
	v_mfma_f32_16x16x32_bf16 v[30:33], v[200:203], v[240:243], v[30:33]
	s_waitcnt vmcnt(1)
	ds_write_b128 v100, v[114:117] offset:64512
	s_waitcnt vmcnt(0)
	ds_write_b128 v101, v[88:91] offset:32256
	s_waitcnt lgkmcnt(0)
	s_barrier
	s_setprio 0
	ds_read_b128 v[212:215], v245 offset:55296
	ds_read_b128 v[196:199], v244 offset:18432
	ds_read_b128 v[216:219], v245 offset:57600
	ds_read_b128 v[220:223], v245 offset:59904
	ds_read_b128 v[224:227], v245 offset:62208
	ds_read_b128 v[200:203], v244 offset:20736
	v_mfma_f32_16x16x32_bf16 v[34:37], v[204:207], v[228:231], v[34:37]
	v_mfma_f32_16x16x32_bf16 v[38:41], v[204:207], v[232:235], v[38:41]
	v_mfma_f32_16x16x32_bf16 v[2:5], v[204:207], v[236:239], v[2:5]
	v_mfma_f32_16x16x32_bf16 v[6:9], v[204:207], v[240:243], v[6:9]
	ds_read_b128 v[204:207], v244 offset:23040
	v_mfma_f32_16x16x32_bf16 v[42:45], v[208:211], v[228:231], v[42:45]
	v_mfma_f32_16x16x32_bf16 v[46:49], v[208:211], v[232:235], v[46:49]
	v_mfma_f32_16x16x32_bf16 v[10:13], v[208:211], v[236:239], v[10:13]
	v_mfma_f32_16x16x32_bf16 v[14:17], v[208:211], v[240:243], v[14:17]
	ds_read_b128 v[208:211], v244 offset:25344
	s_waitcnt lgkmcnt(6)
	v_mfma_f32_16x16x32_bf16 v[50:53], v[196:199], v[212:215], v[50:53]
	ds_read_b128 v[228:231], v245 offset:55360
	s_waitcnt lgkmcnt(6)
	v_mfma_f32_16x16x32_bf16 v[54:57], v[196:199], v[216:219], v[54:57]
	ds_read_b128 v[232:235], v245 offset:57664
	s_waitcnt lgkmcnt(6)
	v_mfma_f32_16x16x32_bf16 v[18:21], v[196:199], v[220:223], v[18:21]
	ds_read_b128 v[236:239], v245 offset:59968
	s_waitcnt lgkmcnt(6)
	v_mfma_f32_16x16x32_bf16 v[22:25], v[196:199], v[224:227], v[22:25]
	ds_read_b128 v[240:243], v245 offset:62272
	ds_read_b128 v[196:199], v244 offset:18496
	s_waitcnt lgkmcnt(7)
	v_mfma_f32_16x16x32_bf16 v[58:61], v[200:203], v[212:215], v[58:61]
	v_mfma_f32_16x16x32_bf16 v[62:65], v[200:203], v[216:219], v[62:65]
	v_mfma_f32_16x16x32_bf16 v[26:29], v[200:203], v[220:223], v[26:29]
	v_mfma_f32_16x16x32_bf16 v[30:33], v[200:203], v[224:227], v[30:33]
	ds_read_b128 v[200:203], v244 offset:20800
	s_waitcnt lgkmcnt(7)
	v_mfma_f32_16x16x32_bf16 v[34:37], v[204:207], v[212:215], v[34:37]
	v_mfma_f32_16x16x32_bf16 v[38:41], v[204:207], v[216:219], v[38:41]
	v_mfma_f32_16x16x32_bf16 v[2:5], v[204:207], v[220:223], v[2:5]
	v_mfma_f32_16x16x32_bf16 v[6:9], v[204:207], v[224:227], v[6:9]
	ds_read_b128 v[204:207], v244 offset:23104
	s_waitcnt lgkmcnt(7)
	v_mfma_f32_16x16x32_bf16 v[42:45], v[208:211], v[212:215], v[42:45]
	v_mfma_f32_16x16x32_bf16 v[46:49], v[208:211], v[216:219], v[46:49]
	v_mfma_f32_16x16x32_bf16 v[10:13], v[208:211], v[220:223], v[10:13]
	v_mfma_f32_16x16x32_bf16 v[14:17], v[208:211], v[224:227], v[14:17]
	ds_read_b128 v[208:211], v244 offset:25408
	s_waitcnt lgkmcnt(3)
	v_mfma_f32_16x16x32_bf16 v[50:53], v[196:199], v[228:231], v[50:53]
	v_mfma_f32_16x16x32_bf16 v[54:57], v[196:199], v[232:235], v[54:57]
	v_mfma_f32_16x16x32_bf16 v[18:21], v[196:199], v[236:239], v[18:21]
	v_mfma_f32_16x16x32_bf16 v[22:25], v[196:199], v[240:243], v[22:25]
	s_waitcnt lgkmcnt(2)
	v_mfma_f32_16x16x32_bf16 v[58:61], v[200:203], v[228:231], v[58:61]
	v_mfma_f32_16x16x32_bf16 v[62:65], v[200:203], v[232:235], v[62:65]
	v_mfma_f32_16x16x32_bf16 v[26:29], v[200:203], v[236:239], v[26:29]
	v_mfma_f32_16x16x32_bf16 v[30:33], v[200:203], v[240:243], v[30:33]
	s_add_i32 s6, s6, 1
	s_add_i32 s5, s5, s3
	v_or_b32_e32 v70, s0, v92
	s_lshl_b32 s0, s7, 1
	v_lshl_add_u64 v[110:111], v[80:81], 0, s[0:1]
	v_lshlrev_b32_e32 v74, 10, v70
	v_lshl_add_u64 v[112:113], v[110:111], 0, v[74:75]
	s_waitcnt lgkmcnt(0)
	s_barrier
	v_mfma_f32_16x16x32_bf16 v[34:37], v[204:207], v[228:231], v[34:37]
	v_mfma_f32_16x16x32_bf16 v[38:41], v[204:207], v[232:235], v[38:41]
	v_mfma_f32_16x16x32_bf16 v[2:5], v[204:207], v[236:239], v[2:5]
	v_mfma_f32_16x16x32_bf16 v[6:9], v[204:207], v[240:243], v[6:9]
	v_mfma_f32_16x16x32_bf16 v[42:45], v[208:211], v[228:231], v[42:45]
	v_mfma_f32_16x16x32_bf16 v[46:49], v[208:211], v[232:235], v[46:49]
	v_mfma_f32_16x16x32_bf16 v[10:13], v[208:211], v[236:239], v[10:13]
	v_mfma_f32_16x16x32_bf16 v[14:17], v[208:211], v[240:243], v[14:17]
	s_nop 7
	v_permlane16_swap_b32_e32 v50, v54
	v_permlane16_swap_b32_e32 v51, v55
	v_permlane16_swap_b32_e32 v52, v56
	v_permlane16_swap_b32_e32 v53, v57
	v_permlane16_swap_b32_e32 v58, v62
	v_permlane16_swap_b32_e32 v59, v63
	v_permlane16_swap_b32_e32 v60, v64
	v_permlane16_swap_b32_e32 v61, v65
	v_permlane16_swap_b32_e32 v18, v22
	v_permlane16_swap_b32_e32 v19, v23
	v_permlane16_swap_b32_e32 v20, v24
	v_permlane16_swap_b32_e32 v21, v25
	v_permlane16_swap_b32_e32 v26, v30
	v_permlane16_swap_b32_e32 v27, v31
	v_permlane16_swap_b32_e32 v28, v32
	v_permlane16_swap_b32_e32 v29, v33
	v_permlane16_swap_b32_e32 v34, v38
	v_permlane16_swap_b32_e32 v35, v39
	v_permlane16_swap_b32_e32 v36, v40
	v_permlane16_swap_b32_e32 v37, v41
	v_permlane16_swap_b32_e32 v42, v46
	v_permlane16_swap_b32_e32 v43, v47
	v_permlane16_swap_b32_e32 v44, v48
	v_permlane16_swap_b32_e32 v45, v49
	v_permlane16_swap_b32_e32 v2, v6
	v_permlane16_swap_b32_e32 v3, v7
	v_permlane16_swap_b32_e32 v4, v8
	v_permlane16_swap_b32_e32 v5, v9
	v_permlane16_swap_b32_e32 v10, v14
	v_permlane16_swap_b32_e32 v11, v15
	v_permlane16_swap_b32_e32 v12, v16
	v_permlane16_swap_b32_e32 v13, v17
	v_permlane32_swap_b32_e32 v50, v54
	v_permlane32_swap_b32_e32 v51, v55
	v_permlane32_swap_b32_e32 v52, v56
	v_permlane32_swap_b32_e32 v53, v57
	v_permlane32_swap_b32_e32 v58, v62
	v_permlane32_swap_b32_e32 v59, v63
	v_permlane32_swap_b32_e32 v60, v64
	v_permlane32_swap_b32_e32 v61, v65
	v_permlane32_swap_b32_e32 v18, v22
	v_permlane32_swap_b32_e32 v19, v23
	v_permlane32_swap_b32_e32 v20, v24
	v_permlane32_swap_b32_e32 v21, v25
	v_permlane32_swap_b32_e32 v26, v30
	v_permlane32_swap_b32_e32 v27, v31
	v_permlane32_swap_b32_e32 v28, v32
	v_permlane32_swap_b32_e32 v29, v33
	v_permlane32_swap_b32_e32 v34, v38
	v_permlane32_swap_b32_e32 v35, v39
	v_permlane32_swap_b32_e32 v36, v40
	v_permlane32_swap_b32_e32 v37, v41
	v_permlane32_swap_b32_e32 v42, v46
	v_permlane32_swap_b32_e32 v43, v47
	v_permlane32_swap_b32_e32 v44, v48
	v_permlane32_swap_b32_e32 v45, v49
	v_permlane32_swap_b32_e32 v2, v6
	v_permlane32_swap_b32_e32 v3, v7
	v_permlane32_swap_b32_e32 v4, v8
	v_permlane32_swap_b32_e32 v5, v9
	v_permlane32_swap_b32_e32 v10, v14
	v_permlane32_swap_b32_e32 v11, v15
	v_permlane32_swap_b32_e32 v12, v16
	v_permlane32_swap_b32_e32 v13, v17
	global_load_dwordx4 v[106:109], v[112:113], off
	s_mul_i32 s0, s6, s3
	s_add_i32 s0, s0, s2
	s_cmp_lt_u32 s5, 48
	global_load_dwordx4 v[88:91], v[112:113], off offset:32
	global_load_dwordx4 v[70:73], v[112:113], off offset:64
	s_waitcnt vmcnt(2)
	v_mov_b32_e32 v86, v108
	global_load_dwordx4 v[66:69], v[112:113], off offset:96
	v_permlane32_swap_b32_e32 v106, v86
	v_mov_b32_e32 v102, v109
	s_nop 1
	v_permlane32_swap_b32_e32 v107, v102
	s_waitcnt vmcnt(2)
	v_mov_b32_e32 v108, v90
	v_mov_b32_e32 v109, v91
	s_nop 0
	v_permlane32_swap_b32_e32 v88, v108
	v_permlane32_swap_b32_e32 v89, v109
	s_waitcnt vmcnt(1)
	v_mov_b32_e32 v112, v72
	v_mov_b32_e32 v113, v73
	v_lshlrev_b32_e32 v72, 16, v106
	v_and_b32_e32 v73, 0xffff0000, v106
	v_pk_mul_f32 v[72:73], v[50:51], v[72:73]
	v_lshlrev_b32_e32 v50, 16, v107
	v_and_b32_e32 v51, 0xffff0000, v107
	v_pk_mul_f32 v[84:85], v[52:53], v[50:51]
	v_lshlrev_b32_e32 v50, 16, v86
	v_and_b32_e32 v51, 0xffff0000, v86
	v_pk_mul_f32 v[86:87], v[54:55], v[50:51]
	v_lshlrev_b32_e32 v54, 16, v102
	v_and_b32_e32 v55, 0xffff0000, v102
	v_pk_mul_f32 v[102:103], v[56:57], v[54:55]
	v_cvt_pk_bf16_f32 v55, v84, v85
	v_cvt_pk_bf16_f32 v56, v86, v87
	v_cvt_pk_bf16_f32 v57, v102, v103
	v_cvt_pk_bf16_f32 v54, v72, v73
	v_add_lshl_u32 v72, s7, v97, 1
	v_mov_b32_e32 v73, v75
	v_permlane32_swap_b32_e32 v54, v56
	v_permlane32_swap_b32_e32 v55, v57
	v_lshlrev_b32_e32 v106, 16, v88
	v_and_b32_e32 v107, 0xffff0000, v88
	v_lshlrev_b32_e32 v88, 16, v89
	v_and_b32_e32 v89, 0xffff0000, v89
	v_pk_mul_f32 v[60:61], v[60:61], v[88:89]
	v_lshlrev_b32_e32 v88, 16, v108
	v_and_b32_e32 v89, 0xffff0000, v108
	v_pk_mul_f32 v[62:63], v[62:63], v[88:89]
	v_lshlrev_b32_e32 v88, 16, v109
	v_and_b32_e32 v89, 0xffff0000, v109
	v_pk_mul_f32 v[58:59], v[58:59], v[106:107]
	v_pk_mul_f32 v[64:65], v[64:65], v[88:89]
	v_cvt_pk_bf16_f32 v58, v58, v59
	v_cvt_pk_bf16_f32 v59, v60, v61
	v_cvt_pk_bf16_f32 v60, v62, v63
	v_cvt_pk_bf16_f32 v61, v64, v65
	v_permlane32_swap_b32_e32 v70, v112
	v_permlane32_swap_b32_e32 v58, v60
	v_permlane32_swap_b32_e32 v59, v61
	v_permlane32_swap_b32_e32 v71, v113
	s_waitcnt vmcnt(0)
	v_mov_b32_e32 v114, v68
	v_mov_b32_e32 v115, v69
	v_lshl_add_u64 v[68:69], v[82:83], 0, v[74:75]
	v_or_b32_e32 v74, 0x8000, v74
	v_lshl_add_u64 v[90:91], v[110:111], 0, v[74:75]
	global_load_dwordx4 v[50:53], v[90:91], off
	global_load_dwordx4 v[84:87], v[90:91], off offset:32
	global_load_dwordx4 v[102:105], v[90:91], off offset:64
	v_lshl_add_u64 v[68:69], v[68:69], 0, v[72:73]
	global_store_dwordx4 v[68:69], v[54:57], off
	global_load_dwordx4 v[54:57], v[90:91], off offset:96
	v_permlane32_swap_b32_e32 v66, v114
	global_store_dwordx4 v[68:69], v[58:61], off offset:32
	v_permlane32_swap_b32_e32 v67, v115
	s_nop 0
	v_lshlrev_b32_e32 v58, 16, v70
	v_and_b32_e32 v59, 0xffff0000, v70
	v_pk_mul_f32 v[34:35], v[34:35], v[58:59]
	v_lshlrev_b32_e32 v58, 16, v71
	v_and_b32_e32 v59, 0xffff0000, v71
	v_pk_mul_f32 v[36:37], v[36:37], v[58:59]
	v_lshlrev_b32_e32 v58, 16, v112
	v_and_b32_e32 v59, 0xffff0000, v112
	v_pk_mul_f32 v[38:39], v[38:39], v[58:59]
	v_lshlrev_b32_e32 v58, 16, v113
	v_and_b32_e32 v59, 0xffff0000, v113
	v_pk_mul_f32 v[40:41], v[40:41], v[58:59]
	v_cvt_pk_bf16_f32 v34, v34, v35
	v_cvt_pk_bf16_f32 v35, v36, v37
	v_cvt_pk_bf16_f32 v36, v38, v39
	v_cvt_pk_bf16_f32 v37, v40, v41
	s_nop 0
	v_permlane32_swap_b32_e32 v34, v36
	v_permlane32_swap_b32_e32 v35, v37
	global_store_dwordx4 v[68:69], v[34:37], off offset:64
	v_lshlrev_b32_e32 v38, 16, v114
	v_and_b32_e32 v39, 0xffff0000, v114
	v_lshlrev_b32_e32 v34, 16, v66
	v_and_b32_e32 v35, 0xffff0000, v66
	v_lshlrev_b32_e32 v36, 16, v67
	v_and_b32_e32 v37, 0xffff0000, v67
	v_lshlrev_b32_e32 v40, 16, v115
	v_and_b32_e32 v41, 0xffff0000, v115
	v_pk_mul_f32 v[34:35], v[42:43], v[34:35]
	v_pk_mul_f32 v[36:37], v[44:45], v[36:37]
	v_pk_mul_f32 v[38:39], v[46:47], v[38:39]
	v_pk_mul_f32 v[40:41], v[48:49], v[40:41]
	v_cvt_pk_bf16_f32 v34, v34, v35
	v_cvt_pk_bf16_f32 v35, v36, v37
	v_cvt_pk_bf16_f32 v36, v38, v39
	v_cvt_pk_bf16_f32 v37, v40, v41
	s_nop 0
	v_permlane32_swap_b32_e32 v34, v36
	v_permlane32_swap_b32_e32 v35, v37
	global_store_dwordx4 v[68:69], v[34:37], off offset:96
	s_waitcnt vmcnt(7)
	v_mov_b32_e32 v38, v52
	s_nop 1
	v_permlane32_swap_b32_e32 v50, v38
	v_mov_b32_e32 v39, v53
	s_nop 1
	v_permlane32_swap_b32_e32 v51, v39
	v_lshlrev_b32_e32 v36, 16, v50
	v_and_b32_e32 v37, 0xffff0000, v50
	v_pk_mul_f32 v[18:19], v[18:19], v[36:37]
	v_lshlrev_b32_e32 v36, 16, v51
	v_and_b32_e32 v37, 0xffff0000, v51
	v_pk_mul_f32 v[20:21], v[20:21], v[36:37]
	v_lshlrev_b32_e32 v36, 16, v38
	v_and_b32_e32 v37, 0xffff0000, v38
	v_pk_mul_f32 v[22:23], v[22:23], v[36:37]
	v_lshlrev_b32_e32 v36, 16, v39
	v_and_b32_e32 v37, 0xffff0000, v39
	v_pk_mul_f32 v[24:25], v[24:25], v[36:37]
	s_waitcnt vmcnt(6)
	v_mov_b32_e32 v40, v86
	v_lshl_add_u64 v[34:35], v[82:83], 0, v[74:75]
	v_cvt_pk_bf16_f32 v18, v18, v19
	v_cvt_pk_bf16_f32 v19, v20, v21
	v_cvt_pk_bf16_f32 v20, v22, v23
	v_cvt_pk_bf16_f32 v21, v24, v25
	v_permlane32_swap_b32_e32 v84, v40
	v_mov_b32_e32 v41, v87
	v_permlane32_swap_b32_e32 v18, v20
	v_permlane32_swap_b32_e32 v19, v21
	v_lshl_add_u64 v[22:23], v[34:35], 0, v[72:73]
	v_permlane32_swap_b32_e32 v85, v41
	global_store_dwordx4 v[22:23], v[18:21], off
	v_lshlrev_b32_e32 v24, 16, v40
	v_and_b32_e32 v25, 0xffff0000, v40
	v_lshlrev_b32_e32 v18, 16, v84
	v_and_b32_e32 v19, 0xffff0000, v84
	v_pk_mul_f32 v[18:19], v[26:27], v[18:19]
	v_lshlrev_b32_e32 v20, 16, v85
	v_and_b32_e32 v21, 0xffff0000, v85
	v_lshlrev_b32_e32 v26, 16, v41
	v_and_b32_e32 v27, 0xffff0000, v41
	v_pk_mul_f32 v[20:21], v[28:29], v[20:21]
	v_pk_mul_f32 v[24:25], v[30:31], v[24:25]
	v_pk_mul_f32 v[26:27], v[32:33], v[26:27]
	s_waitcnt vmcnt(6)
	v_mov_b32_e32 v42, v104
	v_cvt_pk_bf16_f32 v18, v18, v19
	v_cvt_pk_bf16_f32 v19, v20, v21
	v_cvt_pk_bf16_f32 v20, v24, v25
	v_cvt_pk_bf16_f32 v21, v26, v27
	v_permlane32_swap_b32_e32 v102, v42
	v_mov_b32_e32 v43, v105
	v_permlane32_swap_b32_e32 v18, v20
	v_permlane32_swap_b32_e32 v19, v21
	v_permlane32_swap_b32_e32 v103, v43
	global_store_dwordx4 v[22:23], v[18:21], off offset:32
	s_waitcnt vmcnt(5)
	v_mov_b32_e32 v44, v56
	v_mov_b32_e32 v45, v57
	v_lshlrev_b32_e32 v18, 16, v102
	v_and_b32_e32 v19, 0xffff0000, v102
	v_pk_mul_f32 v[2:3], v[2:3], v[18:19]
	v_lshlrev_b32_e32 v18, 16, v103
	v_and_b32_e32 v19, 0xffff0000, v103
	v_pk_mul_f32 v[4:5], v[4:5], v[18:19]
	v_lshlrev_b32_e32 v18, 16, v42
	v_and_b32_e32 v19, 0xffff0000, v42
	v_pk_mul_f32 v[6:7], v[6:7], v[18:19]
	v_lshlrev_b32_e32 v18, 16, v43
	v_and_b32_e32 v19, 0xffff0000, v43
	v_pk_mul_f32 v[8:9], v[8:9], v[18:19]
	v_cvt_pk_bf16_f32 v2, v2, v3
	v_cvt_pk_bf16_f32 v3, v4, v5
	v_cvt_pk_bf16_f32 v4, v6, v7
	v_cvt_pk_bf16_f32 v5, v8, v9
	v_permlane32_swap_b32_e32 v54, v44
	v_permlane32_swap_b32_e32 v55, v45
	v_permlane32_swap_b32_e32 v2, v4
	v_permlane32_swap_b32_e32 v3, v5
	global_store_dwordx4 v[22:23], v[2:5], off offset:64
	v_lshlrev_b32_e32 v6, 16, v44
	v_and_b32_e32 v7, 0xffff0000, v44
	v_lshlrev_b32_e32 v2, 16, v54
	v_and_b32_e32 v3, 0xffff0000, v54
	v_lshlrev_b32_e32 v4, 16, v55
	v_and_b32_e32 v5, 0xffff0000, v55
	v_lshlrev_b32_e32 v8, 16, v45
	v_and_b32_e32 v9, 0xffff0000, v45
	v_pk_mul_f32 v[2:3], v[10:11], v[2:3]
	v_pk_mul_f32 v[4:5], v[12:13], v[4:5]
	v_pk_mul_f32 v[6:7], v[14:15], v[6:7]
	v_pk_mul_f32 v[8:9], v[16:17], v[8:9]
	v_cvt_pk_bf16_f32 v2, v2, v3
	v_cvt_pk_bf16_f32 v3, v4, v5
	v_cvt_pk_bf16_f32 v4, v6, v7
	v_cvt_pk_bf16_f32 v5, v8, v9
	s_nop 0
	v_permlane32_swap_b32_e32 v2, v4
	v_permlane32_swap_b32_e32 v3, v5
	global_store_dwordx4 v[22:23], v[2:5], off offset:96
	s_cbranch_scc1 .LBB0_828

.LBB0_979:
	s_lshr_b32 s0, s2, 2
	s_and_b32 s2, s2, 3
	s_or_b32 s2, s2, s8
	s_lshl_b32 s2, s2, 7
	v_or_b32_e32 v2, s2, v89
	v_lshlrev_b32_e32 v66, 11, v2
	s_add_i32 s0, s0, s9
	v_lshl_add_u64 v[72:73], v[68:69], 0, v[66:67]
	v_add_lshl_u32 v66, s2, v90, 11
	s_lshl_b32 s3, s0, 7
	v_lshl_add_u64 v[74:75], v[68:69], 0, v[66:67]
	v_add_lshl_u32 v66, s2, v91, 11
	v_lshl_add_u64 v[76:77], v[68:69], 0, v[66:67]
	v_add_lshl_u32 v66, s2, v92, 11
	v_or_b32_e32 v2, s3, v89
	v_lshl_add_u64 v[78:79], v[68:69], 0, v[66:67]
	v_lshlrev_b32_e32 v66, 11, v2
	v_lshl_add_u64 v[80:81], v[70:71], 0, v[66:67]
	v_add_lshl_u32 v66, s3, v90, 11
	v_lshl_add_u64 v[82:83], v[70:71], 0, v[66:67]
	v_add_lshl_u32 v66, s3, v91, 11
	v_lshl_add_u64 v[84:85], v[70:71], 0, v[66:67]
	v_add_lshl_u32 v66, s3, v92, 11
	v_lshl_add_u64 v[86:87], v[70:71], 0, v[66:67]
	global_load_dwordx4 v[2:5], v[72:73], off
	global_load_dwordx4 v[6:9], v[74:75], off
	global_load_dwordx4 v[10:13], v[76:77], off
	global_load_dwordx4 v[14:17], v[78:79], off
	global_load_dwordx4 v[18:21], v[80:81], off
	global_load_dwordx4 v[22:25], v[82:83], off
	global_load_dwordx4 v[26:29], v[84:85], off
	global_load_dwordx4 v[30:33], v[86:87], off
	global_load_dwordx4 v[98:101], v[72:73], off offset:128
	global_load_dwordx4 v[102:105], v[74:75], off offset:128
	global_load_dwordx4 v[106:109], v[76:77], off offset:128
	global_load_dwordx4 v[110:113], v[78:79], off offset:128
	global_load_dwordx4 v[114:117], v[80:81], off offset:128
	global_load_dwordx4 v[118:121], v[82:83], off offset:128
	global_load_dwordx4 v[122:125], v[84:85], off offset:128
	global_load_dwordx4 v[126:129], v[86:87], off offset:128
	s_waitcnt vmcnt(15)
	ds_write_b128 v95, v[2:5]
	s_waitcnt vmcnt(14)
	ds_write_b128 v95, v[6:9] offset:4608
	s_waitcnt vmcnt(13)
	ds_write_b128 v95, v[10:13] offset:9216
	s_waitcnt vmcnt(12)
	ds_write_b128 v95, v[14:17] offset:13824
	s_waitcnt vmcnt(11)
	ds_write_b128 v95, v[18:21] offset:36864
	s_waitcnt vmcnt(10)
	ds_write_b128 v95, v[22:25] offset:41472
	s_waitcnt vmcnt(9)
	ds_write_b128 v95, v[26:29] offset:46080
	s_waitcnt vmcnt(8)
	ds_write_b128 v95, v[30:33] offset:50688
	s_waitcnt lgkmcnt(0)
	s_barrier
	global_load_dwordx4 v[136:139], v[72:73], off offset:256
	global_load_dwordx4 v[140:143], v[74:75], off offset:256
	global_load_dwordx4 v[144:147], v[76:77], off offset:256
	global_load_dwordx4 v[148:151], v[78:79], off offset:256
	global_load_dwordx4 v[152:155], v[80:81], off offset:256
	global_load_dwordx4 v[156:159], v[82:83], off offset:256
	global_load_dwordx4 v[160:163], v[84:85], off offset:256
	global_load_dwordx4 v[164:167], v[86:87], off offset:256
	v_and_b32_e32 v246, 15, v1
	v_add_u32_e32 v246, 4, v246
	v_bfe_u32 v246, v246, 3, 1
	v_bfe_u32 v249, v1, 4, 2
	v_xor_b32_e32 v246, v246, v249
	v_bfe_u32 v249, v1, 5, 1
	v_sub_u32_e32 v246, v246, v249
	v_lshlrev_b32_e32 v246, 4, v246
	v_bfe_u32 v249, v1, 4, 1
	v_mul_u32_u24_e32 v249, 0x900, v249
	v_sub_u32_e32 v246, v246, v249
	v_add_u32_e32 v244, v246, v93
	v_add_u32_e32 v245, v246, v94
	ds_read_b128 v[212:215], v245 offset:36864
	ds_read_b128 v[196:199], v244
	ds_read_b128 v[216:219], v245 offset:39168
	ds_read_b128 v[220:223], v245 offset:41472
	ds_read_b128 v[224:227], v245 offset:43776
	ds_read_b128 v[200:203], v244 offset:2304
	ds_read_b128 v[204:207], v244 offset:4608
	ds_read_b128 v[208:211], v244 offset:6912
	s_waitcnt lgkmcnt(6)
	v_mfma_f32_16x16x32_bf16 v[34:37], v[196:199], v[212:215], 0
	ds_read_b128 v[228:231], v245 offset:36928
	s_waitcnt lgkmcnt(6)
	v_mfma_f32_16x16x32_bf16 v[38:41], v[196:199], v[216:219], 0
	ds_read_b128 v[232:235], v245 offset:39232
	s_waitcnt lgkmcnt(6)
	v_mfma_f32_16x16x32_bf16 v[2:5], v[196:199], v[220:223], 0
	ds_read_b128 v[236:239], v245 offset:41536
	s_waitcnt lgkmcnt(6)
	v_mfma_f32_16x16x32_bf16 v[6:9], v[196:199], v[224:227], 0
	ds_read_b128 v[240:243], v245 offset:43840
	ds_read_b128 v[196:199], v244 offset:64
	s_waitcnt lgkmcnt(7)
	v_mfma_f32_16x16x32_bf16 v[42:45], v[200:203], v[212:215], 0
	v_mfma_f32_16x16x32_bf16 v[46:49], v[200:203], v[216:219], 0
	v_mfma_f32_16x16x32_bf16 v[10:13], v[200:203], v[220:223], 0
	v_mfma_f32_16x16x32_bf16 v[14:17], v[200:203], v[224:227], 0
	ds_read_b128 v[200:203], v244 offset:2368
	s_waitcnt lgkmcnt(7)
	v_mfma_f32_16x16x32_bf16 v[50:53], v[204:207], v[212:215], 0
	v_mfma_f32_16x16x32_bf16 v[54:57], v[204:207], v[216:219], 0
	v_mfma_f32_16x16x32_bf16 v[18:21], v[204:207], v[220:223], 0
	v_mfma_f32_16x16x32_bf16 v[22:25], v[204:207], v[224:227], 0
	ds_read_b128 v[204:207], v244 offset:4672
	s_setprio 1
	s_waitcnt vmcnt(15)
	ds_write_b128 v95, v[98:101] offset:18432
	s_waitcnt vmcnt(14)
	ds_write_b128 v95, v[102:105] offset:23040
	s_waitcnt lgkmcnt(9)
	v_mfma_f32_16x16x32_bf16 v[58:61], v[208:211], v[212:215], 0
	v_mfma_f32_16x16x32_bf16 v[62:65], v[208:211], v[216:219], 0
	v_mfma_f32_16x16x32_bf16 v[26:29], v[208:211], v[220:223], 0
	v_mfma_f32_16x16x32_bf16 v[30:33], v[208:211], v[224:227], 0
	ds_read_b128 v[208:211], v244 offset:6976
	s_waitcnt vmcnt(13)
	ds_write_b128 v95, v[106:109] offset:27648
	s_waitcnt vmcnt(12)
	ds_write_b128 v95, v[110:113] offset:32256
	s_waitcnt lgkmcnt(7)
	v_mfma_f32_16x16x32_bf16 v[34:37], v[196:199], v[228:231], v[34:37]
	v_mfma_f32_16x16x32_bf16 v[38:41], v[196:199], v[232:235], v[38:41]
	v_mfma_f32_16x16x32_bf16 v[2:5], v[196:199], v[236:239], v[2:5]
	v_mfma_f32_16x16x32_bf16 v[6:9], v[196:199], v[240:243], v[6:9]
	s_waitcnt vmcnt(11)
	ds_write_b128 v95, v[114:117] offset:55296
	s_waitcnt vmcnt(10)
	ds_write_b128 v95, v[118:121] offset:59904
	s_waitcnt lgkmcnt(8)
	v_mfma_f32_16x16x32_bf16 v[42:45], v[200:203], v[228:231], v[42:45]
	v_mfma_f32_16x16x32_bf16 v[46:49], v[200:203], v[232:235], v[46:49]
	v_mfma_f32_16x16x32_bf16 v[10:13], v[200:203], v[236:239], v[10:13]
	v_mfma_f32_16x16x32_bf16 v[14:17], v[200:203], v[240:243], v[14:17]
	s_waitcnt vmcnt(9)
	ds_write_b128 v95, v[122:125] offset:64512
	s_waitcnt vmcnt(8)
	ds_write_b128 v96, v[126:129] offset:32256
	s_waitcnt lgkmcnt(0)
	s_barrier
	s_setprio 0
	ds_read_b128 v[212:215], v245 offset:55296
	ds_read_b128 v[196:199], v244 offset:18432
	ds_read_b128 v[216:219], v245 offset:57600
	ds_read_b128 v[220:223], v245 offset:59904
	ds_read_b128 v[224:227], v245 offset:62208
	ds_read_b128 v[200:203], v244 offset:20736
	v_mfma_f32_16x16x32_bf16 v[50:53], v[204:207], v[228:231], v[50:53]
	v_mfma_f32_16x16x32_bf16 v[54:57], v[204:207], v[232:235], v[54:57]
	v_mfma_f32_16x16x32_bf16 v[18:21], v[204:207], v[236:239], v[18:21]
	v_mfma_f32_16x16x32_bf16 v[22:25], v[204:207], v[240:243], v[22:25]
	ds_read_b128 v[204:207], v244 offset:23040
	v_mfma_f32_16x16x32_bf16 v[58:61], v[208:211], v[228:231], v[58:61]
	v_mfma_f32_16x16x32_bf16 v[62:65], v[208:211], v[232:235], v[62:65]
	v_mfma_f32_16x16x32_bf16 v[26:29], v[208:211], v[236:239], v[26:29]
	v_mfma_f32_16x16x32_bf16 v[30:33], v[208:211], v[240:243], v[30:33]
	ds_read_b128 v[208:211], v244 offset:25344
	global_load_dwordx4 v[98:101], v[72:73], off offset:384
	global_load_dwordx4 v[102:105], v[74:75], off offset:384
	global_load_dwordx4 v[106:109], v[76:77], off offset:384
	global_load_dwordx4 v[110:113], v[78:79], off offset:384
	global_load_dwordx4 v[114:117], v[80:81], off offset:384
	global_load_dwordx4 v[118:121], v[82:83], off offset:384
	global_load_dwordx4 v[122:125], v[84:85], off offset:384
	global_load_dwordx4 v[126:129], v[86:87], off offset:384
	s_waitcnt lgkmcnt(6)
	v_mfma_f32_16x16x32_bf16 v[34:37], v[196:199], v[212:215], v[34:37]
	ds_read_b128 v[228:231], v245 offset:55360
	s_waitcnt lgkmcnt(6)
	v_mfma_f32_16x16x32_bf16 v[38:41], v[196:199], v[216:219], v[38:41]
	ds_read_b128 v[232:235], v245 offset:57664
	s_waitcnt lgkmcnt(6)
	v_mfma_f32_16x16x32_bf16 v[2:5], v[196:199], v[220:223], v[2:5]
	ds_read_b128 v[236:239], v245 offset:59968
	s_waitcnt lgkmcnt(6)
	v_mfma_f32_16x16x32_bf16 v[6:9], v[196:199], v[224:227], v[6:9]
	ds_read_b128 v[240:243], v245 offset:62272
	ds_read_b128 v[196:199], v244 offset:18496
	s_waitcnt lgkmcnt(7)
	v_mfma_f32_16x16x32_bf16 v[42:45], v[200:203], v[212:215], v[42:45]
	v_mfma_f32_16x16x32_bf16 v[46:49], v[200:203], v[216:219], v[46:49]
	v_mfma_f32_16x16x32_bf16 v[10:13], v[200:203], v[220:223], v[10:13]
	v_mfma_f32_16x16x32_bf16 v[14:17], v[200:203], v[224:227], v[14:17]
	ds_read_b128 v[200:203], v244 offset:20800
	s_waitcnt lgkmcnt(7)
	v_mfma_f32_16x16x32_bf16 v[50:53], v[204:207], v[212:215], v[50:53]
	v_mfma_f32_16x16x32_bf16 v[54:57], v[204:207], v[216:219], v[54:57]
	v_mfma_f32_16x16x32_bf16 v[18:21], v[204:207], v[220:223], v[18:21]
	v_mfma_f32_16x16x32_bf16 v[22:25], v[204:207], v[224:227], v[22:25]
	ds_read_b128 v[204:207], v244 offset:23104
	s_setprio 1
	s_waitcnt vmcnt(15)
	ds_write_b128 v95, v[136:139]
	s_waitcnt vmcnt(14)
	ds_write_b128 v95, v[140:143] offset:4608
	s_waitcnt lgkmcnt(9)
	v_mfma_f32_16x16x32_bf16 v[58:61], v[208:211], v[212:215], v[58:61]
	v_mfma_f32_16x16x32_bf16 v[62:65], v[208:211], v[216:219], v[62:65]
	v_mfma_f32_16x16x32_bf16 v[26:29], v[208:211], v[220:223], v[26:29]
	v_mfma_f32_16x16x32_bf16 v[30:33], v[208:211], v[224:227], v[30:33]
	ds_read_b128 v[208:211], v244 offset:25408
	s_waitcnt vmcnt(13)
	ds_write_b128 v95, v[144:147] offset:9216
	s_waitcnt vmcnt(12)
	ds_write_b128 v95, v[148:151] offset:13824
	s_waitcnt lgkmcnt(7)
	v_mfma_f32_16x16x32_bf16 v[34:37], v[196:199], v[228:231], v[34:37]
	v_mfma_f32_16x16x32_bf16 v[38:41], v[196:199], v[232:235], v[38:41]
	v_mfma_f32_16x16x32_bf16 v[2:5], v[196:199], v[236:239], v[2:5]
	v_mfma_f32_16x16x32_bf16 v[6:9], v[196:199], v[240:243], v[6:9]
	s_waitcnt vmcnt(11)
	ds_write_b128 v95, v[152:155] offset:36864
	s_waitcnt vmcnt(10)
	ds_write_b128 v95, v[156:159] offset:41472
	s_waitcnt lgkmcnt(8)
	v_mfma_f32_16x16x32_bf16 v[42:45], v[200:203], v[228:231], v[42:45]
	v_mfma_f32_16x16x32_bf16 v[46:49], v[200:203], v[232:235], v[46:49]
	v_mfma_f32_16x16x32_bf16 v[10:13], v[200:203], v[236:239], v[10:13]
	v_mfma_f32_16x16x32_bf16 v[14:17], v[200:203], v[240:243], v[14:17]
	s_waitcnt vmcnt(9)
	ds_write_b128 v95, v[160:163] offset:46080
	s_waitcnt vmcnt(8)
	ds_write_b128 v95, v[164:167] offset:50688
	s_waitcnt lgkmcnt(0)
	s_barrier
	s_setprio 0
	ds_read_b128 v[212:215], v245 offset:36864
	ds_read_b128 v[196:199], v244
	ds_read_b128 v[216:219], v245 offset:39168
	ds_read_b128 v[220:223], v245 offset:41472
	ds_read_b128 v[224:227], v245 offset:43776
	ds_read_b128 v[200:203], v244 offset:2304
	v_mfma_f32_16x16x32_bf16 v[50:53], v[204:207], v[228:231], v[50:53]
	v_mfma_f32_16x16x32_bf16 v[54:57], v[204:207], v[232:235], v[54:57]
	v_mfma_f32_16x16x32_bf16 v[18:21], v[204:207], v[236:239], v[18:21]
	v_mfma_f32_16x16x32_bf16 v[22:25], v[204:207], v[240:243], v[22:25]
	ds_read_b128 v[204:207], v244 offset:4608
	v_mfma_f32_16x16x32_bf16 v[58:61], v[208:211], v[228:231], v[58:61]
	v_mfma_f32_16x16x32_bf16 v[62:65], v[208:211], v[232:235], v[62:65]
	v_mfma_f32_16x16x32_bf16 v[26:29], v[208:211], v[236:239], v[26:29]
	v_mfma_f32_16x16x32_bf16 v[30:33], v[208:211], v[240:243], v[30:33]
	ds_read_b128 v[208:211], v244 offset:6912
	global_load_dwordx4 v[136:139], v[72:73], off offset:512
	global_load_dwordx4 v[140:143], v[74:75], off offset:512
	global_load_dwordx4 v[144:147], v[76:77], off offset:512
	global_load_dwordx4 v[148:151], v[78:79], off offset:512
	global_load_dwordx4 v[152:155], v[80:81], off offset:512
	global_load_dwordx4 v[156:159], v[82:83], off offset:512
	global_load_dwordx4 v[160:163], v[84:85], off offset:512
	global_load_dwordx4 v[164:167], v[86:87], off offset:512
	s_waitcnt lgkmcnt(6)
	v_mfma_f32_16x16x32_bf16 v[34:37], v[196:199], v[212:215], v[34:37]
	ds_read_b128 v[228:231], v245 offset:36928
	s_waitcnt lgkmcnt(6)
	v_mfma_f32_16x16x32_bf16 v[38:41], v[196:199], v[216:219], v[38:41]
	ds_read_b128 v[232:235], v245 offset:39232
	s_waitcnt lgkmcnt(6)
	v_mfma_f32_16x16x32_bf16 v[2:5], v[196:199], v[220:223], v[2:5]
	ds_read_b128 v[236:239], v245 offset:41536
	s_waitcnt lgkmcnt(6)
	v_mfma_f32_16x16x32_bf16 v[6:9], v[196:199], v[224:227], v[6:9]
	ds_read_b128 v[240:243], v245 offset:43840
	ds_read_b128 v[196:199], v244 offset:64
	s_waitcnt lgkmcnt(7)
	v_mfma_f32_16x16x32_bf16 v[42:45], v[200:203], v[212:215], v[42:45]
	v_mfma_f32_16x16x32_bf16 v[46:49], v[200:203], v[216:219], v[46:49]
	v_mfma_f32_16x16x32_bf16 v[10:13], v[200:203], v[220:223], v[10:13]
	v_mfma_f32_16x16x32_bf16 v[14:17], v[200:203], v[224:227], v[14:17]
	ds_read_b128 v[200:203], v244 offset:2368
	s_waitcnt lgkmcnt(7)
	v_mfma_f32_16x16x32_bf16 v[50:53], v[204:207], v[212:215], v[50:53]
	v_mfma_f32_16x16x32_bf16 v[54:57], v[204:207], v[216:219], v[54:57]
	v_mfma_f32_16x16x32_bf16 v[18:21], v[204:207], v[220:223], v[18:21]
	v_mfma_f32_16x16x32_bf16 v[22:25], v[204:207], v[224:227], v[22:25]
	ds_read_b128 v[204:207], v244 offset:4672
	s_setprio 1
	s_waitcnt vmcnt(15)
	ds_write_b128 v95, v[98:101] offset:18432
	s_waitcnt vmcnt(14)
	ds_write_b128 v95, v[102:105] offset:23040
	s_waitcnt lgkmcnt(9)
	v_mfma_f32_16x16x32_bf16 v[58:61], v[208:211], v[212:215], v[58:61]
	v_mfma_f32_16x16x32_bf16 v[62:65], v[208:211], v[216:219], v[62:65]
	v_mfma_f32_16x16x32_bf16 v[26:29], v[208:211], v[220:223], v[26:29]
	v_mfma_f32_16x16x32_bf16 v[30:33], v[208:211], v[224:227], v[30:33]
	ds_read_b128 v[208:211], v244 offset:6976
	s_waitcnt vmcnt(13)
	ds_write_b128 v95, v[106:109] offset:27648
	s_waitcnt vmcnt(12)
	ds_write_b128 v95, v[110:113] offset:32256
	s_waitcnt lgkmcnt(7)
	v_mfma_f32_16x16x32_bf16 v[34:37], v[196:199], v[228:231], v[34:37]
	v_mfma_f32_16x16x32_bf16 v[38:41], v[196:199], v[232:235], v[38:41]
	v_mfma_f32_16x16x32_bf16 v[2:5], v[196:199], v[236:239], v[2:5]
	v_mfma_f32_16x16x32_bf16 v[6:9], v[196:199], v[240:243], v[6:9]
	s_waitcnt vmcnt(11)
	ds_write_b128 v95, v[114:117] offset:55296
	s_waitcnt vmcnt(10)
	ds_write_b128 v95, v[118:121] offset:59904
	s_waitcnt lgkmcnt(8)
	v_mfma_f32_16x16x32_bf16 v[42:45], v[200:203], v[228:231], v[42:45]
	v_mfma_f32_16x16x32_bf16 v[46:49], v[200:203], v[232:235], v[46:49]
	v_mfma_f32_16x16x32_bf16 v[10:13], v[200:203], v[236:239], v[10:13]
	v_mfma_f32_16x16x32_bf16 v[14:17], v[200:203], v[240:243], v[14:17]
	s_waitcnt vmcnt(9)
	ds_write_b128 v95, v[122:125] offset:64512
	s_waitcnt vmcnt(8)
	ds_write_b128 v96, v[126:129] offset:32256
	s_waitcnt lgkmcnt(0)
	s_barrier
	s_setprio 0
	ds_read_b128 v[212:215], v245 offset:55296
	ds_read_b128 v[196:199], v244 offset:18432
	ds_read_b128 v[216:219], v245 offset:57600
	ds_read_b128 v[220:223], v245 offset:59904
	ds_read_b128 v[224:227], v245 offset:62208
	ds_read_b128 v[200:203], v244 offset:20736
	v_mfma_f32_16x16x32_bf16 v[50:53], v[204:207], v[228:231], v[50:53]
	v_mfma_f32_16x16x32_bf16 v[54:57], v[204:207], v[232:235], v[54:57]
	v_mfma_f32_16x16x32_bf16 v[18:21], v[204:207], v[236:239], v[18:21]
	v_mfma_f32_16x16x32_bf16 v[22:25], v[204:207], v[240:243], v[22:25]
	ds_read_b128 v[204:207], v244 offset:23040
	v_mfma_f32_16x16x32_bf16 v[58:61], v[208:211], v[228:231], v[58:61]
	v_mfma_f32_16x16x32_bf16 v[62:65], v[208:211], v[232:235], v[62:65]
	v_mfma_f32_16x16x32_bf16 v[26:29], v[208:211], v[236:239], v[26:29]
	v_mfma_f32_16x16x32_bf16 v[30:33], v[208:211], v[240:243], v[30:33]
	ds_read_b128 v[208:211], v244 offset:25344
	global_load_dwordx4 v[98:101], v[72:73], off offset:640
	global_load_dwordx4 v[102:105], v[74:75], off offset:640
	global_load_dwordx4 v[106:109], v[76:77], off offset:640
	global_load_dwordx4 v[110:113], v[78:79], off offset:640
	global_load_dwordx4 v[114:117], v[80:81], off offset:640
	global_load_dwordx4 v[118:121], v[82:83], off offset:640
	global_load_dwordx4 v[122:125], v[84:85], off offset:640
	global_load_dwordx4 v[126:129], v[86:87], off offset:640
	s_waitcnt lgkmcnt(6)
	v_mfma_f32_16x16x32_bf16 v[34:37], v[196:199], v[212:215], v[34:37]
	ds_read_b128 v[228:231], v245 offset:55360
	s_waitcnt lgkmcnt(6)
	v_mfma_f32_16x16x32_bf16 v[38:41], v[196:199], v[216:219], v[38:41]
	ds_read_b128 v[232:235], v245 offset:57664
	s_waitcnt lgkmcnt(6)
	v_mfma_f32_16x16x32_bf16 v[2:5], v[196:199], v[220:223], v[2:5]
	ds_read_b128 v[236:239], v245 offset:59968
	s_waitcnt lgkmcnt(6)
	v_mfma_f32_16x16x32_bf16 v[6:9], v[196:199], v[224:227], v[6:9]
	ds_read_b128 v[240:243], v245 offset:62272
	ds_read_b128 v[196:199], v244 offset:18496
	s_waitcnt lgkmcnt(7)
	v_mfma_f32_16x16x32_bf16 v[42:45], v[200:203], v[212:215], v[42:45]
	v_mfma_f32_16x16x32_bf16 v[46:49], v[200:203], v[216:219], v[46:49]
	v_mfma_f32_16x16x32_bf16 v[10:13], v[200:203], v[220:223], v[10:13]
	v_mfma_f32_16x16x32_bf16 v[14:17], v[200:203], v[224:227], v[14:17]
	ds_read_b128 v[200:203], v244 offset:20800
	s_waitcnt lgkmcnt(7)
	v_mfma_f32_16x16x32_bf16 v[50:53], v[204:207], v[212:215], v[50:53]
	v_mfma_f32_16x16x32_bf16 v[54:57], v[204:207], v[216:219], v[54:57]
	v_mfma_f32_16x16x32_bf16 v[18:21], v[204:207], v[220:223], v[18:21]
	v_mfma_f32_16x16x32_bf16 v[22:25], v[204:207], v[224:227], v[22:25]
	ds_read_b128 v[204:207], v244 offset:23104
	s_setprio 1
	s_waitcnt vmcnt(15)
	ds_write_b128 v95, v[136:139]
	s_waitcnt vmcnt(14)
	ds_write_b128 v95, v[140:143] offset:4608
	s_waitcnt lgkmcnt(9)
	v_mfma_f32_16x16x32_bf16 v[58:61], v[208:211], v[212:215], v[58:61]
	v_mfma_f32_16x16x32_bf16 v[62:65], v[208:211], v[216:219], v[62:65]
	v_mfma_f32_16x16x32_bf16 v[26:29], v[208:211], v[220:223], v[26:29]
	v_mfma_f32_16x16x32_bf16 v[30:33], v[208:211], v[224:227], v[30:33]
	ds_read_b128 v[208:211], v244 offset:25408
	s_waitcnt vmcnt(13)
	ds_write_b128 v95, v[144:147] offset:9216
	s_waitcnt vmcnt(12)
	ds_write_b128 v95, v[148:151] offset:13824
	s_waitcnt lgkmcnt(7)
	v_mfma_f32_16x16x32_bf16 v[34:37], v[196:199], v[228:231], v[34:37]
	v_mfma_f32_16x16x32_bf16 v[38:41], v[196:199], v[232:235], v[38:41]
	v_mfma_f32_16x16x32_bf16 v[2:5], v[196:199], v[236:239], v[2:5]
	v_mfma_f32_16x16x32_bf16 v[6:9], v[196:199], v[240:243], v[6:9]
	s_waitcnt vmcnt(11)
	ds_write_b128 v95, v[152:155] offset:36864
	s_waitcnt vmcnt(10)
	ds_write_b128 v95, v[156:159] offset:41472
	s_waitcnt lgkmcnt(8)
	v_mfma_f32_16x16x32_bf16 v[42:45], v[200:203], v[228:231], v[42:45]
	v_mfma_f32_16x16x32_bf16 v[46:49], v[200:203], v[232:235], v[46:49]
	v_mfma_f32_16x16x32_bf16 v[10:13], v[200:203], v[236:239], v[10:13]
	v_mfma_f32_16x16x32_bf16 v[14:17], v[200:203], v[240:243], v[14:17]
	s_waitcnt vmcnt(9)
	ds_write_b128 v95, v[160:163] offset:46080
	s_waitcnt vmcnt(8)
	ds_write_b128 v95, v[164:167] offset:50688
	s_waitcnt lgkmcnt(0)
	s_barrier
	s_setprio 0
	ds_read_b128 v[212:215], v245 offset:36864
	ds_read_b128 v[196:199], v244
	ds_read_b128 v[216:219], v245 offset:39168
	ds_read_b128 v[220:223], v245 offset:41472
	ds_read_b128 v[224:227], v245 offset:43776
	ds_read_b128 v[200:203], v244 offset:2304
	v_mfma_f32_16x16x32_bf16 v[50:53], v[204:207], v[228:231], v[50:53]
	v_mfma_f32_16x16x32_bf16 v[54:57], v[204:207], v[232:235], v[54:57]
	v_mfma_f32_16x16x32_bf16 v[18:21], v[204:207], v[236:239], v[18:21]
	v_mfma_f32_16x16x32_bf16 v[22:25], v[204:207], v[240:243], v[22:25]
	ds_read_b128 v[204:207], v244 offset:4608
	v_mfma_f32_16x16x32_bf16 v[58:61], v[208:211], v[228:231], v[58:61]
	v_mfma_f32_16x16x32_bf16 v[62:65], v[208:211], v[232:235], v[62:65]
	v_mfma_f32_16x16x32_bf16 v[26:29], v[208:211], v[236:239], v[26:29]
	v_mfma_f32_16x16x32_bf16 v[30:33], v[208:211], v[240:243], v[30:33]
	ds_read_b128 v[208:211], v244 offset:6912
	global_load_dwordx4 v[136:139], v[72:73], off offset:768
	global_load_dwordx4 v[140:143], v[74:75], off offset:768
	global_load_dwordx4 v[144:147], v[76:77], off offset:768
	global_load_dwordx4 v[148:151], v[78:79], off offset:768
	global_load_dwordx4 v[152:155], v[80:81], off offset:768
	global_load_dwordx4 v[156:159], v[82:83], off offset:768
	global_load_dwordx4 v[160:163], v[84:85], off offset:768
	global_load_dwordx4 v[164:167], v[86:87], off offset:768
	s_waitcnt lgkmcnt(6)
	v_mfma_f32_16x16x32_bf16 v[34:37], v[196:199], v[212:215], v[34:37]
	ds_read_b128 v[228:231], v245 offset:36928
	s_waitcnt lgkmcnt(6)
	v_mfma_f32_16x16x32_bf16 v[38:41], v[196:199], v[216:219], v[38:41]
	ds_read_b128 v[232:235], v245 offset:39232
	s_waitcnt lgkmcnt(6)
	v_mfma_f32_16x16x32_bf16 v[2:5], v[196:199], v[220:223], v[2:5]
	ds_read_b128 v[236:239], v245 offset:41536
	s_waitcnt lgkmcnt(6)
	v_mfma_f32_16x16x32_bf16 v[6:9], v[196:199], v[224:227], v[6:9]
	ds_read_b128 v[240:243], v245 offset:43840
	ds_read_b128 v[196:199], v244 offset:64
	s_waitcnt lgkmcnt(7)
	v_mfma_f32_16x16x32_bf16 v[42:45], v[200:203], v[212:215], v[42:45]
	v_mfma_f32_16x16x32_bf16 v[46:49], v[200:203], v[216:219], v[46:49]
	v_mfma_f32_16x16x32_bf16 v[10:13], v[200:203], v[220:223], v[10:13]
	v_mfma_f32_16x16x32_bf16 v[14:17], v[200:203], v[224:227], v[14:17]
	ds_read_b128 v[200:203], v244 offset:2368
	s_waitcnt lgkmcnt(7)
	v_mfma_f32_16x16x32_bf16 v[50:53], v[204:207], v[212:215], v[50:53]
	v_mfma_f32_16x16x32_bf16 v[54:57], v[204:207], v[216:219], v[54:57]
	v_mfma_f32_16x16x32_bf16 v[18:21], v[204:207], v[220:223], v[18:21]
	v_mfma_f32_16x16x32_bf16 v[22:25], v[204:207], v[224:227], v[22:25]
	ds_read_b128 v[204:207], v244 offset:4672
	s_setprio 1
	s_waitcnt vmcnt(15)
	ds_write_b128 v95, v[98:101] offset:18432
	s_waitcnt vmcnt(14)
	ds_write_b128 v95, v[102:105] offset:23040
	s_waitcnt lgkmcnt(9)
	v_mfma_f32_16x16x32_bf16 v[58:61], v[208:211], v[212:215], v[58:61]
	v_mfma_f32_16x16x32_bf16 v[62:65], v[208:211], v[216:219], v[62:65]
	v_mfma_f32_16x16x32_bf16 v[26:29], v[208:211], v[220:223], v[26:29]
	v_mfma_f32_16x16x32_bf16 v[30:33], v[208:211], v[224:227], v[30:33]
	ds_read_b128 v[208:211], v244 offset:6976
	s_waitcnt vmcnt(13)
	ds_write_b128 v95, v[106:109] offset:27648
	s_waitcnt vmcnt(12)
	ds_write_b128 v95, v[110:113] offset:32256
	s_waitcnt lgkmcnt(7)
	v_mfma_f32_16x16x32_bf16 v[34:37], v[196:199], v[228:231], v[34:37]
	v_mfma_f32_16x16x32_bf16 v[38:41], v[196:199], v[232:235], v[38:41]
	v_mfma_f32_16x16x32_bf16 v[2:5], v[196:199], v[236:239], v[2:5]
	v_mfma_f32_16x16x32_bf16 v[6:9], v[196:199], v[240:243], v[6:9]
	s_waitcnt vmcnt(11)
	ds_write_b128 v95, v[114:117] offset:55296
	s_waitcnt vmcnt(10)
	ds_write_b128 v95, v[118:121] offset:59904
	s_waitcnt lgkmcnt(8)
	v_mfma_f32_16x16x32_bf16 v[42:45], v[200:203], v[228:231], v[42:45]
	v_mfma_f32_16x16x32_bf16 v[46:49], v[200:203], v[232:235], v[46:49]
	v_mfma_f32_16x16x32_bf16 v[10:13], v[200:203], v[236:239], v[10:13]
	v_mfma_f32_16x16x32_bf16 v[14:17], v[200:203], v[240:243], v[14:17]
	s_waitcnt vmcnt(9)
	ds_write_b128 v95, v[122:125] offset:64512
	s_waitcnt vmcnt(8)
	ds_write_b128 v96, v[126:129] offset:32256
	s_waitcnt lgkmcnt(0)
	s_barrier
	s_setprio 0
	ds_read_b128 v[212:215], v245 offset:55296
	ds_read_b128 v[196:199], v244 offset:18432
	ds_read_b128 v[216:219], v245 offset:57600
	ds_read_b128 v[220:223], v245 offset:59904
	ds_read_b128 v[224:227], v245 offset:62208
	ds_read_b128 v[200:203], v244 offset:20736
	v_mfma_f32_16x16x32_bf16 v[50:53], v[204:207], v[228:231], v[50:53]
	v_mfma_f32_16x16x32_bf16 v[54:57], v[204:207], v[232:235], v[54:57]
	v_mfma_f32_16x16x32_bf16 v[18:21], v[204:207], v[236:239], v[18:21]
	v_mfma_f32_16x16x32_bf16 v[22:25], v[204:207], v[240:243], v[22:25]
	ds_read_b128 v[204:207], v244 offset:23040
	v_mfma_f32_16x16x32_bf16 v[58:61], v[208:211], v[228:231], v[58:61]
	v_mfma_f32_16x16x32_bf16 v[62:65], v[208:211], v[232:235], v[62:65]
	v_mfma_f32_16x16x32_bf16 v[26:29], v[208:211], v[236:239], v[26:29]
	v_mfma_f32_16x16x32_bf16 v[30:33], v[208:211], v[240:243], v[30:33]
	ds_read_b128 v[208:211], v244 offset:25344
	global_load_dwordx4 v[98:101], v[72:73], off offset:896
	global_load_dwordx4 v[102:105], v[74:75], off offset:896
	global_load_dwordx4 v[106:109], v[76:77], off offset:896
	global_load_dwordx4 v[110:113], v[78:79], off offset:896
	global_load_dwordx4 v[114:117], v[80:81], off offset:896
	global_load_dwordx4 v[118:121], v[82:83], off offset:896
	global_load_dwordx4 v[122:125], v[84:85], off offset:896
	global_load_dwordx4 v[126:129], v[86:87], off offset:896
	s_waitcnt lgkmcnt(6)
	v_mfma_f32_16x16x32_bf16 v[34:37], v[196:199], v[212:215], v[34:37]
	ds_read_b128 v[228:231], v245 offset:55360
	s_waitcnt lgkmcnt(6)
	v_mfma_f32_16x16x32_bf16 v[38:41], v[196:199], v[216:219], v[38:41]
	ds_read_b128 v[232:235], v245 offset:57664
	s_waitcnt lgkmcnt(6)
	v_mfma_f32_16x16x32_bf16 v[2:5], v[196:199], v[220:223], v[2:5]
	ds_read_b128 v[236:239], v245 offset:59968
	s_waitcnt lgkmcnt(6)
	v_mfma_f32_16x16x32_bf16 v[6:9], v[196:199], v[224:227], v[6:9]
	ds_read_b128 v[240:243], v245 offset:62272
	ds_read_b128 v[196:199], v244 offset:18496
	s_waitcnt lgkmcnt(7)
	v_mfma_f32_16x16x32_bf16 v[42:45], v[200:203], v[212:215], v[42:45]
	v_mfma_f32_16x16x32_bf16 v[46:49], v[200:203], v[216:219], v[46:49]
	v_mfma_f32_16x16x32_bf16 v[10:13], v[200:203], v[220:223], v[10:13]
	v_mfma_f32_16x16x32_bf16 v[14:17], v[200:203], v[224:227], v[14:17]
	ds_read_b128 v[200:203], v244 offset:20800
	s_waitcnt lgkmcnt(7)
	v_mfma_f32_16x16x32_bf16 v[50:53], v[204:207], v[212:215], v[50:53]
	v_mfma_f32_16x16x32_bf16 v[54:57], v[204:207], v[216:219], v[54:57]
	v_mfma_f32_16x16x32_bf16 v[18:21], v[204:207], v[220:223], v[18:21]
	v_mfma_f32_16x16x32_bf16 v[22:25], v[204:207], v[224:227], v[22:25]
	ds_read_b128 v[204:207], v244 offset:23104
	s_setprio 1
	s_waitcnt vmcnt(15)
	ds_write_b128 v95, v[136:139]
	s_waitcnt vmcnt(14)
	ds_write_b128 v95, v[140:143] offset:4608
	s_waitcnt lgkmcnt(9)
	v_mfma_f32_16x16x32_bf16 v[58:61], v[208:211], v[212:215], v[58:61]
	v_mfma_f32_16x16x32_bf16 v[62:65], v[208:211], v[216:219], v[62:65]
	v_mfma_f32_16x16x32_bf16 v[26:29], v[208:211], v[220:223], v[26:29]
	v_mfma_f32_16x16x32_bf16 v[30:33], v[208:211], v[224:227], v[30:33]
	ds_read_b128 v[208:211], v244 offset:25408
	s_waitcnt vmcnt(13)
	ds_write_b128 v95, v[144:147] offset:9216
	s_waitcnt vmcnt(12)
	ds_write_b128 v95, v[148:151] offset:13824
	s_waitcnt lgkmcnt(7)
	v_mfma_f32_16x16x32_bf16 v[34:37], v[196:199], v[228:231], v[34:37]
	v_mfma_f32_16x16x32_bf16 v[38:41], v[196:199], v[232:235], v[38:41]
	v_mfma_f32_16x16x32_bf16 v[2:5], v[196:199], v[236:239], v[2:5]
	v_mfma_f32_16x16x32_bf16 v[6:9], v[196:199], v[240:243], v[6:9]
	s_waitcnt vmcnt(11)
	ds_write_b128 v95, v[152:155] offset:36864
	s_waitcnt vmcnt(10)
	ds_write_b128 v95, v[156:159] offset:41472
	s_waitcnt lgkmcnt(8)
	v_mfma_f32_16x16x32_bf16 v[42:45], v[200:203], v[228:231], v[42:45]
	v_mfma_f32_16x16x32_bf16 v[46:49], v[200:203], v[232:235], v[46:49]
	v_mfma_f32_16x16x32_bf16 v[10:13], v[200:203], v[236:239], v[10:13]
	v_mfma_f32_16x16x32_bf16 v[14:17], v[200:203], v[240:243], v[14:17]
	s_waitcnt vmcnt(9)
	ds_write_b128 v95, v[160:163] offset:46080
	s_waitcnt vmcnt(8)
	ds_write_b128 v95, v[164:167] offset:50688
	s_waitcnt lgkmcnt(0)
	s_barrier
	s_setprio 0
	ds_read_b128 v[212:215], v245 offset:36864
	ds_read_b128 v[196:199], v244
	ds_read_b128 v[216:219], v245 offset:39168
	ds_read_b128 v[220:223], v245 offset:41472
	ds_read_b128 v[224:227], v245 offset:43776
	ds_read_b128 v[200:203], v244 offset:2304
	v_mfma_f32_16x16x32_bf16 v[50:53], v[204:207], v[228:231], v[50:53]
	v_mfma_f32_16x16x32_bf16 v[54:57], v[204:207], v[232:235], v[54:57]
	v_mfma_f32_16x16x32_bf16 v[18:21], v[204:207], v[236:239], v[18:21]
	v_mfma_f32_16x16x32_bf16 v[22:25], v[204:207], v[240:243], v[22:25]
	ds_read_b128 v[204:207], v244 offset:4608
	v_mfma_f32_16x16x32_bf16 v[58:61], v[208:211], v[228:231], v[58:61]
	v_mfma_f32_16x16x32_bf16 v[62:65], v[208:211], v[232:235], v[62:65]
	v_mfma_f32_16x16x32_bf16 v[26:29], v[208:211], v[236:239], v[26:29]
	v_mfma_f32_16x16x32_bf16 v[30:33], v[208:211], v[240:243], v[30:33]
	ds_read_b128 v[208:211], v244 offset:6912
	global_load_dwordx4 v[136:139], v[72:73], off offset:1024
	global_load_dwordx4 v[140:143], v[74:75], off offset:1024
	global_load_dwordx4 v[144:147], v[76:77], off offset:1024
	global_load_dwordx4 v[148:151], v[78:79], off offset:1024
	global_load_dwordx4 v[152:155], v[80:81], off offset:1024
	global_load_dwordx4 v[156:159], v[82:83], off offset:1024
	global_load_dwordx4 v[160:163], v[84:85], off offset:1024
	global_load_dwordx4 v[164:167], v[86:87], off offset:1024
	s_waitcnt lgkmcnt(6)
	v_mfma_f32_16x16x32_bf16 v[34:37], v[196:199], v[212:215], v[34:37]
	ds_read_b128 v[228:231], v245 offset:36928
	s_waitcnt lgkmcnt(6)
	v_mfma_f32_16x16x32_bf16 v[38:41], v[196:199], v[216:219], v[38:41]
	ds_read_b128 v[232:235], v245 offset:39232
	s_waitcnt lgkmcnt(6)
	v_mfma_f32_16x16x32_bf16 v[2:5], v[196:199], v[220:223], v[2:5]
	ds_read_b128 v[236:239], v245 offset:41536
	s_waitcnt lgkmcnt(6)
	v_mfma_f32_16x16x32_bf16 v[6:9], v[196:199], v[224:227], v[6:9]
	ds_read_b128 v[240:243], v245 offset:43840
	ds_read_b128 v[196:199], v244 offset:64
	s_waitcnt lgkmcnt(7)
	v_mfma_f32_16x16x32_bf16 v[42:45], v[200:203], v[212:215], v[42:45]
	v_mfma_f32_16x16x32_bf16 v[46:49], v[200:203], v[216:219], v[46:49]
	v_mfma_f32_16x16x32_bf16 v[10:13], v[200:203], v[220:223], v[10:13]
	v_mfma_f32_16x16x32_bf16 v[14:17], v[200:203], v[224:227], v[14:17]
	ds_read_b128 v[200:203], v244 offset:2368
	s_waitcnt lgkmcnt(7)
	v_mfma_f32_16x16x32_bf16 v[50:53], v[204:207], v[212:215], v[50:53]
	v_mfma_f32_16x16x32_bf16 v[54:57], v[204:207], v[216:219], v[54:57]
	v_mfma_f32_16x16x32_bf16 v[18:21], v[204:207], v[220:223], v[18:21]
	v_mfma_f32_16x16x32_bf16 v[22:25], v[204:207], v[224:227], v[22:25]
	ds_read_b128 v[204:207], v244 offset:4672
	s_setprio 1
	s_waitcnt vmcnt(15)
	ds_write_b128 v95, v[98:101] offset:18432
	s_waitcnt vmcnt(14)
	ds_write_b128 v95, v[102:105] offset:23040
	s_waitcnt lgkmcnt(9)
	v_mfma_f32_16x16x32_bf16 v[58:61], v[208:211], v[212:215], v[58:61]
	v_mfma_f32_16x16x32_bf16 v[62:65], v[208:211], v[216:219], v[62:65]
	v_mfma_f32_16x16x32_bf16 v[26:29], v[208:211], v[220:223], v[26:29]
	v_mfma_f32_16x16x32_bf16 v[30:33], v[208:211], v[224:227], v[30:33]
	ds_read_b128 v[208:211], v244 offset:6976
	s_waitcnt vmcnt(13)
	ds_write_b128 v95, v[106:109] offset:27648
	s_waitcnt vmcnt(12)
	ds_write_b128 v95, v[110:113] offset:32256
	s_waitcnt lgkmcnt(7)
	v_mfma_f32_16x16x32_bf16 v[34:37], v[196:199], v[228:231], v[34:37]
	v_mfma_f32_16x16x32_bf16 v[38:41], v[196:199], v[232:235], v[38:41]
	v_mfma_f32_16x16x32_bf16 v[2:5], v[196:199], v[236:239], v[2:5]
	v_mfma_f32_16x16x32_bf16 v[6:9], v[196:199], v[240:243], v[6:9]
	s_waitcnt vmcnt(11)
	ds_write_b128 v95, v[114:117] offset:55296
	s_waitcnt vmcnt(10)
	ds_write_b128 v95, v[118:121] offset:59904
	s_waitcnt lgkmcnt(8)
	v_mfma_f32_16x16x32_bf16 v[42:45], v[200:203], v[228:231], v[42:45]
	v_mfma_f32_16x16x32_bf16 v[46:49], v[200:203], v[232:235], v[46:49]
	v_mfma_f32_16x16x32_bf16 v[10:13], v[200:203], v[236:239], v[10:13]
	v_mfma_f32_16x16x32_bf16 v[14:17], v[200:203], v[240:243], v[14:17]
	s_waitcnt vmcnt(9)
	ds_write_b128 v95, v[122:125] offset:64512
	s_waitcnt vmcnt(8)
	ds_write_b128 v96, v[126:129] offset:32256
	s_waitcnt lgkmcnt(0)
	s_barrier
	s_setprio 0
	ds_read_b128 v[212:215], v245 offset:55296
	ds_read_b128 v[196:199], v244 offset:18432
	ds_read_b128 v[216:219], v245 offset:57600
	ds_read_b128 v[220:223], v245 offset:59904
	ds_read_b128 v[224:227], v245 offset:62208
	ds_read_b128 v[200:203], v244 offset:20736
	v_mfma_f32_16x16x32_bf16 v[50:53], v[204:207], v[228:231], v[50:53]
	v_mfma_f32_16x16x32_bf16 v[54:57], v[204:207], v[232:235], v[54:57]
	v_mfma_f32_16x16x32_bf16 v[18:21], v[204:207], v[236:239], v[18:21]
	v_mfma_f32_16x16x32_bf16 v[22:25], v[204:207], v[240:243], v[22:25]
	ds_read_b128 v[204:207], v244 offset:23040
	v_mfma_f32_16x16x32_bf16 v[58:61], v[208:211], v[228:231], v[58:61]
	v_mfma_f32_16x16x32_bf16 v[62:65], v[208:211], v[232:235], v[62:65]
	v_mfma_f32_16x16x32_bf16 v[26:29], v[208:211], v[236:239], v[26:29]
	v_mfma_f32_16x16x32_bf16 v[30:33], v[208:211], v[240:243], v[30:33]
	ds_read_b128 v[208:211], v244 offset:25344
	global_load_dwordx4 v[98:101], v[72:73], off offset:1152
	global_load_dwordx4 v[102:105], v[74:75], off offset:1152
	global_load_dwordx4 v[106:109], v[76:77], off offset:1152
	global_load_dwordx4 v[110:113], v[78:79], off offset:1152
	global_load_dwordx4 v[114:117], v[80:81], off offset:1152
	global_load_dwordx4 v[118:121], v[82:83], off offset:1152
	global_load_dwordx4 v[122:125], v[84:85], off offset:1152
	global_load_dwordx4 v[126:129], v[86:87], off offset:1152
	s_waitcnt lgkmcnt(6)
	v_mfma_f32_16x16x32_bf16 v[34:37], v[196:199], v[212:215], v[34:37]
	ds_read_b128 v[228:231], v245 offset:55360
	s_waitcnt lgkmcnt(6)
	v_mfma_f32_16x16x32_bf16 v[38:41], v[196:199], v[216:219], v[38:41]
	ds_read_b128 v[232:235], v245 offset:57664
	s_waitcnt lgkmcnt(6)
	v_mfma_f32_16x16x32_bf16 v[2:5], v[196:199], v[220:223], v[2:5]
	ds_read_b128 v[236:239], v245 offset:59968
	s_waitcnt lgkmcnt(6)
	v_mfma_f32_16x16x32_bf16 v[6:9], v[196:199], v[224:227], v[6:9]
	ds_read_b128 v[240:243], v245 offset:62272
	ds_read_b128 v[196:199], v244 offset:18496
	s_waitcnt lgkmcnt(7)
	v_mfma_f32_16x16x32_bf16 v[42:45], v[200:203], v[212:215], v[42:45]
	v_mfma_f32_16x16x32_bf16 v[46:49], v[200:203], v[216:219], v[46:49]
	v_mfma_f32_16x16x32_bf16 v[10:13], v[200:203], v[220:223], v[10:13]
	v_mfma_f32_16x16x32_bf16 v[14:17], v[200:203], v[224:227], v[14:17]
	ds_read_b128 v[200:203], v244 offset:20800
	s_waitcnt lgkmcnt(7)
	v_mfma_f32_16x16x32_bf16 v[50:53], v[204:207], v[212:215], v[50:53]
	v_mfma_f32_16x16x32_bf16 v[54:57], v[204:207], v[216:219], v[54:57]
	v_mfma_f32_16x16x32_bf16 v[18:21], v[204:207], v[220:223], v[18:21]
	v_mfma_f32_16x16x32_bf16 v[22:25], v[204:207], v[224:227], v[22:25]
	ds_read_b128 v[204:207], v244 offset:23104
	s_setprio 1
	s_waitcnt vmcnt(15)
	ds_write_b128 v95, v[136:139]
	s_waitcnt vmcnt(14)
	ds_write_b128 v95, v[140:143] offset:4608
	s_waitcnt lgkmcnt(9)
	v_mfma_f32_16x16x32_bf16 v[58:61], v[208:211], v[212:215], v[58:61]
	v_mfma_f32_16x16x32_bf16 v[62:65], v[208:211], v[216:219], v[62:65]
	v_mfma_f32_16x16x32_bf16 v[26:29], v[208:211], v[220:223], v[26:29]
	v_mfma_f32_16x16x32_bf16 v[30:33], v[208:211], v[224:227], v[30:33]
	ds_read_b128 v[208:211], v244 offset:25408
	s_waitcnt vmcnt(13)
	ds_write_b128 v95, v[144:147] offset:9216
	s_waitcnt vmcnt(12)
	ds_write_b128 v95, v[148:151] offset:13824
	s_waitcnt lgkmcnt(7)
	v_mfma_f32_16x16x32_bf16 v[34:37], v[196:199], v[228:231], v[34:37]
	v_mfma_f32_16x16x32_bf16 v[38:41], v[196:199], v[232:235], v[38:41]
	v_mfma_f32_16x16x32_bf16 v[2:5], v[196:199], v[236:239], v[2:5]
	v_mfma_f32_16x16x32_bf16 v[6:9], v[196:199], v[240:243], v[6:9]
	s_waitcnt vmcnt(11)
	ds_write_b128 v95, v[152:155] offset:36864
	s_waitcnt vmcnt(10)
	ds_write_b128 v95, v[156:159] offset:41472
	s_waitcnt lgkmcnt(8)
	v_mfma_f32_16x16x32_bf16 v[42:45], v[200:203], v[228:231], v[42:45]
	v_mfma_f32_16x16x32_bf16 v[46:49], v[200:203], v[232:235], v[46:49]
	v_mfma_f32_16x16x32_bf16 v[10:13], v[200:203], v[236:239], v[10:13]
	v_mfma_f32_16x16x32_bf16 v[14:17], v[200:203], v[240:243], v[14:17]
	s_waitcnt vmcnt(9)
	ds_write_b128 v95, v[160:163] offset:46080
	s_waitcnt vmcnt(8)
	ds_write_b128 v95, v[164:167] offset:50688
	s_waitcnt lgkmcnt(0)
	s_barrier
	s_setprio 0
	ds_read_b128 v[212:215], v245 offset:36864
	ds_read_b128 v[196:199], v244
	ds_read_b128 v[216:219], v245 offset:39168
	ds_read_b128 v[220:223], v245 offset:41472
	ds_read_b128 v[224:227], v245 offset:43776
	ds_read_b128 v[200:203], v244 offset:2304
	v_mfma_f32_16x16x32_bf16 v[50:53], v[204:207], v[228:231], v[50:53]
	v_mfma_f32_16x16x32_bf16 v[54:57], v[204:207], v[232:235], v[54:57]
	v_mfma_f32_16x16x32_bf16 v[18:21], v[204:207], v[236:239], v[18:21]
	v_mfma_f32_16x16x32_bf16 v[22:25], v[204:207], v[240:243], v[22:25]
	ds_read_b128 v[204:207], v244 offset:4608
	v_mfma_f32_16x16x32_bf16 v[58:61], v[208:211], v[228:231], v[58:61]
	v_mfma_f32_16x16x32_bf16 v[62:65], v[208:211], v[232:235], v[62:65]
	v_mfma_f32_16x16x32_bf16 v[26:29], v[208:211], v[236:239], v[26:29]
	v_mfma_f32_16x16x32_bf16 v[30:33], v[208:211], v[240:243], v[30:33]
	ds_read_b128 v[208:211], v244 offset:6912
	global_load_dwordx4 v[136:139], v[72:73], off offset:1280
	global_load_dwordx4 v[140:143], v[74:75], off offset:1280
	global_load_dwordx4 v[144:147], v[76:77], off offset:1280
	global_load_dwordx4 v[148:151], v[78:79], off offset:1280
	global_load_dwordx4 v[152:155], v[80:81], off offset:1280
	global_load_dwordx4 v[156:159], v[82:83], off offset:1280
	global_load_dwordx4 v[160:163], v[84:85], off offset:1280
	global_load_dwordx4 v[164:167], v[86:87], off offset:1280
	s_waitcnt lgkmcnt(6)
	v_mfma_f32_16x16x32_bf16 v[34:37], v[196:199], v[212:215], v[34:37]
	ds_read_b128 v[228:231], v245 offset:36928
	s_waitcnt lgkmcnt(6)
	v_mfma_f32_16x16x32_bf16 v[38:41], v[196:199], v[216:219], v[38:41]
	ds_read_b128 v[232:235], v245 offset:39232
	s_waitcnt lgkmcnt(6)
	v_mfma_f32_16x16x32_bf16 v[2:5], v[196:199], v[220:223], v[2:5]
	ds_read_b128 v[236:239], v245 offset:41536
	s_waitcnt lgkmcnt(6)
	v_mfma_f32_16x16x32_bf16 v[6:9], v[196:199], v[224:227], v[6:9]
	ds_read_b128 v[240:243], v245 offset:43840
	ds_read_b128 v[196:199], v244 offset:64
	s_waitcnt lgkmcnt(7)
	v_mfma_f32_16x16x32_bf16 v[42:45], v[200:203], v[212:215], v[42:45]
	v_mfma_f32_16x16x32_bf16 v[46:49], v[200:203], v[216:219], v[46:49]
	v_mfma_f32_16x16x32_bf16 v[10:13], v[200:203], v[220:223], v[10:13]
	v_mfma_f32_16x16x32_bf16 v[14:17], v[200:203], v[224:227], v[14:17]
	ds_read_b128 v[200:203], v244 offset:2368
	s_waitcnt lgkmcnt(7)
	v_mfma_f32_16x16x32_bf16 v[50:53], v[204:207], v[212:215], v[50:53]
	v_mfma_f32_16x16x32_bf16 v[54:57], v[204:207], v[216:219], v[54:57]
	v_mfma_f32_16x16x32_bf16 v[18:21], v[204:207], v[220:223], v[18:21]
	v_mfma_f32_16x16x32_bf16 v[22:25], v[204:207], v[224:227], v[22:25]
	ds_read_b128 v[204:207], v244 offset:4672
	s_setprio 1
	s_waitcnt vmcnt(15)
	ds_write_b128 v95, v[98:101] offset:18432
	s_waitcnt vmcnt(14)
	ds_write_b128 v95, v[102:105] offset:23040
	s_waitcnt lgkmcnt(9)
	v_mfma_f32_16x16x32_bf16 v[58:61], v[208:211], v[212:215], v[58:61]
	v_mfma_f32_16x16x32_bf16 v[62:65], v[208:211], v[216:219], v[62:65]
	v_mfma_f32_16x16x32_bf16 v[26:29], v[208:211], v[220:223], v[26:29]
	v_mfma_f32_16x16x32_bf16 v[30:33], v[208:211], v[224:227], v[30:33]
	ds_read_b128 v[208:211], v244 offset:6976
	s_waitcnt vmcnt(13)
	ds_write_b128 v95, v[106:109] offset:27648
	s_waitcnt vmcnt(12)
	ds_write_b128 v95, v[110:113] offset:32256
	s_waitcnt lgkmcnt(7)
	v_mfma_f32_16x16x32_bf16 v[34:37], v[196:199], v[228:231], v[34:37]
	v_mfma_f32_16x16x32_bf16 v[38:41], v[196:199], v[232:235], v[38:41]
	v_mfma_f32_16x16x32_bf16 v[2:5], v[196:199], v[236:239], v[2:5]
	v_mfma_f32_16x16x32_bf16 v[6:9], v[196:199], v[240:243], v[6:9]
	s_waitcnt vmcnt(11)
	ds_write_b128 v95, v[114:117] offset:55296
	s_waitcnt vmcnt(10)
	ds_write_b128 v95, v[118:121] offset:59904
	s_waitcnt lgkmcnt(8)
	v_mfma_f32_16x16x32_bf16 v[42:45], v[200:203], v[228:231], v[42:45]
	v_mfma_f32_16x16x32_bf16 v[46:49], v[200:203], v[232:235], v[46:49]
	v_mfma_f32_16x16x32_bf16 v[10:13], v[200:203], v[236:239], v[10:13]
	v_mfma_f32_16x16x32_bf16 v[14:17], v[200:203], v[240:243], v[14:17]
	s_waitcnt vmcnt(9)
	ds_write_b128 v95, v[122:125] offset:64512
	s_waitcnt vmcnt(8)
	ds_write_b128 v96, v[126:129] offset:32256
	s_waitcnt lgkmcnt(0)
	s_barrier
	s_setprio 0
	ds_read_b128 v[212:215], v245 offset:55296
	ds_read_b128 v[196:199], v244 offset:18432
	ds_read_b128 v[216:219], v245 offset:57600
	ds_read_b128 v[220:223], v245 offset:59904
	ds_read_b128 v[224:227], v245 offset:62208
	ds_read_b128 v[200:203], v244 offset:20736
	v_mfma_f32_16x16x32_bf16 v[50:53], v[204:207], v[228:231], v[50:53]
	v_mfma_f32_16x16x32_bf16 v[54:57], v[204:207], v[232:235], v[54:57]
	v_mfma_f32_16x16x32_bf16 v[18:21], v[204:207], v[236:239], v[18:21]
	v_mfma_f32_16x16x32_bf16 v[22:25], v[204:207], v[240:243], v[22:25]
	ds_read_b128 v[204:207], v244 offset:23040
	v_mfma_f32_16x16x32_bf16 v[58:61], v[208:211], v[228:231], v[58:61]
	v_mfma_f32_16x16x32_bf16 v[62:65], v[208:211], v[232:235], v[62:65]
	v_mfma_f32_16x16x32_bf16 v[26:29], v[208:211], v[236:239], v[26:29]
	v_mfma_f32_16x16x32_bf16 v[30:33], v[208:211], v[240:243], v[30:33]
	ds_read_b128 v[208:211], v244 offset:25344
	global_load_dwordx4 v[98:101], v[72:73], off offset:1408
	global_load_dwordx4 v[102:105], v[74:75], off offset:1408
	global_load_dwordx4 v[106:109], v[76:77], off offset:1408
	global_load_dwordx4 v[110:113], v[78:79], off offset:1408
	global_load_dwordx4 v[114:117], v[80:81], off offset:1408
	global_load_dwordx4 v[118:121], v[82:83], off offset:1408
	global_load_dwordx4 v[122:125], v[84:85], off offset:1408
	global_load_dwordx4 v[126:129], v[86:87], off offset:1408
	s_waitcnt lgkmcnt(6)
	v_mfma_f32_16x16x32_bf16 v[34:37], v[196:199], v[212:215], v[34:37]
	ds_read_b128 v[228:231], v245 offset:55360
	s_waitcnt lgkmcnt(6)
	v_mfma_f32_16x16x32_bf16 v[38:41], v[196:199], v[216:219], v[38:41]
	ds_read_b128 v[232:235], v245 offset:57664
	s_waitcnt lgkmcnt(6)
	v_mfma_f32_16x16x32_bf16 v[2:5], v[196:199], v[220:223], v[2:5]
	ds_read_b128 v[236:239], v245 offset:59968
	s_waitcnt lgkmcnt(6)
	v_mfma_f32_16x16x32_bf16 v[6:9], v[196:199], v[224:227], v[6:9]
	ds_read_b128 v[240:243], v245 offset:62272
	ds_read_b128 v[196:199], v244 offset:18496
	s_waitcnt lgkmcnt(7)
	v_mfma_f32_16x16x32_bf16 v[42:45], v[200:203], v[212:215], v[42:45]
	v_mfma_f32_16x16x32_bf16 v[46:49], v[200:203], v[216:219], v[46:49]
	v_mfma_f32_16x16x32_bf16 v[10:13], v[200:203], v[220:223], v[10:13]
	v_mfma_f32_16x16x32_bf16 v[14:17], v[200:203], v[224:227], v[14:17]
	ds_read_b128 v[200:203], v244 offset:20800
	s_waitcnt lgkmcnt(7)
	v_mfma_f32_16x16x32_bf16 v[50:53], v[204:207], v[212:215], v[50:53]
	v_mfma_f32_16x16x32_bf16 v[54:57], v[204:207], v[216:219], v[54:57]
	v_mfma_f32_16x16x32_bf16 v[18:21], v[204:207], v[220:223], v[18:21]
	v_mfma_f32_16x16x32_bf16 v[22:25], v[204:207], v[224:227], v[22:25]
	ds_read_b128 v[204:207], v244 offset:23104
	s_setprio 1
	s_waitcnt vmcnt(15)
	ds_write_b128 v95, v[136:139]
	s_waitcnt vmcnt(14)
	ds_write_b128 v95, v[140:143] offset:4608
	s_waitcnt lgkmcnt(9)
	v_mfma_f32_16x16x32_bf16 v[58:61], v[208:211], v[212:215], v[58:61]
	v_mfma_f32_16x16x32_bf16 v[62:65], v[208:211], v[216:219], v[62:65]
	v_mfma_f32_16x16x32_bf16 v[26:29], v[208:211], v[220:223], v[26:29]
	v_mfma_f32_16x16x32_bf16 v[30:33], v[208:211], v[224:227], v[30:33]
	ds_read_b128 v[208:211], v244 offset:25408
	s_waitcnt vmcnt(13)
	ds_write_b128 v95, v[144:147] offset:9216
	s_waitcnt vmcnt(12)
	ds_write_b128 v95, v[148:151] offset:13824
	s_waitcnt lgkmcnt(7)
	v_mfma_f32_16x16x32_bf16 v[34:37], v[196:199], v[228:231], v[34:37]
	v_mfma_f32_16x16x32_bf16 v[38:41], v[196:199], v[232:235], v[38:41]
	v_mfma_f32_16x16x32_bf16 v[2:5], v[196:199], v[236:239], v[2:5]
	v_mfma_f32_16x16x32_bf16 v[6:9], v[196:199], v[240:243], v[6:9]
	s_waitcnt vmcnt(11)
	ds_write_b128 v95, v[152:155] offset:36864
	s_waitcnt vmcnt(10)
	ds_write_b128 v95, v[156:159] offset:41472
	s_waitcnt lgkmcnt(8)
	v_mfma_f32_16x16x32_bf16 v[42:45], v[200:203], v[228:231], v[42:45]
	v_mfma_f32_16x16x32_bf16 v[46:49], v[200:203], v[232:235], v[46:49]
	v_mfma_f32_16x16x32_bf16 v[10:13], v[200:203], v[236:239], v[10:13]
	v_mfma_f32_16x16x32_bf16 v[14:17], v[200:203], v[240:243], v[14:17]
	s_waitcnt vmcnt(9)
	ds_write_b128 v95, v[160:163] offset:46080
	s_waitcnt vmcnt(8)
	ds_write_b128 v95, v[164:167] offset:50688
	s_waitcnt lgkmcnt(0)
	s_barrier
	s_setprio 0
	ds_read_b128 v[212:215], v245 offset:36864
	ds_read_b128 v[196:199], v244
	ds_read_b128 v[216:219], v245 offset:39168
	ds_read_b128 v[220:223], v245 offset:41472
	ds_read_b128 v[224:227], v245 offset:43776
	ds_read_b128 v[200:203], v244 offset:2304
	v_mfma_f32_16x16x32_bf16 v[50:53], v[204:207], v[228:231], v[50:53]
	v_mfma_f32_16x16x32_bf16 v[54:57], v[204:207], v[232:235], v[54:57]
	v_mfma_f32_16x16x32_bf16 v[18:21], v[204:207], v[236:239], v[18:21]
	v_mfma_f32_16x16x32_bf16 v[22:25], v[204:207], v[240:243], v[22:25]
	ds_read_b128 v[204:207], v244 offset:4608
	v_mfma_f32_16x16x32_bf16 v[58:61], v[208:211], v[228:231], v[58:61]
	v_mfma_f32_16x16x32_bf16 v[62:65], v[208:211], v[232:235], v[62:65]
	v_mfma_f32_16x16x32_bf16 v[26:29], v[208:211], v[236:239], v[26:29]
	v_mfma_f32_16x16x32_bf16 v[30:33], v[208:211], v[240:243], v[30:33]
	ds_read_b128 v[208:211], v244 offset:6912
	global_load_dwordx4 v[136:139], v[72:73], off offset:1536
	global_load_dwordx4 v[140:143], v[74:75], off offset:1536
	global_load_dwordx4 v[144:147], v[76:77], off offset:1536
	global_load_dwordx4 v[148:151], v[78:79], off offset:1536
	global_load_dwordx4 v[152:155], v[80:81], off offset:1536
	global_load_dwordx4 v[156:159], v[82:83], off offset:1536
	global_load_dwordx4 v[160:163], v[84:85], off offset:1536
	global_load_dwordx4 v[164:167], v[86:87], off offset:1536
	s_waitcnt lgkmcnt(6)
	v_mfma_f32_16x16x32_bf16 v[34:37], v[196:199], v[212:215], v[34:37]
	ds_read_b128 v[228:231], v245 offset:36928
	s_waitcnt lgkmcnt(6)
	v_mfma_f32_16x16x32_bf16 v[38:41], v[196:199], v[216:219], v[38:41]
	ds_read_b128 v[232:235], v245 offset:39232
	s_waitcnt lgkmcnt(6)
	v_mfma_f32_16x16x32_bf16 v[2:5], v[196:199], v[220:223], v[2:5]
	ds_read_b128 v[236:239], v245 offset:41536
	s_waitcnt lgkmcnt(6)
	v_mfma_f32_16x16x32_bf16 v[6:9], v[196:199], v[224:227], v[6:9]
	ds_read_b128 v[240:243], v245 offset:43840
	ds_read_b128 v[196:199], v244 offset:64
	s_waitcnt lgkmcnt(7)
	v_mfma_f32_16x16x32_bf16 v[42:45], v[200:203], v[212:215], v[42:45]
	v_mfma_f32_16x16x32_bf16 v[46:49], v[200:203], v[216:219], v[46:49]
	v_mfma_f32_16x16x32_bf16 v[10:13], v[200:203], v[220:223], v[10:13]
	v_mfma_f32_16x16x32_bf16 v[14:17], v[200:203], v[224:227], v[14:17]
	ds_read_b128 v[200:203], v244 offset:2368
	s_waitcnt lgkmcnt(7)
	v_mfma_f32_16x16x32_bf16 v[50:53], v[204:207], v[212:215], v[50:53]
	v_mfma_f32_16x16x32_bf16 v[54:57], v[204:207], v[216:219], v[54:57]
	v_mfma_f32_16x16x32_bf16 v[18:21], v[204:207], v[220:223], v[18:21]
	v_mfma_f32_16x16x32_bf16 v[22:25], v[204:207], v[224:227], v[22:25]
	ds_read_b128 v[204:207], v244 offset:4672
	s_setprio 1
	s_waitcnt vmcnt(15)
	ds_write_b128 v95, v[98:101] offset:18432
	s_waitcnt vmcnt(14)
	ds_write_b128 v95, v[102:105] offset:23040
	s_waitcnt lgkmcnt(9)
	v_mfma_f32_16x16x32_bf16 v[58:61], v[208:211], v[212:215], v[58:61]
	v_mfma_f32_16x16x32_bf16 v[62:65], v[208:211], v[216:219], v[62:65]
	v_mfma_f32_16x16x32_bf16 v[26:29], v[208:211], v[220:223], v[26:29]
	v_mfma_f32_16x16x32_bf16 v[30:33], v[208:211], v[224:227], v[30:33]
	ds_read_b128 v[208:211], v244 offset:6976
	s_waitcnt vmcnt(13)
	ds_write_b128 v95, v[106:109] offset:27648
	s_waitcnt vmcnt(12)
	ds_write_b128 v95, v[110:113] offset:32256
	s_waitcnt lgkmcnt(7)
	v_mfma_f32_16x16x32_bf16 v[34:37], v[196:199], v[228:231], v[34:37]
	v_mfma_f32_16x16x32_bf16 v[38:41], v[196:199], v[232:235], v[38:41]
	v_mfma_f32_16x16x32_bf16 v[2:5], v[196:199], v[236:239], v[2:5]
	v_mfma_f32_16x16x32_bf16 v[6:9], v[196:199], v[240:243], v[6:9]
	s_waitcnt vmcnt(11)
	ds_write_b128 v95, v[114:117] offset:55296
	s_waitcnt vmcnt(10)
	ds_write_b128 v95, v[118:121] offset:59904
	s_waitcnt lgkmcnt(8)
	v_mfma_f32_16x16x32_bf16 v[42:45], v[200:203], v[228:231], v[42:45]
	v_mfma_f32_16x16x32_bf16 v[46:49], v[200:203], v[232:235], v[46:49]
	v_mfma_f32_16x16x32_bf16 v[10:13], v[200:203], v[236:239], v[10:13]
	v_mfma_f32_16x16x32_bf16 v[14:17], v[200:203], v[240:243], v[14:17]
	s_waitcnt vmcnt(9)
	ds_write_b128 v95, v[122:125] offset:64512
	s_waitcnt vmcnt(8)
	ds_write_b128 v96, v[126:129] offset:32256
	s_waitcnt lgkmcnt(0)
	s_barrier
	s_setprio 0
	ds_read_b128 v[212:215], v245 offset:55296
	ds_read_b128 v[196:199], v244 offset:18432
	ds_read_b128 v[216:219], v245 offset:57600
	ds_read_b128 v[220:223], v245 offset:59904
	ds_read_b128 v[224:227], v245 offset:62208
	ds_read_b128 v[200:203], v244 offset:20736
	v_mfma_f32_16x16x32_bf16 v[50:53], v[204:207], v[228:231], v[50:53]
	v_mfma_f32_16x16x32_bf16 v[54:57], v[204:207], v[232:235], v[54:57]
	v_mfma_f32_16x16x32_bf16 v[18:21], v[204:207], v[236:239], v[18:21]
	v_mfma_f32_16x16x32_bf16 v[22:25], v[204:207], v[240:243], v[22:25]
	ds_read_b128 v[204:207], v244 offset:23040
	v_mfma_f32_16x16x32_bf16 v[58:61], v[208:211], v[228:231], v[58:61]
	v_mfma_f32_16x16x32_bf16 v[62:65], v[208:211], v[232:235], v[62:65]
	v_mfma_f32_16x16x32_bf16 v[26:29], v[208:211], v[236:239], v[26:29]
	v_mfma_f32_16x16x32_bf16 v[30:33], v[208:211], v[240:243], v[30:33]
	ds_read_b128 v[208:211], v244 offset:25344
	global_load_dwordx4 v[98:101], v[72:73], off offset:1664
	global_load_dwordx4 v[102:105], v[74:75], off offset:1664
	global_load_dwordx4 v[106:109], v[76:77], off offset:1664
	global_load_dwordx4 v[110:113], v[78:79], off offset:1664
	global_load_dwordx4 v[114:117], v[80:81], off offset:1664
	global_load_dwordx4 v[118:121], v[82:83], off offset:1664
	global_load_dwordx4 v[122:125], v[84:85], off offset:1664
	global_load_dwordx4 v[126:129], v[86:87], off offset:1664
	s_waitcnt lgkmcnt(6)
	v_mfma_f32_16x16x32_bf16 v[34:37], v[196:199], v[212:215], v[34:37]
	ds_read_b128 v[228:231], v245 offset:55360
	s_waitcnt lgkmcnt(6)
	v_mfma_f32_16x16x32_bf16 v[38:41], v[196:199], v[216:219], v[38:41]
	ds_read_b128 v[232:235], v245 offset:57664
	s_waitcnt lgkmcnt(6)
	v_mfma_f32_16x16x32_bf16 v[2:5], v[196:199], v[220:223], v[2:5]
	ds_read_b128 v[236:239], v245 offset:59968
	s_waitcnt lgkmcnt(6)
	v_mfma_f32_16x16x32_bf16 v[6:9], v[196:199], v[224:227], v[6:9]
	ds_read_b128 v[240:243], v245 offset:62272
	ds_read_b128 v[196:199], v244 offset:18496
	s_waitcnt lgkmcnt(7)
	v_mfma_f32_16x16x32_bf16 v[42:45], v[200:203], v[212:215], v[42:45]
	v_mfma_f32_16x16x32_bf16 v[46:49], v[200:203], v[216:219], v[46:49]
	v_mfma_f32_16x16x32_bf16 v[10:13], v[200:203], v[220:223], v[10:13]
	v_mfma_f32_16x16x32_bf16 v[14:17], v[200:203], v[224:227], v[14:17]
	ds_read_b128 v[200:203], v244 offset:20800
	s_waitcnt lgkmcnt(7)
	v_mfma_f32_16x16x32_bf16 v[50:53], v[204:207], v[212:215], v[50:53]
	v_mfma_f32_16x16x32_bf16 v[54:57], v[204:207], v[216:219], v[54:57]
	v_mfma_f32_16x16x32_bf16 v[18:21], v[204:207], v[220:223], v[18:21]
	v_mfma_f32_16x16x32_bf16 v[22:25], v[204:207], v[224:227], v[22:25]
	ds_read_b128 v[204:207], v244 offset:23104
	s_setprio 1
	s_waitcnt vmcnt(15)
	ds_write_b128 v95, v[136:139]
	s_waitcnt vmcnt(14)
	ds_write_b128 v95, v[140:143] offset:4608
	s_waitcnt lgkmcnt(9)
	v_mfma_f32_16x16x32_bf16 v[58:61], v[208:211], v[212:215], v[58:61]
	v_mfma_f32_16x16x32_bf16 v[62:65], v[208:211], v[216:219], v[62:65]
	v_mfma_f32_16x16x32_bf16 v[26:29], v[208:211], v[220:223], v[26:29]
	v_mfma_f32_16x16x32_bf16 v[30:33], v[208:211], v[224:227], v[30:33]
	ds_read_b128 v[208:211], v244 offset:25408
	s_waitcnt vmcnt(13)
	ds_write_b128 v95, v[144:147] offset:9216
	s_waitcnt vmcnt(12)
	ds_write_b128 v95, v[148:151] offset:13824
	s_waitcnt lgkmcnt(7)
	v_mfma_f32_16x16x32_bf16 v[34:37], v[196:199], v[228:231], v[34:37]
	v_mfma_f32_16x16x32_bf16 v[38:41], v[196:199], v[232:235], v[38:41]
	v_mfma_f32_16x16x32_bf16 v[2:5], v[196:199], v[236:239], v[2:5]
	v_mfma_f32_16x16x32_bf16 v[6:9], v[196:199], v[240:243], v[6:9]
	s_waitcnt vmcnt(11)
	ds_write_b128 v95, v[152:155] offset:36864
	s_waitcnt vmcnt(10)
	ds_write_b128 v95, v[156:159] offset:41472
	s_waitcnt lgkmcnt(8)
	v_mfma_f32_16x16x32_bf16 v[42:45], v[200:203], v[228:231], v[42:45]
	v_mfma_f32_16x16x32_bf16 v[46:49], v[200:203], v[232:235], v[46:49]
	v_mfma_f32_16x16x32_bf16 v[10:13], v[200:203], v[236:239], v[10:13]
	v_mfma_f32_16x16x32_bf16 v[14:17], v[200:203], v[240:243], v[14:17]
	s_waitcnt vmcnt(9)
	ds_write_b128 v95, v[160:163] offset:46080
	s_waitcnt vmcnt(8)
	ds_write_b128 v95, v[164:167] offset:50688
	s_waitcnt lgkmcnt(0)
	s_barrier
	s_setprio 0
	ds_read_b128 v[212:215], v245 offset:36864
	ds_read_b128 v[196:199], v244
	ds_read_b128 v[216:219], v245 offset:39168
	ds_read_b128 v[220:223], v245 offset:41472
	ds_read_b128 v[224:227], v245 offset:43776
	ds_read_b128 v[200:203], v244 offset:2304
	v_mfma_f32_16x16x32_bf16 v[50:53], v[204:207], v[228:231], v[50:53]
	v_mfma_f32_16x16x32_bf16 v[54:57], v[204:207], v[232:235], v[54:57]
	v_mfma_f32_16x16x32_bf16 v[18:21], v[204:207], v[236:239], v[18:21]
	v_mfma_f32_16x16x32_bf16 v[22:25], v[204:207], v[240:243], v[22:25]
	ds_read_b128 v[204:207], v244 offset:4608
	v_mfma_f32_16x16x32_bf16 v[58:61], v[208:211], v[228:231], v[58:61]
	v_mfma_f32_16x16x32_bf16 v[62:65], v[208:211], v[232:235], v[62:65]
	v_mfma_f32_16x16x32_bf16 v[26:29], v[208:211], v[236:239], v[26:29]
	v_mfma_f32_16x16x32_bf16 v[30:33], v[208:211], v[240:243], v[30:33]
	ds_read_b128 v[208:211], v244 offset:6912
	global_load_dwordx4 v[136:139], v[72:73], off offset:1792
	global_load_dwordx4 v[140:143], v[74:75], off offset:1792
	global_load_dwordx4 v[144:147], v[76:77], off offset:1792
	global_load_dwordx4 v[148:151], v[78:79], off offset:1792
	global_load_dwordx4 v[152:155], v[80:81], off offset:1792
	global_load_dwordx4 v[156:159], v[82:83], off offset:1792
	global_load_dwordx4 v[160:163], v[84:85], off offset:1792
	global_load_dwordx4 v[164:167], v[86:87], off offset:1792
	s_waitcnt lgkmcnt(6)
	v_mfma_f32_16x16x32_bf16 v[34:37], v[196:199], v[212:215], v[34:37]
	ds_read_b128 v[228:231], v245 offset:36928
	s_waitcnt lgkmcnt(6)
	v_mfma_f32_16x16x32_bf16 v[38:41], v[196:199], v[216:219], v[38:41]
	ds_read_b128 v[232:235], v245 offset:39232
	s_waitcnt lgkmcnt(6)
	v_mfma_f32_16x16x32_bf16 v[2:5], v[196:199], v[220:223], v[2:5]
	ds_read_b128 v[236:239], v245 offset:41536
	s_waitcnt lgkmcnt(6)
	v_mfma_f32_16x16x32_bf16 v[6:9], v[196:199], v[224:227], v[6:9]
	ds_read_b128 v[240:243], v245 offset:43840
	ds_read_b128 v[196:199], v244 offset:64
	s_waitcnt lgkmcnt(7)
	v_mfma_f32_16x16x32_bf16 v[42:45], v[200:203], v[212:215], v[42:45]
	v_mfma_f32_16x16x32_bf16 v[46:49], v[200:203], v[216:219], v[46:49]
	v_mfma_f32_16x16x32_bf16 v[10:13], v[200:203], v[220:223], v[10:13]
	v_mfma_f32_16x16x32_bf16 v[14:17], v[200:203], v[224:227], v[14:17]
	ds_read_b128 v[200:203], v244 offset:2368
	s_waitcnt lgkmcnt(7)
	v_mfma_f32_16x16x32_bf16 v[50:53], v[204:207], v[212:215], v[50:53]
	v_mfma_f32_16x16x32_bf16 v[54:57], v[204:207], v[216:219], v[54:57]
	v_mfma_f32_16x16x32_bf16 v[18:21], v[204:207], v[220:223], v[18:21]
	v_mfma_f32_16x16x32_bf16 v[22:25], v[204:207], v[224:227], v[22:25]
	ds_read_b128 v[204:207], v244 offset:4672
	s_setprio 1
	s_waitcnt vmcnt(15)
	ds_write_b128 v95, v[98:101] offset:18432
	s_waitcnt vmcnt(14)
	ds_write_b128 v95, v[102:105] offset:23040
	s_waitcnt lgkmcnt(9)
	v_mfma_f32_16x16x32_bf16 v[58:61], v[208:211], v[212:215], v[58:61]
	v_mfma_f32_16x16x32_bf16 v[62:65], v[208:211], v[216:219], v[62:65]
	v_mfma_f32_16x16x32_bf16 v[26:29], v[208:211], v[220:223], v[26:29]
	v_mfma_f32_16x16x32_bf16 v[30:33], v[208:211], v[224:227], v[30:33]
	ds_read_b128 v[208:211], v244 offset:6976
	s_waitcnt vmcnt(13)
	ds_write_b128 v95, v[106:109] offset:27648
	s_waitcnt vmcnt(12)
	ds_write_b128 v95, v[110:113] offset:32256
	s_waitcnt lgkmcnt(7)
	v_mfma_f32_16x16x32_bf16 v[34:37], v[196:199], v[228:231], v[34:37]
	v_mfma_f32_16x16x32_bf16 v[38:41], v[196:199], v[232:235], v[38:41]
	v_mfma_f32_16x16x32_bf16 v[2:5], v[196:199], v[236:239], v[2:5]
	v_mfma_f32_16x16x32_bf16 v[6:9], v[196:199], v[240:243], v[6:9]
	s_waitcnt vmcnt(11)
	ds_write_b128 v95, v[114:117] offset:55296
	s_waitcnt vmcnt(10)
	ds_write_b128 v95, v[118:121] offset:59904
	s_waitcnt lgkmcnt(8)
	v_mfma_f32_16x16x32_bf16 v[42:45], v[200:203], v[228:231], v[42:45]
	v_mfma_f32_16x16x32_bf16 v[46:49], v[200:203], v[232:235], v[46:49]
	v_mfma_f32_16x16x32_bf16 v[10:13], v[200:203], v[236:239], v[10:13]
	v_mfma_f32_16x16x32_bf16 v[14:17], v[200:203], v[240:243], v[14:17]
	s_waitcnt vmcnt(9)
	ds_write_b128 v95, v[122:125] offset:64512
	s_waitcnt vmcnt(8)
	ds_write_b128 v96, v[126:129] offset:32256
	s_waitcnt lgkmcnt(0)
	s_barrier
	s_setprio 0
	ds_read_b128 v[212:215], v245 offset:55296
	ds_read_b128 v[196:199], v244 offset:18432
	ds_read_b128 v[216:219], v245 offset:57600
	ds_read_b128 v[220:223], v245 offset:59904
	ds_read_b128 v[224:227], v245 offset:62208
	ds_read_b128 v[200:203], v244 offset:20736
	v_mfma_f32_16x16x32_bf16 v[50:53], v[204:207], v[228:231], v[50:53]
	v_mfma_f32_16x16x32_bf16 v[54:57], v[204:207], v[232:235], v[54:57]
	v_mfma_f32_16x16x32_bf16 v[18:21], v[204:207], v[236:239], v[18:21]
	v_mfma_f32_16x16x32_bf16 v[22:25], v[204:207], v[240:243], v[22:25]
	ds_read_b128 v[204:207], v244 offset:23040
	v_mfma_f32_16x16x32_bf16 v[58:61], v[208:211], v[228:231], v[58:61]
	v_mfma_f32_16x16x32_bf16 v[62:65], v[208:211], v[232:235], v[62:65]
	v_mfma_f32_16x16x32_bf16 v[26:29], v[208:211], v[236:239], v[26:29]
	v_mfma_f32_16x16x32_bf16 v[30:33], v[208:211], v[240:243], v[30:33]
	ds_read_b128 v[208:211], v244 offset:25344
	global_load_dwordx4 v[98:101], v[72:73], off offset:1920
	s_nop 0
	global_load_dwordx4 v[72:75], v[74:75], off offset:1920
	s_nop 0
	global_load_dwordx4 v[102:105], v[76:77], off offset:1920
	s_nop 0
	global_load_dwordx4 v[76:79], v[78:79], off offset:1920
	s_nop 0
	global_load_dwordx4 v[106:109], v[80:81], off offset:1920
	s_nop 0
	global_load_dwordx4 v[80:83], v[82:83], off offset:1920
	s_nop 0
	global_load_dwordx4 v[110:113], v[84:85], off offset:1920
	s_nop 0
	global_load_dwordx4 v[84:87], v[86:87], off offset:1920
	s_waitcnt lgkmcnt(6)
	v_mfma_f32_16x16x32_bf16 v[34:37], v[196:199], v[212:215], v[34:37]
	ds_read_b128 v[228:231], v245 offset:55360
	s_waitcnt lgkmcnt(6)
	v_mfma_f32_16x16x32_bf16 v[38:41], v[196:199], v[216:219], v[38:41]
	ds_read_b128 v[232:235], v245 offset:57664
	s_waitcnt lgkmcnt(6)
	v_mfma_f32_16x16x32_bf16 v[2:5], v[196:199], v[220:223], v[2:5]
	ds_read_b128 v[236:239], v245 offset:59968
	s_waitcnt lgkmcnt(6)
	v_mfma_f32_16x16x32_bf16 v[6:9], v[196:199], v[224:227], v[6:9]
	ds_read_b128 v[240:243], v245 offset:62272
	ds_read_b128 v[196:199], v244 offset:18496
	s_waitcnt lgkmcnt(7)
	v_mfma_f32_16x16x32_bf16 v[42:45], v[200:203], v[212:215], v[42:45]
	v_mfma_f32_16x16x32_bf16 v[46:49], v[200:203], v[216:219], v[46:49]
	v_mfma_f32_16x16x32_bf16 v[10:13], v[200:203], v[220:223], v[10:13]
	v_mfma_f32_16x16x32_bf16 v[14:17], v[200:203], v[224:227], v[14:17]
	ds_read_b128 v[200:203], v244 offset:20800
	s_waitcnt lgkmcnt(7)
	v_mfma_f32_16x16x32_bf16 v[50:53], v[204:207], v[212:215], v[50:53]
	v_mfma_f32_16x16x32_bf16 v[54:57], v[204:207], v[216:219], v[54:57]
	v_mfma_f32_16x16x32_bf16 v[18:21], v[204:207], v[220:223], v[18:21]
	v_mfma_f32_16x16x32_bf16 v[22:25], v[204:207], v[224:227], v[22:25]
	ds_read_b128 v[204:207], v244 offset:23104
	s_setprio 1
	s_waitcnt vmcnt(15)
	ds_write_b128 v95, v[136:139]
	s_waitcnt vmcnt(14)
	ds_write_b128 v95, v[140:143] offset:4608
	s_waitcnt lgkmcnt(9)
	v_mfma_f32_16x16x32_bf16 v[58:61], v[208:211], v[212:215], v[58:61]
	v_mfma_f32_16x16x32_bf16 v[62:65], v[208:211], v[216:219], v[62:65]
	v_mfma_f32_16x16x32_bf16 v[26:29], v[208:211], v[220:223], v[26:29]
	v_mfma_f32_16x16x32_bf16 v[30:33], v[208:211], v[224:227], v[30:33]
	ds_read_b128 v[208:211], v244 offset:25408
	s_waitcnt vmcnt(13)
	ds_write_b128 v95, v[144:147] offset:9216
	s_waitcnt vmcnt(12)
	ds_write_b128 v95, v[148:151] offset:13824
	s_waitcnt lgkmcnt(7)
	v_mfma_f32_16x16x32_bf16 v[34:37], v[196:199], v[228:231], v[34:37]
	v_mfma_f32_16x16x32_bf16 v[38:41], v[196:199], v[232:235], v[38:41]
	v_mfma_f32_16x16x32_bf16 v[2:5], v[196:199], v[236:239], v[2:5]
	v_mfma_f32_16x16x32_bf16 v[6:9], v[196:199], v[240:243], v[6:9]
	s_waitcnt vmcnt(11)
	ds_write_b128 v95, v[152:155] offset:36864
	s_waitcnt vmcnt(10)
	ds_write_b128 v95, v[156:159] offset:41472
	s_waitcnt lgkmcnt(8)
	v_mfma_f32_16x16x32_bf16 v[42:45], v[200:203], v[228:231], v[42:45]
	v_mfma_f32_16x16x32_bf16 v[46:49], v[200:203], v[232:235], v[46:49]
	v_mfma_f32_16x16x32_bf16 v[10:13], v[200:203], v[236:239], v[10:13]
	v_mfma_f32_16x16x32_bf16 v[14:17], v[200:203], v[240:243], v[14:17]
	s_waitcnt vmcnt(9)
	ds_write_b128 v95, v[160:163] offset:46080
	s_waitcnt vmcnt(8)
	ds_write_b128 v95, v[164:167] offset:50688
	s_waitcnt lgkmcnt(0)
	s_barrier
	s_setprio 0
	ds_read_b128 v[212:215], v245 offset:36864
	ds_read_b128 v[196:199], v244
	ds_read_b128 v[216:219], v245 offset:39168
	ds_read_b128 v[220:223], v245 offset:41472
	ds_read_b128 v[224:227], v245 offset:43776
	ds_read_b128 v[200:203], v244 offset:2304
	v_mfma_f32_16x16x32_bf16 v[50:53], v[204:207], v[228:231], v[50:53]
	v_mfma_f32_16x16x32_bf16 v[54:57], v[204:207], v[232:235], v[54:57]
	v_mfma_f32_16x16x32_bf16 v[18:21], v[204:207], v[236:239], v[18:21]
	v_mfma_f32_16x16x32_bf16 v[22:25], v[204:207], v[240:243], v[22:25]
	ds_read_b128 v[204:207], v244 offset:4608
	v_mfma_f32_16x16x32_bf16 v[58:61], v[208:211], v[228:231], v[58:61]
	v_mfma_f32_16x16x32_bf16 v[62:65], v[208:211], v[232:235], v[62:65]
	v_mfma_f32_16x16x32_bf16 v[26:29], v[208:211], v[236:239], v[26:29]
	v_mfma_f32_16x16x32_bf16 v[30:33], v[208:211], v[240:243], v[30:33]
	ds_read_b128 v[208:211], v244 offset:6912
	s_waitcnt lgkmcnt(6)
	v_mfma_f32_16x16x32_bf16 v[34:37], v[196:199], v[212:215], v[34:37]
	ds_read_b128 v[228:231], v245 offset:36928
	s_waitcnt lgkmcnt(6)
	v_mfma_f32_16x16x32_bf16 v[38:41], v[196:199], v[216:219], v[38:41]
	ds_read_b128 v[232:235], v245 offset:39232
	s_waitcnt lgkmcnt(6)
	v_mfma_f32_16x16x32_bf16 v[2:5], v[196:199], v[220:223], v[2:5]
	ds_read_b128 v[236:239], v245 offset:41536
	s_waitcnt lgkmcnt(6)
	v_mfma_f32_16x16x32_bf16 v[6:9], v[196:199], v[224:227], v[6:9]
	ds_read_b128 v[240:243], v245 offset:43840
	ds_read_b128 v[196:199], v244 offset:64
	s_waitcnt lgkmcnt(7)
	v_mfma_f32_16x16x32_bf16 v[42:45], v[200:203], v[212:215], v[42:45]
	v_mfma_f32_16x16x32_bf16 v[46:49], v[200:203], v[216:219], v[46:49]
	v_mfma_f32_16x16x32_bf16 v[10:13], v[200:203], v[220:223], v[10:13]
	v_mfma_f32_16x16x32_bf16 v[14:17], v[200:203], v[224:227], v[14:17]
	ds_read_b128 v[200:203], v244 offset:2368
	s_waitcnt lgkmcnt(7)
	v_mfma_f32_16x16x32_bf16 v[50:53], v[204:207], v[212:215], v[50:53]
	v_mfma_f32_16x16x32_bf16 v[54:57], v[204:207], v[216:219], v[54:57]
	v_mfma_f32_16x16x32_bf16 v[18:21], v[204:207], v[220:223], v[18:21]
	v_mfma_f32_16x16x32_bf16 v[22:25], v[204:207], v[224:227], v[22:25]
	ds_read_b128 v[204:207], v244 offset:4672
	s_setprio 1
	s_waitcnt vmcnt(7)
	ds_write_b128 v95, v[98:101] offset:18432
	s_waitcnt vmcnt(6)
	ds_write_b128 v95, v[72:75] offset:23040
	s_waitcnt lgkmcnt(9)
	v_mfma_f32_16x16x32_bf16 v[58:61], v[208:211], v[212:215], v[58:61]
	v_mfma_f32_16x16x32_bf16 v[62:65], v[208:211], v[216:219], v[62:65]
	v_mfma_f32_16x16x32_bf16 v[26:29], v[208:211], v[220:223], v[26:29]
	v_mfma_f32_16x16x32_bf16 v[30:33], v[208:211], v[224:227], v[30:33]
	ds_read_b128 v[208:211], v244 offset:6976
	s_waitcnt vmcnt(5)
	ds_write_b128 v95, v[102:105] offset:27648
	s_waitcnt vmcnt(4)
	ds_write_b128 v95, v[76:79] offset:32256
	s_waitcnt lgkmcnt(7)
	v_mfma_f32_16x16x32_bf16 v[34:37], v[196:199], v[228:231], v[34:37]
	v_mfma_f32_16x16x32_bf16 v[38:41], v[196:199], v[232:235], v[38:41]
	v_mfma_f32_16x16x32_bf16 v[2:5], v[196:199], v[236:239], v[2:5]
	v_mfma_f32_16x16x32_bf16 v[6:9], v[196:199], v[240:243], v[6:9]
	s_waitcnt vmcnt(3)
	ds_write_b128 v95, v[106:109] offset:55296
	s_waitcnt vmcnt(2)
	ds_write_b128 v95, v[80:83] offset:59904
	s_waitcnt lgkmcnt(8)
	v_mfma_f32_16x16x32_bf16 v[42:45], v[200:203], v[228:231], v[42:45]
	v_mfma_f32_16x16x32_bf16 v[46:49], v[200:203], v[232:235], v[46:49]
	v_mfma_f32_16x16x32_bf16 v[10:13], v[200:203], v[236:239], v[10:13]
	v_mfma_f32_16x16x32_bf16 v[14:17], v[200:203], v[240:243], v[14:17]
	s_waitcnt vmcnt(1)
	ds_write_b128 v95, v[110:113] offset:64512
	s_waitcnt vmcnt(0)
	ds_write_b128 v96, v[84:87] offset:32256
	s_waitcnt lgkmcnt(0)
	s_barrier
	s_setprio 0
	ds_read_b128 v[212:215], v245 offset:55296
	ds_read_b128 v[196:199], v244 offset:18432
	ds_read_b128 v[216:219], v245 offset:57600
	ds_read_b128 v[220:223], v245 offset:59904
	ds_read_b128 v[224:227], v245 offset:62208
	ds_read_b128 v[200:203], v244 offset:20736
	v_mfma_f32_16x16x32_bf16 v[50:53], v[204:207], v[228:231], v[50:53]
	v_mfma_f32_16x16x32_bf16 v[54:57], v[204:207], v[232:235], v[54:57]
	v_mfma_f32_16x16x32_bf16 v[18:21], v[204:207], v[236:239], v[18:21]
	v_mfma_f32_16x16x32_bf16 v[22:25], v[204:207], v[240:243], v[22:25]
	ds_read_b128 v[204:207], v244 offset:23040
	v_mfma_f32_16x16x32_bf16 v[58:61], v[208:211], v[228:231], v[58:61]
	v_mfma_f32_16x16x32_bf16 v[62:65], v[208:211], v[232:235], v[62:65]
	v_mfma_f32_16x16x32_bf16 v[26:29], v[208:211], v[236:239], v[26:29]
	v_mfma_f32_16x16x32_bf16 v[30:33], v[208:211], v[240:243], v[30:33]
	ds_read_b128 v[208:211], v244 offset:25344
	s_waitcnt lgkmcnt(6)
	v_mfma_f32_16x16x32_bf16 v[34:37], v[196:199], v[212:215], v[34:37]
	ds_read_b128 v[228:231], v245 offset:55360
	s_waitcnt lgkmcnt(6)
	v_mfma_f32_16x16x32_bf16 v[38:41], v[196:199], v[216:219], v[38:41]
	ds_read_b128 v[232:235], v245 offset:57664
	s_waitcnt lgkmcnt(6)
	v_mfma_f32_16x16x32_bf16 v[2:5], v[196:199], v[220:223], v[2:5]
	ds_read_b128 v[236:239], v245 offset:59968
	s_waitcnt lgkmcnt(6)
	v_mfma_f32_16x16x32_bf16 v[6:9], v[196:199], v[224:227], v[6:9]
	ds_read_b128 v[240:243], v245 offset:62272
	ds_read_b128 v[196:199], v244 offset:18496
	s_waitcnt lgkmcnt(7)
	v_mfma_f32_16x16x32_bf16 v[42:45], v[200:203], v[212:215], v[42:45]
	v_mfma_f32_16x16x32_bf16 v[46:49], v[200:203], v[216:219], v[46:49]
	v_mfma_f32_16x16x32_bf16 v[10:13], v[200:203], v[220:223], v[10:13]
	v_mfma_f32_16x16x32_bf16 v[14:17], v[200:203], v[224:227], v[14:17]
	ds_read_b128 v[200:203], v244 offset:20800
	s_waitcnt lgkmcnt(7)
	v_mfma_f32_16x16x32_bf16 v[50:53], v[204:207], v[212:215], v[50:53]
	v_mfma_f32_16x16x32_bf16 v[54:57], v[204:207], v[216:219], v[54:57]
	v_mfma_f32_16x16x32_bf16 v[18:21], v[204:207], v[220:223], v[18:21]
	v_mfma_f32_16x16x32_bf16 v[22:25], v[204:207], v[224:227], v[22:25]
	ds_read_b128 v[204:207], v244 offset:23104
	s_waitcnt lgkmcnt(7)
	v_mfma_f32_16x16x32_bf16 v[58:61], v[208:211], v[212:215], v[58:61]
	v_mfma_f32_16x16x32_bf16 v[62:65], v[208:211], v[216:219], v[62:65]
	v_mfma_f32_16x16x32_bf16 v[26:29], v[208:211], v[220:223], v[26:29]
	v_mfma_f32_16x16x32_bf16 v[30:33], v[208:211], v[224:227], v[30:33]
	ds_read_b128 v[208:211], v244 offset:25408
	s_waitcnt lgkmcnt(3)
	v_mfma_f32_16x16x32_bf16 v[34:37], v[196:199], v[228:231], v[34:37]
	v_mfma_f32_16x16x32_bf16 v[38:41], v[196:199], v[232:235], v[38:41]
	v_mfma_f32_16x16x32_bf16 v[2:5], v[196:199], v[236:239], v[2:5]
	v_mfma_f32_16x16x32_bf16 v[6:9], v[196:199], v[240:243], v[6:9]
	s_waitcnt lgkmcnt(2)
	v_mfma_f32_16x16x32_bf16 v[42:45], v[200:203], v[228:231], v[42:45]
	v_mfma_f32_16x16x32_bf16 v[46:49], v[200:203], v[232:235], v[46:49]
	v_mfma_f32_16x16x32_bf16 v[10:13], v[200:203], v[236:239], v[10:13]
	v_mfma_f32_16x16x32_bf16 v[14:17], v[200:203], v[240:243], v[14:17]
	v_or_b32_e32 v66, s3, v88
	s_addk_i32 s3, 0xf000
	s_lshr_b32 s3, s3, 12
	s_cmp_lt_u32 s0, 32
	s_cselect_b64 vcc, -1, 0
	s_and_b64 s[4:5], vcc, exec
	s_mul_i32 s0, s3, 0xc00
	s_cselect_b32 s5, s17, s19
	s_cselect_b32 s4, s16, s18
	s_addk_i32 s0, 0xc00
	s_and_b64 s[12:13], vcc, exec
	s_cselect_b32 s0, 0, s0
	v_add_u32_e32 v72, 0xfffff000, v66
	v_cndmask_b32_e32 v72, v72, v66, vcc
	v_mov_b32_e32 v73, v67
	v_lshlrev_b64 v[72:73], 12, v[72:73]
	v_lshl_add_u64 v[78:79], s[4:5], 0, v[72:73]
	v_add_lshl_u32 v72, s2, v97, 2
	s_lshl_b64 s[2:3], s[0:1], 2
	s_add_u32 s0, s82, s2
	s_addc_u32 s3, s83, s3
	v_mov_b32_e32 v73, v67
	s_add_u32 s2, s0, 0xe958000
	v_lshl_add_u64 v[148:149], v[78:79], 0, v[72:73]
	s_addc_u32 s3, s3, 0
	v_or_b32_e32 v156, 0xe0, v72
	v_or_b32_e32 v157, 32, v72
	v_or_b32_e32 v158, 64, v72
	v_or_b32_e32 v159, 0x60, v72
	v_or_b32_e32 v160, 0x80, v72
	v_or_b32_e32 v161, 0xa0, v72
	v_or_b32_e32 v162, 0xc0, v72
	s_waitcnt lgkmcnt(0)
	s_barrier
	v_mfma_f32_16x16x32_bf16 v[50:53], v[204:207], v[228:231], v[50:53]
	v_mfma_f32_16x16x32_bf16 v[54:57], v[204:207], v[232:235], v[54:57]
	v_mfma_f32_16x16x32_bf16 v[18:21], v[204:207], v[236:239], v[18:21]
	v_mfma_f32_16x16x32_bf16 v[22:25], v[204:207], v[240:243], v[22:25]
	v_mfma_f32_16x16x32_bf16 v[58:61], v[208:211], v[228:231], v[58:61]
	v_mfma_f32_16x16x32_bf16 v[62:65], v[208:211], v[232:235], v[62:65]
	v_mfma_f32_16x16x32_bf16 v[26:29], v[208:211], v[236:239], v[26:29]
	v_mfma_f32_16x16x32_bf16 v[30:33], v[208:211], v[240:243], v[30:33]
	s_nop 7
	v_permlane16_swap_b32_e32 v34, v38
	v_permlane16_swap_b32_e32 v35, v39
	v_permlane16_swap_b32_e32 v36, v40
	v_permlane16_swap_b32_e32 v37, v41
	v_permlane16_swap_b32_e32 v42, v46
	v_permlane16_swap_b32_e32 v43, v47
	v_permlane16_swap_b32_e32 v44, v48
	v_permlane16_swap_b32_e32 v45, v49
	v_permlane16_swap_b32_e32 v2, v6
	v_permlane16_swap_b32_e32 v3, v7
	v_permlane16_swap_b32_e32 v4, v8
	v_permlane16_swap_b32_e32 v5, v9
	v_permlane16_swap_b32_e32 v10, v14
	v_permlane16_swap_b32_e32 v11, v15
	v_permlane16_swap_b32_e32 v12, v16
	v_permlane16_swap_b32_e32 v13, v17
	v_permlane16_swap_b32_e32 v50, v54
	v_permlane16_swap_b32_e32 v51, v55
	v_permlane16_swap_b32_e32 v52, v56
	v_permlane16_swap_b32_e32 v53, v57
	v_permlane16_swap_b32_e32 v58, v62
	v_permlane16_swap_b32_e32 v59, v63
	v_permlane16_swap_b32_e32 v60, v64
	v_permlane16_swap_b32_e32 v61, v65
	v_permlane16_swap_b32_e32 v18, v22
	v_permlane16_swap_b32_e32 v19, v23
	v_permlane16_swap_b32_e32 v20, v24
	v_permlane16_swap_b32_e32 v21, v25
	v_permlane16_swap_b32_e32 v26, v30
	v_permlane16_swap_b32_e32 v27, v31
	v_permlane16_swap_b32_e32 v28, v32
	v_permlane16_swap_b32_e32 v29, v33
	v_permlane32_swap_b32_e32 v34, v38
	v_permlane32_swap_b32_e32 v35, v39
	v_permlane32_swap_b32_e32 v36, v40
	v_permlane32_swap_b32_e32 v37, v41
	v_permlane32_swap_b32_e32 v42, v46
	v_permlane32_swap_b32_e32 v43, v47
	v_permlane32_swap_b32_e32 v44, v48
	v_permlane32_swap_b32_e32 v45, v49
	v_permlane32_swap_b32_e32 v2, v6
	v_permlane32_swap_b32_e32 v3, v7
	v_permlane32_swap_b32_e32 v4, v8
	v_permlane32_swap_b32_e32 v5, v9
	v_permlane32_swap_b32_e32 v10, v14
	v_permlane32_swap_b32_e32 v11, v15
	v_permlane32_swap_b32_e32 v12, v16
	v_permlane32_swap_b32_e32 v13, v17
	v_permlane32_swap_b32_e32 v50, v54
	v_permlane32_swap_b32_e32 v51, v55
	v_permlane32_swap_b32_e32 v52, v56
	v_permlane32_swap_b32_e32 v53, v57
	v_permlane32_swap_b32_e32 v58, v62
	v_permlane32_swap_b32_e32 v59, v63
	v_permlane32_swap_b32_e32 v60, v64
	v_permlane32_swap_b32_e32 v61, v65
	v_permlane32_swap_b32_e32 v18, v22
	v_permlane32_swap_b32_e32 v19, v23
	v_permlane32_swap_b32_e32 v20, v24
	v_permlane32_swap_b32_e32 v21, v25
	v_permlane32_swap_b32_e32 v26, v30
	v_permlane32_swap_b32_e32 v27, v31
	v_permlane32_swap_b32_e32 v28, v32
	v_permlane32_swap_b32_e32 v29, v33
	global_load_dwordx4 v[102:105], v[148:149], off offset:224
	s_add_i32 s11, s11, 1
	s_mul_i32 s0, s11, s7
	s_add_i32 s10, s10, s7
	global_load_dwordx4 v[84:87], v156, s[2:3]
	global_load_dwordx4 v[78:81], v[148:149], off offset:192
	v_lshlrev_b64 v[82:83], 12, v[66:67]
	v_lshl_add_u64 v[82:83], s[80:81], 0, v[82:83]
	v_lshl_add_u64 v[82:83], v[82:83], 0, v[72:73]
	s_waitcnt vmcnt(1)
	v_pk_fma_f32 v[64:65], v[64:65], v[86:87], v[104:105]
	global_load_dwordx4 v[74:77], v162, s[2:3]
	global_load_dwordx4 v[98:101], v[148:149], off offset:160
	global_load_dwordx4 v[106:109], v161, s[2:3]
	global_load_dwordx4 v[110:113], v[148:149], off offset:128
	global_load_dwordx4 v[114:117], v160, s[2:3]
	global_load_dwordx4 v[118:121], v[148:149], off offset:96
	global_load_dwordx4 v[122:125], v159, s[2:3]
	global_load_dwordx4 v[126:129], v[148:149], off offset:64
	global_load_dwordx4 v[136:139], v158, s[2:3]
	global_load_dwordx4 v[140:143], v[148:149], off offset:32
	global_load_dwordx4 v[144:147], v157, s[2:3]
	v_or_b32_e32 v86, 32, v66
	global_load_dwordx4 v[148:151], v[148:149], off
	v_pk_fma_f32 v[62:63], v[62:63], v[84:85], v[102:103]
	global_load_dwordx4 v[152:155], v72, s[2:3]
	v_mov_b32_e32 v87, v67
	global_store_dwordx4 v[82:83], v[62:65], off offset:224
	s_waitcnt vmcnt(13)
	v_pk_fma_f32 v[58:59], v[58:59], v[74:75], v[78:79]
	v_pk_fma_f32 v[60:61], v[60:61], v[76:77], v[80:81]
	s_waitcnt vmcnt(11)
	v_pk_fma_f32 v[54:55], v[54:55], v[106:107], v[98:99]
	v_pk_fma_f32 v[56:57], v[56:57], v[108:109], v[100:101]
	s_waitcnt vmcnt(9)
	v_pk_fma_f32 v[50:51], v[50:51], v[114:115], v[110:111]
	v_pk_fma_f32 v[52:53], v[52:53], v[116:117], v[112:113]
	s_waitcnt vmcnt(7)
	v_pk_fma_f32 v[46:47], v[46:47], v[122:123], v[118:119]
	v_pk_fma_f32 v[48:49], v[48:49], v[124:125], v[120:121]
	s_waitcnt vmcnt(5)
	v_pk_fma_f32 v[42:43], v[42:43], v[136:137], v[126:127]
	v_pk_fma_f32 v[44:45], v[44:45], v[138:139], v[128:129]
	s_waitcnt vmcnt(3)
	v_pk_fma_f32 v[38:39], v[38:39], v[144:145], v[140:141]
	v_pk_fma_f32 v[40:41], v[40:41], v[146:147], v[142:143]
	global_store_dwordx4 v[82:83], v[38:41], off offset:32
	global_store_dwordx4 v[82:83], v[42:45], off offset:64
	s_waitcnt vmcnt(3)
	v_pk_fma_f32 v[34:35], v[34:35], v[152:153], v[148:149]
	v_pk_fma_f32 v[36:37], v[36:37], v[154:155], v[150:151]
	global_store_dwordx4 v[82:83], v[34:37], off
	global_store_dwordx4 v[82:83], v[46:49], off offset:96
	global_store_dwordx4 v[82:83], v[50:53], off offset:128
	v_add_u32_e32 v34, 0xfffff020, v66
	v_cndmask_b32_e32 v66, v34, v86, vcc
	v_lshlrev_b64 v[34:35], 12, v[66:67]
	v_lshl_add_u64 v[34:35], s[4:5], 0, v[34:35]
	global_store_dwordx4 v[82:83], v[54:57], off offset:160
	global_store_dwordx4 v[82:83], v[58:61], off offset:192
	v_lshl_add_u64 v[118:119], v[34:35], 0, v[72:73]
	global_load_dwordx4 v[34:37], v[118:119], off offset:224
	global_load_dwordx4 v[38:41], v156, s[2:3]
	global_load_dwordx4 v[42:45], v[118:119], off offset:192
	global_load_dwordx4 v[46:49], v162, s[2:3]
	global_load_dwordx4 v[50:53], v[118:119], off offset:160
	global_load_dwordx4 v[54:57], v161, s[2:3]
	global_load_dwordx4 v[58:61], v[118:119], off offset:128
	global_load_dwordx4 v[62:65], v160, s[2:3]
	global_load_dwordx4 v[74:77], v[118:119], off offset:96
	global_load_dwordx4 v[78:81], v159, s[2:3]
	global_load_dwordx4 v[82:85], v[118:119], off offset:64
	global_load_dwordx4 v[98:101], v158, s[2:3]
	global_load_dwordx4 v[102:105], v[118:119], off offset:32
	global_load_dwordx4 v[106:109], v157, s[2:3]
	global_load_dwordx4 v[110:113], v[118:119], off
	global_load_dwordx4 v[114:117], v72, s[2:3]
	v_lshlrev_b64 v[86:87], 12, v[86:87]
	v_lshl_add_u64 v[86:87], s[80:81], 0, v[86:87]
	s_add_i32 s2, s0, s6
	v_lshl_add_u64 v[72:73], v[86:87], 0, v[72:73]
	s_cmpk_lt_u32 s10, 0x60
	s_waitcnt vmcnt(14)
	v_pk_fma_f32 v[30:31], v[30:31], v[38:39], v[34:35]
	v_pk_fma_f32 v[32:33], v[32:33], v[40:41], v[36:37]
	s_waitcnt vmcnt(12)
	v_pk_fma_f32 v[26:27], v[26:27], v[46:47], v[42:43]
	v_pk_fma_f32 v[28:29], v[28:29], v[48:49], v[44:45]
	s_waitcnt vmcnt(10)
	v_pk_fma_f32 v[22:23], v[22:23], v[54:55], v[50:51]
	v_pk_fma_f32 v[24:25], v[24:25], v[56:57], v[52:53]
	s_waitcnt vmcnt(8)
	v_pk_fma_f32 v[18:19], v[18:19], v[62:63], v[58:59]
	v_pk_fma_f32 v[20:21], v[20:21], v[64:65], v[60:61]
	s_waitcnt vmcnt(6)
	v_pk_fma_f32 v[14:15], v[14:15], v[78:79], v[74:75]
	v_pk_fma_f32 v[16:17], v[16:17], v[80:81], v[76:77]
	s_waitcnt vmcnt(4)
	v_pk_fma_f32 v[10:11], v[10:11], v[98:99], v[82:83]
	v_pk_fma_f32 v[12:13], v[12:13], v[100:101], v[84:85]
	s_waitcnt vmcnt(2)
	v_pk_fma_f32 v[6:7], v[6:7], v[106:107], v[102:103]
	v_pk_fma_f32 v[8:9], v[8:9], v[108:109], v[104:105]
	s_waitcnt vmcnt(0)
	v_pk_fma_f32 v[2:3], v[2:3], v[114:115], v[110:111]
	v_pk_fma_f32 v[4:5], v[4:5], v[116:117], v[112:113]
	global_store_dwordx4 v[72:73], v[2:5], off
	global_store_dwordx4 v[72:73], v[6:9], off offset:32
	global_store_dwordx4 v[72:73], v[10:13], off offset:64
	global_store_dwordx4 v[72:73], v[14:17], off offset:96
	global_store_dwordx4 v[72:73], v[18:21], off offset:128
	global_store_dwordx4 v[72:73], v[22:25], off offset:160
	global_store_dwordx4 v[72:73], v[26:29], off offset:192
	global_store_dwordx4 v[72:73], v[30:33], off offset:224
	s_cbranch_scc1 .LBB0_979

.LBB0_1149:
	v_ashrrev_i32_e32 v3, 31, v2
	v_lshlrev_b64 v[2:3], 11, v[2:3]
	v_lshl_add_u64 v[70:71], v[86:87], 0, v[2:3]
	v_or_b32_e32 v2, s56, v154
	v_ashrrev_i32_e32 v3, 31, v2
	v_lshlrev_b64 v[2:3], 11, v[2:3]
	v_lshl_add_u64 v[72:73], v[84:85], 0, v[2:3]
	v_add_u32_e32 v2, s56, v155
	v_ashrrev_i32_e32 v3, 31, v2
	v_lshlrev_b64 v[2:3], 11, v[2:3]
	v_lshl_add_u64 v[74:75], v[84:85], 0, v[2:3]
	v_add_u32_e32 v2, s56, v156
	v_ashrrev_i32_e32 v3, 31, v2
	v_lshlrev_b64 v[2:3], 11, v[2:3]
	v_lshl_add_u64 v[76:77], v[84:85], 0, v[2:3]
	v_add_u32_e32 v2, s56, v157
	v_ashrrev_i32_e32 v3, 31, v2
	v_ashrrev_i32_e32 v9, 31, v8
	v_ashrrev_i32_e32 v5, 31, v4
	v_lshlrev_b64 v[2:3], 11, v[2:3]
	v_ashrrev_i32_e32 v7, 31, v6
	v_lshlrev_b64 v[8:9], 11, v[8:9]
	v_lshlrev_b64 v[4:5], 11, v[4:5]
	v_lshl_add_u64 v[78:79], v[84:85], 0, v[2:3]
	v_lshlrev_b64 v[2:3], 11, v[6:7]
	v_lshl_add_u64 v[66:67], v[86:87], 0, v[8:9]
	v_lshl_add_u64 v[68:69], v[86:87], 0, v[4:5]
	v_lshl_add_u64 v[80:81], v[86:87], 0, v[2:3]
	global_load_dwordx4 v[2:5], v[70:71], off
	global_load_dwordx4 v[6:9], v[68:69], off
	global_load_dwordx4 v[10:13], v[66:67], off
	global_load_dwordx4 v[14:17], v[80:81], off
	global_load_dwordx4 v[18:21], v[72:73], off
	global_load_dwordx4 v[22:25], v[74:75], off
	global_load_dwordx4 v[26:29], v[76:77], off
	global_load_dwordx4 v[30:33], v[78:79], off
	global_load_dwordx4 v[122:125], v[70:71], off offset:128
	global_load_dwordx4 v[126:129], v[68:69], off offset:128
	global_load_dwordx4 v[136:139], v[66:67], off offset:128
	global_load_dwordx4 v[140:143], v[80:81], off offset:128
	global_load_dwordx4 v[144:147], v[72:73], off offset:128
	global_load_dwordx4 v[148:151], v[74:75], off offset:128
	global_load_dwordx4 v[172:175], v[76:77], off offset:128
	global_load_dwordx4 v[176:179], v[78:79], off offset:128
	s_waitcnt vmcnt(15)
	ds_write_b128 v164, v[2:5] offset:36864
	s_waitcnt vmcnt(14)
	ds_write_b128 v164, v[6:9] offset:41472
	s_waitcnt vmcnt(13)
	ds_write_b128 v164, v[10:13] offset:46080
	s_waitcnt vmcnt(12)
	ds_write_b128 v164, v[14:17] offset:50688
	s_waitcnt vmcnt(11)
	ds_write_b128 v164, v[18:21]
	s_waitcnt vmcnt(10)
	ds_write_b128 v164, v[22:25] offset:4608
	s_waitcnt vmcnt(9)
	ds_write_b128 v164, v[26:29] offset:9216
	s_waitcnt vmcnt(8)
	ds_write_b128 v164, v[30:33] offset:13824
	s_waitcnt lgkmcnt(0)
	s_barrier
	global_load_dwordx4 v[180:183], v[74:75], off offset:256
	global_load_dwordx4 v[188:191], v[76:77], off offset:256
	global_load_dwordx4 v[192:195], v[72:73], off offset:256
	global_load_dwordx4 v[196:199], v[70:71], off offset:256
	global_load_dwordx4 v[200:203], v[68:69], off offset:256
	global_load_dwordx4 v[204:207], v[66:67], off offset:256
	global_load_dwordx4 v[208:211], v[78:79], off offset:256
	global_load_dwordx4 v[212:215], v[80:81], off offset:256
	v_and_b32_e32 v246, 15, v1
	v_add_u32_e32 v246, 4, v246
	v_bfe_u32 v246, v246, 3, 1
	v_bfe_u32 v249, v1, 4, 2
	v_xor_b32_e32 v246, v246, v249
	v_bfe_u32 v249, v1, 5, 1
	v_sub_u32_e32 v246, v246, v249
	v_lshlrev_b32_e32 v246, 4, v246
	v_bfe_u32 v249, v1, 4, 1
	v_mul_u32_u24_e32 v249, 0x900, v249
	v_sub_u32_e32 v246, v246, v249
	v_add_u32_e32 v244, v246, v161
	v_add_u32_e32 v245, v246, v163
	ds_read_b128 v[232:235], v245 offset:36864
	ds_read_b128 v[216:219], v244
	ds_read_b128 v[236:239], v245 offset:39168
	ds_read_b128 v[240:243], v245 offset:41472
	ds_read_b128 v[252:255], v245 offset:43776
	ds_read_b128 v[220:223], v244 offset:2304
	ds_read_b128 v[224:227], v244 offset:4608
	ds_read_b128 v[228:231], v244 offset:6912
	s_waitcnt lgkmcnt(6)
	v_mfma_f32_16x16x32_bf16 v[50:53], v[216:219], v[232:235], 0
	s_waitcnt lgkmcnt(5)
	v_mfma_f32_16x16x32_bf16 v[54:57], v[216:219], v[236:239], 0
	s_waitcnt lgkmcnt(4)
	v_mfma_f32_16x16x32_bf16 v[34:37], v[216:219], v[240:243], 0
	s_waitcnt lgkmcnt(3)
	v_mfma_f32_16x16x32_bf16 v[38:41], v[216:219], v[252:255], 0
	ds_read_b128 v[216:219], v244 offset:64
	s_waitcnt lgkmcnt(3)
	v_mfma_f32_16x16x32_bf16 v[58:61], v[220:223], v[232:235], 0
	v_mfma_f32_16x16x32_bf16 v[62:65], v[220:223], v[236:239], 0
	v_mfma_f32_16x16x32_bf16 v[42:45], v[220:223], v[240:243], 0
	v_mfma_f32_16x16x32_bf16 v[46:49], v[220:223], v[252:255], 0
	ds_read_b128 v[220:223], v244 offset:2368
	s_setprio 1
	s_waitcnt vmcnt(11)
	ds_write_b128 v164, v[144:147] offset:18432
	s_waitcnt vmcnt(10)
	ds_write_b128 v164, v[148:151] offset:23040
	s_waitcnt lgkmcnt(5)
	v_mfma_f32_16x16x32_bf16 v[18:21], v[224:227], v[232:235], 0
	v_mfma_f32_16x16x32_bf16 v[22:25], v[224:227], v[236:239], 0
	v_mfma_f32_16x16x32_bf16 v[2:5], v[224:227], v[240:243], 0
	v_mfma_f32_16x16x32_bf16 v[6:9], v[224:227], v[252:255], 0
	ds_read_b128 v[224:227], v244 offset:4672
	s_waitcnt vmcnt(9)
	ds_write_b128 v164, v[172:175] offset:27648
	s_waitcnt vmcnt(8)
	ds_write_b128 v164, v[176:179] offset:32256
	s_waitcnt lgkmcnt(7)
	v_mfma_f32_16x16x32_bf16 v[26:29], v[228:231], v[232:235], 0
	ds_read_b128 v[232:235], v245 offset:36928
	v_mfma_f32_16x16x32_bf16 v[30:33], v[228:231], v[236:239], 0
	ds_read_b128 v[236:239], v245 offset:39232
	v_mfma_f32_16x16x32_bf16 v[10:13], v[228:231], v[240:243], 0
	ds_read_b128 v[240:243], v245 offset:41536
	v_mfma_f32_16x16x32_bf16 v[14:17], v[228:231], v[252:255], 0
	ds_read_b128 v[252:255], v245 offset:43840
	ds_read_b128 v[228:231], v244 offset:6976
	s_waitcnt lgkmcnt(4)
	v_mfma_f32_16x16x32_bf16 v[50:53], v[216:219], v[232:235], v[50:53]
	s_waitcnt lgkmcnt(3)
	v_mfma_f32_16x16x32_bf16 v[54:57], v[216:219], v[236:239], v[54:57]
	s_waitcnt lgkmcnt(2)
	v_mfma_f32_16x16x32_bf16 v[34:37], v[216:219], v[240:243], v[34:37]
	s_waitcnt lgkmcnt(1)
	v_mfma_f32_16x16x32_bf16 v[38:41], v[216:219], v[252:255], v[38:41]
	ds_write_b128 v164, v[122:125] offset:55296
	ds_write_b128 v164, v[126:129] offset:59904
	v_mfma_f32_16x16x32_bf16 v[58:61], v[220:223], v[232:235], v[58:61]
	v_mfma_f32_16x16x32_bf16 v[62:65], v[220:223], v[236:239], v[62:65]
	v_mfma_f32_16x16x32_bf16 v[42:45], v[220:223], v[240:243], v[42:45]
	v_mfma_f32_16x16x32_bf16 v[46:49], v[220:223], v[252:255], v[46:49]
	ds_write_b128 v164, v[136:139] offset:64512
	ds_write_b128 v165, v[140:143] offset:32256
	v_mfma_f32_16x16x32_bf16 v[18:21], v[224:227], v[232:235], v[18:21]
	v_mfma_f32_16x16x32_bf16 v[22:25], v[224:227], v[236:239], v[22:25]
	v_mfma_f32_16x16x32_bf16 v[2:5], v[224:227], v[240:243], v[2:5]
	v_mfma_f32_16x16x32_bf16 v[6:9], v[224:227], v[252:255], v[6:9]
	s_waitcnt lgkmcnt(4)
	v_mfma_f32_16x16x32_bf16 v[26:29], v[228:231], v[232:235], v[26:29]
	v_mfma_f32_16x16x32_bf16 v[30:33], v[228:231], v[236:239], v[30:33]
	v_mfma_f32_16x16x32_bf16 v[10:13], v[228:231], v[240:243], v[10:13]
	v_mfma_f32_16x16x32_bf16 v[14:17], v[228:231], v[252:255], v[14:17]
	s_waitcnt lgkmcnt(0)
	s_barrier
	s_setprio 0
	global_load_dwordx4 v[122:125], v[72:73], off offset:384
	global_load_dwordx4 v[126:129], v[74:75], off offset:384
	global_load_dwordx4 v[136:139], v[76:77], off offset:384
	global_load_dwordx4 v[140:143], v[78:79], off offset:384
	global_load_dwordx4 v[144:147], v[70:71], off offset:384
	global_load_dwordx4 v[148:151], v[68:69], off offset:384
	global_load_dwordx4 v[172:175], v[66:67], off offset:384
	global_load_dwordx4 v[176:179], v[80:81], off offset:384
	ds_read_b128 v[232:235], v245 offset:55296
	ds_read_b128 v[216:219], v244 offset:18432
	ds_read_b128 v[236:239], v245 offset:57600
	ds_read_b128 v[240:243], v245 offset:59904
	ds_read_b128 v[252:255], v245 offset:62208
	ds_read_b128 v[220:223], v244 offset:20736
	ds_read_b128 v[224:227], v244 offset:23040
	ds_read_b128 v[228:231], v244 offset:25344
	s_waitcnt lgkmcnt(6)
	v_mfma_f32_16x16x32_bf16 v[50:53], v[216:219], v[232:235], v[50:53]
	s_waitcnt lgkmcnt(5)
	v_mfma_f32_16x16x32_bf16 v[54:57], v[216:219], v[236:239], v[54:57]
	s_waitcnt lgkmcnt(4)
	v_mfma_f32_16x16x32_bf16 v[34:37], v[216:219], v[240:243], v[34:37]
	s_waitcnt lgkmcnt(3)
	v_mfma_f32_16x16x32_bf16 v[38:41], v[216:219], v[252:255], v[38:41]
	ds_read_b128 v[216:219], v244 offset:18496
	s_waitcnt lgkmcnt(3)
	v_mfma_f32_16x16x32_bf16 v[58:61], v[220:223], v[232:235], v[58:61]
	v_mfma_f32_16x16x32_bf16 v[62:65], v[220:223], v[236:239], v[62:65]
	v_mfma_f32_16x16x32_bf16 v[42:45], v[220:223], v[240:243], v[42:45]
	v_mfma_f32_16x16x32_bf16 v[46:49], v[220:223], v[252:255], v[46:49]
	ds_read_b128 v[220:223], v244 offset:20800
	s_setprio 1
	s_waitcnt vmcnt(13)
	ds_write_b128 v164, v[192:195]
	ds_write_b128 v164, v[180:183] offset:4608
	s_waitcnt lgkmcnt(5)
	v_mfma_f32_16x16x32_bf16 v[18:21], v[224:227], v[232:235], v[18:21]
	v_mfma_f32_16x16x32_bf16 v[22:25], v[224:227], v[236:239], v[22:25]
	v_mfma_f32_16x16x32_bf16 v[2:5], v[224:227], v[240:243], v[2:5]
	v_mfma_f32_16x16x32_bf16 v[6:9], v[224:227], v[252:255], v[6:9]
	ds_read_b128 v[224:227], v244 offset:23104
	ds_write_b128 v164, v[188:191] offset:9216
	s_waitcnt vmcnt(9)
	ds_write_b128 v164, v[208:211] offset:13824
	s_waitcnt lgkmcnt(7)
	v_mfma_f32_16x16x32_bf16 v[26:29], v[228:231], v[232:235], v[26:29]
	ds_read_b128 v[232:235], v245 offset:55360
	v_mfma_f32_16x16x32_bf16 v[30:33], v[228:231], v[236:239], v[30:33]
	ds_read_b128 v[236:239], v245 offset:57664
	v_mfma_f32_16x16x32_bf16 v[10:13], v[228:231], v[240:243], v[10:13]
	ds_read_b128 v[240:243], v245 offset:59968
	v_mfma_f32_16x16x32_bf16 v[14:17], v[228:231], v[252:255], v[14:17]
	ds_read_b128 v[252:255], v245 offset:62272
	ds_read_b128 v[228:231], v244 offset:25408
	s_waitcnt lgkmcnt(4)
	v_mfma_f32_16x16x32_bf16 v[50:53], v[216:219], v[232:235], v[50:53]
	s_waitcnt lgkmcnt(3)
	v_mfma_f32_16x16x32_bf16 v[54:57], v[216:219], v[236:239], v[54:57]
	s_waitcnt lgkmcnt(2)
	v_mfma_f32_16x16x32_bf16 v[34:37], v[216:219], v[240:243], v[34:37]
	s_waitcnt lgkmcnt(1)
	v_mfma_f32_16x16x32_bf16 v[38:41], v[216:219], v[252:255], v[38:41]
	ds_write_b128 v164, v[196:199] offset:36864
	ds_write_b128 v164, v[200:203] offset:41472
	v_mfma_f32_16x16x32_bf16 v[58:61], v[220:223], v[232:235], v[58:61]
	v_mfma_f32_16x16x32_bf16 v[62:65], v[220:223], v[236:239], v[62:65]
	v_mfma_f32_16x16x32_bf16 v[42:45], v[220:223], v[240:243], v[42:45]
	v_mfma_f32_16x16x32_bf16 v[46:49], v[220:223], v[252:255], v[46:49]
	ds_write_b128 v164, v[204:207] offset:46080
	s_waitcnt vmcnt(8)
	ds_write_b128 v164, v[212:215] offset:50688
	v_mfma_f32_16x16x32_bf16 v[18:21], v[224:227], v[232:235], v[18:21]
	v_mfma_f32_16x16x32_bf16 v[22:25], v[224:227], v[236:239], v[22:25]
	v_mfma_f32_16x16x32_bf16 v[2:5], v[224:227], v[240:243], v[2:5]
	v_mfma_f32_16x16x32_bf16 v[6:9], v[224:227], v[252:255], v[6:9]
	s_waitcnt lgkmcnt(4)
	v_mfma_f32_16x16x32_bf16 v[26:29], v[228:231], v[232:235], v[26:29]
	v_mfma_f32_16x16x32_bf16 v[30:33], v[228:231], v[236:239], v[30:33]
	v_mfma_f32_16x16x32_bf16 v[10:13], v[228:231], v[240:243], v[10:13]
	v_mfma_f32_16x16x32_bf16 v[14:17], v[228:231], v[252:255], v[14:17]
	s_waitcnt lgkmcnt(0)
	s_barrier
	s_setprio 0
	global_load_dwordx4 v[180:183], v[72:73], off offset:512
	global_load_dwordx4 v[188:191], v[74:75], off offset:512
	global_load_dwordx4 v[192:195], v[76:77], off offset:512
	global_load_dwordx4 v[196:199], v[78:79], off offset:512
	global_load_dwordx4 v[200:203], v[70:71], off offset:512
	global_load_dwordx4 v[204:207], v[68:69], off offset:512
	global_load_dwordx4 v[208:211], v[66:67], off offset:512
	global_load_dwordx4 v[212:215], v[80:81], off offset:512
	ds_read_b128 v[232:235], v245 offset:36864
	ds_read_b128 v[216:219], v244
	ds_read_b128 v[236:239], v245 offset:39168
	ds_read_b128 v[240:243], v245 offset:41472
	ds_read_b128 v[252:255], v245 offset:43776
	ds_read_b128 v[220:223], v244 offset:2304
	ds_read_b128 v[224:227], v244 offset:4608
	ds_read_b128 v[228:231], v244 offset:6912
	s_waitcnt lgkmcnt(6)
	v_mfma_f32_16x16x32_bf16 v[50:53], v[216:219], v[232:235], v[50:53]
	s_waitcnt lgkmcnt(5)
	v_mfma_f32_16x16x32_bf16 v[54:57], v[216:219], v[236:239], v[54:57]
	s_waitcnt lgkmcnt(4)
	v_mfma_f32_16x16x32_bf16 v[34:37], v[216:219], v[240:243], v[34:37]
	s_waitcnt lgkmcnt(3)
	v_mfma_f32_16x16x32_bf16 v[38:41], v[216:219], v[252:255], v[38:41]
	ds_read_b128 v[216:219], v244 offset:64
	s_waitcnt lgkmcnt(3)
	v_mfma_f32_16x16x32_bf16 v[58:61], v[220:223], v[232:235], v[58:61]
	v_mfma_f32_16x16x32_bf16 v[62:65], v[220:223], v[236:239], v[62:65]
	v_mfma_f32_16x16x32_bf16 v[42:45], v[220:223], v[240:243], v[42:45]
	v_mfma_f32_16x16x32_bf16 v[46:49], v[220:223], v[252:255], v[46:49]
	ds_read_b128 v[220:223], v244 offset:2368
	s_setprio 1
	s_waitcnt vmcnt(15)
	ds_write_b128 v164, v[122:125] offset:18432
	s_waitcnt vmcnt(14)
	ds_write_b128 v164, v[126:129] offset:23040
	s_waitcnt lgkmcnt(5)
	v_mfma_f32_16x16x32_bf16 v[18:21], v[224:227], v[232:235], v[18:21]
	v_mfma_f32_16x16x32_bf16 v[22:25], v[224:227], v[236:239], v[22:25]
	v_mfma_f32_16x16x32_bf16 v[2:5], v[224:227], v[240:243], v[2:5]
	v_mfma_f32_16x16x32_bf16 v[6:9], v[224:227], v[252:255], v[6:9]
	ds_read_b128 v[224:227], v244 offset:4672
	s_waitcnt vmcnt(13)
	ds_write_b128 v164, v[136:139] offset:27648
	s_waitcnt vmcnt(12)
	ds_write_b128 v164, v[140:143] offset:32256
	s_waitcnt lgkmcnt(7)
	v_mfma_f32_16x16x32_bf16 v[26:29], v[228:231], v[232:235], v[26:29]
	ds_read_b128 v[232:235], v245 offset:36928
	v_mfma_f32_16x16x32_bf16 v[30:33], v[228:231], v[236:239], v[30:33]
	ds_read_b128 v[236:239], v245 offset:39232
	v_mfma_f32_16x16x32_bf16 v[10:13], v[228:231], v[240:243], v[10:13]
	ds_read_b128 v[240:243], v245 offset:41536
	v_mfma_f32_16x16x32_bf16 v[14:17], v[228:231], v[252:255], v[14:17]
	ds_read_b128 v[252:255], v245 offset:43840
	ds_read_b128 v[228:231], v244 offset:6976
	s_waitcnt lgkmcnt(4)
	v_mfma_f32_16x16x32_bf16 v[50:53], v[216:219], v[232:235], v[50:53]
	s_waitcnt lgkmcnt(3)
	v_mfma_f32_16x16x32_bf16 v[54:57], v[216:219], v[236:239], v[54:57]
	s_waitcnt lgkmcnt(2)
	v_mfma_f32_16x16x32_bf16 v[34:37], v[216:219], v[240:243], v[34:37]
	s_waitcnt lgkmcnt(1)
	v_mfma_f32_16x16x32_bf16 v[38:41], v[216:219], v[252:255], v[38:41]
	s_waitcnt vmcnt(11)
	ds_write_b128 v164, v[144:147] offset:55296
	s_waitcnt vmcnt(10)
	ds_write_b128 v164, v[148:151] offset:59904
	v_mfma_f32_16x16x32_bf16 v[58:61], v[220:223], v[232:235], v[58:61]
	v_mfma_f32_16x16x32_bf16 v[62:65], v[220:223], v[236:239], v[62:65]
	v_mfma_f32_16x16x32_bf16 v[42:45], v[220:223], v[240:243], v[42:45]
	v_mfma_f32_16x16x32_bf16 v[46:49], v[220:223], v[252:255], v[46:49]
	s_waitcnt vmcnt(9)
	ds_write_b128 v164, v[172:175] offset:64512
	s_waitcnt vmcnt(8)
	ds_write_b128 v165, v[176:179] offset:32256
	v_mfma_f32_16x16x32_bf16 v[18:21], v[224:227], v[232:235], v[18:21]
	v_mfma_f32_16x16x32_bf16 v[22:25], v[224:227], v[236:239], v[22:25]
	v_mfma_f32_16x16x32_bf16 v[2:5], v[224:227], v[240:243], v[2:5]
	v_mfma_f32_16x16x32_bf16 v[6:9], v[224:227], v[252:255], v[6:9]
	s_waitcnt lgkmcnt(4)
	v_mfma_f32_16x16x32_bf16 v[26:29], v[228:231], v[232:235], v[26:29]
	v_mfma_f32_16x16x32_bf16 v[30:33], v[228:231], v[236:239], v[30:33]
	v_mfma_f32_16x16x32_bf16 v[10:13], v[228:231], v[240:243], v[10:13]
	v_mfma_f32_16x16x32_bf16 v[14:17], v[228:231], v[252:255], v[14:17]
	s_waitcnt lgkmcnt(0)
	s_barrier
	s_setprio 0
	global_load_dwordx4 v[122:125], v[72:73], off offset:640
	global_load_dwordx4 v[126:129], v[74:75], off offset:640
	global_load_dwordx4 v[136:139], v[76:77], off offset:640
	global_load_dwordx4 v[140:143], v[78:79], off offset:640
	global_load_dwordx4 v[144:147], v[70:71], off offset:640
	global_load_dwordx4 v[148:151], v[68:69], off offset:640
	global_load_dwordx4 v[172:175], v[66:67], off offset:640
	global_load_dwordx4 v[176:179], v[80:81], off offset:640
	ds_read_b128 v[232:235], v245 offset:55296
	ds_read_b128 v[216:219], v244 offset:18432
	ds_read_b128 v[236:239], v245 offset:57600
	ds_read_b128 v[240:243], v245 offset:59904
	ds_read_b128 v[252:255], v245 offset:62208
	ds_read_b128 v[220:223], v244 offset:20736
	ds_read_b128 v[224:227], v244 offset:23040
	ds_read_b128 v[228:231], v244 offset:25344
	s_waitcnt lgkmcnt(6)
	v_mfma_f32_16x16x32_bf16 v[50:53], v[216:219], v[232:235], v[50:53]
	s_waitcnt lgkmcnt(5)
	v_mfma_f32_16x16x32_bf16 v[54:57], v[216:219], v[236:239], v[54:57]
	s_waitcnt lgkmcnt(4)
	v_mfma_f32_16x16x32_bf16 v[34:37], v[216:219], v[240:243], v[34:37]
	s_waitcnt lgkmcnt(3)
	v_mfma_f32_16x16x32_bf16 v[38:41], v[216:219], v[252:255], v[38:41]
	ds_read_b128 v[216:219], v244 offset:18496
	s_waitcnt lgkmcnt(3)
	v_mfma_f32_16x16x32_bf16 v[58:61], v[220:223], v[232:235], v[58:61]
	v_mfma_f32_16x16x32_bf16 v[62:65], v[220:223], v[236:239], v[62:65]
	v_mfma_f32_16x16x32_bf16 v[42:45], v[220:223], v[240:243], v[42:45]
	v_mfma_f32_16x16x32_bf16 v[46:49], v[220:223], v[252:255], v[46:49]
	ds_read_b128 v[220:223], v244 offset:20800
	s_setprio 1
	s_waitcnt vmcnt(15)
	ds_write_b128 v164, v[180:183]
	s_waitcnt vmcnt(14)
	ds_write_b128 v164, v[188:191] offset:4608
	s_waitcnt lgkmcnt(5)
	v_mfma_f32_16x16x32_bf16 v[18:21], v[224:227], v[232:235], v[18:21]
	v_mfma_f32_16x16x32_bf16 v[22:25], v[224:227], v[236:239], v[22:25]
	v_mfma_f32_16x16x32_bf16 v[2:5], v[224:227], v[240:243], v[2:5]
	v_mfma_f32_16x16x32_bf16 v[6:9], v[224:227], v[252:255], v[6:9]
	ds_read_b128 v[224:227], v244 offset:23104
	s_waitcnt vmcnt(13)
	ds_write_b128 v164, v[192:195] offset:9216
	s_waitcnt vmcnt(12)
	ds_write_b128 v164, v[196:199] offset:13824
	s_waitcnt lgkmcnt(7)
	v_mfma_f32_16x16x32_bf16 v[26:29], v[228:231], v[232:235], v[26:29]
	ds_read_b128 v[232:235], v245 offset:55360
	v_mfma_f32_16x16x32_bf16 v[30:33], v[228:231], v[236:239], v[30:33]
	ds_read_b128 v[236:239], v245 offset:57664
	v_mfma_f32_16x16x32_bf16 v[10:13], v[228:231], v[240:243], v[10:13]
	ds_read_b128 v[240:243], v245 offset:59968
	v_mfma_f32_16x16x32_bf16 v[14:17], v[228:231], v[252:255], v[14:17]
	ds_read_b128 v[252:255], v245 offset:62272
	ds_read_b128 v[228:231], v244 offset:25408
	s_waitcnt lgkmcnt(4)
	v_mfma_f32_16x16x32_bf16 v[50:53], v[216:219], v[232:235], v[50:53]
	s_waitcnt lgkmcnt(3)
	v_mfma_f32_16x16x32_bf16 v[54:57], v[216:219], v[236:239], v[54:57]
	s_waitcnt lgkmcnt(2)
	v_mfma_f32_16x16x32_bf16 v[34:37], v[216:219], v[240:243], v[34:37]
	s_waitcnt lgkmcnt(1)
	v_mfma_f32_16x16x32_bf16 v[38:41], v[216:219], v[252:255], v[38:41]
	s_waitcnt vmcnt(11)
	ds_write_b128 v164, v[200:203] offset:36864
	s_waitcnt vmcnt(10)
	ds_write_b128 v164, v[204:207] offset:41472
	v_mfma_f32_16x16x32_bf16 v[58:61], v[220:223], v[232:235], v[58:61]
	v_mfma_f32_16x16x32_bf16 v[62:65], v[220:223], v[236:239], v[62:65]
	v_mfma_f32_16x16x32_bf16 v[42:45], v[220:223], v[240:243], v[42:45]
	v_mfma_f32_16x16x32_bf16 v[46:49], v[220:223], v[252:255], v[46:49]
	s_waitcnt vmcnt(9)
	ds_write_b128 v164, v[208:211] offset:46080
	s_waitcnt vmcnt(8)
	ds_write_b128 v164, v[212:215] offset:50688
	v_mfma_f32_16x16x32_bf16 v[18:21], v[224:227], v[232:235], v[18:21]
	v_mfma_f32_16x16x32_bf16 v[22:25], v[224:227], v[236:239], v[22:25]
	v_mfma_f32_16x16x32_bf16 v[2:5], v[224:227], v[240:243], v[2:5]
	v_mfma_f32_16x16x32_bf16 v[6:9], v[224:227], v[252:255], v[6:9]
	s_waitcnt lgkmcnt(4)
	v_mfma_f32_16x16x32_bf16 v[26:29], v[228:231], v[232:235], v[26:29]
	v_mfma_f32_16x16x32_bf16 v[30:33], v[228:231], v[236:239], v[30:33]
	v_mfma_f32_16x16x32_bf16 v[10:13], v[228:231], v[240:243], v[10:13]
	v_mfma_f32_16x16x32_bf16 v[14:17], v[228:231], v[252:255], v[14:17]
	s_waitcnt lgkmcnt(0)
	s_barrier
	s_setprio 0
	global_load_dwordx4 v[180:183], v[72:73], off offset:768
	global_load_dwordx4 v[188:191], v[74:75], off offset:768
	global_load_dwordx4 v[192:195], v[76:77], off offset:768
	global_load_dwordx4 v[196:199], v[78:79], off offset:768
	global_load_dwordx4 v[200:203], v[70:71], off offset:768
	global_load_dwordx4 v[204:207], v[68:69], off offset:768
	global_load_dwordx4 v[208:211], v[66:67], off offset:768
	global_load_dwordx4 v[212:215], v[80:81], off offset:768
	ds_read_b128 v[232:235], v245 offset:36864
	ds_read_b128 v[216:219], v244
	ds_read_b128 v[236:239], v245 offset:39168
	ds_read_b128 v[240:243], v245 offset:41472
	ds_read_b128 v[252:255], v245 offset:43776
	ds_read_b128 v[220:223], v244 offset:2304
	ds_read_b128 v[224:227], v244 offset:4608
	ds_read_b128 v[228:231], v244 offset:6912
	s_waitcnt lgkmcnt(6)
	v_mfma_f32_16x16x32_bf16 v[50:53], v[216:219], v[232:235], v[50:53]
	s_waitcnt lgkmcnt(5)
	v_mfma_f32_16x16x32_bf16 v[54:57], v[216:219], v[236:239], v[54:57]
	s_waitcnt lgkmcnt(4)
	v_mfma_f32_16x16x32_bf16 v[34:37], v[216:219], v[240:243], v[34:37]
	s_waitcnt lgkmcnt(3)
	v_mfma_f32_16x16x32_bf16 v[38:41], v[216:219], v[252:255], v[38:41]
	ds_read_b128 v[216:219], v244 offset:64
	s_waitcnt lgkmcnt(3)
	v_mfma_f32_16x16x32_bf16 v[58:61], v[220:223], v[232:235], v[58:61]
	v_mfma_f32_16x16x32_bf16 v[62:65], v[220:223], v[236:239], v[62:65]
	v_mfma_f32_16x16x32_bf16 v[42:45], v[220:223], v[240:243], v[42:45]
	v_mfma_f32_16x16x32_bf16 v[46:49], v[220:223], v[252:255], v[46:49]
	ds_read_b128 v[220:223], v244 offset:2368
	s_setprio 1
	s_waitcnt vmcnt(15)
	ds_write_b128 v164, v[122:125] offset:18432
	s_waitcnt vmcnt(14)
	ds_write_b128 v164, v[126:129] offset:23040
	s_waitcnt lgkmcnt(5)
	v_mfma_f32_16x16x32_bf16 v[18:21], v[224:227], v[232:235], v[18:21]
	v_mfma_f32_16x16x32_bf16 v[22:25], v[224:227], v[236:239], v[22:25]
	v_mfma_f32_16x16x32_bf16 v[2:5], v[224:227], v[240:243], v[2:5]
	v_mfma_f32_16x16x32_bf16 v[6:9], v[224:227], v[252:255], v[6:9]
	ds_read_b128 v[224:227], v244 offset:4672
	s_waitcnt vmcnt(13)
	ds_write_b128 v164, v[136:139] offset:27648
	s_waitcnt vmcnt(12)
	ds_write_b128 v164, v[140:143] offset:32256
	s_waitcnt lgkmcnt(7)
	v_mfma_f32_16x16x32_bf16 v[26:29], v[228:231], v[232:235], v[26:29]
	ds_read_b128 v[232:235], v245 offset:36928
	v_mfma_f32_16x16x32_bf16 v[30:33], v[228:231], v[236:239], v[30:33]
	ds_read_b128 v[236:239], v245 offset:39232
	v_mfma_f32_16x16x32_bf16 v[10:13], v[228:231], v[240:243], v[10:13]
	ds_read_b128 v[240:243], v245 offset:41536
	v_mfma_f32_16x16x32_bf16 v[14:17], v[228:231], v[252:255], v[14:17]
	ds_read_b128 v[252:255], v245 offset:43840
	ds_read_b128 v[228:231], v244 offset:6976
	s_waitcnt lgkmcnt(4)
	v_mfma_f32_16x16x32_bf16 v[50:53], v[216:219], v[232:235], v[50:53]
	s_waitcnt lgkmcnt(3)
	v_mfma_f32_16x16x32_bf16 v[54:57], v[216:219], v[236:239], v[54:57]
	s_waitcnt lgkmcnt(2)
	v_mfma_f32_16x16x32_bf16 v[34:37], v[216:219], v[240:243], v[34:37]
	s_waitcnt lgkmcnt(1)
	v_mfma_f32_16x16x32_bf16 v[38:41], v[216:219], v[252:255], v[38:41]
	s_waitcnt vmcnt(11)
	ds_write_b128 v164, v[144:147] offset:55296
	s_waitcnt vmcnt(10)
	ds_write_b128 v164, v[148:151] offset:59904
	v_mfma_f32_16x16x32_bf16 v[58:61], v[220:223], v[232:235], v[58:61]
	v_mfma_f32_16x16x32_bf16 v[62:65], v[220:223], v[236:239], v[62:65]
	v_mfma_f32_16x16x32_bf16 v[42:45], v[220:223], v[240:243], v[42:45]
	v_mfma_f32_16x16x32_bf16 v[46:49], v[220:223], v[252:255], v[46:49]
	s_waitcnt vmcnt(9)
	ds_write_b128 v164, v[172:175] offset:64512
	s_waitcnt vmcnt(8)
	ds_write_b128 v165, v[176:179] offset:32256
	v_mfma_f32_16x16x32_bf16 v[18:21], v[224:227], v[232:235], v[18:21]
	v_mfma_f32_16x16x32_bf16 v[22:25], v[224:227], v[236:239], v[22:25]
	v_mfma_f32_16x16x32_bf16 v[2:5], v[224:227], v[240:243], v[2:5]
	v_mfma_f32_16x16x32_bf16 v[6:9], v[224:227], v[252:255], v[6:9]
	s_waitcnt lgkmcnt(4)
	v_mfma_f32_16x16x32_bf16 v[26:29], v[228:231], v[232:235], v[26:29]
	v_mfma_f32_16x16x32_bf16 v[30:33], v[228:231], v[236:239], v[30:33]
	v_mfma_f32_16x16x32_bf16 v[10:13], v[228:231], v[240:243], v[10:13]
	v_mfma_f32_16x16x32_bf16 v[14:17], v[228:231], v[252:255], v[14:17]
	s_waitcnt lgkmcnt(0)
	s_barrier
	s_setprio 0
	global_load_dwordx4 v[122:125], v[72:73], off offset:896
	global_load_dwordx4 v[126:129], v[74:75], off offset:896
	global_load_dwordx4 v[136:139], v[76:77], off offset:896
	global_load_dwordx4 v[140:143], v[78:79], off offset:896
	global_load_dwordx4 v[144:147], v[70:71], off offset:896
	global_load_dwordx4 v[148:151], v[68:69], off offset:896
	global_load_dwordx4 v[172:175], v[66:67], off offset:896
	global_load_dwordx4 v[176:179], v[80:81], off offset:896
	ds_read_b128 v[232:235], v245 offset:55296
	ds_read_b128 v[216:219], v244 offset:18432
	ds_read_b128 v[236:239], v245 offset:57600
	ds_read_b128 v[240:243], v245 offset:59904
	ds_read_b128 v[252:255], v245 offset:62208
	ds_read_b128 v[220:223], v244 offset:20736
	ds_read_b128 v[224:227], v244 offset:23040
	ds_read_b128 v[228:231], v244 offset:25344
	s_waitcnt lgkmcnt(6)
	v_mfma_f32_16x16x32_bf16 v[50:53], v[216:219], v[232:235], v[50:53]
	s_waitcnt lgkmcnt(5)
	v_mfma_f32_16x16x32_bf16 v[54:57], v[216:219], v[236:239], v[54:57]
	s_waitcnt lgkmcnt(4)
	v_mfma_f32_16x16x32_bf16 v[34:37], v[216:219], v[240:243], v[34:37]
	s_waitcnt lgkmcnt(3)
	v_mfma_f32_16x16x32_bf16 v[38:41], v[216:219], v[252:255], v[38:41]
	ds_read_b128 v[216:219], v244 offset:18496
	s_waitcnt lgkmcnt(3)
	v_mfma_f32_16x16x32_bf16 v[58:61], v[220:223], v[232:235], v[58:61]
	v_mfma_f32_16x16x32_bf16 v[62:65], v[220:223], v[236:239], v[62:65]
	v_mfma_f32_16x16x32_bf16 v[42:45], v[220:223], v[240:243], v[42:45]
	v_mfma_f32_16x16x32_bf16 v[46:49], v[220:223], v[252:255], v[46:49]
	ds_read_b128 v[220:223], v244 offset:20800
	s_setprio 1
	s_waitcnt vmcnt(15)
	ds_write_b128 v164, v[180:183]
	s_waitcnt vmcnt(14)
	ds_write_b128 v164, v[188:191] offset:4608
	s_waitcnt lgkmcnt(5)
	v_mfma_f32_16x16x32_bf16 v[18:21], v[224:227], v[232:235], v[18:21]
	v_mfma_f32_16x16x32_bf16 v[22:25], v[224:227], v[236:239], v[22:25]
	v_mfma_f32_16x16x32_bf16 v[2:5], v[224:227], v[240:243], v[2:5]
	v_mfma_f32_16x16x32_bf16 v[6:9], v[224:227], v[252:255], v[6:9]
	ds_read_b128 v[224:227], v244 offset:23104
	s_waitcnt vmcnt(13)
	ds_write_b128 v164, v[192:195] offset:9216
	s_waitcnt vmcnt(12)
	ds_write_b128 v164, v[196:199] offset:13824
	s_waitcnt lgkmcnt(7)
	v_mfma_f32_16x16x32_bf16 v[26:29], v[228:231], v[232:235], v[26:29]
	ds_read_b128 v[232:235], v245 offset:55360
	v_mfma_f32_16x16x32_bf16 v[30:33], v[228:231], v[236:239], v[30:33]
	ds_read_b128 v[236:239], v245 offset:57664
	v_mfma_f32_16x16x32_bf16 v[10:13], v[228:231], v[240:243], v[10:13]
	ds_read_b128 v[240:243], v245 offset:59968
	v_mfma_f32_16x16x32_bf16 v[14:17], v[228:231], v[252:255], v[14:17]
	ds_read_b128 v[252:255], v245 offset:62272
	ds_read_b128 v[228:231], v244 offset:25408
	s_waitcnt lgkmcnt(4)
	v_mfma_f32_16x16x32_bf16 v[50:53], v[216:219], v[232:235], v[50:53]
	s_waitcnt lgkmcnt(3)
	v_mfma_f32_16x16x32_bf16 v[54:57], v[216:219], v[236:239], v[54:57]
	s_waitcnt lgkmcnt(2)
	v_mfma_f32_16x16x32_bf16 v[34:37], v[216:219], v[240:243], v[34:37]
	s_waitcnt lgkmcnt(1)
	v_mfma_f32_16x16x32_bf16 v[38:41], v[216:219], v[252:255], v[38:41]
	s_waitcnt vmcnt(11)
	ds_write_b128 v164, v[200:203] offset:36864
	s_waitcnt vmcnt(10)
	ds_write_b128 v164, v[204:207] offset:41472
	v_mfma_f32_16x16x32_bf16 v[58:61], v[220:223], v[232:235], v[58:61]
	v_mfma_f32_16x16x32_bf16 v[62:65], v[220:223], v[236:239], v[62:65]
	v_mfma_f32_16x16x32_bf16 v[42:45], v[220:223], v[240:243], v[42:45]
	v_mfma_f32_16x16x32_bf16 v[46:49], v[220:223], v[252:255], v[46:49]
	s_waitcnt vmcnt(9)
	ds_write_b128 v164, v[208:211] offset:46080
	s_waitcnt vmcnt(8)
	ds_write_b128 v164, v[212:215] offset:50688
	v_mfma_f32_16x16x32_bf16 v[18:21], v[224:227], v[232:235], v[18:21]
	v_mfma_f32_16x16x32_bf16 v[22:25], v[224:227], v[236:239], v[22:25]
	v_mfma_f32_16x16x32_bf16 v[2:5], v[224:227], v[240:243], v[2:5]
	v_mfma_f32_16x16x32_bf16 v[6:9], v[224:227], v[252:255], v[6:9]
	s_waitcnt lgkmcnt(4)
	v_mfma_f32_16x16x32_bf16 v[26:29], v[228:231], v[232:235], v[26:29]
	v_mfma_f32_16x16x32_bf16 v[30:33], v[228:231], v[236:239], v[30:33]
	v_mfma_f32_16x16x32_bf16 v[10:13], v[228:231], v[240:243], v[10:13]
	v_mfma_f32_16x16x32_bf16 v[14:17], v[228:231], v[252:255], v[14:17]
	s_waitcnt lgkmcnt(0)
	s_barrier
	s_setprio 0
	global_load_dwordx4 v[180:183], v[72:73], off offset:1024
	global_load_dwordx4 v[188:191], v[74:75], off offset:1024
	global_load_dwordx4 v[192:195], v[76:77], off offset:1024
	global_load_dwordx4 v[196:199], v[78:79], off offset:1024
	global_load_dwordx4 v[200:203], v[70:71], off offset:1024
	global_load_dwordx4 v[204:207], v[68:69], off offset:1024
	global_load_dwordx4 v[208:211], v[66:67], off offset:1024
	global_load_dwordx4 v[212:215], v[80:81], off offset:1024
	ds_read_b128 v[232:235], v245 offset:36864
	ds_read_b128 v[216:219], v244
	ds_read_b128 v[236:239], v245 offset:39168
	ds_read_b128 v[240:243], v245 offset:41472
	ds_read_b128 v[252:255], v245 offset:43776
	ds_read_b128 v[220:223], v244 offset:2304
	ds_read_b128 v[224:227], v244 offset:4608
	ds_read_b128 v[228:231], v244 offset:6912
	s_waitcnt lgkmcnt(6)
	v_mfma_f32_16x16x32_bf16 v[50:53], v[216:219], v[232:235], v[50:53]
	s_waitcnt lgkmcnt(5)
	v_mfma_f32_16x16x32_bf16 v[54:57], v[216:219], v[236:239], v[54:57]
	s_waitcnt lgkmcnt(4)
	v_mfma_f32_16x16x32_bf16 v[34:37], v[216:219], v[240:243], v[34:37]
	s_waitcnt lgkmcnt(3)
	v_mfma_f32_16x16x32_bf16 v[38:41], v[216:219], v[252:255], v[38:41]
	ds_read_b128 v[216:219], v244 offset:64
	s_waitcnt lgkmcnt(3)
	v_mfma_f32_16x16x32_bf16 v[58:61], v[220:223], v[232:235], v[58:61]
	v_mfma_f32_16x16x32_bf16 v[62:65], v[220:223], v[236:239], v[62:65]
	v_mfma_f32_16x16x32_bf16 v[42:45], v[220:223], v[240:243], v[42:45]
	v_mfma_f32_16x16x32_bf16 v[46:49], v[220:223], v[252:255], v[46:49]
	ds_read_b128 v[220:223], v244 offset:2368
	s_setprio 1
	s_waitcnt vmcnt(15)
	ds_write_b128 v164, v[122:125] offset:18432
	s_waitcnt vmcnt(14)
	ds_write_b128 v164, v[126:129] offset:23040
	s_waitcnt lgkmcnt(5)
	v_mfma_f32_16x16x32_bf16 v[18:21], v[224:227], v[232:235], v[18:21]
	v_mfma_f32_16x16x32_bf16 v[22:25], v[224:227], v[236:239], v[22:25]
	v_mfma_f32_16x16x32_bf16 v[2:5], v[224:227], v[240:243], v[2:5]
	v_mfma_f32_16x16x32_bf16 v[6:9], v[224:227], v[252:255], v[6:9]
	ds_read_b128 v[224:227], v244 offset:4672
	s_waitcnt vmcnt(13)
	ds_write_b128 v164, v[136:139] offset:27648
	s_waitcnt vmcnt(12)
	ds_write_b128 v164, v[140:143] offset:32256
	s_waitcnt lgkmcnt(7)
	v_mfma_f32_16x16x32_bf16 v[26:29], v[228:231], v[232:235], v[26:29]
	ds_read_b128 v[232:235], v245 offset:36928
	v_mfma_f32_16x16x32_bf16 v[30:33], v[228:231], v[236:239], v[30:33]
	ds_read_b128 v[236:239], v245 offset:39232
	v_mfma_f32_16x16x32_bf16 v[10:13], v[228:231], v[240:243], v[10:13]
	ds_read_b128 v[240:243], v245 offset:41536
	v_mfma_f32_16x16x32_bf16 v[14:17], v[228:231], v[252:255], v[14:17]
	ds_read_b128 v[252:255], v245 offset:43840
	ds_read_b128 v[228:231], v244 offset:6976
	s_waitcnt lgkmcnt(4)
	v_mfma_f32_16x16x32_bf16 v[50:53], v[216:219], v[232:235], v[50:53]
	s_waitcnt lgkmcnt(3)
	v_mfma_f32_16x16x32_bf16 v[54:57], v[216:219], v[236:239], v[54:57]
	s_waitcnt lgkmcnt(2)
	v_mfma_f32_16x16x32_bf16 v[34:37], v[216:219], v[240:243], v[34:37]
	s_waitcnt lgkmcnt(1)
	v_mfma_f32_16x16x32_bf16 v[38:41], v[216:219], v[252:255], v[38:41]
	s_waitcnt vmcnt(11)
	ds_write_b128 v164, v[144:147] offset:55296
	s_waitcnt vmcnt(10)
	ds_write_b128 v164, v[148:151] offset:59904
	v_mfma_f32_16x16x32_bf16 v[58:61], v[220:223], v[232:235], v[58:61]
	v_mfma_f32_16x16x32_bf16 v[62:65], v[220:223], v[236:239], v[62:65]
	v_mfma_f32_16x16x32_bf16 v[42:45], v[220:223], v[240:243], v[42:45]
	v_mfma_f32_16x16x32_bf16 v[46:49], v[220:223], v[252:255], v[46:49]
	s_waitcnt vmcnt(9)
	ds_write_b128 v164, v[172:175] offset:64512
	s_waitcnt vmcnt(8)
	ds_write_b128 v165, v[176:179] offset:32256
	v_mfma_f32_16x16x32_bf16 v[18:21], v[224:227], v[232:235], v[18:21]
	v_mfma_f32_16x16x32_bf16 v[22:25], v[224:227], v[236:239], v[22:25]
	v_mfma_f32_16x16x32_bf16 v[2:5], v[224:227], v[240:243], v[2:5]
	v_mfma_f32_16x16x32_bf16 v[6:9], v[224:227], v[252:255], v[6:9]
	s_waitcnt lgkmcnt(4)
	v_mfma_f32_16x16x32_bf16 v[26:29], v[228:231], v[232:235], v[26:29]
	v_mfma_f32_16x16x32_bf16 v[30:33], v[228:231], v[236:239], v[30:33]
	v_mfma_f32_16x16x32_bf16 v[10:13], v[228:231], v[240:243], v[10:13]
	v_mfma_f32_16x16x32_bf16 v[14:17], v[228:231], v[252:255], v[14:17]
	s_waitcnt lgkmcnt(0)
	s_barrier
	s_setprio 0
	global_load_dwordx4 v[122:125], v[72:73], off offset:1152
	global_load_dwordx4 v[126:129], v[74:75], off offset:1152
	global_load_dwordx4 v[136:139], v[76:77], off offset:1152
	global_load_dwordx4 v[140:143], v[78:79], off offset:1152
	global_load_dwordx4 v[144:147], v[70:71], off offset:1152
	global_load_dwordx4 v[148:151], v[68:69], off offset:1152
	global_load_dwordx4 v[172:175], v[66:67], off offset:1152
	global_load_dwordx4 v[176:179], v[80:81], off offset:1152
	ds_read_b128 v[232:235], v245 offset:55296
	ds_read_b128 v[216:219], v244 offset:18432
	ds_read_b128 v[236:239], v245 offset:57600
	ds_read_b128 v[240:243], v245 offset:59904
	ds_read_b128 v[252:255], v245 offset:62208
	ds_read_b128 v[220:223], v244 offset:20736
	ds_read_b128 v[224:227], v244 offset:23040
	ds_read_b128 v[228:231], v244 offset:25344
	s_waitcnt lgkmcnt(6)
	v_mfma_f32_16x16x32_bf16 v[50:53], v[216:219], v[232:235], v[50:53]
	s_waitcnt lgkmcnt(5)
	v_mfma_f32_16x16x32_bf16 v[54:57], v[216:219], v[236:239], v[54:57]
	s_waitcnt lgkmcnt(4)
	v_mfma_f32_16x16x32_bf16 v[34:37], v[216:219], v[240:243], v[34:37]
	s_waitcnt lgkmcnt(3)
	v_mfma_f32_16x16x32_bf16 v[38:41], v[216:219], v[252:255], v[38:41]
	ds_read_b128 v[216:219], v244 offset:18496
	s_waitcnt lgkmcnt(3)
	v_mfma_f32_16x16x32_bf16 v[58:61], v[220:223], v[232:235], v[58:61]
	v_mfma_f32_16x16x32_bf16 v[62:65], v[220:223], v[236:239], v[62:65]
	v_mfma_f32_16x16x32_bf16 v[42:45], v[220:223], v[240:243], v[42:45]
	v_mfma_f32_16x16x32_bf16 v[46:49], v[220:223], v[252:255], v[46:49]
	ds_read_b128 v[220:223], v244 offset:20800
	s_setprio 1
	s_waitcnt vmcnt(15)
	ds_write_b128 v164, v[180:183]
	s_waitcnt vmcnt(14)
	ds_write_b128 v164, v[188:191] offset:4608
	s_waitcnt lgkmcnt(5)
	v_mfma_f32_16x16x32_bf16 v[18:21], v[224:227], v[232:235], v[18:21]
	v_mfma_f32_16x16x32_bf16 v[22:25], v[224:227], v[236:239], v[22:25]
	v_mfma_f32_16x16x32_bf16 v[2:5], v[224:227], v[240:243], v[2:5]
	v_mfma_f32_16x16x32_bf16 v[6:9], v[224:227], v[252:255], v[6:9]
	ds_read_b128 v[224:227], v244 offset:23104
	s_waitcnt vmcnt(13)
	ds_write_b128 v164, v[192:195] offset:9216
	s_waitcnt vmcnt(12)
	ds_write_b128 v164, v[196:199] offset:13824
	s_waitcnt lgkmcnt(7)
	v_mfma_f32_16x16x32_bf16 v[26:29], v[228:231], v[232:235], v[26:29]
	ds_read_b128 v[232:235], v245 offset:55360
	v_mfma_f32_16x16x32_bf16 v[30:33], v[228:231], v[236:239], v[30:33]
	ds_read_b128 v[236:239], v245 offset:57664
	v_mfma_f32_16x16x32_bf16 v[10:13], v[228:231], v[240:243], v[10:13]
	ds_read_b128 v[240:243], v245 offset:59968
	v_mfma_f32_16x16x32_bf16 v[14:17], v[228:231], v[252:255], v[14:17]
	ds_read_b128 v[252:255], v245 offset:62272
	ds_read_b128 v[228:231], v244 offset:25408
	s_waitcnt lgkmcnt(4)
	v_mfma_f32_16x16x32_bf16 v[50:53], v[216:219], v[232:235], v[50:53]
	s_waitcnt lgkmcnt(3)
	v_mfma_f32_16x16x32_bf16 v[54:57], v[216:219], v[236:239], v[54:57]
	s_waitcnt lgkmcnt(2)
	v_mfma_f32_16x16x32_bf16 v[34:37], v[216:219], v[240:243], v[34:37]
	s_waitcnt lgkmcnt(1)
	v_mfma_f32_16x16x32_bf16 v[38:41], v[216:219], v[252:255], v[38:41]
	s_waitcnt vmcnt(11)
	ds_write_b128 v164, v[200:203] offset:36864
	s_waitcnt vmcnt(10)
	ds_write_b128 v164, v[204:207] offset:41472
	v_mfma_f32_16x16x32_bf16 v[58:61], v[220:223], v[232:235], v[58:61]
	v_mfma_f32_16x16x32_bf16 v[62:65], v[220:223], v[236:239], v[62:65]
	v_mfma_f32_16x16x32_bf16 v[42:45], v[220:223], v[240:243], v[42:45]
	v_mfma_f32_16x16x32_bf16 v[46:49], v[220:223], v[252:255], v[46:49]
	s_waitcnt vmcnt(9)
	ds_write_b128 v164, v[208:211] offset:46080
	s_waitcnt vmcnt(8)
	ds_write_b128 v164, v[212:215] offset:50688
	v_mfma_f32_16x16x32_bf16 v[18:21], v[224:227], v[232:235], v[18:21]
	v_mfma_f32_16x16x32_bf16 v[22:25], v[224:227], v[236:239], v[22:25]
	v_mfma_f32_16x16x32_bf16 v[2:5], v[224:227], v[240:243], v[2:5]
	v_mfma_f32_16x16x32_bf16 v[6:9], v[224:227], v[252:255], v[6:9]
	s_waitcnt lgkmcnt(4)
	v_mfma_f32_16x16x32_bf16 v[26:29], v[228:231], v[232:235], v[26:29]
	v_mfma_f32_16x16x32_bf16 v[30:33], v[228:231], v[236:239], v[30:33]
	v_mfma_f32_16x16x32_bf16 v[10:13], v[228:231], v[240:243], v[10:13]
	v_mfma_f32_16x16x32_bf16 v[14:17], v[228:231], v[252:255], v[14:17]
	s_waitcnt lgkmcnt(0)
	s_barrier
	s_setprio 0
	global_load_dwordx4 v[180:183], v[72:73], off offset:1280
	global_load_dwordx4 v[188:191], v[74:75], off offset:1280
	global_load_dwordx4 v[192:195], v[76:77], off offset:1280
	global_load_dwordx4 v[196:199], v[78:79], off offset:1280
	global_load_dwordx4 v[200:203], v[70:71], off offset:1280
	global_load_dwordx4 v[204:207], v[68:69], off offset:1280
	global_load_dwordx4 v[208:211], v[66:67], off offset:1280
	global_load_dwordx4 v[212:215], v[80:81], off offset:1280
	ds_read_b128 v[232:235], v245 offset:36864
	ds_read_b128 v[216:219], v244
	ds_read_b128 v[236:239], v245 offset:39168
	ds_read_b128 v[240:243], v245 offset:41472
	ds_read_b128 v[252:255], v245 offset:43776
	ds_read_b128 v[220:223], v244 offset:2304
	ds_read_b128 v[224:227], v244 offset:4608
	ds_read_b128 v[228:231], v244 offset:6912
	s_waitcnt lgkmcnt(6)
	v_mfma_f32_16x16x32_bf16 v[50:53], v[216:219], v[232:235], v[50:53]
	s_waitcnt lgkmcnt(5)
	v_mfma_f32_16x16x32_bf16 v[54:57], v[216:219], v[236:239], v[54:57]
	s_waitcnt lgkmcnt(4)
	v_mfma_f32_16x16x32_bf16 v[34:37], v[216:219], v[240:243], v[34:37]
	s_waitcnt lgkmcnt(3)
	v_mfma_f32_16x16x32_bf16 v[38:41], v[216:219], v[252:255], v[38:41]
	ds_read_b128 v[216:219], v244 offset:64
	s_waitcnt lgkmcnt(3)
	v_mfma_f32_16x16x32_bf16 v[58:61], v[220:223], v[232:235], v[58:61]
	v_mfma_f32_16x16x32_bf16 v[62:65], v[220:223], v[236:239], v[62:65]
	v_mfma_f32_16x16x32_bf16 v[42:45], v[220:223], v[240:243], v[42:45]
	v_mfma_f32_16x16x32_bf16 v[46:49], v[220:223], v[252:255], v[46:49]
	ds_read_b128 v[220:223], v244 offset:2368
	s_setprio 1
	s_waitcnt vmcnt(15)
	ds_write_b128 v164, v[122:125] offset:18432
	s_waitcnt vmcnt(14)
	ds_write_b128 v164, v[126:129] offset:23040
	s_waitcnt lgkmcnt(5)
	v_mfma_f32_16x16x32_bf16 v[18:21], v[224:227], v[232:235], v[18:21]
	v_mfma_f32_16x16x32_bf16 v[22:25], v[224:227], v[236:239], v[22:25]
	v_mfma_f32_16x16x32_bf16 v[2:5], v[224:227], v[240:243], v[2:5]
	v_mfma_f32_16x16x32_bf16 v[6:9], v[224:227], v[252:255], v[6:9]
	ds_read_b128 v[224:227], v244 offset:4672
	s_waitcnt vmcnt(13)
	ds_write_b128 v164, v[136:139] offset:27648
	s_waitcnt vmcnt(12)
	ds_write_b128 v164, v[140:143] offset:32256
	s_waitcnt lgkmcnt(7)
	v_mfma_f32_16x16x32_bf16 v[26:29], v[228:231], v[232:235], v[26:29]
	ds_read_b128 v[232:235], v245 offset:36928
	v_mfma_f32_16x16x32_bf16 v[30:33], v[228:231], v[236:239], v[30:33]
	ds_read_b128 v[236:239], v245 offset:39232
	v_mfma_f32_16x16x32_bf16 v[10:13], v[228:231], v[240:243], v[10:13]
	ds_read_b128 v[240:243], v245 offset:41536
	v_mfma_f32_16x16x32_bf16 v[14:17], v[228:231], v[252:255], v[14:17]
	ds_read_b128 v[252:255], v245 offset:43840
	ds_read_b128 v[228:231], v244 offset:6976
	s_waitcnt lgkmcnt(4)
	v_mfma_f32_16x16x32_bf16 v[50:53], v[216:219], v[232:235], v[50:53]
	s_waitcnt lgkmcnt(3)
	v_mfma_f32_16x16x32_bf16 v[54:57], v[216:219], v[236:239], v[54:57]
	s_waitcnt lgkmcnt(2)
	v_mfma_f32_16x16x32_bf16 v[34:37], v[216:219], v[240:243], v[34:37]
	s_waitcnt lgkmcnt(1)
	v_mfma_f32_16x16x32_bf16 v[38:41], v[216:219], v[252:255], v[38:41]
	s_waitcnt vmcnt(11)
	ds_write_b128 v164, v[144:147] offset:55296
	s_waitcnt vmcnt(10)
	ds_write_b128 v164, v[148:151] offset:59904
	v_mfma_f32_16x16x32_bf16 v[58:61], v[220:223], v[232:235], v[58:61]
	v_mfma_f32_16x16x32_bf16 v[62:65], v[220:223], v[236:239], v[62:65]
	v_mfma_f32_16x16x32_bf16 v[42:45], v[220:223], v[240:243], v[42:45]
	v_mfma_f32_16x16x32_bf16 v[46:49], v[220:223], v[252:255], v[46:49]
	s_waitcnt vmcnt(9)
	ds_write_b128 v164, v[172:175] offset:64512
	s_waitcnt vmcnt(8)
	ds_write_b128 v165, v[176:179] offset:32256
	v_mfma_f32_16x16x32_bf16 v[18:21], v[224:227], v[232:235], v[18:21]
	v_mfma_f32_16x16x32_bf16 v[22:25], v[224:227], v[236:239], v[22:25]
	v_mfma_f32_16x16x32_bf16 v[2:5], v[224:227], v[240:243], v[2:5]
	v_mfma_f32_16x16x32_bf16 v[6:9], v[224:227], v[252:255], v[6:9]
	s_waitcnt lgkmcnt(4)
	v_mfma_f32_16x16x32_bf16 v[26:29], v[228:231], v[232:235], v[26:29]
	v_mfma_f32_16x16x32_bf16 v[30:33], v[228:231], v[236:239], v[30:33]
	v_mfma_f32_16x16x32_bf16 v[10:13], v[228:231], v[240:243], v[10:13]
	v_mfma_f32_16x16x32_bf16 v[14:17], v[228:231], v[252:255], v[14:17]
	s_waitcnt lgkmcnt(0)
	s_barrier
	s_setprio 0
	global_load_dwordx4 v[122:125], v[72:73], off offset:1408
	global_load_dwordx4 v[126:129], v[74:75], off offset:1408
	global_load_dwordx4 v[136:139], v[76:77], off offset:1408
	global_load_dwordx4 v[140:143], v[78:79], off offset:1408
	global_load_dwordx4 v[144:147], v[70:71], off offset:1408
	global_load_dwordx4 v[148:151], v[68:69], off offset:1408
	global_load_dwordx4 v[172:175], v[66:67], off offset:1408
	global_load_dwordx4 v[176:179], v[80:81], off offset:1408
	ds_read_b128 v[232:235], v245 offset:55296
	ds_read_b128 v[216:219], v244 offset:18432
	ds_read_b128 v[236:239], v245 offset:57600
	ds_read_b128 v[240:243], v245 offset:59904
	ds_read_b128 v[252:255], v245 offset:62208
	ds_read_b128 v[220:223], v244 offset:20736
	ds_read_b128 v[224:227], v244 offset:23040
	ds_read_b128 v[228:231], v244 offset:25344
	s_waitcnt lgkmcnt(6)
	v_mfma_f32_16x16x32_bf16 v[50:53], v[216:219], v[232:235], v[50:53]
	s_waitcnt lgkmcnt(5)
	v_mfma_f32_16x16x32_bf16 v[54:57], v[216:219], v[236:239], v[54:57]
	s_waitcnt lgkmcnt(4)
	v_mfma_f32_16x16x32_bf16 v[34:37], v[216:219], v[240:243], v[34:37]
	s_waitcnt lgkmcnt(3)
	v_mfma_f32_16x16x32_bf16 v[38:41], v[216:219], v[252:255], v[38:41]
	ds_read_b128 v[216:219], v244 offset:18496
	s_waitcnt lgkmcnt(3)
	v_mfma_f32_16x16x32_bf16 v[58:61], v[220:223], v[232:235], v[58:61]
	v_mfma_f32_16x16x32_bf16 v[62:65], v[220:223], v[236:239], v[62:65]
	v_mfma_f32_16x16x32_bf16 v[42:45], v[220:223], v[240:243], v[42:45]
	v_mfma_f32_16x16x32_bf16 v[46:49], v[220:223], v[252:255], v[46:49]
	ds_read_b128 v[220:223], v244 offset:20800
	s_setprio 1
	s_waitcnt vmcnt(15)
	ds_write_b128 v164, v[180:183]
	s_waitcnt vmcnt(14)
	ds_write_b128 v164, v[188:191] offset:4608
	s_waitcnt lgkmcnt(5)
	v_mfma_f32_16x16x32_bf16 v[18:21], v[224:227], v[232:235], v[18:21]
	v_mfma_f32_16x16x32_bf16 v[22:25], v[224:227], v[236:239], v[22:25]
	v_mfma_f32_16x16x32_bf16 v[2:5], v[224:227], v[240:243], v[2:5]
	v_mfma_f32_16x16x32_bf16 v[6:9], v[224:227], v[252:255], v[6:9]
	ds_read_b128 v[224:227], v244 offset:23104
	s_waitcnt vmcnt(13)
	ds_write_b128 v164, v[192:195] offset:9216
	s_waitcnt vmcnt(12)
	ds_write_b128 v164, v[196:199] offset:13824
	s_waitcnt lgkmcnt(7)
	v_mfma_f32_16x16x32_bf16 v[26:29], v[228:231], v[232:235], v[26:29]
	ds_read_b128 v[232:235], v245 offset:55360
	v_mfma_f32_16x16x32_bf16 v[30:33], v[228:231], v[236:239], v[30:33]
	ds_read_b128 v[236:239], v245 offset:57664
	v_mfma_f32_16x16x32_bf16 v[10:13], v[228:231], v[240:243], v[10:13]
	ds_read_b128 v[240:243], v245 offset:59968
	v_mfma_f32_16x16x32_bf16 v[14:17], v[228:231], v[252:255], v[14:17]
	ds_read_b128 v[252:255], v245 offset:62272
	ds_read_b128 v[228:231], v244 offset:25408
	s_waitcnt lgkmcnt(4)
	v_mfma_f32_16x16x32_bf16 v[50:53], v[216:219], v[232:235], v[50:53]
	s_waitcnt lgkmcnt(3)
	v_mfma_f32_16x16x32_bf16 v[54:57], v[216:219], v[236:239], v[54:57]
	s_waitcnt lgkmcnt(2)
	v_mfma_f32_16x16x32_bf16 v[34:37], v[216:219], v[240:243], v[34:37]
	s_waitcnt lgkmcnt(1)
	v_mfma_f32_16x16x32_bf16 v[38:41], v[216:219], v[252:255], v[38:41]
	s_waitcnt vmcnt(11)
	ds_write_b128 v164, v[200:203] offset:36864
	s_waitcnt vmcnt(10)
	ds_write_b128 v164, v[204:207] offset:41472
	v_mfma_f32_16x16x32_bf16 v[58:61], v[220:223], v[232:235], v[58:61]
	v_mfma_f32_16x16x32_bf16 v[62:65], v[220:223], v[236:239], v[62:65]
	v_mfma_f32_16x16x32_bf16 v[42:45], v[220:223], v[240:243], v[42:45]
	v_mfma_f32_16x16x32_bf16 v[46:49], v[220:223], v[252:255], v[46:49]
	s_waitcnt vmcnt(9)
	ds_write_b128 v164, v[208:211] offset:46080
	s_waitcnt vmcnt(8)
	ds_write_b128 v164, v[212:215] offset:50688
	v_mfma_f32_16x16x32_bf16 v[18:21], v[224:227], v[232:235], v[18:21]
	v_mfma_f32_16x16x32_bf16 v[22:25], v[224:227], v[236:239], v[22:25]
	v_mfma_f32_16x16x32_bf16 v[2:5], v[224:227], v[240:243], v[2:5]
	v_mfma_f32_16x16x32_bf16 v[6:9], v[224:227], v[252:255], v[6:9]
	s_waitcnt lgkmcnt(4)
	v_mfma_f32_16x16x32_bf16 v[26:29], v[228:231], v[232:235], v[26:29]
	v_mfma_f32_16x16x32_bf16 v[30:33], v[228:231], v[236:239], v[30:33]
	v_mfma_f32_16x16x32_bf16 v[10:13], v[228:231], v[240:243], v[10:13]
	v_mfma_f32_16x16x32_bf16 v[14:17], v[228:231], v[252:255], v[14:17]
	s_waitcnt lgkmcnt(0)
	s_barrier
	s_setprio 0
	global_load_dwordx4 v[180:183], v[72:73], off offset:1536
	global_load_dwordx4 v[188:191], v[74:75], off offset:1536
	global_load_dwordx4 v[192:195], v[76:77], off offset:1536
	global_load_dwordx4 v[196:199], v[78:79], off offset:1536
	global_load_dwordx4 v[200:203], v[70:71], off offset:1536
	global_load_dwordx4 v[204:207], v[68:69], off offset:1536
	global_load_dwordx4 v[208:211], v[66:67], off offset:1536
	global_load_dwordx4 v[212:215], v[80:81], off offset:1536
	ds_read_b128 v[232:235], v245 offset:36864
	ds_read_b128 v[216:219], v244
	ds_read_b128 v[236:239], v245 offset:39168
	ds_read_b128 v[240:243], v245 offset:41472
	ds_read_b128 v[252:255], v245 offset:43776
	ds_read_b128 v[220:223], v244 offset:2304
	ds_read_b128 v[224:227], v244 offset:4608
	ds_read_b128 v[228:231], v244 offset:6912
	s_waitcnt lgkmcnt(6)
	v_mfma_f32_16x16x32_bf16 v[50:53], v[216:219], v[232:235], v[50:53]
	s_waitcnt lgkmcnt(5)
	v_mfma_f32_16x16x32_bf16 v[54:57], v[216:219], v[236:239], v[54:57]
	s_waitcnt lgkmcnt(4)
	v_mfma_f32_16x16x32_bf16 v[34:37], v[216:219], v[240:243], v[34:37]
	s_waitcnt lgkmcnt(3)
	v_mfma_f32_16x16x32_bf16 v[38:41], v[216:219], v[252:255], v[38:41]
	ds_read_b128 v[216:219], v244 offset:64
	s_waitcnt lgkmcnt(3)
	v_mfma_f32_16x16x32_bf16 v[58:61], v[220:223], v[232:235], v[58:61]
	v_mfma_f32_16x16x32_bf16 v[62:65], v[220:223], v[236:239], v[62:65]
	v_mfma_f32_16x16x32_bf16 v[42:45], v[220:223], v[240:243], v[42:45]
	v_mfma_f32_16x16x32_bf16 v[46:49], v[220:223], v[252:255], v[46:49]
	ds_read_b128 v[220:223], v244 offset:2368
	s_setprio 1
	s_waitcnt vmcnt(15)
	ds_write_b128 v164, v[122:125] offset:18432
	s_waitcnt vmcnt(14)
	ds_write_b128 v164, v[126:129] offset:23040
	s_waitcnt lgkmcnt(5)
	v_mfma_f32_16x16x32_bf16 v[18:21], v[224:227], v[232:235], v[18:21]
	v_mfma_f32_16x16x32_bf16 v[22:25], v[224:227], v[236:239], v[22:25]
	v_mfma_f32_16x16x32_bf16 v[2:5], v[224:227], v[240:243], v[2:5]
	v_mfma_f32_16x16x32_bf16 v[6:9], v[224:227], v[252:255], v[6:9]
	ds_read_b128 v[224:227], v244 offset:4672
	s_waitcnt vmcnt(13)
	ds_write_b128 v164, v[136:139] offset:27648
	s_waitcnt vmcnt(12)
	ds_write_b128 v164, v[140:143] offset:32256
	s_waitcnt lgkmcnt(7)
	v_mfma_f32_16x16x32_bf16 v[26:29], v[228:231], v[232:235], v[26:29]
	ds_read_b128 v[232:235], v245 offset:36928
	v_mfma_f32_16x16x32_bf16 v[30:33], v[228:231], v[236:239], v[30:33]
	ds_read_b128 v[236:239], v245 offset:39232
	v_mfma_f32_16x16x32_bf16 v[10:13], v[228:231], v[240:243], v[10:13]
	ds_read_b128 v[240:243], v245 offset:41536
	v_mfma_f32_16x16x32_bf16 v[14:17], v[228:231], v[252:255], v[14:17]
	ds_read_b128 v[252:255], v245 offset:43840
	ds_read_b128 v[228:231], v244 offset:6976
	s_waitcnt lgkmcnt(4)
	v_mfma_f32_16x16x32_bf16 v[50:53], v[216:219], v[232:235], v[50:53]
	s_waitcnt lgkmcnt(3)
	v_mfma_f32_16x16x32_bf16 v[54:57], v[216:219], v[236:239], v[54:57]
	s_waitcnt lgkmcnt(2)
	v_mfma_f32_16x16x32_bf16 v[34:37], v[216:219], v[240:243], v[34:37]
	s_waitcnt lgkmcnt(1)
	v_mfma_f32_16x16x32_bf16 v[38:41], v[216:219], v[252:255], v[38:41]
	s_waitcnt vmcnt(11)
	ds_write_b128 v164, v[144:147] offset:55296
	s_waitcnt vmcnt(10)
	ds_write_b128 v164, v[148:151] offset:59904
	v_mfma_f32_16x16x32_bf16 v[58:61], v[220:223], v[232:235], v[58:61]
	v_mfma_f32_16x16x32_bf16 v[62:65], v[220:223], v[236:239], v[62:65]
	v_mfma_f32_16x16x32_bf16 v[42:45], v[220:223], v[240:243], v[42:45]
	v_mfma_f32_16x16x32_bf16 v[46:49], v[220:223], v[252:255], v[46:49]
	s_waitcnt vmcnt(9)
	ds_write_b128 v164, v[172:175] offset:64512
	s_waitcnt vmcnt(8)
	ds_write_b128 v165, v[176:179] offset:32256
	v_mfma_f32_16x16x32_bf16 v[18:21], v[224:227], v[232:235], v[18:21]
	v_mfma_f32_16x16x32_bf16 v[22:25], v[224:227], v[236:239], v[22:25]
	v_mfma_f32_16x16x32_bf16 v[2:5], v[224:227], v[240:243], v[2:5]
	v_mfma_f32_16x16x32_bf16 v[6:9], v[224:227], v[252:255], v[6:9]
	s_waitcnt lgkmcnt(4)
	v_mfma_f32_16x16x32_bf16 v[26:29], v[228:231], v[232:235], v[26:29]
	v_mfma_f32_16x16x32_bf16 v[30:33], v[228:231], v[236:239], v[30:33]
	v_mfma_f32_16x16x32_bf16 v[10:13], v[228:231], v[240:243], v[10:13]
	v_mfma_f32_16x16x32_bf16 v[14:17], v[228:231], v[252:255], v[14:17]
	s_waitcnt lgkmcnt(0)
	s_barrier
	s_setprio 0
	global_load_dwordx4 v[122:125], v[72:73], off offset:1664
	global_load_dwordx4 v[126:129], v[74:75], off offset:1664
	global_load_dwordx4 v[136:139], v[76:77], off offset:1664
	global_load_dwordx4 v[140:143], v[78:79], off offset:1664
	global_load_dwordx4 v[144:147], v[70:71], off offset:1664
	global_load_dwordx4 v[148:151], v[68:69], off offset:1664
	global_load_dwordx4 v[172:175], v[66:67], off offset:1664
	global_load_dwordx4 v[176:179], v[80:81], off offset:1664
	ds_read_b128 v[232:235], v245 offset:55296
	ds_read_b128 v[216:219], v244 offset:18432
	ds_read_b128 v[236:239], v245 offset:57600
	ds_read_b128 v[240:243], v245 offset:59904
	ds_read_b128 v[252:255], v245 offset:62208
	ds_read_b128 v[220:223], v244 offset:20736
	ds_read_b128 v[224:227], v244 offset:23040
	ds_read_b128 v[228:231], v244 offset:25344
	s_waitcnt lgkmcnt(6)
	v_mfma_f32_16x16x32_bf16 v[50:53], v[216:219], v[232:235], v[50:53]
	s_waitcnt lgkmcnt(5)
	v_mfma_f32_16x16x32_bf16 v[54:57], v[216:219], v[236:239], v[54:57]
	s_waitcnt lgkmcnt(4)
	v_mfma_f32_16x16x32_bf16 v[34:37], v[216:219], v[240:243], v[34:37]
	s_waitcnt lgkmcnt(3)
	v_mfma_f32_16x16x32_bf16 v[38:41], v[216:219], v[252:255], v[38:41]
	ds_read_b128 v[216:219], v244 offset:18496
	s_waitcnt lgkmcnt(3)
	v_mfma_f32_16x16x32_bf16 v[58:61], v[220:223], v[232:235], v[58:61]
	v_mfma_f32_16x16x32_bf16 v[62:65], v[220:223], v[236:239], v[62:65]
	v_mfma_f32_16x16x32_bf16 v[42:45], v[220:223], v[240:243], v[42:45]
	v_mfma_f32_16x16x32_bf16 v[46:49], v[220:223], v[252:255], v[46:49]
	ds_read_b128 v[220:223], v244 offset:20800
	s_setprio 1
	s_waitcnt vmcnt(15)
	ds_write_b128 v164, v[180:183]
	s_waitcnt vmcnt(14)
	ds_write_b128 v164, v[188:191] offset:4608
	s_waitcnt lgkmcnt(5)
	v_mfma_f32_16x16x32_bf16 v[18:21], v[224:227], v[232:235], v[18:21]
	v_mfma_f32_16x16x32_bf16 v[22:25], v[224:227], v[236:239], v[22:25]
	v_mfma_f32_16x16x32_bf16 v[2:5], v[224:227], v[240:243], v[2:5]
	v_mfma_f32_16x16x32_bf16 v[6:9], v[224:227], v[252:255], v[6:9]
	ds_read_b128 v[224:227], v244 offset:23104
	s_waitcnt vmcnt(13)
	ds_write_b128 v164, v[192:195] offset:9216
	s_waitcnt vmcnt(12)
	ds_write_b128 v164, v[196:199] offset:13824
	s_waitcnt lgkmcnt(7)
	v_mfma_f32_16x16x32_bf16 v[26:29], v[228:231], v[232:235], v[26:29]
	ds_read_b128 v[232:235], v245 offset:55360
	v_mfma_f32_16x16x32_bf16 v[30:33], v[228:231], v[236:239], v[30:33]
	ds_read_b128 v[236:239], v245 offset:57664
	v_mfma_f32_16x16x32_bf16 v[10:13], v[228:231], v[240:243], v[10:13]
	ds_read_b128 v[240:243], v245 offset:59968
	v_mfma_f32_16x16x32_bf16 v[14:17], v[228:231], v[252:255], v[14:17]
	ds_read_b128 v[252:255], v245 offset:62272
	ds_read_b128 v[228:231], v244 offset:25408
	s_waitcnt lgkmcnt(4)
	v_mfma_f32_16x16x32_bf16 v[50:53], v[216:219], v[232:235], v[50:53]
	s_waitcnt lgkmcnt(3)
	v_mfma_f32_16x16x32_bf16 v[54:57], v[216:219], v[236:239], v[54:57]
	s_waitcnt lgkmcnt(2)
	v_mfma_f32_16x16x32_bf16 v[34:37], v[216:219], v[240:243], v[34:37]
	s_waitcnt lgkmcnt(1)
	v_mfma_f32_16x16x32_bf16 v[38:41], v[216:219], v[252:255], v[38:41]
	s_waitcnt vmcnt(11)
	ds_write_b128 v164, v[200:203] offset:36864
	s_waitcnt vmcnt(10)
	ds_write_b128 v164, v[204:207] offset:41472
	v_mfma_f32_16x16x32_bf16 v[58:61], v[220:223], v[232:235], v[58:61]
	v_mfma_f32_16x16x32_bf16 v[62:65], v[220:223], v[236:239], v[62:65]
	v_mfma_f32_16x16x32_bf16 v[42:45], v[220:223], v[240:243], v[42:45]
	v_mfma_f32_16x16x32_bf16 v[46:49], v[220:223], v[252:255], v[46:49]
	s_waitcnt vmcnt(9)
	ds_write_b128 v164, v[208:211] offset:46080
	s_waitcnt vmcnt(8)
	ds_write_b128 v164, v[212:215] offset:50688
	v_mfma_f32_16x16x32_bf16 v[18:21], v[224:227], v[232:235], v[18:21]
	v_mfma_f32_16x16x32_bf16 v[22:25], v[224:227], v[236:239], v[22:25]
	v_mfma_f32_16x16x32_bf16 v[2:5], v[224:227], v[240:243], v[2:5]
	v_mfma_f32_16x16x32_bf16 v[6:9], v[224:227], v[252:255], v[6:9]
	s_waitcnt lgkmcnt(4)
	v_mfma_f32_16x16x32_bf16 v[26:29], v[228:231], v[232:235], v[26:29]
	v_mfma_f32_16x16x32_bf16 v[30:33], v[228:231], v[236:239], v[30:33]
	v_mfma_f32_16x16x32_bf16 v[10:13], v[228:231], v[240:243], v[10:13]
	v_mfma_f32_16x16x32_bf16 v[14:17], v[228:231], v[252:255], v[14:17]
	s_waitcnt lgkmcnt(0)
	s_barrier
	s_setprio 0
	global_load_dwordx4 v[180:183], v[72:73], off offset:1792
	global_load_dwordx4 v[188:191], v[74:75], off offset:1792
	global_load_dwordx4 v[192:195], v[76:77], off offset:1792
	global_load_dwordx4 v[196:199], v[78:79], off offset:1792
	global_load_dwordx4 v[200:203], v[70:71], off offset:1792
	global_load_dwordx4 v[204:207], v[68:69], off offset:1792
	global_load_dwordx4 v[208:211], v[66:67], off offset:1792
	global_load_dwordx4 v[212:215], v[80:81], off offset:1792
	ds_read_b128 v[232:235], v245 offset:36864
	ds_read_b128 v[216:219], v244
	ds_read_b128 v[236:239], v245 offset:39168
	ds_read_b128 v[240:243], v245 offset:41472
	ds_read_b128 v[252:255], v245 offset:43776
	ds_read_b128 v[220:223], v244 offset:2304
	ds_read_b128 v[224:227], v244 offset:4608
	ds_read_b128 v[228:231], v244 offset:6912
	s_waitcnt lgkmcnt(6)
	v_mfma_f32_16x16x32_bf16 v[50:53], v[216:219], v[232:235], v[50:53]
	s_waitcnt lgkmcnt(5)
	v_mfma_f32_16x16x32_bf16 v[54:57], v[216:219], v[236:239], v[54:57]
	s_waitcnt lgkmcnt(4)
	v_mfma_f32_16x16x32_bf16 v[34:37], v[216:219], v[240:243], v[34:37]
	s_waitcnt lgkmcnt(3)
	v_mfma_f32_16x16x32_bf16 v[38:41], v[216:219], v[252:255], v[38:41]
	ds_read_b128 v[216:219], v244 offset:64
	s_waitcnt lgkmcnt(3)
	v_mfma_f32_16x16x32_bf16 v[58:61], v[220:223], v[232:235], v[58:61]
	v_mfma_f32_16x16x32_bf16 v[62:65], v[220:223], v[236:239], v[62:65]
	v_mfma_f32_16x16x32_bf16 v[42:45], v[220:223], v[240:243], v[42:45]
	v_mfma_f32_16x16x32_bf16 v[46:49], v[220:223], v[252:255], v[46:49]
	ds_read_b128 v[220:223], v244 offset:2368
	s_setprio 1
	s_waitcnt vmcnt(15)
	ds_write_b128 v164, v[122:125] offset:18432
	s_waitcnt vmcnt(14)
	ds_write_b128 v164, v[126:129] offset:23040
	s_waitcnt lgkmcnt(5)
	v_mfma_f32_16x16x32_bf16 v[18:21], v[224:227], v[232:235], v[18:21]
	v_mfma_f32_16x16x32_bf16 v[22:25], v[224:227], v[236:239], v[22:25]
	v_mfma_f32_16x16x32_bf16 v[2:5], v[224:227], v[240:243], v[2:5]
	v_mfma_f32_16x16x32_bf16 v[6:9], v[224:227], v[252:255], v[6:9]
	ds_read_b128 v[224:227], v244 offset:4672
	s_waitcnt vmcnt(13)
	ds_write_b128 v164, v[136:139] offset:27648
	s_waitcnt vmcnt(12)
	ds_write_b128 v164, v[140:143] offset:32256
	s_waitcnt lgkmcnt(7)
	v_mfma_f32_16x16x32_bf16 v[26:29], v[228:231], v[232:235], v[26:29]
	ds_read_b128 v[232:235], v245 offset:36928
	v_mfma_f32_16x16x32_bf16 v[30:33], v[228:231], v[236:239], v[30:33]
	ds_read_b128 v[236:239], v245 offset:39232
	v_mfma_f32_16x16x32_bf16 v[10:13], v[228:231], v[240:243], v[10:13]
	ds_read_b128 v[240:243], v245 offset:41536
	v_mfma_f32_16x16x32_bf16 v[14:17], v[228:231], v[252:255], v[14:17]
	ds_read_b128 v[252:255], v245 offset:43840
	ds_read_b128 v[228:231], v244 offset:6976
	s_waitcnt lgkmcnt(4)
	v_mfma_f32_16x16x32_bf16 v[50:53], v[216:219], v[232:235], v[50:53]
	s_waitcnt lgkmcnt(3)
	v_mfma_f32_16x16x32_bf16 v[54:57], v[216:219], v[236:239], v[54:57]
	s_waitcnt lgkmcnt(2)
	v_mfma_f32_16x16x32_bf16 v[34:37], v[216:219], v[240:243], v[34:37]
	s_waitcnt lgkmcnt(1)
	v_mfma_f32_16x16x32_bf16 v[38:41], v[216:219], v[252:255], v[38:41]
	s_waitcnt vmcnt(11)
	ds_write_b128 v164, v[144:147] offset:55296
	s_waitcnt vmcnt(10)
	ds_write_b128 v164, v[148:151] offset:59904
	v_mfma_f32_16x16x32_bf16 v[58:61], v[220:223], v[232:235], v[58:61]
	v_mfma_f32_16x16x32_bf16 v[62:65], v[220:223], v[236:239], v[62:65]
	v_mfma_f32_16x16x32_bf16 v[42:45], v[220:223], v[240:243], v[42:45]
	v_mfma_f32_16x16x32_bf16 v[46:49], v[220:223], v[252:255], v[46:49]
	s_waitcnt vmcnt(9)
	ds_write_b128 v164, v[172:175] offset:64512
	s_waitcnt vmcnt(8)
	ds_write_b128 v165, v[176:179] offset:32256
	v_mfma_f32_16x16x32_bf16 v[18:21], v[224:227], v[232:235], v[18:21]
	v_mfma_f32_16x16x32_bf16 v[22:25], v[224:227], v[236:239], v[22:25]
	v_mfma_f32_16x16x32_bf16 v[2:5], v[224:227], v[240:243], v[2:5]
	v_mfma_f32_16x16x32_bf16 v[6:9], v[224:227], v[252:255], v[6:9]
	s_waitcnt lgkmcnt(4)
	v_mfma_f32_16x16x32_bf16 v[26:29], v[228:231], v[232:235], v[26:29]
	v_mfma_f32_16x16x32_bf16 v[30:33], v[228:231], v[236:239], v[30:33]
	v_mfma_f32_16x16x32_bf16 v[10:13], v[228:231], v[240:243], v[10:13]
	v_mfma_f32_16x16x32_bf16 v[14:17], v[228:231], v[252:255], v[14:17]
	s_waitcnt lgkmcnt(0)
	s_barrier
	s_setprio 0
	global_load_dwordx4 v[122:125], v[72:73], off offset:1920
	s_nop 0
	global_load_dwordx4 v[72:75], v[74:75], off offset:1920
	s_nop 0
	global_load_dwordx4 v[126:129], v[76:77], off offset:1920
	s_nop 0
	global_load_dwordx4 v[76:79], v[78:79], off offset:1920
	s_nop 0
	global_load_dwordx4 v[136:139], v[70:71], off offset:1920
	s_nop 0
	global_load_dwordx4 v[68:71], v[68:69], off offset:1920
	s_nop 0
	global_load_dwordx4 v[140:143], v[66:67], off offset:1920
	global_load_dwordx4 v[144:147], v[80:81], off offset:1920
	ds_read_b128 v[232:235], v245 offset:55296
	ds_read_b128 v[216:219], v244 offset:18432
	ds_read_b128 v[236:239], v245 offset:57600
	ds_read_b128 v[240:243], v245 offset:59904
	ds_read_b128 v[252:255], v245 offset:62208
	ds_read_b128 v[220:223], v244 offset:20736
	ds_read_b128 v[224:227], v244 offset:23040
	ds_read_b128 v[228:231], v244 offset:25344
	s_waitcnt lgkmcnt(6)
	v_mfma_f32_16x16x32_bf16 v[50:53], v[216:219], v[232:235], v[50:53]
	s_waitcnt lgkmcnt(5)
	v_mfma_f32_16x16x32_bf16 v[54:57], v[216:219], v[236:239], v[54:57]
	s_waitcnt lgkmcnt(4)
	v_mfma_f32_16x16x32_bf16 v[34:37], v[216:219], v[240:243], v[34:37]
	s_waitcnt lgkmcnt(3)
	v_mfma_f32_16x16x32_bf16 v[38:41], v[216:219], v[252:255], v[38:41]
	ds_read_b128 v[216:219], v244 offset:18496
	s_waitcnt lgkmcnt(3)
	v_mfma_f32_16x16x32_bf16 v[58:61], v[220:223], v[232:235], v[58:61]
	v_mfma_f32_16x16x32_bf16 v[62:65], v[220:223], v[236:239], v[62:65]
	v_mfma_f32_16x16x32_bf16 v[42:45], v[220:223], v[240:243], v[42:45]
	v_mfma_f32_16x16x32_bf16 v[46:49], v[220:223], v[252:255], v[46:49]
	ds_read_b128 v[220:223], v244 offset:20800
	s_setprio 1
	s_waitcnt vmcnt(15)
	ds_write_b128 v164, v[180:183]
	s_waitcnt vmcnt(14)
	ds_write_b128 v164, v[188:191] offset:4608
	s_waitcnt lgkmcnt(5)
	v_mfma_f32_16x16x32_bf16 v[18:21], v[224:227], v[232:235], v[18:21]
	v_mfma_f32_16x16x32_bf16 v[22:25], v[224:227], v[236:239], v[22:25]
	v_mfma_f32_16x16x32_bf16 v[2:5], v[224:227], v[240:243], v[2:5]
	v_mfma_f32_16x16x32_bf16 v[6:9], v[224:227], v[252:255], v[6:9]
	ds_read_b128 v[224:227], v244 offset:23104
	s_waitcnt vmcnt(13)
	ds_write_b128 v164, v[192:195] offset:9216
	s_waitcnt vmcnt(12)
	ds_write_b128 v164, v[196:199] offset:13824
	s_waitcnt lgkmcnt(7)
	v_mfma_f32_16x16x32_bf16 v[26:29], v[228:231], v[232:235], v[26:29]
	ds_read_b128 v[232:235], v245 offset:55360
	v_mfma_f32_16x16x32_bf16 v[30:33], v[228:231], v[236:239], v[30:33]
	ds_read_b128 v[236:239], v245 offset:57664
	v_mfma_f32_16x16x32_bf16 v[10:13], v[228:231], v[240:243], v[10:13]
	ds_read_b128 v[240:243], v245 offset:59968
	v_mfma_f32_16x16x32_bf16 v[14:17], v[228:231], v[252:255], v[14:17]
	ds_read_b128 v[252:255], v245 offset:62272
	ds_read_b128 v[228:231], v244 offset:25408
	s_waitcnt lgkmcnt(4)
	v_mfma_f32_16x16x32_bf16 v[50:53], v[216:219], v[232:235], v[50:53]
	s_waitcnt lgkmcnt(3)
	v_mfma_f32_16x16x32_bf16 v[54:57], v[216:219], v[236:239], v[54:57]
	s_waitcnt lgkmcnt(2)
	v_mfma_f32_16x16x32_bf16 v[34:37], v[216:219], v[240:243], v[34:37]
	s_waitcnt lgkmcnt(1)
	v_mfma_f32_16x16x32_bf16 v[38:41], v[216:219], v[252:255], v[38:41]
	s_waitcnt vmcnt(11)
	ds_write_b128 v164, v[200:203] offset:36864
	s_waitcnt vmcnt(10)
	ds_write_b128 v164, v[204:207] offset:41472
	v_mfma_f32_16x16x32_bf16 v[58:61], v[220:223], v[232:235], v[58:61]
	v_mfma_f32_16x16x32_bf16 v[62:65], v[220:223], v[236:239], v[62:65]
	v_mfma_f32_16x16x32_bf16 v[42:45], v[220:223], v[240:243], v[42:45]
	v_mfma_f32_16x16x32_bf16 v[46:49], v[220:223], v[252:255], v[46:49]
	s_waitcnt vmcnt(9)
	ds_write_b128 v164, v[208:211] offset:46080
	s_waitcnt vmcnt(8)
	ds_write_b128 v164, v[212:215] offset:50688
	v_mfma_f32_16x16x32_bf16 v[18:21], v[224:227], v[232:235], v[18:21]
	v_mfma_f32_16x16x32_bf16 v[22:25], v[224:227], v[236:239], v[22:25]
	v_mfma_f32_16x16x32_bf16 v[2:5], v[224:227], v[240:243], v[2:5]
	v_mfma_f32_16x16x32_bf16 v[6:9], v[224:227], v[252:255], v[6:9]
	s_waitcnt lgkmcnt(4)
	v_mfma_f32_16x16x32_bf16 v[26:29], v[228:231], v[232:235], v[26:29]
	v_mfma_f32_16x16x32_bf16 v[30:33], v[228:231], v[236:239], v[30:33]
	v_mfma_f32_16x16x32_bf16 v[10:13], v[228:231], v[240:243], v[10:13]
	v_mfma_f32_16x16x32_bf16 v[14:17], v[228:231], v[252:255], v[14:17]
	s_waitcnt lgkmcnt(0)
	s_barrier
	s_setprio 0
	ds_read_b128 v[232:235], v245 offset:36864
	ds_read_b128 v[216:219], v244
	ds_read_b128 v[236:239], v245 offset:39168
	ds_read_b128 v[240:243], v245 offset:41472
	ds_read_b128 v[252:255], v245 offset:43776
	ds_read_b128 v[220:223], v244 offset:2304
	ds_read_b128 v[224:227], v244 offset:4608
	ds_read_b128 v[228:231], v244 offset:6912
	s_waitcnt lgkmcnt(6)
	v_mfma_f32_16x16x32_bf16 v[50:53], v[216:219], v[232:235], v[50:53]
	s_waitcnt lgkmcnt(5)
	v_mfma_f32_16x16x32_bf16 v[54:57], v[216:219], v[236:239], v[54:57]
	s_waitcnt lgkmcnt(4)
	v_mfma_f32_16x16x32_bf16 v[34:37], v[216:219], v[240:243], v[34:37]
	s_waitcnt lgkmcnt(3)
	v_mfma_f32_16x16x32_bf16 v[38:41], v[216:219], v[252:255], v[38:41]
	ds_read_b128 v[216:219], v244 offset:64
	s_waitcnt lgkmcnt(3)
	v_mfma_f32_16x16x32_bf16 v[58:61], v[220:223], v[232:235], v[58:61]
	v_mfma_f32_16x16x32_bf16 v[62:65], v[220:223], v[236:239], v[62:65]
	v_mfma_f32_16x16x32_bf16 v[42:45], v[220:223], v[240:243], v[42:45]
	v_mfma_f32_16x16x32_bf16 v[46:49], v[220:223], v[252:255], v[46:49]
	ds_read_b128 v[220:223], v244 offset:2368
	s_setprio 1
	s_waitcnt vmcnt(7)
	ds_write_b128 v164, v[122:125] offset:18432
	s_waitcnt vmcnt(6)
	ds_write_b128 v164, v[72:75] offset:23040
	s_waitcnt lgkmcnt(5)
	v_mfma_f32_16x16x32_bf16 v[18:21], v[224:227], v[232:235], v[18:21]
	v_mfma_f32_16x16x32_bf16 v[22:25], v[224:227], v[236:239], v[22:25]
	v_mfma_f32_16x16x32_bf16 v[2:5], v[224:227], v[240:243], v[2:5]
	v_mfma_f32_16x16x32_bf16 v[6:9], v[224:227], v[252:255], v[6:9]
	ds_read_b128 v[224:227], v244 offset:4672
	s_waitcnt vmcnt(5)
	ds_write_b128 v164, v[126:129] offset:27648
	s_waitcnt vmcnt(4)
	ds_write_b128 v164, v[76:79] offset:32256
	s_waitcnt lgkmcnt(7)
	v_mfma_f32_16x16x32_bf16 v[26:29], v[228:231], v[232:235], v[26:29]
	ds_read_b128 v[232:235], v245 offset:36928
	v_mfma_f32_16x16x32_bf16 v[30:33], v[228:231], v[236:239], v[30:33]
	ds_read_b128 v[236:239], v245 offset:39232
	v_mfma_f32_16x16x32_bf16 v[10:13], v[228:231], v[240:243], v[10:13]
	ds_read_b128 v[240:243], v245 offset:41536
	v_mfma_f32_16x16x32_bf16 v[14:17], v[228:231], v[252:255], v[14:17]
	ds_read_b128 v[252:255], v245 offset:43840
	ds_read_b128 v[228:231], v244 offset:6976
	s_waitcnt lgkmcnt(4)
	v_mfma_f32_16x16x32_bf16 v[50:53], v[216:219], v[232:235], v[50:53]
	s_waitcnt lgkmcnt(3)
	v_mfma_f32_16x16x32_bf16 v[54:57], v[216:219], v[236:239], v[54:57]
	s_waitcnt lgkmcnt(2)
	v_mfma_f32_16x16x32_bf16 v[34:37], v[216:219], v[240:243], v[34:37]
	s_waitcnt lgkmcnt(1)
	v_mfma_f32_16x16x32_bf16 v[38:41], v[216:219], v[252:255], v[38:41]
	s_waitcnt vmcnt(3)
	ds_write_b128 v164, v[136:139] offset:55296
	s_waitcnt vmcnt(2)
	ds_write_b128 v164, v[68:71] offset:59904
	v_mfma_f32_16x16x32_bf16 v[58:61], v[220:223], v[232:235], v[58:61]
	v_mfma_f32_16x16x32_bf16 v[62:65], v[220:223], v[236:239], v[62:65]
	v_mfma_f32_16x16x32_bf16 v[42:45], v[220:223], v[240:243], v[42:45]
	v_mfma_f32_16x16x32_bf16 v[46:49], v[220:223], v[252:255], v[46:49]
	s_waitcnt vmcnt(1)
	ds_write_b128 v164, v[140:143] offset:64512
	s_waitcnt vmcnt(0)
	ds_write_b128 v165, v[144:147] offset:32256
	v_mfma_f32_16x16x32_bf16 v[18:21], v[224:227], v[232:235], v[18:21]
	v_mfma_f32_16x16x32_bf16 v[22:25], v[224:227], v[236:239], v[22:25]
	v_mfma_f32_16x16x32_bf16 v[2:5], v[224:227], v[240:243], v[2:5]
	v_mfma_f32_16x16x32_bf16 v[6:9], v[224:227], v[252:255], v[6:9]
	s_waitcnt lgkmcnt(4)
	v_mfma_f32_16x16x32_bf16 v[26:29], v[228:231], v[232:235], v[26:29]
	v_mfma_f32_16x16x32_bf16 v[30:33], v[228:231], v[236:239], v[30:33]
	v_mfma_f32_16x16x32_bf16 v[10:13], v[228:231], v[240:243], v[10:13]
	v_mfma_f32_16x16x32_bf16 v[14:17], v[228:231], v[252:255], v[14:17]
	s_waitcnt lgkmcnt(0)
	s_barrier
	s_setprio 0
	ds_read_b128 v[232:235], v245 offset:55296
	ds_read_b128 v[216:219], v244 offset:18432
	ds_read_b128 v[236:239], v245 offset:57600
	ds_read_b128 v[240:243], v245 offset:59904
	ds_read_b128 v[252:255], v245 offset:62208
	ds_read_b128 v[220:223], v244 offset:20736
	ds_read_b128 v[224:227], v244 offset:23040
	ds_read_b128 v[228:231], v244 offset:25344
	s_waitcnt lgkmcnt(6)
	v_mfma_f32_16x16x32_bf16 v[50:53], v[216:219], v[232:235], v[50:53]
	s_waitcnt lgkmcnt(5)
	v_mfma_f32_16x16x32_bf16 v[54:57], v[216:219], v[236:239], v[54:57]
	s_waitcnt lgkmcnt(4)
	v_mfma_f32_16x16x32_bf16 v[34:37], v[216:219], v[240:243], v[34:37]
	s_waitcnt lgkmcnt(3)
	v_mfma_f32_16x16x32_bf16 v[38:41], v[216:219], v[252:255], v[38:41]
	ds_read_b128 v[216:219], v244 offset:18496
	s_waitcnt lgkmcnt(3)
	v_mfma_f32_16x16x32_bf16 v[58:61], v[220:223], v[232:235], v[58:61]
	v_mfma_f32_16x16x32_bf16 v[62:65], v[220:223], v[236:239], v[62:65]
	v_mfma_f32_16x16x32_bf16 v[42:45], v[220:223], v[240:243], v[42:45]
	v_mfma_f32_16x16x32_bf16 v[46:49], v[220:223], v[252:255], v[46:49]
	ds_read_b128 v[220:223], v244 offset:20800
	s_waitcnt lgkmcnt(3)
	v_mfma_f32_16x16x32_bf16 v[18:21], v[224:227], v[232:235], v[18:21]
	v_mfma_f32_16x16x32_bf16 v[22:25], v[224:227], v[236:239], v[22:25]
	v_mfma_f32_16x16x32_bf16 v[2:5], v[224:227], v[240:243], v[2:5]
	v_mfma_f32_16x16x32_bf16 v[6:9], v[224:227], v[252:255], v[6:9]
	ds_read_b128 v[224:227], v244 offset:23104
	s_waitcnt lgkmcnt(3)
	v_mfma_f32_16x16x32_bf16 v[26:29], v[228:231], v[232:235], v[26:29]
	ds_read_b128 v[232:235], v245 offset:55360
	v_mfma_f32_16x16x32_bf16 v[30:33], v[228:231], v[236:239], v[30:33]
	ds_read_b128 v[236:239], v245 offset:57664
	v_mfma_f32_16x16x32_bf16 v[10:13], v[228:231], v[240:243], v[10:13]
	ds_read_b128 v[240:243], v245 offset:59968
	v_mfma_f32_16x16x32_bf16 v[14:17], v[228:231], v[252:255], v[14:17]
	ds_read_b128 v[252:255], v245 offset:62272
	ds_read_b128 v[228:231], v244 offset:25408
	s_waitcnt lgkmcnt(4)
	v_mfma_f32_16x16x32_bf16 v[50:53], v[216:219], v[232:235], v[50:53]
	s_waitcnt lgkmcnt(3)
	v_mfma_f32_16x16x32_bf16 v[54:57], v[216:219], v[236:239], v[54:57]
	s_waitcnt lgkmcnt(2)
	v_mfma_f32_16x16x32_bf16 v[34:37], v[216:219], v[240:243], v[34:37]
	s_waitcnt lgkmcnt(1)
	v_mfma_f32_16x16x32_bf16 v[38:41], v[216:219], v[252:255], v[38:41]
	v_mfma_f32_16x16x32_bf16 v[58:61], v[220:223], v[232:235], v[58:61]
	v_mfma_f32_16x16x32_bf16 v[62:65], v[220:223], v[236:239], v[62:65]
	v_mfma_f32_16x16x32_bf16 v[42:45], v[220:223], v[240:243], v[42:45]
	v_mfma_f32_16x16x32_bf16 v[46:49], v[220:223], v[252:255], v[46:49]
	v_mfma_f32_16x16x32_bf16 v[18:21], v[224:227], v[232:235], v[18:21]
	v_mfma_f32_16x16x32_bf16 v[22:25], v[224:227], v[236:239], v[22:25]
	v_mfma_f32_16x16x32_bf16 v[2:5], v[224:227], v[240:243], v[2:5]
	v_mfma_f32_16x16x32_bf16 v[6:9], v[224:227], v[252:255], v[6:9]
	s_waitcnt lgkmcnt(0)
	v_mfma_f32_16x16x32_bf16 v[26:29], v[228:231], v[232:235], v[26:29]
	v_mfma_f32_16x16x32_bf16 v[30:33], v[228:231], v[236:239], v[30:33]
	v_mfma_f32_16x16x32_bf16 v[10:13], v[228:231], v[240:243], v[10:13]
	v_mfma_f32_16x16x32_bf16 v[14:17], v[228:231], v[252:255], v[14:17]
	s_mov_b64 s[2:3], 0
	s_waitcnt lgkmcnt(0)
	s_barrier
	s_nop 7
	v_permlane16_swap_b32_e32 v50, v54
	v_permlane16_swap_b32_e32 v51, v55
	v_permlane16_swap_b32_e32 v52, v56
	v_permlane16_swap_b32_e32 v53, v57
	v_permlane16_swap_b32_e32 v58, v62
	v_permlane16_swap_b32_e32 v59, v63
	v_permlane16_swap_b32_e32 v60, v64
	v_permlane16_swap_b32_e32 v61, v65
	v_permlane16_swap_b32_e32 v34, v38
	v_permlane16_swap_b32_e32 v35, v39
	v_permlane16_swap_b32_e32 v36, v40
	v_permlane16_swap_b32_e32 v37, v41
	v_permlane16_swap_b32_e32 v42, v46
	v_permlane16_swap_b32_e32 v43, v47
	v_permlane16_swap_b32_e32 v44, v48
	v_permlane16_swap_b32_e32 v45, v49
	v_permlane16_swap_b32_e32 v18, v22
	v_permlane16_swap_b32_e32 v19, v23
	v_permlane16_swap_b32_e32 v20, v24
	v_permlane16_swap_b32_e32 v21, v25
	v_permlane16_swap_b32_e32 v26, v30
	v_permlane16_swap_b32_e32 v27, v31
	v_permlane16_swap_b32_e32 v28, v32
	v_permlane16_swap_b32_e32 v29, v33
	v_permlane16_swap_b32_e32 v2, v6
	v_permlane16_swap_b32_e32 v3, v7
	v_permlane16_swap_b32_e32 v4, v8
	v_permlane16_swap_b32_e32 v5, v9
	v_permlane16_swap_b32_e32 v10, v14
	v_permlane16_swap_b32_e32 v11, v15
	v_permlane16_swap_b32_e32 v12, v16
	v_permlane16_swap_b32_e32 v13, v17
	v_permlane32_swap_b32_e32 v50, v54
	v_permlane32_swap_b32_e32 v51, v55
	v_permlane32_swap_b32_e32 v52, v56
	v_permlane32_swap_b32_e32 v53, v57
	v_permlane32_swap_b32_e32 v58, v62
	v_permlane32_swap_b32_e32 v59, v63
	v_permlane32_swap_b32_e32 v60, v64
	v_permlane32_swap_b32_e32 v61, v65
	v_permlane32_swap_b32_e32 v34, v38
	v_permlane32_swap_b32_e32 v35, v39
	v_permlane32_swap_b32_e32 v36, v40
	v_permlane32_swap_b32_e32 v37, v41
	v_permlane32_swap_b32_e32 v42, v46
	v_permlane32_swap_b32_e32 v43, v47
	v_permlane32_swap_b32_e32 v44, v48
	v_permlane32_swap_b32_e32 v45, v49
	v_permlane32_swap_b32_e32 v18, v22
	v_permlane32_swap_b32_e32 v19, v23
	v_permlane32_swap_b32_e32 v20, v24
	v_permlane32_swap_b32_e32 v21, v25
	v_permlane32_swap_b32_e32 v26, v30
	v_permlane32_swap_b32_e32 v27, v31
	v_permlane32_swap_b32_e32 v28, v32
	v_permlane32_swap_b32_e32 v29, v33
	v_permlane32_swap_b32_e32 v2, v6
	v_permlane32_swap_b32_e32 v3, v7
	v_permlane32_swap_b32_e32 v4, v8
	v_permlane32_swap_b32_e32 v5, v9
	v_permlane32_swap_b32_e32 v10, v14
	v_permlane32_swap_b32_e32 v11, v15
	v_permlane32_swap_b32_e32 v12, v16
	v_permlane32_swap_b32_e32 v13, v17

.LBB0_1167:
	v_ashrrev_i32_e32 v3, 31, v2
	v_lshlrev_b64 v[2:3], 11, v[2:3]
	v_ashrrev_i32_e32 v9, 31, v8
	v_lshl_add_u64 v[70:71], v[86:87], 0, v[2:3]
	v_lshlrev_b64 v[2:3], 11, v[8:9]
	v_lshl_add_u64 v[72:73], v[86:87], 0, v[2:3]
	v_or_b32_e32 v2, s56, v154
	v_ashrrev_i32_e32 v3, 31, v2
	v_lshlrev_b64 v[2:3], 11, v[2:3]
	v_lshl_add_u64 v[74:75], v[84:85], 0, v[2:3]
	v_add_u32_e32 v2, s56, v155
	v_ashrrev_i32_e32 v3, 31, v2
	v_lshlrev_b64 v[2:3], 11, v[2:3]
	v_lshl_add_u64 v[76:77], v[84:85], 0, v[2:3]
	v_add_u32_e32 v2, s56, v156
	v_ashrrev_i32_e32 v3, 31, v2
	v_lshlrev_b64 v[2:3], 11, v[2:3]
	v_lshl_add_u64 v[78:79], v[84:85], 0, v[2:3]
	v_add_u32_e32 v2, s56, v157
	v_ashrrev_i32_e32 v7, 31, v6
	v_ashrrev_i32_e32 v5, 31, v4
	v_ashrrev_i32_e32 v3, 31, v2
	v_lshlrev_b64 v[6:7], 11, v[6:7]
	v_lshlrev_b64 v[4:5], 11, v[4:5]
	v_lshlrev_b64 v[2:3], 11, v[2:3]
	v_lshl_add_u64 v[66:67], v[86:87], 0, v[6:7]
	v_lshl_add_u64 v[68:69], v[86:87], 0, v[4:5]
	v_lshl_add_u64 v[80:81], v[84:85], 0, v[2:3]
	global_load_dwordx4 v[2:5], v[70:71], off
	global_load_dwordx4 v[6:9], v[68:69], off
	global_load_dwordx4 v[10:13], v[66:67], off
	global_load_dwordx4 v[14:17], v[72:73], off
	global_load_dwordx4 v[18:21], v[74:75], off
	global_load_dwordx4 v[22:25], v[76:77], off
	global_load_dwordx4 v[26:29], v[78:79], off
	global_load_dwordx4 v[30:33], v[80:81], off
	global_load_dwordx4 v[122:125], v[70:71], off offset:128
	global_load_dwordx4 v[126:129], v[68:69], off offset:128
	global_load_dwordx4 v[136:139], v[66:67], off offset:128
	global_load_dwordx4 v[140:143], v[72:73], off offset:128
	global_load_dwordx4 v[144:147], v[74:75], off offset:128
	global_load_dwordx4 v[148:151], v[76:77], off offset:128
	global_load_dwordx4 v[172:175], v[78:79], off offset:128
	global_load_dwordx4 v[176:179], v[80:81], off offset:128
	s_waitcnt vmcnt(15)
	ds_write_b128 v164, v[2:5]
	s_waitcnt vmcnt(14)
	ds_write_b128 v164, v[6:9] offset:4608
	s_waitcnt vmcnt(13)
	ds_write_b128 v164, v[10:13] offset:9216
	s_waitcnt vmcnt(12)
	ds_write_b128 v164, v[14:17] offset:13824
	s_waitcnt vmcnt(11)
	ds_write_b128 v164, v[18:21] offset:36864
	s_waitcnt vmcnt(10)
	ds_write_b128 v164, v[22:25] offset:41472
	s_waitcnt vmcnt(9)
	ds_write_b128 v164, v[26:29] offset:46080
	s_waitcnt vmcnt(8)
	ds_write_b128 v164, v[30:33] offset:50688
	s_waitcnt lgkmcnt(0)
	s_barrier
	global_load_dwordx4 v[180:183], v[68:69], off offset:256
	global_load_dwordx4 v[188:191], v[66:67], off offset:256
	global_load_dwordx4 v[192:195], v[70:71], off offset:256
	global_load_dwordx4 v[196:199], v[72:73], off offset:256
	global_load_dwordx4 v[200:203], v[74:75], off offset:256
	global_load_dwordx4 v[204:207], v[76:77], off offset:256
	global_load_dwordx4 v[208:211], v[78:79], off offset:256
	global_load_dwordx4 v[212:215], v[80:81], off offset:256
	v_and_b32_e32 v246, 15, v1
	v_add_u32_e32 v246, 4, v246
	v_bfe_u32 v246, v246, 3, 1
	v_bfe_u32 v249, v1, 4, 2
	v_xor_b32_e32 v246, v246, v249
	v_bfe_u32 v249, v1, 5, 1
	v_sub_u32_e32 v246, v246, v249
	v_lshlrev_b32_e32 v246, 4, v246
	v_bfe_u32 v249, v1, 4, 1
	v_mul_u32_u24_e32 v249, 0x900, v249
	v_sub_u32_e32 v246, v246, v249
	v_add_u32_e32 v244, v246, v161
	v_add_u32_e32 v245, v246, v163
	ds_read_b128 v[232:235], v245 offset:36864
	ds_read_b128 v[216:219], v244
	ds_read_b128 v[236:239], v245 offset:39168
	ds_read_b128 v[240:243], v245 offset:41472
	ds_read_b128 v[252:255], v245 offset:43776
	ds_read_b128 v[220:223], v244 offset:2304
	ds_read_b128 v[224:227], v244 offset:4608
	ds_read_b128 v[228:231], v244 offset:6912
	s_waitcnt lgkmcnt(6)
	v_mfma_f32_16x16x32_bf16 v[50:53], v[216:219], v[232:235], 0
	s_waitcnt lgkmcnt(5)
	v_mfma_f32_16x16x32_bf16 v[54:57], v[216:219], v[236:239], 0
	s_waitcnt lgkmcnt(4)
	v_mfma_f32_16x16x32_bf16 v[34:37], v[216:219], v[240:243], 0
	s_waitcnt lgkmcnt(3)
	v_mfma_f32_16x16x32_bf16 v[38:41], v[216:219], v[252:255], 0
	ds_read_b128 v[216:219], v244 offset:64
	s_waitcnt lgkmcnt(3)
	v_mfma_f32_16x16x32_bf16 v[58:61], v[220:223], v[232:235], 0
	v_mfma_f32_16x16x32_bf16 v[62:65], v[220:223], v[236:239], 0
	v_mfma_f32_16x16x32_bf16 v[42:45], v[220:223], v[240:243], 0
	v_mfma_f32_16x16x32_bf16 v[46:49], v[220:223], v[252:255], 0
	ds_read_b128 v[220:223], v244 offset:2368
	s_setprio 1
	s_waitcnt vmcnt(15)
	ds_write_b128 v164, v[122:125] offset:18432
	s_waitcnt vmcnt(14)
	ds_write_b128 v164, v[126:129] offset:23040
	s_waitcnt lgkmcnt(5)
	v_mfma_f32_16x16x32_bf16 v[18:21], v[224:227], v[232:235], 0
	v_mfma_f32_16x16x32_bf16 v[22:25], v[224:227], v[236:239], 0
	v_mfma_f32_16x16x32_bf16 v[2:5], v[224:227], v[240:243], 0
	v_mfma_f32_16x16x32_bf16 v[6:9], v[224:227], v[252:255], 0
	ds_read_b128 v[224:227], v244 offset:4672
	s_waitcnt vmcnt(13)
	ds_write_b128 v164, v[136:139] offset:27648
	s_waitcnt vmcnt(12)
	ds_write_b128 v164, v[140:143] offset:32256
	s_waitcnt lgkmcnt(7)
	v_mfma_f32_16x16x32_bf16 v[26:29], v[228:231], v[232:235], 0
	ds_read_b128 v[232:235], v245 offset:36928
	v_mfma_f32_16x16x32_bf16 v[30:33], v[228:231], v[236:239], 0
	ds_read_b128 v[236:239], v245 offset:39232
	v_mfma_f32_16x16x32_bf16 v[10:13], v[228:231], v[240:243], 0
	ds_read_b128 v[240:243], v245 offset:41536
	v_mfma_f32_16x16x32_bf16 v[14:17], v[228:231], v[252:255], 0
	ds_read_b128 v[252:255], v245 offset:43840
	ds_read_b128 v[228:231], v244 offset:6976
	s_waitcnt lgkmcnt(4)
	v_mfma_f32_16x16x32_bf16 v[50:53], v[216:219], v[232:235], v[50:53]
	s_waitcnt lgkmcnt(3)
	v_mfma_f32_16x16x32_bf16 v[54:57], v[216:219], v[236:239], v[54:57]
	s_waitcnt lgkmcnt(2)
	v_mfma_f32_16x16x32_bf16 v[34:37], v[216:219], v[240:243], v[34:37]
	s_waitcnt lgkmcnt(1)
	v_mfma_f32_16x16x32_bf16 v[38:41], v[216:219], v[252:255], v[38:41]
	s_waitcnt vmcnt(11)
	ds_write_b128 v164, v[144:147] offset:55296
	s_waitcnt vmcnt(10)
	ds_write_b128 v164, v[148:151] offset:59904
	v_mfma_f32_16x16x32_bf16 v[58:61], v[220:223], v[232:235], v[58:61]
	v_mfma_f32_16x16x32_bf16 v[62:65], v[220:223], v[236:239], v[62:65]
	v_mfma_f32_16x16x32_bf16 v[42:45], v[220:223], v[240:243], v[42:45]
	v_mfma_f32_16x16x32_bf16 v[46:49], v[220:223], v[252:255], v[46:49]
	s_waitcnt vmcnt(9)
	ds_write_b128 v164, v[172:175] offset:64512
	s_waitcnt vmcnt(8)
	ds_write_b128 v165, v[176:179] offset:32256
	v_mfma_f32_16x16x32_bf16 v[18:21], v[224:227], v[232:235], v[18:21]
	v_mfma_f32_16x16x32_bf16 v[22:25], v[224:227], v[236:239], v[22:25]
	v_mfma_f32_16x16x32_bf16 v[2:5], v[224:227], v[240:243], v[2:5]
	v_mfma_f32_16x16x32_bf16 v[6:9], v[224:227], v[252:255], v[6:9]
	s_waitcnt lgkmcnt(4)
	v_mfma_f32_16x16x32_bf16 v[26:29], v[228:231], v[232:235], v[26:29]
	v_mfma_f32_16x16x32_bf16 v[30:33], v[228:231], v[236:239], v[30:33]
	v_mfma_f32_16x16x32_bf16 v[10:13], v[228:231], v[240:243], v[10:13]
	v_mfma_f32_16x16x32_bf16 v[14:17], v[228:231], v[252:255], v[14:17]
	s_waitcnt lgkmcnt(0)
	s_barrier
	s_setprio 0
	global_load_dwordx4 v[122:125], v[70:71], off offset:384
	global_load_dwordx4 v[126:129], v[68:69], off offset:384
	global_load_dwordx4 v[136:139], v[66:67], off offset:384
	global_load_dwordx4 v[140:143], v[72:73], off offset:384
	global_load_dwordx4 v[144:147], v[74:75], off offset:384
	global_load_dwordx4 v[148:151], v[76:77], off offset:384
	global_load_dwordx4 v[172:175], v[78:79], off offset:384
	global_load_dwordx4 v[176:179], v[80:81], off offset:384
	ds_read_b128 v[232:235], v245 offset:55296
	ds_read_b128 v[216:219], v244 offset:18432
	ds_read_b128 v[236:239], v245 offset:57600
	ds_read_b128 v[240:243], v245 offset:59904
	ds_read_b128 v[252:255], v245 offset:62208
	ds_read_b128 v[220:223], v244 offset:20736
	ds_read_b128 v[224:227], v244 offset:23040
	ds_read_b128 v[228:231], v244 offset:25344
	s_waitcnt lgkmcnt(6)
	v_mfma_f32_16x16x32_bf16 v[50:53], v[216:219], v[232:235], v[50:53]
	s_waitcnt lgkmcnt(5)
	v_mfma_f32_16x16x32_bf16 v[54:57], v[216:219], v[236:239], v[54:57]
	s_waitcnt lgkmcnt(4)
	v_mfma_f32_16x16x32_bf16 v[34:37], v[216:219], v[240:243], v[34:37]
	s_waitcnt lgkmcnt(3)
	v_mfma_f32_16x16x32_bf16 v[38:41], v[216:219], v[252:255], v[38:41]
	ds_read_b128 v[216:219], v244 offset:18496
	s_waitcnt lgkmcnt(3)
	v_mfma_f32_16x16x32_bf16 v[58:61], v[220:223], v[232:235], v[58:61]
	v_mfma_f32_16x16x32_bf16 v[62:65], v[220:223], v[236:239], v[62:65]
	v_mfma_f32_16x16x32_bf16 v[42:45], v[220:223], v[240:243], v[42:45]
	v_mfma_f32_16x16x32_bf16 v[46:49], v[220:223], v[252:255], v[46:49]
	ds_read_b128 v[220:223], v244 offset:20800
	s_setprio 1
	s_waitcnt vmcnt(13)
	ds_write_b128 v164, v[192:195]
	ds_write_b128 v164, v[180:183] offset:4608
	s_waitcnt lgkmcnt(5)
	v_mfma_f32_16x16x32_bf16 v[18:21], v[224:227], v[232:235], v[18:21]
	v_mfma_f32_16x16x32_bf16 v[22:25], v[224:227], v[236:239], v[22:25]
	v_mfma_f32_16x16x32_bf16 v[2:5], v[224:227], v[240:243], v[2:5]
	v_mfma_f32_16x16x32_bf16 v[6:9], v[224:227], v[252:255], v[6:9]
	ds_read_b128 v[224:227], v244 offset:23104
	ds_write_b128 v164, v[188:191] offset:9216
	s_waitcnt vmcnt(12)
	ds_write_b128 v164, v[196:199] offset:13824
	s_waitcnt lgkmcnt(7)
	v_mfma_f32_16x16x32_bf16 v[26:29], v[228:231], v[232:235], v[26:29]
	ds_read_b128 v[232:235], v245 offset:55360
	v_mfma_f32_16x16x32_bf16 v[30:33], v[228:231], v[236:239], v[30:33]
	ds_read_b128 v[236:239], v245 offset:57664
	v_mfma_f32_16x16x32_bf16 v[10:13], v[228:231], v[240:243], v[10:13]
	ds_read_b128 v[240:243], v245 offset:59968
	v_mfma_f32_16x16x32_bf16 v[14:17], v[228:231], v[252:255], v[14:17]
	ds_read_b128 v[252:255], v245 offset:62272
	ds_read_b128 v[228:231], v244 offset:25408
	s_waitcnt lgkmcnt(4)
	v_mfma_f32_16x16x32_bf16 v[50:53], v[216:219], v[232:235], v[50:53]
	s_waitcnt lgkmcnt(3)
	v_mfma_f32_16x16x32_bf16 v[54:57], v[216:219], v[236:239], v[54:57]
	s_waitcnt lgkmcnt(2)
	v_mfma_f32_16x16x32_bf16 v[34:37], v[216:219], v[240:243], v[34:37]
	s_waitcnt lgkmcnt(1)
	v_mfma_f32_16x16x32_bf16 v[38:41], v[216:219], v[252:255], v[38:41]
	s_waitcnt vmcnt(11)
	ds_write_b128 v164, v[200:203] offset:36864
	s_waitcnt vmcnt(10)
	ds_write_b128 v164, v[204:207] offset:41472
	v_mfma_f32_16x16x32_bf16 v[58:61], v[220:223], v[232:235], v[58:61]
	v_mfma_f32_16x16x32_bf16 v[62:65], v[220:223], v[236:239], v[62:65]
	v_mfma_f32_16x16x32_bf16 v[42:45], v[220:223], v[240:243], v[42:45]
	v_mfma_f32_16x16x32_bf16 v[46:49], v[220:223], v[252:255], v[46:49]
	s_waitcnt vmcnt(9)
	ds_write_b128 v164, v[208:211] offset:46080
	s_waitcnt vmcnt(8)
	ds_write_b128 v164, v[212:215] offset:50688
	v_mfma_f32_16x16x32_bf16 v[18:21], v[224:227], v[232:235], v[18:21]
	v_mfma_f32_16x16x32_bf16 v[22:25], v[224:227], v[236:239], v[22:25]
	v_mfma_f32_16x16x32_bf16 v[2:5], v[224:227], v[240:243], v[2:5]
	v_mfma_f32_16x16x32_bf16 v[6:9], v[224:227], v[252:255], v[6:9]
	s_waitcnt lgkmcnt(4)
	v_mfma_f32_16x16x32_bf16 v[26:29], v[228:231], v[232:235], v[26:29]
	v_mfma_f32_16x16x32_bf16 v[30:33], v[228:231], v[236:239], v[30:33]
	v_mfma_f32_16x16x32_bf16 v[10:13], v[228:231], v[240:243], v[10:13]
	v_mfma_f32_16x16x32_bf16 v[14:17], v[228:231], v[252:255], v[14:17]
	s_waitcnt lgkmcnt(0)
	s_barrier
	s_setprio 0
	global_load_dwordx4 v[180:183], v[70:71], off offset:512
	global_load_dwordx4 v[188:191], v[68:69], off offset:512
	global_load_dwordx4 v[192:195], v[66:67], off offset:512
	global_load_dwordx4 v[196:199], v[72:73], off offset:512
	global_load_dwordx4 v[200:203], v[74:75], off offset:512
	global_load_dwordx4 v[204:207], v[76:77], off offset:512
	global_load_dwordx4 v[208:211], v[78:79], off offset:512
	global_load_dwordx4 v[212:215], v[80:81], off offset:512
	ds_read_b128 v[232:235], v245 offset:36864
	ds_read_b128 v[216:219], v244
	ds_read_b128 v[236:239], v245 offset:39168
	ds_read_b128 v[240:243], v245 offset:41472
	ds_read_b128 v[252:255], v245 offset:43776
	ds_read_b128 v[220:223], v244 offset:2304
	ds_read_b128 v[224:227], v244 offset:4608
	ds_read_b128 v[228:231], v244 offset:6912
	s_waitcnt lgkmcnt(6)
	v_mfma_f32_16x16x32_bf16 v[50:53], v[216:219], v[232:235], v[50:53]
	s_waitcnt lgkmcnt(5)
	v_mfma_f32_16x16x32_bf16 v[54:57], v[216:219], v[236:239], v[54:57]
	s_waitcnt lgkmcnt(4)
	v_mfma_f32_16x16x32_bf16 v[34:37], v[216:219], v[240:243], v[34:37]
	s_waitcnt lgkmcnt(3)
	v_mfma_f32_16x16x32_bf16 v[38:41], v[216:219], v[252:255], v[38:41]
	ds_read_b128 v[216:219], v244 offset:64
	s_waitcnt lgkmcnt(3)
	v_mfma_f32_16x16x32_bf16 v[58:61], v[220:223], v[232:235], v[58:61]
	v_mfma_f32_16x16x32_bf16 v[62:65], v[220:223], v[236:239], v[62:65]
	v_mfma_f32_16x16x32_bf16 v[42:45], v[220:223], v[240:243], v[42:45]
	v_mfma_f32_16x16x32_bf16 v[46:49], v[220:223], v[252:255], v[46:49]
	ds_read_b128 v[220:223], v244 offset:2368
	s_setprio 1
	s_waitcnt vmcnt(15)
	ds_write_b128 v164, v[122:125] offset:18432
	s_waitcnt vmcnt(14)
	ds_write_b128 v164, v[126:129] offset:23040
	s_waitcnt lgkmcnt(5)
	v_mfma_f32_16x16x32_bf16 v[18:21], v[224:227], v[232:235], v[18:21]
	v_mfma_f32_16x16x32_bf16 v[22:25], v[224:227], v[236:239], v[22:25]
	v_mfma_f32_16x16x32_bf16 v[2:5], v[224:227], v[240:243], v[2:5]
	v_mfma_f32_16x16x32_bf16 v[6:9], v[224:227], v[252:255], v[6:9]
	ds_read_b128 v[224:227], v244 offset:4672
	s_waitcnt vmcnt(13)
	ds_write_b128 v164, v[136:139] offset:27648
	s_waitcnt vmcnt(12)
	ds_write_b128 v164, v[140:143] offset:32256
	s_waitcnt lgkmcnt(7)
	v_mfma_f32_16x16x32_bf16 v[26:29], v[228:231], v[232:235], v[26:29]
	ds_read_b128 v[232:235], v245 offset:36928
	v_mfma_f32_16x16x32_bf16 v[30:33], v[228:231], v[236:239], v[30:33]
	ds_read_b128 v[236:239], v245 offset:39232
	v_mfma_f32_16x16x32_bf16 v[10:13], v[228:231], v[240:243], v[10:13]
	ds_read_b128 v[240:243], v245 offset:41536
	v_mfma_f32_16x16x32_bf16 v[14:17], v[228:231], v[252:255], v[14:17]
	ds_read_b128 v[252:255], v245 offset:43840
	ds_read_b128 v[228:231], v244 offset:6976
	s_waitcnt lgkmcnt(4)
	v_mfma_f32_16x16x32_bf16 v[50:53], v[216:219], v[232:235], v[50:53]
	s_waitcnt lgkmcnt(3)
	v_mfma_f32_16x16x32_bf16 v[54:57], v[216:219], v[236:239], v[54:57]
	s_waitcnt lgkmcnt(2)
	v_mfma_f32_16x16x32_bf16 v[34:37], v[216:219], v[240:243], v[34:37]
	s_waitcnt lgkmcnt(1)
	v_mfma_f32_16x16x32_bf16 v[38:41], v[216:219], v[252:255], v[38:41]
	s_waitcnt vmcnt(11)
	ds_write_b128 v164, v[144:147] offset:55296
	s_waitcnt vmcnt(10)
	ds_write_b128 v164, v[148:151] offset:59904
	v_mfma_f32_16x16x32_bf16 v[58:61], v[220:223], v[232:235], v[58:61]
	v_mfma_f32_16x16x32_bf16 v[62:65], v[220:223], v[236:239], v[62:65]
	v_mfma_f32_16x16x32_bf16 v[42:45], v[220:223], v[240:243], v[42:45]
	v_mfma_f32_16x16x32_bf16 v[46:49], v[220:223], v[252:255], v[46:49]
	s_waitcnt vmcnt(9)
	ds_write_b128 v164, v[172:175] offset:64512
	s_waitcnt vmcnt(8)
	ds_write_b128 v165, v[176:179] offset:32256
	v_mfma_f32_16x16x32_bf16 v[18:21], v[224:227], v[232:235], v[18:21]
	v_mfma_f32_16x16x32_bf16 v[22:25], v[224:227], v[236:239], v[22:25]
	v_mfma_f32_16x16x32_bf16 v[2:5], v[224:227], v[240:243], v[2:5]
	v_mfma_f32_16x16x32_bf16 v[6:9], v[224:227], v[252:255], v[6:9]
	s_waitcnt lgkmcnt(4)
	v_mfma_f32_16x16x32_bf16 v[26:29], v[228:231], v[232:235], v[26:29]
	v_mfma_f32_16x16x32_bf16 v[30:33], v[228:231], v[236:239], v[30:33]
	v_mfma_f32_16x16x32_bf16 v[10:13], v[228:231], v[240:243], v[10:13]
	v_mfma_f32_16x16x32_bf16 v[14:17], v[228:231], v[252:255], v[14:17]
	s_waitcnt lgkmcnt(0)
	s_barrier
	s_setprio 0
	global_load_dwordx4 v[122:125], v[70:71], off offset:640
	global_load_dwordx4 v[126:129], v[68:69], off offset:640
	global_load_dwordx4 v[136:139], v[66:67], off offset:640
	global_load_dwordx4 v[140:143], v[72:73], off offset:640
	global_load_dwordx4 v[144:147], v[74:75], off offset:640
	global_load_dwordx4 v[148:151], v[76:77], off offset:640
	global_load_dwordx4 v[172:175], v[78:79], off offset:640
	global_load_dwordx4 v[176:179], v[80:81], off offset:640
	ds_read_b128 v[232:235], v245 offset:55296
	ds_read_b128 v[216:219], v244 offset:18432
	ds_read_b128 v[236:239], v245 offset:57600
	ds_read_b128 v[240:243], v245 offset:59904
	ds_read_b128 v[252:255], v245 offset:62208
	ds_read_b128 v[220:223], v244 offset:20736
	ds_read_b128 v[224:227], v244 offset:23040
	ds_read_b128 v[228:231], v244 offset:25344
	s_waitcnt lgkmcnt(6)
	v_mfma_f32_16x16x32_bf16 v[50:53], v[216:219], v[232:235], v[50:53]
	s_waitcnt lgkmcnt(5)
	v_mfma_f32_16x16x32_bf16 v[54:57], v[216:219], v[236:239], v[54:57]
	s_waitcnt lgkmcnt(4)
	v_mfma_f32_16x16x32_bf16 v[34:37], v[216:219], v[240:243], v[34:37]
	s_waitcnt lgkmcnt(3)
	v_mfma_f32_16x16x32_bf16 v[38:41], v[216:219], v[252:255], v[38:41]
	ds_read_b128 v[216:219], v244 offset:18496
	s_waitcnt lgkmcnt(3)
	v_mfma_f32_16x16x32_bf16 v[58:61], v[220:223], v[232:235], v[58:61]
	v_mfma_f32_16x16x32_bf16 v[62:65], v[220:223], v[236:239], v[62:65]
	v_mfma_f32_16x16x32_bf16 v[42:45], v[220:223], v[240:243], v[42:45]
	v_mfma_f32_16x16x32_bf16 v[46:49], v[220:223], v[252:255], v[46:49]
	ds_read_b128 v[220:223], v244 offset:20800
	s_setprio 1
	s_waitcnt vmcnt(15)
	ds_write_b128 v164, v[180:183]
	s_waitcnt vmcnt(14)
	ds_write_b128 v164, v[188:191] offset:4608
	s_waitcnt lgkmcnt(5)
	v_mfma_f32_16x16x32_bf16 v[18:21], v[224:227], v[232:235], v[18:21]
	v_mfma_f32_16x16x32_bf16 v[22:25], v[224:227], v[236:239], v[22:25]
	v_mfma_f32_16x16x32_bf16 v[2:5], v[224:227], v[240:243], v[2:5]
	v_mfma_f32_16x16x32_bf16 v[6:9], v[224:227], v[252:255], v[6:9]
	ds_read_b128 v[224:227], v244 offset:23104
	s_waitcnt vmcnt(13)
	ds_write_b128 v164, v[192:195] offset:9216
	s_waitcnt vmcnt(12)
	ds_write_b128 v164, v[196:199] offset:13824
	s_waitcnt lgkmcnt(7)
	v_mfma_f32_16x16x32_bf16 v[26:29], v[228:231], v[232:235], v[26:29]
	ds_read_b128 v[232:235], v245 offset:55360
	v_mfma_f32_16x16x32_bf16 v[30:33], v[228:231], v[236:239], v[30:33]
	ds_read_b128 v[236:239], v245 offset:57664
	v_mfma_f32_16x16x32_bf16 v[10:13], v[228:231], v[240:243], v[10:13]
	ds_read_b128 v[240:243], v245 offset:59968
	v_mfma_f32_16x16x32_bf16 v[14:17], v[228:231], v[252:255], v[14:17]
	ds_read_b128 v[252:255], v245 offset:62272
	ds_read_b128 v[228:231], v244 offset:25408
	s_waitcnt lgkmcnt(4)
	v_mfma_f32_16x16x32_bf16 v[50:53], v[216:219], v[232:235], v[50:53]
	s_waitcnt lgkmcnt(3)
	v_mfma_f32_16x16x32_bf16 v[54:57], v[216:219], v[236:239], v[54:57]
	s_waitcnt lgkmcnt(2)
	v_mfma_f32_16x16x32_bf16 v[34:37], v[216:219], v[240:243], v[34:37]
	s_waitcnt lgkmcnt(1)
	v_mfma_f32_16x16x32_bf16 v[38:41], v[216:219], v[252:255], v[38:41]
	s_waitcnt vmcnt(11)
	ds_write_b128 v164, v[200:203] offset:36864
	s_waitcnt vmcnt(10)
	ds_write_b128 v164, v[204:207] offset:41472
	v_mfma_f32_16x16x32_bf16 v[58:61], v[220:223], v[232:235], v[58:61]
	v_mfma_f32_16x16x32_bf16 v[62:65], v[220:223], v[236:239], v[62:65]
	v_mfma_f32_16x16x32_bf16 v[42:45], v[220:223], v[240:243], v[42:45]
	v_mfma_f32_16x16x32_bf16 v[46:49], v[220:223], v[252:255], v[46:49]
	s_waitcnt vmcnt(9)
	ds_write_b128 v164, v[208:211] offset:46080
	s_waitcnt vmcnt(8)
	ds_write_b128 v164, v[212:215] offset:50688
	v_mfma_f32_16x16x32_bf16 v[18:21], v[224:227], v[232:235], v[18:21]
	v_mfma_f32_16x16x32_bf16 v[22:25], v[224:227], v[236:239], v[22:25]
	v_mfma_f32_16x16x32_bf16 v[2:5], v[224:227], v[240:243], v[2:5]
	v_mfma_f32_16x16x32_bf16 v[6:9], v[224:227], v[252:255], v[6:9]
	s_waitcnt lgkmcnt(4)
	v_mfma_f32_16x16x32_bf16 v[26:29], v[228:231], v[232:235], v[26:29]
	v_mfma_f32_16x16x32_bf16 v[30:33], v[228:231], v[236:239], v[30:33]
	v_mfma_f32_16x16x32_bf16 v[10:13], v[228:231], v[240:243], v[10:13]
	v_mfma_f32_16x16x32_bf16 v[14:17], v[228:231], v[252:255], v[14:17]
	s_waitcnt lgkmcnt(0)
	s_barrier
	s_setprio 0
	global_load_dwordx4 v[180:183], v[70:71], off offset:768
	global_load_dwordx4 v[188:191], v[68:69], off offset:768
	global_load_dwordx4 v[192:195], v[66:67], off offset:768
	global_load_dwordx4 v[196:199], v[72:73], off offset:768
	global_load_dwordx4 v[200:203], v[74:75], off offset:768
	global_load_dwordx4 v[204:207], v[76:77], off offset:768
	global_load_dwordx4 v[208:211], v[78:79], off offset:768
	global_load_dwordx4 v[212:215], v[80:81], off offset:768
	ds_read_b128 v[232:235], v245 offset:36864
	ds_read_b128 v[216:219], v244
	ds_read_b128 v[236:239], v245 offset:39168
	ds_read_b128 v[240:243], v245 offset:41472
	ds_read_b128 v[252:255], v245 offset:43776
	ds_read_b128 v[220:223], v244 offset:2304
	ds_read_b128 v[224:227], v244 offset:4608
	ds_read_b128 v[228:231], v244 offset:6912
	s_waitcnt lgkmcnt(6)
	v_mfma_f32_16x16x32_bf16 v[50:53], v[216:219], v[232:235], v[50:53]
	s_waitcnt lgkmcnt(5)
	v_mfma_f32_16x16x32_bf16 v[54:57], v[216:219], v[236:239], v[54:57]
	s_waitcnt lgkmcnt(4)
	v_mfma_f32_16x16x32_bf16 v[34:37], v[216:219], v[240:243], v[34:37]
	s_waitcnt lgkmcnt(3)
	v_mfma_f32_16x16x32_bf16 v[38:41], v[216:219], v[252:255], v[38:41]
	ds_read_b128 v[216:219], v244 offset:64
	s_waitcnt lgkmcnt(3)
	v_mfma_f32_16x16x32_bf16 v[58:61], v[220:223], v[232:235], v[58:61]
	v_mfma_f32_16x16x32_bf16 v[62:65], v[220:223], v[236:239], v[62:65]
	v_mfma_f32_16x16x32_bf16 v[42:45], v[220:223], v[240:243], v[42:45]
	v_mfma_f32_16x16x32_bf16 v[46:49], v[220:223], v[252:255], v[46:49]
	ds_read_b128 v[220:223], v244 offset:2368
	s_setprio 1
	s_waitcnt vmcnt(15)
	ds_write_b128 v164, v[122:125] offset:18432
	s_waitcnt vmcnt(14)
	ds_write_b128 v164, v[126:129] offset:23040
	s_waitcnt lgkmcnt(5)
	v_mfma_f32_16x16x32_bf16 v[18:21], v[224:227], v[232:235], v[18:21]
	v_mfma_f32_16x16x32_bf16 v[22:25], v[224:227], v[236:239], v[22:25]
	v_mfma_f32_16x16x32_bf16 v[2:5], v[224:227], v[240:243], v[2:5]
	v_mfma_f32_16x16x32_bf16 v[6:9], v[224:227], v[252:255], v[6:9]
	ds_read_b128 v[224:227], v244 offset:4672
	s_waitcnt vmcnt(13)
	ds_write_b128 v164, v[136:139] offset:27648
	s_waitcnt vmcnt(12)
	ds_write_b128 v164, v[140:143] offset:32256
	s_waitcnt lgkmcnt(7)
	v_mfma_f32_16x16x32_bf16 v[26:29], v[228:231], v[232:235], v[26:29]
	ds_read_b128 v[232:235], v245 offset:36928
	v_mfma_f32_16x16x32_bf16 v[30:33], v[228:231], v[236:239], v[30:33]
	ds_read_b128 v[236:239], v245 offset:39232
	v_mfma_f32_16x16x32_bf16 v[10:13], v[228:231], v[240:243], v[10:13]
	ds_read_b128 v[240:243], v245 offset:41536
	v_mfma_f32_16x16x32_bf16 v[14:17], v[228:231], v[252:255], v[14:17]
	ds_read_b128 v[252:255], v245 offset:43840
	ds_read_b128 v[228:231], v244 offset:6976
	s_waitcnt lgkmcnt(4)
	v_mfma_f32_16x16x32_bf16 v[50:53], v[216:219], v[232:235], v[50:53]
	s_waitcnt lgkmcnt(3)
	v_mfma_f32_16x16x32_bf16 v[54:57], v[216:219], v[236:239], v[54:57]
	s_waitcnt lgkmcnt(2)
	v_mfma_f32_16x16x32_bf16 v[34:37], v[216:219], v[240:243], v[34:37]
	s_waitcnt lgkmcnt(1)
	v_mfma_f32_16x16x32_bf16 v[38:41], v[216:219], v[252:255], v[38:41]
	s_waitcnt vmcnt(11)
	ds_write_b128 v164, v[144:147] offset:55296
	s_waitcnt vmcnt(10)
	ds_write_b128 v164, v[148:151] offset:59904
	v_mfma_f32_16x16x32_bf16 v[58:61], v[220:223], v[232:235], v[58:61]
	v_mfma_f32_16x16x32_bf16 v[62:65], v[220:223], v[236:239], v[62:65]
	v_mfma_f32_16x16x32_bf16 v[42:45], v[220:223], v[240:243], v[42:45]
	v_mfma_f32_16x16x32_bf16 v[46:49], v[220:223], v[252:255], v[46:49]
	s_waitcnt vmcnt(9)
	ds_write_b128 v164, v[172:175] offset:64512
	s_waitcnt vmcnt(8)
	ds_write_b128 v165, v[176:179] offset:32256
	v_mfma_f32_16x16x32_bf16 v[18:21], v[224:227], v[232:235], v[18:21]
	v_mfma_f32_16x16x32_bf16 v[22:25], v[224:227], v[236:239], v[22:25]
	v_mfma_f32_16x16x32_bf16 v[2:5], v[224:227], v[240:243], v[2:5]
	v_mfma_f32_16x16x32_bf16 v[6:9], v[224:227], v[252:255], v[6:9]
	s_waitcnt lgkmcnt(4)
	v_mfma_f32_16x16x32_bf16 v[26:29], v[228:231], v[232:235], v[26:29]
	v_mfma_f32_16x16x32_bf16 v[30:33], v[228:231], v[236:239], v[30:33]
	v_mfma_f32_16x16x32_bf16 v[10:13], v[228:231], v[240:243], v[10:13]
	v_mfma_f32_16x16x32_bf16 v[14:17], v[228:231], v[252:255], v[14:17]
	s_waitcnt lgkmcnt(0)
	s_barrier
	s_setprio 0
	global_load_dwordx4 v[122:125], v[70:71], off offset:896
	global_load_dwordx4 v[126:129], v[68:69], off offset:896
	global_load_dwordx4 v[136:139], v[66:67], off offset:896
	global_load_dwordx4 v[140:143], v[72:73], off offset:896
	global_load_dwordx4 v[144:147], v[74:75], off offset:896
	global_load_dwordx4 v[148:151], v[76:77], off offset:896
	global_load_dwordx4 v[172:175], v[78:79], off offset:896
	global_load_dwordx4 v[176:179], v[80:81], off offset:896
	ds_read_b128 v[232:235], v245 offset:55296
	ds_read_b128 v[216:219], v244 offset:18432
	ds_read_b128 v[236:239], v245 offset:57600
	ds_read_b128 v[240:243], v245 offset:59904
	ds_read_b128 v[252:255], v245 offset:62208
	ds_read_b128 v[220:223], v244 offset:20736
	ds_read_b128 v[224:227], v244 offset:23040
	ds_read_b128 v[228:231], v244 offset:25344
	s_waitcnt lgkmcnt(6)
	v_mfma_f32_16x16x32_bf16 v[50:53], v[216:219], v[232:235], v[50:53]
	s_waitcnt lgkmcnt(5)
	v_mfma_f32_16x16x32_bf16 v[54:57], v[216:219], v[236:239], v[54:57]
	s_waitcnt lgkmcnt(4)
	v_mfma_f32_16x16x32_bf16 v[34:37], v[216:219], v[240:243], v[34:37]
	s_waitcnt lgkmcnt(3)
	v_mfma_f32_16x16x32_bf16 v[38:41], v[216:219], v[252:255], v[38:41]
	ds_read_b128 v[216:219], v244 offset:18496
	s_waitcnt lgkmcnt(3)
	v_mfma_f32_16x16x32_bf16 v[58:61], v[220:223], v[232:235], v[58:61]
	v_mfma_f32_16x16x32_bf16 v[62:65], v[220:223], v[236:239], v[62:65]
	v_mfma_f32_16x16x32_bf16 v[42:45], v[220:223], v[240:243], v[42:45]
	v_mfma_f32_16x16x32_bf16 v[46:49], v[220:223], v[252:255], v[46:49]
	ds_read_b128 v[220:223], v244 offset:20800
	s_setprio 1
	s_waitcnt vmcnt(15)
	ds_write_b128 v164, v[180:183]
	s_waitcnt vmcnt(14)
	ds_write_b128 v164, v[188:191] offset:4608
	s_waitcnt lgkmcnt(5)
	v_mfma_f32_16x16x32_bf16 v[18:21], v[224:227], v[232:235], v[18:21]
	v_mfma_f32_16x16x32_bf16 v[22:25], v[224:227], v[236:239], v[22:25]
	v_mfma_f32_16x16x32_bf16 v[2:5], v[224:227], v[240:243], v[2:5]
	v_mfma_f32_16x16x32_bf16 v[6:9], v[224:227], v[252:255], v[6:9]
	ds_read_b128 v[224:227], v244 offset:23104
	s_waitcnt vmcnt(13)
	ds_write_b128 v164, v[192:195] offset:9216
	s_waitcnt vmcnt(12)
	ds_write_b128 v164, v[196:199] offset:13824
	s_waitcnt lgkmcnt(7)
	v_mfma_f32_16x16x32_bf16 v[26:29], v[228:231], v[232:235], v[26:29]
	ds_read_b128 v[232:235], v245 offset:55360
	v_mfma_f32_16x16x32_bf16 v[30:33], v[228:231], v[236:239], v[30:33]
	ds_read_b128 v[236:239], v245 offset:57664
	v_mfma_f32_16x16x32_bf16 v[10:13], v[228:231], v[240:243], v[10:13]
	ds_read_b128 v[240:243], v245 offset:59968
	v_mfma_f32_16x16x32_bf16 v[14:17], v[228:231], v[252:255], v[14:17]
	ds_read_b128 v[252:255], v245 offset:62272
	ds_read_b128 v[228:231], v244 offset:25408
	s_waitcnt lgkmcnt(4)
	v_mfma_f32_16x16x32_bf16 v[50:53], v[216:219], v[232:235], v[50:53]
	s_waitcnt lgkmcnt(3)
	v_mfma_f32_16x16x32_bf16 v[54:57], v[216:219], v[236:239], v[54:57]
	s_waitcnt lgkmcnt(2)
	v_mfma_f32_16x16x32_bf16 v[34:37], v[216:219], v[240:243], v[34:37]
	s_waitcnt lgkmcnt(1)
	v_mfma_f32_16x16x32_bf16 v[38:41], v[216:219], v[252:255], v[38:41]
	s_waitcnt vmcnt(11)
	ds_write_b128 v164, v[200:203] offset:36864
	s_waitcnt vmcnt(10)
	ds_write_b128 v164, v[204:207] offset:41472
	v_mfma_f32_16x16x32_bf16 v[58:61], v[220:223], v[232:235], v[58:61]
	v_mfma_f32_16x16x32_bf16 v[62:65], v[220:223], v[236:239], v[62:65]
	v_mfma_f32_16x16x32_bf16 v[42:45], v[220:223], v[240:243], v[42:45]
	v_mfma_f32_16x16x32_bf16 v[46:49], v[220:223], v[252:255], v[46:49]
	s_waitcnt vmcnt(9)
	ds_write_b128 v164, v[208:211] offset:46080
	s_waitcnt vmcnt(8)
	ds_write_b128 v164, v[212:215] offset:50688
	v_mfma_f32_16x16x32_bf16 v[18:21], v[224:227], v[232:235], v[18:21]
	v_mfma_f32_16x16x32_bf16 v[22:25], v[224:227], v[236:239], v[22:25]
	v_mfma_f32_16x16x32_bf16 v[2:5], v[224:227], v[240:243], v[2:5]
	v_mfma_f32_16x16x32_bf16 v[6:9], v[224:227], v[252:255], v[6:9]
	s_waitcnt lgkmcnt(4)
	v_mfma_f32_16x16x32_bf16 v[26:29], v[228:231], v[232:235], v[26:29]
	v_mfma_f32_16x16x32_bf16 v[30:33], v[228:231], v[236:239], v[30:33]
	v_mfma_f32_16x16x32_bf16 v[10:13], v[228:231], v[240:243], v[10:13]
	v_mfma_f32_16x16x32_bf16 v[14:17], v[228:231], v[252:255], v[14:17]
	s_waitcnt lgkmcnt(0)
	s_barrier
	s_setprio 0
	global_load_dwordx4 v[180:183], v[70:71], off offset:1024
	global_load_dwordx4 v[188:191], v[68:69], off offset:1024
	global_load_dwordx4 v[192:195], v[66:67], off offset:1024
	global_load_dwordx4 v[196:199], v[72:73], off offset:1024
	global_load_dwordx4 v[200:203], v[74:75], off offset:1024
	global_load_dwordx4 v[204:207], v[76:77], off offset:1024
	global_load_dwordx4 v[208:211], v[78:79], off offset:1024
	global_load_dwordx4 v[212:215], v[80:81], off offset:1024
	ds_read_b128 v[232:235], v245 offset:36864
	ds_read_b128 v[216:219], v244
	ds_read_b128 v[236:239], v245 offset:39168
	ds_read_b128 v[240:243], v245 offset:41472
	ds_read_b128 v[252:255], v245 offset:43776
	ds_read_b128 v[220:223], v244 offset:2304
	ds_read_b128 v[224:227], v244 offset:4608
	ds_read_b128 v[228:231], v244 offset:6912
	s_waitcnt lgkmcnt(6)
	v_mfma_f32_16x16x32_bf16 v[50:53], v[216:219], v[232:235], v[50:53]
	s_waitcnt lgkmcnt(5)
	v_mfma_f32_16x16x32_bf16 v[54:57], v[216:219], v[236:239], v[54:57]
	s_waitcnt lgkmcnt(4)
	v_mfma_f32_16x16x32_bf16 v[34:37], v[216:219], v[240:243], v[34:37]
	s_waitcnt lgkmcnt(3)
	v_mfma_f32_16x16x32_bf16 v[38:41], v[216:219], v[252:255], v[38:41]
	ds_read_b128 v[216:219], v244 offset:64
	s_waitcnt lgkmcnt(3)
	v_mfma_f32_16x16x32_bf16 v[58:61], v[220:223], v[232:235], v[58:61]
	v_mfma_f32_16x16x32_bf16 v[62:65], v[220:223], v[236:239], v[62:65]
	v_mfma_f32_16x16x32_bf16 v[42:45], v[220:223], v[240:243], v[42:45]
	v_mfma_f32_16x16x32_bf16 v[46:49], v[220:223], v[252:255], v[46:49]
	ds_read_b128 v[220:223], v244 offset:2368
	s_setprio 1
	s_waitcnt vmcnt(15)
	ds_write_b128 v164, v[122:125] offset:18432
	s_waitcnt vmcnt(14)
	ds_write_b128 v164, v[126:129] offset:23040
	s_waitcnt lgkmcnt(5)
	v_mfma_f32_16x16x32_bf16 v[18:21], v[224:227], v[232:235], v[18:21]
	v_mfma_f32_16x16x32_bf16 v[22:25], v[224:227], v[236:239], v[22:25]
	v_mfma_f32_16x16x32_bf16 v[2:5], v[224:227], v[240:243], v[2:5]
	v_mfma_f32_16x16x32_bf16 v[6:9], v[224:227], v[252:255], v[6:9]
	ds_read_b128 v[224:227], v244 offset:4672
	s_waitcnt vmcnt(13)
	ds_write_b128 v164, v[136:139] offset:27648
	s_waitcnt vmcnt(12)
	ds_write_b128 v164, v[140:143] offset:32256
	s_waitcnt lgkmcnt(7)
	v_mfma_f32_16x16x32_bf16 v[26:29], v[228:231], v[232:235], v[26:29]
	ds_read_b128 v[232:235], v245 offset:36928
	v_mfma_f32_16x16x32_bf16 v[30:33], v[228:231], v[236:239], v[30:33]
	ds_read_b128 v[236:239], v245 offset:39232
	v_mfma_f32_16x16x32_bf16 v[10:13], v[228:231], v[240:243], v[10:13]
	ds_read_b128 v[240:243], v245 offset:41536
	v_mfma_f32_16x16x32_bf16 v[14:17], v[228:231], v[252:255], v[14:17]
	ds_read_b128 v[252:255], v245 offset:43840
	ds_read_b128 v[228:231], v244 offset:6976
	s_waitcnt lgkmcnt(4)
	v_mfma_f32_16x16x32_bf16 v[50:53], v[216:219], v[232:235], v[50:53]
	s_waitcnt lgkmcnt(3)
	v_mfma_f32_16x16x32_bf16 v[54:57], v[216:219], v[236:239], v[54:57]
	s_waitcnt lgkmcnt(2)
	v_mfma_f32_16x16x32_bf16 v[34:37], v[216:219], v[240:243], v[34:37]
	s_waitcnt lgkmcnt(1)
	v_mfma_f32_16x16x32_bf16 v[38:41], v[216:219], v[252:255], v[38:41]
	s_waitcnt vmcnt(11)
	ds_write_b128 v164, v[144:147] offset:55296
	s_waitcnt vmcnt(10)
	ds_write_b128 v164, v[148:151] offset:59904
	v_mfma_f32_16x16x32_bf16 v[58:61], v[220:223], v[232:235], v[58:61]
	v_mfma_f32_16x16x32_bf16 v[62:65], v[220:223], v[236:239], v[62:65]
	v_mfma_f32_16x16x32_bf16 v[42:45], v[220:223], v[240:243], v[42:45]
	v_mfma_f32_16x16x32_bf16 v[46:49], v[220:223], v[252:255], v[46:49]
	s_waitcnt vmcnt(9)
	ds_write_b128 v164, v[172:175] offset:64512
	s_waitcnt vmcnt(8)
	ds_write_b128 v165, v[176:179] offset:32256
	v_mfma_f32_16x16x32_bf16 v[18:21], v[224:227], v[232:235], v[18:21]
	v_mfma_f32_16x16x32_bf16 v[22:25], v[224:227], v[236:239], v[22:25]
	v_mfma_f32_16x16x32_bf16 v[2:5], v[224:227], v[240:243], v[2:5]
	v_mfma_f32_16x16x32_bf16 v[6:9], v[224:227], v[252:255], v[6:9]
	s_waitcnt lgkmcnt(4)
	v_mfma_f32_16x16x32_bf16 v[26:29], v[228:231], v[232:235], v[26:29]
	v_mfma_f32_16x16x32_bf16 v[30:33], v[228:231], v[236:239], v[30:33]
	v_mfma_f32_16x16x32_bf16 v[10:13], v[228:231], v[240:243], v[10:13]
	v_mfma_f32_16x16x32_bf16 v[14:17], v[228:231], v[252:255], v[14:17]
	s_waitcnt lgkmcnt(0)
	s_barrier
	s_setprio 0
	global_load_dwordx4 v[122:125], v[70:71], off offset:1152
	global_load_dwordx4 v[126:129], v[68:69], off offset:1152
	global_load_dwordx4 v[136:139], v[66:67], off offset:1152
	global_load_dwordx4 v[140:143], v[72:73], off offset:1152
	global_load_dwordx4 v[144:147], v[74:75], off offset:1152
	global_load_dwordx4 v[148:151], v[76:77], off offset:1152
	global_load_dwordx4 v[172:175], v[78:79], off offset:1152
	global_load_dwordx4 v[176:179], v[80:81], off offset:1152
	ds_read_b128 v[232:235], v245 offset:55296
	ds_read_b128 v[216:219], v244 offset:18432
	ds_read_b128 v[236:239], v245 offset:57600
	ds_read_b128 v[240:243], v245 offset:59904
	ds_read_b128 v[252:255], v245 offset:62208
	ds_read_b128 v[220:223], v244 offset:20736
	ds_read_b128 v[224:227], v244 offset:23040
	ds_read_b128 v[228:231], v244 offset:25344
	s_waitcnt lgkmcnt(6)
	v_mfma_f32_16x16x32_bf16 v[50:53], v[216:219], v[232:235], v[50:53]
	s_waitcnt lgkmcnt(5)
	v_mfma_f32_16x16x32_bf16 v[54:57], v[216:219], v[236:239], v[54:57]
	s_waitcnt lgkmcnt(4)
	v_mfma_f32_16x16x32_bf16 v[34:37], v[216:219], v[240:243], v[34:37]
	s_waitcnt lgkmcnt(3)
	v_mfma_f32_16x16x32_bf16 v[38:41], v[216:219], v[252:255], v[38:41]
	ds_read_b128 v[216:219], v244 offset:18496
	s_waitcnt lgkmcnt(3)
	v_mfma_f32_16x16x32_bf16 v[58:61], v[220:223], v[232:235], v[58:61]
	v_mfma_f32_16x16x32_bf16 v[62:65], v[220:223], v[236:239], v[62:65]
	v_mfma_f32_16x16x32_bf16 v[42:45], v[220:223], v[240:243], v[42:45]
	v_mfma_f32_16x16x32_bf16 v[46:49], v[220:223], v[252:255], v[46:49]
	ds_read_b128 v[220:223], v244 offset:20800
	s_setprio 1
	s_waitcnt vmcnt(15)
	ds_write_b128 v164, v[180:183]
	s_waitcnt vmcnt(14)
	ds_write_b128 v164, v[188:191] offset:4608
	s_waitcnt lgkmcnt(5)
	v_mfma_f32_16x16x32_bf16 v[18:21], v[224:227], v[232:235], v[18:21]
	v_mfma_f32_16x16x32_bf16 v[22:25], v[224:227], v[236:239], v[22:25]
	v_mfma_f32_16x16x32_bf16 v[2:5], v[224:227], v[240:243], v[2:5]
	v_mfma_f32_16x16x32_bf16 v[6:9], v[224:227], v[252:255], v[6:9]
	ds_read_b128 v[224:227], v244 offset:23104
	s_waitcnt vmcnt(13)
	ds_write_b128 v164, v[192:195] offset:9216
	s_waitcnt vmcnt(12)
	ds_write_b128 v164, v[196:199] offset:13824
	s_waitcnt lgkmcnt(7)
	v_mfma_f32_16x16x32_bf16 v[26:29], v[228:231], v[232:235], v[26:29]
	ds_read_b128 v[232:235], v245 offset:55360
	v_mfma_f32_16x16x32_bf16 v[30:33], v[228:231], v[236:239], v[30:33]
	ds_read_b128 v[236:239], v245 offset:57664
	v_mfma_f32_16x16x32_bf16 v[10:13], v[228:231], v[240:243], v[10:13]
	ds_read_b128 v[240:243], v245 offset:59968
	v_mfma_f32_16x16x32_bf16 v[14:17], v[228:231], v[252:255], v[14:17]
	ds_read_b128 v[252:255], v245 offset:62272
	ds_read_b128 v[228:231], v244 offset:25408
	s_waitcnt lgkmcnt(4)
	v_mfma_f32_16x16x32_bf16 v[50:53], v[216:219], v[232:235], v[50:53]
	s_waitcnt lgkmcnt(3)
	v_mfma_f32_16x16x32_bf16 v[54:57], v[216:219], v[236:239], v[54:57]
	s_waitcnt lgkmcnt(2)
	v_mfma_f32_16x16x32_bf16 v[34:37], v[216:219], v[240:243], v[34:37]
	s_waitcnt lgkmcnt(1)
	v_mfma_f32_16x16x32_bf16 v[38:41], v[216:219], v[252:255], v[38:41]
	s_waitcnt vmcnt(11)
	ds_write_b128 v164, v[200:203] offset:36864
	s_waitcnt vmcnt(10)
	ds_write_b128 v164, v[204:207] offset:41472
	v_mfma_f32_16x16x32_bf16 v[58:61], v[220:223], v[232:235], v[58:61]
	v_mfma_f32_16x16x32_bf16 v[62:65], v[220:223], v[236:239], v[62:65]
	v_mfma_f32_16x16x32_bf16 v[42:45], v[220:223], v[240:243], v[42:45]
	v_mfma_f32_16x16x32_bf16 v[46:49], v[220:223], v[252:255], v[46:49]
	s_waitcnt vmcnt(9)
	ds_write_b128 v164, v[208:211] offset:46080
	s_waitcnt vmcnt(8)
	ds_write_b128 v164, v[212:215] offset:50688
	v_mfma_f32_16x16x32_bf16 v[18:21], v[224:227], v[232:235], v[18:21]
	v_mfma_f32_16x16x32_bf16 v[22:25], v[224:227], v[236:239], v[22:25]
	v_mfma_f32_16x16x32_bf16 v[2:5], v[224:227], v[240:243], v[2:5]
	v_mfma_f32_16x16x32_bf16 v[6:9], v[224:227], v[252:255], v[6:9]
	s_waitcnt lgkmcnt(4)
	v_mfma_f32_16x16x32_bf16 v[26:29], v[228:231], v[232:235], v[26:29]
	v_mfma_f32_16x16x32_bf16 v[30:33], v[228:231], v[236:239], v[30:33]
	v_mfma_f32_16x16x32_bf16 v[10:13], v[228:231], v[240:243], v[10:13]
	v_mfma_f32_16x16x32_bf16 v[14:17], v[228:231], v[252:255], v[14:17]
	s_waitcnt lgkmcnt(0)
	s_barrier
	s_setprio 0
	global_load_dwordx4 v[180:183], v[70:71], off offset:1280
	global_load_dwordx4 v[188:191], v[68:69], off offset:1280
	global_load_dwordx4 v[192:195], v[66:67], off offset:1280
	global_load_dwordx4 v[196:199], v[72:73], off offset:1280
	global_load_dwordx4 v[200:203], v[74:75], off offset:1280
	global_load_dwordx4 v[204:207], v[76:77], off offset:1280
	global_load_dwordx4 v[208:211], v[78:79], off offset:1280
	global_load_dwordx4 v[212:215], v[80:81], off offset:1280
	ds_read_b128 v[232:235], v245 offset:36864
	ds_read_b128 v[216:219], v244
	ds_read_b128 v[236:239], v245 offset:39168
	ds_read_b128 v[240:243], v245 offset:41472
	ds_read_b128 v[252:255], v245 offset:43776
	ds_read_b128 v[220:223], v244 offset:2304
	ds_read_b128 v[224:227], v244 offset:4608
	ds_read_b128 v[228:231], v244 offset:6912
	s_waitcnt lgkmcnt(6)
	v_mfma_f32_16x16x32_bf16 v[50:53], v[216:219], v[232:235], v[50:53]
	s_waitcnt lgkmcnt(5)
	v_mfma_f32_16x16x32_bf16 v[54:57], v[216:219], v[236:239], v[54:57]
	s_waitcnt lgkmcnt(4)
	v_mfma_f32_16x16x32_bf16 v[34:37], v[216:219], v[240:243], v[34:37]
	s_waitcnt lgkmcnt(3)
	v_mfma_f32_16x16x32_bf16 v[38:41], v[216:219], v[252:255], v[38:41]
	ds_read_b128 v[216:219], v244 offset:64
	s_waitcnt lgkmcnt(3)
	v_mfma_f32_16x16x32_bf16 v[58:61], v[220:223], v[232:235], v[58:61]
	v_mfma_f32_16x16x32_bf16 v[62:65], v[220:223], v[236:239], v[62:65]
	v_mfma_f32_16x16x32_bf16 v[42:45], v[220:223], v[240:243], v[42:45]
	v_mfma_f32_16x16x32_bf16 v[46:49], v[220:223], v[252:255], v[46:49]
	ds_read_b128 v[220:223], v244 offset:2368
	s_setprio 1
	s_waitcnt vmcnt(15)
	ds_write_b128 v164, v[122:125] offset:18432
	s_waitcnt vmcnt(14)
	ds_write_b128 v164, v[126:129] offset:23040
	s_waitcnt lgkmcnt(5)
	v_mfma_f32_16x16x32_bf16 v[18:21], v[224:227], v[232:235], v[18:21]
	v_mfma_f32_16x16x32_bf16 v[22:25], v[224:227], v[236:239], v[22:25]
	v_mfma_f32_16x16x32_bf16 v[2:5], v[224:227], v[240:243], v[2:5]
	v_mfma_f32_16x16x32_bf16 v[6:9], v[224:227], v[252:255], v[6:9]
	ds_read_b128 v[224:227], v244 offset:4672
	s_waitcnt vmcnt(13)
	ds_write_b128 v164, v[136:139] offset:27648
	s_waitcnt vmcnt(12)
	ds_write_b128 v164, v[140:143] offset:32256
	s_waitcnt lgkmcnt(7)
	v_mfma_f32_16x16x32_bf16 v[26:29], v[228:231], v[232:235], v[26:29]
	ds_read_b128 v[232:235], v245 offset:36928
	v_mfma_f32_16x16x32_bf16 v[30:33], v[228:231], v[236:239], v[30:33]
	ds_read_b128 v[236:239], v245 offset:39232
	v_mfma_f32_16x16x32_bf16 v[10:13], v[228:231], v[240:243], v[10:13]
	ds_read_b128 v[240:243], v245 offset:41536
	v_mfma_f32_16x16x32_bf16 v[14:17], v[228:231], v[252:255], v[14:17]
	ds_read_b128 v[252:255], v245 offset:43840
	ds_read_b128 v[228:231], v244 offset:6976
	s_waitcnt lgkmcnt(4)
	v_mfma_f32_16x16x32_bf16 v[50:53], v[216:219], v[232:235], v[50:53]
	s_waitcnt lgkmcnt(3)
	v_mfma_f32_16x16x32_bf16 v[54:57], v[216:219], v[236:239], v[54:57]
	s_waitcnt lgkmcnt(2)
	v_mfma_f32_16x16x32_bf16 v[34:37], v[216:219], v[240:243], v[34:37]
	s_waitcnt lgkmcnt(1)
	v_mfma_f32_16x16x32_bf16 v[38:41], v[216:219], v[252:255], v[38:41]
	s_waitcnt vmcnt(11)
	ds_write_b128 v164, v[144:147] offset:55296
	s_waitcnt vmcnt(10)
	ds_write_b128 v164, v[148:151] offset:59904
	v_mfma_f32_16x16x32_bf16 v[58:61], v[220:223], v[232:235], v[58:61]
	v_mfma_f32_16x16x32_bf16 v[62:65], v[220:223], v[236:239], v[62:65]
	v_mfma_f32_16x16x32_bf16 v[42:45], v[220:223], v[240:243], v[42:45]
	v_mfma_f32_16x16x32_bf16 v[46:49], v[220:223], v[252:255], v[46:49]
	s_waitcnt vmcnt(9)
	ds_write_b128 v164, v[172:175] offset:64512
	s_waitcnt vmcnt(8)
	ds_write_b128 v165, v[176:179] offset:32256
	v_mfma_f32_16x16x32_bf16 v[18:21], v[224:227], v[232:235], v[18:21]
	v_mfma_f32_16x16x32_bf16 v[22:25], v[224:227], v[236:239], v[22:25]
	v_mfma_f32_16x16x32_bf16 v[2:5], v[224:227], v[240:243], v[2:5]
	v_mfma_f32_16x16x32_bf16 v[6:9], v[224:227], v[252:255], v[6:9]
	s_waitcnt lgkmcnt(4)
	v_mfma_f32_16x16x32_bf16 v[26:29], v[228:231], v[232:235], v[26:29]
	v_mfma_f32_16x16x32_bf16 v[30:33], v[228:231], v[236:239], v[30:33]
	v_mfma_f32_16x16x32_bf16 v[10:13], v[228:231], v[240:243], v[10:13]
	v_mfma_f32_16x16x32_bf16 v[14:17], v[228:231], v[252:255], v[14:17]
	s_waitcnt lgkmcnt(0)
	s_barrier
	s_setprio 0
	global_load_dwordx4 v[122:125], v[70:71], off offset:1408
	global_load_dwordx4 v[126:129], v[68:69], off offset:1408
	global_load_dwordx4 v[136:139], v[66:67], off offset:1408
	global_load_dwordx4 v[140:143], v[72:73], off offset:1408
	global_load_dwordx4 v[144:147], v[74:75], off offset:1408
	global_load_dwordx4 v[148:151], v[76:77], off offset:1408
	global_load_dwordx4 v[172:175], v[78:79], off offset:1408
	global_load_dwordx4 v[176:179], v[80:81], off offset:1408
	ds_read_b128 v[232:235], v245 offset:55296
	ds_read_b128 v[216:219], v244 offset:18432
	ds_read_b128 v[236:239], v245 offset:57600
	ds_read_b128 v[240:243], v245 offset:59904
	ds_read_b128 v[252:255], v245 offset:62208
	ds_read_b128 v[220:223], v244 offset:20736
	ds_read_b128 v[224:227], v244 offset:23040
	ds_read_b128 v[228:231], v244 offset:25344
	s_waitcnt lgkmcnt(6)
	v_mfma_f32_16x16x32_bf16 v[50:53], v[216:219], v[232:235], v[50:53]
	s_waitcnt lgkmcnt(5)
	v_mfma_f32_16x16x32_bf16 v[54:57], v[216:219], v[236:239], v[54:57]
	s_waitcnt lgkmcnt(4)
	v_mfma_f32_16x16x32_bf16 v[34:37], v[216:219], v[240:243], v[34:37]
	s_waitcnt lgkmcnt(3)
	v_mfma_f32_16x16x32_bf16 v[38:41], v[216:219], v[252:255], v[38:41]
	ds_read_b128 v[216:219], v244 offset:18496
	s_waitcnt lgkmcnt(3)
	v_mfma_f32_16x16x32_bf16 v[58:61], v[220:223], v[232:235], v[58:61]
	v_mfma_f32_16x16x32_bf16 v[62:65], v[220:223], v[236:239], v[62:65]
	v_mfma_f32_16x16x32_bf16 v[42:45], v[220:223], v[240:243], v[42:45]
	v_mfma_f32_16x16x32_bf16 v[46:49], v[220:223], v[252:255], v[46:49]
	ds_read_b128 v[220:223], v244 offset:20800
	s_setprio 1
	s_waitcnt vmcnt(15)
	ds_write_b128 v164, v[180:183]
	s_waitcnt vmcnt(14)
	ds_write_b128 v164, v[188:191] offset:4608
	s_waitcnt lgkmcnt(5)
	v_mfma_f32_16x16x32_bf16 v[18:21], v[224:227], v[232:235], v[18:21]
	v_mfma_f32_16x16x32_bf16 v[22:25], v[224:227], v[236:239], v[22:25]
	v_mfma_f32_16x16x32_bf16 v[2:5], v[224:227], v[240:243], v[2:5]
	v_mfma_f32_16x16x32_bf16 v[6:9], v[224:227], v[252:255], v[6:9]
	ds_read_b128 v[224:227], v244 offset:23104
	s_waitcnt vmcnt(13)
	ds_write_b128 v164, v[192:195] offset:9216
	s_waitcnt vmcnt(12)
	ds_write_b128 v164, v[196:199] offset:13824
	s_waitcnt lgkmcnt(7)
	v_mfma_f32_16x16x32_bf16 v[26:29], v[228:231], v[232:235], v[26:29]
	ds_read_b128 v[232:235], v245 offset:55360
	v_mfma_f32_16x16x32_bf16 v[30:33], v[228:231], v[236:239], v[30:33]
	ds_read_b128 v[236:239], v245 offset:57664
	v_mfma_f32_16x16x32_bf16 v[10:13], v[228:231], v[240:243], v[10:13]
	ds_read_b128 v[240:243], v245 offset:59968
	v_mfma_f32_16x16x32_bf16 v[14:17], v[228:231], v[252:255], v[14:17]
	ds_read_b128 v[252:255], v245 offset:62272
	ds_read_b128 v[228:231], v244 offset:25408
	s_waitcnt lgkmcnt(4)
	v_mfma_f32_16x16x32_bf16 v[50:53], v[216:219], v[232:235], v[50:53]
	s_waitcnt lgkmcnt(3)
	v_mfma_f32_16x16x32_bf16 v[54:57], v[216:219], v[236:239], v[54:57]
	s_waitcnt lgkmcnt(2)
	v_mfma_f32_16x16x32_bf16 v[34:37], v[216:219], v[240:243], v[34:37]
	s_waitcnt lgkmcnt(1)
	v_mfma_f32_16x16x32_bf16 v[38:41], v[216:219], v[252:255], v[38:41]
	s_waitcnt vmcnt(11)
	ds_write_b128 v164, v[200:203] offset:36864
	s_waitcnt vmcnt(10)
	ds_write_b128 v164, v[204:207] offset:41472
	v_mfma_f32_16x16x32_bf16 v[58:61], v[220:223], v[232:235], v[58:61]
	v_mfma_f32_16x16x32_bf16 v[62:65], v[220:223], v[236:239], v[62:65]
	v_mfma_f32_16x16x32_bf16 v[42:45], v[220:223], v[240:243], v[42:45]
	v_mfma_f32_16x16x32_bf16 v[46:49], v[220:223], v[252:255], v[46:49]
	s_waitcnt vmcnt(9)
	ds_write_b128 v164, v[208:211] offset:46080
	s_waitcnt vmcnt(8)
	ds_write_b128 v164, v[212:215] offset:50688
	v_mfma_f32_16x16x32_bf16 v[18:21], v[224:227], v[232:235], v[18:21]
	v_mfma_f32_16x16x32_bf16 v[22:25], v[224:227], v[236:239], v[22:25]
	v_mfma_f32_16x16x32_bf16 v[2:5], v[224:227], v[240:243], v[2:5]
	v_mfma_f32_16x16x32_bf16 v[6:9], v[224:227], v[252:255], v[6:9]
	s_waitcnt lgkmcnt(4)
	v_mfma_f32_16x16x32_bf16 v[26:29], v[228:231], v[232:235], v[26:29]
	v_mfma_f32_16x16x32_bf16 v[30:33], v[228:231], v[236:239], v[30:33]
	v_mfma_f32_16x16x32_bf16 v[10:13], v[228:231], v[240:243], v[10:13]
	v_mfma_f32_16x16x32_bf16 v[14:17], v[228:231], v[252:255], v[14:17]
	s_waitcnt lgkmcnt(0)
	s_barrier
	s_setprio 0
	global_load_dwordx4 v[180:183], v[70:71], off offset:1536
	global_load_dwordx4 v[188:191], v[68:69], off offset:1536
	global_load_dwordx4 v[192:195], v[66:67], off offset:1536
	global_load_dwordx4 v[196:199], v[72:73], off offset:1536
	global_load_dwordx4 v[200:203], v[74:75], off offset:1536
	global_load_dwordx4 v[204:207], v[76:77], off offset:1536
	global_load_dwordx4 v[208:211], v[78:79], off offset:1536
	global_load_dwordx4 v[212:215], v[80:81], off offset:1536
	ds_read_b128 v[232:235], v245 offset:36864
	ds_read_b128 v[216:219], v244
	ds_read_b128 v[236:239], v245 offset:39168
	ds_read_b128 v[240:243], v245 offset:41472
	ds_read_b128 v[252:255], v245 offset:43776
	ds_read_b128 v[220:223], v244 offset:2304
	ds_read_b128 v[224:227], v244 offset:4608
	ds_read_b128 v[228:231], v244 offset:6912
	s_waitcnt lgkmcnt(6)
	v_mfma_f32_16x16x32_bf16 v[50:53], v[216:219], v[232:235], v[50:53]
	s_waitcnt lgkmcnt(5)
	v_mfma_f32_16x16x32_bf16 v[54:57], v[216:219], v[236:239], v[54:57]
	s_waitcnt lgkmcnt(4)
	v_mfma_f32_16x16x32_bf16 v[34:37], v[216:219], v[240:243], v[34:37]
	s_waitcnt lgkmcnt(3)
	v_mfma_f32_16x16x32_bf16 v[38:41], v[216:219], v[252:255], v[38:41]
	ds_read_b128 v[216:219], v244 offset:64
	s_waitcnt lgkmcnt(3)
	v_mfma_f32_16x16x32_bf16 v[58:61], v[220:223], v[232:235], v[58:61]
	v_mfma_f32_16x16x32_bf16 v[62:65], v[220:223], v[236:239], v[62:65]
	v_mfma_f32_16x16x32_bf16 v[42:45], v[220:223], v[240:243], v[42:45]
	v_mfma_f32_16x16x32_bf16 v[46:49], v[220:223], v[252:255], v[46:49]
	ds_read_b128 v[220:223], v244 offset:2368
	s_setprio 1
	s_waitcnt vmcnt(15)
	ds_write_b128 v164, v[122:125] offset:18432
	s_waitcnt vmcnt(14)
	ds_write_b128 v164, v[126:129] offset:23040
	s_waitcnt lgkmcnt(5)
	v_mfma_f32_16x16x32_bf16 v[18:21], v[224:227], v[232:235], v[18:21]
	v_mfma_f32_16x16x32_bf16 v[22:25], v[224:227], v[236:239], v[22:25]
	v_mfma_f32_16x16x32_bf16 v[2:5], v[224:227], v[240:243], v[2:5]
	v_mfma_f32_16x16x32_bf16 v[6:9], v[224:227], v[252:255], v[6:9]
	ds_read_b128 v[224:227], v244 offset:4672
	s_waitcnt vmcnt(13)
	ds_write_b128 v164, v[136:139] offset:27648
	s_waitcnt vmcnt(12)
	ds_write_b128 v164, v[140:143] offset:32256
	s_waitcnt lgkmcnt(7)
	v_mfma_f32_16x16x32_bf16 v[26:29], v[228:231], v[232:235], v[26:29]
	ds_read_b128 v[232:235], v245 offset:36928
	v_mfma_f32_16x16x32_bf16 v[30:33], v[228:231], v[236:239], v[30:33]
	ds_read_b128 v[236:239], v245 offset:39232
	v_mfma_f32_16x16x32_bf16 v[10:13], v[228:231], v[240:243], v[10:13]
	ds_read_b128 v[240:243], v245 offset:41536
	v_mfma_f32_16x16x32_bf16 v[14:17], v[228:231], v[252:255], v[14:17]
	ds_read_b128 v[252:255], v245 offset:43840
	ds_read_b128 v[228:231], v244 offset:6976
	s_waitcnt lgkmcnt(4)
	v_mfma_f32_16x16x32_bf16 v[50:53], v[216:219], v[232:235], v[50:53]
	s_waitcnt lgkmcnt(3)
	v_mfma_f32_16x16x32_bf16 v[54:57], v[216:219], v[236:239], v[54:57]
	s_waitcnt lgkmcnt(2)
	v_mfma_f32_16x16x32_bf16 v[34:37], v[216:219], v[240:243], v[34:37]
	s_waitcnt lgkmcnt(1)
	v_mfma_f32_16x16x32_bf16 v[38:41], v[216:219], v[252:255], v[38:41]
	s_waitcnt vmcnt(11)
	ds_write_b128 v164, v[144:147] offset:55296
	s_waitcnt vmcnt(10)
	ds_write_b128 v164, v[148:151] offset:59904
	v_mfma_f32_16x16x32_bf16 v[58:61], v[220:223], v[232:235], v[58:61]
	v_mfma_f32_16x16x32_bf16 v[62:65], v[220:223], v[236:239], v[62:65]
	v_mfma_f32_16x16x32_bf16 v[42:45], v[220:223], v[240:243], v[42:45]
	v_mfma_f32_16x16x32_bf16 v[46:49], v[220:223], v[252:255], v[46:49]
	s_waitcnt vmcnt(9)
	ds_write_b128 v164, v[172:175] offset:64512
	s_waitcnt vmcnt(8)
	ds_write_b128 v165, v[176:179] offset:32256
	v_mfma_f32_16x16x32_bf16 v[18:21], v[224:227], v[232:235], v[18:21]
	v_mfma_f32_16x16x32_bf16 v[22:25], v[224:227], v[236:239], v[22:25]
	v_mfma_f32_16x16x32_bf16 v[2:5], v[224:227], v[240:243], v[2:5]
	v_mfma_f32_16x16x32_bf16 v[6:9], v[224:227], v[252:255], v[6:9]
	s_waitcnt lgkmcnt(4)
	v_mfma_f32_16x16x32_bf16 v[26:29], v[228:231], v[232:235], v[26:29]
	v_mfma_f32_16x16x32_bf16 v[30:33], v[228:231], v[236:239], v[30:33]
	v_mfma_f32_16x16x32_bf16 v[10:13], v[228:231], v[240:243], v[10:13]
	v_mfma_f32_16x16x32_bf16 v[14:17], v[228:231], v[252:255], v[14:17]
	s_waitcnt lgkmcnt(0)
	s_barrier
	s_setprio 0
	global_load_dwordx4 v[122:125], v[70:71], off offset:1664
	global_load_dwordx4 v[126:129], v[68:69], off offset:1664
	global_load_dwordx4 v[136:139], v[66:67], off offset:1664
	global_load_dwordx4 v[140:143], v[72:73], off offset:1664
	global_load_dwordx4 v[144:147], v[74:75], off offset:1664
	global_load_dwordx4 v[148:151], v[76:77], off offset:1664
	global_load_dwordx4 v[172:175], v[78:79], off offset:1664
	global_load_dwordx4 v[176:179], v[80:81], off offset:1664
	ds_read_b128 v[232:235], v245 offset:55296
	ds_read_b128 v[216:219], v244 offset:18432
	ds_read_b128 v[236:239], v245 offset:57600
	ds_read_b128 v[240:243], v245 offset:59904
	ds_read_b128 v[252:255], v245 offset:62208
	ds_read_b128 v[220:223], v244 offset:20736
	ds_read_b128 v[224:227], v244 offset:23040
	ds_read_b128 v[228:231], v244 offset:25344
	s_waitcnt lgkmcnt(6)
	v_mfma_f32_16x16x32_bf16 v[50:53], v[216:219], v[232:235], v[50:53]
	s_waitcnt lgkmcnt(5)
	v_mfma_f32_16x16x32_bf16 v[54:57], v[216:219], v[236:239], v[54:57]
	s_waitcnt lgkmcnt(4)
	v_mfma_f32_16x16x32_bf16 v[34:37], v[216:219], v[240:243], v[34:37]
	s_waitcnt lgkmcnt(3)
	v_mfma_f32_16x16x32_bf16 v[38:41], v[216:219], v[252:255], v[38:41]
	ds_read_b128 v[216:219], v244 offset:18496
	s_waitcnt lgkmcnt(3)
	v_mfma_f32_16x16x32_bf16 v[58:61], v[220:223], v[232:235], v[58:61]
	v_mfma_f32_16x16x32_bf16 v[62:65], v[220:223], v[236:239], v[62:65]
	v_mfma_f32_16x16x32_bf16 v[42:45], v[220:223], v[240:243], v[42:45]
	v_mfma_f32_16x16x32_bf16 v[46:49], v[220:223], v[252:255], v[46:49]
	ds_read_b128 v[220:223], v244 offset:20800
	s_setprio 1
	s_waitcnt vmcnt(15)
	ds_write_b128 v164, v[180:183]
	s_waitcnt vmcnt(14)
	ds_write_b128 v164, v[188:191] offset:4608
	s_waitcnt lgkmcnt(5)
	v_mfma_f32_16x16x32_bf16 v[18:21], v[224:227], v[232:235], v[18:21]
	v_mfma_f32_16x16x32_bf16 v[22:25], v[224:227], v[236:239], v[22:25]
	v_mfma_f32_16x16x32_bf16 v[2:5], v[224:227], v[240:243], v[2:5]
	v_mfma_f32_16x16x32_bf16 v[6:9], v[224:227], v[252:255], v[6:9]
	ds_read_b128 v[224:227], v244 offset:23104
	s_waitcnt vmcnt(13)
	ds_write_b128 v164, v[192:195] offset:9216
	s_waitcnt vmcnt(12)
	ds_write_b128 v164, v[196:199] offset:13824
	s_waitcnt lgkmcnt(7)
	v_mfma_f32_16x16x32_bf16 v[26:29], v[228:231], v[232:235], v[26:29]
	ds_read_b128 v[232:235], v245 offset:55360
	v_mfma_f32_16x16x32_bf16 v[30:33], v[228:231], v[236:239], v[30:33]
	ds_read_b128 v[236:239], v245 offset:57664
	v_mfma_f32_16x16x32_bf16 v[10:13], v[228:231], v[240:243], v[10:13]
	ds_read_b128 v[240:243], v245 offset:59968
	v_mfma_f32_16x16x32_bf16 v[14:17], v[228:231], v[252:255], v[14:17]
	ds_read_b128 v[252:255], v245 offset:62272
	ds_read_b128 v[228:231], v244 offset:25408
	s_waitcnt lgkmcnt(4)
	v_mfma_f32_16x16x32_bf16 v[50:53], v[216:219], v[232:235], v[50:53]
	s_waitcnt lgkmcnt(3)
	v_mfma_f32_16x16x32_bf16 v[54:57], v[216:219], v[236:239], v[54:57]
	s_waitcnt lgkmcnt(2)
	v_mfma_f32_16x16x32_bf16 v[34:37], v[216:219], v[240:243], v[34:37]
	s_waitcnt lgkmcnt(1)
	v_mfma_f32_16x16x32_bf16 v[38:41], v[216:219], v[252:255], v[38:41]
	s_waitcnt vmcnt(11)
	ds_write_b128 v164, v[200:203] offset:36864
	s_waitcnt vmcnt(10)
	ds_write_b128 v164, v[204:207] offset:41472
	v_mfma_f32_16x16x32_bf16 v[58:61], v[220:223], v[232:235], v[58:61]
	v_mfma_f32_16x16x32_bf16 v[62:65], v[220:223], v[236:239], v[62:65]
	v_mfma_f32_16x16x32_bf16 v[42:45], v[220:223], v[240:243], v[42:45]
	v_mfma_f32_16x16x32_bf16 v[46:49], v[220:223], v[252:255], v[46:49]
	s_waitcnt vmcnt(9)
	ds_write_b128 v164, v[208:211] offset:46080
	s_waitcnt vmcnt(8)
	ds_write_b128 v164, v[212:215] offset:50688
	v_mfma_f32_16x16x32_bf16 v[18:21], v[224:227], v[232:235], v[18:21]
	v_mfma_f32_16x16x32_bf16 v[22:25], v[224:227], v[236:239], v[22:25]
	v_mfma_f32_16x16x32_bf16 v[2:5], v[224:227], v[240:243], v[2:5]
	v_mfma_f32_16x16x32_bf16 v[6:9], v[224:227], v[252:255], v[6:9]
	s_waitcnt lgkmcnt(4)
	v_mfma_f32_16x16x32_bf16 v[26:29], v[228:231], v[232:235], v[26:29]
	v_mfma_f32_16x16x32_bf16 v[30:33], v[228:231], v[236:239], v[30:33]
	v_mfma_f32_16x16x32_bf16 v[10:13], v[228:231], v[240:243], v[10:13]
	v_mfma_f32_16x16x32_bf16 v[14:17], v[228:231], v[252:255], v[14:17]
	s_waitcnt lgkmcnt(0)
	s_barrier
	s_setprio 0
	global_load_dwordx4 v[180:183], v[70:71], off offset:1792
	global_load_dwordx4 v[188:191], v[68:69], off offset:1792
	global_load_dwordx4 v[192:195], v[66:67], off offset:1792
	global_load_dwordx4 v[196:199], v[72:73], off offset:1792
	global_load_dwordx4 v[200:203], v[74:75], off offset:1792
	global_load_dwordx4 v[204:207], v[76:77], off offset:1792
	global_load_dwordx4 v[208:211], v[78:79], off offset:1792
	global_load_dwordx4 v[212:215], v[80:81], off offset:1792
	ds_read_b128 v[232:235], v245 offset:36864
	ds_read_b128 v[216:219], v244
	ds_read_b128 v[236:239], v245 offset:39168
	ds_read_b128 v[240:243], v245 offset:41472
	ds_read_b128 v[252:255], v245 offset:43776
	ds_read_b128 v[220:223], v244 offset:2304
	ds_read_b128 v[224:227], v244 offset:4608
	ds_read_b128 v[228:231], v244 offset:6912
	s_waitcnt lgkmcnt(6)
	v_mfma_f32_16x16x32_bf16 v[50:53], v[216:219], v[232:235], v[50:53]
	s_waitcnt lgkmcnt(5)
	v_mfma_f32_16x16x32_bf16 v[54:57], v[216:219], v[236:239], v[54:57]
	s_waitcnt lgkmcnt(4)
	v_mfma_f32_16x16x32_bf16 v[34:37], v[216:219], v[240:243], v[34:37]
	s_waitcnt lgkmcnt(3)
	v_mfma_f32_16x16x32_bf16 v[38:41], v[216:219], v[252:255], v[38:41]
	ds_read_b128 v[216:219], v244 offset:64
	s_waitcnt lgkmcnt(3)
	v_mfma_f32_16x16x32_bf16 v[58:61], v[220:223], v[232:235], v[58:61]
	v_mfma_f32_16x16x32_bf16 v[62:65], v[220:223], v[236:239], v[62:65]
	v_mfma_f32_16x16x32_bf16 v[42:45], v[220:223], v[240:243], v[42:45]
	v_mfma_f32_16x16x32_bf16 v[46:49], v[220:223], v[252:255], v[46:49]
	ds_read_b128 v[220:223], v244 offset:2368
	s_setprio 1
	s_waitcnt vmcnt(15)
	ds_write_b128 v164, v[122:125] offset:18432
	s_waitcnt vmcnt(14)
	ds_write_b128 v164, v[126:129] offset:23040
	s_waitcnt lgkmcnt(5)
	v_mfma_f32_16x16x32_bf16 v[18:21], v[224:227], v[232:235], v[18:21]
	v_mfma_f32_16x16x32_bf16 v[22:25], v[224:227], v[236:239], v[22:25]
	v_mfma_f32_16x16x32_bf16 v[2:5], v[224:227], v[240:243], v[2:5]
	v_mfma_f32_16x16x32_bf16 v[6:9], v[224:227], v[252:255], v[6:9]
	ds_read_b128 v[224:227], v244 offset:4672
	s_waitcnt vmcnt(13)
	ds_write_b128 v164, v[136:139] offset:27648
	s_waitcnt vmcnt(12)
	ds_write_b128 v164, v[140:143] offset:32256
	s_waitcnt lgkmcnt(7)
	v_mfma_f32_16x16x32_bf16 v[26:29], v[228:231], v[232:235], v[26:29]
	ds_read_b128 v[232:235], v245 offset:36928
	v_mfma_f32_16x16x32_bf16 v[30:33], v[228:231], v[236:239], v[30:33]
	ds_read_b128 v[236:239], v245 offset:39232
	v_mfma_f32_16x16x32_bf16 v[10:13], v[228:231], v[240:243], v[10:13]
	ds_read_b128 v[240:243], v245 offset:41536
	v_mfma_f32_16x16x32_bf16 v[14:17], v[228:231], v[252:255], v[14:17]
	ds_read_b128 v[252:255], v245 offset:43840
	ds_read_b128 v[228:231], v244 offset:6976
	s_waitcnt lgkmcnt(4)
	v_mfma_f32_16x16x32_bf16 v[50:53], v[216:219], v[232:235], v[50:53]
	s_waitcnt lgkmcnt(3)
	v_mfma_f32_16x16x32_bf16 v[54:57], v[216:219], v[236:239], v[54:57]
	s_waitcnt lgkmcnt(2)
	v_mfma_f32_16x16x32_bf16 v[34:37], v[216:219], v[240:243], v[34:37]
	s_waitcnt lgkmcnt(1)
	v_mfma_f32_16x16x32_bf16 v[38:41], v[216:219], v[252:255], v[38:41]
	s_waitcnt vmcnt(11)
	ds_write_b128 v164, v[144:147] offset:55296
	s_waitcnt vmcnt(10)
	ds_write_b128 v164, v[148:151] offset:59904
	v_mfma_f32_16x16x32_bf16 v[58:61], v[220:223], v[232:235], v[58:61]
	v_mfma_f32_16x16x32_bf16 v[62:65], v[220:223], v[236:239], v[62:65]
	v_mfma_f32_16x16x32_bf16 v[42:45], v[220:223], v[240:243], v[42:45]
	v_mfma_f32_16x16x32_bf16 v[46:49], v[220:223], v[252:255], v[46:49]
	s_waitcnt vmcnt(9)
	ds_write_b128 v164, v[172:175] offset:64512
	s_waitcnt vmcnt(8)
	ds_write_b128 v165, v[176:179] offset:32256
	v_mfma_f32_16x16x32_bf16 v[18:21], v[224:227], v[232:235], v[18:21]
	v_mfma_f32_16x16x32_bf16 v[22:25], v[224:227], v[236:239], v[22:25]
	v_mfma_f32_16x16x32_bf16 v[2:5], v[224:227], v[240:243], v[2:5]
	v_mfma_f32_16x16x32_bf16 v[6:9], v[224:227], v[252:255], v[6:9]
	s_waitcnt lgkmcnt(4)
	v_mfma_f32_16x16x32_bf16 v[26:29], v[228:231], v[232:235], v[26:29]
	v_mfma_f32_16x16x32_bf16 v[30:33], v[228:231], v[236:239], v[30:33]
	v_mfma_f32_16x16x32_bf16 v[10:13], v[228:231], v[240:243], v[10:13]
	v_mfma_f32_16x16x32_bf16 v[14:17], v[228:231], v[252:255], v[14:17]
	s_waitcnt lgkmcnt(0)
	s_barrier
	s_setprio 0
	global_load_dwordx4 v[122:125], v[70:71], off offset:1920
	s_nop 0
	global_load_dwordx4 v[68:71], v[68:69], off offset:1920
	s_nop 0
	global_load_dwordx4 v[126:129], v[66:67], off offset:1920
	global_load_dwordx4 v[136:139], v[72:73], off offset:1920
	s_nop 0
	global_load_dwordx4 v[72:75], v[74:75], off offset:1920
	s_nop 0
	global_load_dwordx4 v[140:143], v[76:77], off offset:1920
	s_nop 0
	global_load_dwordx4 v[76:79], v[78:79], off offset:1920
	s_nop 0
	global_load_dwordx4 v[144:147], v[80:81], off offset:1920
	ds_read_b128 v[232:235], v245 offset:55296
	ds_read_b128 v[216:219], v244 offset:18432
	ds_read_b128 v[236:239], v245 offset:57600
	ds_read_b128 v[240:243], v245 offset:59904
	ds_read_b128 v[252:255], v245 offset:62208
	ds_read_b128 v[220:223], v244 offset:20736
	ds_read_b128 v[224:227], v244 offset:23040
	ds_read_b128 v[228:231], v244 offset:25344
	s_waitcnt lgkmcnt(6)
	v_mfma_f32_16x16x32_bf16 v[50:53], v[216:219], v[232:235], v[50:53]
	s_waitcnt lgkmcnt(5)
	v_mfma_f32_16x16x32_bf16 v[54:57], v[216:219], v[236:239], v[54:57]
	s_waitcnt lgkmcnt(4)
	v_mfma_f32_16x16x32_bf16 v[34:37], v[216:219], v[240:243], v[34:37]
	s_waitcnt lgkmcnt(3)
	v_mfma_f32_16x16x32_bf16 v[38:41], v[216:219], v[252:255], v[38:41]
	ds_read_b128 v[216:219], v244 offset:18496
	s_waitcnt lgkmcnt(3)
	v_mfma_f32_16x16x32_bf16 v[58:61], v[220:223], v[232:235], v[58:61]
	v_mfma_f32_16x16x32_bf16 v[62:65], v[220:223], v[236:239], v[62:65]
	v_mfma_f32_16x16x32_bf16 v[42:45], v[220:223], v[240:243], v[42:45]
	v_mfma_f32_16x16x32_bf16 v[46:49], v[220:223], v[252:255], v[46:49]
	ds_read_b128 v[220:223], v244 offset:20800
	s_setprio 1
	s_waitcnt vmcnt(15)
	ds_write_b128 v164, v[180:183]
	s_waitcnt vmcnt(14)
	ds_write_b128 v164, v[188:191] offset:4608
	s_waitcnt lgkmcnt(5)
	v_mfma_f32_16x16x32_bf16 v[18:21], v[224:227], v[232:235], v[18:21]
	v_mfma_f32_16x16x32_bf16 v[22:25], v[224:227], v[236:239], v[22:25]
	v_mfma_f32_16x16x32_bf16 v[2:5], v[224:227], v[240:243], v[2:5]
	v_mfma_f32_16x16x32_bf16 v[6:9], v[224:227], v[252:255], v[6:9]
	ds_read_b128 v[224:227], v244 offset:23104
	s_waitcnt vmcnt(13)
	ds_write_b128 v164, v[192:195] offset:9216
	s_waitcnt vmcnt(12)
	ds_write_b128 v164, v[196:199] offset:13824
	s_waitcnt lgkmcnt(7)
	v_mfma_f32_16x16x32_bf16 v[26:29], v[228:231], v[232:235], v[26:29]
	ds_read_b128 v[232:235], v245 offset:55360
	v_mfma_f32_16x16x32_bf16 v[30:33], v[228:231], v[236:239], v[30:33]
	ds_read_b128 v[236:239], v245 offset:57664
	v_mfma_f32_16x16x32_bf16 v[10:13], v[228:231], v[240:243], v[10:13]
	ds_read_b128 v[240:243], v245 offset:59968
	v_mfma_f32_16x16x32_bf16 v[14:17], v[228:231], v[252:255], v[14:17]
	ds_read_b128 v[252:255], v245 offset:62272
	ds_read_b128 v[228:231], v244 offset:25408
	s_waitcnt lgkmcnt(4)
	v_mfma_f32_16x16x32_bf16 v[50:53], v[216:219], v[232:235], v[50:53]
	s_waitcnt lgkmcnt(3)
	v_mfma_f32_16x16x32_bf16 v[54:57], v[216:219], v[236:239], v[54:57]
	s_waitcnt lgkmcnt(2)
	v_mfma_f32_16x16x32_bf16 v[34:37], v[216:219], v[240:243], v[34:37]
	s_waitcnt lgkmcnt(1)
	v_mfma_f32_16x16x32_bf16 v[38:41], v[216:219], v[252:255], v[38:41]
	s_waitcnt vmcnt(11)
	ds_write_b128 v164, v[200:203] offset:36864
	s_waitcnt vmcnt(10)
	ds_write_b128 v164, v[204:207] offset:41472
	v_mfma_f32_16x16x32_bf16 v[58:61], v[220:223], v[232:235], v[58:61]
	v_mfma_f32_16x16x32_bf16 v[62:65], v[220:223], v[236:239], v[62:65]
	v_mfma_f32_16x16x32_bf16 v[42:45], v[220:223], v[240:243], v[42:45]
	v_mfma_f32_16x16x32_bf16 v[46:49], v[220:223], v[252:255], v[46:49]
	s_waitcnt vmcnt(9)
	ds_write_b128 v164, v[208:211] offset:46080
	s_waitcnt vmcnt(8)
	ds_write_b128 v164, v[212:215] offset:50688
	v_mfma_f32_16x16x32_bf16 v[18:21], v[224:227], v[232:235], v[18:21]
	v_mfma_f32_16x16x32_bf16 v[22:25], v[224:227], v[236:239], v[22:25]
	v_mfma_f32_16x16x32_bf16 v[2:5], v[224:227], v[240:243], v[2:5]
	v_mfma_f32_16x16x32_bf16 v[6:9], v[224:227], v[252:255], v[6:9]
	s_waitcnt lgkmcnt(4)
	v_mfma_f32_16x16x32_bf16 v[26:29], v[228:231], v[232:235], v[26:29]
	v_mfma_f32_16x16x32_bf16 v[30:33], v[228:231], v[236:239], v[30:33]
	v_mfma_f32_16x16x32_bf16 v[10:13], v[228:231], v[240:243], v[10:13]
	v_mfma_f32_16x16x32_bf16 v[14:17], v[228:231], v[252:255], v[14:17]
	s_waitcnt lgkmcnt(0)
	s_barrier
	s_setprio 0
	ds_read_b128 v[232:235], v245 offset:36864
	ds_read_b128 v[216:219], v244
	ds_read_b128 v[236:239], v245 offset:39168
	ds_read_b128 v[240:243], v245 offset:41472
	ds_read_b128 v[252:255], v245 offset:43776
	ds_read_b128 v[220:223], v244 offset:2304
	ds_read_b128 v[224:227], v244 offset:4608
	ds_read_b128 v[228:231], v244 offset:6912
	s_waitcnt lgkmcnt(6)
	v_mfma_f32_16x16x32_bf16 v[50:53], v[216:219], v[232:235], v[50:53]
	s_waitcnt lgkmcnt(5)
	v_mfma_f32_16x16x32_bf16 v[54:57], v[216:219], v[236:239], v[54:57]
	s_waitcnt lgkmcnt(4)
	v_mfma_f32_16x16x32_bf16 v[34:37], v[216:219], v[240:243], v[34:37]
	s_waitcnt lgkmcnt(3)
	v_mfma_f32_16x16x32_bf16 v[38:41], v[216:219], v[252:255], v[38:41]
	ds_read_b128 v[216:219], v244 offset:64
	s_waitcnt lgkmcnt(3)
	v_mfma_f32_16x16x32_bf16 v[58:61], v[220:223], v[232:235], v[58:61]
	v_mfma_f32_16x16x32_bf16 v[62:65], v[220:223], v[236:239], v[62:65]
	v_mfma_f32_16x16x32_bf16 v[42:45], v[220:223], v[240:243], v[42:45]
	v_mfma_f32_16x16x32_bf16 v[46:49], v[220:223], v[252:255], v[46:49]
	ds_read_b128 v[220:223], v244 offset:2368
	s_setprio 1
	s_waitcnt vmcnt(7)
	ds_write_b128 v164, v[122:125] offset:18432
	s_waitcnt vmcnt(6)
	ds_write_b128 v164, v[68:71] offset:23040
	s_waitcnt lgkmcnt(5)
	v_mfma_f32_16x16x32_bf16 v[18:21], v[224:227], v[232:235], v[18:21]
	v_mfma_f32_16x16x32_bf16 v[22:25], v[224:227], v[236:239], v[22:25]
	v_mfma_f32_16x16x32_bf16 v[2:5], v[224:227], v[240:243], v[2:5]
	v_mfma_f32_16x16x32_bf16 v[6:9], v[224:227], v[252:255], v[6:9]
	ds_read_b128 v[224:227], v244 offset:4672
	s_waitcnt vmcnt(5)
	ds_write_b128 v164, v[126:129] offset:27648
	s_waitcnt vmcnt(4)
	ds_write_b128 v164, v[136:139] offset:32256
	s_waitcnt lgkmcnt(7)
	v_mfma_f32_16x16x32_bf16 v[26:29], v[228:231], v[232:235], v[26:29]
	ds_read_b128 v[232:235], v245 offset:36928
	v_mfma_f32_16x16x32_bf16 v[30:33], v[228:231], v[236:239], v[30:33]
	ds_read_b128 v[236:239], v245 offset:39232
	v_mfma_f32_16x16x32_bf16 v[10:13], v[228:231], v[240:243], v[10:13]
	ds_read_b128 v[240:243], v245 offset:41536
	v_mfma_f32_16x16x32_bf16 v[14:17], v[228:231], v[252:255], v[14:17]
	ds_read_b128 v[252:255], v245 offset:43840
	ds_read_b128 v[228:231], v244 offset:6976
	s_waitcnt lgkmcnt(4)
	v_mfma_f32_16x16x32_bf16 v[50:53], v[216:219], v[232:235], v[50:53]
	s_waitcnt lgkmcnt(3)
	v_mfma_f32_16x16x32_bf16 v[54:57], v[216:219], v[236:239], v[54:57]
	s_waitcnt lgkmcnt(2)
	v_mfma_f32_16x16x32_bf16 v[34:37], v[216:219], v[240:243], v[34:37]
	s_waitcnt lgkmcnt(1)
	v_mfma_f32_16x16x32_bf16 v[38:41], v[216:219], v[252:255], v[38:41]
	s_waitcnt vmcnt(3)
	ds_write_b128 v164, v[72:75] offset:55296
	s_waitcnt vmcnt(2)
	ds_write_b128 v164, v[140:143] offset:59904
	v_mfma_f32_16x16x32_bf16 v[58:61], v[220:223], v[232:235], v[58:61]
	v_mfma_f32_16x16x32_bf16 v[62:65], v[220:223], v[236:239], v[62:65]
	v_mfma_f32_16x16x32_bf16 v[42:45], v[220:223], v[240:243], v[42:45]
	v_mfma_f32_16x16x32_bf16 v[46:49], v[220:223], v[252:255], v[46:49]
	s_waitcnt vmcnt(1)
	ds_write_b128 v164, v[76:79] offset:64512
	s_waitcnt vmcnt(0)
	ds_write_b128 v165, v[144:147] offset:32256
	v_mfma_f32_16x16x32_bf16 v[18:21], v[224:227], v[232:235], v[18:21]
	v_mfma_f32_16x16x32_bf16 v[22:25], v[224:227], v[236:239], v[22:25]
	v_mfma_f32_16x16x32_bf16 v[2:5], v[224:227], v[240:243], v[2:5]
	v_mfma_f32_16x16x32_bf16 v[6:9], v[224:227], v[252:255], v[6:9]
	s_waitcnt lgkmcnt(4)
	v_mfma_f32_16x16x32_bf16 v[26:29], v[228:231], v[232:235], v[26:29]
	v_mfma_f32_16x16x32_bf16 v[30:33], v[228:231], v[236:239], v[30:33]
	v_mfma_f32_16x16x32_bf16 v[10:13], v[228:231], v[240:243], v[10:13]
	v_mfma_f32_16x16x32_bf16 v[14:17], v[228:231], v[252:255], v[14:17]
	s_waitcnt lgkmcnt(0)
	s_barrier
	s_setprio 0
	ds_read_b128 v[232:235], v245 offset:55296
	ds_read_b128 v[216:219], v244 offset:18432
	ds_read_b128 v[236:239], v245 offset:57600
	ds_read_b128 v[240:243], v245 offset:59904
	ds_read_b128 v[252:255], v245 offset:62208
	ds_read_b128 v[220:223], v244 offset:20736
	ds_read_b128 v[224:227], v244 offset:23040
	ds_read_b128 v[228:231], v244 offset:25344
	s_waitcnt lgkmcnt(6)
	v_mfma_f32_16x16x32_bf16 v[50:53], v[216:219], v[232:235], v[50:53]
	s_waitcnt lgkmcnt(5)
	v_mfma_f32_16x16x32_bf16 v[54:57], v[216:219], v[236:239], v[54:57]
	s_waitcnt lgkmcnt(4)
	v_mfma_f32_16x16x32_bf16 v[34:37], v[216:219], v[240:243], v[34:37]
	s_waitcnt lgkmcnt(3)
	v_mfma_f32_16x16x32_bf16 v[38:41], v[216:219], v[252:255], v[38:41]
	ds_read_b128 v[216:219], v244 offset:18496
	s_waitcnt lgkmcnt(3)
	v_mfma_f32_16x16x32_bf16 v[58:61], v[220:223], v[232:235], v[58:61]
	v_mfma_f32_16x16x32_bf16 v[62:65], v[220:223], v[236:239], v[62:65]
	v_mfma_f32_16x16x32_bf16 v[42:45], v[220:223], v[240:243], v[42:45]
	v_mfma_f32_16x16x32_bf16 v[46:49], v[220:223], v[252:255], v[46:49]
	ds_read_b128 v[220:223], v244 offset:20800
	s_waitcnt lgkmcnt(3)
	v_mfma_f32_16x16x32_bf16 v[18:21], v[224:227], v[232:235], v[18:21]
	v_mfma_f32_16x16x32_bf16 v[22:25], v[224:227], v[236:239], v[22:25]
	v_mfma_f32_16x16x32_bf16 v[2:5], v[224:227], v[240:243], v[2:5]
	v_mfma_f32_16x16x32_bf16 v[6:9], v[224:227], v[252:255], v[6:9]
	ds_read_b128 v[224:227], v244 offset:23104
	s_waitcnt lgkmcnt(3)
	v_mfma_f32_16x16x32_bf16 v[26:29], v[228:231], v[232:235], v[26:29]
	ds_read_b128 v[232:235], v245 offset:55360
	v_mfma_f32_16x16x32_bf16 v[30:33], v[228:231], v[236:239], v[30:33]
	ds_read_b128 v[236:239], v245 offset:57664
	v_mfma_f32_16x16x32_bf16 v[10:13], v[228:231], v[240:243], v[10:13]
	ds_read_b128 v[240:243], v245 offset:59968
	v_mfma_f32_16x16x32_bf16 v[14:17], v[228:231], v[252:255], v[14:17]
	ds_read_b128 v[252:255], v245 offset:62272
	ds_read_b128 v[228:231], v244 offset:25408
	s_waitcnt lgkmcnt(4)
	v_mfma_f32_16x16x32_bf16 v[50:53], v[216:219], v[232:235], v[50:53]
	s_waitcnt lgkmcnt(3)
	v_mfma_f32_16x16x32_bf16 v[54:57], v[216:219], v[236:239], v[54:57]
	s_waitcnt lgkmcnt(2)
	v_mfma_f32_16x16x32_bf16 v[34:37], v[216:219], v[240:243], v[34:37]
	s_waitcnt lgkmcnt(1)
	v_mfma_f32_16x16x32_bf16 v[38:41], v[216:219], v[252:255], v[38:41]
	v_mfma_f32_16x16x32_bf16 v[58:61], v[220:223], v[232:235], v[58:61]
	v_mfma_f32_16x16x32_bf16 v[62:65], v[220:223], v[236:239], v[62:65]
	v_mfma_f32_16x16x32_bf16 v[42:45], v[220:223], v[240:243], v[42:45]
	v_mfma_f32_16x16x32_bf16 v[46:49], v[220:223], v[252:255], v[46:49]
	v_mfma_f32_16x16x32_bf16 v[18:21], v[224:227], v[232:235], v[18:21]
	v_mfma_f32_16x16x32_bf16 v[22:25], v[224:227], v[236:239], v[22:25]
	v_mfma_f32_16x16x32_bf16 v[2:5], v[224:227], v[240:243], v[2:5]
	v_mfma_f32_16x16x32_bf16 v[6:9], v[224:227], v[252:255], v[6:9]
	s_waitcnt lgkmcnt(0)
	v_mfma_f32_16x16x32_bf16 v[26:29], v[228:231], v[232:235], v[26:29]
	v_mfma_f32_16x16x32_bf16 v[30:33], v[228:231], v[236:239], v[30:33]
	v_mfma_f32_16x16x32_bf16 v[10:13], v[228:231], v[240:243], v[10:13]
	v_mfma_f32_16x16x32_bf16 v[14:17], v[228:231], v[252:255], v[14:17]
	s_waitcnt lgkmcnt(0)
	s_barrier
	s_nop 7
	v_permlane16_swap_b32_e32 v50, v54
	v_permlane16_swap_b32_e32 v51, v55
	v_permlane16_swap_b32_e32 v52, v56
	v_permlane16_swap_b32_e32 v53, v57
	v_permlane16_swap_b32_e32 v58, v62
	v_permlane16_swap_b32_e32 v59, v63
	v_permlane16_swap_b32_e32 v60, v64
	v_permlane16_swap_b32_e32 v61, v65
	v_permlane16_swap_b32_e32 v34, v38
	v_permlane16_swap_b32_e32 v35, v39
	v_permlane16_swap_b32_e32 v36, v40
	v_permlane16_swap_b32_e32 v37, v41
	v_permlane16_swap_b32_e32 v42, v46
	v_permlane16_swap_b32_e32 v43, v47
	v_permlane16_swap_b32_e32 v44, v48
	v_permlane16_swap_b32_e32 v45, v49
	v_permlane16_swap_b32_e32 v18, v22
	v_permlane16_swap_b32_e32 v19, v23
	v_permlane16_swap_b32_e32 v20, v24
	v_permlane16_swap_b32_e32 v21, v25
	v_permlane16_swap_b32_e32 v26, v30
	v_permlane16_swap_b32_e32 v27, v31
	v_permlane16_swap_b32_e32 v28, v32
	v_permlane16_swap_b32_e32 v29, v33
	v_permlane16_swap_b32_e32 v2, v6
	v_permlane16_swap_b32_e32 v3, v7
	v_permlane16_swap_b32_e32 v4, v8
	v_permlane16_swap_b32_e32 v5, v9
	v_permlane16_swap_b32_e32 v10, v14
	v_permlane16_swap_b32_e32 v11, v15
	v_permlane16_swap_b32_e32 v12, v16
	v_permlane16_swap_b32_e32 v13, v17
	v_permlane32_swap_b32_e32 v50, v54
	v_permlane32_swap_b32_e32 v51, v55
	v_permlane32_swap_b32_e32 v52, v56
	v_permlane32_swap_b32_e32 v53, v57
	v_permlane32_swap_b32_e32 v58, v62
	v_permlane32_swap_b32_e32 v59, v63
	v_permlane32_swap_b32_e32 v60, v64
	v_permlane32_swap_b32_e32 v61, v65
	v_permlane32_swap_b32_e32 v34, v38
	v_permlane32_swap_b32_e32 v35, v39
	v_permlane32_swap_b32_e32 v36, v40
	v_permlane32_swap_b32_e32 v37, v41
	v_permlane32_swap_b32_e32 v42, v46
	v_permlane32_swap_b32_e32 v43, v47
	v_permlane32_swap_b32_e32 v44, v48
	v_permlane32_swap_b32_e32 v45, v49
	v_permlane32_swap_b32_e32 v18, v22
	v_permlane32_swap_b32_e32 v19, v23
	v_permlane32_swap_b32_e32 v20, v24
	v_permlane32_swap_b32_e32 v21, v25
	v_permlane32_swap_b32_e32 v26, v30
	v_permlane32_swap_b32_e32 v27, v31
	v_permlane32_swap_b32_e32 v28, v32
	v_permlane32_swap_b32_e32 v29, v33
	v_permlane32_swap_b32_e32 v2, v6
	v_permlane32_swap_b32_e32 v3, v7
	v_permlane32_swap_b32_e32 v4, v8
	v_permlane32_swap_b32_e32 v5, v9
	v_permlane32_swap_b32_e32 v10, v14
	v_permlane32_swap_b32_e32 v11, v15
	v_permlane32_swap_b32_e32 v12, v16
	v_permlane32_swap_b32_e32 v13, v17

.LBB0_1641:
	s_and_b32 s3, s2, 0xffff
	s_mul_i32 s3, s3, 0xaaab
	s_lshr_b32 s3, s3, 18
	s_mul_i32 s10, s3, 6
	s_sub_i32 s2, s2, s10
	s_and_b32 s2, s2, 0xffff
	s_add_i32 s2, s6, s2
	s_lshl_b32 s10, s2, 7
	v_or_b32_e32 v2, s10, v91
	v_lshlrev_b32_e32 v66, 11, v2
	v_lshl_add_u64 v[74:75], v[68:69], 0, v[66:67]
	v_add_lshl_u32 v66, s10, v92, 11
	s_add_i32 s3, s8, s3
	v_lshl_add_u64 v[76:77], v[68:69], 0, v[66:67]
	v_add_lshl_u32 v66, s10, v93, 11
	s_lshl_b32 s11, s3, 7
	v_lshl_add_u64 v[78:79], v[68:69], 0, v[66:67]
	v_add_lshl_u32 v66, s10, v94, 11
	v_lshl_add_u64 v[80:81], v[68:69], 0, v[66:67]
	v_or_b32_e32 v66, s11, v91
	v_lshlrev_b64 v[2:3], 11, v[66:67]
	v_add_u32_e32 v66, s11, v92
	v_lshl_add_u64 v[82:83], v[70:71], 0, v[2:3]
	v_lshlrev_b64 v[2:3], 11, v[66:67]
	v_add_u32_e32 v66, s11, v93
	v_lshl_add_u64 v[84:85], v[70:71], 0, v[2:3]
	v_lshlrev_b64 v[2:3], 11, v[66:67]
	v_add_u32_e32 v66, s11, v94
	v_lshl_add_u64 v[86:87], v[70:71], 0, v[2:3]
	v_lshlrev_b64 v[2:3], 11, v[66:67]
	v_lshl_add_u64 v[88:89], v[70:71], 0, v[2:3]
	global_load_dwordx4 v[2:5], v[74:75], off
	global_load_dwordx4 v[6:9], v[76:77], off
	global_load_dwordx4 v[10:13], v[78:79], off
	global_load_dwordx4 v[14:17], v[80:81], off
	global_load_dwordx4 v[18:21], v[82:83], off
	global_load_dwordx4 v[22:25], v[84:85], off
	global_load_dwordx4 v[26:29], v[86:87], off
	global_load_dwordx4 v[30:33], v[88:89], off
	global_load_dwordx4 v[102:105], v[74:75], off offset:128
	global_load_dwordx4 v[106:109], v[76:77], off offset:128
	global_load_dwordx4 v[110:113], v[78:79], off offset:128
	global_load_dwordx4 v[114:117], v[80:81], off offset:128
	global_load_dwordx4 v[118:121], v[82:83], off offset:128
	global_load_dwordx4 v[122:125], v[84:85], off offset:128
	global_load_dwordx4 v[126:129], v[86:87], off offset:128
	global_load_dwordx4 v[132:135], v[88:89], off offset:128
	s_waitcnt vmcnt(15)
	ds_write_b128 v98, v[2:5]
	s_waitcnt vmcnt(14)
	ds_write_b128 v98, v[6:9] offset:4608
	s_waitcnt vmcnt(13)
	ds_write_b128 v98, v[10:13] offset:9216
	s_waitcnt vmcnt(12)
	ds_write_b128 v98, v[14:17] offset:13824
	s_waitcnt vmcnt(11)
	ds_write_b128 v98, v[18:21] offset:36864
	s_waitcnt vmcnt(10)
	ds_write_b128 v98, v[22:25] offset:41472
	s_waitcnt vmcnt(9)
	ds_write_b128 v98, v[26:29] offset:46080
	s_waitcnt vmcnt(8)
	ds_write_b128 v98, v[30:33] offset:50688
	s_waitcnt lgkmcnt(0)
	s_barrier
	global_load_dwordx4 v[136:139], v[74:75], off offset:256
	global_load_dwordx4 v[140:143], v[76:77], off offset:256
	global_load_dwordx4 v[144:147], v[78:79], off offset:256
	global_load_dwordx4 v[148:151], v[80:81], off offset:256
	global_load_dwordx4 v[152:155], v[82:83], off offset:256
	global_load_dwordx4 v[156:159], v[84:85], off offset:256
	global_load_dwordx4 v[160:163], v[86:87], off offset:256
	global_load_dwordx4 v[164:167], v[88:89], off offset:256
	v_and_b32_e32 v246, 15, v1
	v_add_u32_e32 v246, 4, v246
	v_bfe_u32 v246, v246, 3, 1
	v_bfe_u32 v249, v1, 4, 2
	v_xor_b32_e32 v246, v246, v249
	v_bfe_u32 v249, v1, 5, 1
	v_sub_u32_e32 v246, v246, v249
	v_lshlrev_b32_e32 v246, 4, v246
	v_bfe_u32 v249, v1, 4, 1
	v_mul_u32_u24_e32 v249, 0x900, v249
	v_sub_u32_e32 v246, v246, v249
	v_add_u32_e32 v244, v246, v96
	v_add_u32_e32 v245, v246, v97
	ds_read_b128 v[212:215], v245 offset:36864
	ds_read_b128 v[196:199], v244
	ds_read_b128 v[216:219], v245 offset:39168
	ds_read_b128 v[220:223], v245 offset:41472
	ds_read_b128 v[224:227], v245 offset:43776
	ds_read_b128 v[200:203], v244 offset:2304
	ds_read_b128 v[204:207], v244 offset:4608
	ds_read_b128 v[208:211], v244 offset:6912
	s_waitcnt lgkmcnt(6)
	v_mfma_f32_16x16x32_bf16 v[50:53], v[196:199], v[212:215], 0
	ds_read_b128 v[228:231], v245 offset:36928
	s_waitcnt lgkmcnt(6)
	v_mfma_f32_16x16x32_bf16 v[54:57], v[196:199], v[216:219], 0
	ds_read_b128 v[232:235], v245 offset:39232
	s_waitcnt lgkmcnt(6)
	v_mfma_f32_16x16x32_bf16 v[18:21], v[196:199], v[220:223], 0
	ds_read_b128 v[236:239], v245 offset:41536
	s_waitcnt lgkmcnt(6)
	v_mfma_f32_16x16x32_bf16 v[22:25], v[196:199], v[224:227], 0
	ds_read_b128 v[240:243], v245 offset:43840
	ds_read_b128 v[196:199], v244 offset:64
	s_waitcnt lgkmcnt(7)
	v_mfma_f32_16x16x32_bf16 v[58:61], v[200:203], v[212:215], 0
	v_mfma_f32_16x16x32_bf16 v[62:65], v[200:203], v[216:219], 0
	v_mfma_f32_16x16x32_bf16 v[26:29], v[200:203], v[220:223], 0
	v_mfma_f32_16x16x32_bf16 v[30:33], v[200:203], v[224:227], 0
	ds_read_b128 v[200:203], v244 offset:2368
	s_waitcnt lgkmcnt(7)
	v_mfma_f32_16x16x32_bf16 v[34:37], v[204:207], v[212:215], 0
	v_mfma_f32_16x16x32_bf16 v[38:41], v[204:207], v[216:219], 0
	v_mfma_f32_16x16x32_bf16 v[2:5], v[204:207], v[220:223], 0
	v_mfma_f32_16x16x32_bf16 v[6:9], v[204:207], v[224:227], 0
	ds_read_b128 v[204:207], v244 offset:4672
	s_setprio 1
	s_waitcnt vmcnt(15)
	ds_write_b128 v98, v[102:105] offset:18432
	s_waitcnt vmcnt(14)
	ds_write_b128 v98, v[106:109] offset:23040
	s_waitcnt lgkmcnt(9)
	v_mfma_f32_16x16x32_bf16 v[42:45], v[208:211], v[212:215], 0
	v_mfma_f32_16x16x32_bf16 v[46:49], v[208:211], v[216:219], 0
	v_mfma_f32_16x16x32_bf16 v[10:13], v[208:211], v[220:223], 0
	v_mfma_f32_16x16x32_bf16 v[14:17], v[208:211], v[224:227], 0
	ds_read_b128 v[208:211], v244 offset:6976
	s_waitcnt vmcnt(13)
	ds_write_b128 v98, v[110:113] offset:27648
	s_waitcnt vmcnt(12)
	ds_write_b128 v98, v[114:117] offset:32256
	s_waitcnt lgkmcnt(7)
	v_mfma_f32_16x16x32_bf16 v[50:53], v[196:199], v[228:231], v[50:53]
	v_mfma_f32_16x16x32_bf16 v[54:57], v[196:199], v[232:235], v[54:57]
	v_mfma_f32_16x16x32_bf16 v[18:21], v[196:199], v[236:239], v[18:21]
	v_mfma_f32_16x16x32_bf16 v[22:25], v[196:199], v[240:243], v[22:25]
	s_waitcnt vmcnt(11)
	ds_write_b128 v98, v[118:121] offset:55296
	s_waitcnt vmcnt(10)
	ds_write_b128 v98, v[122:125] offset:59904
	s_waitcnt lgkmcnt(8)
	v_mfma_f32_16x16x32_bf16 v[58:61], v[200:203], v[228:231], v[58:61]
	v_mfma_f32_16x16x32_bf16 v[62:65], v[200:203], v[232:235], v[62:65]
	v_mfma_f32_16x16x32_bf16 v[26:29], v[200:203], v[236:239], v[26:29]
	v_mfma_f32_16x16x32_bf16 v[30:33], v[200:203], v[240:243], v[30:33]
	s_waitcnt vmcnt(9)
	ds_write_b128 v98, v[126:129] offset:64512
	s_waitcnt vmcnt(8)
	ds_write_b128 v99, v[132:135] offset:32256
	s_waitcnt lgkmcnt(0)
	s_barrier
	s_setprio 0
	ds_read_b128 v[212:215], v245 offset:55296
	ds_read_b128 v[196:199], v244 offset:18432
	ds_read_b128 v[216:219], v245 offset:57600
	ds_read_b128 v[220:223], v245 offset:59904
	ds_read_b128 v[224:227], v245 offset:62208
	ds_read_b128 v[200:203], v244 offset:20736
	v_mfma_f32_16x16x32_bf16 v[34:37], v[204:207], v[228:231], v[34:37]
	v_mfma_f32_16x16x32_bf16 v[38:41], v[204:207], v[232:235], v[38:41]
	v_mfma_f32_16x16x32_bf16 v[2:5], v[204:207], v[236:239], v[2:5]
	v_mfma_f32_16x16x32_bf16 v[6:9], v[204:207], v[240:243], v[6:9]
	ds_read_b128 v[204:207], v244 offset:23040
	v_mfma_f32_16x16x32_bf16 v[42:45], v[208:211], v[228:231], v[42:45]
	v_mfma_f32_16x16x32_bf16 v[46:49], v[208:211], v[232:235], v[46:49]
	v_mfma_f32_16x16x32_bf16 v[10:13], v[208:211], v[236:239], v[10:13]
	v_mfma_f32_16x16x32_bf16 v[14:17], v[208:211], v[240:243], v[14:17]
	ds_read_b128 v[208:211], v244 offset:25344
	global_load_dwordx4 v[102:105], v[74:75], off offset:384
	global_load_dwordx4 v[106:109], v[76:77], off offset:384
	global_load_dwordx4 v[110:113], v[78:79], off offset:384
	global_load_dwordx4 v[114:117], v[80:81], off offset:384
	global_load_dwordx4 v[118:121], v[82:83], off offset:384
	global_load_dwordx4 v[122:125], v[84:85], off offset:384
	global_load_dwordx4 v[126:129], v[86:87], off offset:384
	global_load_dwordx4 v[132:135], v[88:89], off offset:384
	s_waitcnt lgkmcnt(6)
	v_mfma_f32_16x16x32_bf16 v[50:53], v[196:199], v[212:215], v[50:53]
	ds_read_b128 v[228:231], v245 offset:55360
	s_waitcnt lgkmcnt(6)
	v_mfma_f32_16x16x32_bf16 v[54:57], v[196:199], v[216:219], v[54:57]
	ds_read_b128 v[232:235], v245 offset:57664
	s_waitcnt lgkmcnt(6)
	v_mfma_f32_16x16x32_bf16 v[18:21], v[196:199], v[220:223], v[18:21]
	ds_read_b128 v[236:239], v245 offset:59968
	s_waitcnt lgkmcnt(6)
	v_mfma_f32_16x16x32_bf16 v[22:25], v[196:199], v[224:227], v[22:25]
	ds_read_b128 v[240:243], v245 offset:62272
	ds_read_b128 v[196:199], v244 offset:18496
	s_waitcnt lgkmcnt(7)
	v_mfma_f32_16x16x32_bf16 v[58:61], v[200:203], v[212:215], v[58:61]
	v_mfma_f32_16x16x32_bf16 v[62:65], v[200:203], v[216:219], v[62:65]
	v_mfma_f32_16x16x32_bf16 v[26:29], v[200:203], v[220:223], v[26:29]
	v_mfma_f32_16x16x32_bf16 v[30:33], v[200:203], v[224:227], v[30:33]
	ds_read_b128 v[200:203], v244 offset:20800
	s_waitcnt lgkmcnt(7)
	v_mfma_f32_16x16x32_bf16 v[34:37], v[204:207], v[212:215], v[34:37]
	v_mfma_f32_16x16x32_bf16 v[38:41], v[204:207], v[216:219], v[38:41]
	v_mfma_f32_16x16x32_bf16 v[2:5], v[204:207], v[220:223], v[2:5]
	v_mfma_f32_16x16x32_bf16 v[6:9], v[204:207], v[224:227], v[6:9]
	ds_read_b128 v[204:207], v244 offset:23104
	s_setprio 1
	s_waitcnt vmcnt(15)
	ds_write_b128 v98, v[136:139]
	s_waitcnt vmcnt(14)
	ds_write_b128 v98, v[140:143] offset:4608
	s_waitcnt lgkmcnt(9)
	v_mfma_f32_16x16x32_bf16 v[42:45], v[208:211], v[212:215], v[42:45]
	v_mfma_f32_16x16x32_bf16 v[46:49], v[208:211], v[216:219], v[46:49]
	v_mfma_f32_16x16x32_bf16 v[10:13], v[208:211], v[220:223], v[10:13]
	v_mfma_f32_16x16x32_bf16 v[14:17], v[208:211], v[224:227], v[14:17]
	ds_read_b128 v[208:211], v244 offset:25408
	s_waitcnt vmcnt(13)
	ds_write_b128 v98, v[144:147] offset:9216
	s_waitcnt vmcnt(12)
	ds_write_b128 v98, v[148:151] offset:13824
	s_waitcnt lgkmcnt(7)
	v_mfma_f32_16x16x32_bf16 v[50:53], v[196:199], v[228:231], v[50:53]
	v_mfma_f32_16x16x32_bf16 v[54:57], v[196:199], v[232:235], v[54:57]
	v_mfma_f32_16x16x32_bf16 v[18:21], v[196:199], v[236:239], v[18:21]
	v_mfma_f32_16x16x32_bf16 v[22:25], v[196:199], v[240:243], v[22:25]
	s_waitcnt vmcnt(11)
	ds_write_b128 v98, v[152:155] offset:36864
	s_waitcnt vmcnt(10)
	ds_write_b128 v98, v[156:159] offset:41472
	s_waitcnt lgkmcnt(8)
	v_mfma_f32_16x16x32_bf16 v[58:61], v[200:203], v[228:231], v[58:61]
	v_mfma_f32_16x16x32_bf16 v[62:65], v[200:203], v[232:235], v[62:65]
	v_mfma_f32_16x16x32_bf16 v[26:29], v[200:203], v[236:239], v[26:29]
	v_mfma_f32_16x16x32_bf16 v[30:33], v[200:203], v[240:243], v[30:33]
	s_waitcnt vmcnt(9)
	ds_write_b128 v98, v[160:163] offset:46080
	s_waitcnt vmcnt(8)
	ds_write_b128 v98, v[164:167] offset:50688
	s_waitcnt lgkmcnt(0)
	s_barrier
	s_setprio 0
	ds_read_b128 v[212:215], v245 offset:36864
	ds_read_b128 v[196:199], v244
	ds_read_b128 v[216:219], v245 offset:39168
	ds_read_b128 v[220:223], v245 offset:41472
	ds_read_b128 v[224:227], v245 offset:43776
	ds_read_b128 v[200:203], v244 offset:2304
	v_mfma_f32_16x16x32_bf16 v[34:37], v[204:207], v[228:231], v[34:37]
	v_mfma_f32_16x16x32_bf16 v[38:41], v[204:207], v[232:235], v[38:41]
	v_mfma_f32_16x16x32_bf16 v[2:5], v[204:207], v[236:239], v[2:5]
	v_mfma_f32_16x16x32_bf16 v[6:9], v[204:207], v[240:243], v[6:9]
	ds_read_b128 v[204:207], v244 offset:4608
	v_mfma_f32_16x16x32_bf16 v[42:45], v[208:211], v[228:231], v[42:45]
	v_mfma_f32_16x16x32_bf16 v[46:49], v[208:211], v[232:235], v[46:49]
	v_mfma_f32_16x16x32_bf16 v[10:13], v[208:211], v[236:239], v[10:13]
	v_mfma_f32_16x16x32_bf16 v[14:17], v[208:211], v[240:243], v[14:17]
	ds_read_b128 v[208:211], v244 offset:6912
	global_load_dwordx4 v[136:139], v[74:75], off offset:512
	global_load_dwordx4 v[140:143], v[76:77], off offset:512
	global_load_dwordx4 v[144:147], v[78:79], off offset:512
	global_load_dwordx4 v[148:151], v[80:81], off offset:512
	global_load_dwordx4 v[152:155], v[82:83], off offset:512
	global_load_dwordx4 v[156:159], v[84:85], off offset:512
	global_load_dwordx4 v[160:163], v[86:87], off offset:512
	global_load_dwordx4 v[164:167], v[88:89], off offset:512
	s_waitcnt lgkmcnt(6)
	v_mfma_f32_16x16x32_bf16 v[50:53], v[196:199], v[212:215], v[50:53]
	ds_read_b128 v[228:231], v245 offset:36928
	s_waitcnt lgkmcnt(6)
	v_mfma_f32_16x16x32_bf16 v[54:57], v[196:199], v[216:219], v[54:57]
	ds_read_b128 v[232:235], v245 offset:39232
	s_waitcnt lgkmcnt(6)
	v_mfma_f32_16x16x32_bf16 v[18:21], v[196:199], v[220:223], v[18:21]
	ds_read_b128 v[236:239], v245 offset:41536
	s_waitcnt lgkmcnt(6)
	v_mfma_f32_16x16x32_bf16 v[22:25], v[196:199], v[224:227], v[22:25]
	ds_read_b128 v[240:243], v245 offset:43840
	ds_read_b128 v[196:199], v244 offset:64
	s_waitcnt lgkmcnt(7)
	v_mfma_f32_16x16x32_bf16 v[58:61], v[200:203], v[212:215], v[58:61]
	v_mfma_f32_16x16x32_bf16 v[62:65], v[200:203], v[216:219], v[62:65]
	v_mfma_f32_16x16x32_bf16 v[26:29], v[200:203], v[220:223], v[26:29]
	v_mfma_f32_16x16x32_bf16 v[30:33], v[200:203], v[224:227], v[30:33]
	ds_read_b128 v[200:203], v244 offset:2368
	s_waitcnt lgkmcnt(7)
	v_mfma_f32_16x16x32_bf16 v[34:37], v[204:207], v[212:215], v[34:37]
	v_mfma_f32_16x16x32_bf16 v[38:41], v[204:207], v[216:219], v[38:41]
	v_mfma_f32_16x16x32_bf16 v[2:5], v[204:207], v[220:223], v[2:5]
	v_mfma_f32_16x16x32_bf16 v[6:9], v[204:207], v[224:227], v[6:9]
	ds_read_b128 v[204:207], v244 offset:4672
	s_setprio 1
	s_waitcnt vmcnt(15)
	ds_write_b128 v98, v[102:105] offset:18432
	s_waitcnt vmcnt(14)
	ds_write_b128 v98, v[106:109] offset:23040
	s_waitcnt lgkmcnt(9)
	v_mfma_f32_16x16x32_bf16 v[42:45], v[208:211], v[212:215], v[42:45]
	v_mfma_f32_16x16x32_bf16 v[46:49], v[208:211], v[216:219], v[46:49]
	v_mfma_f32_16x16x32_bf16 v[10:13], v[208:211], v[220:223], v[10:13]
	v_mfma_f32_16x16x32_bf16 v[14:17], v[208:211], v[224:227], v[14:17]
	ds_read_b128 v[208:211], v244 offset:6976
	s_waitcnt vmcnt(13)
	ds_write_b128 v98, v[110:113] offset:27648
	s_waitcnt vmcnt(12)
	ds_write_b128 v98, v[114:117] offset:32256
	s_waitcnt lgkmcnt(7)
	v_mfma_f32_16x16x32_bf16 v[50:53], v[196:199], v[228:231], v[50:53]
	v_mfma_f32_16x16x32_bf16 v[54:57], v[196:199], v[232:235], v[54:57]
	v_mfma_f32_16x16x32_bf16 v[18:21], v[196:199], v[236:239], v[18:21]
	v_mfma_f32_16x16x32_bf16 v[22:25], v[196:199], v[240:243], v[22:25]
	s_waitcnt vmcnt(11)
	ds_write_b128 v98, v[118:121] offset:55296
	s_waitcnt vmcnt(10)
	ds_write_b128 v98, v[122:125] offset:59904
	s_waitcnt lgkmcnt(8)
	v_mfma_f32_16x16x32_bf16 v[58:61], v[200:203], v[228:231], v[58:61]
	v_mfma_f32_16x16x32_bf16 v[62:65], v[200:203], v[232:235], v[62:65]
	v_mfma_f32_16x16x32_bf16 v[26:29], v[200:203], v[236:239], v[26:29]
	v_mfma_f32_16x16x32_bf16 v[30:33], v[200:203], v[240:243], v[30:33]
	s_waitcnt vmcnt(9)
	ds_write_b128 v98, v[126:129] offset:64512
	s_waitcnt vmcnt(8)
	ds_write_b128 v99, v[132:135] offset:32256
	s_waitcnt lgkmcnt(0)
	s_barrier
	s_setprio 0
	ds_read_b128 v[212:215], v245 offset:55296
	ds_read_b128 v[196:199], v244 offset:18432
	ds_read_b128 v[216:219], v245 offset:57600
	ds_read_b128 v[220:223], v245 offset:59904
	ds_read_b128 v[224:227], v245 offset:62208
	ds_read_b128 v[200:203], v244 offset:20736
	v_mfma_f32_16x16x32_bf16 v[34:37], v[204:207], v[228:231], v[34:37]
	v_mfma_f32_16x16x32_bf16 v[38:41], v[204:207], v[232:235], v[38:41]
	v_mfma_f32_16x16x32_bf16 v[2:5], v[204:207], v[236:239], v[2:5]
	v_mfma_f32_16x16x32_bf16 v[6:9], v[204:207], v[240:243], v[6:9]
	ds_read_b128 v[204:207], v244 offset:23040
	v_mfma_f32_16x16x32_bf16 v[42:45], v[208:211], v[228:231], v[42:45]
	v_mfma_f32_16x16x32_bf16 v[46:49], v[208:211], v[232:235], v[46:49]
	v_mfma_f32_16x16x32_bf16 v[10:13], v[208:211], v[236:239], v[10:13]
	v_mfma_f32_16x16x32_bf16 v[14:17], v[208:211], v[240:243], v[14:17]
	ds_read_b128 v[208:211], v244 offset:25344
	global_load_dwordx4 v[102:105], v[74:75], off offset:640
	global_load_dwordx4 v[106:109], v[76:77], off offset:640
	global_load_dwordx4 v[110:113], v[78:79], off offset:640
	global_load_dwordx4 v[114:117], v[80:81], off offset:640
	global_load_dwordx4 v[118:121], v[82:83], off offset:640
	global_load_dwordx4 v[122:125], v[84:85], off offset:640
	global_load_dwordx4 v[126:129], v[86:87], off offset:640
	global_load_dwordx4 v[132:135], v[88:89], off offset:640
	s_waitcnt lgkmcnt(6)
	v_mfma_f32_16x16x32_bf16 v[50:53], v[196:199], v[212:215], v[50:53]
	ds_read_b128 v[228:231], v245 offset:55360
	s_waitcnt lgkmcnt(6)
	v_mfma_f32_16x16x32_bf16 v[54:57], v[196:199], v[216:219], v[54:57]
	ds_read_b128 v[232:235], v245 offset:57664
	s_waitcnt lgkmcnt(6)
	v_mfma_f32_16x16x32_bf16 v[18:21], v[196:199], v[220:223], v[18:21]
	ds_read_b128 v[236:239], v245 offset:59968
	s_waitcnt lgkmcnt(6)
	v_mfma_f32_16x16x32_bf16 v[22:25], v[196:199], v[224:227], v[22:25]
	ds_read_b128 v[240:243], v245 offset:62272
	ds_read_b128 v[196:199], v244 offset:18496
	s_waitcnt lgkmcnt(7)
	v_mfma_f32_16x16x32_bf16 v[58:61], v[200:203], v[212:215], v[58:61]
	v_mfma_f32_16x16x32_bf16 v[62:65], v[200:203], v[216:219], v[62:65]
	v_mfma_f32_16x16x32_bf16 v[26:29], v[200:203], v[220:223], v[26:29]
	v_mfma_f32_16x16x32_bf16 v[30:33], v[200:203], v[224:227], v[30:33]
	ds_read_b128 v[200:203], v244 offset:20800
	s_waitcnt lgkmcnt(7)
	v_mfma_f32_16x16x32_bf16 v[34:37], v[204:207], v[212:215], v[34:37]
	v_mfma_f32_16x16x32_bf16 v[38:41], v[204:207], v[216:219], v[38:41]
	v_mfma_f32_16x16x32_bf16 v[2:5], v[204:207], v[220:223], v[2:5]
	v_mfma_f32_16x16x32_bf16 v[6:9], v[204:207], v[224:227], v[6:9]
	ds_read_b128 v[204:207], v244 offset:23104
	s_setprio 1
	s_waitcnt vmcnt(15)
	ds_write_b128 v98, v[136:139]
	s_waitcnt vmcnt(14)
	ds_write_b128 v98, v[140:143] offset:4608
	s_waitcnt lgkmcnt(9)
	v_mfma_f32_16x16x32_bf16 v[42:45], v[208:211], v[212:215], v[42:45]
	v_mfma_f32_16x16x32_bf16 v[46:49], v[208:211], v[216:219], v[46:49]
	v_mfma_f32_16x16x32_bf16 v[10:13], v[208:211], v[220:223], v[10:13]
	v_mfma_f32_16x16x32_bf16 v[14:17], v[208:211], v[224:227], v[14:17]
	ds_read_b128 v[208:211], v244 offset:25408
	s_waitcnt vmcnt(13)
	ds_write_b128 v98, v[144:147] offset:9216
	s_waitcnt vmcnt(12)
	ds_write_b128 v98, v[148:151] offset:13824
	s_waitcnt lgkmcnt(7)
	v_mfma_f32_16x16x32_bf16 v[50:53], v[196:199], v[228:231], v[50:53]
	v_mfma_f32_16x16x32_bf16 v[54:57], v[196:199], v[232:235], v[54:57]
	v_mfma_f32_16x16x32_bf16 v[18:21], v[196:199], v[236:239], v[18:21]
	v_mfma_f32_16x16x32_bf16 v[22:25], v[196:199], v[240:243], v[22:25]
	s_waitcnt vmcnt(11)
	ds_write_b128 v98, v[152:155] offset:36864
	s_waitcnt vmcnt(10)
	ds_write_b128 v98, v[156:159] offset:41472
	s_waitcnt lgkmcnt(8)
	v_mfma_f32_16x16x32_bf16 v[58:61], v[200:203], v[228:231], v[58:61]
	v_mfma_f32_16x16x32_bf16 v[62:65], v[200:203], v[232:235], v[62:65]
	v_mfma_f32_16x16x32_bf16 v[26:29], v[200:203], v[236:239], v[26:29]
	v_mfma_f32_16x16x32_bf16 v[30:33], v[200:203], v[240:243], v[30:33]
	s_waitcnt vmcnt(9)
	ds_write_b128 v98, v[160:163] offset:46080
	s_waitcnt vmcnt(8)
	ds_write_b128 v98, v[164:167] offset:50688
	s_waitcnt lgkmcnt(0)
	s_barrier
	s_setprio 0
	ds_read_b128 v[212:215], v245 offset:36864
	ds_read_b128 v[196:199], v244
	ds_read_b128 v[216:219], v245 offset:39168
	ds_read_b128 v[220:223], v245 offset:41472
	ds_read_b128 v[224:227], v245 offset:43776
	ds_read_b128 v[200:203], v244 offset:2304
	v_mfma_f32_16x16x32_bf16 v[34:37], v[204:207], v[228:231], v[34:37]
	v_mfma_f32_16x16x32_bf16 v[38:41], v[204:207], v[232:235], v[38:41]
	v_mfma_f32_16x16x32_bf16 v[2:5], v[204:207], v[236:239], v[2:5]
	v_mfma_f32_16x16x32_bf16 v[6:9], v[204:207], v[240:243], v[6:9]
	ds_read_b128 v[204:207], v244 offset:4608
	v_mfma_f32_16x16x32_bf16 v[42:45], v[208:211], v[228:231], v[42:45]
	v_mfma_f32_16x16x32_bf16 v[46:49], v[208:211], v[232:235], v[46:49]
	v_mfma_f32_16x16x32_bf16 v[10:13], v[208:211], v[236:239], v[10:13]
	v_mfma_f32_16x16x32_bf16 v[14:17], v[208:211], v[240:243], v[14:17]
	ds_read_b128 v[208:211], v244 offset:6912
	global_load_dwordx4 v[136:139], v[74:75], off offset:768
	global_load_dwordx4 v[140:143], v[76:77], off offset:768
	global_load_dwordx4 v[144:147], v[78:79], off offset:768
	global_load_dwordx4 v[148:151], v[80:81], off offset:768
	global_load_dwordx4 v[152:155], v[82:83], off offset:768
	global_load_dwordx4 v[156:159], v[84:85], off offset:768
	global_load_dwordx4 v[160:163], v[86:87], off offset:768
	global_load_dwordx4 v[164:167], v[88:89], off offset:768
	s_waitcnt lgkmcnt(6)
	v_mfma_f32_16x16x32_bf16 v[50:53], v[196:199], v[212:215], v[50:53]
	ds_read_b128 v[228:231], v245 offset:36928
	s_waitcnt lgkmcnt(6)
	v_mfma_f32_16x16x32_bf16 v[54:57], v[196:199], v[216:219], v[54:57]
	ds_read_b128 v[232:235], v245 offset:39232
	s_waitcnt lgkmcnt(6)
	v_mfma_f32_16x16x32_bf16 v[18:21], v[196:199], v[220:223], v[18:21]
	ds_read_b128 v[236:239], v245 offset:41536
	s_waitcnt lgkmcnt(6)
	v_mfma_f32_16x16x32_bf16 v[22:25], v[196:199], v[224:227], v[22:25]
	ds_read_b128 v[240:243], v245 offset:43840
	ds_read_b128 v[196:199], v244 offset:64
	s_waitcnt lgkmcnt(7)
	v_mfma_f32_16x16x32_bf16 v[58:61], v[200:203], v[212:215], v[58:61]
	v_mfma_f32_16x16x32_bf16 v[62:65], v[200:203], v[216:219], v[62:65]
	v_mfma_f32_16x16x32_bf16 v[26:29], v[200:203], v[220:223], v[26:29]
	v_mfma_f32_16x16x32_bf16 v[30:33], v[200:203], v[224:227], v[30:33]
	ds_read_b128 v[200:203], v244 offset:2368
	s_waitcnt lgkmcnt(7)
	v_mfma_f32_16x16x32_bf16 v[34:37], v[204:207], v[212:215], v[34:37]
	v_mfma_f32_16x16x32_bf16 v[38:41], v[204:207], v[216:219], v[38:41]
	v_mfma_f32_16x16x32_bf16 v[2:5], v[204:207], v[220:223], v[2:5]
	v_mfma_f32_16x16x32_bf16 v[6:9], v[204:207], v[224:227], v[6:9]
	ds_read_b128 v[204:207], v244 offset:4672
	s_setprio 1
	s_waitcnt vmcnt(15)
	ds_write_b128 v98, v[102:105] offset:18432
	s_waitcnt vmcnt(14)
	ds_write_b128 v98, v[106:109] offset:23040
	s_waitcnt lgkmcnt(9)
	v_mfma_f32_16x16x32_bf16 v[42:45], v[208:211], v[212:215], v[42:45]
	v_mfma_f32_16x16x32_bf16 v[46:49], v[208:211], v[216:219], v[46:49]
	v_mfma_f32_16x16x32_bf16 v[10:13], v[208:211], v[220:223], v[10:13]
	v_mfma_f32_16x16x32_bf16 v[14:17], v[208:211], v[224:227], v[14:17]
	ds_read_b128 v[208:211], v244 offset:6976
	s_waitcnt vmcnt(13)
	ds_write_b128 v98, v[110:113] offset:27648
	s_waitcnt vmcnt(12)
	ds_write_b128 v98, v[114:117] offset:32256
	s_waitcnt lgkmcnt(7)
	v_mfma_f32_16x16x32_bf16 v[50:53], v[196:199], v[228:231], v[50:53]
	v_mfma_f32_16x16x32_bf16 v[54:57], v[196:199], v[232:235], v[54:57]
	v_mfma_f32_16x16x32_bf16 v[18:21], v[196:199], v[236:239], v[18:21]
	v_mfma_f32_16x16x32_bf16 v[22:25], v[196:199], v[240:243], v[22:25]
	s_waitcnt vmcnt(11)
	ds_write_b128 v98, v[118:121] offset:55296
	s_waitcnt vmcnt(10)
	ds_write_b128 v98, v[122:125] offset:59904
	s_waitcnt lgkmcnt(8)
	v_mfma_f32_16x16x32_bf16 v[58:61], v[200:203], v[228:231], v[58:61]
	v_mfma_f32_16x16x32_bf16 v[62:65], v[200:203], v[232:235], v[62:65]
	v_mfma_f32_16x16x32_bf16 v[26:29], v[200:203], v[236:239], v[26:29]
	v_mfma_f32_16x16x32_bf16 v[30:33], v[200:203], v[240:243], v[30:33]
	s_waitcnt vmcnt(9)
	ds_write_b128 v98, v[126:129] offset:64512
	s_waitcnt vmcnt(8)
	ds_write_b128 v99, v[132:135] offset:32256
	s_waitcnt lgkmcnt(0)
	s_barrier
	s_setprio 0
	ds_read_b128 v[212:215], v245 offset:55296
	ds_read_b128 v[196:199], v244 offset:18432
	ds_read_b128 v[216:219], v245 offset:57600
	ds_read_b128 v[220:223], v245 offset:59904
	ds_read_b128 v[224:227], v245 offset:62208
	ds_read_b128 v[200:203], v244 offset:20736
	v_mfma_f32_16x16x32_bf16 v[34:37], v[204:207], v[228:231], v[34:37]
	v_mfma_f32_16x16x32_bf16 v[38:41], v[204:207], v[232:235], v[38:41]
	v_mfma_f32_16x16x32_bf16 v[2:5], v[204:207], v[236:239], v[2:5]
	v_mfma_f32_16x16x32_bf16 v[6:9], v[204:207], v[240:243], v[6:9]
	ds_read_b128 v[204:207], v244 offset:23040
	v_mfma_f32_16x16x32_bf16 v[42:45], v[208:211], v[228:231], v[42:45]
	v_mfma_f32_16x16x32_bf16 v[46:49], v[208:211], v[232:235], v[46:49]
	v_mfma_f32_16x16x32_bf16 v[10:13], v[208:211], v[236:239], v[10:13]
	v_mfma_f32_16x16x32_bf16 v[14:17], v[208:211], v[240:243], v[14:17]
	ds_read_b128 v[208:211], v244 offset:25344
	global_load_dwordx4 v[102:105], v[74:75], off offset:896
	global_load_dwordx4 v[106:109], v[76:77], off offset:896
	global_load_dwordx4 v[110:113], v[78:79], off offset:896
	global_load_dwordx4 v[114:117], v[80:81], off offset:896
	global_load_dwordx4 v[118:121], v[82:83], off offset:896
	global_load_dwordx4 v[122:125], v[84:85], off offset:896
	global_load_dwordx4 v[126:129], v[86:87], off offset:896
	global_load_dwordx4 v[132:135], v[88:89], off offset:896
	s_waitcnt lgkmcnt(6)
	v_mfma_f32_16x16x32_bf16 v[50:53], v[196:199], v[212:215], v[50:53]
	ds_read_b128 v[228:231], v245 offset:55360
	s_waitcnt lgkmcnt(6)
	v_mfma_f32_16x16x32_bf16 v[54:57], v[196:199], v[216:219], v[54:57]
	ds_read_b128 v[232:235], v245 offset:57664
	s_waitcnt lgkmcnt(6)
	v_mfma_f32_16x16x32_bf16 v[18:21], v[196:199], v[220:223], v[18:21]
	ds_read_b128 v[236:239], v245 offset:59968
	s_waitcnt lgkmcnt(6)
	v_mfma_f32_16x16x32_bf16 v[22:25], v[196:199], v[224:227], v[22:25]
	ds_read_b128 v[240:243], v245 offset:62272
	ds_read_b128 v[196:199], v244 offset:18496
	s_waitcnt lgkmcnt(7)
	v_mfma_f32_16x16x32_bf16 v[58:61], v[200:203], v[212:215], v[58:61]
	v_mfma_f32_16x16x32_bf16 v[62:65], v[200:203], v[216:219], v[62:65]
	v_mfma_f32_16x16x32_bf16 v[26:29], v[200:203], v[220:223], v[26:29]
	v_mfma_f32_16x16x32_bf16 v[30:33], v[200:203], v[224:227], v[30:33]
	ds_read_b128 v[200:203], v244 offset:20800
	s_waitcnt lgkmcnt(7)
	v_mfma_f32_16x16x32_bf16 v[34:37], v[204:207], v[212:215], v[34:37]
	v_mfma_f32_16x16x32_bf16 v[38:41], v[204:207], v[216:219], v[38:41]
	v_mfma_f32_16x16x32_bf16 v[2:5], v[204:207], v[220:223], v[2:5]
	v_mfma_f32_16x16x32_bf16 v[6:9], v[204:207], v[224:227], v[6:9]
	ds_read_b128 v[204:207], v244 offset:23104
	s_setprio 1
	s_waitcnt vmcnt(15)
	ds_write_b128 v98, v[136:139]
	s_waitcnt vmcnt(14)
	ds_write_b128 v98, v[140:143] offset:4608
	s_waitcnt lgkmcnt(9)
	v_mfma_f32_16x16x32_bf16 v[42:45], v[208:211], v[212:215], v[42:45]
	v_mfma_f32_16x16x32_bf16 v[46:49], v[208:211], v[216:219], v[46:49]
	v_mfma_f32_16x16x32_bf16 v[10:13], v[208:211], v[220:223], v[10:13]
	v_mfma_f32_16x16x32_bf16 v[14:17], v[208:211], v[224:227], v[14:17]
	ds_read_b128 v[208:211], v244 offset:25408
	s_waitcnt vmcnt(13)
	ds_write_b128 v98, v[144:147] offset:9216
	s_waitcnt vmcnt(12)
	ds_write_b128 v98, v[148:151] offset:13824
	s_waitcnt lgkmcnt(7)
	v_mfma_f32_16x16x32_bf16 v[50:53], v[196:199], v[228:231], v[50:53]
	v_mfma_f32_16x16x32_bf16 v[54:57], v[196:199], v[232:235], v[54:57]
	v_mfma_f32_16x16x32_bf16 v[18:21], v[196:199], v[236:239], v[18:21]
	v_mfma_f32_16x16x32_bf16 v[22:25], v[196:199], v[240:243], v[22:25]
	s_waitcnt vmcnt(11)
	ds_write_b128 v98, v[152:155] offset:36864
	s_waitcnt vmcnt(10)
	ds_write_b128 v98, v[156:159] offset:41472
	s_waitcnt lgkmcnt(8)
	v_mfma_f32_16x16x32_bf16 v[58:61], v[200:203], v[228:231], v[58:61]
	v_mfma_f32_16x16x32_bf16 v[62:65], v[200:203], v[232:235], v[62:65]
	v_mfma_f32_16x16x32_bf16 v[26:29], v[200:203], v[236:239], v[26:29]
	v_mfma_f32_16x16x32_bf16 v[30:33], v[200:203], v[240:243], v[30:33]
	s_waitcnt vmcnt(9)
	ds_write_b128 v98, v[160:163] offset:46080
	s_waitcnt vmcnt(8)
	ds_write_b128 v98, v[164:167] offset:50688
	s_waitcnt lgkmcnt(0)
	s_barrier
	s_setprio 0
	ds_read_b128 v[212:215], v245 offset:36864
	ds_read_b128 v[196:199], v244
	ds_read_b128 v[216:219], v245 offset:39168
	ds_read_b128 v[220:223], v245 offset:41472
	ds_read_b128 v[224:227], v245 offset:43776
	ds_read_b128 v[200:203], v244 offset:2304
	v_mfma_f32_16x16x32_bf16 v[34:37], v[204:207], v[228:231], v[34:37]
	v_mfma_f32_16x16x32_bf16 v[38:41], v[204:207], v[232:235], v[38:41]
	v_mfma_f32_16x16x32_bf16 v[2:5], v[204:207], v[236:239], v[2:5]
	v_mfma_f32_16x16x32_bf16 v[6:9], v[204:207], v[240:243], v[6:9]
	ds_read_b128 v[204:207], v244 offset:4608
	v_mfma_f32_16x16x32_bf16 v[42:45], v[208:211], v[228:231], v[42:45]
	v_mfma_f32_16x16x32_bf16 v[46:49], v[208:211], v[232:235], v[46:49]
	v_mfma_f32_16x16x32_bf16 v[10:13], v[208:211], v[236:239], v[10:13]
	v_mfma_f32_16x16x32_bf16 v[14:17], v[208:211], v[240:243], v[14:17]
	ds_read_b128 v[208:211], v244 offset:6912
	global_load_dwordx4 v[136:139], v[74:75], off offset:1024
	global_load_dwordx4 v[140:143], v[76:77], off offset:1024
	global_load_dwordx4 v[144:147], v[78:79], off offset:1024
	global_load_dwordx4 v[148:151], v[80:81], off offset:1024
	global_load_dwordx4 v[152:155], v[82:83], off offset:1024
	global_load_dwordx4 v[156:159], v[84:85], off offset:1024
	global_load_dwordx4 v[160:163], v[86:87], off offset:1024
	global_load_dwordx4 v[164:167], v[88:89], off offset:1024
	s_waitcnt lgkmcnt(6)
	v_mfma_f32_16x16x32_bf16 v[50:53], v[196:199], v[212:215], v[50:53]
	ds_read_b128 v[228:231], v245 offset:36928
	s_waitcnt lgkmcnt(6)
	v_mfma_f32_16x16x32_bf16 v[54:57], v[196:199], v[216:219], v[54:57]
	ds_read_b128 v[232:235], v245 offset:39232
	s_waitcnt lgkmcnt(6)
	v_mfma_f32_16x16x32_bf16 v[18:21], v[196:199], v[220:223], v[18:21]
	ds_read_b128 v[236:239], v245 offset:41536
	s_waitcnt lgkmcnt(6)
	v_mfma_f32_16x16x32_bf16 v[22:25], v[196:199], v[224:227], v[22:25]
	ds_read_b128 v[240:243], v245 offset:43840
	ds_read_b128 v[196:199], v244 offset:64
	s_waitcnt lgkmcnt(7)
	v_mfma_f32_16x16x32_bf16 v[58:61], v[200:203], v[212:215], v[58:61]
	v_mfma_f32_16x16x32_bf16 v[62:65], v[200:203], v[216:219], v[62:65]
	v_mfma_f32_16x16x32_bf16 v[26:29], v[200:203], v[220:223], v[26:29]
	v_mfma_f32_16x16x32_bf16 v[30:33], v[200:203], v[224:227], v[30:33]
	ds_read_b128 v[200:203], v244 offset:2368
	s_waitcnt lgkmcnt(7)
	v_mfma_f32_16x16x32_bf16 v[34:37], v[204:207], v[212:215], v[34:37]
	v_mfma_f32_16x16x32_bf16 v[38:41], v[204:207], v[216:219], v[38:41]
	v_mfma_f32_16x16x32_bf16 v[2:5], v[204:207], v[220:223], v[2:5]
	v_mfma_f32_16x16x32_bf16 v[6:9], v[204:207], v[224:227], v[6:9]
	ds_read_b128 v[204:207], v244 offset:4672
	s_setprio 1
	s_waitcnt vmcnt(15)
	ds_write_b128 v98, v[102:105] offset:18432
	s_waitcnt vmcnt(14)
	ds_write_b128 v98, v[106:109] offset:23040
	s_waitcnt lgkmcnt(9)
	v_mfma_f32_16x16x32_bf16 v[42:45], v[208:211], v[212:215], v[42:45]
	v_mfma_f32_16x16x32_bf16 v[46:49], v[208:211], v[216:219], v[46:49]
	v_mfma_f32_16x16x32_bf16 v[10:13], v[208:211], v[220:223], v[10:13]
	v_mfma_f32_16x16x32_bf16 v[14:17], v[208:211], v[224:227], v[14:17]
	ds_read_b128 v[208:211], v244 offset:6976
	s_waitcnt vmcnt(13)
	ds_write_b128 v98, v[110:113] offset:27648
	s_waitcnt vmcnt(12)
	ds_write_b128 v98, v[114:117] offset:32256
	s_waitcnt lgkmcnt(7)
	v_mfma_f32_16x16x32_bf16 v[50:53], v[196:199], v[228:231], v[50:53]
	v_mfma_f32_16x16x32_bf16 v[54:57], v[196:199], v[232:235], v[54:57]
	v_mfma_f32_16x16x32_bf16 v[18:21], v[196:199], v[236:239], v[18:21]
	v_mfma_f32_16x16x32_bf16 v[22:25], v[196:199], v[240:243], v[22:25]
	s_waitcnt vmcnt(11)
	ds_write_b128 v98, v[118:121] offset:55296
	s_waitcnt vmcnt(10)
	ds_write_b128 v98, v[122:125] offset:59904
	s_waitcnt lgkmcnt(8)
	v_mfma_f32_16x16x32_bf16 v[58:61], v[200:203], v[228:231], v[58:61]
	v_mfma_f32_16x16x32_bf16 v[62:65], v[200:203], v[232:235], v[62:65]
	v_mfma_f32_16x16x32_bf16 v[26:29], v[200:203], v[236:239], v[26:29]
	v_mfma_f32_16x16x32_bf16 v[30:33], v[200:203], v[240:243], v[30:33]
	s_waitcnt vmcnt(9)
	ds_write_b128 v98, v[126:129] offset:64512
	s_waitcnt vmcnt(8)
	ds_write_b128 v99, v[132:135] offset:32256
	s_waitcnt lgkmcnt(0)
	s_barrier
	s_setprio 0
	ds_read_b128 v[212:215], v245 offset:55296
	ds_read_b128 v[196:199], v244 offset:18432
	ds_read_b128 v[216:219], v245 offset:57600
	ds_read_b128 v[220:223], v245 offset:59904
	ds_read_b128 v[224:227], v245 offset:62208
	ds_read_b128 v[200:203], v244 offset:20736
	v_mfma_f32_16x16x32_bf16 v[34:37], v[204:207], v[228:231], v[34:37]
	v_mfma_f32_16x16x32_bf16 v[38:41], v[204:207], v[232:235], v[38:41]
	v_mfma_f32_16x16x32_bf16 v[2:5], v[204:207], v[236:239], v[2:5]
	v_mfma_f32_16x16x32_bf16 v[6:9], v[204:207], v[240:243], v[6:9]
	ds_read_b128 v[204:207], v244 offset:23040
	v_mfma_f32_16x16x32_bf16 v[42:45], v[208:211], v[228:231], v[42:45]
	v_mfma_f32_16x16x32_bf16 v[46:49], v[208:211], v[232:235], v[46:49]
	v_mfma_f32_16x16x32_bf16 v[10:13], v[208:211], v[236:239], v[10:13]
	v_mfma_f32_16x16x32_bf16 v[14:17], v[208:211], v[240:243], v[14:17]
	ds_read_b128 v[208:211], v244 offset:25344
	global_load_dwordx4 v[102:105], v[74:75], off offset:1152
	global_load_dwordx4 v[106:109], v[76:77], off offset:1152
	global_load_dwordx4 v[110:113], v[78:79], off offset:1152
	global_load_dwordx4 v[114:117], v[80:81], off offset:1152
	global_load_dwordx4 v[118:121], v[82:83], off offset:1152
	global_load_dwordx4 v[122:125], v[84:85], off offset:1152
	global_load_dwordx4 v[126:129], v[86:87], off offset:1152
	global_load_dwordx4 v[132:135], v[88:89], off offset:1152
	s_waitcnt lgkmcnt(6)
	v_mfma_f32_16x16x32_bf16 v[50:53], v[196:199], v[212:215], v[50:53]
	ds_read_b128 v[228:231], v245 offset:55360
	s_waitcnt lgkmcnt(6)
	v_mfma_f32_16x16x32_bf16 v[54:57], v[196:199], v[216:219], v[54:57]
	ds_read_b128 v[232:235], v245 offset:57664
	s_waitcnt lgkmcnt(6)
	v_mfma_f32_16x16x32_bf16 v[18:21], v[196:199], v[220:223], v[18:21]
	ds_read_b128 v[236:239], v245 offset:59968
	s_waitcnt lgkmcnt(6)
	v_mfma_f32_16x16x32_bf16 v[22:25], v[196:199], v[224:227], v[22:25]
	ds_read_b128 v[240:243], v245 offset:62272
	ds_read_b128 v[196:199], v244 offset:18496
	s_waitcnt lgkmcnt(7)
	v_mfma_f32_16x16x32_bf16 v[58:61], v[200:203], v[212:215], v[58:61]
	v_mfma_f32_16x16x32_bf16 v[62:65], v[200:203], v[216:219], v[62:65]
	v_mfma_f32_16x16x32_bf16 v[26:29], v[200:203], v[220:223], v[26:29]
	v_mfma_f32_16x16x32_bf16 v[30:33], v[200:203], v[224:227], v[30:33]
	ds_read_b128 v[200:203], v244 offset:20800
	s_waitcnt lgkmcnt(7)
	v_mfma_f32_16x16x32_bf16 v[34:37], v[204:207], v[212:215], v[34:37]
	v_mfma_f32_16x16x32_bf16 v[38:41], v[204:207], v[216:219], v[38:41]
	v_mfma_f32_16x16x32_bf16 v[2:5], v[204:207], v[220:223], v[2:5]
	v_mfma_f32_16x16x32_bf16 v[6:9], v[204:207], v[224:227], v[6:9]
	ds_read_b128 v[204:207], v244 offset:23104
	s_setprio 1
	s_waitcnt vmcnt(15)
	ds_write_b128 v98, v[136:139]
	s_waitcnt vmcnt(14)
	ds_write_b128 v98, v[140:143] offset:4608
	s_waitcnt lgkmcnt(9)
	v_mfma_f32_16x16x32_bf16 v[42:45], v[208:211], v[212:215], v[42:45]
	v_mfma_f32_16x16x32_bf16 v[46:49], v[208:211], v[216:219], v[46:49]
	v_mfma_f32_16x16x32_bf16 v[10:13], v[208:211], v[220:223], v[10:13]
	v_mfma_f32_16x16x32_bf16 v[14:17], v[208:211], v[224:227], v[14:17]
	ds_read_b128 v[208:211], v244 offset:25408
	s_waitcnt vmcnt(13)
	ds_write_b128 v98, v[144:147] offset:9216
	s_waitcnt vmcnt(12)
	ds_write_b128 v98, v[148:151] offset:13824
	s_waitcnt lgkmcnt(7)
	v_mfma_f32_16x16x32_bf16 v[50:53], v[196:199], v[228:231], v[50:53]
	v_mfma_f32_16x16x32_bf16 v[54:57], v[196:199], v[232:235], v[54:57]
	v_mfma_f32_16x16x32_bf16 v[18:21], v[196:199], v[236:239], v[18:21]
	v_mfma_f32_16x16x32_bf16 v[22:25], v[196:199], v[240:243], v[22:25]
	s_waitcnt vmcnt(11)
	ds_write_b128 v98, v[152:155] offset:36864
	s_waitcnt vmcnt(10)
	ds_write_b128 v98, v[156:159] offset:41472
	s_waitcnt lgkmcnt(8)
	v_mfma_f32_16x16x32_bf16 v[58:61], v[200:203], v[228:231], v[58:61]
	v_mfma_f32_16x16x32_bf16 v[62:65], v[200:203], v[232:235], v[62:65]
	v_mfma_f32_16x16x32_bf16 v[26:29], v[200:203], v[236:239], v[26:29]
	v_mfma_f32_16x16x32_bf16 v[30:33], v[200:203], v[240:243], v[30:33]
	s_waitcnt vmcnt(9)
	ds_write_b128 v98, v[160:163] offset:46080
	s_waitcnt vmcnt(8)
	ds_write_b128 v98, v[164:167] offset:50688
	s_waitcnt lgkmcnt(0)
	s_barrier
	s_setprio 0
	ds_read_b128 v[212:215], v245 offset:36864
	ds_read_b128 v[196:199], v244
	ds_read_b128 v[216:219], v245 offset:39168
	ds_read_b128 v[220:223], v245 offset:41472
	ds_read_b128 v[224:227], v245 offset:43776
	ds_read_b128 v[200:203], v244 offset:2304
	v_mfma_f32_16x16x32_bf16 v[34:37], v[204:207], v[228:231], v[34:37]
	v_mfma_f32_16x16x32_bf16 v[38:41], v[204:207], v[232:235], v[38:41]
	v_mfma_f32_16x16x32_bf16 v[2:5], v[204:207], v[236:239], v[2:5]
	v_mfma_f32_16x16x32_bf16 v[6:9], v[204:207], v[240:243], v[6:9]
	ds_read_b128 v[204:207], v244 offset:4608
	v_mfma_f32_16x16x32_bf16 v[42:45], v[208:211], v[228:231], v[42:45]
	v_mfma_f32_16x16x32_bf16 v[46:49], v[208:211], v[232:235], v[46:49]
	v_mfma_f32_16x16x32_bf16 v[10:13], v[208:211], v[236:239], v[10:13]
	v_mfma_f32_16x16x32_bf16 v[14:17], v[208:211], v[240:243], v[14:17]
	ds_read_b128 v[208:211], v244 offset:6912
	global_load_dwordx4 v[136:139], v[74:75], off offset:1280
	global_load_dwordx4 v[140:143], v[76:77], off offset:1280
	global_load_dwordx4 v[144:147], v[78:79], off offset:1280
	global_load_dwordx4 v[148:151], v[80:81], off offset:1280
	global_load_dwordx4 v[152:155], v[82:83], off offset:1280
	global_load_dwordx4 v[156:159], v[84:85], off offset:1280
	global_load_dwordx4 v[160:163], v[86:87], off offset:1280
	global_load_dwordx4 v[164:167], v[88:89], off offset:1280
	s_waitcnt lgkmcnt(6)
	v_mfma_f32_16x16x32_bf16 v[50:53], v[196:199], v[212:215], v[50:53]
	ds_read_b128 v[228:231], v245 offset:36928
	s_waitcnt lgkmcnt(6)
	v_mfma_f32_16x16x32_bf16 v[54:57], v[196:199], v[216:219], v[54:57]
	ds_read_b128 v[232:235], v245 offset:39232
	s_waitcnt lgkmcnt(6)
	v_mfma_f32_16x16x32_bf16 v[18:21], v[196:199], v[220:223], v[18:21]
	ds_read_b128 v[236:239], v245 offset:41536
	s_waitcnt lgkmcnt(6)
	v_mfma_f32_16x16x32_bf16 v[22:25], v[196:199], v[224:227], v[22:25]
	ds_read_b128 v[240:243], v245 offset:43840
	ds_read_b128 v[196:199], v244 offset:64
	s_waitcnt lgkmcnt(7)
	v_mfma_f32_16x16x32_bf16 v[58:61], v[200:203], v[212:215], v[58:61]
	v_mfma_f32_16x16x32_bf16 v[62:65], v[200:203], v[216:219], v[62:65]
	v_mfma_f32_16x16x32_bf16 v[26:29], v[200:203], v[220:223], v[26:29]
	v_mfma_f32_16x16x32_bf16 v[30:33], v[200:203], v[224:227], v[30:33]
	ds_read_b128 v[200:203], v244 offset:2368
	s_waitcnt lgkmcnt(7)
	v_mfma_f32_16x16x32_bf16 v[34:37], v[204:207], v[212:215], v[34:37]
	v_mfma_f32_16x16x32_bf16 v[38:41], v[204:207], v[216:219], v[38:41]
	v_mfma_f32_16x16x32_bf16 v[2:5], v[204:207], v[220:223], v[2:5]
	v_mfma_f32_16x16x32_bf16 v[6:9], v[204:207], v[224:227], v[6:9]
	ds_read_b128 v[204:207], v244 offset:4672
	s_setprio 1
	s_waitcnt vmcnt(15)
	ds_write_b128 v98, v[102:105] offset:18432
	s_waitcnt vmcnt(14)
	ds_write_b128 v98, v[106:109] offset:23040
	s_waitcnt lgkmcnt(9)
	v_mfma_f32_16x16x32_bf16 v[42:45], v[208:211], v[212:215], v[42:45]
	v_mfma_f32_16x16x32_bf16 v[46:49], v[208:211], v[216:219], v[46:49]
	v_mfma_f32_16x16x32_bf16 v[10:13], v[208:211], v[220:223], v[10:13]
	v_mfma_f32_16x16x32_bf16 v[14:17], v[208:211], v[224:227], v[14:17]
	ds_read_b128 v[208:211], v244 offset:6976
	s_waitcnt vmcnt(13)
	ds_write_b128 v98, v[110:113] offset:27648
	s_waitcnt vmcnt(12)
	ds_write_b128 v98, v[114:117] offset:32256
	s_waitcnt lgkmcnt(7)
	v_mfma_f32_16x16x32_bf16 v[50:53], v[196:199], v[228:231], v[50:53]
	v_mfma_f32_16x16x32_bf16 v[54:57], v[196:199], v[232:235], v[54:57]
	v_mfma_f32_16x16x32_bf16 v[18:21], v[196:199], v[236:239], v[18:21]
	v_mfma_f32_16x16x32_bf16 v[22:25], v[196:199], v[240:243], v[22:25]
	s_waitcnt vmcnt(11)
	ds_write_b128 v98, v[118:121] offset:55296
	s_waitcnt vmcnt(10)
	ds_write_b128 v98, v[122:125] offset:59904
	s_waitcnt lgkmcnt(8)
	v_mfma_f32_16x16x32_bf16 v[58:61], v[200:203], v[228:231], v[58:61]
	v_mfma_f32_16x16x32_bf16 v[62:65], v[200:203], v[232:235], v[62:65]
	v_mfma_f32_16x16x32_bf16 v[26:29], v[200:203], v[236:239], v[26:29]
	v_mfma_f32_16x16x32_bf16 v[30:33], v[200:203], v[240:243], v[30:33]
	s_waitcnt vmcnt(9)
	ds_write_b128 v98, v[126:129] offset:64512
	s_waitcnt vmcnt(8)
	ds_write_b128 v99, v[132:135] offset:32256
	s_waitcnt lgkmcnt(0)
	s_barrier
	s_setprio 0
	ds_read_b128 v[212:215], v245 offset:55296
	ds_read_b128 v[196:199], v244 offset:18432
	ds_read_b128 v[216:219], v245 offset:57600
	ds_read_b128 v[220:223], v245 offset:59904
	ds_read_b128 v[224:227], v245 offset:62208
	ds_read_b128 v[200:203], v244 offset:20736
	v_mfma_f32_16x16x32_bf16 v[34:37], v[204:207], v[228:231], v[34:37]
	v_mfma_f32_16x16x32_bf16 v[38:41], v[204:207], v[232:235], v[38:41]
	v_mfma_f32_16x16x32_bf16 v[2:5], v[204:207], v[236:239], v[2:5]
	v_mfma_f32_16x16x32_bf16 v[6:9], v[204:207], v[240:243], v[6:9]
	ds_read_b128 v[204:207], v244 offset:23040
	v_mfma_f32_16x16x32_bf16 v[42:45], v[208:211], v[228:231], v[42:45]
	v_mfma_f32_16x16x32_bf16 v[46:49], v[208:211], v[232:235], v[46:49]
	v_mfma_f32_16x16x32_bf16 v[10:13], v[208:211], v[236:239], v[10:13]
	v_mfma_f32_16x16x32_bf16 v[14:17], v[208:211], v[240:243], v[14:17]
	ds_read_b128 v[208:211], v244 offset:25344
	global_load_dwordx4 v[102:105], v[74:75], off offset:1408
	global_load_dwordx4 v[106:109], v[76:77], off offset:1408
	global_load_dwordx4 v[110:113], v[78:79], off offset:1408
	global_load_dwordx4 v[114:117], v[80:81], off offset:1408
	global_load_dwordx4 v[118:121], v[82:83], off offset:1408
	global_load_dwordx4 v[122:125], v[84:85], off offset:1408
	global_load_dwordx4 v[126:129], v[86:87], off offset:1408
	global_load_dwordx4 v[132:135], v[88:89], off offset:1408
	s_waitcnt lgkmcnt(6)
	v_mfma_f32_16x16x32_bf16 v[50:53], v[196:199], v[212:215], v[50:53]
	ds_read_b128 v[228:231], v245 offset:55360
	s_waitcnt lgkmcnt(6)
	v_mfma_f32_16x16x32_bf16 v[54:57], v[196:199], v[216:219], v[54:57]
	ds_read_b128 v[232:235], v245 offset:57664
	s_waitcnt lgkmcnt(6)
	v_mfma_f32_16x16x32_bf16 v[18:21], v[196:199], v[220:223], v[18:21]
	ds_read_b128 v[236:239], v245 offset:59968
	s_waitcnt lgkmcnt(6)
	v_mfma_f32_16x16x32_bf16 v[22:25], v[196:199], v[224:227], v[22:25]
	ds_read_b128 v[240:243], v245 offset:62272
	ds_read_b128 v[196:199], v244 offset:18496
	s_waitcnt lgkmcnt(7)
	v_mfma_f32_16x16x32_bf16 v[58:61], v[200:203], v[212:215], v[58:61]
	v_mfma_f32_16x16x32_bf16 v[62:65], v[200:203], v[216:219], v[62:65]
	v_mfma_f32_16x16x32_bf16 v[26:29], v[200:203], v[220:223], v[26:29]
	v_mfma_f32_16x16x32_bf16 v[30:33], v[200:203], v[224:227], v[30:33]
	ds_read_b128 v[200:203], v244 offset:20800
	s_waitcnt lgkmcnt(7)
	v_mfma_f32_16x16x32_bf16 v[34:37], v[204:207], v[212:215], v[34:37]
	v_mfma_f32_16x16x32_bf16 v[38:41], v[204:207], v[216:219], v[38:41]
	v_mfma_f32_16x16x32_bf16 v[2:5], v[204:207], v[220:223], v[2:5]
	v_mfma_f32_16x16x32_bf16 v[6:9], v[204:207], v[224:227], v[6:9]
	ds_read_b128 v[204:207], v244 offset:23104
	s_setprio 1
	s_waitcnt vmcnt(15)
	ds_write_b128 v98, v[136:139]
	s_waitcnt vmcnt(14)
	ds_write_b128 v98, v[140:143] offset:4608
	s_waitcnt lgkmcnt(9)
	v_mfma_f32_16x16x32_bf16 v[42:45], v[208:211], v[212:215], v[42:45]
	v_mfma_f32_16x16x32_bf16 v[46:49], v[208:211], v[216:219], v[46:49]
	v_mfma_f32_16x16x32_bf16 v[10:13], v[208:211], v[220:223], v[10:13]
	v_mfma_f32_16x16x32_bf16 v[14:17], v[208:211], v[224:227], v[14:17]
	ds_read_b128 v[208:211], v244 offset:25408
	s_waitcnt vmcnt(13)
	ds_write_b128 v98, v[144:147] offset:9216
	s_waitcnt vmcnt(12)
	ds_write_b128 v98, v[148:151] offset:13824
	s_waitcnt lgkmcnt(7)
	v_mfma_f32_16x16x32_bf16 v[50:53], v[196:199], v[228:231], v[50:53]
	v_mfma_f32_16x16x32_bf16 v[54:57], v[196:199], v[232:235], v[54:57]
	v_mfma_f32_16x16x32_bf16 v[18:21], v[196:199], v[236:239], v[18:21]
	v_mfma_f32_16x16x32_bf16 v[22:25], v[196:199], v[240:243], v[22:25]
	s_waitcnt vmcnt(11)
	ds_write_b128 v98, v[152:155] offset:36864
	s_waitcnt vmcnt(10)
	ds_write_b128 v98, v[156:159] offset:41472
	s_waitcnt lgkmcnt(8)
	v_mfma_f32_16x16x32_bf16 v[58:61], v[200:203], v[228:231], v[58:61]
	v_mfma_f32_16x16x32_bf16 v[62:65], v[200:203], v[232:235], v[62:65]
	v_mfma_f32_16x16x32_bf16 v[26:29], v[200:203], v[236:239], v[26:29]
	v_mfma_f32_16x16x32_bf16 v[30:33], v[200:203], v[240:243], v[30:33]
	s_waitcnt vmcnt(9)
	ds_write_b128 v98, v[160:163] offset:46080
	s_waitcnt vmcnt(8)
	ds_write_b128 v98, v[164:167] offset:50688
	s_waitcnt lgkmcnt(0)
	s_barrier
	s_setprio 0
	ds_read_b128 v[212:215], v245 offset:36864
	ds_read_b128 v[196:199], v244
	ds_read_b128 v[216:219], v245 offset:39168
	ds_read_b128 v[220:223], v245 offset:41472
	ds_read_b128 v[224:227], v245 offset:43776
	ds_read_b128 v[200:203], v244 offset:2304
	v_mfma_f32_16x16x32_bf16 v[34:37], v[204:207], v[228:231], v[34:37]
	v_mfma_f32_16x16x32_bf16 v[38:41], v[204:207], v[232:235], v[38:41]
	v_mfma_f32_16x16x32_bf16 v[2:5], v[204:207], v[236:239], v[2:5]
	v_mfma_f32_16x16x32_bf16 v[6:9], v[204:207], v[240:243], v[6:9]
	ds_read_b128 v[204:207], v244 offset:4608
	v_mfma_f32_16x16x32_bf16 v[42:45], v[208:211], v[228:231], v[42:45]
	v_mfma_f32_16x16x32_bf16 v[46:49], v[208:211], v[232:235], v[46:49]
	v_mfma_f32_16x16x32_bf16 v[10:13], v[208:211], v[236:239], v[10:13]
	v_mfma_f32_16x16x32_bf16 v[14:17], v[208:211], v[240:243], v[14:17]
	ds_read_b128 v[208:211], v244 offset:6912
	global_load_dwordx4 v[136:139], v[74:75], off offset:1536
	global_load_dwordx4 v[140:143], v[76:77], off offset:1536
	global_load_dwordx4 v[144:147], v[78:79], off offset:1536
	global_load_dwordx4 v[148:151], v[80:81], off offset:1536
	global_load_dwordx4 v[152:155], v[82:83], off offset:1536
	global_load_dwordx4 v[156:159], v[84:85], off offset:1536
	global_load_dwordx4 v[160:163], v[86:87], off offset:1536
	global_load_dwordx4 v[164:167], v[88:89], off offset:1536
	s_waitcnt lgkmcnt(6)
	v_mfma_f32_16x16x32_bf16 v[50:53], v[196:199], v[212:215], v[50:53]
	ds_read_b128 v[228:231], v245 offset:36928
	s_waitcnt lgkmcnt(6)
	v_mfma_f32_16x16x32_bf16 v[54:57], v[196:199], v[216:219], v[54:57]
	ds_read_b128 v[232:235], v245 offset:39232
	s_waitcnt lgkmcnt(6)
	v_mfma_f32_16x16x32_bf16 v[18:21], v[196:199], v[220:223], v[18:21]
	ds_read_b128 v[236:239], v245 offset:41536
	s_waitcnt lgkmcnt(6)
	v_mfma_f32_16x16x32_bf16 v[22:25], v[196:199], v[224:227], v[22:25]
	ds_read_b128 v[240:243], v245 offset:43840
	ds_read_b128 v[196:199], v244 offset:64
	s_waitcnt lgkmcnt(7)
	v_mfma_f32_16x16x32_bf16 v[58:61], v[200:203], v[212:215], v[58:61]
	v_mfma_f32_16x16x32_bf16 v[62:65], v[200:203], v[216:219], v[62:65]
	v_mfma_f32_16x16x32_bf16 v[26:29], v[200:203], v[220:223], v[26:29]
	v_mfma_f32_16x16x32_bf16 v[30:33], v[200:203], v[224:227], v[30:33]
	ds_read_b128 v[200:203], v244 offset:2368
	s_waitcnt lgkmcnt(7)
	v_mfma_f32_16x16x32_bf16 v[34:37], v[204:207], v[212:215], v[34:37]
	v_mfma_f32_16x16x32_bf16 v[38:41], v[204:207], v[216:219], v[38:41]
	v_mfma_f32_16x16x32_bf16 v[2:5], v[204:207], v[220:223], v[2:5]
	v_mfma_f32_16x16x32_bf16 v[6:9], v[204:207], v[224:227], v[6:9]
	ds_read_b128 v[204:207], v244 offset:4672
	s_setprio 1
	s_waitcnt vmcnt(15)
	ds_write_b128 v98, v[102:105] offset:18432
	s_waitcnt vmcnt(14)
	ds_write_b128 v98, v[106:109] offset:23040
	s_waitcnt lgkmcnt(9)
	v_mfma_f32_16x16x32_bf16 v[42:45], v[208:211], v[212:215], v[42:45]
	v_mfma_f32_16x16x32_bf16 v[46:49], v[208:211], v[216:219], v[46:49]
	v_mfma_f32_16x16x32_bf16 v[10:13], v[208:211], v[220:223], v[10:13]
	v_mfma_f32_16x16x32_bf16 v[14:17], v[208:211], v[224:227], v[14:17]
	ds_read_b128 v[208:211], v244 offset:6976
	s_waitcnt vmcnt(13)
	ds_write_b128 v98, v[110:113] offset:27648
	s_waitcnt vmcnt(12)
	ds_write_b128 v98, v[114:117] offset:32256
	s_waitcnt lgkmcnt(7)
	v_mfma_f32_16x16x32_bf16 v[50:53], v[196:199], v[228:231], v[50:53]
	v_mfma_f32_16x16x32_bf16 v[54:57], v[196:199], v[232:235], v[54:57]
	v_mfma_f32_16x16x32_bf16 v[18:21], v[196:199], v[236:239], v[18:21]
	v_mfma_f32_16x16x32_bf16 v[22:25], v[196:199], v[240:243], v[22:25]
	s_waitcnt vmcnt(11)
	ds_write_b128 v98, v[118:121] offset:55296
	s_waitcnt vmcnt(10)
	ds_write_b128 v98, v[122:125] offset:59904
	s_waitcnt lgkmcnt(8)
	v_mfma_f32_16x16x32_bf16 v[58:61], v[200:203], v[228:231], v[58:61]
	v_mfma_f32_16x16x32_bf16 v[62:65], v[200:203], v[232:235], v[62:65]
	v_mfma_f32_16x16x32_bf16 v[26:29], v[200:203], v[236:239], v[26:29]
	v_mfma_f32_16x16x32_bf16 v[30:33], v[200:203], v[240:243], v[30:33]
	s_waitcnt vmcnt(9)
	ds_write_b128 v98, v[126:129] offset:64512
	s_waitcnt vmcnt(8)
	ds_write_b128 v99, v[132:135] offset:32256
	s_waitcnt lgkmcnt(0)
	s_barrier
	s_setprio 0
	ds_read_b128 v[212:215], v245 offset:55296
	ds_read_b128 v[196:199], v244 offset:18432
	ds_read_b128 v[216:219], v245 offset:57600
	ds_read_b128 v[220:223], v245 offset:59904
	ds_read_b128 v[224:227], v245 offset:62208
	ds_read_b128 v[200:203], v244 offset:20736
	v_mfma_f32_16x16x32_bf16 v[34:37], v[204:207], v[228:231], v[34:37]
	v_mfma_f32_16x16x32_bf16 v[38:41], v[204:207], v[232:235], v[38:41]
	v_mfma_f32_16x16x32_bf16 v[2:5], v[204:207], v[236:239], v[2:5]
	v_mfma_f32_16x16x32_bf16 v[6:9], v[204:207], v[240:243], v[6:9]
	ds_read_b128 v[204:207], v244 offset:23040
	v_mfma_f32_16x16x32_bf16 v[42:45], v[208:211], v[228:231], v[42:45]
	v_mfma_f32_16x16x32_bf16 v[46:49], v[208:211], v[232:235], v[46:49]
	v_mfma_f32_16x16x32_bf16 v[10:13], v[208:211], v[236:239], v[10:13]
	v_mfma_f32_16x16x32_bf16 v[14:17], v[208:211], v[240:243], v[14:17]
	ds_read_b128 v[208:211], v244 offset:25344
	global_load_dwordx4 v[102:105], v[74:75], off offset:1664
	global_load_dwordx4 v[106:109], v[76:77], off offset:1664
	global_load_dwordx4 v[110:113], v[78:79], off offset:1664
	global_load_dwordx4 v[114:117], v[80:81], off offset:1664
	global_load_dwordx4 v[118:121], v[82:83], off offset:1664
	global_load_dwordx4 v[122:125], v[84:85], off offset:1664
	global_load_dwordx4 v[126:129], v[86:87], off offset:1664
	global_load_dwordx4 v[132:135], v[88:89], off offset:1664
	s_waitcnt lgkmcnt(6)
	v_mfma_f32_16x16x32_bf16 v[50:53], v[196:199], v[212:215], v[50:53]
	ds_read_b128 v[228:231], v245 offset:55360
	s_waitcnt lgkmcnt(6)
	v_mfma_f32_16x16x32_bf16 v[54:57], v[196:199], v[216:219], v[54:57]
	ds_read_b128 v[232:235], v245 offset:57664
	s_waitcnt lgkmcnt(6)
	v_mfma_f32_16x16x32_bf16 v[18:21], v[196:199], v[220:223], v[18:21]
	ds_read_b128 v[236:239], v245 offset:59968
	s_waitcnt lgkmcnt(6)
	v_mfma_f32_16x16x32_bf16 v[22:25], v[196:199], v[224:227], v[22:25]
	ds_read_b128 v[240:243], v245 offset:62272
	ds_read_b128 v[196:199], v244 offset:18496
	s_waitcnt lgkmcnt(7)
	v_mfma_f32_16x16x32_bf16 v[58:61], v[200:203], v[212:215], v[58:61]
	v_mfma_f32_16x16x32_bf16 v[62:65], v[200:203], v[216:219], v[62:65]
	v_mfma_f32_16x16x32_bf16 v[26:29], v[200:203], v[220:223], v[26:29]
	v_mfma_f32_16x16x32_bf16 v[30:33], v[200:203], v[224:227], v[30:33]
	ds_read_b128 v[200:203], v244 offset:20800
	s_waitcnt lgkmcnt(7)
	v_mfma_f32_16x16x32_bf16 v[34:37], v[204:207], v[212:215], v[34:37]
	v_mfma_f32_16x16x32_bf16 v[38:41], v[204:207], v[216:219], v[38:41]
	v_mfma_f32_16x16x32_bf16 v[2:5], v[204:207], v[220:223], v[2:5]
	v_mfma_f32_16x16x32_bf16 v[6:9], v[204:207], v[224:227], v[6:9]
	ds_read_b128 v[204:207], v244 offset:23104
	s_setprio 1
	s_waitcnt vmcnt(15)
	ds_write_b128 v98, v[136:139]
	s_waitcnt vmcnt(14)
	ds_write_b128 v98, v[140:143] offset:4608
	s_waitcnt lgkmcnt(9)
	v_mfma_f32_16x16x32_bf16 v[42:45], v[208:211], v[212:215], v[42:45]
	v_mfma_f32_16x16x32_bf16 v[46:49], v[208:211], v[216:219], v[46:49]
	v_mfma_f32_16x16x32_bf16 v[10:13], v[208:211], v[220:223], v[10:13]
	v_mfma_f32_16x16x32_bf16 v[14:17], v[208:211], v[224:227], v[14:17]
	ds_read_b128 v[208:211], v244 offset:25408
	s_waitcnt vmcnt(13)
	ds_write_b128 v98, v[144:147] offset:9216
	s_waitcnt vmcnt(12)
	ds_write_b128 v98, v[148:151] offset:13824
	s_waitcnt lgkmcnt(7)
	v_mfma_f32_16x16x32_bf16 v[50:53], v[196:199], v[228:231], v[50:53]
	v_mfma_f32_16x16x32_bf16 v[54:57], v[196:199], v[232:235], v[54:57]
	v_mfma_f32_16x16x32_bf16 v[18:21], v[196:199], v[236:239], v[18:21]
	v_mfma_f32_16x16x32_bf16 v[22:25], v[196:199], v[240:243], v[22:25]
	s_waitcnt vmcnt(11)
	ds_write_b128 v98, v[152:155] offset:36864
	s_waitcnt vmcnt(10)
	ds_write_b128 v98, v[156:159] offset:41472
	s_waitcnt lgkmcnt(8)
	v_mfma_f32_16x16x32_bf16 v[58:61], v[200:203], v[228:231], v[58:61]
	v_mfma_f32_16x16x32_bf16 v[62:65], v[200:203], v[232:235], v[62:65]
	v_mfma_f32_16x16x32_bf16 v[26:29], v[200:203], v[236:239], v[26:29]
	v_mfma_f32_16x16x32_bf16 v[30:33], v[200:203], v[240:243], v[30:33]
	s_waitcnt vmcnt(9)
	ds_write_b128 v98, v[160:163] offset:46080
	s_waitcnt vmcnt(8)
	ds_write_b128 v98, v[164:167] offset:50688
	s_waitcnt lgkmcnt(0)
	s_barrier
	s_setprio 0
	ds_read_b128 v[212:215], v245 offset:36864
	ds_read_b128 v[196:199], v244
	ds_read_b128 v[216:219], v245 offset:39168
	ds_read_b128 v[220:223], v245 offset:41472
	ds_read_b128 v[224:227], v245 offset:43776
	ds_read_b128 v[200:203], v244 offset:2304
	v_mfma_f32_16x16x32_bf16 v[34:37], v[204:207], v[228:231], v[34:37]
	v_mfma_f32_16x16x32_bf16 v[38:41], v[204:207], v[232:235], v[38:41]
	v_mfma_f32_16x16x32_bf16 v[2:5], v[204:207], v[236:239], v[2:5]
	v_mfma_f32_16x16x32_bf16 v[6:9], v[204:207], v[240:243], v[6:9]
	ds_read_b128 v[204:207], v244 offset:4608
	v_mfma_f32_16x16x32_bf16 v[42:45], v[208:211], v[228:231], v[42:45]
	v_mfma_f32_16x16x32_bf16 v[46:49], v[208:211], v[232:235], v[46:49]
	v_mfma_f32_16x16x32_bf16 v[10:13], v[208:211], v[236:239], v[10:13]
	v_mfma_f32_16x16x32_bf16 v[14:17], v[208:211], v[240:243], v[14:17]
	ds_read_b128 v[208:211], v244 offset:6912
	global_load_dwordx4 v[136:139], v[74:75], off offset:1792
	global_load_dwordx4 v[140:143], v[76:77], off offset:1792
	global_load_dwordx4 v[144:147], v[78:79], off offset:1792
	global_load_dwordx4 v[148:151], v[80:81], off offset:1792
	global_load_dwordx4 v[152:155], v[82:83], off offset:1792
	global_load_dwordx4 v[156:159], v[84:85], off offset:1792
	global_load_dwordx4 v[160:163], v[86:87], off offset:1792
	global_load_dwordx4 v[164:167], v[88:89], off offset:1792
	s_waitcnt lgkmcnt(6)
	v_mfma_f32_16x16x32_bf16 v[50:53], v[196:199], v[212:215], v[50:53]
	ds_read_b128 v[228:231], v245 offset:36928
	s_waitcnt lgkmcnt(6)
	v_mfma_f32_16x16x32_bf16 v[54:57], v[196:199], v[216:219], v[54:57]
	ds_read_b128 v[232:235], v245 offset:39232
	s_waitcnt lgkmcnt(6)
	v_mfma_f32_16x16x32_bf16 v[18:21], v[196:199], v[220:223], v[18:21]
	ds_read_b128 v[236:239], v245 offset:41536
	s_waitcnt lgkmcnt(6)
	v_mfma_f32_16x16x32_bf16 v[22:25], v[196:199], v[224:227], v[22:25]
	ds_read_b128 v[240:243], v245 offset:43840
	ds_read_b128 v[196:199], v244 offset:64
	s_waitcnt lgkmcnt(7)
	v_mfma_f32_16x16x32_bf16 v[58:61], v[200:203], v[212:215], v[58:61]
	v_mfma_f32_16x16x32_bf16 v[62:65], v[200:203], v[216:219], v[62:65]
	v_mfma_f32_16x16x32_bf16 v[26:29], v[200:203], v[220:223], v[26:29]
	v_mfma_f32_16x16x32_bf16 v[30:33], v[200:203], v[224:227], v[30:33]
	ds_read_b128 v[200:203], v244 offset:2368
	s_waitcnt lgkmcnt(7)
	v_mfma_f32_16x16x32_bf16 v[34:37], v[204:207], v[212:215], v[34:37]
	v_mfma_f32_16x16x32_bf16 v[38:41], v[204:207], v[216:219], v[38:41]
	v_mfma_f32_16x16x32_bf16 v[2:5], v[204:207], v[220:223], v[2:5]
	v_mfma_f32_16x16x32_bf16 v[6:9], v[204:207], v[224:227], v[6:9]
	ds_read_b128 v[204:207], v244 offset:4672
	s_setprio 1
	s_waitcnt vmcnt(15)
	ds_write_b128 v98, v[102:105] offset:18432
	s_waitcnt vmcnt(14)
	ds_write_b128 v98, v[106:109] offset:23040
	s_waitcnt lgkmcnt(9)
	v_mfma_f32_16x16x32_bf16 v[42:45], v[208:211], v[212:215], v[42:45]
	v_mfma_f32_16x16x32_bf16 v[46:49], v[208:211], v[216:219], v[46:49]
	v_mfma_f32_16x16x32_bf16 v[10:13], v[208:211], v[220:223], v[10:13]
	v_mfma_f32_16x16x32_bf16 v[14:17], v[208:211], v[224:227], v[14:17]
	ds_read_b128 v[208:211], v244 offset:6976
	s_waitcnt vmcnt(13)
	ds_write_b128 v98, v[110:113] offset:27648
	s_waitcnt vmcnt(12)
	ds_write_b128 v98, v[114:117] offset:32256
	s_waitcnt lgkmcnt(7)
	v_mfma_f32_16x16x32_bf16 v[50:53], v[196:199], v[228:231], v[50:53]
	v_mfma_f32_16x16x32_bf16 v[54:57], v[196:199], v[232:235], v[54:57]
	v_mfma_f32_16x16x32_bf16 v[18:21], v[196:199], v[236:239], v[18:21]
	v_mfma_f32_16x16x32_bf16 v[22:25], v[196:199], v[240:243], v[22:25]
	s_waitcnt vmcnt(11)
	ds_write_b128 v98, v[118:121] offset:55296
	s_waitcnt vmcnt(10)
	ds_write_b128 v98, v[122:125] offset:59904
	s_waitcnt lgkmcnt(8)
	v_mfma_f32_16x16x32_bf16 v[58:61], v[200:203], v[228:231], v[58:61]
	v_mfma_f32_16x16x32_bf16 v[62:65], v[200:203], v[232:235], v[62:65]
	v_mfma_f32_16x16x32_bf16 v[26:29], v[200:203], v[236:239], v[26:29]
	v_mfma_f32_16x16x32_bf16 v[30:33], v[200:203], v[240:243], v[30:33]
	s_waitcnt vmcnt(9)
	ds_write_b128 v98, v[126:129] offset:64512
	s_waitcnt vmcnt(8)
	ds_write_b128 v99, v[132:135] offset:32256
	s_waitcnt lgkmcnt(0)
	s_barrier
	s_setprio 0
	ds_read_b128 v[212:215], v245 offset:55296
	ds_read_b128 v[196:199], v244 offset:18432
	ds_read_b128 v[216:219], v245 offset:57600
	ds_read_b128 v[220:223], v245 offset:59904
	ds_read_b128 v[224:227], v245 offset:62208
	ds_read_b128 v[200:203], v244 offset:20736
	v_mfma_f32_16x16x32_bf16 v[34:37], v[204:207], v[228:231], v[34:37]
	v_mfma_f32_16x16x32_bf16 v[38:41], v[204:207], v[232:235], v[38:41]
	v_mfma_f32_16x16x32_bf16 v[2:5], v[204:207], v[236:239], v[2:5]
	v_mfma_f32_16x16x32_bf16 v[6:9], v[204:207], v[240:243], v[6:9]
	ds_read_b128 v[204:207], v244 offset:23040
	v_mfma_f32_16x16x32_bf16 v[42:45], v[208:211], v[228:231], v[42:45]
	v_mfma_f32_16x16x32_bf16 v[46:49], v[208:211], v[232:235], v[46:49]
	v_mfma_f32_16x16x32_bf16 v[10:13], v[208:211], v[236:239], v[10:13]
	v_mfma_f32_16x16x32_bf16 v[14:17], v[208:211], v[240:243], v[14:17]
	ds_read_b128 v[208:211], v244 offset:25344
	global_load_dwordx4 v[102:105], v[74:75], off offset:1920
	s_nop 0
	global_load_dwordx4 v[74:77], v[76:77], off offset:1920
	s_nop 0
	global_load_dwordx4 v[106:109], v[78:79], off offset:1920
	s_nop 0
	global_load_dwordx4 v[78:81], v[80:81], off offset:1920
	s_nop 0
	global_load_dwordx4 v[110:113], v[82:83], off offset:1920
	s_nop 0
	global_load_dwordx4 v[82:85], v[84:85], off offset:1920
	s_nop 0
	global_load_dwordx4 v[114:117], v[86:87], off offset:1920
	s_nop 0
	global_load_dwordx4 v[86:89], v[88:89], off offset:1920
	s_waitcnt lgkmcnt(6)
	v_mfma_f32_16x16x32_bf16 v[50:53], v[196:199], v[212:215], v[50:53]
	ds_read_b128 v[228:231], v245 offset:55360
	s_waitcnt lgkmcnt(6)
	v_mfma_f32_16x16x32_bf16 v[54:57], v[196:199], v[216:219], v[54:57]
	ds_read_b128 v[232:235], v245 offset:57664
	s_waitcnt lgkmcnt(6)
	v_mfma_f32_16x16x32_bf16 v[18:21], v[196:199], v[220:223], v[18:21]
	ds_read_b128 v[236:239], v245 offset:59968
	s_waitcnt lgkmcnt(6)
	v_mfma_f32_16x16x32_bf16 v[22:25], v[196:199], v[224:227], v[22:25]
	ds_read_b128 v[240:243], v245 offset:62272
	ds_read_b128 v[196:199], v244 offset:18496
	s_waitcnt lgkmcnt(7)
	v_mfma_f32_16x16x32_bf16 v[58:61], v[200:203], v[212:215], v[58:61]
	v_mfma_f32_16x16x32_bf16 v[62:65], v[200:203], v[216:219], v[62:65]
	v_mfma_f32_16x16x32_bf16 v[26:29], v[200:203], v[220:223], v[26:29]
	v_mfma_f32_16x16x32_bf16 v[30:33], v[200:203], v[224:227], v[30:33]
	ds_read_b128 v[200:203], v244 offset:20800
	s_waitcnt lgkmcnt(7)
	v_mfma_f32_16x16x32_bf16 v[34:37], v[204:207], v[212:215], v[34:37]
	v_mfma_f32_16x16x32_bf16 v[38:41], v[204:207], v[216:219], v[38:41]
	v_mfma_f32_16x16x32_bf16 v[2:5], v[204:207], v[220:223], v[2:5]
	v_mfma_f32_16x16x32_bf16 v[6:9], v[204:207], v[224:227], v[6:9]
	ds_read_b128 v[204:207], v244 offset:23104
	s_setprio 1
	s_waitcnt vmcnt(15)
	ds_write_b128 v98, v[136:139]
	s_waitcnt vmcnt(14)
	ds_write_b128 v98, v[140:143] offset:4608
	s_waitcnt lgkmcnt(9)
	v_mfma_f32_16x16x32_bf16 v[42:45], v[208:211], v[212:215], v[42:45]
	v_mfma_f32_16x16x32_bf16 v[46:49], v[208:211], v[216:219], v[46:49]
	v_mfma_f32_16x16x32_bf16 v[10:13], v[208:211], v[220:223], v[10:13]
	v_mfma_f32_16x16x32_bf16 v[14:17], v[208:211], v[224:227], v[14:17]
	ds_read_b128 v[208:211], v244 offset:25408
	s_waitcnt vmcnt(13)
	ds_write_b128 v98, v[144:147] offset:9216
	s_waitcnt vmcnt(12)
	ds_write_b128 v98, v[148:151] offset:13824
	s_waitcnt lgkmcnt(7)
	v_mfma_f32_16x16x32_bf16 v[50:53], v[196:199], v[228:231], v[50:53]
	v_mfma_f32_16x16x32_bf16 v[54:57], v[196:199], v[232:235], v[54:57]
	v_mfma_f32_16x16x32_bf16 v[18:21], v[196:199], v[236:239], v[18:21]
	v_mfma_f32_16x16x32_bf16 v[22:25], v[196:199], v[240:243], v[22:25]
	s_waitcnt vmcnt(11)
	ds_write_b128 v98, v[152:155] offset:36864
	s_waitcnt vmcnt(10)
	ds_write_b128 v98, v[156:159] offset:41472
	s_waitcnt lgkmcnt(8)
	v_mfma_f32_16x16x32_bf16 v[58:61], v[200:203], v[228:231], v[58:61]
	v_mfma_f32_16x16x32_bf16 v[62:65], v[200:203], v[232:235], v[62:65]
	v_mfma_f32_16x16x32_bf16 v[26:29], v[200:203], v[236:239], v[26:29]
	v_mfma_f32_16x16x32_bf16 v[30:33], v[200:203], v[240:243], v[30:33]
	s_waitcnt vmcnt(9)
	ds_write_b128 v98, v[160:163] offset:46080
	s_waitcnt vmcnt(8)
	ds_write_b128 v98, v[164:167] offset:50688
	s_waitcnt lgkmcnt(0)
	s_barrier
	s_setprio 0
	ds_read_b128 v[212:215], v245 offset:36864
	ds_read_b128 v[196:199], v244
	ds_read_b128 v[216:219], v245 offset:39168
	ds_read_b128 v[220:223], v245 offset:41472
	ds_read_b128 v[224:227], v245 offset:43776
	ds_read_b128 v[200:203], v244 offset:2304
	v_mfma_f32_16x16x32_bf16 v[34:37], v[204:207], v[228:231], v[34:37]
	v_mfma_f32_16x16x32_bf16 v[38:41], v[204:207], v[232:235], v[38:41]
	v_mfma_f32_16x16x32_bf16 v[2:5], v[204:207], v[236:239], v[2:5]
	v_mfma_f32_16x16x32_bf16 v[6:9], v[204:207], v[240:243], v[6:9]
	ds_read_b128 v[204:207], v244 offset:4608
	v_mfma_f32_16x16x32_bf16 v[42:45], v[208:211], v[228:231], v[42:45]
	v_mfma_f32_16x16x32_bf16 v[46:49], v[208:211], v[232:235], v[46:49]
	v_mfma_f32_16x16x32_bf16 v[10:13], v[208:211], v[236:239], v[10:13]
	v_mfma_f32_16x16x32_bf16 v[14:17], v[208:211], v[240:243], v[14:17]
	ds_read_b128 v[208:211], v244 offset:6912
	s_waitcnt lgkmcnt(6)
	v_mfma_f32_16x16x32_bf16 v[50:53], v[196:199], v[212:215], v[50:53]
	ds_read_b128 v[228:231], v245 offset:36928
	s_waitcnt lgkmcnt(6)
	v_mfma_f32_16x16x32_bf16 v[54:57], v[196:199], v[216:219], v[54:57]
	ds_read_b128 v[232:235], v245 offset:39232
	s_waitcnt lgkmcnt(6)
	v_mfma_f32_16x16x32_bf16 v[18:21], v[196:199], v[220:223], v[18:21]
	ds_read_b128 v[236:239], v245 offset:41536
	s_waitcnt lgkmcnt(6)
	v_mfma_f32_16x16x32_bf16 v[22:25], v[196:199], v[224:227], v[22:25]
	ds_read_b128 v[240:243], v245 offset:43840
	ds_read_b128 v[196:199], v244 offset:64
	s_waitcnt lgkmcnt(7)
	v_mfma_f32_16x16x32_bf16 v[58:61], v[200:203], v[212:215], v[58:61]
	v_mfma_f32_16x16x32_bf16 v[62:65], v[200:203], v[216:219], v[62:65]
	v_mfma_f32_16x16x32_bf16 v[26:29], v[200:203], v[220:223], v[26:29]
	v_mfma_f32_16x16x32_bf16 v[30:33], v[200:203], v[224:227], v[30:33]
	ds_read_b128 v[200:203], v244 offset:2368
	s_waitcnt lgkmcnt(7)
	v_mfma_f32_16x16x32_bf16 v[34:37], v[204:207], v[212:215], v[34:37]
	v_mfma_f32_16x16x32_bf16 v[38:41], v[204:207], v[216:219], v[38:41]
	v_mfma_f32_16x16x32_bf16 v[2:5], v[204:207], v[220:223], v[2:5]
	v_mfma_f32_16x16x32_bf16 v[6:9], v[204:207], v[224:227], v[6:9]
	ds_read_b128 v[204:207], v244 offset:4672
	s_setprio 1
	s_waitcnt vmcnt(7)
	ds_write_b128 v98, v[102:105] offset:18432
	s_waitcnt vmcnt(6)
	ds_write_b128 v98, v[74:77] offset:23040
	s_waitcnt lgkmcnt(9)
	v_mfma_f32_16x16x32_bf16 v[42:45], v[208:211], v[212:215], v[42:45]
	v_mfma_f32_16x16x32_bf16 v[46:49], v[208:211], v[216:219], v[46:49]
	v_mfma_f32_16x16x32_bf16 v[10:13], v[208:211], v[220:223], v[10:13]
	v_mfma_f32_16x16x32_bf16 v[14:17], v[208:211], v[224:227], v[14:17]
	ds_read_b128 v[208:211], v244 offset:6976
	s_waitcnt vmcnt(5)
	ds_write_b128 v98, v[106:109] offset:27648
	s_waitcnt vmcnt(4)
	ds_write_b128 v98, v[78:81] offset:32256
	s_waitcnt lgkmcnt(7)
	v_mfma_f32_16x16x32_bf16 v[50:53], v[196:199], v[228:231], v[50:53]
	v_mfma_f32_16x16x32_bf16 v[54:57], v[196:199], v[232:235], v[54:57]
	v_mfma_f32_16x16x32_bf16 v[18:21], v[196:199], v[236:239], v[18:21]
	v_mfma_f32_16x16x32_bf16 v[22:25], v[196:199], v[240:243], v[22:25]
	s_waitcnt vmcnt(3)
	ds_write_b128 v98, v[110:113] offset:55296
	s_waitcnt vmcnt(2)
	ds_write_b128 v98, v[82:85] offset:59904
	s_waitcnt lgkmcnt(8)
	v_mfma_f32_16x16x32_bf16 v[58:61], v[200:203], v[228:231], v[58:61]
	v_mfma_f32_16x16x32_bf16 v[62:65], v[200:203], v[232:235], v[62:65]
	v_mfma_f32_16x16x32_bf16 v[26:29], v[200:203], v[236:239], v[26:29]
	v_mfma_f32_16x16x32_bf16 v[30:33], v[200:203], v[240:243], v[30:33]
	s_waitcnt vmcnt(1)
	ds_write_b128 v98, v[114:117] offset:64512
	s_waitcnt vmcnt(0)
	ds_write_b128 v99, v[86:89] offset:32256
	s_waitcnt lgkmcnt(0)
	s_barrier
	s_setprio 0
	ds_read_b128 v[212:215], v245 offset:55296
	ds_read_b128 v[196:199], v244 offset:18432
	ds_read_b128 v[216:219], v245 offset:57600
	ds_read_b128 v[220:223], v245 offset:59904
	ds_read_b128 v[224:227], v245 offset:62208
	ds_read_b128 v[200:203], v244 offset:20736
	v_mfma_f32_16x16x32_bf16 v[34:37], v[204:207], v[228:231], v[34:37]
	v_mfma_f32_16x16x32_bf16 v[38:41], v[204:207], v[232:235], v[38:41]
	v_mfma_f32_16x16x32_bf16 v[2:5], v[204:207], v[236:239], v[2:5]
	v_mfma_f32_16x16x32_bf16 v[6:9], v[204:207], v[240:243], v[6:9]
	ds_read_b128 v[204:207], v244 offset:23040
	v_mfma_f32_16x16x32_bf16 v[42:45], v[208:211], v[228:231], v[42:45]
	v_mfma_f32_16x16x32_bf16 v[46:49], v[208:211], v[232:235], v[46:49]
	v_mfma_f32_16x16x32_bf16 v[10:13], v[208:211], v[236:239], v[10:13]
	v_mfma_f32_16x16x32_bf16 v[14:17], v[208:211], v[240:243], v[14:17]
	ds_read_b128 v[208:211], v244 offset:25344
	s_waitcnt lgkmcnt(6)
	v_mfma_f32_16x16x32_bf16 v[50:53], v[196:199], v[212:215], v[50:53]
	ds_read_b128 v[228:231], v245 offset:55360
	s_waitcnt lgkmcnt(6)
	v_mfma_f32_16x16x32_bf16 v[54:57], v[196:199], v[216:219], v[54:57]
	ds_read_b128 v[232:235], v245 offset:57664
	s_waitcnt lgkmcnt(6)
	v_mfma_f32_16x16x32_bf16 v[18:21], v[196:199], v[220:223], v[18:21]
	ds_read_b128 v[236:239], v245 offset:59968
	s_waitcnt lgkmcnt(6)
	v_mfma_f32_16x16x32_bf16 v[22:25], v[196:199], v[224:227], v[22:25]
	ds_read_b128 v[240:243], v245 offset:62272
	ds_read_b128 v[196:199], v244 offset:18496
	s_waitcnt lgkmcnt(7)
	v_mfma_f32_16x16x32_bf16 v[58:61], v[200:203], v[212:215], v[58:61]
	v_mfma_f32_16x16x32_bf16 v[62:65], v[200:203], v[216:219], v[62:65]
	v_mfma_f32_16x16x32_bf16 v[26:29], v[200:203], v[220:223], v[26:29]
	v_mfma_f32_16x16x32_bf16 v[30:33], v[200:203], v[224:227], v[30:33]
	ds_read_b128 v[200:203], v244 offset:20800
	s_waitcnt lgkmcnt(7)
	v_mfma_f32_16x16x32_bf16 v[34:37], v[204:207], v[212:215], v[34:37]
	v_mfma_f32_16x16x32_bf16 v[38:41], v[204:207], v[216:219], v[38:41]
	v_mfma_f32_16x16x32_bf16 v[2:5], v[204:207], v[220:223], v[2:5]
	v_mfma_f32_16x16x32_bf16 v[6:9], v[204:207], v[224:227], v[6:9]
	ds_read_b128 v[204:207], v244 offset:23104
	s_waitcnt lgkmcnt(7)
	v_mfma_f32_16x16x32_bf16 v[42:45], v[208:211], v[212:215], v[42:45]
	v_mfma_f32_16x16x32_bf16 v[46:49], v[208:211], v[216:219], v[46:49]
	v_mfma_f32_16x16x32_bf16 v[10:13], v[208:211], v[220:223], v[10:13]
	v_mfma_f32_16x16x32_bf16 v[14:17], v[208:211], v[224:227], v[14:17]
	ds_read_b128 v[208:211], v244 offset:25408
	s_waitcnt lgkmcnt(3)
	v_mfma_f32_16x16x32_bf16 v[50:53], v[196:199], v[228:231], v[50:53]
	v_mfma_f32_16x16x32_bf16 v[54:57], v[196:199], v[232:235], v[54:57]
	v_mfma_f32_16x16x32_bf16 v[18:21], v[196:199], v[236:239], v[18:21]
	v_mfma_f32_16x16x32_bf16 v[22:25], v[196:199], v[240:243], v[22:25]
	s_waitcnt lgkmcnt(2)
	v_mfma_f32_16x16x32_bf16 v[58:61], v[200:203], v[228:231], v[58:61]
	v_mfma_f32_16x16x32_bf16 v[62:65], v[200:203], v[232:235], v[62:65]
	v_mfma_f32_16x16x32_bf16 v[26:29], v[200:203], v[236:239], v[26:29]
	v_mfma_f32_16x16x32_bf16 v[30:33], v[200:203], v[240:243], v[30:33]
	s_lshr_b32 s14, s2, 3
	s_bfe_u32 s13, s2, 0x10002
	s_cmp_lt_i32 s14, 1
	s_mov_b64 s[2:3], -1
	s_waitcnt lgkmcnt(0)
	s_barrier
	v_mfma_f32_16x16x32_bf16 v[34:37], v[204:207], v[228:231], v[34:37]
	v_mfma_f32_16x16x32_bf16 v[38:41], v[204:207], v[232:235], v[38:41]
	v_mfma_f32_16x16x32_bf16 v[2:5], v[204:207], v[236:239], v[2:5]
	v_mfma_f32_16x16x32_bf16 v[6:9], v[204:207], v[240:243], v[6:9]
	v_mfma_f32_16x16x32_bf16 v[42:45], v[208:211], v[228:231], v[42:45]
	v_mfma_f32_16x16x32_bf16 v[46:49], v[208:211], v[232:235], v[46:49]
	v_mfma_f32_16x16x32_bf16 v[10:13], v[208:211], v[236:239], v[10:13]
	v_mfma_f32_16x16x32_bf16 v[14:17], v[208:211], v[240:243], v[14:17]
	s_nop 7
	v_permlane16_swap_b32_e32 v50, v54
	v_permlane16_swap_b32_e32 v51, v55
	v_permlane16_swap_b32_e32 v52, v56
	v_permlane16_swap_b32_e32 v53, v57
	v_permlane16_swap_b32_e32 v58, v62
	v_permlane16_swap_b32_e32 v59, v63
	v_permlane16_swap_b32_e32 v60, v64
	v_permlane16_swap_b32_e32 v61, v65
	v_permlane16_swap_b32_e32 v18, v22
	v_permlane16_swap_b32_e32 v19, v23
	v_permlane16_swap_b32_e32 v20, v24
	v_permlane16_swap_b32_e32 v21, v25
	v_permlane16_swap_b32_e32 v26, v30
	v_permlane16_swap_b32_e32 v27, v31
	v_permlane16_swap_b32_e32 v28, v32
	v_permlane16_swap_b32_e32 v29, v33
	v_permlane16_swap_b32_e32 v34, v38
	v_permlane16_swap_b32_e32 v35, v39
	v_permlane16_swap_b32_e32 v36, v40
	v_permlane16_swap_b32_e32 v37, v41
	v_permlane16_swap_b32_e32 v42, v46
	v_permlane16_swap_b32_e32 v43, v47
	v_permlane16_swap_b32_e32 v44, v48
	v_permlane16_swap_b32_e32 v45, v49
	v_permlane16_swap_b32_e32 v2, v6
	v_permlane16_swap_b32_e32 v3, v7
	v_permlane16_swap_b32_e32 v4, v8
	v_permlane16_swap_b32_e32 v5, v9
	v_permlane16_swap_b32_e32 v10, v14
	v_permlane16_swap_b32_e32 v11, v15
	v_permlane16_swap_b32_e32 v12, v16
	v_permlane16_swap_b32_e32 v13, v17
	v_permlane32_swap_b32_e32 v50, v54
	v_permlane32_swap_b32_e32 v51, v55
	v_permlane32_swap_b32_e32 v52, v56
	v_permlane32_swap_b32_e32 v53, v57
	v_permlane32_swap_b32_e32 v58, v62
	v_permlane32_swap_b32_e32 v59, v63
	v_permlane32_swap_b32_e32 v60, v64
	v_permlane32_swap_b32_e32 v61, v65
	v_permlane32_swap_b32_e32 v18, v22
	v_permlane32_swap_b32_e32 v19, v23
	v_permlane32_swap_b32_e32 v20, v24
	v_permlane32_swap_b32_e32 v21, v25
	v_permlane32_swap_b32_e32 v26, v30
	v_permlane32_swap_b32_e32 v27, v31
	v_permlane32_swap_b32_e32 v28, v32
	v_permlane32_swap_b32_e32 v29, v33
	v_permlane32_swap_b32_e32 v34, v38
	v_permlane32_swap_b32_e32 v35, v39
	v_permlane32_swap_b32_e32 v36, v40
	v_permlane32_swap_b32_e32 v37, v41
	v_permlane32_swap_b32_e32 v42, v46
	v_permlane32_swap_b32_e32 v43, v47
	v_permlane32_swap_b32_e32 v44, v48
	v_permlane32_swap_b32_e32 v45, v49
	v_permlane32_swap_b32_e32 v2, v6
	v_permlane32_swap_b32_e32 v3, v7
	v_permlane32_swap_b32_e32 v4, v8
	v_permlane32_swap_b32_e32 v5, v9
	v_permlane32_swap_b32_e32 v10, v14
	v_permlane32_swap_b32_e32 v11, v15
	v_permlane32_swap_b32_e32 v12, v16
	v_permlane32_swap_b32_e32 v13, v17
	s_cbranch_scc1 .LBB0_1647
	s_and_b32 s2, 0xffff, s14
	s_cmp_lg_u32 s2, 1
	s_mov_b64 s[2:3], -1
	s_cbranch_scc0 .LBB0_1644
	s_cmp_eq_u32 s13, 0
	s_cselect_b32 s12, 3, 10
	s_mov_b64 s[2:3], 0

.LBB0_1720:
	s_lshr_b32 s8, s0, 2
	s_lshl_b32 s0, s0, 7
	s_and_b32 s7, s0, 0x180
	v_or_b32_e32 v2, s7, v93
	v_lshlrev_b32_e32 v74, 10, v2
	s_add_i32 s8, s8, s4
	v_lshl_add_u64 v[66:67], v[76:77], 0, v[74:75]
	v_add_lshl_u32 v74, s7, v94, 10
	s_lshl_b32 s0, s8, 7
	v_lshl_add_u64 v[68:69], v[76:77], 0, v[74:75]
	v_add_lshl_u32 v74, s7, v95, 10
	v_lshl_add_u64 v[70:71], v[76:77], 0, v[74:75]
	v_add_lshl_u32 v74, s7, v96, 10
	v_or_b32_e32 v2, s0, v93
	v_lshl_add_u64 v[72:73], v[76:77], 0, v[74:75]
	v_lshlrev_b32_e32 v74, 10, v2
	v_lshl_add_u64 v[84:85], v[78:79], 0, v[74:75]
	v_add_lshl_u32 v74, s0, v94, 10
	v_lshl_add_u64 v[86:87], v[78:79], 0, v[74:75]
	v_add_lshl_u32 v74, s0, v95, 10
	v_lshl_add_u64 v[88:89], v[78:79], 0, v[74:75]
	v_add_lshl_u32 v74, s0, v96, 10
	v_lshl_add_u64 v[90:91], v[78:79], 0, v[74:75]
	global_load_dwordx4 v[2:5], v[66:67], off
	global_load_dwordx4 v[6:9], v[68:69], off
	global_load_dwordx4 v[10:13], v[70:71], off
	global_load_dwordx4 v[14:17], v[72:73], off
	global_load_dwordx4 v[18:21], v[84:85], off
	global_load_dwordx4 v[22:25], v[86:87], off
	global_load_dwordx4 v[26:29], v[88:89], off
	global_load_dwordx4 v[30:33], v[90:91], off
	global_load_dwordx4 v[102:105], v[66:67], off offset:128
	global_load_dwordx4 v[106:109], v[68:69], off offset:128
	global_load_dwordx4 v[110:113], v[70:71], off offset:128
	global_load_dwordx4 v[114:117], v[72:73], off offset:128
	global_load_dwordx4 v[118:121], v[84:85], off offset:128
	global_load_dwordx4 v[122:125], v[86:87], off offset:128
	global_load_dwordx4 v[126:129], v[88:89], off offset:128
	global_load_dwordx4 v[132:135], v[90:91], off offset:128
	s_waitcnt vmcnt(15)
	ds_write_b128 v100, v[2:5]
	s_waitcnt vmcnt(14)
	ds_write_b128 v100, v[6:9] offset:4608
	s_waitcnt vmcnt(13)
	ds_write_b128 v100, v[10:13] offset:9216
	s_waitcnt vmcnt(12)
	ds_write_b128 v100, v[14:17] offset:13824
	s_waitcnt vmcnt(11)
	ds_write_b128 v100, v[18:21] offset:36864
	s_waitcnt vmcnt(10)
	ds_write_b128 v100, v[22:25] offset:41472
	s_waitcnt vmcnt(9)
	ds_write_b128 v100, v[26:29] offset:46080
	s_waitcnt vmcnt(8)
	ds_write_b128 v100, v[30:33] offset:50688
	s_waitcnt lgkmcnt(0)
	s_barrier
	global_load_dwordx4 v[136:139], v[66:67], off offset:256
	global_load_dwordx4 v[140:143], v[68:69], off offset:256
	global_load_dwordx4 v[144:147], v[70:71], off offset:256
	global_load_dwordx4 v[148:151], v[72:73], off offset:256
	global_load_dwordx4 v[152:155], v[84:85], off offset:256
	global_load_dwordx4 v[156:159], v[86:87], off offset:256
	global_load_dwordx4 v[160:163], v[88:89], off offset:256
	global_load_dwordx4 v[164:167], v[90:91], off offset:256
	v_and_b32_e32 v246, 15, v1
	v_add_u32_e32 v246, 4, v246
	v_bfe_u32 v246, v246, 3, 1
	v_bfe_u32 v249, v1, 4, 2
	v_xor_b32_e32 v246, v246, v249
	v_bfe_u32 v249, v1, 5, 1
	v_sub_u32_e32 v246, v246, v249
	v_lshlrev_b32_e32 v246, 4, v246
	v_bfe_u32 v249, v1, 4, 1
	v_mul_u32_u24_e32 v249, 0x900, v249
	v_sub_u32_e32 v246, v246, v249
	v_add_u32_e32 v244, v246, v98
	v_add_u32_e32 v245, v246, v99
	ds_read_b128 v[212:215], v245 offset:36864
	ds_read_b128 v[196:199], v244
	ds_read_b128 v[216:219], v245 offset:39168
	ds_read_b128 v[220:223], v245 offset:41472
	ds_read_b128 v[224:227], v245 offset:43776
	ds_read_b128 v[200:203], v244 offset:2304
	ds_read_b128 v[204:207], v244 offset:4608
	ds_read_b128 v[208:211], v244 offset:6912
	s_waitcnt lgkmcnt(6)
	v_mfma_f32_16x16x32_bf16 v[50:53], v[196:199], v[212:215], 0
	ds_read_b128 v[228:231], v245 offset:36928
	s_waitcnt lgkmcnt(6)
	v_mfma_f32_16x16x32_bf16 v[54:57], v[196:199], v[216:219], 0
	ds_read_b128 v[232:235], v245 offset:39232
	s_waitcnt lgkmcnt(6)
	v_mfma_f32_16x16x32_bf16 v[18:21], v[196:199], v[220:223], 0
	ds_read_b128 v[236:239], v245 offset:41536
	s_waitcnt lgkmcnt(6)
	v_mfma_f32_16x16x32_bf16 v[22:25], v[196:199], v[224:227], 0
	ds_read_b128 v[240:243], v245 offset:43840
	ds_read_b128 v[196:199], v244 offset:64
	s_waitcnt lgkmcnt(7)
	v_mfma_f32_16x16x32_bf16 v[58:61], v[200:203], v[212:215], 0
	v_mfma_f32_16x16x32_bf16 v[62:65], v[200:203], v[216:219], 0
	v_mfma_f32_16x16x32_bf16 v[26:29], v[200:203], v[220:223], 0
	v_mfma_f32_16x16x32_bf16 v[30:33], v[200:203], v[224:227], 0
	ds_read_b128 v[200:203], v244 offset:2368
	s_waitcnt lgkmcnt(7)
	v_mfma_f32_16x16x32_bf16 v[34:37], v[204:207], v[212:215], 0
	v_mfma_f32_16x16x32_bf16 v[38:41], v[204:207], v[216:219], 0
	v_mfma_f32_16x16x32_bf16 v[2:5], v[204:207], v[220:223], 0
	v_mfma_f32_16x16x32_bf16 v[6:9], v[204:207], v[224:227], 0
	ds_read_b128 v[204:207], v244 offset:4672
	s_setprio 1
	s_waitcnt vmcnt(15)
	ds_write_b128 v100, v[102:105] offset:18432
	s_waitcnt vmcnt(14)
	ds_write_b128 v100, v[106:109] offset:23040
	s_waitcnt lgkmcnt(9)
	v_mfma_f32_16x16x32_bf16 v[42:45], v[208:211], v[212:215], 0
	v_mfma_f32_16x16x32_bf16 v[46:49], v[208:211], v[216:219], 0
	v_mfma_f32_16x16x32_bf16 v[10:13], v[208:211], v[220:223], 0
	v_mfma_f32_16x16x32_bf16 v[14:17], v[208:211], v[224:227], 0
	ds_read_b128 v[208:211], v244 offset:6976
	s_waitcnt vmcnt(13)
	ds_write_b128 v100, v[110:113] offset:27648
	s_waitcnt vmcnt(12)
	ds_write_b128 v100, v[114:117] offset:32256
	s_waitcnt lgkmcnt(7)
	v_mfma_f32_16x16x32_bf16 v[50:53], v[196:199], v[228:231], v[50:53]
	v_mfma_f32_16x16x32_bf16 v[54:57], v[196:199], v[232:235], v[54:57]
	v_mfma_f32_16x16x32_bf16 v[18:21], v[196:199], v[236:239], v[18:21]
	v_mfma_f32_16x16x32_bf16 v[22:25], v[196:199], v[240:243], v[22:25]
	s_waitcnt vmcnt(11)
	ds_write_b128 v100, v[118:121] offset:55296
	s_waitcnt vmcnt(10)
	ds_write_b128 v100, v[122:125] offset:59904
	s_waitcnt lgkmcnt(8)
	v_mfma_f32_16x16x32_bf16 v[58:61], v[200:203], v[228:231], v[58:61]
	v_mfma_f32_16x16x32_bf16 v[62:65], v[200:203], v[232:235], v[62:65]
	v_mfma_f32_16x16x32_bf16 v[26:29], v[200:203], v[236:239], v[26:29]
	v_mfma_f32_16x16x32_bf16 v[30:33], v[200:203], v[240:243], v[30:33]
	s_waitcnt vmcnt(9)
	ds_write_b128 v100, v[126:129] offset:64512
	s_waitcnt vmcnt(8)
	ds_write_b128 v101, v[132:135] offset:32256
	s_waitcnt lgkmcnt(0)
	s_barrier
	s_setprio 0
	ds_read_b128 v[212:215], v245 offset:55296
	ds_read_b128 v[196:199], v244 offset:18432
	ds_read_b128 v[216:219], v245 offset:57600
	ds_read_b128 v[220:223], v245 offset:59904
	ds_read_b128 v[224:227], v245 offset:62208
	ds_read_b128 v[200:203], v244 offset:20736
	v_mfma_f32_16x16x32_bf16 v[34:37], v[204:207], v[228:231], v[34:37]
	v_mfma_f32_16x16x32_bf16 v[38:41], v[204:207], v[232:235], v[38:41]
	v_mfma_f32_16x16x32_bf16 v[2:5], v[204:207], v[236:239], v[2:5]
	v_mfma_f32_16x16x32_bf16 v[6:9], v[204:207], v[240:243], v[6:9]
	ds_read_b128 v[204:207], v244 offset:23040
	v_mfma_f32_16x16x32_bf16 v[42:45], v[208:211], v[228:231], v[42:45]
	v_mfma_f32_16x16x32_bf16 v[46:49], v[208:211], v[232:235], v[46:49]
	v_mfma_f32_16x16x32_bf16 v[10:13], v[208:211], v[236:239], v[10:13]
	v_mfma_f32_16x16x32_bf16 v[14:17], v[208:211], v[240:243], v[14:17]
	ds_read_b128 v[208:211], v244 offset:25344
	global_load_dwordx4 v[102:105], v[66:67], off offset:384
	global_load_dwordx4 v[106:109], v[68:69], off offset:384
	global_load_dwordx4 v[110:113], v[70:71], off offset:384
	global_load_dwordx4 v[114:117], v[72:73], off offset:384
	global_load_dwordx4 v[118:121], v[84:85], off offset:384
	global_load_dwordx4 v[122:125], v[86:87], off offset:384
	global_load_dwordx4 v[126:129], v[88:89], off offset:384
	global_load_dwordx4 v[132:135], v[90:91], off offset:384
	s_waitcnt lgkmcnt(6)
	v_mfma_f32_16x16x32_bf16 v[50:53], v[196:199], v[212:215], v[50:53]
	ds_read_b128 v[228:231], v245 offset:55360
	s_waitcnt lgkmcnt(6)
	v_mfma_f32_16x16x32_bf16 v[54:57], v[196:199], v[216:219], v[54:57]
	ds_read_b128 v[232:235], v245 offset:57664
	s_waitcnt lgkmcnt(6)
	v_mfma_f32_16x16x32_bf16 v[18:21], v[196:199], v[220:223], v[18:21]
	ds_read_b128 v[236:239], v245 offset:59968
	s_waitcnt lgkmcnt(6)
	v_mfma_f32_16x16x32_bf16 v[22:25], v[196:199], v[224:227], v[22:25]
	ds_read_b128 v[240:243], v245 offset:62272
	ds_read_b128 v[196:199], v244 offset:18496
	s_waitcnt lgkmcnt(7)
	v_mfma_f32_16x16x32_bf16 v[58:61], v[200:203], v[212:215], v[58:61]
	v_mfma_f32_16x16x32_bf16 v[62:65], v[200:203], v[216:219], v[62:65]
	v_mfma_f32_16x16x32_bf16 v[26:29], v[200:203], v[220:223], v[26:29]
	v_mfma_f32_16x16x32_bf16 v[30:33], v[200:203], v[224:227], v[30:33]
	ds_read_b128 v[200:203], v244 offset:20800
	s_waitcnt lgkmcnt(7)
	v_mfma_f32_16x16x32_bf16 v[34:37], v[204:207], v[212:215], v[34:37]
	v_mfma_f32_16x16x32_bf16 v[38:41], v[204:207], v[216:219], v[38:41]
	v_mfma_f32_16x16x32_bf16 v[2:5], v[204:207], v[220:223], v[2:5]
	v_mfma_f32_16x16x32_bf16 v[6:9], v[204:207], v[224:227], v[6:9]
	ds_read_b128 v[204:207], v244 offset:23104
	s_setprio 1
	s_waitcnt vmcnt(15)
	ds_write_b128 v100, v[136:139]
	s_waitcnt vmcnt(14)
	ds_write_b128 v100, v[140:143] offset:4608
	s_waitcnt lgkmcnt(9)
	v_mfma_f32_16x16x32_bf16 v[42:45], v[208:211], v[212:215], v[42:45]
	v_mfma_f32_16x16x32_bf16 v[46:49], v[208:211], v[216:219], v[46:49]
	v_mfma_f32_16x16x32_bf16 v[10:13], v[208:211], v[220:223], v[10:13]
	v_mfma_f32_16x16x32_bf16 v[14:17], v[208:211], v[224:227], v[14:17]
	ds_read_b128 v[208:211], v244 offset:25408
	s_waitcnt vmcnt(13)
	ds_write_b128 v100, v[144:147] offset:9216
	s_waitcnt vmcnt(12)
	ds_write_b128 v100, v[148:151] offset:13824
	s_waitcnt lgkmcnt(7)
	v_mfma_f32_16x16x32_bf16 v[50:53], v[196:199], v[228:231], v[50:53]
	v_mfma_f32_16x16x32_bf16 v[54:57], v[196:199], v[232:235], v[54:57]
	v_mfma_f32_16x16x32_bf16 v[18:21], v[196:199], v[236:239], v[18:21]
	v_mfma_f32_16x16x32_bf16 v[22:25], v[196:199], v[240:243], v[22:25]
	s_waitcnt vmcnt(11)
	ds_write_b128 v100, v[152:155] offset:36864
	s_waitcnt vmcnt(10)
	ds_write_b128 v100, v[156:159] offset:41472
	s_waitcnt lgkmcnt(8)
	v_mfma_f32_16x16x32_bf16 v[58:61], v[200:203], v[228:231], v[58:61]
	v_mfma_f32_16x16x32_bf16 v[62:65], v[200:203], v[232:235], v[62:65]
	v_mfma_f32_16x16x32_bf16 v[26:29], v[200:203], v[236:239], v[26:29]
	v_mfma_f32_16x16x32_bf16 v[30:33], v[200:203], v[240:243], v[30:33]
	s_waitcnt vmcnt(9)
	ds_write_b128 v100, v[160:163] offset:46080
	s_waitcnt vmcnt(8)
	ds_write_b128 v100, v[164:167] offset:50688
	s_waitcnt lgkmcnt(0)
	s_barrier
	s_setprio 0
	ds_read_b128 v[212:215], v245 offset:36864
	ds_read_b128 v[196:199], v244
	ds_read_b128 v[216:219], v245 offset:39168
	ds_read_b128 v[220:223], v245 offset:41472
	ds_read_b128 v[224:227], v245 offset:43776
	ds_read_b128 v[200:203], v244 offset:2304
	v_mfma_f32_16x16x32_bf16 v[34:37], v[204:207], v[228:231], v[34:37]
	v_mfma_f32_16x16x32_bf16 v[38:41], v[204:207], v[232:235], v[38:41]
	v_mfma_f32_16x16x32_bf16 v[2:5], v[204:207], v[236:239], v[2:5]
	v_mfma_f32_16x16x32_bf16 v[6:9], v[204:207], v[240:243], v[6:9]
	ds_read_b128 v[204:207], v244 offset:4608
	v_mfma_f32_16x16x32_bf16 v[42:45], v[208:211], v[228:231], v[42:45]
	v_mfma_f32_16x16x32_bf16 v[46:49], v[208:211], v[232:235], v[46:49]
	v_mfma_f32_16x16x32_bf16 v[10:13], v[208:211], v[236:239], v[10:13]
	v_mfma_f32_16x16x32_bf16 v[14:17], v[208:211], v[240:243], v[14:17]
	ds_read_b128 v[208:211], v244 offset:6912
	global_load_dwordx4 v[136:139], v[66:67], off offset:512
	global_load_dwordx4 v[140:143], v[68:69], off offset:512
	global_load_dwordx4 v[144:147], v[70:71], off offset:512
	global_load_dwordx4 v[148:151], v[72:73], off offset:512
	global_load_dwordx4 v[152:155], v[84:85], off offset:512
	global_load_dwordx4 v[156:159], v[86:87], off offset:512
	global_load_dwordx4 v[160:163], v[88:89], off offset:512
	global_load_dwordx4 v[164:167], v[90:91], off offset:512
	s_waitcnt lgkmcnt(6)
	v_mfma_f32_16x16x32_bf16 v[50:53], v[196:199], v[212:215], v[50:53]
	ds_read_b128 v[228:231], v245 offset:36928
	s_waitcnt lgkmcnt(6)
	v_mfma_f32_16x16x32_bf16 v[54:57], v[196:199], v[216:219], v[54:57]
	ds_read_b128 v[232:235], v245 offset:39232
	s_waitcnt lgkmcnt(6)
	v_mfma_f32_16x16x32_bf16 v[18:21], v[196:199], v[220:223], v[18:21]
	ds_read_b128 v[236:239], v245 offset:41536
	s_waitcnt lgkmcnt(6)
	v_mfma_f32_16x16x32_bf16 v[22:25], v[196:199], v[224:227], v[22:25]
	ds_read_b128 v[240:243], v245 offset:43840
	ds_read_b128 v[196:199], v244 offset:64
	s_waitcnt lgkmcnt(7)
	v_mfma_f32_16x16x32_bf16 v[58:61], v[200:203], v[212:215], v[58:61]
	v_mfma_f32_16x16x32_bf16 v[62:65], v[200:203], v[216:219], v[62:65]
	v_mfma_f32_16x16x32_bf16 v[26:29], v[200:203], v[220:223], v[26:29]
	v_mfma_f32_16x16x32_bf16 v[30:33], v[200:203], v[224:227], v[30:33]
	ds_read_b128 v[200:203], v244 offset:2368
	s_waitcnt lgkmcnt(7)
	v_mfma_f32_16x16x32_bf16 v[34:37], v[204:207], v[212:215], v[34:37]
	v_mfma_f32_16x16x32_bf16 v[38:41], v[204:207], v[216:219], v[38:41]
	v_mfma_f32_16x16x32_bf16 v[2:5], v[204:207], v[220:223], v[2:5]
	v_mfma_f32_16x16x32_bf16 v[6:9], v[204:207], v[224:227], v[6:9]
	ds_read_b128 v[204:207], v244 offset:4672
	s_setprio 1
	s_waitcnt vmcnt(15)
	ds_write_b128 v100, v[102:105] offset:18432
	s_waitcnt vmcnt(14)
	ds_write_b128 v100, v[106:109] offset:23040
	s_waitcnt lgkmcnt(9)
	v_mfma_f32_16x16x32_bf16 v[42:45], v[208:211], v[212:215], v[42:45]
	v_mfma_f32_16x16x32_bf16 v[46:49], v[208:211], v[216:219], v[46:49]
	v_mfma_f32_16x16x32_bf16 v[10:13], v[208:211], v[220:223], v[10:13]
	v_mfma_f32_16x16x32_bf16 v[14:17], v[208:211], v[224:227], v[14:17]
	ds_read_b128 v[208:211], v244 offset:6976
	s_waitcnt vmcnt(13)
	ds_write_b128 v100, v[110:113] offset:27648
	s_waitcnt vmcnt(12)
	ds_write_b128 v100, v[114:117] offset:32256
	s_waitcnt lgkmcnt(7)
	v_mfma_f32_16x16x32_bf16 v[50:53], v[196:199], v[228:231], v[50:53]
	v_mfma_f32_16x16x32_bf16 v[54:57], v[196:199], v[232:235], v[54:57]
	v_mfma_f32_16x16x32_bf16 v[18:21], v[196:199], v[236:239], v[18:21]
	v_mfma_f32_16x16x32_bf16 v[22:25], v[196:199], v[240:243], v[22:25]
	s_waitcnt vmcnt(11)
	ds_write_b128 v100, v[118:121] offset:55296
	s_waitcnt vmcnt(10)
	ds_write_b128 v100, v[122:125] offset:59904
	s_waitcnt lgkmcnt(8)
	v_mfma_f32_16x16x32_bf16 v[58:61], v[200:203], v[228:231], v[58:61]
	v_mfma_f32_16x16x32_bf16 v[62:65], v[200:203], v[232:235], v[62:65]
	v_mfma_f32_16x16x32_bf16 v[26:29], v[200:203], v[236:239], v[26:29]
	v_mfma_f32_16x16x32_bf16 v[30:33], v[200:203], v[240:243], v[30:33]
	s_waitcnt vmcnt(9)
	ds_write_b128 v100, v[126:129] offset:64512
	s_waitcnt vmcnt(8)
	ds_write_b128 v101, v[132:135] offset:32256
	s_waitcnt lgkmcnt(0)
	s_barrier
	s_setprio 0
	ds_read_b128 v[212:215], v245 offset:55296
	ds_read_b128 v[196:199], v244 offset:18432
	ds_read_b128 v[216:219], v245 offset:57600
	ds_read_b128 v[220:223], v245 offset:59904
	ds_read_b128 v[224:227], v245 offset:62208
	ds_read_b128 v[200:203], v244 offset:20736
	v_mfma_f32_16x16x32_bf16 v[34:37], v[204:207], v[228:231], v[34:37]
	v_mfma_f32_16x16x32_bf16 v[38:41], v[204:207], v[232:235], v[38:41]
	v_mfma_f32_16x16x32_bf16 v[2:5], v[204:207], v[236:239], v[2:5]
	v_mfma_f32_16x16x32_bf16 v[6:9], v[204:207], v[240:243], v[6:9]
	ds_read_b128 v[204:207], v244 offset:23040
	v_mfma_f32_16x16x32_bf16 v[42:45], v[208:211], v[228:231], v[42:45]
	v_mfma_f32_16x16x32_bf16 v[46:49], v[208:211], v[232:235], v[46:49]
	v_mfma_f32_16x16x32_bf16 v[10:13], v[208:211], v[236:239], v[10:13]
	v_mfma_f32_16x16x32_bf16 v[14:17], v[208:211], v[240:243], v[14:17]
	ds_read_b128 v[208:211], v244 offset:25344
	global_load_dwordx4 v[102:105], v[66:67], off offset:640
	global_load_dwordx4 v[106:109], v[68:69], off offset:640
	global_load_dwordx4 v[110:113], v[70:71], off offset:640
	global_load_dwordx4 v[114:117], v[72:73], off offset:640
	global_load_dwordx4 v[118:121], v[84:85], off offset:640
	global_load_dwordx4 v[122:125], v[86:87], off offset:640
	global_load_dwordx4 v[126:129], v[88:89], off offset:640
	global_load_dwordx4 v[132:135], v[90:91], off offset:640
	s_waitcnt lgkmcnt(6)
	v_mfma_f32_16x16x32_bf16 v[50:53], v[196:199], v[212:215], v[50:53]
	ds_read_b128 v[228:231], v245 offset:55360
	s_waitcnt lgkmcnt(6)
	v_mfma_f32_16x16x32_bf16 v[54:57], v[196:199], v[216:219], v[54:57]
	ds_read_b128 v[232:235], v245 offset:57664
	s_waitcnt lgkmcnt(6)
	v_mfma_f32_16x16x32_bf16 v[18:21], v[196:199], v[220:223], v[18:21]
	ds_read_b128 v[236:239], v245 offset:59968
	s_waitcnt lgkmcnt(6)
	v_mfma_f32_16x16x32_bf16 v[22:25], v[196:199], v[224:227], v[22:25]
	ds_read_b128 v[240:243], v245 offset:62272
	ds_read_b128 v[196:199], v244 offset:18496
	s_waitcnt lgkmcnt(7)
	v_mfma_f32_16x16x32_bf16 v[58:61], v[200:203], v[212:215], v[58:61]
	v_mfma_f32_16x16x32_bf16 v[62:65], v[200:203], v[216:219], v[62:65]
	v_mfma_f32_16x16x32_bf16 v[26:29], v[200:203], v[220:223], v[26:29]
	v_mfma_f32_16x16x32_bf16 v[30:33], v[200:203], v[224:227], v[30:33]
	ds_read_b128 v[200:203], v244 offset:20800
	s_waitcnt lgkmcnt(7)
	v_mfma_f32_16x16x32_bf16 v[34:37], v[204:207], v[212:215], v[34:37]
	v_mfma_f32_16x16x32_bf16 v[38:41], v[204:207], v[216:219], v[38:41]
	v_mfma_f32_16x16x32_bf16 v[2:5], v[204:207], v[220:223], v[2:5]
	v_mfma_f32_16x16x32_bf16 v[6:9], v[204:207], v[224:227], v[6:9]
	ds_read_b128 v[204:207], v244 offset:23104
	s_setprio 1
	s_waitcnt vmcnt(15)
	ds_write_b128 v100, v[136:139]
	s_waitcnt vmcnt(14)
	ds_write_b128 v100, v[140:143] offset:4608
	s_waitcnt lgkmcnt(9)
	v_mfma_f32_16x16x32_bf16 v[42:45], v[208:211], v[212:215], v[42:45]
	v_mfma_f32_16x16x32_bf16 v[46:49], v[208:211], v[216:219], v[46:49]
	v_mfma_f32_16x16x32_bf16 v[10:13], v[208:211], v[220:223], v[10:13]
	v_mfma_f32_16x16x32_bf16 v[14:17], v[208:211], v[224:227], v[14:17]
	ds_read_b128 v[208:211], v244 offset:25408
	s_waitcnt vmcnt(13)
	ds_write_b128 v100, v[144:147] offset:9216
	s_waitcnt vmcnt(12)
	ds_write_b128 v100, v[148:151] offset:13824
	s_waitcnt lgkmcnt(7)
	v_mfma_f32_16x16x32_bf16 v[50:53], v[196:199], v[228:231], v[50:53]
	v_mfma_f32_16x16x32_bf16 v[54:57], v[196:199], v[232:235], v[54:57]
	v_mfma_f32_16x16x32_bf16 v[18:21], v[196:199], v[236:239], v[18:21]
	v_mfma_f32_16x16x32_bf16 v[22:25], v[196:199], v[240:243], v[22:25]
	s_waitcnt vmcnt(11)
	ds_write_b128 v100, v[152:155] offset:36864
	s_waitcnt vmcnt(10)
	ds_write_b128 v100, v[156:159] offset:41472
	s_waitcnt lgkmcnt(8)
	v_mfma_f32_16x16x32_bf16 v[58:61], v[200:203], v[228:231], v[58:61]
	v_mfma_f32_16x16x32_bf16 v[62:65], v[200:203], v[232:235], v[62:65]
	v_mfma_f32_16x16x32_bf16 v[26:29], v[200:203], v[236:239], v[26:29]
	v_mfma_f32_16x16x32_bf16 v[30:33], v[200:203], v[240:243], v[30:33]
	s_waitcnt vmcnt(9)
	ds_write_b128 v100, v[160:163] offset:46080
	s_waitcnt vmcnt(8)
	ds_write_b128 v100, v[164:167] offset:50688
	s_waitcnt lgkmcnt(0)
	s_barrier
	s_setprio 0
	ds_read_b128 v[212:215], v245 offset:36864
	ds_read_b128 v[196:199], v244
	ds_read_b128 v[216:219], v245 offset:39168
	ds_read_b128 v[220:223], v245 offset:41472
	ds_read_b128 v[224:227], v245 offset:43776
	ds_read_b128 v[200:203], v244 offset:2304
	v_mfma_f32_16x16x32_bf16 v[34:37], v[204:207], v[228:231], v[34:37]
	v_mfma_f32_16x16x32_bf16 v[38:41], v[204:207], v[232:235], v[38:41]
	v_mfma_f32_16x16x32_bf16 v[2:5], v[204:207], v[236:239], v[2:5]
	v_mfma_f32_16x16x32_bf16 v[6:9], v[204:207], v[240:243], v[6:9]
	ds_read_b128 v[204:207], v244 offset:4608
	v_mfma_f32_16x16x32_bf16 v[42:45], v[208:211], v[228:231], v[42:45]
	v_mfma_f32_16x16x32_bf16 v[46:49], v[208:211], v[232:235], v[46:49]
	v_mfma_f32_16x16x32_bf16 v[10:13], v[208:211], v[236:239], v[10:13]
	v_mfma_f32_16x16x32_bf16 v[14:17], v[208:211], v[240:243], v[14:17]
	ds_read_b128 v[208:211], v244 offset:6912
	global_load_dwordx4 v[136:139], v[66:67], off offset:768
	global_load_dwordx4 v[140:143], v[68:69], off offset:768
	global_load_dwordx4 v[144:147], v[70:71], off offset:768
	global_load_dwordx4 v[148:151], v[72:73], off offset:768
	global_load_dwordx4 v[152:155], v[84:85], off offset:768
	global_load_dwordx4 v[156:159], v[86:87], off offset:768
	global_load_dwordx4 v[160:163], v[88:89], off offset:768
	global_load_dwordx4 v[164:167], v[90:91], off offset:768
	s_waitcnt lgkmcnt(6)
	v_mfma_f32_16x16x32_bf16 v[50:53], v[196:199], v[212:215], v[50:53]
	ds_read_b128 v[228:231], v245 offset:36928
	s_waitcnt lgkmcnt(6)
	v_mfma_f32_16x16x32_bf16 v[54:57], v[196:199], v[216:219], v[54:57]
	ds_read_b128 v[232:235], v245 offset:39232
	s_waitcnt lgkmcnt(6)
	v_mfma_f32_16x16x32_bf16 v[18:21], v[196:199], v[220:223], v[18:21]
	ds_read_b128 v[236:239], v245 offset:41536
	s_waitcnt lgkmcnt(6)
	v_mfma_f32_16x16x32_bf16 v[22:25], v[196:199], v[224:227], v[22:25]
	ds_read_b128 v[240:243], v245 offset:43840
	ds_read_b128 v[196:199], v244 offset:64
	s_waitcnt lgkmcnt(7)
	v_mfma_f32_16x16x32_bf16 v[58:61], v[200:203], v[212:215], v[58:61]
	v_mfma_f32_16x16x32_bf16 v[62:65], v[200:203], v[216:219], v[62:65]
	v_mfma_f32_16x16x32_bf16 v[26:29], v[200:203], v[220:223], v[26:29]
	v_mfma_f32_16x16x32_bf16 v[30:33], v[200:203], v[224:227], v[30:33]
	ds_read_b128 v[200:203], v244 offset:2368
	s_waitcnt lgkmcnt(7)
	v_mfma_f32_16x16x32_bf16 v[34:37], v[204:207], v[212:215], v[34:37]
	v_mfma_f32_16x16x32_bf16 v[38:41], v[204:207], v[216:219], v[38:41]
	v_mfma_f32_16x16x32_bf16 v[2:5], v[204:207], v[220:223], v[2:5]
	v_mfma_f32_16x16x32_bf16 v[6:9], v[204:207], v[224:227], v[6:9]
	ds_read_b128 v[204:207], v244 offset:4672
	s_setprio 1
	s_waitcnt vmcnt(15)
	ds_write_b128 v100, v[102:105] offset:18432
	s_waitcnt vmcnt(14)
	ds_write_b128 v100, v[106:109] offset:23040
	s_waitcnt lgkmcnt(9)
	v_mfma_f32_16x16x32_bf16 v[42:45], v[208:211], v[212:215], v[42:45]
	v_mfma_f32_16x16x32_bf16 v[46:49], v[208:211], v[216:219], v[46:49]
	v_mfma_f32_16x16x32_bf16 v[10:13], v[208:211], v[220:223], v[10:13]
	v_mfma_f32_16x16x32_bf16 v[14:17], v[208:211], v[224:227], v[14:17]
	ds_read_b128 v[208:211], v244 offset:6976
	s_waitcnt vmcnt(13)
	ds_write_b128 v100, v[110:113] offset:27648
	s_waitcnt vmcnt(12)
	ds_write_b128 v100, v[114:117] offset:32256
	s_waitcnt lgkmcnt(7)
	v_mfma_f32_16x16x32_bf16 v[50:53], v[196:199], v[228:231], v[50:53]
	v_mfma_f32_16x16x32_bf16 v[54:57], v[196:199], v[232:235], v[54:57]
	v_mfma_f32_16x16x32_bf16 v[18:21], v[196:199], v[236:239], v[18:21]
	v_mfma_f32_16x16x32_bf16 v[22:25], v[196:199], v[240:243], v[22:25]
	s_waitcnt vmcnt(11)
	ds_write_b128 v100, v[118:121] offset:55296
	s_waitcnt vmcnt(10)
	ds_write_b128 v100, v[122:125] offset:59904
	s_waitcnt lgkmcnt(8)
	v_mfma_f32_16x16x32_bf16 v[58:61], v[200:203], v[228:231], v[58:61]
	v_mfma_f32_16x16x32_bf16 v[62:65], v[200:203], v[232:235], v[62:65]
	v_mfma_f32_16x16x32_bf16 v[26:29], v[200:203], v[236:239], v[26:29]
	v_mfma_f32_16x16x32_bf16 v[30:33], v[200:203], v[240:243], v[30:33]
	s_waitcnt vmcnt(9)
	ds_write_b128 v100, v[126:129] offset:64512
	s_waitcnt vmcnt(8)
	ds_write_b128 v101, v[132:135] offset:32256
	s_waitcnt lgkmcnt(0)
	s_barrier
	s_setprio 0
	ds_read_b128 v[212:215], v245 offset:55296
	ds_read_b128 v[196:199], v244 offset:18432
	ds_read_b128 v[216:219], v245 offset:57600
	ds_read_b128 v[220:223], v245 offset:59904
	ds_read_b128 v[224:227], v245 offset:62208
	ds_read_b128 v[200:203], v244 offset:20736
	v_mfma_f32_16x16x32_bf16 v[34:37], v[204:207], v[228:231], v[34:37]
	v_mfma_f32_16x16x32_bf16 v[38:41], v[204:207], v[232:235], v[38:41]
	v_mfma_f32_16x16x32_bf16 v[2:5], v[204:207], v[236:239], v[2:5]
	v_mfma_f32_16x16x32_bf16 v[6:9], v[204:207], v[240:243], v[6:9]
	ds_read_b128 v[204:207], v244 offset:23040
	v_mfma_f32_16x16x32_bf16 v[42:45], v[208:211], v[228:231], v[42:45]
	v_mfma_f32_16x16x32_bf16 v[46:49], v[208:211], v[232:235], v[46:49]
	v_mfma_f32_16x16x32_bf16 v[10:13], v[208:211], v[236:239], v[10:13]
	v_mfma_f32_16x16x32_bf16 v[14:17], v[208:211], v[240:243], v[14:17]
	ds_read_b128 v[208:211], v244 offset:25344
	global_load_dwordx4 v[102:105], v[66:67], off offset:896
	s_nop 0
	global_load_dwordx4 v[66:69], v[68:69], off offset:896
	s_nop 0
	global_load_dwordx4 v[106:109], v[70:71], off offset:896
	s_nop 0
	global_load_dwordx4 v[70:73], v[72:73], off offset:896
	s_nop 0
	global_load_dwordx4 v[110:113], v[84:85], off offset:896
	s_nop 0
	global_load_dwordx4 v[84:87], v[86:87], off offset:896
	s_nop 0
	global_load_dwordx4 v[114:117], v[88:89], off offset:896
	s_nop 0
	global_load_dwordx4 v[88:91], v[90:91], off offset:896
	s_waitcnt lgkmcnt(6)
	v_mfma_f32_16x16x32_bf16 v[50:53], v[196:199], v[212:215], v[50:53]
	ds_read_b128 v[228:231], v245 offset:55360
	s_waitcnt lgkmcnt(6)
	v_mfma_f32_16x16x32_bf16 v[54:57], v[196:199], v[216:219], v[54:57]
	ds_read_b128 v[232:235], v245 offset:57664
	s_waitcnt lgkmcnt(6)
	v_mfma_f32_16x16x32_bf16 v[18:21], v[196:199], v[220:223], v[18:21]
	ds_read_b128 v[236:239], v245 offset:59968
	s_waitcnt lgkmcnt(6)
	v_mfma_f32_16x16x32_bf16 v[22:25], v[196:199], v[224:227], v[22:25]
	ds_read_b128 v[240:243], v245 offset:62272
	ds_read_b128 v[196:199], v244 offset:18496
	s_waitcnt lgkmcnt(7)
	v_mfma_f32_16x16x32_bf16 v[58:61], v[200:203], v[212:215], v[58:61]
	v_mfma_f32_16x16x32_bf16 v[62:65], v[200:203], v[216:219], v[62:65]
	v_mfma_f32_16x16x32_bf16 v[26:29], v[200:203], v[220:223], v[26:29]
	v_mfma_f32_16x16x32_bf16 v[30:33], v[200:203], v[224:227], v[30:33]
	ds_read_b128 v[200:203], v244 offset:20800
	s_waitcnt lgkmcnt(7)
	v_mfma_f32_16x16x32_bf16 v[34:37], v[204:207], v[212:215], v[34:37]
	v_mfma_f32_16x16x32_bf16 v[38:41], v[204:207], v[216:219], v[38:41]
	v_mfma_f32_16x16x32_bf16 v[2:5], v[204:207], v[220:223], v[2:5]
	v_mfma_f32_16x16x32_bf16 v[6:9], v[204:207], v[224:227], v[6:9]
	ds_read_b128 v[204:207], v244 offset:23104
	s_setprio 1
	s_waitcnt vmcnt(15)
	ds_write_b128 v100, v[136:139]
	s_waitcnt vmcnt(14)
	ds_write_b128 v100, v[140:143] offset:4608
	s_waitcnt lgkmcnt(9)
	v_mfma_f32_16x16x32_bf16 v[42:45], v[208:211], v[212:215], v[42:45]
	v_mfma_f32_16x16x32_bf16 v[46:49], v[208:211], v[216:219], v[46:49]
	v_mfma_f32_16x16x32_bf16 v[10:13], v[208:211], v[220:223], v[10:13]
	v_mfma_f32_16x16x32_bf16 v[14:17], v[208:211], v[224:227], v[14:17]
	ds_read_b128 v[208:211], v244 offset:25408
	s_waitcnt vmcnt(13)
	ds_write_b128 v100, v[144:147] offset:9216
	s_waitcnt vmcnt(12)
	ds_write_b128 v100, v[148:151] offset:13824
	s_waitcnt lgkmcnt(7)
	v_mfma_f32_16x16x32_bf16 v[50:53], v[196:199], v[228:231], v[50:53]
	v_mfma_f32_16x16x32_bf16 v[54:57], v[196:199], v[232:235], v[54:57]
	v_mfma_f32_16x16x32_bf16 v[18:21], v[196:199], v[236:239], v[18:21]
	v_mfma_f32_16x16x32_bf16 v[22:25], v[196:199], v[240:243], v[22:25]
	s_waitcnt vmcnt(11)
	ds_write_b128 v100, v[152:155] offset:36864
	s_waitcnt vmcnt(10)
	ds_write_b128 v100, v[156:159] offset:41472
	s_waitcnt lgkmcnt(8)
	v_mfma_f32_16x16x32_bf16 v[58:61], v[200:203], v[228:231], v[58:61]
	v_mfma_f32_16x16x32_bf16 v[62:65], v[200:203], v[232:235], v[62:65]
	v_mfma_f32_16x16x32_bf16 v[26:29], v[200:203], v[236:239], v[26:29]
	v_mfma_f32_16x16x32_bf16 v[30:33], v[200:203], v[240:243], v[30:33]
	s_waitcnt vmcnt(9)
	ds_write_b128 v100, v[160:163] offset:46080
	s_waitcnt vmcnt(8)
	ds_write_b128 v100, v[164:167] offset:50688
	s_waitcnt lgkmcnt(0)
	s_barrier
	s_setprio 0
	ds_read_b128 v[212:215], v245 offset:36864
	ds_read_b128 v[196:199], v244
	ds_read_b128 v[216:219], v245 offset:39168
	ds_read_b128 v[220:223], v245 offset:41472
	ds_read_b128 v[224:227], v245 offset:43776
	ds_read_b128 v[200:203], v244 offset:2304
	v_mfma_f32_16x16x32_bf16 v[34:37], v[204:207], v[228:231], v[34:37]
	v_mfma_f32_16x16x32_bf16 v[38:41], v[204:207], v[232:235], v[38:41]
	v_mfma_f32_16x16x32_bf16 v[2:5], v[204:207], v[236:239], v[2:5]
	v_mfma_f32_16x16x32_bf16 v[6:9], v[204:207], v[240:243], v[6:9]
	ds_read_b128 v[204:207], v244 offset:4608
	v_mfma_f32_16x16x32_bf16 v[42:45], v[208:211], v[228:231], v[42:45]
	v_mfma_f32_16x16x32_bf16 v[46:49], v[208:211], v[232:235], v[46:49]
	v_mfma_f32_16x16x32_bf16 v[10:13], v[208:211], v[236:239], v[10:13]
	v_mfma_f32_16x16x32_bf16 v[14:17], v[208:211], v[240:243], v[14:17]
	ds_read_b128 v[208:211], v244 offset:6912
	s_waitcnt lgkmcnt(6)
	v_mfma_f32_16x16x32_bf16 v[50:53], v[196:199], v[212:215], v[50:53]
	ds_read_b128 v[228:231], v245 offset:36928
	s_waitcnt lgkmcnt(6)
	v_mfma_f32_16x16x32_bf16 v[54:57], v[196:199], v[216:219], v[54:57]
	ds_read_b128 v[232:235], v245 offset:39232
	s_waitcnt lgkmcnt(6)
	v_mfma_f32_16x16x32_bf16 v[18:21], v[196:199], v[220:223], v[18:21]
	ds_read_b128 v[236:239], v245 offset:41536
	s_waitcnt lgkmcnt(6)
	v_mfma_f32_16x16x32_bf16 v[22:25], v[196:199], v[224:227], v[22:25]
	ds_read_b128 v[240:243], v245 offset:43840
	ds_read_b128 v[196:199], v244 offset:64
	s_waitcnt lgkmcnt(7)
	v_mfma_f32_16x16x32_bf16 v[58:61], v[200:203], v[212:215], v[58:61]
	v_mfma_f32_16x16x32_bf16 v[62:65], v[200:203], v[216:219], v[62:65]
	v_mfma_f32_16x16x32_bf16 v[26:29], v[200:203], v[220:223], v[26:29]
	v_mfma_f32_16x16x32_bf16 v[30:33], v[200:203], v[224:227], v[30:33]
	ds_read_b128 v[200:203], v244 offset:2368
	s_waitcnt lgkmcnt(7)
	v_mfma_f32_16x16x32_bf16 v[34:37], v[204:207], v[212:215], v[34:37]
	v_mfma_f32_16x16x32_bf16 v[38:41], v[204:207], v[216:219], v[38:41]
	v_mfma_f32_16x16x32_bf16 v[2:5], v[204:207], v[220:223], v[2:5]
	v_mfma_f32_16x16x32_bf16 v[6:9], v[204:207], v[224:227], v[6:9]
	ds_read_b128 v[204:207], v244 offset:4672
	s_setprio 1
	s_waitcnt vmcnt(7)
	ds_write_b128 v100, v[102:105] offset:18432
	s_waitcnt vmcnt(6)
	ds_write_b128 v100, v[66:69] offset:23040
	s_waitcnt lgkmcnt(9)
	v_mfma_f32_16x16x32_bf16 v[42:45], v[208:211], v[212:215], v[42:45]
	v_mfma_f32_16x16x32_bf16 v[46:49], v[208:211], v[216:219], v[46:49]
	v_mfma_f32_16x16x32_bf16 v[10:13], v[208:211], v[220:223], v[10:13]
	v_mfma_f32_16x16x32_bf16 v[14:17], v[208:211], v[224:227], v[14:17]
	ds_read_b128 v[208:211], v244 offset:6976
	s_waitcnt vmcnt(5)
	ds_write_b128 v100, v[106:109] offset:27648
	s_waitcnt vmcnt(4)
	ds_write_b128 v100, v[70:73] offset:32256
	s_waitcnt lgkmcnt(7)
	v_mfma_f32_16x16x32_bf16 v[50:53], v[196:199], v[228:231], v[50:53]
	v_mfma_f32_16x16x32_bf16 v[54:57], v[196:199], v[232:235], v[54:57]
	v_mfma_f32_16x16x32_bf16 v[18:21], v[196:199], v[236:239], v[18:21]
	v_mfma_f32_16x16x32_bf16 v[22:25], v[196:199], v[240:243], v[22:25]
	s_waitcnt vmcnt(3)
	ds_write_b128 v100, v[110:113] offset:55296
	s_waitcnt vmcnt(2)
	ds_write_b128 v100, v[84:87] offset:59904
	s_waitcnt lgkmcnt(8)
	v_mfma_f32_16x16x32_bf16 v[58:61], v[200:203], v[228:231], v[58:61]
	v_mfma_f32_16x16x32_bf16 v[62:65], v[200:203], v[232:235], v[62:65]
	v_mfma_f32_16x16x32_bf16 v[26:29], v[200:203], v[236:239], v[26:29]
	v_mfma_f32_16x16x32_bf16 v[30:33], v[200:203], v[240:243], v[30:33]
	s_waitcnt vmcnt(1)
	ds_write_b128 v100, v[114:117] offset:64512
	s_waitcnt vmcnt(0)
	ds_write_b128 v101, v[88:91] offset:32256
	s_waitcnt lgkmcnt(0)
	s_barrier
	s_setprio 0
	ds_read_b128 v[212:215], v245 offset:55296
	ds_read_b128 v[196:199], v244 offset:18432
	ds_read_b128 v[216:219], v245 offset:57600
	ds_read_b128 v[220:223], v245 offset:59904
	ds_read_b128 v[224:227], v245 offset:62208
	ds_read_b128 v[200:203], v244 offset:20736
	v_mfma_f32_16x16x32_bf16 v[34:37], v[204:207], v[228:231], v[34:37]
	v_mfma_f32_16x16x32_bf16 v[38:41], v[204:207], v[232:235], v[38:41]
	v_mfma_f32_16x16x32_bf16 v[2:5], v[204:207], v[236:239], v[2:5]
	v_mfma_f32_16x16x32_bf16 v[6:9], v[204:207], v[240:243], v[6:9]
	ds_read_b128 v[204:207], v244 offset:23040
	v_mfma_f32_16x16x32_bf16 v[42:45], v[208:211], v[228:231], v[42:45]
	v_mfma_f32_16x16x32_bf16 v[46:49], v[208:211], v[232:235], v[46:49]
	v_mfma_f32_16x16x32_bf16 v[10:13], v[208:211], v[236:239], v[10:13]
	v_mfma_f32_16x16x32_bf16 v[14:17], v[208:211], v[240:243], v[14:17]
	ds_read_b128 v[208:211], v244 offset:25344
	s_waitcnt lgkmcnt(6)
	v_mfma_f32_16x16x32_bf16 v[50:53], v[196:199], v[212:215], v[50:53]
	ds_read_b128 v[228:231], v245 offset:55360
	s_waitcnt lgkmcnt(6)
	v_mfma_f32_16x16x32_bf16 v[54:57], v[196:199], v[216:219], v[54:57]
	ds_read_b128 v[232:235], v245 offset:57664
	s_waitcnt lgkmcnt(6)
	v_mfma_f32_16x16x32_bf16 v[18:21], v[196:199], v[220:223], v[18:21]
	ds_read_b128 v[236:239], v245 offset:59968
	s_waitcnt lgkmcnt(6)
	v_mfma_f32_16x16x32_bf16 v[22:25], v[196:199], v[224:227], v[22:25]
	ds_read_b128 v[240:243], v245 offset:62272
	ds_read_b128 v[196:199], v244 offset:18496
	s_waitcnt lgkmcnt(7)
	v_mfma_f32_16x16x32_bf16 v[58:61], v[200:203], v[212:215], v[58:61]
	v_mfma_f32_16x16x32_bf16 v[62:65], v[200:203], v[216:219], v[62:65]
	v_mfma_f32_16x16x32_bf16 v[26:29], v[200:203], v[220:223], v[26:29]
	v_mfma_f32_16x16x32_bf16 v[30:33], v[200:203], v[224:227], v[30:33]
	ds_read_b128 v[200:203], v244 offset:20800
	s_waitcnt lgkmcnt(7)
	v_mfma_f32_16x16x32_bf16 v[34:37], v[204:207], v[212:215], v[34:37]
	v_mfma_f32_16x16x32_bf16 v[38:41], v[204:207], v[216:219], v[38:41]
	v_mfma_f32_16x16x32_bf16 v[2:5], v[204:207], v[220:223], v[2:5]
	v_mfma_f32_16x16x32_bf16 v[6:9], v[204:207], v[224:227], v[6:9]
	ds_read_b128 v[204:207], v244 offset:23104
	s_waitcnt lgkmcnt(7)
	v_mfma_f32_16x16x32_bf16 v[42:45], v[208:211], v[212:215], v[42:45]
	v_mfma_f32_16x16x32_bf16 v[46:49], v[208:211], v[216:219], v[46:49]
	v_mfma_f32_16x16x32_bf16 v[10:13], v[208:211], v[220:223], v[10:13]
	v_mfma_f32_16x16x32_bf16 v[14:17], v[208:211], v[224:227], v[14:17]
	ds_read_b128 v[208:211], v244 offset:25408
	s_waitcnt lgkmcnt(3)
	v_mfma_f32_16x16x32_bf16 v[50:53], v[196:199], v[228:231], v[50:53]
	v_mfma_f32_16x16x32_bf16 v[54:57], v[196:199], v[232:235], v[54:57]
	v_mfma_f32_16x16x32_bf16 v[18:21], v[196:199], v[236:239], v[18:21]
	v_mfma_f32_16x16x32_bf16 v[22:25], v[196:199], v[240:243], v[22:25]
	s_waitcnt lgkmcnt(2)
	v_mfma_f32_16x16x32_bf16 v[58:61], v[200:203], v[228:231], v[58:61]
	v_mfma_f32_16x16x32_bf16 v[62:65], v[200:203], v[232:235], v[62:65]
	v_mfma_f32_16x16x32_bf16 v[26:29], v[200:203], v[236:239], v[26:29]
	v_mfma_f32_16x16x32_bf16 v[30:33], v[200:203], v[240:243], v[30:33]
	s_add_i32 s6, s6, 1
	s_add_i32 s5, s5, s3
	v_or_b32_e32 v70, s0, v92
	s_lshl_b32 s0, s7, 1
	v_lshl_add_u64 v[110:111], v[80:81], 0, s[0:1]
	v_lshlrev_b32_e32 v74, 10, v70
	v_lshl_add_u64 v[112:113], v[110:111], 0, v[74:75]
	s_waitcnt lgkmcnt(0)
	s_barrier
	v_mfma_f32_16x16x32_bf16 v[34:37], v[204:207], v[228:231], v[34:37]
	v_mfma_f32_16x16x32_bf16 v[38:41], v[204:207], v[232:235], v[38:41]
	v_mfma_f32_16x16x32_bf16 v[2:5], v[204:207], v[236:239], v[2:5]
	v_mfma_f32_16x16x32_bf16 v[6:9], v[204:207], v[240:243], v[6:9]
	v_mfma_f32_16x16x32_bf16 v[42:45], v[208:211], v[228:231], v[42:45]
	v_mfma_f32_16x16x32_bf16 v[46:49], v[208:211], v[232:235], v[46:49]
	v_mfma_f32_16x16x32_bf16 v[10:13], v[208:211], v[236:239], v[10:13]
	v_mfma_f32_16x16x32_bf16 v[14:17], v[208:211], v[240:243], v[14:17]
	s_nop 7
	v_permlane16_swap_b32_e32 v50, v54
	v_permlane16_swap_b32_e32 v51, v55
	v_permlane16_swap_b32_e32 v52, v56
	v_permlane16_swap_b32_e32 v53, v57
	v_permlane16_swap_b32_e32 v58, v62
	v_permlane16_swap_b32_e32 v59, v63
	v_permlane16_swap_b32_e32 v60, v64
	v_permlane16_swap_b32_e32 v61, v65
	v_permlane16_swap_b32_e32 v18, v22
	v_permlane16_swap_b32_e32 v19, v23
	v_permlane16_swap_b32_e32 v20, v24
	v_permlane16_swap_b32_e32 v21, v25
	v_permlane16_swap_b32_e32 v26, v30
	v_permlane16_swap_b32_e32 v27, v31
	v_permlane16_swap_b32_e32 v28, v32
	v_permlane16_swap_b32_e32 v29, v33
	v_permlane16_swap_b32_e32 v34, v38
	v_permlane16_swap_b32_e32 v35, v39
	v_permlane16_swap_b32_e32 v36, v40
	v_permlane16_swap_b32_e32 v37, v41
	v_permlane16_swap_b32_e32 v42, v46
	v_permlane16_swap_b32_e32 v43, v47
	v_permlane16_swap_b32_e32 v44, v48
	v_permlane16_swap_b32_e32 v45, v49
	v_permlane16_swap_b32_e32 v2, v6
	v_permlane16_swap_b32_e32 v3, v7
	v_permlane16_swap_b32_e32 v4, v8
	v_permlane16_swap_b32_e32 v5, v9
	v_permlane16_swap_b32_e32 v10, v14
	v_permlane16_swap_b32_e32 v11, v15
	v_permlane16_swap_b32_e32 v12, v16
	v_permlane16_swap_b32_e32 v13, v17
	v_permlane32_swap_b32_e32 v50, v54
	v_permlane32_swap_b32_e32 v51, v55
	v_permlane32_swap_b32_e32 v52, v56
	v_permlane32_swap_b32_e32 v53, v57
	v_permlane32_swap_b32_e32 v58, v62
	v_permlane32_swap_b32_e32 v59, v63
	v_permlane32_swap_b32_e32 v60, v64
	v_permlane32_swap_b32_e32 v61, v65
	v_permlane32_swap_b32_e32 v18, v22
	v_permlane32_swap_b32_e32 v19, v23
	v_permlane32_swap_b32_e32 v20, v24
	v_permlane32_swap_b32_e32 v21, v25
	v_permlane32_swap_b32_e32 v26, v30
	v_permlane32_swap_b32_e32 v27, v31
	v_permlane32_swap_b32_e32 v28, v32
	v_permlane32_swap_b32_e32 v29, v33
	v_permlane32_swap_b32_e32 v34, v38
	v_permlane32_swap_b32_e32 v35, v39
	v_permlane32_swap_b32_e32 v36, v40
	v_permlane32_swap_b32_e32 v37, v41
	v_permlane32_swap_b32_e32 v42, v46
	v_permlane32_swap_b32_e32 v43, v47
	v_permlane32_swap_b32_e32 v44, v48
	v_permlane32_swap_b32_e32 v45, v49
	v_permlane32_swap_b32_e32 v2, v6
	v_permlane32_swap_b32_e32 v3, v7
	v_permlane32_swap_b32_e32 v4, v8
	v_permlane32_swap_b32_e32 v5, v9
	v_permlane32_swap_b32_e32 v10, v14
	v_permlane32_swap_b32_e32 v11, v15
	v_permlane32_swap_b32_e32 v12, v16
	v_permlane32_swap_b32_e32 v13, v17
	global_load_dwordx4 v[106:109], v[112:113], off
	s_mul_i32 s0, s6, s3
	s_add_i32 s0, s0, s2
	s_cmp_lt_u32 s5, 48
	global_load_dwordx4 v[88:91], v[112:113], off offset:32
	global_load_dwordx4 v[70:73], v[112:113], off offset:64
	s_waitcnt vmcnt(2)
	v_mov_b32_e32 v86, v108
	global_load_dwordx4 v[66:69], v[112:113], off offset:96
	v_permlane32_swap_b32_e32 v106, v86
	v_mov_b32_e32 v102, v109
	s_nop 1
	v_permlane32_swap_b32_e32 v107, v102
	s_waitcnt vmcnt(2)
	v_mov_b32_e32 v108, v90
	v_mov_b32_e32 v109, v91
	s_nop 0
	v_permlane32_swap_b32_e32 v88, v108
	v_permlane32_swap_b32_e32 v89, v109
	s_waitcnt vmcnt(1)
	v_mov_b32_e32 v112, v72
	v_mov_b32_e32 v113, v73
	v_lshlrev_b32_e32 v72, 16, v106
	v_and_b32_e32 v73, 0xffff0000, v106
	v_pk_mul_f32 v[72:73], v[50:51], v[72:73]
	v_lshlrev_b32_e32 v50, 16, v107
	v_and_b32_e32 v51, 0xffff0000, v107
	v_pk_mul_f32 v[84:85], v[52:53], v[50:51]
	v_lshlrev_b32_e32 v50, 16, v86
	v_and_b32_e32 v51, 0xffff0000, v86
	v_pk_mul_f32 v[86:87], v[54:55], v[50:51]
	v_lshlrev_b32_e32 v54, 16, v102
	v_and_b32_e32 v55, 0xffff0000, v102
	v_pk_mul_f32 v[102:103], v[56:57], v[54:55]
	v_cvt_pk_bf16_f32 v55, v84, v85
	v_cvt_pk_bf16_f32 v56, v86, v87
	v_cvt_pk_bf16_f32 v57, v102, v103
	v_cvt_pk_bf16_f32 v54, v72, v73
	v_add_lshl_u32 v72, s7, v97, 1
	v_mov_b32_e32 v73, v75
	v_permlane32_swap_b32_e32 v54, v56
	v_permlane32_swap_b32_e32 v55, v57
	v_lshlrev_b32_e32 v106, 16, v88
	v_and_b32_e32 v107, 0xffff0000, v88
	v_lshlrev_b32_e32 v88, 16, v89
	v_and_b32_e32 v89, 0xffff0000, v89
	v_pk_mul_f32 v[60:61], v[60:61], v[88:89]
	v_lshlrev_b32_e32 v88, 16, v108
	v_and_b32_e32 v89, 0xffff0000, v108
	v_pk_mul_f32 v[62:63], v[62:63], v[88:89]
	v_lshlrev_b32_e32 v88, 16, v109
	v_and_b32_e32 v89, 0xffff0000, v109
	v_pk_mul_f32 v[58:59], v[58:59], v[106:107]
	v_pk_mul_f32 v[64:65], v[64:65], v[88:89]
	v_cvt_pk_bf16_f32 v58, v58, v59
	v_cvt_pk_bf16_f32 v59, v60, v61
	v_cvt_pk_bf16_f32 v60, v62, v63
	v_cvt_pk_bf16_f32 v61, v64, v65
	v_permlane32_swap_b32_e32 v70, v112
	v_permlane32_swap_b32_e32 v58, v60
	v_permlane32_swap_b32_e32 v59, v61
	v_permlane32_swap_b32_e32 v71, v113
	s_waitcnt vmcnt(0)
	v_mov_b32_e32 v114, v68
	v_mov_b32_e32 v115, v69
	v_lshl_add_u64 v[68:69], v[82:83], 0, v[74:75]
	v_or_b32_e32 v74, 0x8000, v74
	v_lshl_add_u64 v[90:91], v[110:111], 0, v[74:75]
	global_load_dwordx4 v[50:53], v[90:91], off
	global_load_dwordx4 v[84:87], v[90:91], off offset:32
	global_load_dwordx4 v[102:105], v[90:91], off offset:64
	v_lshl_add_u64 v[68:69], v[68:69], 0, v[72:73]
	global_store_dwordx4 v[68:69], v[54:57], off
	global_load_dwordx4 v[54:57], v[90:91], off offset:96
	v_permlane32_swap_b32_e32 v66, v114
	global_store_dwordx4 v[68:69], v[58:61], off offset:32
	v_permlane32_swap_b32_e32 v67, v115
	s_nop 0
	v_lshlrev_b32_e32 v58, 16, v70
	v_and_b32_e32 v59, 0xffff0000, v70
	v_pk_mul_f32 v[34:35], v[34:35], v[58:59]
	v_lshlrev_b32_e32 v58, 16, v71
	v_and_b32_e32 v59, 0xffff0000, v71
	v_pk_mul_f32 v[36:37], v[36:37], v[58:59]
	v_lshlrev_b32_e32 v58, 16, v112
	v_and_b32_e32 v59, 0xffff0000, v112
	v_pk_mul_f32 v[38:39], v[38:39], v[58:59]
	v_lshlrev_b32_e32 v58, 16, v113
	v_and_b32_e32 v59, 0xffff0000, v113
	v_pk_mul_f32 v[40:41], v[40:41], v[58:59]
	v_cvt_pk_bf16_f32 v34, v34, v35
	v_cvt_pk_bf16_f32 v35, v36, v37
	v_cvt_pk_bf16_f32 v36, v38, v39
	v_cvt_pk_bf16_f32 v37, v40, v41
	s_nop 0
	v_permlane32_swap_b32_e32 v34, v36
	v_permlane32_swap_b32_e32 v35, v37
	global_store_dwordx4 v[68:69], v[34:37], off offset:64
	v_lshlrev_b32_e32 v38, 16, v114
	v_and_b32_e32 v39, 0xffff0000, v114
	v_lshlrev_b32_e32 v34, 16, v66
	v_and_b32_e32 v35, 0xffff0000, v66
	v_lshlrev_b32_e32 v36, 16, v67
	v_and_b32_e32 v37, 0xffff0000, v67
	v_lshlrev_b32_e32 v40, 16, v115
	v_and_b32_e32 v41, 0xffff0000, v115
	v_pk_mul_f32 v[34:35], v[42:43], v[34:35]
	v_pk_mul_f32 v[36:37], v[44:45], v[36:37]
	v_pk_mul_f32 v[38:39], v[46:47], v[38:39]
	v_pk_mul_f32 v[40:41], v[48:49], v[40:41]
	v_cvt_pk_bf16_f32 v34, v34, v35
	v_cvt_pk_bf16_f32 v35, v36, v37
	v_cvt_pk_bf16_f32 v36, v38, v39
	v_cvt_pk_bf16_f32 v37, v40, v41
	s_nop 0
	v_permlane32_swap_b32_e32 v34, v36
	v_permlane32_swap_b32_e32 v35, v37
	global_store_dwordx4 v[68:69], v[34:37], off offset:96
	s_waitcnt vmcnt(7)
	v_mov_b32_e32 v38, v52
	s_nop 1
	v_permlane32_swap_b32_e32 v50, v38
	v_mov_b32_e32 v39, v53
	s_nop 1
	v_permlane32_swap_b32_e32 v51, v39
	v_lshlrev_b32_e32 v36, 16, v50
	v_and_b32_e32 v37, 0xffff0000, v50
	v_pk_mul_f32 v[18:19], v[18:19], v[36:37]
	v_lshlrev_b32_e32 v36, 16, v51
	v_and_b32_e32 v37, 0xffff0000, v51
	v_pk_mul_f32 v[20:21], v[20:21], v[36:37]
	v_lshlrev_b32_e32 v36, 16, v38
	v_and_b32_e32 v37, 0xffff0000, v38
	v_pk_mul_f32 v[22:23], v[22:23], v[36:37]
	v_lshlrev_b32_e32 v36, 16, v39
	v_and_b32_e32 v37, 0xffff0000, v39
	v_pk_mul_f32 v[24:25], v[24:25], v[36:37]
	s_waitcnt vmcnt(6)
	v_mov_b32_e32 v40, v86
	v_lshl_add_u64 v[34:35], v[82:83], 0, v[74:75]
	v_cvt_pk_bf16_f32 v18, v18, v19
	v_cvt_pk_bf16_f32 v19, v20, v21
	v_cvt_pk_bf16_f32 v20, v22, v23
	v_cvt_pk_bf16_f32 v21, v24, v25
	v_permlane32_swap_b32_e32 v84, v40
	v_mov_b32_e32 v41, v87
	v_permlane32_swap_b32_e32 v18, v20
	v_permlane32_swap_b32_e32 v19, v21
	v_lshl_add_u64 v[22:23], v[34:35], 0, v[72:73]
	v_permlane32_swap_b32_e32 v85, v41
	global_store_dwordx4 v[22:23], v[18:21], off
	v_lshlrev_b32_e32 v24, 16, v40
	v_and_b32_e32 v25, 0xffff0000, v40
	v_lshlrev_b32_e32 v18, 16, v84
	v_and_b32_e32 v19, 0xffff0000, v84
	v_pk_mul_f32 v[18:19], v[26:27], v[18:19]
	v_lshlrev_b32_e32 v20, 16, v85
	v_and_b32_e32 v21, 0xffff0000, v85
	v_lshlrev_b32_e32 v26, 16, v41
	v_and_b32_e32 v27, 0xffff0000, v41
	v_pk_mul_f32 v[20:21], v[28:29], v[20:21]
	v_pk_mul_f32 v[24:25], v[30:31], v[24:25]
	v_pk_mul_f32 v[26:27], v[32:33], v[26:27]
	s_waitcnt vmcnt(6)
	v_mov_b32_e32 v42, v104
	v_cvt_pk_bf16_f32 v18, v18, v19
	v_cvt_pk_bf16_f32 v19, v20, v21
	v_cvt_pk_bf16_f32 v20, v24, v25
	v_cvt_pk_bf16_f32 v21, v26, v27
	v_permlane32_swap_b32_e32 v102, v42
	v_mov_b32_e32 v43, v105
	v_permlane32_swap_b32_e32 v18, v20
	v_permlane32_swap_b32_e32 v19, v21
	v_permlane32_swap_b32_e32 v103, v43
	global_store_dwordx4 v[22:23], v[18:21], off offset:32
	s_waitcnt vmcnt(5)
	v_mov_b32_e32 v44, v56
	v_mov_b32_e32 v45, v57
	v_lshlrev_b32_e32 v18, 16, v102
	v_and_b32_e32 v19, 0xffff0000, v102
	v_pk_mul_f32 v[2:3], v[2:3], v[18:19]
	v_lshlrev_b32_e32 v18, 16, v103
	v_and_b32_e32 v19, 0xffff0000, v103
	v_pk_mul_f32 v[4:5], v[4:5], v[18:19]
	v_lshlrev_b32_e32 v18, 16, v42
	v_and_b32_e32 v19, 0xffff0000, v42
	v_pk_mul_f32 v[6:7], v[6:7], v[18:19]
	v_lshlrev_b32_e32 v18, 16, v43
	v_and_b32_e32 v19, 0xffff0000, v43
	v_pk_mul_f32 v[8:9], v[8:9], v[18:19]
	v_cvt_pk_bf16_f32 v2, v2, v3
	v_cvt_pk_bf16_f32 v3, v4, v5
	v_cvt_pk_bf16_f32 v4, v6, v7
	v_cvt_pk_bf16_f32 v5, v8, v9
	v_permlane32_swap_b32_e32 v54, v44
	v_permlane32_swap_b32_e32 v55, v45
	v_permlane32_swap_b32_e32 v2, v4
	v_permlane32_swap_b32_e32 v3, v5
	global_store_dwordx4 v[22:23], v[2:5], off offset:64
	v_lshlrev_b32_e32 v6, 16, v44
	v_and_b32_e32 v7, 0xffff0000, v44
	v_lshlrev_b32_e32 v2, 16, v54
	v_and_b32_e32 v3, 0xffff0000, v54
	v_lshlrev_b32_e32 v4, 16, v55
	v_and_b32_e32 v5, 0xffff0000, v55
	v_lshlrev_b32_e32 v8, 16, v45
	v_and_b32_e32 v9, 0xffff0000, v45
	v_pk_mul_f32 v[2:3], v[10:11], v[2:3]
	v_pk_mul_f32 v[4:5], v[12:13], v[4:5]
	v_pk_mul_f32 v[6:7], v[14:15], v[6:7]
	v_pk_mul_f32 v[8:9], v[16:17], v[8:9]
	v_cvt_pk_bf16_f32 v2, v2, v3
	v_cvt_pk_bf16_f32 v3, v4, v5
	v_cvt_pk_bf16_f32 v4, v6, v7
	v_cvt_pk_bf16_f32 v5, v8, v9
	s_nop 0
	v_permlane32_swap_b32_e32 v2, v4
	v_permlane32_swap_b32_e32 v3, v5
	global_store_dwordx4 v[22:23], v[2:5], off offset:96
	s_cbranch_scc1 .LBB0_1720

.LBB0_1871:
	s_lshr_b32 s0, s4, 2
	s_and_b32 s4, s4, 3
	s_or_b32 s4, s4, s8
	s_lshl_b32 s4, s4, 7
	v_or_b32_e32 v2, s4, v89
	v_lshlrev_b32_e32 v66, 11, v2
	s_add_i32 s0, s0, s9
	v_lshl_add_u64 v[72:73], v[68:69], 0, v[66:67]
	v_add_lshl_u32 v66, s4, v90, 11
	s_lshl_b32 s5, s0, 7
	v_lshl_add_u64 v[74:75], v[68:69], 0, v[66:67]
	v_add_lshl_u32 v66, s4, v91, 11
	v_lshl_add_u64 v[76:77], v[68:69], 0, v[66:67]
	v_add_lshl_u32 v66, s4, v92, 11
	v_or_b32_e32 v2, s5, v89
	v_lshl_add_u64 v[78:79], v[68:69], 0, v[66:67]
	v_lshlrev_b32_e32 v66, 11, v2
	v_lshl_add_u64 v[80:81], v[70:71], 0, v[66:67]
	v_add_lshl_u32 v66, s5, v90, 11
	v_lshl_add_u64 v[82:83], v[70:71], 0, v[66:67]
	v_add_lshl_u32 v66, s5, v91, 11
	v_lshl_add_u64 v[84:85], v[70:71], 0, v[66:67]
	v_add_lshl_u32 v66, s5, v92, 11
	v_lshl_add_u64 v[86:87], v[70:71], 0, v[66:67]
	global_load_dwordx4 v[2:5], v[72:73], off
	global_load_dwordx4 v[6:9], v[74:75], off
	global_load_dwordx4 v[10:13], v[76:77], off
	global_load_dwordx4 v[14:17], v[78:79], off
	global_load_dwordx4 v[18:21], v[80:81], off
	global_load_dwordx4 v[22:25], v[82:83], off
	global_load_dwordx4 v[26:29], v[84:85], off
	global_load_dwordx4 v[30:33], v[86:87], off
	global_load_dwordx4 v[98:101], v[72:73], off offset:128
	global_load_dwordx4 v[102:105], v[74:75], off offset:128
	global_load_dwordx4 v[106:109], v[76:77], off offset:128
	global_load_dwordx4 v[110:113], v[78:79], off offset:128
	global_load_dwordx4 v[114:117], v[80:81], off offset:128
	global_load_dwordx4 v[118:121], v[82:83], off offset:128
	global_load_dwordx4 v[122:125], v[84:85], off offset:128
	global_load_dwordx4 v[126:129], v[86:87], off offset:128
	s_waitcnt vmcnt(15)
	ds_write_b128 v95, v[2:5]
	s_waitcnt vmcnt(14)
	ds_write_b128 v95, v[6:9] offset:4608
	s_waitcnt vmcnt(13)
	ds_write_b128 v95, v[10:13] offset:9216
	s_waitcnt vmcnt(12)
	ds_write_b128 v95, v[14:17] offset:13824
	s_waitcnt vmcnt(11)
	ds_write_b128 v95, v[18:21] offset:36864
	s_waitcnt vmcnt(10)
	ds_write_b128 v95, v[22:25] offset:41472
	s_waitcnt vmcnt(9)
	ds_write_b128 v95, v[26:29] offset:46080
	s_waitcnt vmcnt(8)
	ds_write_b128 v95, v[30:33] offset:50688
	s_waitcnt lgkmcnt(0)
	s_barrier
	global_load_dwordx4 v[132:135], v[72:73], off offset:256
	global_load_dwordx4 v[136:139], v[74:75], off offset:256
	global_load_dwordx4 v[140:143], v[76:77], off offset:256
	global_load_dwordx4 v[144:147], v[78:79], off offset:256
	global_load_dwordx4 v[148:151], v[80:81], off offset:256
	global_load_dwordx4 v[152:155], v[82:83], off offset:256
	global_load_dwordx4 v[156:159], v[84:85], off offset:256
	global_load_dwordx4 v[160:163], v[86:87], off offset:256
	v_and_b32_e32 v246, 15, v1
	v_add_u32_e32 v246, 4, v246
	v_bfe_u32 v246, v246, 3, 1
	v_bfe_u32 v249, v1, 4, 2
	v_xor_b32_e32 v246, v246, v249
	v_bfe_u32 v249, v1, 5, 1
	v_sub_u32_e32 v246, v246, v249
	v_lshlrev_b32_e32 v246, 4, v246
	v_bfe_u32 v249, v1, 4, 1
	v_mul_u32_u24_e32 v249, 0x900, v249
	v_sub_u32_e32 v246, v246, v249
	v_add_u32_e32 v244, v246, v93
	v_add_u32_e32 v245, v246, v94
	ds_read_b128 v[212:215], v245 offset:36864
	ds_read_b128 v[196:199], v244
	ds_read_b128 v[216:219], v245 offset:39168
	ds_read_b128 v[220:223], v245 offset:41472
	ds_read_b128 v[224:227], v245 offset:43776
	ds_read_b128 v[200:203], v244 offset:2304
	ds_read_b128 v[204:207], v244 offset:4608
	ds_read_b128 v[208:211], v244 offset:6912
	s_waitcnt lgkmcnt(6)
	v_mfma_f32_16x16x32_bf16 v[34:37], v[196:199], v[212:215], 0
	ds_read_b128 v[228:231], v245 offset:36928
	s_waitcnt lgkmcnt(6)
	v_mfma_f32_16x16x32_bf16 v[38:41], v[196:199], v[216:219], 0
	ds_read_b128 v[232:235], v245 offset:39232
	s_waitcnt lgkmcnt(6)
	v_mfma_f32_16x16x32_bf16 v[2:5], v[196:199], v[220:223], 0
	ds_read_b128 v[236:239], v245 offset:41536
	s_waitcnt lgkmcnt(6)
	v_mfma_f32_16x16x32_bf16 v[6:9], v[196:199], v[224:227], 0
	ds_read_b128 v[240:243], v245 offset:43840
	ds_read_b128 v[196:199], v244 offset:64
	s_waitcnt lgkmcnt(7)
	v_mfma_f32_16x16x32_bf16 v[42:45], v[200:203], v[212:215], 0
	v_mfma_f32_16x16x32_bf16 v[46:49], v[200:203], v[216:219], 0
	v_mfma_f32_16x16x32_bf16 v[10:13], v[200:203], v[220:223], 0
	v_mfma_f32_16x16x32_bf16 v[14:17], v[200:203], v[224:227], 0
	ds_read_b128 v[200:203], v244 offset:2368
	s_waitcnt lgkmcnt(7)
	v_mfma_f32_16x16x32_bf16 v[50:53], v[204:207], v[212:215], 0
	v_mfma_f32_16x16x32_bf16 v[54:57], v[204:207], v[216:219], 0
	v_mfma_f32_16x16x32_bf16 v[18:21], v[204:207], v[220:223], 0
	v_mfma_f32_16x16x32_bf16 v[22:25], v[204:207], v[224:227], 0
	ds_read_b128 v[204:207], v244 offset:4672
	s_setprio 1
	s_waitcnt vmcnt(15)
	ds_write_b128 v95, v[98:101] offset:18432
	s_waitcnt vmcnt(14)
	ds_write_b128 v95, v[102:105] offset:23040
	s_waitcnt lgkmcnt(9)
	v_mfma_f32_16x16x32_bf16 v[58:61], v[208:211], v[212:215], 0
	v_mfma_f32_16x16x32_bf16 v[62:65], v[208:211], v[216:219], 0
	v_mfma_f32_16x16x32_bf16 v[26:29], v[208:211], v[220:223], 0
	v_mfma_f32_16x16x32_bf16 v[30:33], v[208:211], v[224:227], 0
	ds_read_b128 v[208:211], v244 offset:6976
	s_waitcnt vmcnt(13)
	ds_write_b128 v95, v[106:109] offset:27648
	s_waitcnt vmcnt(12)
	ds_write_b128 v95, v[110:113] offset:32256
	s_waitcnt lgkmcnt(7)
	v_mfma_f32_16x16x32_bf16 v[34:37], v[196:199], v[228:231], v[34:37]
	v_mfma_f32_16x16x32_bf16 v[38:41], v[196:199], v[232:235], v[38:41]
	v_mfma_f32_16x16x32_bf16 v[2:5], v[196:199], v[236:239], v[2:5]
	v_mfma_f32_16x16x32_bf16 v[6:9], v[196:199], v[240:243], v[6:9]
	s_waitcnt vmcnt(11)
	ds_write_b128 v95, v[114:117] offset:55296
	s_waitcnt vmcnt(10)
	ds_write_b128 v95, v[118:121] offset:59904
	s_waitcnt lgkmcnt(8)
	v_mfma_f32_16x16x32_bf16 v[42:45], v[200:203], v[228:231], v[42:45]
	v_mfma_f32_16x16x32_bf16 v[46:49], v[200:203], v[232:235], v[46:49]
	v_mfma_f32_16x16x32_bf16 v[10:13], v[200:203], v[236:239], v[10:13]
	v_mfma_f32_16x16x32_bf16 v[14:17], v[200:203], v[240:243], v[14:17]
	s_waitcnt vmcnt(9)
	ds_write_b128 v95, v[122:125] offset:64512
	s_waitcnt vmcnt(8)
	ds_write_b128 v96, v[126:129] offset:32256
	s_waitcnt lgkmcnt(0)
	s_barrier
	s_setprio 0
	ds_read_b128 v[212:215], v245 offset:55296
	ds_read_b128 v[196:199], v244 offset:18432
	ds_read_b128 v[216:219], v245 offset:57600
	ds_read_b128 v[220:223], v245 offset:59904
	ds_read_b128 v[224:227], v245 offset:62208
	ds_read_b128 v[200:203], v244 offset:20736
	v_mfma_f32_16x16x32_bf16 v[50:53], v[204:207], v[228:231], v[50:53]
	v_mfma_f32_16x16x32_bf16 v[54:57], v[204:207], v[232:235], v[54:57]
	v_mfma_f32_16x16x32_bf16 v[18:21], v[204:207], v[236:239], v[18:21]
	v_mfma_f32_16x16x32_bf16 v[22:25], v[204:207], v[240:243], v[22:25]
	ds_read_b128 v[204:207], v244 offset:23040
	v_mfma_f32_16x16x32_bf16 v[58:61], v[208:211], v[228:231], v[58:61]
	v_mfma_f32_16x16x32_bf16 v[62:65], v[208:211], v[232:235], v[62:65]
	v_mfma_f32_16x16x32_bf16 v[26:29], v[208:211], v[236:239], v[26:29]
	v_mfma_f32_16x16x32_bf16 v[30:33], v[208:211], v[240:243], v[30:33]
	ds_read_b128 v[208:211], v244 offset:25344
	global_load_dwordx4 v[98:101], v[72:73], off offset:384
	global_load_dwordx4 v[102:105], v[74:75], off offset:384
	global_load_dwordx4 v[106:109], v[76:77], off offset:384
	global_load_dwordx4 v[110:113], v[78:79], off offset:384
	global_load_dwordx4 v[114:117], v[80:81], off offset:384
	global_load_dwordx4 v[118:121], v[82:83], off offset:384
	global_load_dwordx4 v[122:125], v[84:85], off offset:384
	global_load_dwordx4 v[126:129], v[86:87], off offset:384
	s_waitcnt lgkmcnt(6)
	v_mfma_f32_16x16x32_bf16 v[34:37], v[196:199], v[212:215], v[34:37]
	ds_read_b128 v[228:231], v245 offset:55360
	s_waitcnt lgkmcnt(6)
	v_mfma_f32_16x16x32_bf16 v[38:41], v[196:199], v[216:219], v[38:41]
	ds_read_b128 v[232:235], v245 offset:57664
	s_waitcnt lgkmcnt(6)
	v_mfma_f32_16x16x32_bf16 v[2:5], v[196:199], v[220:223], v[2:5]
	ds_read_b128 v[236:239], v245 offset:59968
	s_waitcnt lgkmcnt(6)
	v_mfma_f32_16x16x32_bf16 v[6:9], v[196:199], v[224:227], v[6:9]
	ds_read_b128 v[240:243], v245 offset:62272
	ds_read_b128 v[196:199], v244 offset:18496
	s_waitcnt lgkmcnt(7)
	v_mfma_f32_16x16x32_bf16 v[42:45], v[200:203], v[212:215], v[42:45]
	v_mfma_f32_16x16x32_bf16 v[46:49], v[200:203], v[216:219], v[46:49]
	v_mfma_f32_16x16x32_bf16 v[10:13], v[200:203], v[220:223], v[10:13]
	v_mfma_f32_16x16x32_bf16 v[14:17], v[200:203], v[224:227], v[14:17]
	ds_read_b128 v[200:203], v244 offset:20800
	s_waitcnt lgkmcnt(7)
	v_mfma_f32_16x16x32_bf16 v[50:53], v[204:207], v[212:215], v[50:53]
	v_mfma_f32_16x16x32_bf16 v[54:57], v[204:207], v[216:219], v[54:57]
	v_mfma_f32_16x16x32_bf16 v[18:21], v[204:207], v[220:223], v[18:21]
	v_mfma_f32_16x16x32_bf16 v[22:25], v[204:207], v[224:227], v[22:25]
	ds_read_b128 v[204:207], v244 offset:23104
	s_setprio 1
	s_waitcnt vmcnt(15)
	ds_write_b128 v95, v[132:135]
	s_waitcnt vmcnt(14)
	ds_write_b128 v95, v[136:139] offset:4608
	s_waitcnt lgkmcnt(9)
	v_mfma_f32_16x16x32_bf16 v[58:61], v[208:211], v[212:215], v[58:61]
	v_mfma_f32_16x16x32_bf16 v[62:65], v[208:211], v[216:219], v[62:65]
	v_mfma_f32_16x16x32_bf16 v[26:29], v[208:211], v[220:223], v[26:29]
	v_mfma_f32_16x16x32_bf16 v[30:33], v[208:211], v[224:227], v[30:33]
	ds_read_b128 v[208:211], v244 offset:25408
	s_waitcnt vmcnt(13)
	ds_write_b128 v95, v[140:143] offset:9216
	s_waitcnt vmcnt(12)
	ds_write_b128 v95, v[144:147] offset:13824
	s_waitcnt lgkmcnt(7)
	v_mfma_f32_16x16x32_bf16 v[34:37], v[196:199], v[228:231], v[34:37]
	v_mfma_f32_16x16x32_bf16 v[38:41], v[196:199], v[232:235], v[38:41]
	v_mfma_f32_16x16x32_bf16 v[2:5], v[196:199], v[236:239], v[2:5]
	v_mfma_f32_16x16x32_bf16 v[6:9], v[196:199], v[240:243], v[6:9]
	s_waitcnt vmcnt(11)
	ds_write_b128 v95, v[148:151] offset:36864
	s_waitcnt vmcnt(10)
	ds_write_b128 v95, v[152:155] offset:41472
	s_waitcnt lgkmcnt(8)
	v_mfma_f32_16x16x32_bf16 v[42:45], v[200:203], v[228:231], v[42:45]
	v_mfma_f32_16x16x32_bf16 v[46:49], v[200:203], v[232:235], v[46:49]
	v_mfma_f32_16x16x32_bf16 v[10:13], v[200:203], v[236:239], v[10:13]
	v_mfma_f32_16x16x32_bf16 v[14:17], v[200:203], v[240:243], v[14:17]
	s_waitcnt vmcnt(9)
	ds_write_b128 v95, v[156:159] offset:46080
	s_waitcnt vmcnt(8)
	ds_write_b128 v95, v[160:163] offset:50688
	s_waitcnt lgkmcnt(0)
	s_barrier
	s_setprio 0
	ds_read_b128 v[212:215], v245 offset:36864
	ds_read_b128 v[196:199], v244
	ds_read_b128 v[216:219], v245 offset:39168
	ds_read_b128 v[220:223], v245 offset:41472
	ds_read_b128 v[224:227], v245 offset:43776
	ds_read_b128 v[200:203], v244 offset:2304
	v_mfma_f32_16x16x32_bf16 v[50:53], v[204:207], v[228:231], v[50:53]
	v_mfma_f32_16x16x32_bf16 v[54:57], v[204:207], v[232:235], v[54:57]
	v_mfma_f32_16x16x32_bf16 v[18:21], v[204:207], v[236:239], v[18:21]
	v_mfma_f32_16x16x32_bf16 v[22:25], v[204:207], v[240:243], v[22:25]
	ds_read_b128 v[204:207], v244 offset:4608
	v_mfma_f32_16x16x32_bf16 v[58:61], v[208:211], v[228:231], v[58:61]
	v_mfma_f32_16x16x32_bf16 v[62:65], v[208:211], v[232:235], v[62:65]
	v_mfma_f32_16x16x32_bf16 v[26:29], v[208:211], v[236:239], v[26:29]
	v_mfma_f32_16x16x32_bf16 v[30:33], v[208:211], v[240:243], v[30:33]
	ds_read_b128 v[208:211], v244 offset:6912
	global_load_dwordx4 v[132:135], v[72:73], off offset:512
	global_load_dwordx4 v[136:139], v[74:75], off offset:512
	global_load_dwordx4 v[140:143], v[76:77], off offset:512
	global_load_dwordx4 v[144:147], v[78:79], off offset:512
	global_load_dwordx4 v[148:151], v[80:81], off offset:512
	global_load_dwordx4 v[152:155], v[82:83], off offset:512
	global_load_dwordx4 v[156:159], v[84:85], off offset:512
	global_load_dwordx4 v[160:163], v[86:87], off offset:512
	s_waitcnt lgkmcnt(6)
	v_mfma_f32_16x16x32_bf16 v[34:37], v[196:199], v[212:215], v[34:37]
	ds_read_b128 v[228:231], v245 offset:36928
	s_waitcnt lgkmcnt(6)
	v_mfma_f32_16x16x32_bf16 v[38:41], v[196:199], v[216:219], v[38:41]
	ds_read_b128 v[232:235], v245 offset:39232
	s_waitcnt lgkmcnt(6)
	v_mfma_f32_16x16x32_bf16 v[2:5], v[196:199], v[220:223], v[2:5]
	ds_read_b128 v[236:239], v245 offset:41536
	s_waitcnt lgkmcnt(6)
	v_mfma_f32_16x16x32_bf16 v[6:9], v[196:199], v[224:227], v[6:9]
	ds_read_b128 v[240:243], v245 offset:43840
	ds_read_b128 v[196:199], v244 offset:64
	s_waitcnt lgkmcnt(7)
	v_mfma_f32_16x16x32_bf16 v[42:45], v[200:203], v[212:215], v[42:45]
	v_mfma_f32_16x16x32_bf16 v[46:49], v[200:203], v[216:219], v[46:49]
	v_mfma_f32_16x16x32_bf16 v[10:13], v[200:203], v[220:223], v[10:13]
	v_mfma_f32_16x16x32_bf16 v[14:17], v[200:203], v[224:227], v[14:17]
	ds_read_b128 v[200:203], v244 offset:2368
	s_waitcnt lgkmcnt(7)
	v_mfma_f32_16x16x32_bf16 v[50:53], v[204:207], v[212:215], v[50:53]
	v_mfma_f32_16x16x32_bf16 v[54:57], v[204:207], v[216:219], v[54:57]
	v_mfma_f32_16x16x32_bf16 v[18:21], v[204:207], v[220:223], v[18:21]
	v_mfma_f32_16x16x32_bf16 v[22:25], v[204:207], v[224:227], v[22:25]
	ds_read_b128 v[204:207], v244 offset:4672
	s_setprio 1
	s_waitcnt vmcnt(15)
	ds_write_b128 v95, v[98:101] offset:18432
	s_waitcnt vmcnt(14)
	ds_write_b128 v95, v[102:105] offset:23040
	s_waitcnt lgkmcnt(9)
	v_mfma_f32_16x16x32_bf16 v[58:61], v[208:211], v[212:215], v[58:61]
	v_mfma_f32_16x16x32_bf16 v[62:65], v[208:211], v[216:219], v[62:65]
	v_mfma_f32_16x16x32_bf16 v[26:29], v[208:211], v[220:223], v[26:29]
	v_mfma_f32_16x16x32_bf16 v[30:33], v[208:211], v[224:227], v[30:33]
	ds_read_b128 v[208:211], v244 offset:6976
	s_waitcnt vmcnt(13)
	ds_write_b128 v95, v[106:109] offset:27648
	s_waitcnt vmcnt(12)
	ds_write_b128 v95, v[110:113] offset:32256
	s_waitcnt lgkmcnt(7)
	v_mfma_f32_16x16x32_bf16 v[34:37], v[196:199], v[228:231], v[34:37]
	v_mfma_f32_16x16x32_bf16 v[38:41], v[196:199], v[232:235], v[38:41]
	v_mfma_f32_16x16x32_bf16 v[2:5], v[196:199], v[236:239], v[2:5]
	v_mfma_f32_16x16x32_bf16 v[6:9], v[196:199], v[240:243], v[6:9]
	s_waitcnt vmcnt(11)
	ds_write_b128 v95, v[114:117] offset:55296
	s_waitcnt vmcnt(10)
	ds_write_b128 v95, v[118:121] offset:59904
	s_waitcnt lgkmcnt(8)
	v_mfma_f32_16x16x32_bf16 v[42:45], v[200:203], v[228:231], v[42:45]
	v_mfma_f32_16x16x32_bf16 v[46:49], v[200:203], v[232:235], v[46:49]
	v_mfma_f32_16x16x32_bf16 v[10:13], v[200:203], v[236:239], v[10:13]
	v_mfma_f32_16x16x32_bf16 v[14:17], v[200:203], v[240:243], v[14:17]
	s_waitcnt vmcnt(9)
	ds_write_b128 v95, v[122:125] offset:64512
	s_waitcnt vmcnt(8)
	ds_write_b128 v96, v[126:129] offset:32256
	s_waitcnt lgkmcnt(0)
	s_barrier
	s_setprio 0
	ds_read_b128 v[212:215], v245 offset:55296
	ds_read_b128 v[196:199], v244 offset:18432
	ds_read_b128 v[216:219], v245 offset:57600
	ds_read_b128 v[220:223], v245 offset:59904
	ds_read_b128 v[224:227], v245 offset:62208
	ds_read_b128 v[200:203], v244 offset:20736
	v_mfma_f32_16x16x32_bf16 v[50:53], v[204:207], v[228:231], v[50:53]
	v_mfma_f32_16x16x32_bf16 v[54:57], v[204:207], v[232:235], v[54:57]
	v_mfma_f32_16x16x32_bf16 v[18:21], v[204:207], v[236:239], v[18:21]
	v_mfma_f32_16x16x32_bf16 v[22:25], v[204:207], v[240:243], v[22:25]
	ds_read_b128 v[204:207], v244 offset:23040
	v_mfma_f32_16x16x32_bf16 v[58:61], v[208:211], v[228:231], v[58:61]
	v_mfma_f32_16x16x32_bf16 v[62:65], v[208:211], v[232:235], v[62:65]
	v_mfma_f32_16x16x32_bf16 v[26:29], v[208:211], v[236:239], v[26:29]
	v_mfma_f32_16x16x32_bf16 v[30:33], v[208:211], v[240:243], v[30:33]
	ds_read_b128 v[208:211], v244 offset:25344
	global_load_dwordx4 v[98:101], v[72:73], off offset:640
	global_load_dwordx4 v[102:105], v[74:75], off offset:640
	global_load_dwordx4 v[106:109], v[76:77], off offset:640
	global_load_dwordx4 v[110:113], v[78:79], off offset:640
	global_load_dwordx4 v[114:117], v[80:81], off offset:640
	global_load_dwordx4 v[118:121], v[82:83], off offset:640
	global_load_dwordx4 v[122:125], v[84:85], off offset:640
	global_load_dwordx4 v[126:129], v[86:87], off offset:640
	s_waitcnt lgkmcnt(6)
	v_mfma_f32_16x16x32_bf16 v[34:37], v[196:199], v[212:215], v[34:37]
	ds_read_b128 v[228:231], v245 offset:55360
	s_waitcnt lgkmcnt(6)
	v_mfma_f32_16x16x32_bf16 v[38:41], v[196:199], v[216:219], v[38:41]
	ds_read_b128 v[232:235], v245 offset:57664
	s_waitcnt lgkmcnt(6)
	v_mfma_f32_16x16x32_bf16 v[2:5], v[196:199], v[220:223], v[2:5]
	ds_read_b128 v[236:239], v245 offset:59968
	s_waitcnt lgkmcnt(6)
	v_mfma_f32_16x16x32_bf16 v[6:9], v[196:199], v[224:227], v[6:9]
	ds_read_b128 v[240:243], v245 offset:62272
	ds_read_b128 v[196:199], v244 offset:18496
	s_waitcnt lgkmcnt(7)
	v_mfma_f32_16x16x32_bf16 v[42:45], v[200:203], v[212:215], v[42:45]
	v_mfma_f32_16x16x32_bf16 v[46:49], v[200:203], v[216:219], v[46:49]
	v_mfma_f32_16x16x32_bf16 v[10:13], v[200:203], v[220:223], v[10:13]
	v_mfma_f32_16x16x32_bf16 v[14:17], v[200:203], v[224:227], v[14:17]
	ds_read_b128 v[200:203], v244 offset:20800
	s_waitcnt lgkmcnt(7)
	v_mfma_f32_16x16x32_bf16 v[50:53], v[204:207], v[212:215], v[50:53]
	v_mfma_f32_16x16x32_bf16 v[54:57], v[204:207], v[216:219], v[54:57]
	v_mfma_f32_16x16x32_bf16 v[18:21], v[204:207], v[220:223], v[18:21]
	v_mfma_f32_16x16x32_bf16 v[22:25], v[204:207], v[224:227], v[22:25]
	ds_read_b128 v[204:207], v244 offset:23104
	s_setprio 1
	s_waitcnt vmcnt(15)
	ds_write_b128 v95, v[132:135]
	s_waitcnt vmcnt(14)
	ds_write_b128 v95, v[136:139] offset:4608
	s_waitcnt lgkmcnt(9)
	v_mfma_f32_16x16x32_bf16 v[58:61], v[208:211], v[212:215], v[58:61]
	v_mfma_f32_16x16x32_bf16 v[62:65], v[208:211], v[216:219], v[62:65]
	v_mfma_f32_16x16x32_bf16 v[26:29], v[208:211], v[220:223], v[26:29]
	v_mfma_f32_16x16x32_bf16 v[30:33], v[208:211], v[224:227], v[30:33]
	ds_read_b128 v[208:211], v244 offset:25408
	s_waitcnt vmcnt(13)
	ds_write_b128 v95, v[140:143] offset:9216
	s_waitcnt vmcnt(12)
	ds_write_b128 v95, v[144:147] offset:13824
	s_waitcnt lgkmcnt(7)
	v_mfma_f32_16x16x32_bf16 v[34:37], v[196:199], v[228:231], v[34:37]
	v_mfma_f32_16x16x32_bf16 v[38:41], v[196:199], v[232:235], v[38:41]
	v_mfma_f32_16x16x32_bf16 v[2:5], v[196:199], v[236:239], v[2:5]
	v_mfma_f32_16x16x32_bf16 v[6:9], v[196:199], v[240:243], v[6:9]
	s_waitcnt vmcnt(11)
	ds_write_b128 v95, v[148:151] offset:36864
	s_waitcnt vmcnt(10)
	ds_write_b128 v95, v[152:155] offset:41472
	s_waitcnt lgkmcnt(8)
	v_mfma_f32_16x16x32_bf16 v[42:45], v[200:203], v[228:231], v[42:45]
	v_mfma_f32_16x16x32_bf16 v[46:49], v[200:203], v[232:235], v[46:49]
	v_mfma_f32_16x16x32_bf16 v[10:13], v[200:203], v[236:239], v[10:13]
	v_mfma_f32_16x16x32_bf16 v[14:17], v[200:203], v[240:243], v[14:17]
	s_waitcnt vmcnt(9)
	ds_write_b128 v95, v[156:159] offset:46080
	s_waitcnt vmcnt(8)
	ds_write_b128 v95, v[160:163] offset:50688
	s_waitcnt lgkmcnt(0)
	s_barrier
	s_setprio 0
	ds_read_b128 v[212:215], v245 offset:36864
	ds_read_b128 v[196:199], v244
	ds_read_b128 v[216:219], v245 offset:39168
	ds_read_b128 v[220:223], v245 offset:41472
	ds_read_b128 v[224:227], v245 offset:43776
	ds_read_b128 v[200:203], v244 offset:2304
	v_mfma_f32_16x16x32_bf16 v[50:53], v[204:207], v[228:231], v[50:53]
	v_mfma_f32_16x16x32_bf16 v[54:57], v[204:207], v[232:235], v[54:57]
	v_mfma_f32_16x16x32_bf16 v[18:21], v[204:207], v[236:239], v[18:21]
	v_mfma_f32_16x16x32_bf16 v[22:25], v[204:207], v[240:243], v[22:25]
	ds_read_b128 v[204:207], v244 offset:4608
	v_mfma_f32_16x16x32_bf16 v[58:61], v[208:211], v[228:231], v[58:61]
	v_mfma_f32_16x16x32_bf16 v[62:65], v[208:211], v[232:235], v[62:65]
	v_mfma_f32_16x16x32_bf16 v[26:29], v[208:211], v[236:239], v[26:29]
	v_mfma_f32_16x16x32_bf16 v[30:33], v[208:211], v[240:243], v[30:33]
	ds_read_b128 v[208:211], v244 offset:6912
	global_load_dwordx4 v[132:135], v[72:73], off offset:768
	global_load_dwordx4 v[136:139], v[74:75], off offset:768
	global_load_dwordx4 v[140:143], v[76:77], off offset:768
	global_load_dwordx4 v[144:147], v[78:79], off offset:768
	global_load_dwordx4 v[148:151], v[80:81], off offset:768
	global_load_dwordx4 v[152:155], v[82:83], off offset:768
	global_load_dwordx4 v[156:159], v[84:85], off offset:768
	global_load_dwordx4 v[160:163], v[86:87], off offset:768
	s_waitcnt lgkmcnt(6)
	v_mfma_f32_16x16x32_bf16 v[34:37], v[196:199], v[212:215], v[34:37]
	ds_read_b128 v[228:231], v245 offset:36928
	s_waitcnt lgkmcnt(6)
	v_mfma_f32_16x16x32_bf16 v[38:41], v[196:199], v[216:219], v[38:41]
	ds_read_b128 v[232:235], v245 offset:39232
	s_waitcnt lgkmcnt(6)
	v_mfma_f32_16x16x32_bf16 v[2:5], v[196:199], v[220:223], v[2:5]
	ds_read_b128 v[236:239], v245 offset:41536
	s_waitcnt lgkmcnt(6)
	v_mfma_f32_16x16x32_bf16 v[6:9], v[196:199], v[224:227], v[6:9]
	ds_read_b128 v[240:243], v245 offset:43840
	ds_read_b128 v[196:199], v244 offset:64
	s_waitcnt lgkmcnt(7)
	v_mfma_f32_16x16x32_bf16 v[42:45], v[200:203], v[212:215], v[42:45]
	v_mfma_f32_16x16x32_bf16 v[46:49], v[200:203], v[216:219], v[46:49]
	v_mfma_f32_16x16x32_bf16 v[10:13], v[200:203], v[220:223], v[10:13]
	v_mfma_f32_16x16x32_bf16 v[14:17], v[200:203], v[224:227], v[14:17]
	ds_read_b128 v[200:203], v244 offset:2368
	s_waitcnt lgkmcnt(7)
	v_mfma_f32_16x16x32_bf16 v[50:53], v[204:207], v[212:215], v[50:53]
	v_mfma_f32_16x16x32_bf16 v[54:57], v[204:207], v[216:219], v[54:57]
	v_mfma_f32_16x16x32_bf16 v[18:21], v[204:207], v[220:223], v[18:21]
	v_mfma_f32_16x16x32_bf16 v[22:25], v[204:207], v[224:227], v[22:25]
	ds_read_b128 v[204:207], v244 offset:4672
	s_setprio 1
	s_waitcnt vmcnt(15)
	ds_write_b128 v95, v[98:101] offset:18432
	s_waitcnt vmcnt(14)
	ds_write_b128 v95, v[102:105] offset:23040
	s_waitcnt lgkmcnt(9)
	v_mfma_f32_16x16x32_bf16 v[58:61], v[208:211], v[212:215], v[58:61]
	v_mfma_f32_16x16x32_bf16 v[62:65], v[208:211], v[216:219], v[62:65]
	v_mfma_f32_16x16x32_bf16 v[26:29], v[208:211], v[220:223], v[26:29]
	v_mfma_f32_16x16x32_bf16 v[30:33], v[208:211], v[224:227], v[30:33]
	ds_read_b128 v[208:211], v244 offset:6976
	s_waitcnt vmcnt(13)
	ds_write_b128 v95, v[106:109] offset:27648
	s_waitcnt vmcnt(12)
	ds_write_b128 v95, v[110:113] offset:32256
	s_waitcnt lgkmcnt(7)
	v_mfma_f32_16x16x32_bf16 v[34:37], v[196:199], v[228:231], v[34:37]
	v_mfma_f32_16x16x32_bf16 v[38:41], v[196:199], v[232:235], v[38:41]
	v_mfma_f32_16x16x32_bf16 v[2:5], v[196:199], v[236:239], v[2:5]
	v_mfma_f32_16x16x32_bf16 v[6:9], v[196:199], v[240:243], v[6:9]
	s_waitcnt vmcnt(11)
	ds_write_b128 v95, v[114:117] offset:55296
	s_waitcnt vmcnt(10)
	ds_write_b128 v95, v[118:121] offset:59904
	s_waitcnt lgkmcnt(8)
	v_mfma_f32_16x16x32_bf16 v[42:45], v[200:203], v[228:231], v[42:45]
	v_mfma_f32_16x16x32_bf16 v[46:49], v[200:203], v[232:235], v[46:49]
	v_mfma_f32_16x16x32_bf16 v[10:13], v[200:203], v[236:239], v[10:13]
	v_mfma_f32_16x16x32_bf16 v[14:17], v[200:203], v[240:243], v[14:17]
	s_waitcnt vmcnt(9)
	ds_write_b128 v95, v[122:125] offset:64512
	s_waitcnt vmcnt(8)
	ds_write_b128 v96, v[126:129] offset:32256
	s_waitcnt lgkmcnt(0)
	s_barrier
	s_setprio 0
	ds_read_b128 v[212:215], v245 offset:55296
	ds_read_b128 v[196:199], v244 offset:18432
	ds_read_b128 v[216:219], v245 offset:57600
	ds_read_b128 v[220:223], v245 offset:59904
	ds_read_b128 v[224:227], v245 offset:62208
	ds_read_b128 v[200:203], v244 offset:20736
	v_mfma_f32_16x16x32_bf16 v[50:53], v[204:207], v[228:231], v[50:53]
	v_mfma_f32_16x16x32_bf16 v[54:57], v[204:207], v[232:235], v[54:57]
	v_mfma_f32_16x16x32_bf16 v[18:21], v[204:207], v[236:239], v[18:21]
	v_mfma_f32_16x16x32_bf16 v[22:25], v[204:207], v[240:243], v[22:25]
	ds_read_b128 v[204:207], v244 offset:23040
	v_mfma_f32_16x16x32_bf16 v[58:61], v[208:211], v[228:231], v[58:61]
	v_mfma_f32_16x16x32_bf16 v[62:65], v[208:211], v[232:235], v[62:65]
	v_mfma_f32_16x16x32_bf16 v[26:29], v[208:211], v[236:239], v[26:29]
	v_mfma_f32_16x16x32_bf16 v[30:33], v[208:211], v[240:243], v[30:33]
	ds_read_b128 v[208:211], v244 offset:25344
	global_load_dwordx4 v[98:101], v[72:73], off offset:896
	global_load_dwordx4 v[102:105], v[74:75], off offset:896
	global_load_dwordx4 v[106:109], v[76:77], off offset:896
	global_load_dwordx4 v[110:113], v[78:79], off offset:896
	global_load_dwordx4 v[114:117], v[80:81], off offset:896
	global_load_dwordx4 v[118:121], v[82:83], off offset:896
	global_load_dwordx4 v[122:125], v[84:85], off offset:896
	global_load_dwordx4 v[126:129], v[86:87], off offset:896
	s_waitcnt lgkmcnt(6)
	v_mfma_f32_16x16x32_bf16 v[34:37], v[196:199], v[212:215], v[34:37]
	ds_read_b128 v[228:231], v245 offset:55360
	s_waitcnt lgkmcnt(6)
	v_mfma_f32_16x16x32_bf16 v[38:41], v[196:199], v[216:219], v[38:41]
	ds_read_b128 v[232:235], v245 offset:57664
	s_waitcnt lgkmcnt(6)
	v_mfma_f32_16x16x32_bf16 v[2:5], v[196:199], v[220:223], v[2:5]
	ds_read_b128 v[236:239], v245 offset:59968
	s_waitcnt lgkmcnt(6)
	v_mfma_f32_16x16x32_bf16 v[6:9], v[196:199], v[224:227], v[6:9]
	ds_read_b128 v[240:243], v245 offset:62272
	ds_read_b128 v[196:199], v244 offset:18496
	s_waitcnt lgkmcnt(7)
	v_mfma_f32_16x16x32_bf16 v[42:45], v[200:203], v[212:215], v[42:45]
	v_mfma_f32_16x16x32_bf16 v[46:49], v[200:203], v[216:219], v[46:49]
	v_mfma_f32_16x16x32_bf16 v[10:13], v[200:203], v[220:223], v[10:13]
	v_mfma_f32_16x16x32_bf16 v[14:17], v[200:203], v[224:227], v[14:17]
	ds_read_b128 v[200:203], v244 offset:20800
	s_waitcnt lgkmcnt(7)
	v_mfma_f32_16x16x32_bf16 v[50:53], v[204:207], v[212:215], v[50:53]
	v_mfma_f32_16x16x32_bf16 v[54:57], v[204:207], v[216:219], v[54:57]
	v_mfma_f32_16x16x32_bf16 v[18:21], v[204:207], v[220:223], v[18:21]
	v_mfma_f32_16x16x32_bf16 v[22:25], v[204:207], v[224:227], v[22:25]
	ds_read_b128 v[204:207], v244 offset:23104
	s_setprio 1
	s_waitcnt vmcnt(15)
	ds_write_b128 v95, v[132:135]
	s_waitcnt vmcnt(14)
	ds_write_b128 v95, v[136:139] offset:4608
	s_waitcnt lgkmcnt(9)
	v_mfma_f32_16x16x32_bf16 v[58:61], v[208:211], v[212:215], v[58:61]
	v_mfma_f32_16x16x32_bf16 v[62:65], v[208:211], v[216:219], v[62:65]
	v_mfma_f32_16x16x32_bf16 v[26:29], v[208:211], v[220:223], v[26:29]
	v_mfma_f32_16x16x32_bf16 v[30:33], v[208:211], v[224:227], v[30:33]
	ds_read_b128 v[208:211], v244 offset:25408
	s_waitcnt vmcnt(13)
	ds_write_b128 v95, v[140:143] offset:9216
	s_waitcnt vmcnt(12)
	ds_write_b128 v95, v[144:147] offset:13824
	s_waitcnt lgkmcnt(7)
	v_mfma_f32_16x16x32_bf16 v[34:37], v[196:199], v[228:231], v[34:37]
	v_mfma_f32_16x16x32_bf16 v[38:41], v[196:199], v[232:235], v[38:41]
	v_mfma_f32_16x16x32_bf16 v[2:5], v[196:199], v[236:239], v[2:5]
	v_mfma_f32_16x16x32_bf16 v[6:9], v[196:199], v[240:243], v[6:9]
	s_waitcnt vmcnt(11)
	ds_write_b128 v95, v[148:151] offset:36864
	s_waitcnt vmcnt(10)
	ds_write_b128 v95, v[152:155] offset:41472
	s_waitcnt lgkmcnt(8)
	v_mfma_f32_16x16x32_bf16 v[42:45], v[200:203], v[228:231], v[42:45]
	v_mfma_f32_16x16x32_bf16 v[46:49], v[200:203], v[232:235], v[46:49]
	v_mfma_f32_16x16x32_bf16 v[10:13], v[200:203], v[236:239], v[10:13]
	v_mfma_f32_16x16x32_bf16 v[14:17], v[200:203], v[240:243], v[14:17]
	s_waitcnt vmcnt(9)
	ds_write_b128 v95, v[156:159] offset:46080
	s_waitcnt vmcnt(8)
	ds_write_b128 v95, v[160:163] offset:50688
	s_waitcnt lgkmcnt(0)
	s_barrier
	s_setprio 0
	ds_read_b128 v[212:215], v245 offset:36864
	ds_read_b128 v[196:199], v244
	ds_read_b128 v[216:219], v245 offset:39168
	ds_read_b128 v[220:223], v245 offset:41472
	ds_read_b128 v[224:227], v245 offset:43776
	ds_read_b128 v[200:203], v244 offset:2304
	v_mfma_f32_16x16x32_bf16 v[50:53], v[204:207], v[228:231], v[50:53]
	v_mfma_f32_16x16x32_bf16 v[54:57], v[204:207], v[232:235], v[54:57]
	v_mfma_f32_16x16x32_bf16 v[18:21], v[204:207], v[236:239], v[18:21]
	v_mfma_f32_16x16x32_bf16 v[22:25], v[204:207], v[240:243], v[22:25]
	ds_read_b128 v[204:207], v244 offset:4608
	v_mfma_f32_16x16x32_bf16 v[58:61], v[208:211], v[228:231], v[58:61]
	v_mfma_f32_16x16x32_bf16 v[62:65], v[208:211], v[232:235], v[62:65]
	v_mfma_f32_16x16x32_bf16 v[26:29], v[208:211], v[236:239], v[26:29]
	v_mfma_f32_16x16x32_bf16 v[30:33], v[208:211], v[240:243], v[30:33]
	ds_read_b128 v[208:211], v244 offset:6912
	global_load_dwordx4 v[132:135], v[72:73], off offset:1024
	global_load_dwordx4 v[136:139], v[74:75], off offset:1024
	global_load_dwordx4 v[140:143], v[76:77], off offset:1024
	global_load_dwordx4 v[144:147], v[78:79], off offset:1024
	global_load_dwordx4 v[148:151], v[80:81], off offset:1024
	global_load_dwordx4 v[152:155], v[82:83], off offset:1024
	global_load_dwordx4 v[156:159], v[84:85], off offset:1024
	global_load_dwordx4 v[160:163], v[86:87], off offset:1024
	s_waitcnt lgkmcnt(6)
	v_mfma_f32_16x16x32_bf16 v[34:37], v[196:199], v[212:215], v[34:37]
	ds_read_b128 v[228:231], v245 offset:36928
	s_waitcnt lgkmcnt(6)
	v_mfma_f32_16x16x32_bf16 v[38:41], v[196:199], v[216:219], v[38:41]
	ds_read_b128 v[232:235], v245 offset:39232
	s_waitcnt lgkmcnt(6)
	v_mfma_f32_16x16x32_bf16 v[2:5], v[196:199], v[220:223], v[2:5]
	ds_read_b128 v[236:239], v245 offset:41536
	s_waitcnt lgkmcnt(6)
	v_mfma_f32_16x16x32_bf16 v[6:9], v[196:199], v[224:227], v[6:9]
	ds_read_b128 v[240:243], v245 offset:43840
	ds_read_b128 v[196:199], v244 offset:64
	s_waitcnt lgkmcnt(7)
	v_mfma_f32_16x16x32_bf16 v[42:45], v[200:203], v[212:215], v[42:45]
	v_mfma_f32_16x16x32_bf16 v[46:49], v[200:203], v[216:219], v[46:49]
	v_mfma_f32_16x16x32_bf16 v[10:13], v[200:203], v[220:223], v[10:13]
	v_mfma_f32_16x16x32_bf16 v[14:17], v[200:203], v[224:227], v[14:17]
	ds_read_b128 v[200:203], v244 offset:2368
	s_waitcnt lgkmcnt(7)
	v_mfma_f32_16x16x32_bf16 v[50:53], v[204:207], v[212:215], v[50:53]
	v_mfma_f32_16x16x32_bf16 v[54:57], v[204:207], v[216:219], v[54:57]
	v_mfma_f32_16x16x32_bf16 v[18:21], v[204:207], v[220:223], v[18:21]
	v_mfma_f32_16x16x32_bf16 v[22:25], v[204:207], v[224:227], v[22:25]
	ds_read_b128 v[204:207], v244 offset:4672
	s_setprio 1
	s_waitcnt vmcnt(15)
	ds_write_b128 v95, v[98:101] offset:18432
	s_waitcnt vmcnt(14)
	ds_write_b128 v95, v[102:105] offset:23040
	s_waitcnt lgkmcnt(9)
	v_mfma_f32_16x16x32_bf16 v[58:61], v[208:211], v[212:215], v[58:61]
	v_mfma_f32_16x16x32_bf16 v[62:65], v[208:211], v[216:219], v[62:65]
	v_mfma_f32_16x16x32_bf16 v[26:29], v[208:211], v[220:223], v[26:29]
	v_mfma_f32_16x16x32_bf16 v[30:33], v[208:211], v[224:227], v[30:33]
	ds_read_b128 v[208:211], v244 offset:6976
	s_waitcnt vmcnt(13)
	ds_write_b128 v95, v[106:109] offset:27648
	s_waitcnt vmcnt(12)
	ds_write_b128 v95, v[110:113] offset:32256
	s_waitcnt lgkmcnt(7)
	v_mfma_f32_16x16x32_bf16 v[34:37], v[196:199], v[228:231], v[34:37]
	v_mfma_f32_16x16x32_bf16 v[38:41], v[196:199], v[232:235], v[38:41]
	v_mfma_f32_16x16x32_bf16 v[2:5], v[196:199], v[236:239], v[2:5]
	v_mfma_f32_16x16x32_bf16 v[6:9], v[196:199], v[240:243], v[6:9]
	s_waitcnt vmcnt(11)
	ds_write_b128 v95, v[114:117] offset:55296
	s_waitcnt vmcnt(10)
	ds_write_b128 v95, v[118:121] offset:59904
	s_waitcnt lgkmcnt(8)
	v_mfma_f32_16x16x32_bf16 v[42:45], v[200:203], v[228:231], v[42:45]
	v_mfma_f32_16x16x32_bf16 v[46:49], v[200:203], v[232:235], v[46:49]
	v_mfma_f32_16x16x32_bf16 v[10:13], v[200:203], v[236:239], v[10:13]
	v_mfma_f32_16x16x32_bf16 v[14:17], v[200:203], v[240:243], v[14:17]
	s_waitcnt vmcnt(9)
	ds_write_b128 v95, v[122:125] offset:64512
	s_waitcnt vmcnt(8)
	ds_write_b128 v96, v[126:129] offset:32256
	s_waitcnt lgkmcnt(0)
	s_barrier
	s_setprio 0
	ds_read_b128 v[212:215], v245 offset:55296
	ds_read_b128 v[196:199], v244 offset:18432
	ds_read_b128 v[216:219], v245 offset:57600
	ds_read_b128 v[220:223], v245 offset:59904
	ds_read_b128 v[224:227], v245 offset:62208
	ds_read_b128 v[200:203], v244 offset:20736
	v_mfma_f32_16x16x32_bf16 v[50:53], v[204:207], v[228:231], v[50:53]
	v_mfma_f32_16x16x32_bf16 v[54:57], v[204:207], v[232:235], v[54:57]
	v_mfma_f32_16x16x32_bf16 v[18:21], v[204:207], v[236:239], v[18:21]
	v_mfma_f32_16x16x32_bf16 v[22:25], v[204:207], v[240:243], v[22:25]
	ds_read_b128 v[204:207], v244 offset:23040
	v_mfma_f32_16x16x32_bf16 v[58:61], v[208:211], v[228:231], v[58:61]
	v_mfma_f32_16x16x32_bf16 v[62:65], v[208:211], v[232:235], v[62:65]
	v_mfma_f32_16x16x32_bf16 v[26:29], v[208:211], v[236:239], v[26:29]
	v_mfma_f32_16x16x32_bf16 v[30:33], v[208:211], v[240:243], v[30:33]
	ds_read_b128 v[208:211], v244 offset:25344
	global_load_dwordx4 v[98:101], v[72:73], off offset:1152
	global_load_dwordx4 v[102:105], v[74:75], off offset:1152
	global_load_dwordx4 v[106:109], v[76:77], off offset:1152
	global_load_dwordx4 v[110:113], v[78:79], off offset:1152
	global_load_dwordx4 v[114:117], v[80:81], off offset:1152
	global_load_dwordx4 v[118:121], v[82:83], off offset:1152
	global_load_dwordx4 v[122:125], v[84:85], off offset:1152
	global_load_dwordx4 v[126:129], v[86:87], off offset:1152
	s_waitcnt lgkmcnt(6)
	v_mfma_f32_16x16x32_bf16 v[34:37], v[196:199], v[212:215], v[34:37]
	ds_read_b128 v[228:231], v245 offset:55360
	s_waitcnt lgkmcnt(6)
	v_mfma_f32_16x16x32_bf16 v[38:41], v[196:199], v[216:219], v[38:41]
	ds_read_b128 v[232:235], v245 offset:57664
	s_waitcnt lgkmcnt(6)
	v_mfma_f32_16x16x32_bf16 v[2:5], v[196:199], v[220:223], v[2:5]
	ds_read_b128 v[236:239], v245 offset:59968
	s_waitcnt lgkmcnt(6)
	v_mfma_f32_16x16x32_bf16 v[6:9], v[196:199], v[224:227], v[6:9]
	ds_read_b128 v[240:243], v245 offset:62272
	ds_read_b128 v[196:199], v244 offset:18496
	s_waitcnt lgkmcnt(7)
	v_mfma_f32_16x16x32_bf16 v[42:45], v[200:203], v[212:215], v[42:45]
	v_mfma_f32_16x16x32_bf16 v[46:49], v[200:203], v[216:219], v[46:49]
	v_mfma_f32_16x16x32_bf16 v[10:13], v[200:203], v[220:223], v[10:13]
	v_mfma_f32_16x16x32_bf16 v[14:17], v[200:203], v[224:227], v[14:17]
	ds_read_b128 v[200:203], v244 offset:20800
	s_waitcnt lgkmcnt(7)
	v_mfma_f32_16x16x32_bf16 v[50:53], v[204:207], v[212:215], v[50:53]
	v_mfma_f32_16x16x32_bf16 v[54:57], v[204:207], v[216:219], v[54:57]
	v_mfma_f32_16x16x32_bf16 v[18:21], v[204:207], v[220:223], v[18:21]
	v_mfma_f32_16x16x32_bf16 v[22:25], v[204:207], v[224:227], v[22:25]
	ds_read_b128 v[204:207], v244 offset:23104
	s_setprio 1
	s_waitcnt vmcnt(15)
	ds_write_b128 v95, v[132:135]
	s_waitcnt vmcnt(14)
	ds_write_b128 v95, v[136:139] offset:4608
	s_waitcnt lgkmcnt(9)
	v_mfma_f32_16x16x32_bf16 v[58:61], v[208:211], v[212:215], v[58:61]
	v_mfma_f32_16x16x32_bf16 v[62:65], v[208:211], v[216:219], v[62:65]
	v_mfma_f32_16x16x32_bf16 v[26:29], v[208:211], v[220:223], v[26:29]
	v_mfma_f32_16x16x32_bf16 v[30:33], v[208:211], v[224:227], v[30:33]
	ds_read_b128 v[208:211], v244 offset:25408
	s_waitcnt vmcnt(13)
	ds_write_b128 v95, v[140:143] offset:9216
	s_waitcnt vmcnt(12)
	ds_write_b128 v95, v[144:147] offset:13824
	s_waitcnt lgkmcnt(7)
	v_mfma_f32_16x16x32_bf16 v[34:37], v[196:199], v[228:231], v[34:37]
	v_mfma_f32_16x16x32_bf16 v[38:41], v[196:199], v[232:235], v[38:41]
	v_mfma_f32_16x16x32_bf16 v[2:5], v[196:199], v[236:239], v[2:5]
	v_mfma_f32_16x16x32_bf16 v[6:9], v[196:199], v[240:243], v[6:9]
	s_waitcnt vmcnt(11)
	ds_write_b128 v95, v[148:151] offset:36864
	s_waitcnt vmcnt(10)
	ds_write_b128 v95, v[152:155] offset:41472
	s_waitcnt lgkmcnt(8)
	v_mfma_f32_16x16x32_bf16 v[42:45], v[200:203], v[228:231], v[42:45]
	v_mfma_f32_16x16x32_bf16 v[46:49], v[200:203], v[232:235], v[46:49]
	v_mfma_f32_16x16x32_bf16 v[10:13], v[200:203], v[236:239], v[10:13]
	v_mfma_f32_16x16x32_bf16 v[14:17], v[200:203], v[240:243], v[14:17]
	s_waitcnt vmcnt(9)
	ds_write_b128 v95, v[156:159] offset:46080
	s_waitcnt vmcnt(8)
	ds_write_b128 v95, v[160:163] offset:50688
	s_waitcnt lgkmcnt(0)
	s_barrier
	s_setprio 0
	ds_read_b128 v[212:215], v245 offset:36864
	ds_read_b128 v[196:199], v244
	ds_read_b128 v[216:219], v245 offset:39168
	ds_read_b128 v[220:223], v245 offset:41472
	ds_read_b128 v[224:227], v245 offset:43776
	ds_read_b128 v[200:203], v244 offset:2304
	v_mfma_f32_16x16x32_bf16 v[50:53], v[204:207], v[228:231], v[50:53]
	v_mfma_f32_16x16x32_bf16 v[54:57], v[204:207], v[232:235], v[54:57]
	v_mfma_f32_16x16x32_bf16 v[18:21], v[204:207], v[236:239], v[18:21]
	v_mfma_f32_16x16x32_bf16 v[22:25], v[204:207], v[240:243], v[22:25]
	ds_read_b128 v[204:207], v244 offset:4608
	v_mfma_f32_16x16x32_bf16 v[58:61], v[208:211], v[228:231], v[58:61]
	v_mfma_f32_16x16x32_bf16 v[62:65], v[208:211], v[232:235], v[62:65]
	v_mfma_f32_16x16x32_bf16 v[26:29], v[208:211], v[236:239], v[26:29]
	v_mfma_f32_16x16x32_bf16 v[30:33], v[208:211], v[240:243], v[30:33]
	ds_read_b128 v[208:211], v244 offset:6912
	global_load_dwordx4 v[132:135], v[72:73], off offset:1280
	global_load_dwordx4 v[136:139], v[74:75], off offset:1280
	global_load_dwordx4 v[140:143], v[76:77], off offset:1280
	global_load_dwordx4 v[144:147], v[78:79], off offset:1280
	global_load_dwordx4 v[148:151], v[80:81], off offset:1280
	global_load_dwordx4 v[152:155], v[82:83], off offset:1280
	global_load_dwordx4 v[156:159], v[84:85], off offset:1280
	global_load_dwordx4 v[160:163], v[86:87], off offset:1280
	s_waitcnt lgkmcnt(6)
	v_mfma_f32_16x16x32_bf16 v[34:37], v[196:199], v[212:215], v[34:37]
	ds_read_b128 v[228:231], v245 offset:36928
	s_waitcnt lgkmcnt(6)
	v_mfma_f32_16x16x32_bf16 v[38:41], v[196:199], v[216:219], v[38:41]
	ds_read_b128 v[232:235], v245 offset:39232
	s_waitcnt lgkmcnt(6)
	v_mfma_f32_16x16x32_bf16 v[2:5], v[196:199], v[220:223], v[2:5]
	ds_read_b128 v[236:239], v245 offset:41536
	s_waitcnt lgkmcnt(6)
	v_mfma_f32_16x16x32_bf16 v[6:9], v[196:199], v[224:227], v[6:9]
	ds_read_b128 v[240:243], v245 offset:43840
	ds_read_b128 v[196:199], v244 offset:64
	s_waitcnt lgkmcnt(7)
	v_mfma_f32_16x16x32_bf16 v[42:45], v[200:203], v[212:215], v[42:45]
	v_mfma_f32_16x16x32_bf16 v[46:49], v[200:203], v[216:219], v[46:49]
	v_mfma_f32_16x16x32_bf16 v[10:13], v[200:203], v[220:223], v[10:13]
	v_mfma_f32_16x16x32_bf16 v[14:17], v[200:203], v[224:227], v[14:17]
	ds_read_b128 v[200:203], v244 offset:2368
	s_waitcnt lgkmcnt(7)
	v_mfma_f32_16x16x32_bf16 v[50:53], v[204:207], v[212:215], v[50:53]
	v_mfma_f32_16x16x32_bf16 v[54:57], v[204:207], v[216:219], v[54:57]
	v_mfma_f32_16x16x32_bf16 v[18:21], v[204:207], v[220:223], v[18:21]
	v_mfma_f32_16x16x32_bf16 v[22:25], v[204:207], v[224:227], v[22:25]
	ds_read_b128 v[204:207], v244 offset:4672
	s_setprio 1
	s_waitcnt vmcnt(15)
	ds_write_b128 v95, v[98:101] offset:18432
	s_waitcnt vmcnt(14)
	ds_write_b128 v95, v[102:105] offset:23040
	s_waitcnt lgkmcnt(9)
	v_mfma_f32_16x16x32_bf16 v[58:61], v[208:211], v[212:215], v[58:61]
	v_mfma_f32_16x16x32_bf16 v[62:65], v[208:211], v[216:219], v[62:65]
	v_mfma_f32_16x16x32_bf16 v[26:29], v[208:211], v[220:223], v[26:29]
	v_mfma_f32_16x16x32_bf16 v[30:33], v[208:211], v[224:227], v[30:33]
	ds_read_b128 v[208:211], v244 offset:6976
	s_waitcnt vmcnt(13)
	ds_write_b128 v95, v[106:109] offset:27648
	s_waitcnt vmcnt(12)
	ds_write_b128 v95, v[110:113] offset:32256
	s_waitcnt lgkmcnt(7)
	v_mfma_f32_16x16x32_bf16 v[34:37], v[196:199], v[228:231], v[34:37]
	v_mfma_f32_16x16x32_bf16 v[38:41], v[196:199], v[232:235], v[38:41]
	v_mfma_f32_16x16x32_bf16 v[2:5], v[196:199], v[236:239], v[2:5]
	v_mfma_f32_16x16x32_bf16 v[6:9], v[196:199], v[240:243], v[6:9]
	s_waitcnt vmcnt(11)
	ds_write_b128 v95, v[114:117] offset:55296
	s_waitcnt vmcnt(10)
	ds_write_b128 v95, v[118:121] offset:59904
	s_waitcnt lgkmcnt(8)
	v_mfma_f32_16x16x32_bf16 v[42:45], v[200:203], v[228:231], v[42:45]
	v_mfma_f32_16x16x32_bf16 v[46:49], v[200:203], v[232:235], v[46:49]
	v_mfma_f32_16x16x32_bf16 v[10:13], v[200:203], v[236:239], v[10:13]
	v_mfma_f32_16x16x32_bf16 v[14:17], v[200:203], v[240:243], v[14:17]
	s_waitcnt vmcnt(9)
	ds_write_b128 v95, v[122:125] offset:64512
	s_waitcnt vmcnt(8)
	ds_write_b128 v96, v[126:129] offset:32256
	s_waitcnt lgkmcnt(0)
	s_barrier
	s_setprio 0
	ds_read_b128 v[212:215], v245 offset:55296
	ds_read_b128 v[196:199], v244 offset:18432
	ds_read_b128 v[216:219], v245 offset:57600
	ds_read_b128 v[220:223], v245 offset:59904
	ds_read_b128 v[224:227], v245 offset:62208
	ds_read_b128 v[200:203], v244 offset:20736
	v_mfma_f32_16x16x32_bf16 v[50:53], v[204:207], v[228:231], v[50:53]
	v_mfma_f32_16x16x32_bf16 v[54:57], v[204:207], v[232:235], v[54:57]
	v_mfma_f32_16x16x32_bf16 v[18:21], v[204:207], v[236:239], v[18:21]
	v_mfma_f32_16x16x32_bf16 v[22:25], v[204:207], v[240:243], v[22:25]
	ds_read_b128 v[204:207], v244 offset:23040
	v_mfma_f32_16x16x32_bf16 v[58:61], v[208:211], v[228:231], v[58:61]
	v_mfma_f32_16x16x32_bf16 v[62:65], v[208:211], v[232:235], v[62:65]
	v_mfma_f32_16x16x32_bf16 v[26:29], v[208:211], v[236:239], v[26:29]
	v_mfma_f32_16x16x32_bf16 v[30:33], v[208:211], v[240:243], v[30:33]
	ds_read_b128 v[208:211], v244 offset:25344
	global_load_dwordx4 v[98:101], v[72:73], off offset:1408
	global_load_dwordx4 v[102:105], v[74:75], off offset:1408
	global_load_dwordx4 v[106:109], v[76:77], off offset:1408
	global_load_dwordx4 v[110:113], v[78:79], off offset:1408
	global_load_dwordx4 v[114:117], v[80:81], off offset:1408
	global_load_dwordx4 v[118:121], v[82:83], off offset:1408
	global_load_dwordx4 v[122:125], v[84:85], off offset:1408
	global_load_dwordx4 v[126:129], v[86:87], off offset:1408
	s_waitcnt lgkmcnt(6)
	v_mfma_f32_16x16x32_bf16 v[34:37], v[196:199], v[212:215], v[34:37]
	ds_read_b128 v[228:231], v245 offset:55360
	s_waitcnt lgkmcnt(6)
	v_mfma_f32_16x16x32_bf16 v[38:41], v[196:199], v[216:219], v[38:41]
	ds_read_b128 v[232:235], v245 offset:57664
	s_waitcnt lgkmcnt(6)
	v_mfma_f32_16x16x32_bf16 v[2:5], v[196:199], v[220:223], v[2:5]
	ds_read_b128 v[236:239], v245 offset:59968
	s_waitcnt lgkmcnt(6)
	v_mfma_f32_16x16x32_bf16 v[6:9], v[196:199], v[224:227], v[6:9]
	ds_read_b128 v[240:243], v245 offset:62272
	ds_read_b128 v[196:199], v244 offset:18496
	s_waitcnt lgkmcnt(7)
	v_mfma_f32_16x16x32_bf16 v[42:45], v[200:203], v[212:215], v[42:45]
	v_mfma_f32_16x16x32_bf16 v[46:49], v[200:203], v[216:219], v[46:49]
	v_mfma_f32_16x16x32_bf16 v[10:13], v[200:203], v[220:223], v[10:13]
	v_mfma_f32_16x16x32_bf16 v[14:17], v[200:203], v[224:227], v[14:17]
	ds_read_b128 v[200:203], v244 offset:20800
	s_waitcnt lgkmcnt(7)
	v_mfma_f32_16x16x32_bf16 v[50:53], v[204:207], v[212:215], v[50:53]
	v_mfma_f32_16x16x32_bf16 v[54:57], v[204:207], v[216:219], v[54:57]
	v_mfma_f32_16x16x32_bf16 v[18:21], v[204:207], v[220:223], v[18:21]
	v_mfma_f32_16x16x32_bf16 v[22:25], v[204:207], v[224:227], v[22:25]
	ds_read_b128 v[204:207], v244 offset:23104
	s_setprio 1
	s_waitcnt vmcnt(15)
	ds_write_b128 v95, v[132:135]
	s_waitcnt vmcnt(14)
	ds_write_b128 v95, v[136:139] offset:4608
	s_waitcnt lgkmcnt(9)
	v_mfma_f32_16x16x32_bf16 v[58:61], v[208:211], v[212:215], v[58:61]
	v_mfma_f32_16x16x32_bf16 v[62:65], v[208:211], v[216:219], v[62:65]
	v_mfma_f32_16x16x32_bf16 v[26:29], v[208:211], v[220:223], v[26:29]
	v_mfma_f32_16x16x32_bf16 v[30:33], v[208:211], v[224:227], v[30:33]
	ds_read_b128 v[208:211], v244 offset:25408
	s_waitcnt vmcnt(13)
	ds_write_b128 v95, v[140:143] offset:9216
	s_waitcnt vmcnt(12)
	ds_write_b128 v95, v[144:147] offset:13824
	s_waitcnt lgkmcnt(7)
	v_mfma_f32_16x16x32_bf16 v[34:37], v[196:199], v[228:231], v[34:37]
	v_mfma_f32_16x16x32_bf16 v[38:41], v[196:199], v[232:235], v[38:41]
	v_mfma_f32_16x16x32_bf16 v[2:5], v[196:199], v[236:239], v[2:5]
	v_mfma_f32_16x16x32_bf16 v[6:9], v[196:199], v[240:243], v[6:9]
	s_waitcnt vmcnt(11)
	ds_write_b128 v95, v[148:151] offset:36864
	s_waitcnt vmcnt(10)
	ds_write_b128 v95, v[152:155] offset:41472
	s_waitcnt lgkmcnt(8)
	v_mfma_f32_16x16x32_bf16 v[42:45], v[200:203], v[228:231], v[42:45]
	v_mfma_f32_16x16x32_bf16 v[46:49], v[200:203], v[232:235], v[46:49]
	v_mfma_f32_16x16x32_bf16 v[10:13], v[200:203], v[236:239], v[10:13]
	v_mfma_f32_16x16x32_bf16 v[14:17], v[200:203], v[240:243], v[14:17]
	s_waitcnt vmcnt(9)
	ds_write_b128 v95, v[156:159] offset:46080
	s_waitcnt vmcnt(8)
	ds_write_b128 v95, v[160:163] offset:50688
	s_waitcnt lgkmcnt(0)
	s_barrier
	s_setprio 0
	ds_read_b128 v[212:215], v245 offset:36864
	ds_read_b128 v[196:199], v244
	ds_read_b128 v[216:219], v245 offset:39168
	ds_read_b128 v[220:223], v245 offset:41472
	ds_read_b128 v[224:227], v245 offset:43776
	ds_read_b128 v[200:203], v244 offset:2304
	v_mfma_f32_16x16x32_bf16 v[50:53], v[204:207], v[228:231], v[50:53]
	v_mfma_f32_16x16x32_bf16 v[54:57], v[204:207], v[232:235], v[54:57]
	v_mfma_f32_16x16x32_bf16 v[18:21], v[204:207], v[236:239], v[18:21]
	v_mfma_f32_16x16x32_bf16 v[22:25], v[204:207], v[240:243], v[22:25]
	ds_read_b128 v[204:207], v244 offset:4608
	v_mfma_f32_16x16x32_bf16 v[58:61], v[208:211], v[228:231], v[58:61]
	v_mfma_f32_16x16x32_bf16 v[62:65], v[208:211], v[232:235], v[62:65]
	v_mfma_f32_16x16x32_bf16 v[26:29], v[208:211], v[236:239], v[26:29]
	v_mfma_f32_16x16x32_bf16 v[30:33], v[208:211], v[240:243], v[30:33]
	ds_read_b128 v[208:211], v244 offset:6912
	global_load_dwordx4 v[132:135], v[72:73], off offset:1536
	global_load_dwordx4 v[136:139], v[74:75], off offset:1536
	global_load_dwordx4 v[140:143], v[76:77], off offset:1536
	global_load_dwordx4 v[144:147], v[78:79], off offset:1536
	global_load_dwordx4 v[148:151], v[80:81], off offset:1536
	global_load_dwordx4 v[152:155], v[82:83], off offset:1536
	global_load_dwordx4 v[156:159], v[84:85], off offset:1536
	global_load_dwordx4 v[160:163], v[86:87], off offset:1536
	s_waitcnt lgkmcnt(6)
	v_mfma_f32_16x16x32_bf16 v[34:37], v[196:199], v[212:215], v[34:37]
	ds_read_b128 v[228:231], v245 offset:36928
	s_waitcnt lgkmcnt(6)
	v_mfma_f32_16x16x32_bf16 v[38:41], v[196:199], v[216:219], v[38:41]
	ds_read_b128 v[232:235], v245 offset:39232
	s_waitcnt lgkmcnt(6)
	v_mfma_f32_16x16x32_bf16 v[2:5], v[196:199], v[220:223], v[2:5]
	ds_read_b128 v[236:239], v245 offset:41536
	s_waitcnt lgkmcnt(6)
	v_mfma_f32_16x16x32_bf16 v[6:9], v[196:199], v[224:227], v[6:9]
	ds_read_b128 v[240:243], v245 offset:43840
	ds_read_b128 v[196:199], v244 offset:64
	s_waitcnt lgkmcnt(7)
	v_mfma_f32_16x16x32_bf16 v[42:45], v[200:203], v[212:215], v[42:45]
	v_mfma_f32_16x16x32_bf16 v[46:49], v[200:203], v[216:219], v[46:49]
	v_mfma_f32_16x16x32_bf16 v[10:13], v[200:203], v[220:223], v[10:13]
	v_mfma_f32_16x16x32_bf16 v[14:17], v[200:203], v[224:227], v[14:17]
	ds_read_b128 v[200:203], v244 offset:2368
	s_waitcnt lgkmcnt(7)
	v_mfma_f32_16x16x32_bf16 v[50:53], v[204:207], v[212:215], v[50:53]
	v_mfma_f32_16x16x32_bf16 v[54:57], v[204:207], v[216:219], v[54:57]
	v_mfma_f32_16x16x32_bf16 v[18:21], v[204:207], v[220:223], v[18:21]
	v_mfma_f32_16x16x32_bf16 v[22:25], v[204:207], v[224:227], v[22:25]
	ds_read_b128 v[204:207], v244 offset:4672
	s_setprio 1
	s_waitcnt vmcnt(15)
	ds_write_b128 v95, v[98:101] offset:18432
	s_waitcnt vmcnt(14)
	ds_write_b128 v95, v[102:105] offset:23040
	s_waitcnt lgkmcnt(9)
	v_mfma_f32_16x16x32_bf16 v[58:61], v[208:211], v[212:215], v[58:61]
	v_mfma_f32_16x16x32_bf16 v[62:65], v[208:211], v[216:219], v[62:65]
	v_mfma_f32_16x16x32_bf16 v[26:29], v[208:211], v[220:223], v[26:29]
	v_mfma_f32_16x16x32_bf16 v[30:33], v[208:211], v[224:227], v[30:33]
	ds_read_b128 v[208:211], v244 offset:6976
	s_waitcnt vmcnt(13)
	ds_write_b128 v95, v[106:109] offset:27648
	s_waitcnt vmcnt(12)
	ds_write_b128 v95, v[110:113] offset:32256
	s_waitcnt lgkmcnt(7)
	v_mfma_f32_16x16x32_bf16 v[34:37], v[196:199], v[228:231], v[34:37]
	v_mfma_f32_16x16x32_bf16 v[38:41], v[196:199], v[232:235], v[38:41]
	v_mfma_f32_16x16x32_bf16 v[2:5], v[196:199], v[236:239], v[2:5]
	v_mfma_f32_16x16x32_bf16 v[6:9], v[196:199], v[240:243], v[6:9]
	s_waitcnt vmcnt(11)
	ds_write_b128 v95, v[114:117] offset:55296
	s_waitcnt vmcnt(10)
	ds_write_b128 v95, v[118:121] offset:59904
	s_waitcnt lgkmcnt(8)
	v_mfma_f32_16x16x32_bf16 v[42:45], v[200:203], v[228:231], v[42:45]
	v_mfma_f32_16x16x32_bf16 v[46:49], v[200:203], v[232:235], v[46:49]
	v_mfma_f32_16x16x32_bf16 v[10:13], v[200:203], v[236:239], v[10:13]
	v_mfma_f32_16x16x32_bf16 v[14:17], v[200:203], v[240:243], v[14:17]
	s_waitcnt vmcnt(9)
	ds_write_b128 v95, v[122:125] offset:64512
	s_waitcnt vmcnt(8)
	ds_write_b128 v96, v[126:129] offset:32256
	s_waitcnt lgkmcnt(0)
	s_barrier
	s_setprio 0
	ds_read_b128 v[212:215], v245 offset:55296
	ds_read_b128 v[196:199], v244 offset:18432
	ds_read_b128 v[216:219], v245 offset:57600
	ds_read_b128 v[220:223], v245 offset:59904
	ds_read_b128 v[224:227], v245 offset:62208
	ds_read_b128 v[200:203], v244 offset:20736
	v_mfma_f32_16x16x32_bf16 v[50:53], v[204:207], v[228:231], v[50:53]
	v_mfma_f32_16x16x32_bf16 v[54:57], v[204:207], v[232:235], v[54:57]
	v_mfma_f32_16x16x32_bf16 v[18:21], v[204:207], v[236:239], v[18:21]
	v_mfma_f32_16x16x32_bf16 v[22:25], v[204:207], v[240:243], v[22:25]
	ds_read_b128 v[204:207], v244 offset:23040
	v_mfma_f32_16x16x32_bf16 v[58:61], v[208:211], v[228:231], v[58:61]
	v_mfma_f32_16x16x32_bf16 v[62:65], v[208:211], v[232:235], v[62:65]
	v_mfma_f32_16x16x32_bf16 v[26:29], v[208:211], v[236:239], v[26:29]
	v_mfma_f32_16x16x32_bf16 v[30:33], v[208:211], v[240:243], v[30:33]
	ds_read_b128 v[208:211], v244 offset:25344
	global_load_dwordx4 v[98:101], v[72:73], off offset:1664
	global_load_dwordx4 v[102:105], v[74:75], off offset:1664
	global_load_dwordx4 v[106:109], v[76:77], off offset:1664
	global_load_dwordx4 v[110:113], v[78:79], off offset:1664
	global_load_dwordx4 v[114:117], v[80:81], off offset:1664
	global_load_dwordx4 v[118:121], v[82:83], off offset:1664
	global_load_dwordx4 v[122:125], v[84:85], off offset:1664
	global_load_dwordx4 v[126:129], v[86:87], off offset:1664
	s_waitcnt lgkmcnt(6)
	v_mfma_f32_16x16x32_bf16 v[34:37], v[196:199], v[212:215], v[34:37]
	ds_read_b128 v[228:231], v245 offset:55360
	s_waitcnt lgkmcnt(6)
	v_mfma_f32_16x16x32_bf16 v[38:41], v[196:199], v[216:219], v[38:41]
	ds_read_b128 v[232:235], v245 offset:57664
	s_waitcnt lgkmcnt(6)
	v_mfma_f32_16x16x32_bf16 v[2:5], v[196:199], v[220:223], v[2:5]
	ds_read_b128 v[236:239], v245 offset:59968
	s_waitcnt lgkmcnt(6)
	v_mfma_f32_16x16x32_bf16 v[6:9], v[196:199], v[224:227], v[6:9]
	ds_read_b128 v[240:243], v245 offset:62272
	ds_read_b128 v[196:199], v244 offset:18496
	s_waitcnt lgkmcnt(7)
	v_mfma_f32_16x16x32_bf16 v[42:45], v[200:203], v[212:215], v[42:45]
	v_mfma_f32_16x16x32_bf16 v[46:49], v[200:203], v[216:219], v[46:49]
	v_mfma_f32_16x16x32_bf16 v[10:13], v[200:203], v[220:223], v[10:13]
	v_mfma_f32_16x16x32_bf16 v[14:17], v[200:203], v[224:227], v[14:17]
	ds_read_b128 v[200:203], v244 offset:20800
	s_waitcnt lgkmcnt(7)
	v_mfma_f32_16x16x32_bf16 v[50:53], v[204:207], v[212:215], v[50:53]
	v_mfma_f32_16x16x32_bf16 v[54:57], v[204:207], v[216:219], v[54:57]
	v_mfma_f32_16x16x32_bf16 v[18:21], v[204:207], v[220:223], v[18:21]
	v_mfma_f32_16x16x32_bf16 v[22:25], v[204:207], v[224:227], v[22:25]
	ds_read_b128 v[204:207], v244 offset:23104
	s_setprio 1
	s_waitcnt vmcnt(15)
	ds_write_b128 v95, v[132:135]
	s_waitcnt vmcnt(14)
	ds_write_b128 v95, v[136:139] offset:4608
	s_waitcnt lgkmcnt(9)
	v_mfma_f32_16x16x32_bf16 v[58:61], v[208:211], v[212:215], v[58:61]
	v_mfma_f32_16x16x32_bf16 v[62:65], v[208:211], v[216:219], v[62:65]
	v_mfma_f32_16x16x32_bf16 v[26:29], v[208:211], v[220:223], v[26:29]
	v_mfma_f32_16x16x32_bf16 v[30:33], v[208:211], v[224:227], v[30:33]
	ds_read_b128 v[208:211], v244 offset:25408
	s_waitcnt vmcnt(13)
	ds_write_b128 v95, v[140:143] offset:9216
	s_waitcnt vmcnt(12)
	ds_write_b128 v95, v[144:147] offset:13824
	s_waitcnt lgkmcnt(7)
	v_mfma_f32_16x16x32_bf16 v[34:37], v[196:199], v[228:231], v[34:37]
	v_mfma_f32_16x16x32_bf16 v[38:41], v[196:199], v[232:235], v[38:41]
	v_mfma_f32_16x16x32_bf16 v[2:5], v[196:199], v[236:239], v[2:5]
	v_mfma_f32_16x16x32_bf16 v[6:9], v[196:199], v[240:243], v[6:9]
	s_waitcnt vmcnt(11)
	ds_write_b128 v95, v[148:151] offset:36864
	s_waitcnt vmcnt(10)
	ds_write_b128 v95, v[152:155] offset:41472
	s_waitcnt lgkmcnt(8)
	v_mfma_f32_16x16x32_bf16 v[42:45], v[200:203], v[228:231], v[42:45]
	v_mfma_f32_16x16x32_bf16 v[46:49], v[200:203], v[232:235], v[46:49]
	v_mfma_f32_16x16x32_bf16 v[10:13], v[200:203], v[236:239], v[10:13]
	v_mfma_f32_16x16x32_bf16 v[14:17], v[200:203], v[240:243], v[14:17]
	s_waitcnt vmcnt(9)
	ds_write_b128 v95, v[156:159] offset:46080
	s_waitcnt vmcnt(8)
	ds_write_b128 v95, v[160:163] offset:50688
	s_waitcnt lgkmcnt(0)
	s_barrier
	s_setprio 0
	ds_read_b128 v[212:215], v245 offset:36864
	ds_read_b128 v[196:199], v244
	ds_read_b128 v[216:219], v245 offset:39168
	ds_read_b128 v[220:223], v245 offset:41472
	ds_read_b128 v[224:227], v245 offset:43776
	ds_read_b128 v[200:203], v244 offset:2304
	v_mfma_f32_16x16x32_bf16 v[50:53], v[204:207], v[228:231], v[50:53]
	v_mfma_f32_16x16x32_bf16 v[54:57], v[204:207], v[232:235], v[54:57]
	v_mfma_f32_16x16x32_bf16 v[18:21], v[204:207], v[236:239], v[18:21]
	v_mfma_f32_16x16x32_bf16 v[22:25], v[204:207], v[240:243], v[22:25]
	ds_read_b128 v[204:207], v244 offset:4608
	v_mfma_f32_16x16x32_bf16 v[58:61], v[208:211], v[228:231], v[58:61]
	v_mfma_f32_16x16x32_bf16 v[62:65], v[208:211], v[232:235], v[62:65]
	v_mfma_f32_16x16x32_bf16 v[26:29], v[208:211], v[236:239], v[26:29]
	v_mfma_f32_16x16x32_bf16 v[30:33], v[208:211], v[240:243], v[30:33]
	ds_read_b128 v[208:211], v244 offset:6912
	global_load_dwordx4 v[132:135], v[72:73], off offset:1792
	global_load_dwordx4 v[136:139], v[74:75], off offset:1792
	global_load_dwordx4 v[140:143], v[76:77], off offset:1792
	global_load_dwordx4 v[144:147], v[78:79], off offset:1792
	global_load_dwordx4 v[148:151], v[80:81], off offset:1792
	global_load_dwordx4 v[152:155], v[82:83], off offset:1792
	global_load_dwordx4 v[156:159], v[84:85], off offset:1792
	global_load_dwordx4 v[160:163], v[86:87], off offset:1792
	s_waitcnt lgkmcnt(6)
	v_mfma_f32_16x16x32_bf16 v[34:37], v[196:199], v[212:215], v[34:37]
	ds_read_b128 v[228:231], v245 offset:36928
	s_waitcnt lgkmcnt(6)
	v_mfma_f32_16x16x32_bf16 v[38:41], v[196:199], v[216:219], v[38:41]
	ds_read_b128 v[232:235], v245 offset:39232
	s_waitcnt lgkmcnt(6)
	v_mfma_f32_16x16x32_bf16 v[2:5], v[196:199], v[220:223], v[2:5]
	ds_read_b128 v[236:239], v245 offset:41536
	s_waitcnt lgkmcnt(6)
	v_mfma_f32_16x16x32_bf16 v[6:9], v[196:199], v[224:227], v[6:9]
	ds_read_b128 v[240:243], v245 offset:43840
	ds_read_b128 v[196:199], v244 offset:64
	s_waitcnt lgkmcnt(7)
	v_mfma_f32_16x16x32_bf16 v[42:45], v[200:203], v[212:215], v[42:45]
	v_mfma_f32_16x16x32_bf16 v[46:49], v[200:203], v[216:219], v[46:49]
	v_mfma_f32_16x16x32_bf16 v[10:13], v[200:203], v[220:223], v[10:13]
	v_mfma_f32_16x16x32_bf16 v[14:17], v[200:203], v[224:227], v[14:17]
	ds_read_b128 v[200:203], v244 offset:2368
	s_waitcnt lgkmcnt(7)
	v_mfma_f32_16x16x32_bf16 v[50:53], v[204:207], v[212:215], v[50:53]
	v_mfma_f32_16x16x32_bf16 v[54:57], v[204:207], v[216:219], v[54:57]
	v_mfma_f32_16x16x32_bf16 v[18:21], v[204:207], v[220:223], v[18:21]
	v_mfma_f32_16x16x32_bf16 v[22:25], v[204:207], v[224:227], v[22:25]
	ds_read_b128 v[204:207], v244 offset:4672
	s_setprio 1
	s_waitcnt vmcnt(15)
	ds_write_b128 v95, v[98:101] offset:18432
	s_waitcnt vmcnt(14)
	ds_write_b128 v95, v[102:105] offset:23040
	s_waitcnt lgkmcnt(9)
	v_mfma_f32_16x16x32_bf16 v[58:61], v[208:211], v[212:215], v[58:61]
	v_mfma_f32_16x16x32_bf16 v[62:65], v[208:211], v[216:219], v[62:65]
	v_mfma_f32_16x16x32_bf16 v[26:29], v[208:211], v[220:223], v[26:29]
	v_mfma_f32_16x16x32_bf16 v[30:33], v[208:211], v[224:227], v[30:33]
	ds_read_b128 v[208:211], v244 offset:6976
	s_waitcnt vmcnt(13)
	ds_write_b128 v95, v[106:109] offset:27648
	s_waitcnt vmcnt(12)
	ds_write_b128 v95, v[110:113] offset:32256
	s_waitcnt lgkmcnt(7)
	v_mfma_f32_16x16x32_bf16 v[34:37], v[196:199], v[228:231], v[34:37]
	v_mfma_f32_16x16x32_bf16 v[38:41], v[196:199], v[232:235], v[38:41]
	v_mfma_f32_16x16x32_bf16 v[2:5], v[196:199], v[236:239], v[2:5]
	v_mfma_f32_16x16x32_bf16 v[6:9], v[196:199], v[240:243], v[6:9]
	s_waitcnt vmcnt(11)
	ds_write_b128 v95, v[114:117] offset:55296
	s_waitcnt vmcnt(10)
	ds_write_b128 v95, v[118:121] offset:59904
	s_waitcnt lgkmcnt(8)
	v_mfma_f32_16x16x32_bf16 v[42:45], v[200:203], v[228:231], v[42:45]
	v_mfma_f32_16x16x32_bf16 v[46:49], v[200:203], v[232:235], v[46:49]
	v_mfma_f32_16x16x32_bf16 v[10:13], v[200:203], v[236:239], v[10:13]
	v_mfma_f32_16x16x32_bf16 v[14:17], v[200:203], v[240:243], v[14:17]
	s_waitcnt vmcnt(9)
	ds_write_b128 v95, v[122:125] offset:64512
	s_waitcnt vmcnt(8)
	ds_write_b128 v96, v[126:129] offset:32256
	s_waitcnt lgkmcnt(0)
	s_barrier
	s_setprio 0
	ds_read_b128 v[212:215], v245 offset:55296
	ds_read_b128 v[196:199], v244 offset:18432
	ds_read_b128 v[216:219], v245 offset:57600
	ds_read_b128 v[220:223], v245 offset:59904
	ds_read_b128 v[224:227], v245 offset:62208
	ds_read_b128 v[200:203], v244 offset:20736
	v_mfma_f32_16x16x32_bf16 v[50:53], v[204:207], v[228:231], v[50:53]
	v_mfma_f32_16x16x32_bf16 v[54:57], v[204:207], v[232:235], v[54:57]
	v_mfma_f32_16x16x32_bf16 v[18:21], v[204:207], v[236:239], v[18:21]
	v_mfma_f32_16x16x32_bf16 v[22:25], v[204:207], v[240:243], v[22:25]
	ds_read_b128 v[204:207], v244 offset:23040
	v_mfma_f32_16x16x32_bf16 v[58:61], v[208:211], v[228:231], v[58:61]
	v_mfma_f32_16x16x32_bf16 v[62:65], v[208:211], v[232:235], v[62:65]
	v_mfma_f32_16x16x32_bf16 v[26:29], v[208:211], v[236:239], v[26:29]
	v_mfma_f32_16x16x32_bf16 v[30:33], v[208:211], v[240:243], v[30:33]
	ds_read_b128 v[208:211], v244 offset:25344
	global_load_dwordx4 v[98:101], v[72:73], off offset:1920
	s_nop 0
	global_load_dwordx4 v[72:75], v[74:75], off offset:1920
	s_nop 0
	global_load_dwordx4 v[102:105], v[76:77], off offset:1920
	s_nop 0
	global_load_dwordx4 v[76:79], v[78:79], off offset:1920
	s_nop 0
	global_load_dwordx4 v[106:109], v[80:81], off offset:1920
	s_nop 0
	global_load_dwordx4 v[80:83], v[82:83], off offset:1920
	s_nop 0
	global_load_dwordx4 v[110:113], v[84:85], off offset:1920
	s_nop 0
	global_load_dwordx4 v[84:87], v[86:87], off offset:1920
	s_waitcnt lgkmcnt(6)
	v_mfma_f32_16x16x32_bf16 v[34:37], v[196:199], v[212:215], v[34:37]
	ds_read_b128 v[228:231], v245 offset:55360
	s_waitcnt lgkmcnt(6)
	v_mfma_f32_16x16x32_bf16 v[38:41], v[196:199], v[216:219], v[38:41]
	ds_read_b128 v[232:235], v245 offset:57664
	s_waitcnt lgkmcnt(6)
	v_mfma_f32_16x16x32_bf16 v[2:5], v[196:199], v[220:223], v[2:5]
	ds_read_b128 v[236:239], v245 offset:59968
	s_waitcnt lgkmcnt(6)
	v_mfma_f32_16x16x32_bf16 v[6:9], v[196:199], v[224:227], v[6:9]
	ds_read_b128 v[240:243], v245 offset:62272
	ds_read_b128 v[196:199], v244 offset:18496
	s_waitcnt lgkmcnt(7)
	v_mfma_f32_16x16x32_bf16 v[42:45], v[200:203], v[212:215], v[42:45]
	v_mfma_f32_16x16x32_bf16 v[46:49], v[200:203], v[216:219], v[46:49]
	v_mfma_f32_16x16x32_bf16 v[10:13], v[200:203], v[220:223], v[10:13]
	v_mfma_f32_16x16x32_bf16 v[14:17], v[200:203], v[224:227], v[14:17]
	ds_read_b128 v[200:203], v244 offset:20800
	s_waitcnt lgkmcnt(7)
	v_mfma_f32_16x16x32_bf16 v[50:53], v[204:207], v[212:215], v[50:53]
	v_mfma_f32_16x16x32_bf16 v[54:57], v[204:207], v[216:219], v[54:57]
	v_mfma_f32_16x16x32_bf16 v[18:21], v[204:207], v[220:223], v[18:21]
	v_mfma_f32_16x16x32_bf16 v[22:25], v[204:207], v[224:227], v[22:25]
	ds_read_b128 v[204:207], v244 offset:23104
	s_setprio 1
	s_waitcnt vmcnt(15)
	ds_write_b128 v95, v[132:135]
	s_waitcnt vmcnt(14)
	ds_write_b128 v95, v[136:139] offset:4608
	s_waitcnt lgkmcnt(9)
	v_mfma_f32_16x16x32_bf16 v[58:61], v[208:211], v[212:215], v[58:61]
	v_mfma_f32_16x16x32_bf16 v[62:65], v[208:211], v[216:219], v[62:65]
	v_mfma_f32_16x16x32_bf16 v[26:29], v[208:211], v[220:223], v[26:29]
	v_mfma_f32_16x16x32_bf16 v[30:33], v[208:211], v[224:227], v[30:33]
	ds_read_b128 v[208:211], v244 offset:25408
	s_waitcnt vmcnt(13)
	ds_write_b128 v95, v[140:143] offset:9216
	s_waitcnt vmcnt(12)
	ds_write_b128 v95, v[144:147] offset:13824
	s_waitcnt lgkmcnt(7)
	v_mfma_f32_16x16x32_bf16 v[34:37], v[196:199], v[228:231], v[34:37]
	v_mfma_f32_16x16x32_bf16 v[38:41], v[196:199], v[232:235], v[38:41]
	v_mfma_f32_16x16x32_bf16 v[2:5], v[196:199], v[236:239], v[2:5]
	v_mfma_f32_16x16x32_bf16 v[6:9], v[196:199], v[240:243], v[6:9]
	s_waitcnt vmcnt(11)
	ds_write_b128 v95, v[148:151] offset:36864
	s_waitcnt vmcnt(10)
	ds_write_b128 v95, v[152:155] offset:41472
	s_waitcnt lgkmcnt(8)
	v_mfma_f32_16x16x32_bf16 v[42:45], v[200:203], v[228:231], v[42:45]
	v_mfma_f32_16x16x32_bf16 v[46:49], v[200:203], v[232:235], v[46:49]
	v_mfma_f32_16x16x32_bf16 v[10:13], v[200:203], v[236:239], v[10:13]
	v_mfma_f32_16x16x32_bf16 v[14:17], v[200:203], v[240:243], v[14:17]
	s_waitcnt vmcnt(9)
	ds_write_b128 v95, v[156:159] offset:46080
	s_waitcnt vmcnt(8)
	ds_write_b128 v95, v[160:163] offset:50688
	s_waitcnt lgkmcnt(0)
	s_barrier
	s_setprio 0
	ds_read_b128 v[212:215], v245 offset:36864
	ds_read_b128 v[196:199], v244
	ds_read_b128 v[216:219], v245 offset:39168
	ds_read_b128 v[220:223], v245 offset:41472
	ds_read_b128 v[224:227], v245 offset:43776
	ds_read_b128 v[200:203], v244 offset:2304
	v_mfma_f32_16x16x32_bf16 v[50:53], v[204:207], v[228:231], v[50:53]
	v_mfma_f32_16x16x32_bf16 v[54:57], v[204:207], v[232:235], v[54:57]
	v_mfma_f32_16x16x32_bf16 v[18:21], v[204:207], v[236:239], v[18:21]
	v_mfma_f32_16x16x32_bf16 v[22:25], v[204:207], v[240:243], v[22:25]
	ds_read_b128 v[204:207], v244 offset:4608
	v_mfma_f32_16x16x32_bf16 v[58:61], v[208:211], v[228:231], v[58:61]
	v_mfma_f32_16x16x32_bf16 v[62:65], v[208:211], v[232:235], v[62:65]
	v_mfma_f32_16x16x32_bf16 v[26:29], v[208:211], v[236:239], v[26:29]
	v_mfma_f32_16x16x32_bf16 v[30:33], v[208:211], v[240:243], v[30:33]
	ds_read_b128 v[208:211], v244 offset:6912
	s_waitcnt lgkmcnt(6)
	v_mfma_f32_16x16x32_bf16 v[34:37], v[196:199], v[212:215], v[34:37]
	ds_read_b128 v[228:231], v245 offset:36928
	s_waitcnt lgkmcnt(6)
	v_mfma_f32_16x16x32_bf16 v[38:41], v[196:199], v[216:219], v[38:41]
	ds_read_b128 v[232:235], v245 offset:39232
	s_waitcnt lgkmcnt(6)
	v_mfma_f32_16x16x32_bf16 v[2:5], v[196:199], v[220:223], v[2:5]
	ds_read_b128 v[236:239], v245 offset:41536
	s_waitcnt lgkmcnt(6)
	v_mfma_f32_16x16x32_bf16 v[6:9], v[196:199], v[224:227], v[6:9]
	ds_read_b128 v[240:243], v245 offset:43840
	ds_read_b128 v[196:199], v244 offset:64
	s_waitcnt lgkmcnt(7)
	v_mfma_f32_16x16x32_bf16 v[42:45], v[200:203], v[212:215], v[42:45]
	v_mfma_f32_16x16x32_bf16 v[46:49], v[200:203], v[216:219], v[46:49]
	v_mfma_f32_16x16x32_bf16 v[10:13], v[200:203], v[220:223], v[10:13]
	v_mfma_f32_16x16x32_bf16 v[14:17], v[200:203], v[224:227], v[14:17]
	ds_read_b128 v[200:203], v244 offset:2368
	s_waitcnt lgkmcnt(7)
	v_mfma_f32_16x16x32_bf16 v[50:53], v[204:207], v[212:215], v[50:53]
	v_mfma_f32_16x16x32_bf16 v[54:57], v[204:207], v[216:219], v[54:57]
	v_mfma_f32_16x16x32_bf16 v[18:21], v[204:207], v[220:223], v[18:21]
	v_mfma_f32_16x16x32_bf16 v[22:25], v[204:207], v[224:227], v[22:25]
	ds_read_b128 v[204:207], v244 offset:4672
	s_setprio 1
	s_waitcnt vmcnt(7)
	ds_write_b128 v95, v[98:101] offset:18432
	s_waitcnt vmcnt(6)
	ds_write_b128 v95, v[72:75] offset:23040
	s_waitcnt lgkmcnt(9)
	v_mfma_f32_16x16x32_bf16 v[58:61], v[208:211], v[212:215], v[58:61]
	v_mfma_f32_16x16x32_bf16 v[62:65], v[208:211], v[216:219], v[62:65]
	v_mfma_f32_16x16x32_bf16 v[26:29], v[208:211], v[220:223], v[26:29]
	v_mfma_f32_16x16x32_bf16 v[30:33], v[208:211], v[224:227], v[30:33]
	ds_read_b128 v[208:211], v244 offset:6976
	s_waitcnt vmcnt(5)
	ds_write_b128 v95, v[102:105] offset:27648
	s_waitcnt vmcnt(4)
	ds_write_b128 v95, v[76:79] offset:32256
	s_waitcnt lgkmcnt(7)
	v_mfma_f32_16x16x32_bf16 v[34:37], v[196:199], v[228:231], v[34:37]
	v_mfma_f32_16x16x32_bf16 v[38:41], v[196:199], v[232:235], v[38:41]
	v_mfma_f32_16x16x32_bf16 v[2:5], v[196:199], v[236:239], v[2:5]
	v_mfma_f32_16x16x32_bf16 v[6:9], v[196:199], v[240:243], v[6:9]
	s_waitcnt vmcnt(3)
	ds_write_b128 v95, v[106:109] offset:55296
	s_waitcnt vmcnt(2)
	ds_write_b128 v95, v[80:83] offset:59904
	s_waitcnt lgkmcnt(8)
	v_mfma_f32_16x16x32_bf16 v[42:45], v[200:203], v[228:231], v[42:45]
	v_mfma_f32_16x16x32_bf16 v[46:49], v[200:203], v[232:235], v[46:49]
	v_mfma_f32_16x16x32_bf16 v[10:13], v[200:203], v[236:239], v[10:13]
	v_mfma_f32_16x16x32_bf16 v[14:17], v[200:203], v[240:243], v[14:17]
	s_waitcnt vmcnt(1)
	ds_write_b128 v95, v[110:113] offset:64512
	s_waitcnt vmcnt(0)
	ds_write_b128 v96, v[84:87] offset:32256
	s_waitcnt lgkmcnt(0)
	s_barrier
	s_setprio 0
	ds_read_b128 v[212:215], v245 offset:55296
	ds_read_b128 v[196:199], v244 offset:18432
	ds_read_b128 v[216:219], v245 offset:57600
	ds_read_b128 v[220:223], v245 offset:59904
	ds_read_b128 v[224:227], v245 offset:62208
	ds_read_b128 v[200:203], v244 offset:20736
	v_mfma_f32_16x16x32_bf16 v[50:53], v[204:207], v[228:231], v[50:53]
	v_mfma_f32_16x16x32_bf16 v[54:57], v[204:207], v[232:235], v[54:57]
	v_mfma_f32_16x16x32_bf16 v[18:21], v[204:207], v[236:239], v[18:21]
	v_mfma_f32_16x16x32_bf16 v[22:25], v[204:207], v[240:243], v[22:25]
	ds_read_b128 v[204:207], v244 offset:23040
	v_mfma_f32_16x16x32_bf16 v[58:61], v[208:211], v[228:231], v[58:61]
	v_mfma_f32_16x16x32_bf16 v[62:65], v[208:211], v[232:235], v[62:65]
	v_mfma_f32_16x16x32_bf16 v[26:29], v[208:211], v[236:239], v[26:29]
	v_mfma_f32_16x16x32_bf16 v[30:33], v[208:211], v[240:243], v[30:33]
	ds_read_b128 v[208:211], v244 offset:25344
	s_waitcnt lgkmcnt(6)
	v_mfma_f32_16x16x32_bf16 v[34:37], v[196:199], v[212:215], v[34:37]
	ds_read_b128 v[228:231], v245 offset:55360
	s_waitcnt lgkmcnt(6)
	v_mfma_f32_16x16x32_bf16 v[38:41], v[196:199], v[216:219], v[38:41]
	ds_read_b128 v[232:235], v245 offset:57664
	s_waitcnt lgkmcnt(6)
	v_mfma_f32_16x16x32_bf16 v[2:5], v[196:199], v[220:223], v[2:5]
	ds_read_b128 v[236:239], v245 offset:59968
	s_waitcnt lgkmcnt(6)
	v_mfma_f32_16x16x32_bf16 v[6:9], v[196:199], v[224:227], v[6:9]
	ds_read_b128 v[240:243], v245 offset:62272
	ds_read_b128 v[196:199], v244 offset:18496
	s_waitcnt lgkmcnt(7)
	v_mfma_f32_16x16x32_bf16 v[42:45], v[200:203], v[212:215], v[42:45]
	v_mfma_f32_16x16x32_bf16 v[46:49], v[200:203], v[216:219], v[46:49]
	v_mfma_f32_16x16x32_bf16 v[10:13], v[200:203], v[220:223], v[10:13]
	v_mfma_f32_16x16x32_bf16 v[14:17], v[200:203], v[224:227], v[14:17]
	ds_read_b128 v[200:203], v244 offset:20800
	s_waitcnt lgkmcnt(7)
	v_mfma_f32_16x16x32_bf16 v[50:53], v[204:207], v[212:215], v[50:53]
	v_mfma_f32_16x16x32_bf16 v[54:57], v[204:207], v[216:219], v[54:57]
	v_mfma_f32_16x16x32_bf16 v[18:21], v[204:207], v[220:223], v[18:21]
	v_mfma_f32_16x16x32_bf16 v[22:25], v[204:207], v[224:227], v[22:25]
	ds_read_b128 v[204:207], v244 offset:23104
	s_waitcnt lgkmcnt(7)
	v_mfma_f32_16x16x32_bf16 v[58:61], v[208:211], v[212:215], v[58:61]
	v_mfma_f32_16x16x32_bf16 v[62:65], v[208:211], v[216:219], v[62:65]
	v_mfma_f32_16x16x32_bf16 v[26:29], v[208:211], v[220:223], v[26:29]
	v_mfma_f32_16x16x32_bf16 v[30:33], v[208:211], v[224:227], v[30:33]
	ds_read_b128 v[208:211], v244 offset:25408
	s_waitcnt lgkmcnt(3)
	v_mfma_f32_16x16x32_bf16 v[34:37], v[196:199], v[228:231], v[34:37]
	v_mfma_f32_16x16x32_bf16 v[38:41], v[196:199], v[232:235], v[38:41]
	v_mfma_f32_16x16x32_bf16 v[2:5], v[196:199], v[236:239], v[2:5]
	v_mfma_f32_16x16x32_bf16 v[6:9], v[196:199], v[240:243], v[6:9]
	s_waitcnt lgkmcnt(2)
	v_mfma_f32_16x16x32_bf16 v[42:45], v[200:203], v[228:231], v[42:45]
	v_mfma_f32_16x16x32_bf16 v[46:49], v[200:203], v[232:235], v[46:49]
	v_mfma_f32_16x16x32_bf16 v[10:13], v[200:203], v[236:239], v[10:13]
	v_mfma_f32_16x16x32_bf16 v[14:17], v[200:203], v[240:243], v[14:17]
	v_or_b32_e32 v66, s5, v88
	s_addk_i32 s5, 0xf000
	s_lshr_b32 s5, s5, 12
	s_mulk_i32 s5, 0xc00
	s_addk_i32 s5, 0x3000
	s_cmp_gt_u32 s0, 31
	v_lshlrev_b32_e32 v66, 12, v66
	s_cselect_b32 s0, s5, 0x2400
	v_lshl_add_u64 v[148:149], s[80:81], 0, v[66:67]
	v_add_lshl_u32 v66, s4, v97, 2
	s_lshl_b64 s[4:5], s[0:1], 2
	s_add_u32 s0, s82, s4
	s_addc_u32 s5, s83, s5
	s_add_u32 s4, s0, 0xe958000
	v_lshl_add_u64 v[150:151], v[148:149], 0, v[66:67]
	s_addc_u32 s5, s5, 0
	v_or_b32_e32 v152, 0xe0, v66
	v_or_b32_e32 v154, 32, v66
	v_or_b32_e32 v156, 64, v66
	v_or_b32_e32 v158, 0x60, v66
	v_or_b32_e32 v160, 0x80, v66
	v_or_b32_e32 v162, 0xa0, v66
	v_or_b32_e32 v164, 0xc0, v66
	v_mov_b32_e32 v155, v67
	v_mov_b32_e32 v157, v67
	v_mov_b32_e32 v159, v67
	v_mov_b32_e32 v161, v67
	v_mov_b32_e32 v163, v67
	v_mov_b32_e32 v165, v67
	v_mov_b32_e32 v153, v67
	s_add_i32 s11, s11, 1
	s_mul_i32 s0, s11, s7
	s_add_i32 s10, s10, s7
	s_waitcnt lgkmcnt(0)
	s_barrier
	v_mfma_f32_16x16x32_bf16 v[50:53], v[204:207], v[228:231], v[50:53]
	v_mfma_f32_16x16x32_bf16 v[54:57], v[204:207], v[232:235], v[54:57]
	v_mfma_f32_16x16x32_bf16 v[18:21], v[204:207], v[236:239], v[18:21]
	v_mfma_f32_16x16x32_bf16 v[22:25], v[204:207], v[240:243], v[22:25]
	v_mfma_f32_16x16x32_bf16 v[58:61], v[208:211], v[228:231], v[58:61]
	v_mfma_f32_16x16x32_bf16 v[62:65], v[208:211], v[232:235], v[62:65]
	v_mfma_f32_16x16x32_bf16 v[26:29], v[208:211], v[236:239], v[26:29]
	v_mfma_f32_16x16x32_bf16 v[30:33], v[208:211], v[240:243], v[30:33]
	s_nop 7
	v_permlane16_swap_b32_e32 v34, v38
	v_permlane16_swap_b32_e32 v35, v39
	v_permlane16_swap_b32_e32 v36, v40
	v_permlane16_swap_b32_e32 v37, v41
	v_permlane16_swap_b32_e32 v42, v46
	v_permlane16_swap_b32_e32 v43, v47
	v_permlane16_swap_b32_e32 v44, v48
	v_permlane16_swap_b32_e32 v45, v49
	v_permlane16_swap_b32_e32 v2, v6
	v_permlane16_swap_b32_e32 v3, v7
	v_permlane16_swap_b32_e32 v4, v8
	v_permlane16_swap_b32_e32 v5, v9
	v_permlane16_swap_b32_e32 v10, v14
	v_permlane16_swap_b32_e32 v11, v15
	v_permlane16_swap_b32_e32 v12, v16
	v_permlane16_swap_b32_e32 v13, v17
	v_permlane16_swap_b32_e32 v50, v54
	v_permlane16_swap_b32_e32 v51, v55
	v_permlane16_swap_b32_e32 v52, v56
	v_permlane16_swap_b32_e32 v53, v57
	v_permlane16_swap_b32_e32 v58, v62
	v_permlane16_swap_b32_e32 v59, v63
	v_permlane16_swap_b32_e32 v60, v64
	v_permlane16_swap_b32_e32 v61, v65
	v_permlane16_swap_b32_e32 v18, v22
	v_permlane16_swap_b32_e32 v19, v23
	v_permlane16_swap_b32_e32 v20, v24
	v_permlane16_swap_b32_e32 v21, v25
	v_permlane16_swap_b32_e32 v26, v30
	v_permlane16_swap_b32_e32 v27, v31
	v_permlane16_swap_b32_e32 v28, v32
	v_permlane16_swap_b32_e32 v29, v33
	v_permlane32_swap_b32_e32 v34, v38
	v_permlane32_swap_b32_e32 v35, v39
	v_permlane32_swap_b32_e32 v36, v40
	v_permlane32_swap_b32_e32 v37, v41
	v_permlane32_swap_b32_e32 v42, v46
	v_permlane32_swap_b32_e32 v43, v47
	v_permlane32_swap_b32_e32 v44, v48
	v_permlane32_swap_b32_e32 v45, v49
	v_permlane32_swap_b32_e32 v2, v6
	v_permlane32_swap_b32_e32 v3, v7
	v_permlane32_swap_b32_e32 v4, v8
	v_permlane32_swap_b32_e32 v5, v9
	v_permlane32_swap_b32_e32 v10, v14
	v_permlane32_swap_b32_e32 v11, v15
	v_permlane32_swap_b32_e32 v12, v16
	v_permlane32_swap_b32_e32 v13, v17
	v_permlane32_swap_b32_e32 v50, v54
	v_permlane32_swap_b32_e32 v51, v55
	v_permlane32_swap_b32_e32 v52, v56
	v_permlane32_swap_b32_e32 v53, v57
	v_permlane32_swap_b32_e32 v58, v62
	v_permlane32_swap_b32_e32 v59, v63
	v_permlane32_swap_b32_e32 v60, v64
	v_permlane32_swap_b32_e32 v61, v65
	v_permlane32_swap_b32_e32 v18, v22
	v_permlane32_swap_b32_e32 v19, v23
	v_permlane32_swap_b32_e32 v20, v24
	v_permlane32_swap_b32_e32 v21, v25
	v_permlane32_swap_b32_e32 v26, v30
	v_permlane32_swap_b32_e32 v27, v31
	v_permlane32_swap_b32_e32 v28, v32
	v_permlane32_swap_b32_e32 v29, v33
	global_load_dwordx4 v[76:79], v[150:151], off offset:224
	global_load_dwordx4 v[84:87], v152, s[4:5]
	global_load_dwordx4 v[80:83], v[150:151], off offset:192
	s_waitcnt vmcnt(1)
	v_fma_f32 v62, v62, v84, v76
	v_fma_f32 v63, v63, v85, v77
	global_load_dwordx4 v[72:75], v164, s[4:5]
	global_load_dwordx4 v[98:101], v[150:151], off offset:160
	global_load_dwordx4 v[102:105], v162, s[4:5]
	global_load_dwordx4 v[106:109], v[150:151], off offset:128
	global_load_dwordx4 v[110:113], v160, s[4:5]
	global_load_dwordx4 v[114:117], v[150:151], off offset:96
	global_load_dwordx4 v[118:121], v158, s[4:5]
	global_load_dwordx4 v[122:125], v[150:151], off offset:64
	global_load_dwordx4 v[126:129], v156, s[4:5]
	global_load_dwordx4 v[132:135], v[150:151], off offset:32
	global_load_dwordx4 v[136:139], v154, s[4:5]
	global_load_dwordx4 v[140:143], v[150:151], off
	global_load_dwordx4 v[144:147], v66, s[4:5]
	v_pk_fma_f32 v[64:65], v[64:65], v[86:87], v[78:79]
	global_store_dwordx4 v[150:151], v[62:65], off offset:224
	s_waitcnt vmcnt(13)
	v_pk_fma_f32 v[58:59], v[58:59], v[72:73], v[80:81]
	v_pk_fma_f32 v[60:61], v[60:61], v[74:75], v[82:83]
	s_waitcnt vmcnt(11)
	v_pk_fma_f32 v[54:55], v[54:55], v[102:103], v[98:99]
	v_pk_fma_f32 v[56:57], v[56:57], v[104:105], v[100:101]
	s_waitcnt vmcnt(9)
	v_pk_fma_f32 v[50:51], v[50:51], v[110:111], v[106:107]
	v_pk_fma_f32 v[52:53], v[52:53], v[112:113], v[108:109]
	s_waitcnt vmcnt(7)
	v_pk_fma_f32 v[46:47], v[46:47], v[118:119], v[114:115]
	v_pk_fma_f32 v[48:49], v[48:49], v[120:121], v[116:117]
	s_waitcnt vmcnt(5)
	v_pk_fma_f32 v[42:43], v[42:43], v[126:127], v[122:123]
	v_pk_fma_f32 v[44:45], v[44:45], v[128:129], v[124:125]
	s_waitcnt vmcnt(3)
	v_pk_fma_f32 v[38:39], v[38:39], v[136:137], v[132:133]
	v_pk_fma_f32 v[40:41], v[40:41], v[138:139], v[134:135]
	s_waitcnt vmcnt(1)
	v_pk_fma_f32 v[34:35], v[34:35], v[144:145], v[140:141]
	v_pk_fma_f32 v[36:37], v[36:37], v[146:147], v[142:143]
	global_store_dwordx4 v[150:151], v[34:37], off
	global_store_dwordx4 v[150:151], v[38:41], off offset:32
	global_store_dwordx4 v[150:151], v[42:45], off offset:64
	v_lshl_add_u64 v[34:35], v[148:149], 0, s[2:3]
	global_store_dwordx4 v[150:151], v[46:49], off offset:96
	global_store_dwordx4 v[150:151], v[50:53], off offset:128
	global_store_dwordx4 v[150:151], v[54:57], off offset:160
	global_store_dwordx4 v[150:151], v[58:61], off offset:192
	v_lshl_add_u64 v[114:115], v[34:35], 0, v[66:67]
	v_lshl_add_u64 v[116:117], v[34:35], 0, v[154:155]
	v_lshl_add_u64 v[118:119], v[34:35], 0, v[156:157]
	v_lshl_add_u64 v[120:121], v[34:35], 0, v[158:159]
	v_lshl_add_u64 v[122:123], v[34:35], 0, v[160:161]
	v_lshl_add_u64 v[124:125], v[34:35], 0, v[162:163]
	v_lshl_add_u64 v[126:127], v[34:35], 0, v[164:165]
	v_lshl_add_u64 v[128:129], v[34:35], 0, v[152:153]
	global_load_dwordx4 v[34:37], v[128:129], off
	global_load_dwordx4 v[38:41], v152, s[4:5]
	global_load_dwordx4 v[42:45], v[126:127], off
	global_load_dwordx4 v[46:49], v164, s[4:5]
	global_load_dwordx4 v[50:53], v[124:125], off
	global_load_dwordx4 v[54:57], v162, s[4:5]
	global_load_dwordx4 v[58:61], v[122:123], off
	global_load_dwordx4 v[62:65], v160, s[4:5]
	global_load_dwordx4 v[72:75], v[120:121], off
	global_load_dwordx4 v[76:79], v158, s[4:5]
	global_load_dwordx4 v[80:83], v[118:119], off
	global_load_dwordx4 v[84:87], v156, s[4:5]
	global_load_dwordx4 v[98:101], v[116:117], off
	global_load_dwordx4 v[102:105], v154, s[4:5]
	global_load_dwordx4 v[106:109], v[114:115], off
	global_load_dwordx4 v[110:113], v66, s[4:5]
	s_add_i32 s4, s0, s6
	s_cmpk_lt_u32 s10, 0x60
	s_waitcnt vmcnt(14)
	v_pk_fma_f32 v[30:31], v[30:31], v[38:39], v[34:35]
	v_pk_fma_f32 v[32:33], v[32:33], v[40:41], v[36:37]
	s_waitcnt vmcnt(12)
	v_pk_fma_f32 v[26:27], v[26:27], v[46:47], v[42:43]
	v_pk_fma_f32 v[28:29], v[28:29], v[48:49], v[44:45]
	s_waitcnt vmcnt(10)
	v_pk_fma_f32 v[22:23], v[22:23], v[54:55], v[50:51]
	v_pk_fma_f32 v[24:25], v[24:25], v[56:57], v[52:53]
	s_waitcnt vmcnt(8)
	v_pk_fma_f32 v[18:19], v[18:19], v[62:63], v[58:59]
	v_pk_fma_f32 v[20:21], v[20:21], v[64:65], v[60:61]
	s_waitcnt vmcnt(6)
	v_pk_fma_f32 v[14:15], v[14:15], v[76:77], v[72:73]
	v_pk_fma_f32 v[16:17], v[16:17], v[78:79], v[74:75]
	s_waitcnt vmcnt(4)
	v_pk_fma_f32 v[10:11], v[10:11], v[84:85], v[80:81]
	v_pk_fma_f32 v[12:13], v[12:13], v[86:87], v[82:83]
	s_waitcnt vmcnt(2)
	v_pk_fma_f32 v[6:7], v[6:7], v[102:103], v[98:99]
	v_pk_fma_f32 v[8:9], v[8:9], v[104:105], v[100:101]
	s_waitcnt vmcnt(0)
	v_pk_fma_f32 v[2:3], v[2:3], v[110:111], v[106:107]
	v_pk_fma_f32 v[4:5], v[4:5], v[112:113], v[108:109]
	global_store_dwordx4 v[114:115], v[2:5], off
	global_store_dwordx4 v[116:117], v[6:9], off
	global_store_dwordx4 v[118:119], v[10:13], off
	global_store_dwordx4 v[120:121], v[14:17], off
	global_store_dwordx4 v[122:123], v[18:21], off
	global_store_dwordx4 v[124:125], v[22:25], off
	global_store_dwordx4 v[126:127], v[26:29], off
	global_store_dwordx4 v[128:129], v[30:33], off
	s_cbranch_scc1 .LBB0_1871
